# v26: v16 + row-wise phases (norm/readout/final norm): output stores marked nt (streaming)
# baseline (speedup 1.0000x reference)
; #define GAS __attribute__((address_space(1)))
; #define LAS __attribute__((address_space(3)))
; __device__ __forceinline__ void relaunder(Frame& F) { int t = mk_tid(); asm volatile("" : "+v"(t)); F.tid = t; F.lane = t & 63; F.wave = __builtin_amdgcn_readfirstlane(t >> 6); }
; #define NR_LOAD(dst, k_) do { const GAS v2u* xr_ = (const GAS v2u*)(X + (size_t)(nw + 2048 * (k_)) * D) + F.lane; \
;         _Pragma("unroll") for (int j = 0; j < 8; ++j) dst[j] = __builtin_nontemporal_load(xr_ + 64 * j); } while (0)
; __device__ __forceinline__ void norm_mod_phase2(const Args& a, Frame& F, const float* gain, const float* modl, int sh_off, int sc_off, int nrows, const float* slab_gate) {
;     relaunder(F);
;     static_assert(ML == 8 * 2048 && MC <= 2048, "8 latent rows and at most one context row per wave of 2048");
;     const int nw = F.vcu * NWAVES + F.wave;
;     bf16* X = (bf16*)(a.ws + WS_X); bf16* HN = (bf16*)(a.ws + WS_HN);
;     LAS float* CA = (LAS float*)F.lds; LAS float* CB = CA + 5 * D;
;     v2u r0[8], r1[8], r2[8], r3[8], r4[8], r5[8], r6[8], r7[8];
;     ...
;     NR_LOAD(r0, 0); NR_LOAD(r1, 1); NR_LOAD(r2, 2); NR_LOAD(r3, 3); NR_LOAD(r4, 4); NR_LOAD(r5, 5); NR_LOAD(r6, 6); NR_LOAD(r7, 7);
;     { const GAS f32x4* g4 = (const GAS f32x4*)gain;
;       for (int q = F.tid; q < 5 * D / 4; q += NWAVES * 64) { const int bq = q >> 9, cq = q & 511; const GAS f32x4* mb4 = (const GAS f32x4*)(modl + (size_t)bq * MOD_LD);
;           ((LAS f32x4*)CA)[q] = g4[cq] * (mb4[sc_off / 4 + cq] + 1.0f); ((LAS f32x4*)CB)[q] = mb4[sh_off / 4 + cq]; } }
.LBB0_215:
	s_andn2_b64 vcc, exec, s[4:5]
	s_cbranch_vccnz .LBB0_224
	s_getreg_b32 s4, hwreg(HW_REG_HW_ID, 0, 6)
	s_lshl_b32 s4, s4, 2
	s_add_i32 s4, s4, 0
	s_add_i32 s4, s4, 0x20540
	v_mov_b32_e32 v0, s4
	ds_read_b32 v0, v0
	v_mov_b64_e32 v[2:3], s[0:1]
	v_mbcnt_lo_u32_b32 v4, -1, 0
	v_mbcnt_hi_u32_b32 v4, -1, v4
	s_mov_b64 s[20:21], 0x400000
	v_mov_b32_e32 v7, v1
	s_waitcnt lgkmcnt(0)
	v_readfirstlane_b32 s4, v0
	s_nop 1
	v_lshl_add_u32 v142, s4, 6, v4
	v_mov_b32_e32 v128, s72
	v_mov_b32_e32 v129, s73
	v_readfirstlane_b32 s4, v142
	s_ashr_i32 s4, s4, 6
	s_add_i32 s4, s4, s91
	s_ashr_i32 s5, s4, 31
	s_add_i32 s36, s4, 0x800
	s_add_i32 s30, s4, 0x1000
	s_add_i32 s26, s4, 0x1800
	s_add_i32 s22, s4, 0x2000
	s_add_i32 s18, s4, 0x2800
	v_and_b32_e32 v143, 63, v142
	s_lshl_b64 s[6:7], s[4:5], 12
	s_ashr_i32 s37, s36, 31
	s_ashr_i32 s31, s30, 31
	s_ashr_i32 s27, s26, 31
	s_ashr_i32 s23, s22, 31
	s_ashr_i32 s19, s18, 31
	v_lshlrev_b32_e32 v6, 3, v143
	s_lshl_b64 s[8:9], s[36:37], 12
	s_lshl_b64 s[10:11], s[30:31], 12
	s_lshl_b64 s[12:13], s[26:27], 12
	s_lshl_b64 s[14:15], s[22:23], 12
	s_lshl_b64 s[16:17], s[18:19], 12
	s_waitcnt vmcnt(0) lgkmcnt(0)
	v_lshl_add_u64 v[8:9], v[128:129], 0, s[20:21]
	v_lshl_add_u64 v[2:3], v[8:9], 0, s[6:7]
	v_lshl_add_u64 v[4:5], v[8:9], 0, s[8:9]
	v_lshl_add_u64 v[10:11], v[8:9], 0, s[10:11]
	v_lshl_add_u64 v[12:13], v[8:9], 0, s[12:13]
	v_lshl_add_u64 v[14:15], v[8:9], 0, s[14:15]
	v_lshl_add_u64 v[16:17], v[8:9], 0, s[16:17]
	v_lshl_add_u64 v[2:3], v[2:3], 0, v[6:7]
	v_lshl_add_u64 v[4:5], v[4:5], 0, v[6:7]
	v_lshl_add_u64 v[10:11], v[10:11], 0, v[6:7]
	v_lshl_add_u64 v[12:13], v[12:13], 0, v[6:7]
	v_lshl_add_u64 v[14:15], v[14:15], 0, v[6:7]
	v_lshl_add_u64 v[16:17], v[16:17], 0, v[6:7]
	v_and_b32_e32 v184, 0x1ff, v142
	v_lshlrev_b32_e32 v184, 4, v184
	v_mov_b32_e32 v185, 0
	v_mov_b32_e32 v186, s76
	v_lshlrev_b32_e32 v186, 13, v186
	v_mov_b32_e32 v187, 0
	v_lshl_add_u64 v[188:189], v[74:75], 0, v[186:187]
	v_lshl_add_u64 v[188:189], v[188:189], 0, v[184:185]
	global_load_dwordx4 v[192:195], v[188:189], off
	v_add_u32_e32 v196, 0x2000, v184
	v_mov_b32_e32 v201, v184
	v_add_u32_e32 v197, 0xe000, v184
	v_add_u32_e32 v202, 0xc000, v184
	v_add_u32_e32 v198, 0x1a000, v184
	v_add_u32_e32 v203, 0x18000, v184
	v_add_u32_e32 v199, 0x26000, v184
	v_add_u32_e32 v204, 0x24000, v184
	v_add_u32_e32 v200, 0x32000, v184
	v_add_u32_e32 v205, 0x30000, v184
	global_load_dwordx4 v[208:211], v196, s[86:87]
	global_load_dwordx4 v[228:231], v201, s[86:87]
	global_load_dwordx4 v[212:215], v197, s[86:87]
	global_load_dwordx4 v[232:235], v202, s[86:87]
	global_load_dwordx4 v[216:219], v198, s[86:87]
	global_load_dwordx4 v[236:239], v203, s[86:87]
	global_load_dwordx4 v[220:223], v199, s[86:87]
	global_load_dwordx4 v[240:243], v204, s[86:87]
	global_load_dwordx4 v[224:227], v200, s[86:87]
	global_load_dwordx4 v[244:247], v205, s[86:87]
	global_load_dwordx2 v[140:141], v[2:3], off nt
	global_load_dwordx2 v[138:139], v[2:3], off offset:512 nt
	global_load_dwordx2 v[136:137], v[2:3], off offset:1024 nt
	global_load_dwordx2 v[132:133], v[2:3], off offset:1536 nt
	global_load_dwordx2 v[134:135], v[2:3], off offset:2048 nt
	global_load_dwordx2 v[124:125], v[2:3], off offset:2560 nt
	global_load_dwordx2 v[126:127], v[2:3], off offset:3072 nt
	global_load_dwordx2 v[130:131], v[2:3], off offset:3584 nt
	global_load_dwordx2 v[122:123], v[4:5], off nt
	global_load_dwordx2 v[120:121], v[4:5], off offset:512 nt
	global_load_dwordx2 v[118:119], v[4:5], off offset:1024 nt
	global_load_dwordx2 v[116:117], v[4:5], off offset:1536 nt
	global_load_dwordx2 v[114:115], v[4:5], off offset:2048 nt
	global_load_dwordx2 v[112:113], v[4:5], off offset:2560 nt
	global_load_dwordx2 v[110:111], v[4:5], off offset:3072 nt
	global_load_dwordx2 v[108:109], v[4:5], off offset:3584 nt
	global_load_dwordx2 v[106:107], v[10:11], off nt
	global_load_dwordx2 v[104:105], v[10:11], off offset:512 nt
	global_load_dwordx2 v[102:103], v[10:11], off offset:1024 nt
	global_load_dwordx2 v[100:101], v[10:11], off offset:1536 nt
	global_load_dwordx2 v[98:99], v[10:11], off offset:2048 nt
	global_load_dwordx2 v[96:97], v[10:11], off offset:2560 nt
	global_load_dwordx2 v[94:95], v[10:11], off offset:3072 nt
	global_load_dwordx2 v[92:93], v[10:11], off offset:3584 nt
	global_load_dwordx2 v[90:91], v[12:13], off nt
	global_load_dwordx2 v[88:89], v[12:13], off offset:512 nt
	global_load_dwordx2 v[86:87], v[12:13], off offset:1024 nt
	global_load_dwordx2 v[84:85], v[12:13], off offset:1536 nt
	global_load_dwordx2 v[82:83], v[12:13], off offset:2048 nt
	global_load_dwordx2 v[80:81], v[12:13], off offset:2560 nt
	global_load_dwordx2 v[78:79], v[12:13], off offset:3072 nt
	global_load_dwordx2 v[76:77], v[12:13], off offset:3584 nt
	global_load_dwordx2 v[72:73], v[14:15], off nt
	global_load_dwordx2 v[70:71], v[14:15], off offset:512 nt
	global_load_dwordx2 v[68:69], v[14:15], off offset:1024 nt
	global_load_dwordx2 v[66:67], v[14:15], off offset:1536 nt
	global_load_dwordx2 v[64:65], v[14:15], off offset:2048 nt
	global_load_dwordx2 v[62:63], v[14:15], off offset:2560 nt
	global_load_dwordx2 v[60:61], v[14:15], off offset:3072 nt
	global_load_dwordx2 v[58:59], v[14:15], off offset:3584 nt
	global_load_dwordx2 v[56:57], v[16:17], off nt
	global_load_dwordx2 v[54:55], v[16:17], off offset:512 nt
	global_load_dwordx2 v[52:53], v[16:17], off offset:1024 nt
	global_load_dwordx2 v[50:51], v[16:17], off offset:1536 nt
	global_load_dwordx2 v[48:49], v[16:17], off offset:2048 nt
	global_load_dwordx2 v[46:47], v[16:17], off offset:2560 nt
	global_load_dwordx2 v[44:45], v[16:17], off offset:3072 nt
	global_load_dwordx2 v[42:43], v[16:17], off offset:3584 nt
	s_add_i32 s14, s4, 0x3000
	s_ashr_i32 s15, s14, 31
	s_lshl_b64 s[6:7], s[14:15], 12
	s_add_i32 s10, s4, 0x3800
	v_lshl_add_u64 v[2:3], v[8:9], 0, s[6:7]
	s_ashr_i32 s11, s10, 31
	v_lshl_add_u64 v[2:3], v[2:3], 0, v[6:7]
	s_lshl_b64 s[6:7], s[10:11], 12
	global_load_dwordx2 v[40:41], v[2:3], off nt
	global_load_dwordx2 v[38:39], v[2:3], off offset:512 nt
	global_load_dwordx2 v[36:37], v[2:3], off offset:1024 nt
	global_load_dwordx2 v[34:35], v[2:3], off offset:1536 nt
	global_load_dwordx2 v[32:33], v[2:3], off offset:2048 nt
	global_load_dwordx2 v[30:31], v[2:3], off offset:2560 nt
	global_load_dwordx2 v[28:29], v[2:3], off offset:3072 nt
	global_load_dwordx2 v[26:27], v[2:3], off offset:3584 nt
	v_lshl_add_u64 v[2:3], v[8:9], 0, s[6:7]
	v_lshl_add_u64 v[2:3], v[2:3], 0, v[6:7]
	global_load_dwordx2 v[24:25], v[2:3], off nt
	global_load_dwordx2 v[22:23], v[2:3], off offset:512 nt
	global_load_dwordx2 v[20:21], v[2:3], off offset:1024 nt
	global_load_dwordx2 v[18:19], v[2:3], off offset:1536 nt
	global_load_dwordx2 v[16:17], v[2:3], off offset:2048 nt
	global_load_dwordx2 v[14:15], v[2:3], off offset:2560 nt
	global_load_dwordx2 v[12:13], v[2:3], off offset:3072 nt
	global_load_dwordx2 v[10:11], v[2:3], off offset:3584 nt
	s_waitcnt vmcnt(62)
; #define GAS __attribute__((address_space(1)))
; #define LAS __attribute__((address_space(3)))
; __device__ __forceinline__ void norm_mod_phase2(const Args& a, Frame& F, const float* gain, const float* modl, int sh_off, int sc_off, int nrows, const float* slab_gate) {
;     ...
;       for (int q = F.tid; q < 5 * D / 4; q += NWAVES * 64) { const int bq = q >> 9, cq = q & 511; const GAS f32x4* mb4 = (const GAS f32x4*)(modl + (size_t)bq * MOD_LD);
;           ((LAS f32x4*)CA)[q] = g4[cq] * (mb4[sc_off / 4 + cq] + 1.0f); ((LAS f32x4*)CB)[q] = mb4[sh_off / 4 + cq]; } }
;     asm volatile("s_waitcnt lgkmcnt(0)" ::: "memory"); __builtin_amdgcn_s_barrier(); asm volatile("" ::: "memory");
	v_lshl_add_u32 v184, v142, 4, 0
	v_add_u32_e32 v185, 0xa000, v184
	v_pk_add_f32 v[210:211], v[210:211], 1.0 op_sel_hi:[1,0]
	v_pk_add_f32 v[208:209], v[208:209], 1.0 op_sel_hi:[1,0]
	v_pk_mul_f32 v[210:211], v[194:195], v[210:211]
	v_pk_mul_f32 v[208:209], v[192:193], v[208:209]
	ds_write_b128 v184, v[208:211]
	ds_write_b128 v185, v[228:231]
	v_pk_add_f32 v[214:215], v[214:215], 1.0 op_sel_hi:[1,0]
	v_pk_add_f32 v[212:213], v[212:213], 1.0 op_sel_hi:[1,0]
	v_pk_mul_f32 v[214:215], v[194:195], v[214:215]
	v_pk_mul_f32 v[212:213], v[192:193], v[212:213]
	ds_write_b128 v184, v[212:215] offset:8192
	ds_write_b128 v185, v[232:235] offset:8192
	v_pk_add_f32 v[218:219], v[218:219], 1.0 op_sel_hi:[1,0]
	v_pk_add_f32 v[216:217], v[216:217], 1.0 op_sel_hi:[1,0]
	v_pk_mul_f32 v[218:219], v[194:195], v[218:219]
	v_pk_mul_f32 v[216:217], v[192:193], v[216:217]
	ds_write_b128 v184, v[216:219] offset:16384
	ds_write_b128 v185, v[236:239] offset:16384
	v_pk_add_f32 v[222:223], v[222:223], 1.0 op_sel_hi:[1,0]
	v_pk_add_f32 v[220:221], v[220:221], 1.0 op_sel_hi:[1,0]
	v_pk_mul_f32 v[222:223], v[194:195], v[222:223]
	v_pk_mul_f32 v[220:221], v[192:193], v[220:221]
	ds_write_b128 v184, v[220:223] offset:24576
	ds_write_b128 v185, v[240:243] offset:24576
	v_pk_add_f32 v[226:227], v[226:227], 1.0 op_sel_hi:[1,0]
	v_pk_add_f32 v[224:225], v[224:225], 1.0 op_sel_hi:[1,0]
	v_pk_mul_f32 v[226:227], v[194:195], v[226:227]
	v_pk_mul_f32 v[224:225], v[192:193], v[224:225]
	ds_write_b128 v184, v[224:227] offset:32768
	ds_write_b128 v185, v[244:247] offset:32768
	s_waitcnt vmcnt(62)
	v_cvt_f32_f16_sdwa v153, v140 dst_sel:DWORD dst_unused:UNUSED_PAD src0_sel:WORD_1
	v_cvt_f32_f16_sdwa v149, v138 dst_sel:DWORD dst_unused:UNUSED_PAD src0_sel:WORD_1
	v_cvt_f32_f16_e32 v152, v140
	v_cvt_f32_f16_sdwa v155, v141 dst_sel:DWORD dst_unused:UNUSED_PAD src0_sel:WORD_1
	v_cvt_f32_f16_e32 v148, v138
	v_cvt_f32_f16_sdwa v151, v139 dst_sel:DWORD dst_unused:UNUSED_PAD src0_sel:WORD_1
	v_cvt_f32_f16_e32 v154, v141
	v_cvt_f32_f16_e32 v150, v139
	s_waitcnt vmcnt(61)
	v_cvt_f32_f16_sdwa v139, v136 dst_sel:DWORD dst_unused:UNUSED_PAD src0_sel:WORD_1
	v_cvt_f32_f16_sdwa v141, v137 dst_sel:DWORD dst_unused:UNUSED_PAD src0_sel:WORD_1
	s_mov_b64 s[6:7], 0x8c00000
	v_mov_b32_e32 v74, v153
	v_mov_b32_e32 v75, v149
	v_cvt_f32_f16_e32 v138, v136
	v_cvt_f32_f16_e32 v140, v137
	v_lshl_add_u64 v[2:3], v[128:129], 0, s[6:7]
	v_mov_b32_e32 v4, v152
	v_mov_b32_e32 v5, v148
	v_pk_mul_f32 v[74:75], v[74:75], v[74:75]
	v_mov_b32_e32 v128, v155
	v_mov_b32_e32 v129, v151
	v_pk_fma_f32 v[4:5], v[4:5], v[4:5], v[74:75]
	v_mov_b32_e32 v74, v154
	v_mov_b32_e32 v75, v150
	v_pk_mul_f32 v[128:129], v[128:129], v[128:129]
	s_waitcnt vmcnt(60)
	v_cvt_f32_f16_sdwa v145, v132 dst_sel:DWORD dst_unused:UNUSED_PAD src0_sel:WORD_1
	v_pk_fma_f32 v[74:75], v[74:75], v[74:75], v[128:129]
	v_mov_b32_e32 v128, v139
	v_mov_b32_e32 v129, v141
	v_pk_add_f32 v[4:5], v[4:5], v[74:75]
	v_mov_b32_e32 v74, v138
	v_mov_b32_e32 v75, v140
	v_pk_mul_f32 v[128:129], v[128:129], v[128:129]
	v_cvt_f32_f16_e32 v144, v132
	v_cvt_f32_f16_sdwa v147, v133 dst_sel:DWORD dst_unused:UNUSED_PAD src0_sel:WORD_1
	v_pk_fma_f32 v[74:75], v[74:75], v[74:75], v[128:129]
	v_cvt_f32_f16_e32 v146, v133
	s_waitcnt vmcnt(59)
	v_cvt_f32_f16_sdwa v129, v134 dst_sel:DWORD dst_unused:UNUSED_PAD src0_sel:WORD_1
	v_cvt_f32_f16_e32 v128, v134
	v_cvt_f32_f16_sdwa v133, v135 dst_sel:DWORD dst_unused:UNUSED_PAD src0_sel:WORD_1
	v_cvt_f32_f16_e32 v132, v135
	v_mul_f32_e32 v0, v145, v145
	v_pk_fma_f32 v[136:137], v[144:145], v[144:145], v[0:1] op_sel_hi:[1,1,0]
	v_mul_f32_e32 v0, v147, v147
	v_pk_add_f32 v[4:5], v[4:5], v[4:5] op_sel:[0,1] op_sel_hi:[1,0]
	v_pk_add_f32 v[74:75], v[74:75], v[74:75] op_sel:[0,1] op_sel_hi:[1,0]
	v_pk_fma_f32 v[156:157], v[146:147], v[146:147], v[0:1] op_sel_hi:[1,1,0]
	v_pk_mul_f32 v[134:135], v[128:129], v[128:129]
	v_pk_mul_f32 v[158:159], v[132:133], v[132:133]
	v_mov_b32_e32 v5, v134
	v_mov_b32_e32 v75, v135
	v_mov_b32_e32 v137, v158
	v_mov_b32_e32 v157, v159
	v_pk_add_f32 v[4:5], v[4:5], v[74:75]
	v_pk_add_f32 v[74:75], v[136:137], v[156:157]
	s_waitcnt vmcnt(58)
	v_cvt_f32_f16_sdwa v135, v124 dst_sel:DWORD dst_unused:UNUSED_PAD src0_sel:WORD_1
	v_cvt_f32_f16_sdwa v137, v125 dst_sel:DWORD dst_unused:UNUSED_PAD src0_sel:WORD_1
	v_cvt_f32_f16_e32 v134, v124
	v_cvt_f32_f16_e32 v136, v125
	v_pk_add_f32 v[4:5], v[4:5], v[74:75]
	v_mov_b32_e32 v74, v135
	v_mov_b32_e32 v75, v137
	v_pk_add_f32 v[156:157], v[4:5], v[4:5] op_sel:[0,1] op_sel_hi:[1,0]
	v_mov_b32_e32 v4, v134
	v_mov_b32_e32 v5, v136
	v_pk_mul_f32 v[74:75], v[74:75], v[74:75]
	s_waitcnt vmcnt(57)
	v_cvt_f32_f16_sdwa v125, v127 dst_sel:DWORD dst_unused:UNUSED_PAD src0_sel:WORD_1
	v_pk_fma_f32 v[4:5], v[4:5], v[4:5], v[74:75]
	v_cvt_f32_f16_e32 v124, v127
	v_pk_add_f32 v[158:159], v[4:5], v[4:5] op_sel:[0,1] op_sel_hi:[1,0]
	v_cvt_f32_f16_sdwa v5, v126 dst_sel:DWORD dst_unused:UNUSED_PAD src0_sel:WORD_1
	v_cvt_f32_f16_e32 v4, v126
	s_waitcnt vmcnt(56)
	v_cvt_f32_f16_sdwa v75, v130 dst_sel:DWORD dst_unused:UNUSED_PAD src0_sel:WORD_1
	v_cvt_f32_f16_e32 v74, v130
	v_cvt_f32_f16_sdwa v127, v131 dst_sel:DWORD dst_unused:UNUSED_PAD src0_sel:WORD_1
	v_cvt_f32_f16_e32 v126, v131
	v_mul_f32_e32 v0, v5, v5
	v_pk_fma_f32 v[160:161], v[4:5], v[4:5], v[0:1] op_sel_hi:[1,1,0]
	v_mul_f32_e32 v0, v125, v125
	v_pk_fma_f32 v[162:163], v[124:125], v[124:125], v[0:1] op_sel_hi:[1,1,0]
	v_pk_mul_f32 v[130:131], v[74:75], v[74:75]
	v_pk_mul_f32 v[164:165], v[126:127], v[126:127]
	v_mov_b32_e32 v157, v130
	v_mov_b32_e32 v159, v131
	v_mov_b32_e32 v161, v164
	v_mov_b32_e32 v163, v165
	v_pk_add_f32 v[130:131], v[156:157], v[158:159]
	v_pk_add_f32 v[156:157], v[160:161], v[162:163]
	s_lshl_b64 s[8:9], s[4:5], 11
	v_pk_add_f32 v[130:131], v[130:131], v[156:157]
	s_lshl_b64 s[12:13], s[10:11], 11
	v_add_f32_e32 v0, v130, v131
	s_waitcnt lgkmcnt(0)
	s_barrier
; __device__ __forceinline__ void norm_mod_phase2(const Args& a, Frame& F, const float* gain, const float* modl, int sh_off, int sc_off, int nrows, const float* slab_gate) {
;     ...
;     NR_FINISH(r0, nw,            (nw) >> 12);
	s_lshl_b64 s[40:41], s[36:37], 11
	v_add_f32_dpp v0, v0, v0 quad_perm:[1,0,3,2] row_mask:0xf bank_mask:0xf bound_ctrl:1
	s_lshl_b64 s[34:35], s[30:31], 11
	s_lshl_b64 s[28:29], s[26:27], 11
	v_add_f32_dpp v0, v0, v0 quad_perm:[2,3,0,1] row_mask:0xf bank_mask:0xf bound_ctrl:1
	s_lshl_b64 s[24:25], s[22:23], 11
	s_lshl_b64 s[20:21], s[18:19], 11
	v_add_f32_dpp v0, v0, v0 row_half_mirror row_mask:0xf bank_mask:0xf bound_ctrl:1
	s_lshl_b64 s[16:17], s[14:15], 11
	s_nop 0
	v_add_f32_dpp v0, v0, v0 row_mirror row_mask:0xf bank_mask:0xf bound_ctrl:1
	s_nop 0
	v_readlane_b32 s5, v0, 16
	v_readlane_b32 s11, v0, 48
	v_readlane_b32 s6, v0, 0
	v_readlane_b32 s7, v0, 32
	v_mov_b32_e32 v130, s5
	v_mov_b32_e32 v131, s11
	v_pk_add_f32 v[130:131], s[6:7], v[130:131]
	s_lshl_b32 s5, s4, 1
	v_add_f32_e32 v0, v130, v131
	v_fmamk_f32 v0, v0, 0x3a000000, v252
	v_cmp_gt_f32_e32 vcc, s55, v0
	v_mul_f32_e32 v7, 0x4f800000, v0
	s_and_b32 s5, s5, 0xffffe000
	v_cndmask_b32_e32 v0, v0, v7, vcc
	v_sqrt_f32_e32 v7, v0
	s_add_i32 s5, s5, 0
	v_add_u32_e32 v130, -1, v7
	v_fma_f32 v131, -v130, v7, v0
	v_cmp_ge_f32_e64 s[6:7], 0, v131
	v_add_u32_e32 v131, 1, v7
	s_nop 0
	v_cndmask_b32_e64 v130, v7, v130, s[6:7]
	v_fma_f32 v7, -v131, v7, v0
	v_cmp_lt_f32_e64 s[6:7], 0, v7
	s_nop 1
	v_cndmask_b32_e64 v7, v130, v131, s[6:7]
	v_mul_f32_e32 v130, 0x37800000, v7
	v_cndmask_b32_e32 v7, v7, v130, vcc
	v_cmp_class_f32_e32 vcc, v0, v253
	s_nop 1
	v_cndmask_b32_e32 v0, v7, v0, vcc
	v_div_scale_f32 v7, s[6:7], v0, v0, 1.0
	v_rcp_f32_e32 v130, v7
	s_nop 0
	v_fma_f32 v131, -v7, v130, 1.0
	v_fmac_f32_e32 v130, v131, v130
	v_div_scale_f32 v131, vcc, 1.0, v0, 1.0
	v_mul_f32_e32 v142, v131, v130
	v_fma_f32 v156, -v7, v142, v131
	v_fmac_f32_e32 v142, v156, v130
	v_fma_f32 v7, -v7, v142, v131
	v_div_fmas_f32 v7, v7, v130, v142
	v_div_fixup_f32 v142, v7, v0, 1.0
	v_lshlrev_b32_e32 v0, 4, v143
	v_add_u32_e32 v164, s5, v0
	v_pk_mul_f32 v[160:161], v[152:153], v[142:143] op_sel_hi:[1,0]
	v_pk_mul_f32 v[162:163], v[154:155], v[142:143] op_sel_hi:[1,0]
	ds_read_b128 v[152:155], v164
	ds_read_b128 v[156:159], v164 offset:40960
	v_lshl_add_u64 v[130:131], s[8:9], 1, v[2:3]
	v_mov_b32_e32 v7, v1
	v_lshl_add_u64 v[130:131], v[130:131], 0, v[6:7]
	v_pk_mul_f32 v[128:129], v[128:129], v[142:143] op_sel_hi:[1,0]
	s_waitcnt lgkmcnt(0)
	v_pk_fma_f32 v[154:155], v[154:155], v[162:163], v[158:159]
	v_pk_fma_f32 v[152:153], v[152:153], v[160:161], v[156:157]
	v_pk_mul_f32 v[156:157], v[148:149], v[142:143] op_sel_hi:[1,0]
	v_cvt_pk_bf16_f32 v152, v152, v153
	v_cvt_pk_bf16_f32 v153, v154, v155
	global_store_dwordx2 v[130:131], v[152:153], off nt
	v_pk_mul_f32 v[158:159], v[150:151], v[142:143] op_sel_hi:[1,0]
	ds_read_b128 v[148:151], v164 offset:1024
	ds_read_b128 v[152:155], v164 offset:41984
	v_pk_mul_f32 v[132:133], v[132:133], v[142:143] op_sel_hi:[1,0]
	v_pk_mul_f32 v[4:5], v[4:5], v[142:143] op_sel_hi:[1,0]
	v_pk_mul_f32 v[124:125], v[124:125], v[142:143] op_sel_hi:[1,0]
	s_waitcnt lgkmcnt(0)
	v_pk_fma_f32 v[150:151], v[150:151], v[158:159], v[154:155]
	v_pk_fma_f32 v[148:149], v[148:149], v[156:157], v[152:153]
	v_pk_mul_f32 v[152:153], v[138:139], v[142:143] op_sel_hi:[1,0]
	v_cvt_pk_bf16_f32 v148, v148, v149
	v_cvt_pk_bf16_f32 v149, v150, v151
	global_store_dwordx2 v[130:131], v[148:149], off offset:512 nt
	v_pk_mul_f32 v[154:155], v[140:141], v[142:143] op_sel_hi:[1,0]
	ds_read_b128 v[138:141], v164 offset:2048
	ds_read_b128 v[148:151], v164 offset:43008
	s_waitcnt lgkmcnt(0)
	v_pk_fma_f32 v[140:141], v[140:141], v[154:155], v[150:151]
	v_pk_fma_f32 v[138:139], v[138:139], v[152:153], v[148:149]
	v_pk_mul_f32 v[148:149], v[144:145], v[142:143] op_sel_hi:[1,0]
	v_cvt_pk_bf16_f32 v138, v138, v139
	v_cvt_pk_bf16_f32 v139, v140, v141
	global_store_dwordx2 v[130:131], v[138:139], off offset:1024 nt
	v_pk_mul_f32 v[150:151], v[146:147], v[142:143] op_sel_hi:[1,0]
	ds_read_b128 v[138:141], v164 offset:3072
	ds_read_b128 v[144:147], v164 offset:44032
	s_waitcnt lgkmcnt(0)
	v_pk_fma_f32 v[140:141], v[150:151], v[140:141], v[146:147]
	v_pk_fma_f32 v[138:139], v[148:149], v[138:139], v[144:145]
	s_nop 0
	v_cvt_pk_bf16_f32 v138, v138, v139
	v_cvt_pk_bf16_f32 v139, v140, v141
	global_store_dwordx2 v[130:131], v[138:139], off offset:1536 nt
	ds_read_b128 v[138:141], v164 offset:4096
	ds_read_b128 v[144:147], v164 offset:45056
	s_waitcnt lgkmcnt(0)
	v_pk_fma_f32 v[132:133], v[132:133], v[140:141], v[146:147]
	v_pk_fma_f32 v[128:129], v[128:129], v[138:139], v[144:145]
	v_pk_mul_f32 v[140:141], v[136:137], v[142:143] op_sel_hi:[1,0]
	v_cvt_pk_bf16_f32 v128, v128, v129
	v_cvt_pk_bf16_f32 v129, v132, v133
	global_store_dwordx2 v[130:131], v[128:129], off offset:2048 nt
	v_pk_mul_f32 v[128:129], v[134:135], v[142:143] op_sel_hi:[1,0]
	ds_read_b128 v[132:135], v164 offset:5120
	ds_read_b128 v[136:139], v164 offset:46080
	s_waitcnt lgkmcnt(0)
	v_pk_fma_f32 v[134:135], v[140:141], v[134:135], v[138:139]
	v_pk_fma_f32 v[128:129], v[128:129], v[132:133], v[136:137]
	s_nop 0
	v_cvt_pk_bf16_f32 v128, v128, v129
	v_cvt_pk_bf16_f32 v129, v134, v135
	global_store_dwordx2 v[130:131], v[128:129], off offset:2560 nt
	ds_read_b128 v[132:135], v164 offset:6144
	ds_read_b128 v[136:139], v164 offset:47104
	s_waitcnt vmcnt(58)
	v_cvt_f32_f16_sdwa v129, v117 dst_sel:DWORD dst_unused:UNUSED_PAD src0_sel:WORD_1
	v_cvt_f32_f16_e32 v128, v117
	s_waitcnt lgkmcnt(0)
; __device__ __forceinline__ void norm_mod_phase2(const Args& a, Frame& F, const float* gain, const float* modl, int sh_off, int sc_off, int nrows, const float* slab_gate) {
;     ...
;     NR_FINISH(r1, nw + 2048,     (nw + 2048) >> 12);
	v_pk_fma_f32 v[124:125], v[124:125], v[134:135], v[138:139]
	v_pk_fma_f32 v[4:5], v[4:5], v[132:133], v[136:137]
	v_cvt_f32_f16_sdwa v137, v122 dst_sel:DWORD dst_unused:UNUSED_PAD src0_sel:WORD_1
	v_cvt_pk_bf16_f32 v4, v4, v5
	v_cvt_pk_bf16_f32 v5, v124, v125
	global_store_dwordx2 v[130:131], v[4:5], off offset:3072 nt
	v_pk_mul_f32 v[4:5], v[74:75], v[142:143] op_sel_hi:[1,0]
	v_pk_mul_f32 v[74:75], v[126:127], v[142:143] op_sel_hi:[1,0]
	ds_read_b128 v[124:127], v164 offset:7168
	ds_read_b128 v[132:135], v164 offset:48128
	v_cvt_f32_f16_e32 v136, v122
	v_cvt_f32_f16_sdwa v139, v123 dst_sel:DWORD dst_unused:UNUSED_PAD src0_sel:WORD_1
	v_cvt_f32_f16_e32 v138, v123
	v_cvt_f32_f16_sdwa v123, v118 dst_sel:DWORD dst_unused:UNUSED_PAD src0_sel:WORD_1
	s_waitcnt lgkmcnt(0)
	v_pk_fma_f32 v[4:5], v[4:5], v[124:125], v[132:133]
	v_cvt_f32_f16_sdwa v133, v120 dst_sel:DWORD dst_unused:UNUSED_PAD src0_sel:WORD_1
	v_pk_fma_f32 v[74:75], v[74:75], v[126:127], v[134:135]
	v_cvt_f32_f16_e32 v132, v120
	v_cvt_f32_f16_sdwa v135, v121 dst_sel:DWORD dst_unused:UNUSED_PAD src0_sel:WORD_1
	v_cvt_f32_f16_e32 v134, v121
	v_cvt_f32_f16_sdwa v125, v119 dst_sel:DWORD dst_unused:UNUSED_PAD src0_sel:WORD_1
	v_cvt_f32_f16_sdwa v127, v116 dst_sel:DWORD dst_unused:UNUSED_PAD src0_sel:WORD_1
	v_cvt_pk_bf16_f32 v4, v4, v5
	v_cvt_pk_bf16_f32 v5, v74, v75
	v_mov_b32_e32 v74, v137
	v_mov_b32_e32 v75, v133
	v_cvt_f32_f16_e32 v122, v118
	v_cvt_f32_f16_e32 v124, v119
	v_cvt_f32_f16_e32 v126, v116
	global_store_dwordx2 v[130:131], v[4:5], off offset:3584 nt
	v_mov_b32_e32 v4, v136
	v_mov_b32_e32 v5, v132
	v_pk_mul_f32 v[74:75], v[74:75], v[74:75]
	v_mov_b32_e32 v120, v139
	v_mov_b32_e32 v121, v135
	v_pk_fma_f32 v[4:5], v[4:5], v[4:5], v[74:75]
	v_mov_b32_e32 v74, v138
	v_mov_b32_e32 v75, v134
	v_pk_mul_f32 v[120:121], v[120:121], v[120:121]
	v_mov_b32_e32 v118, v123
	v_pk_fma_f32 v[74:75], v[74:75], v[74:75], v[120:121]
	v_mov_b32_e32 v119, v125
	v_mul_f32_e32 v116, v127, v127
	v_pk_add_f32 v[4:5], v[4:5], v[74:75]
	v_mov_b32_e32 v74, v122
	v_mov_b32_e32 v75, v124
	v_pk_mul_f32 v[118:119], v[118:119], v[118:119]
	v_pk_fma_f32 v[120:121], v[126:127], v[126:127], v[116:117] op_sel_hi:[1,1,0]
	v_mul_f32_e32 v116, v129, v129
	v_pk_fma_f32 v[74:75], v[74:75], v[74:75], v[118:119]
	v_pk_fma_f32 v[130:131], v[128:129], v[128:129], v[116:117] op_sel_hi:[1,1,0]
	s_waitcnt vmcnt(59)
	v_cvt_f32_f16_sdwa v117, v114 dst_sel:DWORD dst_unused:UNUSED_PAD src0_sel:WORD_1
	v_cvt_f32_f16_e32 v116, v114
	v_cvt_f32_f16_sdwa v119, v115 dst_sel:DWORD dst_unused:UNUSED_PAD src0_sel:WORD_1
	v_cvt_f32_f16_e32 v118, v115
	v_pk_add_f32 v[4:5], v[4:5], v[4:5] op_sel:[0,1] op_sel_hi:[1,0]
	v_pk_add_f32 v[74:75], v[74:75], v[74:75] op_sel:[0,1] op_sel_hi:[1,0]
	v_pk_mul_f32 v[114:115], v[116:117], v[116:117]
	v_pk_mul_f32 v[140:141], v[118:119], v[118:119]
	v_mov_b32_e32 v5, v114
	v_mov_b32_e32 v75, v115
	v_mov_b32_e32 v121, v140
	v_mov_b32_e32 v131, v141
	v_pk_add_f32 v[4:5], v[4:5], v[74:75]
	v_pk_add_f32 v[74:75], v[120:121], v[130:131]
	s_waitcnt vmcnt(58)
	v_cvt_f32_f16_sdwa v115, v112 dst_sel:DWORD dst_unused:UNUSED_PAD src0_sel:WORD_1
	v_cvt_f32_f16_sdwa v121, v113 dst_sel:DWORD dst_unused:UNUSED_PAD src0_sel:WORD_1
	v_cvt_f32_f16_e32 v114, v112
	v_cvt_f32_f16_e32 v120, v113
	v_pk_add_f32 v[4:5], v[4:5], v[74:75]
	v_mov_b32_e32 v74, v115
	v_mov_b32_e32 v75, v121
	v_pk_add_f32 v[130:131], v[4:5], v[4:5] op_sel:[0,1] op_sel_hi:[1,0]
	v_mov_b32_e32 v4, v114
	v_mov_b32_e32 v5, v120
	v_pk_mul_f32 v[74:75], v[74:75], v[74:75]
	s_waitcnt vmcnt(57)
	v_cvt_f32_f16_sdwa v113, v111 dst_sel:DWORD dst_unused:UNUSED_PAD src0_sel:WORD_1
	v_pk_fma_f32 v[4:5], v[4:5], v[4:5], v[74:75]
	v_cvt_f32_f16_e32 v112, v111
	v_pk_add_f32 v[140:141], v[4:5], v[4:5] op_sel:[0,1] op_sel_hi:[1,0]
	v_cvt_f32_f16_sdwa v5, v110 dst_sel:DWORD dst_unused:UNUSED_PAD src0_sel:WORD_1
	v_cvt_f32_f16_e32 v4, v110
	s_waitcnt vmcnt(56)
	v_cvt_f32_f16_sdwa v111, v109 dst_sel:DWORD dst_unused:UNUSED_PAD src0_sel:WORD_1
	v_cvt_f32_f16_e32 v110, v109
	v_mul_f32_e32 v74, v5, v5
	v_pk_fma_f32 v[144:145], v[4:5], v[4:5], v[74:75] op_sel_hi:[1,1,0]
	v_mul_f32_e32 v74, v113, v113
	v_pk_fma_f32 v[146:147], v[112:113], v[112:113], v[74:75] op_sel_hi:[1,1,0]
	v_cvt_f32_f16_sdwa v75, v108 dst_sel:DWORD dst_unused:UNUSED_PAD src0_sel:WORD_1
	v_cvt_f32_f16_e32 v74, v108
	v_pk_mul_f32 v[148:149], v[110:111], v[110:111]
	v_pk_mul_f32 v[108:109], v[74:75], v[74:75]
	s_nop 0
	v_mov_b32_e32 v131, v108
	v_mov_b32_e32 v141, v109
	v_mov_b32_e32 v145, v148
	v_mov_b32_e32 v147, v149
	v_pk_add_f32 v[108:109], v[130:131], v[140:141]
	v_pk_add_f32 v[130:131], v[144:145], v[146:147]
	s_nop 0
	v_pk_add_f32 v[108:109], v[108:109], v[130:131]
	s_nop 0
	v_add_f32_e32 v108, v108, v109
	s_nop 1
	v_add_f32_dpp v108, v108, v108 quad_perm:[1,0,3,2] row_mask:0xf bank_mask:0xf bound_ctrl:1
	s_nop 1
	v_add_f32_dpp v108, v108, v108 quad_perm:[2,3,0,1] row_mask:0xf bank_mask:0xf bound_ctrl:1
	s_nop 1
	v_add_f32_dpp v108, v108, v108 row_half_mirror row_mask:0xf bank_mask:0xf bound_ctrl:1
	s_nop 1
	v_add_f32_dpp v108, v108, v108 row_mirror row_mask:0xf bank_mask:0xf bound_ctrl:1
	s_nop 0
	v_readlane_b32 s5, v108, 16
	v_readlane_b32 s11, v108, 48
	v_readlane_b32 s6, v108, 0
	v_readlane_b32 s7, v108, 32
	v_mov_b32_e32 v108, s5
	v_mov_b32_e32 v109, s11
	v_pk_add_f32 v[108:109], s[6:7], v[108:109]
	s_lshl_b32 s5, s36, 1
	v_add_f32_e32 v108, v108, v109
	v_fmamk_f32 v108, v108, 0x3a000000, v252
	v_cmp_gt_f32_e32 vcc, s55, v108
	v_mul_f32_e32 v109, 0x4f800000, v108
	s_and_b32 s5, s5, 0xffffe000
	v_cndmask_b32_e32 v108, v108, v109, vcc
	v_sqrt_f32_e32 v109, v108
	s_add_i32 s5, s5, 0
	v_add_u32_e32 v130, -1, v109
	v_fma_f32 v131, -v130, v109, v108
	v_cmp_ge_f32_e64 s[6:7], 0, v131
	v_add_u32_e32 v131, 1, v109
	s_nop 0
	v_cndmask_b32_e64 v130, v109, v130, s[6:7]
	v_fma_f32 v109, -v131, v109, v108
	v_cmp_lt_f32_e64 s[6:7], 0, v109
	s_nop 1
	v_cndmask_b32_e64 v109, v130, v131, s[6:7]
	v_mul_f32_e32 v130, 0x37800000, v109
	v_cndmask_b32_e32 v109, v109, v130, vcc
	v_cmp_class_f32_e32 vcc, v108, v253
	s_nop 1
	v_cndmask_b32_e32 v108, v109, v108, vcc
	v_div_scale_f32 v109, s[6:7], v108, v108, 1.0
	v_rcp_f32_e32 v130, v109
	s_nop 0
	v_fma_f32 v131, -v109, v130, 1.0
	v_fmac_f32_e32 v130, v131, v130
	v_div_scale_f32 v131, vcc, 1.0, v108, 1.0
	v_mul_f32_e32 v140, v131, v130
	v_fma_f32 v141, -v109, v140, v131
	v_fmac_f32_e32 v140, v141, v130
	v_fma_f32 v109, -v109, v140, v131
	v_div_fmas_f32 v109, v109, v130, v140
	v_div_fixup_f32 v130, v109, v108, 1.0
	v_pk_mul_f32 v[140:141], v[136:137], v[130:131] op_sel_hi:[1,0]
	v_pk_mul_f32 v[148:149], v[138:139], v[130:131] op_sel_hi:[1,0]
	v_add_u32_e32 v131, s5, v0
	ds_read_b128 v[136:139], v131
	ds_read_b128 v[144:147], v131 offset:40960
	v_lshl_add_u64 v[108:109], s[40:41], 1, v[2:3]
	v_lshl_add_u64 v[108:109], v[108:109], 0, v[6:7]
	v_pk_mul_f32 v[4:5], v[4:5], v[130:131] op_sel_hi:[1,0]
	s_waitcnt lgkmcnt(0)
; __device__ __forceinline__ void norm_mod_phase2(const Args& a, Frame& F, const float* gain, const float* modl, int sh_off, int sc_off, int nrows, const float* slab_gate) {
;     ...
;     NR_FINISH(r1, nw + 2048,     (nw + 2048) >> 12);
;     NR_FINISH(r2, nw + 2 * 2048, (nw + 2 * 2048) >> 12);
	v_pk_fma_f32 v[138:139], v[138:139], v[148:149], v[146:147]
	v_pk_fma_f32 v[136:137], v[136:137], v[140:141], v[144:145]
	v_pk_mul_f32 v[140:141], v[132:133], v[130:131] op_sel_hi:[1,0]
	v_cvt_pk_bf16_f32 v136, v136, v137
	v_cvt_pk_bf16_f32 v137, v138, v139
	global_store_dwordx2 v[108:109], v[136:137], off nt
	v_pk_mul_f32 v[144:145], v[134:135], v[130:131] op_sel_hi:[1,0]
	ds_read_b128 v[132:135], v131 offset:1024
	ds_read_b128 v[136:139], v131 offset:41984
	s_waitcnt lgkmcnt(0)
	v_pk_fma_f32 v[134:135], v[134:135], v[144:145], v[138:139]
	v_pk_fma_f32 v[132:133], v[132:133], v[140:141], v[136:137]
	v_pk_mul_f32 v[136:137], v[122:123], v[130:131] op_sel_hi:[1,0]
	v_cvt_pk_bf16_f32 v132, v132, v133
	v_cvt_pk_bf16_f32 v133, v134, v135
	global_store_dwordx2 v[108:109], v[132:133], off offset:512 nt
	v_pk_mul_f32 v[138:139], v[124:125], v[130:131] op_sel_hi:[1,0]
	ds_read_b128 v[122:125], v131 offset:2048
	ds_read_b128 v[132:135], v131 offset:43008
	s_waitcnt lgkmcnt(0)
	v_pk_fma_f32 v[124:125], v[124:125], v[138:139], v[134:135]
	v_pk_fma_f32 v[122:123], v[122:123], v[136:137], v[132:133]
	v_pk_mul_f32 v[132:133], v[126:127], v[130:131] op_sel_hi:[1,0]
	v_cvt_pk_bf16_f32 v122, v122, v123
	v_cvt_pk_bf16_f32 v123, v124, v125
	global_store_dwordx2 v[108:109], v[122:123], off offset:1024 nt
	v_pk_mul_f32 v[134:135], v[128:129], v[130:131] op_sel_hi:[1,0]
	ds_read_b128 v[122:125], v131 offset:3072
	ds_read_b128 v[126:129], v131 offset:44032
	s_waitcnt lgkmcnt(0)
	v_pk_fma_f32 v[124:125], v[134:135], v[124:125], v[128:129]
	v_pk_fma_f32 v[122:123], v[132:133], v[122:123], v[126:127]
	v_pk_mul_f32 v[126:127], v[116:117], v[130:131] op_sel_hi:[1,0]
	v_cvt_pk_bf16_f32 v122, v122, v123
	v_cvt_pk_bf16_f32 v123, v124, v125
	global_store_dwordx2 v[108:109], v[122:123], off offset:1536 nt
	v_pk_mul_f32 v[128:129], v[118:119], v[130:131] op_sel_hi:[1,0]
	ds_read_b128 v[116:119], v131 offset:4096
	ds_read_b128 v[122:125], v131 offset:45056
	s_waitcnt lgkmcnt(0)
	v_pk_fma_f32 v[118:119], v[128:129], v[118:119], v[124:125]
	v_pk_fma_f32 v[116:117], v[126:127], v[116:117], v[122:123]
	v_pk_mul_f32 v[122:123], v[114:115], v[130:131] op_sel_hi:[1,0]
	v_cvt_pk_bf16_f32 v116, v116, v117
	v_cvt_pk_bf16_f32 v117, v118, v119
	global_store_dwordx2 v[108:109], v[116:117], off offset:2048 nt
	v_pk_mul_f32 v[124:125], v[120:121], v[130:131] op_sel_hi:[1,0]
	ds_read_b128 v[114:117], v131 offset:5120
	ds_read_b128 v[118:121], v131 offset:46080
	s_waitcnt lgkmcnt(0)
	v_pk_fma_f32 v[116:117], v[124:125], v[116:117], v[120:121]
	v_pk_fma_f32 v[114:115], v[122:123], v[114:115], v[118:119]
	v_pk_mul_f32 v[120:121], v[112:113], v[130:131] op_sel_hi:[1,0]
	v_cvt_pk_bf16_f32 v114, v114, v115
	v_cvt_pk_bf16_f32 v115, v116, v117
	global_store_dwordx2 v[108:109], v[114:115], off offset:2560 nt
	ds_read_b128 v[112:115], v131 offset:6144
	ds_read_b128 v[116:119], v131 offset:47104
	s_waitcnt vmcnt(61)
	v_cvt_f32_f16_sdwa v123, v107 dst_sel:DWORD dst_unused:UNUSED_PAD src0_sel:WORD_1
	v_cvt_f32_f16_e32 v122, v107
	s_waitcnt vmcnt(59)
	v_cvt_f32_f16_sdwa v107, v102 dst_sel:DWORD dst_unused:UNUSED_PAD src0_sel:WORD_1
	s_waitcnt lgkmcnt(0)
	v_pk_fma_f32 v[114:115], v[120:121], v[114:115], v[118:119]
	v_pk_fma_f32 v[4:5], v[4:5], v[112:113], v[116:117]
	v_cvt_f32_f16_sdwa v121, v106 dst_sel:DWORD dst_unused:UNUSED_PAD src0_sel:WORD_1
	v_cvt_pk_bf16_f32 v4, v4, v5
	v_cvt_pk_bf16_f32 v5, v114, v115
	global_store_dwordx2 v[108:109], v[4:5], off offset:3072 nt
	v_pk_mul_f32 v[4:5], v[74:75], v[130:131] op_sel_hi:[1,0]
	v_pk_mul_f32 v[74:75], v[110:111], v[130:131] op_sel_hi:[1,0]
	ds_read_b128 v[110:113], v131 offset:7168
	ds_read_b128 v[114:117], v131 offset:48128
	v_cvt_f32_f16_e32 v120, v106
	v_cvt_f32_f16_sdwa v119, v105 dst_sel:DWORD dst_unused:UNUSED_PAD src0_sel:WORD_1
	v_cvt_f32_f16_e32 v118, v105
	v_cvt_f32_f16_e32 v106, v102
	s_waitcnt lgkmcnt(0)
	v_pk_fma_f32 v[74:75], v[74:75], v[112:113], v[116:117]
	v_cvt_f32_f16_sdwa v117, v104 dst_sel:DWORD dst_unused:UNUSED_PAD src0_sel:WORD_1
	v_pk_fma_f32 v[4:5], v[4:5], v[110:111], v[114:115]
	v_cvt_f32_f16_e32 v116, v104
	v_cvt_pk_bf16_f32 v4, v4, v5
	v_cvt_pk_bf16_f32 v5, v74, v75
	global_store_dwordx2 v[108:109], v[4:5], off offset:3584 nt
	v_cvt_f32_f16_sdwa v109, v103 dst_sel:DWORD dst_unused:UNUSED_PAD src0_sel:WORD_1
	s_waitcnt vmcnt(60)
	v_cvt_f32_f16_sdwa v111, v100 dst_sel:DWORD dst_unused:UNUSED_PAD src0_sel:WORD_1
	v_mov_b32_e32 v74, v121
	v_mov_b32_e32 v75, v117
	v_cvt_f32_f16_e32 v108, v103
	v_cvt_f32_f16_e32 v110, v100
	v_cvt_f32_f16_sdwa v113, v101 dst_sel:DWORD dst_unused:UNUSED_PAD src0_sel:WORD_1
	v_mov_b32_e32 v4, v120
	v_mov_b32_e32 v5, v116
	v_pk_mul_f32 v[74:75], v[74:75], v[74:75]
	v_mov_b32_e32 v104, v123
	v_mov_b32_e32 v105, v119
	v_cvt_f32_f16_e32 v112, v101
	v_pk_fma_f32 v[4:5], v[4:5], v[4:5], v[74:75]
	v_mov_b32_e32 v74, v122
	v_mov_b32_e32 v75, v118
	v_pk_mul_f32 v[104:105], v[104:105], v[104:105]
	v_mov_b32_e32 v102, v107
	v_pk_fma_f32 v[74:75], v[74:75], v[74:75], v[104:105]
	v_mov_b32_e32 v103, v109
	v_mul_f32_e32 v100, v111, v111
	v_pk_add_f32 v[4:5], v[4:5], v[74:75]
	v_mov_b32_e32 v74, v106
	v_mov_b32_e32 v75, v108
	v_pk_mul_f32 v[102:103], v[102:103], v[102:103]
	v_pk_fma_f32 v[104:105], v[110:111], v[110:111], v[100:101] op_sel_hi:[1,1,0]
	v_mul_f32_e32 v100, v113, v113
	v_pk_fma_f32 v[74:75], v[74:75], v[74:75], v[102:103]
	v_pk_fma_f32 v[114:115], v[112:113], v[112:113], v[100:101] op_sel_hi:[1,1,0]
	s_waitcnt vmcnt(59)
; __device__ __forceinline__ void norm_mod_phase2(const Args& a, Frame& F, const float* gain, const float* modl, int sh_off, int sc_off, int nrows, const float* slab_gate) {
;     ...
;     NR_FINISH(r2, nw + 2 * 2048, (nw + 2 * 2048) >> 12);
	v_cvt_f32_f16_sdwa v101, v98 dst_sel:DWORD dst_unused:UNUSED_PAD src0_sel:WORD_1
	v_cvt_f32_f16_e32 v100, v98
	v_cvt_f32_f16_sdwa v103, v99 dst_sel:DWORD dst_unused:UNUSED_PAD src0_sel:WORD_1
	v_cvt_f32_f16_e32 v102, v99
	v_pk_add_f32 v[4:5], v[4:5], v[4:5] op_sel:[0,1] op_sel_hi:[1,0]
	v_pk_add_f32 v[74:75], v[74:75], v[74:75] op_sel:[0,1] op_sel_hi:[1,0]
	v_pk_mul_f32 v[98:99], v[100:101], v[100:101]
	v_pk_mul_f32 v[124:125], v[102:103], v[102:103]
	v_mov_b32_e32 v5, v98
	v_mov_b32_e32 v75, v99
	v_mov_b32_e32 v105, v124
	v_mov_b32_e32 v115, v125
	v_pk_add_f32 v[4:5], v[4:5], v[74:75]
	v_pk_add_f32 v[74:75], v[104:105], v[114:115]
	s_waitcnt vmcnt(58)
	v_cvt_f32_f16_sdwa v99, v96 dst_sel:DWORD dst_unused:UNUSED_PAD src0_sel:WORD_1
	v_cvt_f32_f16_sdwa v105, v97 dst_sel:DWORD dst_unused:UNUSED_PAD src0_sel:WORD_1
	v_cvt_f32_f16_e32 v98, v96
	v_cvt_f32_f16_e32 v104, v97
	v_pk_add_f32 v[4:5], v[4:5], v[74:75]
	v_mov_b32_e32 v74, v99
	v_mov_b32_e32 v75, v105
	v_pk_add_f32 v[114:115], v[4:5], v[4:5] op_sel:[0,1] op_sel_hi:[1,0]
	v_mov_b32_e32 v4, v98
	v_mov_b32_e32 v5, v104
	v_pk_mul_f32 v[74:75], v[74:75], v[74:75]
	s_waitcnt vmcnt(57)
	v_cvt_f32_f16_sdwa v97, v95 dst_sel:DWORD dst_unused:UNUSED_PAD src0_sel:WORD_1
	v_pk_fma_f32 v[4:5], v[4:5], v[4:5], v[74:75]
	v_cvt_f32_f16_e32 v96, v95
	v_pk_add_f32 v[124:125], v[4:5], v[4:5] op_sel:[0,1] op_sel_hi:[1,0]
	v_cvt_f32_f16_sdwa v5, v94 dst_sel:DWORD dst_unused:UNUSED_PAD src0_sel:WORD_1
	v_cvt_f32_f16_e32 v4, v94
	s_waitcnt vmcnt(56)
	v_cvt_f32_f16_sdwa v95, v93 dst_sel:DWORD dst_unused:UNUSED_PAD src0_sel:WORD_1
	v_cvt_f32_f16_e32 v94, v93
	v_mul_f32_e32 v74, v5, v5
	v_pk_fma_f32 v[126:127], v[4:5], v[4:5], v[74:75] op_sel_hi:[1,1,0]
	v_mul_f32_e32 v74, v97, v97
	v_pk_fma_f32 v[128:129], v[96:97], v[96:97], v[74:75] op_sel_hi:[1,1,0]
	v_cvt_f32_f16_sdwa v75, v92 dst_sel:DWORD dst_unused:UNUSED_PAD src0_sel:WORD_1
	v_cvt_f32_f16_e32 v74, v92
	v_pk_mul_f32 v[130:131], v[94:95], v[94:95]
	v_pk_mul_f32 v[92:93], v[74:75], v[74:75]
	s_nop 0
	v_mov_b32_e32 v115, v92
	v_mov_b32_e32 v125, v93
	v_mov_b32_e32 v127, v130
	v_mov_b32_e32 v129, v131
	v_pk_add_f32 v[92:93], v[114:115], v[124:125]
	v_pk_add_f32 v[114:115], v[126:127], v[128:129]
	s_nop 0
	v_pk_add_f32 v[92:93], v[92:93], v[114:115]
	s_nop 0
	v_add_f32_e32 v92, v92, v93
	s_nop 1
	v_add_f32_dpp v92, v92, v92 quad_perm:[1,0,3,2] row_mask:0xf bank_mask:0xf bound_ctrl:1
	s_nop 1
	v_add_f32_dpp v92, v92, v92 quad_perm:[2,3,0,1] row_mask:0xf bank_mask:0xf bound_ctrl:1
	s_nop 1
	v_add_f32_dpp v92, v92, v92 row_half_mirror row_mask:0xf bank_mask:0xf bound_ctrl:1
	s_nop 1
	v_add_f32_dpp v92, v92, v92 row_mirror row_mask:0xf bank_mask:0xf bound_ctrl:1
	s_nop 0
	v_readlane_b32 s5, v92, 16
	v_readlane_b32 s11, v92, 48
	v_readlane_b32 s6, v92, 0
	v_readlane_b32 s7, v92, 32
	v_mov_b32_e32 v92, s5
	v_mov_b32_e32 v93, s11
	v_pk_add_f32 v[92:93], s[6:7], v[92:93]
	s_lshl_b32 s5, s30, 1
	v_add_f32_e32 v92, v92, v93
	v_fmamk_f32 v92, v92, 0x3a000000, v252
	v_cmp_gt_f32_e32 vcc, s55, v92
	v_mul_f32_e32 v93, 0x4f800000, v92
	s_and_b32 s5, s5, 0xffffe000
	v_cndmask_b32_e32 v92, v92, v93, vcc
	v_sqrt_f32_e32 v93, v92
	s_add_i32 s5, s5, 0
	v_add_u32_e32 v114, -1, v93
	v_fma_f32 v115, -v114, v93, v92
	v_cmp_ge_f32_e64 s[6:7], 0, v115
	v_add_u32_e32 v115, 1, v93
	s_nop 0
	v_cndmask_b32_e64 v114, v93, v114, s[6:7]
	v_fma_f32 v93, -v115, v93, v92
	v_cmp_lt_f32_e64 s[6:7], 0, v93
	s_nop 1
	v_cndmask_b32_e64 v93, v114, v115, s[6:7]
	v_mul_f32_e32 v114, 0x37800000, v93
	v_cndmask_b32_e32 v93, v93, v114, vcc
	v_cmp_class_f32_e32 vcc, v92, v253
	s_nop 1
	v_cndmask_b32_e32 v92, v93, v92, vcc
	v_div_scale_f32 v93, s[6:7], v92, v92, 1.0
	v_rcp_f32_e32 v114, v93
	s_nop 0
	v_fma_f32 v115, -v93, v114, 1.0
	v_fmac_f32_e32 v114, v115, v114
	v_div_scale_f32 v115, vcc, 1.0, v92, 1.0
	v_mul_f32_e32 v124, v115, v114
	v_fma_f32 v125, -v93, v124, v115
	v_fmac_f32_e32 v124, v125, v114
	v_fma_f32 v93, -v93, v124, v115
	v_div_fmas_f32 v93, v93, v114, v124
	v_div_fixup_f32 v114, v93, v92, 1.0
	v_pk_mul_f32 v[128:129], v[120:121], v[114:115] op_sel_hi:[1,0]
	v_pk_mul_f32 v[130:131], v[122:123], v[114:115] op_sel_hi:[1,0]
	v_add_u32_e32 v115, s5, v0
	ds_read_b128 v[120:123], v115
	ds_read_b128 v[124:127], v115 offset:40960
	v_lshl_add_u64 v[92:93], s[34:35], 1, v[2:3]
	v_lshl_add_u64 v[92:93], v[92:93], 0, v[6:7]
	v_pk_mul_f32 v[4:5], v[4:5], v[114:115] op_sel_hi:[1,0]
	s_waitcnt lgkmcnt(0)
	v_pk_fma_f32 v[122:123], v[122:123], v[130:131], v[126:127]
	v_pk_fma_f32 v[120:121], v[120:121], v[128:129], v[124:125]
	v_pk_mul_f32 v[124:125], v[116:117], v[114:115] op_sel_hi:[1,0]
	v_cvt_pk_bf16_f32 v120, v120, v121
	v_cvt_pk_bf16_f32 v121, v122, v123
	global_store_dwordx2 v[92:93], v[120:121], off nt
	v_pk_mul_f32 v[126:127], v[118:119], v[114:115] op_sel_hi:[1,0]
	ds_read_b128 v[116:119], v115 offset:1024
	ds_read_b128 v[120:123], v115 offset:41984
	s_waitcnt lgkmcnt(0)
	v_pk_fma_f32 v[118:119], v[118:119], v[126:127], v[122:123]
	v_pk_fma_f32 v[116:117], v[116:117], v[124:125], v[120:121]
	v_pk_mul_f32 v[120:121], v[106:107], v[114:115] op_sel_hi:[1,0]
	v_cvt_pk_bf16_f32 v116, v116, v117
	v_cvt_pk_bf16_f32 v117, v118, v119
	global_store_dwordx2 v[92:93], v[116:117], off offset:512 nt
	v_pk_mul_f32 v[122:123], v[108:109], v[114:115] op_sel_hi:[1,0]
	ds_read_b128 v[106:109], v115 offset:2048
	ds_read_b128 v[116:119], v115 offset:43008
	s_waitcnt lgkmcnt(0)
; __device__ __forceinline__ void norm_mod_phase2(const Args& a, Frame& F, const float* gain, const float* modl, int sh_off, int sc_off, int nrows, const float* slab_gate) {
;     ...
;     NR_FINISH(r2, nw + 2 * 2048, (nw + 2 * 2048) >> 12);
;     NR_FINISH(r3, nw + 3 * 2048, (nw + 3 * 2048) >> 12);
	v_pk_fma_f32 v[108:109], v[108:109], v[122:123], v[118:119]
	v_pk_fma_f32 v[106:107], v[106:107], v[120:121], v[116:117]
	v_pk_mul_f32 v[116:117], v[110:111], v[114:115] op_sel_hi:[1,0]
	v_cvt_pk_bf16_f32 v106, v106, v107
	v_cvt_pk_bf16_f32 v107, v108, v109
	global_store_dwordx2 v[92:93], v[106:107], off offset:1024 nt
	v_pk_mul_f32 v[118:119], v[112:113], v[114:115] op_sel_hi:[1,0]
	ds_read_b128 v[106:109], v115 offset:3072
	ds_read_b128 v[110:113], v115 offset:44032
	s_waitcnt lgkmcnt(0)
	v_pk_fma_f32 v[108:109], v[118:119], v[108:109], v[112:113]
	v_pk_fma_f32 v[106:107], v[116:117], v[106:107], v[110:111]
	v_pk_mul_f32 v[110:111], v[100:101], v[114:115] op_sel_hi:[1,0]
	v_cvt_pk_bf16_f32 v106, v106, v107
	v_cvt_pk_bf16_f32 v107, v108, v109
	global_store_dwordx2 v[92:93], v[106:107], off offset:1536 nt
	v_pk_mul_f32 v[112:113], v[102:103], v[114:115] op_sel_hi:[1,0]
	ds_read_b128 v[100:103], v115 offset:4096
	ds_read_b128 v[106:109], v115 offset:45056
	s_waitcnt lgkmcnt(0)
	v_pk_fma_f32 v[102:103], v[112:113], v[102:103], v[108:109]
	v_pk_fma_f32 v[100:101], v[110:111], v[100:101], v[106:107]
	v_pk_mul_f32 v[106:107], v[98:99], v[114:115] op_sel_hi:[1,0]
	v_cvt_pk_bf16_f32 v100, v100, v101
	v_cvt_pk_bf16_f32 v101, v102, v103
	global_store_dwordx2 v[92:93], v[100:101], off offset:2048 nt
	v_pk_mul_f32 v[108:109], v[104:105], v[114:115] op_sel_hi:[1,0]
	ds_read_b128 v[98:101], v115 offset:5120
	ds_read_b128 v[102:105], v115 offset:46080
	s_waitcnt lgkmcnt(0)
	v_pk_fma_f32 v[100:101], v[108:109], v[100:101], v[104:105]
	v_pk_fma_f32 v[98:99], v[106:107], v[98:99], v[102:103]
	v_pk_mul_f32 v[104:105], v[96:97], v[114:115] op_sel_hi:[1,0]
	v_cvt_pk_bf16_f32 v98, v98, v99
	v_cvt_pk_bf16_f32 v99, v100, v101
	global_store_dwordx2 v[92:93], v[98:99], off offset:2560 nt
	ds_read_b128 v[96:99], v115 offset:6144
	ds_read_b128 v[100:103], v115 offset:47104
	s_waitcnt vmcnt(61)
	v_cvt_f32_f16_sdwa v107, v91 dst_sel:DWORD dst_unused:UNUSED_PAD src0_sel:WORD_1
	v_cvt_f32_f16_e32 v106, v91
	s_waitcnt vmcnt(59)
	v_cvt_f32_f16_sdwa v91, v86 dst_sel:DWORD dst_unused:UNUSED_PAD src0_sel:WORD_1
	s_waitcnt lgkmcnt(0)
	v_pk_fma_f32 v[98:99], v[104:105], v[98:99], v[102:103]
	v_pk_fma_f32 v[4:5], v[4:5], v[96:97], v[100:101]
	v_cvt_f32_f16_sdwa v105, v90 dst_sel:DWORD dst_unused:UNUSED_PAD src0_sel:WORD_1
	v_cvt_pk_bf16_f32 v4, v4, v5
	v_cvt_pk_bf16_f32 v5, v98, v99
	global_store_dwordx2 v[92:93], v[4:5], off offset:3072 nt
	v_pk_mul_f32 v[4:5], v[74:75], v[114:115] op_sel_hi:[1,0]
	v_pk_mul_f32 v[74:75], v[94:95], v[114:115] op_sel_hi:[1,0]
	ds_read_b128 v[94:97], v115 offset:7168
	ds_read_b128 v[98:101], v115 offset:48128
	v_cvt_f32_f16_e32 v104, v90
	v_cvt_f32_f16_sdwa v103, v89 dst_sel:DWORD dst_unused:UNUSED_PAD src0_sel:WORD_1
	v_cvt_f32_f16_e32 v102, v89
	v_cvt_f32_f16_e32 v90, v86
	s_waitcnt lgkmcnt(0)
	v_pk_fma_f32 v[74:75], v[74:75], v[96:97], v[100:101]
	v_cvt_f32_f16_sdwa v101, v88 dst_sel:DWORD dst_unused:UNUSED_PAD src0_sel:WORD_1
	v_pk_fma_f32 v[4:5], v[4:5], v[94:95], v[98:99]
	v_cvt_f32_f16_e32 v100, v88
	v_cvt_pk_bf16_f32 v4, v4, v5
	v_cvt_pk_bf16_f32 v5, v74, v75
	global_store_dwordx2 v[92:93], v[4:5], off offset:3584 nt
	v_cvt_f32_f16_sdwa v93, v87 dst_sel:DWORD dst_unused:UNUSED_PAD src0_sel:WORD_1
	s_waitcnt vmcnt(60)
	v_cvt_f32_f16_sdwa v95, v84 dst_sel:DWORD dst_unused:UNUSED_PAD src0_sel:WORD_1
	v_mov_b32_e32 v74, v105
	v_mov_b32_e32 v75, v101
	v_cvt_f32_f16_e32 v92, v87
	v_cvt_f32_f16_e32 v94, v84
	v_cvt_f32_f16_sdwa v97, v85 dst_sel:DWORD dst_unused:UNUSED_PAD src0_sel:WORD_1
	v_mov_b32_e32 v4, v104
	v_mov_b32_e32 v5, v100
	v_pk_mul_f32 v[74:75], v[74:75], v[74:75]
	v_mov_b32_e32 v88, v107
	v_mov_b32_e32 v89, v103
	v_cvt_f32_f16_e32 v96, v85
	v_pk_fma_f32 v[4:5], v[4:5], v[4:5], v[74:75]
	v_mov_b32_e32 v74, v106
	v_mov_b32_e32 v75, v102
	v_pk_mul_f32 v[88:89], v[88:89], v[88:89]
	v_mov_b32_e32 v86, v91
	v_pk_fma_f32 v[74:75], v[74:75], v[74:75], v[88:89]
	v_mov_b32_e32 v87, v93
	v_mul_f32_e32 v84, v95, v95
	v_pk_add_f32 v[4:5], v[4:5], v[74:75]
	v_mov_b32_e32 v74, v90
	v_mov_b32_e32 v75, v92
	v_pk_mul_f32 v[86:87], v[86:87], v[86:87]
	v_pk_fma_f32 v[88:89], v[94:95], v[94:95], v[84:85] op_sel_hi:[1,1,0]
	v_mul_f32_e32 v84, v97, v97
	v_pk_fma_f32 v[74:75], v[74:75], v[74:75], v[86:87]
	v_pk_fma_f32 v[98:99], v[96:97], v[96:97], v[84:85] op_sel_hi:[1,1,0]
	s_waitcnt vmcnt(59)
	v_cvt_f32_f16_sdwa v85, v82 dst_sel:DWORD dst_unused:UNUSED_PAD src0_sel:WORD_1
	v_cvt_f32_f16_e32 v84, v82
	v_cvt_f32_f16_sdwa v87, v83 dst_sel:DWORD dst_unused:UNUSED_PAD src0_sel:WORD_1
	v_cvt_f32_f16_e32 v86, v83
	v_pk_add_f32 v[4:5], v[4:5], v[4:5] op_sel:[0,1] op_sel_hi:[1,0]
	v_pk_add_f32 v[74:75], v[74:75], v[74:75] op_sel:[0,1] op_sel_hi:[1,0]
	v_pk_mul_f32 v[82:83], v[84:85], v[84:85]
	v_pk_mul_f32 v[108:109], v[86:87], v[86:87]
	v_mov_b32_e32 v5, v82
	v_mov_b32_e32 v75, v83
	v_mov_b32_e32 v89, v108
	v_mov_b32_e32 v99, v109
	v_pk_add_f32 v[4:5], v[4:5], v[74:75]
	v_pk_add_f32 v[74:75], v[88:89], v[98:99]
	s_waitcnt vmcnt(58)
	v_cvt_f32_f16_sdwa v83, v80 dst_sel:DWORD dst_unused:UNUSED_PAD src0_sel:WORD_1
	v_cvt_f32_f16_sdwa v89, v81 dst_sel:DWORD dst_unused:UNUSED_PAD src0_sel:WORD_1
	v_cvt_f32_f16_e32 v82, v80
	v_cvt_f32_f16_e32 v88, v81
	v_pk_add_f32 v[4:5], v[4:5], v[74:75]
	v_mov_b32_e32 v74, v83
	v_mov_b32_e32 v75, v89
	v_pk_add_f32 v[98:99], v[4:5], v[4:5] op_sel:[0,1] op_sel_hi:[1,0]
	v_mov_b32_e32 v4, v82
	v_mov_b32_e32 v5, v88
	v_pk_mul_f32 v[74:75], v[74:75], v[74:75]
	s_waitcnt vmcnt(57)
; __device__ __forceinline__ void norm_mod_phase2(const Args& a, Frame& F, const float* gain, const float* modl, int sh_off, int sc_off, int nrows, const float* slab_gate) {
;     ...
;     NR_FINISH(r3, nw + 3 * 2048, (nw + 3 * 2048) >> 12);
	v_cvt_f32_f16_sdwa v81, v79 dst_sel:DWORD dst_unused:UNUSED_PAD src0_sel:WORD_1
	v_pk_fma_f32 v[4:5], v[4:5], v[4:5], v[74:75]
	v_cvt_f32_f16_e32 v80, v79
	v_pk_add_f32 v[108:109], v[4:5], v[4:5] op_sel:[0,1] op_sel_hi:[1,0]
	v_cvt_f32_f16_sdwa v5, v78 dst_sel:DWORD dst_unused:UNUSED_PAD src0_sel:WORD_1
	v_cvt_f32_f16_e32 v4, v78
	s_waitcnt vmcnt(56)
	v_cvt_f32_f16_sdwa v79, v77 dst_sel:DWORD dst_unused:UNUSED_PAD src0_sel:WORD_1
	v_cvt_f32_f16_e32 v78, v77
	v_mul_f32_e32 v74, v5, v5
	v_pk_fma_f32 v[110:111], v[4:5], v[4:5], v[74:75] op_sel_hi:[1,1,0]
	v_mul_f32_e32 v74, v81, v81
	v_pk_fma_f32 v[112:113], v[80:81], v[80:81], v[74:75] op_sel_hi:[1,1,0]
	v_cvt_f32_f16_sdwa v75, v76 dst_sel:DWORD dst_unused:UNUSED_PAD src0_sel:WORD_1
	v_cvt_f32_f16_e32 v74, v76
	v_pk_mul_f32 v[114:115], v[78:79], v[78:79]
	v_pk_mul_f32 v[76:77], v[74:75], v[74:75]
	s_nop 0
	v_mov_b32_e32 v99, v76
	v_mov_b32_e32 v109, v77
	v_mov_b32_e32 v111, v114
	v_mov_b32_e32 v113, v115
	v_pk_add_f32 v[76:77], v[98:99], v[108:109]
	v_pk_add_f32 v[98:99], v[110:111], v[112:113]
	s_nop 0
	v_pk_add_f32 v[76:77], v[76:77], v[98:99]
	s_nop 0
	v_add_f32_e32 v76, v76, v77
	s_nop 1
	v_add_f32_dpp v76, v76, v76 quad_perm:[1,0,3,2] row_mask:0xf bank_mask:0xf bound_ctrl:1
	s_nop 1
	v_add_f32_dpp v76, v76, v76 quad_perm:[2,3,0,1] row_mask:0xf bank_mask:0xf bound_ctrl:1
	s_nop 1
	v_add_f32_dpp v76, v76, v76 row_half_mirror row_mask:0xf bank_mask:0xf bound_ctrl:1
	s_nop 1
	v_add_f32_dpp v76, v76, v76 row_mirror row_mask:0xf bank_mask:0xf bound_ctrl:1
	s_nop 0
	v_readlane_b32 s5, v76, 16
	v_readlane_b32 s11, v76, 48
	v_readlane_b32 s6, v76, 0
	v_readlane_b32 s7, v76, 32
	v_mov_b32_e32 v76, s5
	v_mov_b32_e32 v77, s11
	v_pk_add_f32 v[76:77], s[6:7], v[76:77]
	s_lshl_b32 s5, s26, 1
	v_add_f32_e32 v76, v76, v77
	v_fmamk_f32 v76, v76, 0x3a000000, v252
	v_cmp_gt_f32_e32 vcc, s55, v76
	v_mul_f32_e32 v77, 0x4f800000, v76
	s_and_b32 s5, s5, 0xffffe000
	v_cndmask_b32_e32 v76, v76, v77, vcc
	v_sqrt_f32_e32 v77, v76
	s_add_i32 s5, s5, 0
	v_add_u32_e32 v98, -1, v77
	v_fma_f32 v99, -v98, v77, v76
	v_cmp_ge_f32_e64 s[6:7], 0, v99
	v_add_u32_e32 v99, 1, v77
	s_nop 0
	v_cndmask_b32_e64 v98, v77, v98, s[6:7]
	v_fma_f32 v77, -v99, v77, v76
	v_cmp_lt_f32_e64 s[6:7], 0, v77
	s_nop 1
	v_cndmask_b32_e64 v77, v98, v99, s[6:7]
	v_mul_f32_e32 v98, 0x37800000, v77
	v_cndmask_b32_e32 v77, v77, v98, vcc
	v_cmp_class_f32_e32 vcc, v76, v253
	s_nop 1
	v_cndmask_b32_e32 v76, v77, v76, vcc
	v_div_scale_f32 v77, s[6:7], v76, v76, 1.0
	v_rcp_f32_e32 v98, v77
	s_nop 0
	v_fma_f32 v99, -v77, v98, 1.0
	v_fmac_f32_e32 v98, v99, v98
	v_div_scale_f32 v99, vcc, 1.0, v76, 1.0
	v_mul_f32_e32 v108, v99, v98
	v_fma_f32 v109, -v77, v108, v99
	v_fmac_f32_e32 v108, v109, v98
	v_fma_f32 v77, -v77, v108, v99
	v_div_fmas_f32 v77, v77, v98, v108
	v_div_fixup_f32 v98, v77, v76, 1.0
	v_pk_mul_f32 v[112:113], v[104:105], v[98:99] op_sel_hi:[1,0]
	v_pk_mul_f32 v[114:115], v[106:107], v[98:99] op_sel_hi:[1,0]
	v_add_u32_e32 v99, s5, v0
	ds_read_b128 v[104:107], v99
	ds_read_b128 v[108:111], v99 offset:40960
	v_lshl_add_u64 v[76:77], s[28:29], 1, v[2:3]
	v_lshl_add_u64 v[76:77], v[76:77], 0, v[6:7]
	v_pk_mul_f32 v[4:5], v[4:5], v[98:99] op_sel_hi:[1,0]
	s_waitcnt lgkmcnt(0)
	v_pk_fma_f32 v[106:107], v[106:107], v[114:115], v[110:111]
	v_pk_fma_f32 v[104:105], v[104:105], v[112:113], v[108:109]
	v_pk_mul_f32 v[108:109], v[100:101], v[98:99] op_sel_hi:[1,0]
	v_cvt_pk_bf16_f32 v104, v104, v105
	v_cvt_pk_bf16_f32 v105, v106, v107
	global_store_dwordx2 v[76:77], v[104:105], off nt
	v_pk_mul_f32 v[110:111], v[102:103], v[98:99] op_sel_hi:[1,0]
	ds_read_b128 v[100:103], v99 offset:1024
	ds_read_b128 v[104:107], v99 offset:41984
	s_waitcnt lgkmcnt(0)
	v_pk_fma_f32 v[102:103], v[102:103], v[110:111], v[106:107]
	v_pk_fma_f32 v[100:101], v[100:101], v[108:109], v[104:105]
	v_pk_mul_f32 v[104:105], v[90:91], v[98:99] op_sel_hi:[1,0]
	v_cvt_pk_bf16_f32 v100, v100, v101
	v_cvt_pk_bf16_f32 v101, v102, v103
	global_store_dwordx2 v[76:77], v[100:101], off offset:512 nt
	v_pk_mul_f32 v[106:107], v[92:93], v[98:99] op_sel_hi:[1,0]
	ds_read_b128 v[90:93], v99 offset:2048
	ds_read_b128 v[100:103], v99 offset:43008
	s_waitcnt lgkmcnt(0)
	v_pk_fma_f32 v[92:93], v[92:93], v[106:107], v[102:103]
	v_pk_fma_f32 v[90:91], v[90:91], v[104:105], v[100:101]
	v_pk_mul_f32 v[100:101], v[94:95], v[98:99] op_sel_hi:[1,0]
	v_cvt_pk_bf16_f32 v90, v90, v91
	v_cvt_pk_bf16_f32 v91, v92, v93
	global_store_dwordx2 v[76:77], v[90:91], off offset:1024 nt
	v_pk_mul_f32 v[102:103], v[96:97], v[98:99] op_sel_hi:[1,0]
	ds_read_b128 v[90:93], v99 offset:3072
	ds_read_b128 v[94:97], v99 offset:44032
	s_waitcnt lgkmcnt(0)
	v_pk_fma_f32 v[92:93], v[102:103], v[92:93], v[96:97]
	v_pk_fma_f32 v[90:91], v[100:101], v[90:91], v[94:95]
	v_pk_mul_f32 v[94:95], v[84:85], v[98:99] op_sel_hi:[1,0]
	v_cvt_pk_bf16_f32 v90, v90, v91
	v_cvt_pk_bf16_f32 v91, v92, v93
	global_store_dwordx2 v[76:77], v[90:91], off offset:1536 nt
	v_pk_mul_f32 v[96:97], v[86:87], v[98:99] op_sel_hi:[1,0]
	ds_read_b128 v[84:87], v99 offset:4096
	ds_read_b128 v[90:93], v99 offset:45056
	s_waitcnt lgkmcnt(0)
	v_pk_fma_f32 v[86:87], v[96:97], v[86:87], v[92:93]
	v_pk_fma_f32 v[84:85], v[94:95], v[84:85], v[90:91]
	v_pk_mul_f32 v[90:91], v[82:83], v[98:99] op_sel_hi:[1,0]
	v_cvt_pk_bf16_f32 v84, v84, v85
	v_cvt_pk_bf16_f32 v85, v86, v87
	global_store_dwordx2 v[76:77], v[84:85], off offset:2048 nt
	v_pk_mul_f32 v[92:93], v[88:89], v[98:99] op_sel_hi:[1,0]
	ds_read_b128 v[82:85], v99 offset:5120
	ds_read_b128 v[86:89], v99 offset:46080
	s_waitcnt lgkmcnt(0)
; __device__ __forceinline__ void norm_mod_phase2(const Args& a, Frame& F, const float* gain, const float* modl, int sh_off, int sc_off, int nrows, const float* slab_gate) {
;     ...
;     NR_FINISH(r3, nw + 3 * 2048, (nw + 3 * 2048) >> 12);
;     NR_FINISH(r4, nw + 4 * 2048, (nw + 4 * 2048) >> 12);
	v_pk_fma_f32 v[84:85], v[92:93], v[84:85], v[88:89]
	v_pk_fma_f32 v[82:83], v[90:91], v[82:83], v[86:87]
	v_pk_mul_f32 v[88:89], v[80:81], v[98:99] op_sel_hi:[1,0]
	v_cvt_pk_bf16_f32 v82, v82, v83
	v_cvt_pk_bf16_f32 v83, v84, v85
	global_store_dwordx2 v[76:77], v[82:83], off offset:2560 nt
	ds_read_b128 v[80:83], v99 offset:6144
	ds_read_b128 v[84:87], v99 offset:47104
	s_waitcnt vmcnt(61)
	v_cvt_f32_f16_sdwa v91, v73 dst_sel:DWORD dst_unused:UNUSED_PAD src0_sel:WORD_1
	v_cvt_f32_f16_e32 v90, v73
	s_waitcnt lgkmcnt(0)
	v_pk_fma_f32 v[82:83], v[88:89], v[82:83], v[86:87]
	v_pk_fma_f32 v[4:5], v[4:5], v[80:81], v[84:85]
	v_cvt_f32_f16_sdwa v89, v72 dst_sel:DWORD dst_unused:UNUSED_PAD src0_sel:WORD_1
	v_cvt_pk_bf16_f32 v4, v4, v5
	v_cvt_pk_bf16_f32 v5, v82, v83
	global_store_dwordx2 v[76:77], v[4:5], off offset:3072 nt
	v_pk_mul_f32 v[4:5], v[74:75], v[98:99] op_sel_hi:[1,0]
	v_pk_mul_f32 v[74:75], v[78:79], v[98:99] op_sel_hi:[1,0]
	ds_read_b128 v[78:81], v99 offset:7168
	ds_read_b128 v[82:85], v99 offset:48128
	v_cvt_f32_f16_e32 v88, v72
	s_waitcnt vmcnt(61)
	v_cvt_f32_f16_sdwa v87, v71 dst_sel:DWORD dst_unused:UNUSED_PAD src0_sel:WORD_1
	v_cvt_f32_f16_e32 v86, v71
	v_mov_b32_e32 v72, v91
	s_waitcnt lgkmcnt(0)
	v_pk_fma_f32 v[74:75], v[74:75], v[80:81], v[84:85]
	v_cvt_f32_f16_sdwa v85, v70 dst_sel:DWORD dst_unused:UNUSED_PAD src0_sel:WORD_1
	v_cvt_f32_f16_e32 v84, v70
	v_pk_fma_f32 v[4:5], v[4:5], v[78:79], v[82:83]
	v_mov_b32_e32 v70, v89
	v_cvt_pk_bf16_f32 v4, v4, v5
	v_cvt_pk_bf16_f32 v5, v74, v75
	global_store_dwordx2 v[76:77], v[4:5], off offset:3584 nt
	v_mov_b32_e32 v71, v85
	s_waitcnt vmcnt(61)
	v_cvt_f32_f16_sdwa v75, v68 dst_sel:DWORD dst_unused:UNUSED_PAD src0_sel:WORD_1
	v_cvt_f32_f16_sdwa v77, v69 dst_sel:DWORD dst_unused:UNUSED_PAD src0_sel:WORD_1
	v_mov_b32_e32 v4, v88
	v_mov_b32_e32 v5, v84
	v_pk_mul_f32 v[70:71], v[70:71], v[70:71]
	v_mov_b32_e32 v73, v87
	v_cvt_f32_f16_e32 v74, v68
	v_cvt_f32_f16_e32 v76, v69
	s_waitcnt vmcnt(60)
	v_cvt_f32_f16_sdwa v79, v66 dst_sel:DWORD dst_unused:UNUSED_PAD src0_sel:WORD_1
	v_pk_fma_f32 v[4:5], v[4:5], v[4:5], v[70:71]
	v_mov_b32_e32 v70, v90
	v_mov_b32_e32 v71, v86
	v_pk_mul_f32 v[72:73], v[72:73], v[72:73]
	v_cvt_f32_f16_e32 v78, v66
	v_cvt_f32_f16_sdwa v81, v67 dst_sel:DWORD dst_unused:UNUSED_PAD src0_sel:WORD_1
	v_pk_fma_f32 v[70:71], v[70:71], v[70:71], v[72:73]
	v_cvt_f32_f16_e32 v80, v67
	v_pk_add_f32 v[4:5], v[4:5], v[70:71]
	v_mov_b32_e32 v70, v75
	v_mov_b32_e32 v71, v77
	v_mov_b32_e32 v68, v74
	v_mov_b32_e32 v69, v76
	v_pk_mul_f32 v[70:71], v[70:71], v[70:71]
	v_mul_f32_e32 v66, v79, v79
	v_pk_fma_f32 v[68:69], v[68:69], v[68:69], v[70:71]
	v_pk_fma_f32 v[72:73], v[78:79], v[78:79], v[66:67] op_sel_hi:[1,1,0]
	v_mul_f32_e32 v66, v81, v81
	v_pk_add_f32 v[70:71], v[68:69], v[68:69] op_sel:[0,1] op_sel_hi:[1,0]
	v_pk_fma_f32 v[82:83], v[80:81], v[80:81], v[66:67] op_sel_hi:[1,1,0]
	s_waitcnt vmcnt(59)
	v_cvt_f32_f16_sdwa v67, v64 dst_sel:DWORD dst_unused:UNUSED_PAD src0_sel:WORD_1
	v_cvt_f32_f16_e32 v66, v64
	v_cvt_f32_f16_sdwa v69, v65 dst_sel:DWORD dst_unused:UNUSED_PAD src0_sel:WORD_1
	v_cvt_f32_f16_e32 v68, v65
	v_pk_add_f32 v[4:5], v[4:5], v[4:5] op_sel:[0,1] op_sel_hi:[1,0]
	v_pk_mul_f32 v[64:65], v[66:67], v[66:67]
	v_pk_mul_f32 v[92:93], v[68:69], v[68:69]
	v_mov_b32_e32 v5, v64
	v_mov_b32_e32 v71, v65
	v_mov_b32_e32 v73, v92
	v_mov_b32_e32 v83, v93
	v_pk_add_f32 v[4:5], v[4:5], v[70:71]
	v_pk_add_f32 v[64:65], v[72:73], v[82:83]
	s_waitcnt vmcnt(58)
	v_cvt_f32_f16_sdwa v71, v62 dst_sel:DWORD dst_unused:UNUSED_PAD src0_sel:WORD_1
	v_cvt_f32_f16_sdwa v73, v63 dst_sel:DWORD dst_unused:UNUSED_PAD src0_sel:WORD_1
	v_cvt_f32_f16_e32 v70, v62
	v_cvt_f32_f16_e32 v72, v63
	v_pk_add_f32 v[4:5], v[4:5], v[64:65]
	v_mov_b32_e32 v62, v71
	v_mov_b32_e32 v63, v73
	v_pk_add_f32 v[82:83], v[4:5], v[4:5] op_sel:[0,1] op_sel_hi:[1,0]
	v_mov_b32_e32 v4, v70
	v_mov_b32_e32 v5, v72
	v_pk_mul_f32 v[62:63], v[62:63], v[62:63]
	s_waitcnt vmcnt(56)
	v_cvt_f32_f16_sdwa v65, v59 dst_sel:DWORD dst_unused:UNUSED_PAD src0_sel:WORD_1
	v_pk_fma_f32 v[4:5], v[4:5], v[4:5], v[62:63]
	v_cvt_f32_f16_sdwa v63, v61 dst_sel:DWORD dst_unused:UNUSED_PAD src0_sel:WORD_1
	v_pk_add_f32 v[92:93], v[4:5], v[4:5] op_sel:[0,1] op_sel_hi:[1,0]
	v_cvt_f32_f16_sdwa v5, v60 dst_sel:DWORD dst_unused:UNUSED_PAD src0_sel:WORD_1
	v_cvt_f32_f16_e32 v4, v60
	v_cvt_f32_f16_e32 v62, v61
	v_cvt_f32_f16_e32 v64, v59
	v_mul_f32_e32 v60, v5, v5
	v_pk_fma_f32 v[94:95], v[4:5], v[4:5], v[60:61] op_sel_hi:[1,1,0]
	v_mul_f32_e32 v60, v63, v63
	v_pk_fma_f32 v[96:97], v[62:63], v[62:63], v[60:61] op_sel_hi:[1,1,0]
	v_cvt_f32_f16_sdwa v61, v58 dst_sel:DWORD dst_unused:UNUSED_PAD src0_sel:WORD_1
	v_cvt_f32_f16_e32 v60, v58
	v_pk_mul_f32 v[98:99], v[64:65], v[64:65]
	v_pk_mul_f32 v[58:59], v[60:61], v[60:61]
	s_nop 0
	v_mov_b32_e32 v83, v58
	v_mov_b32_e32 v93, v59
	v_mov_b32_e32 v95, v98
	v_mov_b32_e32 v97, v99
	v_pk_add_f32 v[58:59], v[82:83], v[92:93]
	v_pk_add_f32 v[82:83], v[94:95], v[96:97]
	s_nop 0
	v_pk_add_f32 v[58:59], v[58:59], v[82:83]
	s_nop 0
	v_add_f32_e32 v58, v58, v59
	s_nop 1
	v_add_f32_dpp v58, v58, v58 quad_perm:[1,0,3,2] row_mask:0xf bank_mask:0xf bound_ctrl:1
	s_nop 1
	v_add_f32_dpp v58, v58, v58 quad_perm:[2,3,0,1] row_mask:0xf bank_mask:0xf bound_ctrl:1
	s_nop 1
	v_add_f32_dpp v58, v58, v58 row_half_mirror row_mask:0xf bank_mask:0xf bound_ctrl:1
	s_nop 1
	v_add_f32_dpp v58, v58, v58 row_mirror row_mask:0xf bank_mask:0xf bound_ctrl:1
	s_nop 0
	v_readlane_b32 s5, v58, 16
	v_readlane_b32 s11, v58, 48
	v_readlane_b32 s6, v58, 0
	v_readlane_b32 s7, v58, 32
	v_mov_b32_e32 v58, s5
	v_mov_b32_e32 v59, s11
; __device__ __forceinline__ void norm_mod_phase2(const Args& a, Frame& F, const float* gain, const float* modl, int sh_off, int sc_off, int nrows, const float* slab_gate) {
;     ...
;     NR_FINISH(r4, nw + 4 * 2048, (nw + 4 * 2048) >> 12);
;     NR_FINISH(r5, nw + 5 * 2048, (nw + 5 * 2048) >> 12);
	v_pk_add_f32 v[58:59], s[6:7], v[58:59]
	s_lshl_b32 s5, s22, 1
	v_add_f32_e32 v58, v58, v59
	v_fmamk_f32 v58, v58, 0x3a000000, v252
	v_cmp_gt_f32_e32 vcc, s55, v58
	v_mul_f32_e32 v59, 0x4f800000, v58
	s_and_b32 s5, s5, 0xffffe000
	v_cndmask_b32_e32 v58, v58, v59, vcc
	v_sqrt_f32_e32 v59, v58
	s_add_i32 s5, s5, 0
	v_add_u32_e32 v82, -1, v59
	v_fma_f32 v83, -v82, v59, v58
	v_cmp_ge_f32_e64 s[6:7], 0, v83
	v_add_u32_e32 v83, 1, v59
	s_nop 0
	v_cndmask_b32_e64 v82, v59, v82, s[6:7]
	v_fma_f32 v59, -v83, v59, v58
	v_cmp_lt_f32_e64 s[6:7], 0, v59
	s_nop 1
	v_cndmask_b32_e64 v59, v82, v83, s[6:7]
	v_mul_f32_e32 v82, 0x37800000, v59
	v_cndmask_b32_e32 v59, v59, v82, vcc
	v_cmp_class_f32_e32 vcc, v58, v253
	s_nop 1
	v_cndmask_b32_e32 v58, v59, v58, vcc
	v_div_scale_f32 v59, s[6:7], v58, v58, 1.0
	v_rcp_f32_e32 v82, v59
	s_nop 0
	v_fma_f32 v83, -v59, v82, 1.0
	v_fmac_f32_e32 v82, v83, v82
	v_div_scale_f32 v83, vcc, 1.0, v58, 1.0
	v_mul_f32_e32 v92, v83, v82
	v_fma_f32 v93, -v59, v92, v83
	v_fmac_f32_e32 v92, v93, v82
	v_fma_f32 v59, -v59, v92, v83
	v_div_fmas_f32 v59, v59, v82, v92
	v_div_fixup_f32 v82, v59, v58, 1.0
	v_pk_mul_f32 v[96:97], v[88:89], v[82:83] op_sel_hi:[1,0]
	v_pk_mul_f32 v[98:99], v[90:91], v[82:83] op_sel_hi:[1,0]
	v_add_u32_e32 v83, s5, v0
	ds_read_b128 v[88:91], v83
	ds_read_b128 v[92:95], v83 offset:40960
	v_lshl_add_u64 v[58:59], s[24:25], 1, v[2:3]
	v_lshl_add_u64 v[58:59], v[58:59], 0, v[6:7]
	v_pk_mul_f32 v[4:5], v[4:5], v[82:83] op_sel_hi:[1,0]
	v_pk_mul_f32 v[62:63], v[62:63], v[82:83] op_sel_hi:[1,0]
	s_waitcnt lgkmcnt(0)
	v_pk_fma_f32 v[90:91], v[90:91], v[98:99], v[94:95]
	v_pk_fma_f32 v[88:89], v[88:89], v[96:97], v[92:93]
	v_pk_mul_f32 v[92:93], v[84:85], v[82:83] op_sel_hi:[1,0]
	v_cvt_pk_bf16_f32 v88, v88, v89
	v_cvt_pk_bf16_f32 v89, v90, v91
	global_store_dwordx2 v[58:59], v[88:89], off nt
	v_pk_mul_f32 v[94:95], v[86:87], v[82:83] op_sel_hi:[1,0]
	ds_read_b128 v[84:87], v83 offset:1024
	ds_read_b128 v[88:91], v83 offset:41984
	s_waitcnt lgkmcnt(0)
	v_pk_fma_f32 v[86:87], v[86:87], v[94:95], v[90:91]
	v_pk_fma_f32 v[84:85], v[84:85], v[92:93], v[88:89]
	v_pk_mul_f32 v[88:89], v[74:75], v[82:83] op_sel_hi:[1,0]
	v_cvt_pk_bf16_f32 v84, v84, v85
	v_cvt_pk_bf16_f32 v85, v86, v87
	global_store_dwordx2 v[58:59], v[84:85], off offset:512 nt
	v_pk_mul_f32 v[90:91], v[76:77], v[82:83] op_sel_hi:[1,0]
	ds_read_b128 v[74:77], v83 offset:2048
	ds_read_b128 v[84:87], v83 offset:43008
	s_waitcnt lgkmcnt(0)
	v_pk_fma_f32 v[76:77], v[76:77], v[90:91], v[86:87]
	v_pk_fma_f32 v[74:75], v[74:75], v[88:89], v[84:85]
	v_pk_mul_f32 v[84:85], v[78:79], v[82:83] op_sel_hi:[1,0]
	v_cvt_pk_bf16_f32 v74, v74, v75
	v_cvt_pk_bf16_f32 v75, v76, v77
	global_store_dwordx2 v[58:59], v[74:75], off offset:1024 nt
	v_pk_mul_f32 v[86:87], v[80:81], v[82:83] op_sel_hi:[1,0]
	ds_read_b128 v[74:77], v83 offset:3072
	ds_read_b128 v[78:81], v83 offset:44032
	s_waitcnt lgkmcnt(0)
	v_pk_fma_f32 v[76:77], v[86:87], v[76:77], v[80:81]
	v_pk_fma_f32 v[74:75], v[84:85], v[74:75], v[78:79]
	v_pk_mul_f32 v[78:79], v[66:67], v[82:83] op_sel_hi:[1,0]
	v_cvt_pk_bf16_f32 v74, v74, v75
	v_cvt_pk_bf16_f32 v75, v76, v77
	global_store_dwordx2 v[58:59], v[74:75], off offset:1536 nt
	v_pk_mul_f32 v[80:81], v[68:69], v[82:83] op_sel_hi:[1,0]
	ds_read_b128 v[66:69], v83 offset:4096
	ds_read_b128 v[74:77], v83 offset:45056
	s_waitcnt lgkmcnt(0)
	v_pk_fma_f32 v[68:69], v[80:81], v[68:69], v[76:77]
	v_pk_fma_f32 v[66:67], v[78:79], v[66:67], v[74:75]
	v_pk_mul_f32 v[74:75], v[70:71], v[82:83] op_sel_hi:[1,0]
	v_cvt_pk_bf16_f32 v66, v66, v67
	v_cvt_pk_bf16_f32 v67, v68, v69
	global_store_dwordx2 v[58:59], v[66:67], off offset:2048 nt
	v_pk_mul_f32 v[76:77], v[72:73], v[82:83] op_sel_hi:[1,0]
	ds_read_b128 v[66:69], v83 offset:5120
	ds_read_b128 v[70:73], v83 offset:46080
	s_waitcnt lgkmcnt(0)
	v_pk_fma_f32 v[68:69], v[76:77], v[68:69], v[72:73]
	v_pk_fma_f32 v[66:67], v[74:75], v[66:67], v[70:71]
	s_waitcnt vmcnt(60)
	v_cvt_f32_f16_sdwa v75, v57 dst_sel:DWORD dst_unused:UNUSED_PAD src0_sel:WORD_1
	v_cvt_pk_bf16_f32 v66, v66, v67
	v_cvt_pk_bf16_f32 v67, v68, v69
	global_store_dwordx2 v[58:59], v[66:67], off offset:2560 nt
	ds_read_b128 v[66:69], v83 offset:6144
	ds_read_b128 v[70:73], v83 offset:47104
	v_cvt_f32_f16_e32 v74, v57
	s_waitcnt lgkmcnt(0)
	v_pk_fma_f32 v[62:63], v[62:63], v[68:69], v[72:73]
	v_pk_fma_f32 v[4:5], v[4:5], v[66:67], v[70:71]
	v_pk_mul_f32 v[68:69], v[64:65], v[82:83] op_sel_hi:[1,0]
	v_cvt_pk_bf16_f32 v4, v4, v5
	v_cvt_pk_bf16_f32 v5, v62, v63
	global_store_dwordx2 v[58:59], v[4:5], off offset:3072 nt
	v_pk_mul_f32 v[4:5], v[60:61], v[82:83] op_sel_hi:[1,0]
	ds_read_b128 v[60:63], v83 offset:7168
	ds_read_b128 v[64:67], v83 offset:48128
	v_cvt_f32_f16_sdwa v73, v56 dst_sel:DWORD dst_unused:UNUSED_PAD src0_sel:WORD_1
	v_cvt_f32_f16_e32 v72, v56
	s_waitcnt vmcnt(61)
	v_cvt_f32_f16_sdwa v71, v55 dst_sel:DWORD dst_unused:UNUSED_PAD src0_sel:WORD_1
	v_cvt_f32_f16_e32 v70, v55
	s_waitcnt lgkmcnt(0)
	v_pk_fma_f32 v[62:63], v[68:69], v[62:63], v[66:67]
	v_cvt_f32_f16_sdwa v69, v54 dst_sel:DWORD dst_unused:UNUSED_PAD src0_sel:WORD_1
	v_cvt_f32_f16_e32 v68, v54
	v_pk_fma_f32 v[4:5], v[4:5], v[60:61], v[64:65]
	v_mov_b32_e32 v54, v73
	v_cvt_pk_bf16_f32 v4, v4, v5
	v_cvt_pk_bf16_f32 v5, v62, v63
	global_store_dwordx2 v[58:59], v[4:5], off offset:3584 nt
	v_mov_b32_e32 v55, v69
	s_waitcnt vmcnt(61)
	v_cvt_f32_f16_sdwa v59, v52 dst_sel:DWORD dst_unused:UNUSED_PAD src0_sel:WORD_1
	v_cvt_f32_f16_sdwa v61, v53 dst_sel:DWORD dst_unused:UNUSED_PAD src0_sel:WORD_1
	v_mov_b32_e32 v4, v72
	v_mov_b32_e32 v5, v68
	v_pk_mul_f32 v[54:55], v[54:55], v[54:55]
	v_mov_b32_e32 v56, v75
	v_mov_b32_e32 v57, v71
	v_cvt_f32_f16_e32 v58, v52
	v_cvt_f32_f16_e32 v60, v53
	s_waitcnt vmcnt(60)
; __device__ __forceinline__ void norm_mod_phase2(const Args& a, Frame& F, const float* gain, const float* modl, int sh_off, int sc_off, int nrows, const float* slab_gate) {
;     ...
;     NR_FINISH(r5, nw + 5 * 2048, (nw + 5 * 2048) >> 12);
;     NR_FINISH(r6, nw + 6 * 2048, (nw + 6 * 2048) >> 12);
	v_cvt_f32_f16_sdwa v63, v50 dst_sel:DWORD dst_unused:UNUSED_PAD src0_sel:WORD_1
	v_pk_fma_f32 v[4:5], v[4:5], v[4:5], v[54:55]
	v_mov_b32_e32 v54, v74
	v_mov_b32_e32 v55, v70
	v_pk_mul_f32 v[56:57], v[56:57], v[56:57]
	v_cvt_f32_f16_e32 v62, v50
	v_cvt_f32_f16_sdwa v65, v51 dst_sel:DWORD dst_unused:UNUSED_PAD src0_sel:WORD_1
	v_pk_fma_f32 v[54:55], v[54:55], v[54:55], v[56:57]
	v_cvt_f32_f16_e32 v64, v51
	v_pk_add_f32 v[4:5], v[4:5], v[54:55]
	v_mov_b32_e32 v54, v59
	v_mov_b32_e32 v55, v61
	v_mov_b32_e32 v52, v58
	v_mov_b32_e32 v53, v60
	v_pk_mul_f32 v[54:55], v[54:55], v[54:55]
	v_mul_f32_e32 v50, v63, v63
	v_pk_fma_f32 v[52:53], v[52:53], v[52:53], v[54:55]
	v_pk_fma_f32 v[56:57], v[62:63], v[62:63], v[50:51] op_sel_hi:[1,1,0]
	v_mul_f32_e32 v50, v65, v65
	v_pk_add_f32 v[54:55], v[52:53], v[52:53] op_sel:[0,1] op_sel_hi:[1,0]
	v_pk_fma_f32 v[66:67], v[64:65], v[64:65], v[50:51] op_sel_hi:[1,1,0]
	s_waitcnt vmcnt(59)
	v_cvt_f32_f16_sdwa v51, v48 dst_sel:DWORD dst_unused:UNUSED_PAD src0_sel:WORD_1
	v_cvt_f32_f16_e32 v50, v48
	v_cvt_f32_f16_sdwa v53, v49 dst_sel:DWORD dst_unused:UNUSED_PAD src0_sel:WORD_1
	v_cvt_f32_f16_e32 v52, v49
	v_pk_add_f32 v[4:5], v[4:5], v[4:5] op_sel:[0,1] op_sel_hi:[1,0]
	v_pk_mul_f32 v[48:49], v[50:51], v[50:51]
	v_pk_mul_f32 v[76:77], v[52:53], v[52:53]
	v_mov_b32_e32 v5, v48
	v_mov_b32_e32 v55, v49
	v_mov_b32_e32 v57, v76
	v_mov_b32_e32 v67, v77
	v_pk_add_f32 v[4:5], v[4:5], v[54:55]
	v_pk_add_f32 v[48:49], v[56:57], v[66:67]
	s_waitcnt vmcnt(58)
	v_cvt_f32_f16_sdwa v55, v46 dst_sel:DWORD dst_unused:UNUSED_PAD src0_sel:WORD_1
	v_cvt_f32_f16_sdwa v57, v47 dst_sel:DWORD dst_unused:UNUSED_PAD src0_sel:WORD_1
	v_cvt_f32_f16_e32 v54, v46
	v_cvt_f32_f16_e32 v56, v47
	v_pk_add_f32 v[4:5], v[4:5], v[48:49]
	v_mov_b32_e32 v46, v55
	v_mov_b32_e32 v47, v57
	v_pk_add_f32 v[66:67], v[4:5], v[4:5] op_sel:[0,1] op_sel_hi:[1,0]
	v_mov_b32_e32 v4, v54
	v_mov_b32_e32 v5, v56
	v_pk_mul_f32 v[46:47], v[46:47], v[46:47]
	s_waitcnt vmcnt(56)
	v_cvt_f32_f16_sdwa v49, v43 dst_sel:DWORD dst_unused:UNUSED_PAD src0_sel:WORD_1
	v_pk_fma_f32 v[4:5], v[4:5], v[4:5], v[46:47]
	v_cvt_f32_f16_sdwa v47, v45 dst_sel:DWORD dst_unused:UNUSED_PAD src0_sel:WORD_1
	v_pk_add_f32 v[76:77], v[4:5], v[4:5] op_sel:[0,1] op_sel_hi:[1,0]
	v_cvt_f32_f16_sdwa v5, v44 dst_sel:DWORD dst_unused:UNUSED_PAD src0_sel:WORD_1
	v_cvt_f32_f16_e32 v4, v44
	v_cvt_f32_f16_e32 v46, v45
	v_cvt_f32_f16_e32 v48, v43
	v_mul_f32_e32 v44, v5, v5
	v_pk_fma_f32 v[78:79], v[4:5], v[4:5], v[44:45] op_sel_hi:[1,1,0]
	v_mul_f32_e32 v44, v47, v47
	v_pk_fma_f32 v[80:81], v[46:47], v[46:47], v[44:45] op_sel_hi:[1,1,0]
	v_cvt_f32_f16_sdwa v45, v42 dst_sel:DWORD dst_unused:UNUSED_PAD src0_sel:WORD_1
	v_cvt_f32_f16_e32 v44, v42
	v_pk_mul_f32 v[82:83], v[48:49], v[48:49]
	v_pk_mul_f32 v[42:43], v[44:45], v[44:45]
	s_nop 0
	v_mov_b32_e32 v67, v42
	v_mov_b32_e32 v77, v43
	v_mov_b32_e32 v79, v82
	v_mov_b32_e32 v81, v83
	v_pk_add_f32 v[42:43], v[66:67], v[76:77]
	v_pk_add_f32 v[66:67], v[78:79], v[80:81]
	s_nop 0
	v_pk_add_f32 v[42:43], v[42:43], v[66:67]
	s_nop 0
	v_add_f32_e32 v42, v42, v43
	s_nop 1
	v_add_f32_dpp v42, v42, v42 quad_perm:[1,0,3,2] row_mask:0xf bank_mask:0xf bound_ctrl:1
	s_nop 1
	v_add_f32_dpp v42, v42, v42 quad_perm:[2,3,0,1] row_mask:0xf bank_mask:0xf bound_ctrl:1
	s_nop 1
	v_add_f32_dpp v42, v42, v42 row_half_mirror row_mask:0xf bank_mask:0xf bound_ctrl:1
	s_nop 1
	v_add_f32_dpp v42, v42, v42 row_mirror row_mask:0xf bank_mask:0xf bound_ctrl:1
	s_nop 0
	v_readlane_b32 s5, v42, 16
	v_readlane_b32 s11, v42, 48
	v_readlane_b32 s6, v42, 0
	v_readlane_b32 s7, v42, 32
	v_mov_b32_e32 v42, s5
	v_mov_b32_e32 v43, s11
	v_pk_add_f32 v[42:43], s[6:7], v[42:43]
	s_lshl_b32 s5, s18, 1
	v_add_f32_e32 v42, v42, v43
	v_fmamk_f32 v42, v42, 0x3a000000, v252
	v_cmp_gt_f32_e32 vcc, s55, v42
	v_mul_f32_e32 v43, 0x4f800000, v42
	s_and_b32 s5, s5, 0xffffe000
	v_cndmask_b32_e32 v42, v42, v43, vcc
	v_sqrt_f32_e32 v43, v42
	s_add_i32 s5, s5, 0
	v_add_u32_e32 v66, -1, v43
	v_fma_f32 v67, -v66, v43, v42
	v_cmp_ge_f32_e64 s[6:7], 0, v67
	v_add_u32_e32 v67, 1, v43
	s_nop 0
	v_cndmask_b32_e64 v66, v43, v66, s[6:7]
	v_fma_f32 v43, -v67, v43, v42
	v_cmp_lt_f32_e64 s[6:7], 0, v43
	s_nop 1
	v_cndmask_b32_e64 v43, v66, v67, s[6:7]
	v_mul_f32_e32 v66, 0x37800000, v43
	v_cndmask_b32_e32 v43, v43, v66, vcc
	v_cmp_class_f32_e32 vcc, v42, v253
	s_nop 1
	v_cndmask_b32_e32 v42, v43, v42, vcc
	v_div_scale_f32 v43, s[6:7], v42, v42, 1.0
	v_rcp_f32_e32 v66, v43
	s_nop 0
	v_fma_f32 v67, -v43, v66, 1.0
	v_fmac_f32_e32 v66, v67, v66
	v_div_scale_f32 v67, vcc, 1.0, v42, 1.0
	v_mul_f32_e32 v76, v67, v66
	v_fma_f32 v77, -v43, v76, v67
	v_fmac_f32_e32 v76, v77, v66
	v_fma_f32 v43, -v43, v76, v67
	v_div_fmas_f32 v43, v43, v66, v76
	v_div_fixup_f32 v66, v43, v42, 1.0
	v_pk_mul_f32 v[80:81], v[72:73], v[66:67] op_sel_hi:[1,0]
	v_pk_mul_f32 v[82:83], v[74:75], v[66:67] op_sel_hi:[1,0]
	v_add_u32_e32 v67, s5, v0
	ds_read_b128 v[72:75], v67
	ds_read_b128 v[76:79], v67 offset:40960
	v_lshl_add_u64 v[42:43], s[20:21], 1, v[2:3]
	v_lshl_add_u64 v[42:43], v[42:43], 0, v[6:7]
	v_pk_mul_f32 v[4:5], v[4:5], v[66:67] op_sel_hi:[1,0]
	v_pk_mul_f32 v[46:47], v[46:47], v[66:67] op_sel_hi:[1,0]
	s_waitcnt lgkmcnt(0)
	v_pk_fma_f32 v[74:75], v[74:75], v[82:83], v[78:79]
	v_pk_fma_f32 v[72:73], v[72:73], v[80:81], v[76:77]
	v_pk_mul_f32 v[76:77], v[68:69], v[66:67] op_sel_hi:[1,0]
	v_cvt_pk_bf16_f32 v72, v72, v73
	v_cvt_pk_bf16_f32 v73, v74, v75
	global_store_dwordx2 v[42:43], v[72:73], off nt
	v_pk_mul_f32 v[78:79], v[70:71], v[66:67] op_sel_hi:[1,0]
	ds_read_b128 v[68:71], v67 offset:1024
	ds_read_b128 v[72:75], v67 offset:41984
	s_waitcnt lgkmcnt(0)
; __device__ __forceinline__ void norm_mod_phase2(const Args& a, Frame& F, const float* gain, const float* modl, int sh_off, int sc_off, int nrows, const float* slab_gate) {
;     ...
;     NR_FINISH(r6, nw + 6 * 2048, (nw + 6 * 2048) >> 12);
;     NR_FINISH(r7, nw + 7 * 2048, (nw + 7 * 2048) >> 12);
	v_pk_fma_f32 v[70:71], v[70:71], v[78:79], v[74:75]
	v_pk_fma_f32 v[68:69], v[68:69], v[76:77], v[72:73]
	v_pk_mul_f32 v[72:73], v[58:59], v[66:67] op_sel_hi:[1,0]
	v_cvt_pk_bf16_f32 v68, v68, v69
	v_cvt_pk_bf16_f32 v69, v70, v71
	global_store_dwordx2 v[42:43], v[68:69], off offset:512 nt
	v_pk_mul_f32 v[74:75], v[60:61], v[66:67] op_sel_hi:[1,0]
	ds_read_b128 v[58:61], v67 offset:2048
	ds_read_b128 v[68:71], v67 offset:43008
	s_waitcnt lgkmcnt(0)
	v_pk_fma_f32 v[60:61], v[60:61], v[74:75], v[70:71]
	v_pk_fma_f32 v[58:59], v[58:59], v[72:73], v[68:69]
	v_pk_mul_f32 v[68:69], v[62:63], v[66:67] op_sel_hi:[1,0]
	v_cvt_pk_bf16_f32 v58, v58, v59
	v_cvt_pk_bf16_f32 v59, v60, v61
	global_store_dwordx2 v[42:43], v[58:59], off offset:1024 nt
	v_pk_mul_f32 v[70:71], v[64:65], v[66:67] op_sel_hi:[1,0]
	ds_read_b128 v[58:61], v67 offset:3072
	ds_read_b128 v[62:65], v67 offset:44032
	s_waitcnt lgkmcnt(0)
	v_pk_fma_f32 v[60:61], v[70:71], v[60:61], v[64:65]
	v_pk_fma_f32 v[58:59], v[68:69], v[58:59], v[62:63]
	v_pk_mul_f32 v[62:63], v[50:51], v[66:67] op_sel_hi:[1,0]
	v_cvt_pk_bf16_f32 v58, v58, v59
	v_cvt_pk_bf16_f32 v59, v60, v61
	global_store_dwordx2 v[42:43], v[58:59], off offset:1536 nt
	v_pk_mul_f32 v[64:65], v[52:53], v[66:67] op_sel_hi:[1,0]
	ds_read_b128 v[50:53], v67 offset:4096
	ds_read_b128 v[58:61], v67 offset:45056
	s_waitcnt lgkmcnt(0)
	v_pk_fma_f32 v[52:53], v[64:65], v[52:53], v[60:61]
	v_pk_fma_f32 v[50:51], v[62:63], v[50:51], v[58:59]
	v_pk_mul_f32 v[58:59], v[54:55], v[66:67] op_sel_hi:[1,0]
	v_cvt_pk_bf16_f32 v50, v50, v51
	v_cvt_pk_bf16_f32 v51, v52, v53
	global_store_dwordx2 v[42:43], v[50:51], off offset:2048 nt
	v_pk_mul_f32 v[60:61], v[56:57], v[66:67] op_sel_hi:[1,0]
	ds_read_b128 v[50:53], v67 offset:5120
	ds_read_b128 v[54:57], v67 offset:46080
	s_waitcnt lgkmcnt(0)
	v_pk_fma_f32 v[52:53], v[60:61], v[52:53], v[56:57]
	v_pk_fma_f32 v[50:51], v[58:59], v[50:51], v[54:55]
	s_waitcnt vmcnt(60)
	v_cvt_f32_f16_sdwa v59, v41 dst_sel:DWORD dst_unused:UNUSED_PAD src0_sel:WORD_1
	v_cvt_pk_bf16_f32 v50, v50, v51
	v_cvt_pk_bf16_f32 v51, v52, v53
	global_store_dwordx2 v[42:43], v[50:51], off offset:2560 nt
	ds_read_b128 v[50:53], v67 offset:6144
	ds_read_b128 v[54:57], v67 offset:47104
	v_cvt_f32_f16_e32 v58, v41
	s_waitcnt lgkmcnt(0)
	v_pk_fma_f32 v[46:47], v[46:47], v[52:53], v[56:57]
	v_pk_fma_f32 v[4:5], v[4:5], v[50:51], v[54:55]
	v_pk_mul_f32 v[52:53], v[48:49], v[66:67] op_sel_hi:[1,0]
	v_cvt_pk_bf16_f32 v4, v4, v5
	v_cvt_pk_bf16_f32 v5, v46, v47
	global_store_dwordx2 v[42:43], v[4:5], off offset:3072 nt
	v_pk_mul_f32 v[4:5], v[44:45], v[66:67] op_sel_hi:[1,0]
	ds_read_b128 v[44:47], v67 offset:7168
	ds_read_b128 v[48:51], v67 offset:48128
	v_cvt_f32_f16_sdwa v57, v40 dst_sel:DWORD dst_unused:UNUSED_PAD src0_sel:WORD_1
	v_cvt_f32_f16_e32 v56, v40
	s_waitcnt vmcnt(61)
	v_cvt_f32_f16_sdwa v55, v39 dst_sel:DWORD dst_unused:UNUSED_PAD src0_sel:WORD_1
	v_cvt_f32_f16_e32 v54, v39
	s_waitcnt lgkmcnt(0)
	v_pk_fma_f32 v[46:47], v[52:53], v[46:47], v[50:51]
	v_cvt_f32_f16_sdwa v53, v38 dst_sel:DWORD dst_unused:UNUSED_PAD src0_sel:WORD_1
	v_cvt_f32_f16_e32 v52, v38
	v_pk_fma_f32 v[4:5], v[4:5], v[44:45], v[48:49]
	v_mov_b32_e32 v38, v57
	v_cvt_pk_bf16_f32 v4, v4, v5
	v_cvt_pk_bf16_f32 v5, v46, v47
	global_store_dwordx2 v[42:43], v[4:5], off offset:3584 nt
	v_mov_b32_e32 v39, v53
	s_waitcnt vmcnt(61)
	v_cvt_f32_f16_sdwa v43, v36 dst_sel:DWORD dst_unused:UNUSED_PAD src0_sel:WORD_1
	v_cvt_f32_f16_sdwa v45, v37 dst_sel:DWORD dst_unused:UNUSED_PAD src0_sel:WORD_1
	v_mov_b32_e32 v4, v56
	v_mov_b32_e32 v5, v52
	v_pk_mul_f32 v[38:39], v[38:39], v[38:39]
	v_mov_b32_e32 v40, v59
	v_mov_b32_e32 v41, v55
	v_cvt_f32_f16_e32 v42, v36
	v_cvt_f32_f16_e32 v44, v37
	s_waitcnt vmcnt(60)
	v_cvt_f32_f16_sdwa v47, v34 dst_sel:DWORD dst_unused:UNUSED_PAD src0_sel:WORD_1
	v_pk_fma_f32 v[4:5], v[4:5], v[4:5], v[38:39]
	v_mov_b32_e32 v38, v58
	v_mov_b32_e32 v39, v54
	v_pk_mul_f32 v[40:41], v[40:41], v[40:41]
	v_cvt_f32_f16_e32 v46, v34
	v_cvt_f32_f16_sdwa v49, v35 dst_sel:DWORD dst_unused:UNUSED_PAD src0_sel:WORD_1
	v_pk_fma_f32 v[38:39], v[38:39], v[38:39], v[40:41]
	v_cvt_f32_f16_e32 v48, v35
	v_pk_add_f32 v[4:5], v[4:5], v[38:39]
	v_mov_b32_e32 v38, v43
	v_mov_b32_e32 v39, v45
	v_mov_b32_e32 v36, v42
	v_mov_b32_e32 v37, v44
	v_pk_mul_f32 v[38:39], v[38:39], v[38:39]
	v_mul_f32_e32 v34, v47, v47
	v_pk_fma_f32 v[36:37], v[36:37], v[36:37], v[38:39]
	v_pk_fma_f32 v[40:41], v[46:47], v[46:47], v[34:35] op_sel_hi:[1,1,0]
	v_mul_f32_e32 v34, v49, v49
	v_pk_add_f32 v[38:39], v[36:37], v[36:37] op_sel:[0,1] op_sel_hi:[1,0]
	v_pk_fma_f32 v[50:51], v[48:49], v[48:49], v[34:35] op_sel_hi:[1,1,0]
	s_waitcnt vmcnt(59)
	v_cvt_f32_f16_sdwa v35, v32 dst_sel:DWORD dst_unused:UNUSED_PAD src0_sel:WORD_1
	v_cvt_f32_f16_e32 v34, v32
	v_cvt_f32_f16_sdwa v37, v33 dst_sel:DWORD dst_unused:UNUSED_PAD src0_sel:WORD_1
	v_cvt_f32_f16_e32 v36, v33
	v_pk_add_f32 v[4:5], v[4:5], v[4:5] op_sel:[0,1] op_sel_hi:[1,0]
	v_pk_mul_f32 v[32:33], v[34:35], v[34:35]
	v_pk_mul_f32 v[60:61], v[36:37], v[36:37]
	v_mov_b32_e32 v5, v32
	v_mov_b32_e32 v39, v33
	v_mov_b32_e32 v41, v60
	v_mov_b32_e32 v51, v61
	v_pk_add_f32 v[4:5], v[4:5], v[38:39]
	v_pk_add_f32 v[32:33], v[40:41], v[50:51]
	s_waitcnt vmcnt(58)
	v_cvt_f32_f16_sdwa v39, v30 dst_sel:DWORD dst_unused:UNUSED_PAD src0_sel:WORD_1
	v_cvt_f32_f16_sdwa v41, v31 dst_sel:DWORD dst_unused:UNUSED_PAD src0_sel:WORD_1
	v_cvt_f32_f16_e32 v38, v30
	v_cvt_f32_f16_e32 v40, v31
	v_pk_add_f32 v[4:5], v[4:5], v[32:33]
	v_mov_b32_e32 v30, v39
	v_mov_b32_e32 v31, v41
	v_pk_add_f32 v[50:51], v[4:5], v[4:5] op_sel:[0,1] op_sel_hi:[1,0]
	v_mov_b32_e32 v4, v38
	v_mov_b32_e32 v5, v40
	v_pk_mul_f32 v[30:31], v[30:31], v[30:31]
	s_waitcnt vmcnt(56)
; __device__ __forceinline__ void norm_mod_phase2(const Args& a, Frame& F, const float* gain, const float* modl, int sh_off, int sc_off, int nrows, const float* slab_gate) {
;     ...
;     NR_FINISH(r6, nw + 6 * 2048, (nw + 6 * 2048) >> 12);
;     NR_FINISH(r7, nw + 7 * 2048, (nw + 7 * 2048) >> 12);
	v_cvt_f32_f16_sdwa v33, v27 dst_sel:DWORD dst_unused:UNUSED_PAD src0_sel:WORD_1
	v_pk_fma_f32 v[4:5], v[4:5], v[4:5], v[30:31]
	v_cvt_f32_f16_sdwa v31, v29 dst_sel:DWORD dst_unused:UNUSED_PAD src0_sel:WORD_1
	v_pk_add_f32 v[60:61], v[4:5], v[4:5] op_sel:[0,1] op_sel_hi:[1,0]
	v_cvt_f32_f16_sdwa v5, v28 dst_sel:DWORD dst_unused:UNUSED_PAD src0_sel:WORD_1
	v_cvt_f32_f16_e32 v4, v28
	v_cvt_f32_f16_e32 v30, v29
	v_cvt_f32_f16_e32 v32, v27
	v_mul_f32_e32 v28, v5, v5
	v_pk_fma_f32 v[62:63], v[4:5], v[4:5], v[28:29] op_sel_hi:[1,1,0]
	v_mul_f32_e32 v28, v31, v31
	v_pk_fma_f32 v[64:65], v[30:31], v[30:31], v[28:29] op_sel_hi:[1,1,0]
	v_cvt_f32_f16_sdwa v29, v26 dst_sel:DWORD dst_unused:UNUSED_PAD src0_sel:WORD_1
	v_cvt_f32_f16_e32 v28, v26
	v_pk_mul_f32 v[66:67], v[32:33], v[32:33]
	v_pk_mul_f32 v[26:27], v[28:29], v[28:29]
	s_nop 0
	v_mov_b32_e32 v51, v26
	v_mov_b32_e32 v61, v27
	v_mov_b32_e32 v63, v66
	v_mov_b32_e32 v65, v67
	v_pk_add_f32 v[26:27], v[50:51], v[60:61]
	v_pk_add_f32 v[50:51], v[62:63], v[64:65]
	s_nop 0
	v_pk_add_f32 v[26:27], v[26:27], v[50:51]
	s_nop 0
	v_add_f32_e32 v26, v26, v27
	s_nop 1
	v_add_f32_dpp v26, v26, v26 quad_perm:[1,0,3,2] row_mask:0xf bank_mask:0xf bound_ctrl:1
	s_nop 1
	v_add_f32_dpp v26, v26, v26 quad_perm:[2,3,0,1] row_mask:0xf bank_mask:0xf bound_ctrl:1
	s_nop 1
	v_add_f32_dpp v26, v26, v26 row_half_mirror row_mask:0xf bank_mask:0xf bound_ctrl:1
	s_nop 1
	v_add_f32_dpp v26, v26, v26 row_mirror row_mask:0xf bank_mask:0xf bound_ctrl:1
	s_nop 0
	v_readlane_b32 s5, v26, 16
	v_readlane_b32 s11, v26, 48
	v_readlane_b32 s6, v26, 0
	v_readlane_b32 s7, v26, 32
	v_mov_b32_e32 v26, s5
	v_mov_b32_e32 v27, s11
	v_pk_add_f32 v[26:27], s[6:7], v[26:27]
	s_lshl_b32 s5, s14, 1
	v_add_f32_e32 v26, v26, v27
	v_fmamk_f32 v26, v26, 0x3a000000, v252
	v_cmp_gt_f32_e32 vcc, s55, v26
	v_mul_f32_e32 v27, 0x4f800000, v26
	s_and_b32 s5, s5, 0xffffe000
	v_cndmask_b32_e32 v26, v26, v27, vcc
	v_sqrt_f32_e32 v27, v26
	s_add_i32 s5, s5, 0
	v_add_u32_e32 v50, -1, v27
	v_fma_f32 v51, -v50, v27, v26
	v_cmp_ge_f32_e64 s[6:7], 0, v51
	v_add_u32_e32 v51, 1, v27
	s_nop 0
	v_cndmask_b32_e64 v50, v27, v50, s[6:7]
	v_fma_f32 v27, -v51, v27, v26
	v_cmp_lt_f32_e64 s[6:7], 0, v27
	s_nop 1
	v_cndmask_b32_e64 v27, v50, v51, s[6:7]
	v_mul_f32_e32 v50, 0x37800000, v27
	v_cndmask_b32_e32 v27, v27, v50, vcc
	v_cmp_class_f32_e32 vcc, v26, v253
	s_nop 1
	v_cndmask_b32_e32 v26, v27, v26, vcc
	v_div_scale_f32 v27, s[6:7], v26, v26, 1.0
	v_rcp_f32_e32 v50, v27
	s_nop 0
	v_fma_f32 v51, -v27, v50, 1.0
	v_fmac_f32_e32 v50, v51, v50
	v_div_scale_f32 v51, vcc, 1.0, v26, 1.0
	v_mul_f32_e32 v60, v51, v50
	v_fma_f32 v61, -v27, v60, v51
	v_fmac_f32_e32 v60, v61, v50
	v_fma_f32 v27, -v27, v60, v51
	v_div_fmas_f32 v27, v27, v50, v60
	v_div_fixup_f32 v50, v27, v26, 1.0
	v_pk_mul_f32 v[64:65], v[56:57], v[50:51] op_sel_hi:[1,0]
	v_pk_mul_f32 v[66:67], v[58:59], v[50:51] op_sel_hi:[1,0]
	v_add_u32_e32 v51, s5, v0
	ds_read_b128 v[56:59], v51
	ds_read_b128 v[60:63], v51 offset:40960
	v_lshl_add_u64 v[26:27], s[16:17], 1, v[2:3]
	v_lshl_add_u64 v[26:27], v[26:27], 0, v[6:7]
	v_pk_mul_f32 v[4:5], v[4:5], v[50:51] op_sel_hi:[1,0]
	v_pk_mul_f32 v[30:31], v[30:31], v[50:51] op_sel_hi:[1,0]
	s_waitcnt lgkmcnt(0)
	v_pk_fma_f32 v[58:59], v[58:59], v[66:67], v[62:63]
	v_pk_fma_f32 v[56:57], v[56:57], v[64:65], v[60:61]
	v_pk_mul_f32 v[60:61], v[52:53], v[50:51] op_sel_hi:[1,0]
	v_cvt_pk_bf16_f32 v56, v56, v57
	v_cvt_pk_bf16_f32 v57, v58, v59
	global_store_dwordx2 v[26:27], v[56:57], off nt
	v_pk_mul_f32 v[62:63], v[54:55], v[50:51] op_sel_hi:[1,0]
	ds_read_b128 v[52:55], v51 offset:1024
	ds_read_b128 v[56:59], v51 offset:41984
	s_waitcnt lgkmcnt(0)
	v_pk_fma_f32 v[54:55], v[54:55], v[62:63], v[58:59]
	v_pk_fma_f32 v[52:53], v[52:53], v[60:61], v[56:57]
	v_pk_mul_f32 v[56:57], v[42:43], v[50:51] op_sel_hi:[1,0]
	v_cvt_pk_bf16_f32 v52, v52, v53
	v_cvt_pk_bf16_f32 v53, v54, v55
	global_store_dwordx2 v[26:27], v[52:53], off offset:512 nt
	v_pk_mul_f32 v[58:59], v[44:45], v[50:51] op_sel_hi:[1,0]
	ds_read_b128 v[42:45], v51 offset:2048
	ds_read_b128 v[52:55], v51 offset:43008
	s_waitcnt lgkmcnt(0)
	v_pk_fma_f32 v[44:45], v[44:45], v[58:59], v[54:55]
	v_pk_fma_f32 v[42:43], v[42:43], v[56:57], v[52:53]
	v_pk_mul_f32 v[52:53], v[46:47], v[50:51] op_sel_hi:[1,0]
	v_cvt_pk_bf16_f32 v42, v42, v43
	v_cvt_pk_bf16_f32 v43, v44, v45
	global_store_dwordx2 v[26:27], v[42:43], off offset:1024 nt
	v_pk_mul_f32 v[54:55], v[48:49], v[50:51] op_sel_hi:[1,0]
	ds_read_b128 v[42:45], v51 offset:3072
	ds_read_b128 v[46:49], v51 offset:44032
	s_waitcnt lgkmcnt(0)
	v_pk_fma_f32 v[44:45], v[54:55], v[44:45], v[48:49]
	v_pk_fma_f32 v[42:43], v[52:53], v[42:43], v[46:47]
	v_pk_mul_f32 v[46:47], v[34:35], v[50:51] op_sel_hi:[1,0]
	v_cvt_pk_bf16_f32 v42, v42, v43
	v_cvt_pk_bf16_f32 v43, v44, v45
	global_store_dwordx2 v[26:27], v[42:43], off offset:1536 nt
	v_pk_mul_f32 v[48:49], v[36:37], v[50:51] op_sel_hi:[1,0]
	ds_read_b128 v[34:37], v51 offset:4096
	ds_read_b128 v[42:45], v51 offset:45056
	s_waitcnt lgkmcnt(0)
	v_pk_fma_f32 v[36:37], v[48:49], v[36:37], v[44:45]
	v_pk_fma_f32 v[34:35], v[46:47], v[34:35], v[42:43]
	v_pk_mul_f32 v[42:43], v[38:39], v[50:51] op_sel_hi:[1,0]
	v_cvt_pk_bf16_f32 v34, v34, v35
	v_cvt_pk_bf16_f32 v35, v36, v37
	global_store_dwordx2 v[26:27], v[34:35], off offset:2048 nt
	v_pk_mul_f32 v[44:45], v[40:41], v[50:51] op_sel_hi:[1,0]
	ds_read_b128 v[34:37], v51 offset:5120
	ds_read_b128 v[38:41], v51 offset:46080
	s_waitcnt lgkmcnt(0)
	v_pk_fma_f32 v[36:37], v[44:45], v[36:37], v[40:41]
	v_pk_fma_f32 v[34:35], v[42:43], v[34:35], v[38:39]
	s_waitcnt vmcnt(60)
; __device__ __forceinline__ void norm_mod_phase2(const Args& a, Frame& F, const float* gain, const float* modl, int sh_off, int sc_off, int nrows, const float* slab_gate) {
;     ...
;     NR_FINISH(r7, nw + 7 * 2048, (nw + 7 * 2048) >> 12);
;     if (ML + nw < nrows) {
	v_cvt_f32_f16_sdwa v43, v25 dst_sel:DWORD dst_unused:UNUSED_PAD src0_sel:WORD_1
	v_cvt_pk_bf16_f32 v34, v34, v35
	v_cvt_pk_bf16_f32 v35, v36, v37
	global_store_dwordx2 v[26:27], v[34:35], off offset:2560 nt
	ds_read_b128 v[34:37], v51 offset:6144
	ds_read_b128 v[38:41], v51 offset:47104
	v_cvt_f32_f16_e32 v42, v25
	s_waitcnt lgkmcnt(0)
	v_pk_fma_f32 v[30:31], v[30:31], v[36:37], v[40:41]
	v_pk_fma_f32 v[4:5], v[4:5], v[34:35], v[38:39]
	v_pk_mul_f32 v[36:37], v[32:33], v[50:51] op_sel_hi:[1,0]
	v_cvt_pk_bf16_f32 v4, v4, v5
	v_cvt_pk_bf16_f32 v5, v30, v31
	global_store_dwordx2 v[26:27], v[4:5], off offset:3072 nt
	v_pk_mul_f32 v[4:5], v[28:29], v[50:51] op_sel_hi:[1,0]
	ds_read_b128 v[28:31], v51 offset:7168
	ds_read_b128 v[32:35], v51 offset:48128
	v_cvt_f32_f16_sdwa v41, v24 dst_sel:DWORD dst_unused:UNUSED_PAD src0_sel:WORD_1
	v_cvt_f32_f16_e32 v40, v24
	s_waitcnt vmcnt(61)
	v_cvt_f32_f16_sdwa v39, v23 dst_sel:DWORD dst_unused:UNUSED_PAD src0_sel:WORD_1
	v_cvt_f32_f16_e32 v38, v23
	s_waitcnt lgkmcnt(0)
	v_pk_fma_f32 v[30:31], v[36:37], v[30:31], v[34:35]
	v_cvt_f32_f16_sdwa v37, v22 dst_sel:DWORD dst_unused:UNUSED_PAD src0_sel:WORD_1
	v_cvt_f32_f16_e32 v36, v22
	v_pk_fma_f32 v[4:5], v[4:5], v[28:29], v[32:33]
	v_mov_b32_e32 v22, v41
	v_cvt_pk_bf16_f32 v4, v4, v5
	v_cvt_pk_bf16_f32 v5, v30, v31
	global_store_dwordx2 v[26:27], v[4:5], off offset:3584 nt
	v_mov_b32_e32 v23, v37
	s_waitcnt vmcnt(61)
	v_cvt_f32_f16_sdwa v27, v20 dst_sel:DWORD dst_unused:UNUSED_PAD src0_sel:WORD_1
	v_cvt_f32_f16_sdwa v29, v21 dst_sel:DWORD dst_unused:UNUSED_PAD src0_sel:WORD_1
	v_mov_b32_e32 v4, v40
	v_mov_b32_e32 v5, v36
	v_pk_mul_f32 v[22:23], v[22:23], v[22:23]
	v_mov_b32_e32 v24, v43
	v_mov_b32_e32 v25, v39
	v_cvt_f32_f16_e32 v26, v20
	v_cvt_f32_f16_e32 v28, v21
	s_waitcnt vmcnt(60)
	v_cvt_f32_f16_sdwa v31, v18 dst_sel:DWORD dst_unused:UNUSED_PAD src0_sel:WORD_1
	v_pk_fma_f32 v[4:5], v[4:5], v[4:5], v[22:23]
	v_mov_b32_e32 v22, v42
	v_mov_b32_e32 v23, v38
	v_pk_mul_f32 v[24:25], v[24:25], v[24:25]
	v_cvt_f32_f16_e32 v30, v18
	v_cvt_f32_f16_sdwa v33, v19 dst_sel:DWORD dst_unused:UNUSED_PAD src0_sel:WORD_1
	v_pk_fma_f32 v[22:23], v[22:23], v[22:23], v[24:25]
	v_cvt_f32_f16_e32 v32, v19
	v_pk_add_f32 v[4:5], v[4:5], v[22:23]
	v_mov_b32_e32 v22, v27
	v_mov_b32_e32 v23, v29
	v_mov_b32_e32 v20, v26
	v_mov_b32_e32 v21, v28
	v_pk_mul_f32 v[22:23], v[22:23], v[22:23]
	v_mul_f32_e32 v18, v31, v31
	v_pk_fma_f32 v[20:21], v[20:21], v[20:21], v[22:23]
	v_pk_fma_f32 v[24:25], v[30:31], v[30:31], v[18:19] op_sel_hi:[1,1,0]
	v_mul_f32_e32 v18, v33, v33
	v_pk_add_f32 v[22:23], v[20:21], v[20:21] op_sel:[0,1] op_sel_hi:[1,0]
	v_pk_fma_f32 v[34:35], v[32:33], v[32:33], v[18:19] op_sel_hi:[1,1,0]
	s_waitcnt vmcnt(59)
	v_cvt_f32_f16_sdwa v19, v16 dst_sel:DWORD dst_unused:UNUSED_PAD src0_sel:WORD_1
	v_cvt_f32_f16_e32 v18, v16
	v_cvt_f32_f16_sdwa v21, v17 dst_sel:DWORD dst_unused:UNUSED_PAD src0_sel:WORD_1
	v_cvt_f32_f16_e32 v20, v17
	v_pk_add_f32 v[4:5], v[4:5], v[4:5] op_sel:[0,1] op_sel_hi:[1,0]
	v_pk_mul_f32 v[16:17], v[18:19], v[18:19]
	v_pk_mul_f32 v[44:45], v[20:21], v[20:21]
	v_mov_b32_e32 v5, v16
	v_mov_b32_e32 v23, v17
	v_mov_b32_e32 v25, v44
	v_mov_b32_e32 v35, v45
	v_pk_add_f32 v[4:5], v[4:5], v[22:23]
	v_pk_add_f32 v[16:17], v[24:25], v[34:35]
	s_waitcnt vmcnt(58)
	v_cvt_f32_f16_sdwa v23, v14 dst_sel:DWORD dst_unused:UNUSED_PAD src0_sel:WORD_1
	v_cvt_f32_f16_sdwa v25, v15 dst_sel:DWORD dst_unused:UNUSED_PAD src0_sel:WORD_1
	v_cvt_f32_f16_e32 v22, v14
	v_cvt_f32_f16_e32 v24, v15
	v_pk_add_f32 v[4:5], v[4:5], v[16:17]
	v_mov_b32_e32 v14, v23
	v_mov_b32_e32 v15, v25
	v_pk_add_f32 v[34:35], v[4:5], v[4:5] op_sel:[0,1] op_sel_hi:[1,0]
	v_mov_b32_e32 v4, v22
	v_mov_b32_e32 v5, v24
	v_pk_mul_f32 v[14:15], v[14:15], v[14:15]
	s_waitcnt vmcnt(56)
	v_cvt_f32_f16_sdwa v17, v11 dst_sel:DWORD dst_unused:UNUSED_PAD src0_sel:WORD_1
	v_pk_fma_f32 v[4:5], v[4:5], v[4:5], v[14:15]
	v_cvt_f32_f16_sdwa v15, v13 dst_sel:DWORD dst_unused:UNUSED_PAD src0_sel:WORD_1
	v_pk_add_f32 v[44:45], v[4:5], v[4:5] op_sel:[0,1] op_sel_hi:[1,0]
	v_cvt_f32_f16_sdwa v5, v12 dst_sel:DWORD dst_unused:UNUSED_PAD src0_sel:WORD_1
	v_cvt_f32_f16_e32 v4, v12
	v_cvt_f32_f16_e32 v14, v13
	v_cvt_f32_f16_e32 v16, v11
	v_mul_f32_e32 v12, v5, v5
	v_pk_fma_f32 v[46:47], v[4:5], v[4:5], v[12:13] op_sel_hi:[1,1,0]
	v_mul_f32_e32 v12, v15, v15
	v_pk_fma_f32 v[48:49], v[14:15], v[14:15], v[12:13] op_sel_hi:[1,1,0]
	v_cvt_f32_f16_sdwa v13, v10 dst_sel:DWORD dst_unused:UNUSED_PAD src0_sel:WORD_1
	v_cvt_f32_f16_e32 v12, v10
	v_pk_mul_f32 v[50:51], v[16:17], v[16:17]
	v_pk_mul_f32 v[10:11], v[12:13], v[12:13]
	s_nop 0
	v_mov_b32_e32 v35, v10
	v_mov_b32_e32 v45, v11
	v_mov_b32_e32 v47, v50
	v_mov_b32_e32 v49, v51
	v_pk_add_f32 v[10:11], v[34:35], v[44:45]
	v_pk_add_f32 v[34:35], v[46:47], v[48:49]
	s_nop 0
	v_pk_add_f32 v[10:11], v[10:11], v[34:35]
	s_nop 0
	v_add_f32_e32 v10, v10, v11
	s_nop 1
	v_add_f32_dpp v10, v10, v10 quad_perm:[1,0,3,2] row_mask:0xf bank_mask:0xf bound_ctrl:1
	s_nop 1
	v_add_f32_dpp v10, v10, v10 quad_perm:[2,3,0,1] row_mask:0xf bank_mask:0xf bound_ctrl:1
	s_nop 1
	v_add_f32_dpp v10, v10, v10 row_half_mirror row_mask:0xf bank_mask:0xf bound_ctrl:1
	s_nop 1
	v_add_f32_dpp v10, v10, v10 row_mirror row_mask:0xf bank_mask:0xf bound_ctrl:1
	s_nop 0
	v_readlane_b32 s5, v10, 16
	v_readlane_b32 s11, v10, 48
	v_readlane_b32 s6, v10, 0
	v_readlane_b32 s7, v10, 32
	v_mov_b32_e32 v10, s5
	v_mov_b32_e32 v11, s11
	v_pk_add_f32 v[10:11], s[6:7], v[10:11]
	s_lshl_b32 s5, s10, 1
	v_add_f32_e32 v10, v10, v11
	v_fmamk_f32 v10, v10, 0x3a000000, v252
	v_cmp_gt_f32_e32 vcc, s55, v10
	v_mul_f32_e32 v11, 0x4f800000, v10
	s_and_b32 s5, s5, 0xffffe000
	v_cndmask_b32_e32 v10, v10, v11, vcc
	v_sqrt_f32_e32 v11, v10
	s_add_i32 s5, s5, 0
	s_cmpk_lt_i32 s4, 0x400
	v_add_u32_e32 v34, -1, v11
	v_fma_f32 v35, -v34, v11, v10
	v_cmp_ge_f32_e64 s[6:7], 0, v35
	v_add_u32_e32 v35, 1, v11
	s_nop 0
	v_cndmask_b32_e64 v34, v11, v34, s[6:7]
	v_fma_f32 v11, -v35, v11, v10
	v_cmp_lt_f32_e64 s[6:7], 0, v11
	s_nop 1
	v_cndmask_b32_e64 v11, v34, v35, s[6:7]
	v_mul_f32_e32 v34, 0x37800000, v11
	v_cndmask_b32_e32 v11, v11, v34, vcc
	v_cmp_class_f32_e32 vcc, v10, v253
	s_nop 1
	v_cndmask_b32_e32 v10, v11, v10, vcc
	v_div_scale_f32 v11, s[6:7], v10, v10, 1.0
	v_rcp_f32_e32 v34, v11
	s_nop 0
	v_fma_f32 v35, -v11, v34, 1.0
	v_fmac_f32_e32 v34, v35, v34
	v_div_scale_f32 v35, vcc, 1.0, v10, 1.0
	v_mul_f32_e32 v44, v35, v34
	v_fma_f32 v45, -v11, v44, v35
	v_fmac_f32_e32 v44, v45, v34
	v_fma_f32 v11, -v11, v44, v35
	v_div_fmas_f32 v11, v11, v34, v44
	v_div_fixup_f32 v34, v11, v10, 1.0
	v_pk_mul_f32 v[48:49], v[40:41], v[34:35] op_sel_hi:[1,0]
	v_pk_mul_f32 v[50:51], v[42:43], v[34:35] op_sel_hi:[1,0]
	v_add_u32_e32 v35, s5, v0
	ds_read_b128 v[40:43], v35
	ds_read_b128 v[44:47], v35 offset:40960
	v_lshl_add_u64 v[10:11], s[12:13], 1, v[2:3]
	v_lshl_add_u64 v[10:11], v[10:11], 0, v[6:7]
	v_pk_mul_f32 v[4:5], v[4:5], v[34:35] op_sel_hi:[1,0]
	v_pk_mul_f32 v[14:15], v[14:15], v[34:35] op_sel_hi:[1,0]
	s_waitcnt lgkmcnt(0)
; #define GAS __attribute__((address_space(1)))
; __device__ __forceinline__ void norm_mod_phase2(const Args& a, Frame& F, const float* gain, const float* modl, int sh_off, int sc_off, int nrows, const float* slab_gate) {
;     ...
;     NR_FINISH(r7, nw + 7 * 2048, (nw + 7 * 2048) >> 12);
;     if (ML + nw < nrows) {
;         const int r = ML + nw, rc = nw;
;         const GAS v2u* xr = (const GAS v2u*)(X + (size_t)r * D) + F.lane;
; #pragma unroll
;         for (int j = 0; j < 8; ++j) r0[j] = xr[64 * j];
;         if (slab_gate != nullptr) { const GAS f32x4* sl = (const GAS f32x4*)((const float*)(a.ws + WS_SLAB) + (size_t)rc * D) + F.lane;
; #pragma unroll
;             for (int j = 0; j < 8; ++j) { const f32x4 p = (sl[64 * j] + sl[64 * j + (size_t)MC * D / 4]) + (sl[64 * j + 2 * ((size_t)MC * D / 4)] + sl[64 * j + 3 * ((size_t)MC * D / 4)]);
	v_pk_fma_f32 v[42:43], v[42:43], v[50:51], v[46:47]
	v_pk_fma_f32 v[40:41], v[40:41], v[48:49], v[44:45]
	v_pk_mul_f32 v[44:45], v[36:37], v[34:35] op_sel_hi:[1,0]
	v_cvt_pk_bf16_f32 v40, v40, v41
	v_cvt_pk_bf16_f32 v41, v42, v43
	global_store_dwordx2 v[10:11], v[40:41], off nt
	v_pk_mul_f32 v[46:47], v[38:39], v[34:35] op_sel_hi:[1,0]
	ds_read_b128 v[36:39], v35 offset:1024
	ds_read_b128 v[40:43], v35 offset:41984
	s_waitcnt lgkmcnt(0)
	v_pk_fma_f32 v[38:39], v[38:39], v[46:47], v[42:43]
	v_pk_fma_f32 v[36:37], v[36:37], v[44:45], v[40:41]
	v_pk_mul_f32 v[40:41], v[26:27], v[34:35] op_sel_hi:[1,0]
	v_cvt_pk_bf16_f32 v36, v36, v37
	v_cvt_pk_bf16_f32 v37, v38, v39
	global_store_dwordx2 v[10:11], v[36:37], off offset:512 nt
	v_pk_mul_f32 v[42:43], v[28:29], v[34:35] op_sel_hi:[1,0]
	ds_read_b128 v[26:29], v35 offset:2048
	ds_read_b128 v[36:39], v35 offset:43008
	s_waitcnt lgkmcnt(0)
	v_pk_fma_f32 v[28:29], v[28:29], v[42:43], v[38:39]
	v_pk_fma_f32 v[26:27], v[26:27], v[40:41], v[36:37]
	v_pk_mul_f32 v[36:37], v[30:31], v[34:35] op_sel_hi:[1,0]
	v_cvt_pk_bf16_f32 v26, v26, v27
	v_cvt_pk_bf16_f32 v27, v28, v29
	global_store_dwordx2 v[10:11], v[26:27], off offset:1024 nt
	v_pk_mul_f32 v[38:39], v[32:33], v[34:35] op_sel_hi:[1,0]
	ds_read_b128 v[26:29], v35 offset:3072
	ds_read_b128 v[30:33], v35 offset:44032
	s_waitcnt lgkmcnt(0)
	v_pk_fma_f32 v[28:29], v[38:39], v[28:29], v[32:33]
	v_pk_fma_f32 v[26:27], v[36:37], v[26:27], v[30:31]
	v_pk_mul_f32 v[30:31], v[18:19], v[34:35] op_sel_hi:[1,0]
	v_cvt_pk_bf16_f32 v26, v26, v27
	v_cvt_pk_bf16_f32 v27, v28, v29
	global_store_dwordx2 v[10:11], v[26:27], off offset:1536 nt
	v_pk_mul_f32 v[32:33], v[20:21], v[34:35] op_sel_hi:[1,0]
	ds_read_b128 v[18:21], v35 offset:4096
	ds_read_b128 v[26:29], v35 offset:45056
	s_waitcnt lgkmcnt(0)
	v_pk_fma_f32 v[20:21], v[32:33], v[20:21], v[28:29]
	v_pk_fma_f32 v[18:19], v[30:31], v[18:19], v[26:27]
	v_pk_mul_f32 v[26:27], v[22:23], v[34:35] op_sel_hi:[1,0]
	v_cvt_pk_bf16_f32 v18, v18, v19
	v_cvt_pk_bf16_f32 v19, v20, v21
	global_store_dwordx2 v[10:11], v[18:19], off offset:2048 nt
	v_pk_mul_f32 v[28:29], v[24:25], v[34:35] op_sel_hi:[1,0]
	ds_read_b128 v[18:21], v35 offset:5120
	ds_read_b128 v[22:25], v35 offset:46080
	s_waitcnt lgkmcnt(0)
	v_pk_fma_f32 v[20:21], v[28:29], v[20:21], v[24:25]
	v_pk_fma_f32 v[18:19], v[26:27], v[18:19], v[22:23]
	s_nop 0
	v_cvt_pk_bf16_f32 v18, v18, v19
	v_cvt_pk_bf16_f32 v19, v20, v21
	global_store_dwordx2 v[10:11], v[18:19], off offset:2560 nt
	ds_read_b128 v[18:21], v35 offset:6144
	ds_read_b128 v[22:25], v35 offset:47104
	s_waitcnt lgkmcnt(0)
	v_pk_fma_f32 v[14:15], v[14:15], v[20:21], v[24:25]
	v_pk_fma_f32 v[4:5], v[4:5], v[18:19], v[22:23]
	v_pk_mul_f32 v[20:21], v[16:17], v[34:35] op_sel_hi:[1,0]
	v_cvt_pk_bf16_f32 v4, v4, v5
	v_cvt_pk_bf16_f32 v5, v14, v15
	global_store_dwordx2 v[10:11], v[4:5], off offset:3072 nt
	v_pk_mul_f32 v[4:5], v[12:13], v[34:35] op_sel_hi:[1,0]
	ds_read_b128 v[12:15], v35 offset:7168
	ds_read_b128 v[16:19], v35 offset:48128
	s_waitcnt lgkmcnt(0)
	v_pk_fma_f32 v[14:15], v[20:21], v[14:15], v[18:19]
	v_pk_fma_f32 v[4:5], v[4:5], v[12:13], v[16:17]
	s_nop 0
	v_cvt_pk_bf16_f32 v4, v4, v5
	v_cvt_pk_bf16_f32 v5, v14, v15
	global_store_dwordx2 v[10:11], v[4:5], off offset:3584 nt
	s_cbranch_scc0 .LBB0_223
	s_addk_i32 s4, 0x4000
	s_ashr_i32 s5, s4, 31
	s_lshl_b64 s[6:7], s[4:5], 12
	v_lshl_add_u64 v[4:5], v[8:9], 0, s[6:7]
	v_lshl_add_u64 v[18:19], v[4:5], 0, v[6:7]
	global_load_dwordx2 v[22:23], v[18:19], off
	global_load_dwordx2 v[20:21], v[18:19], off offset:512
	global_load_dwordx2 v[16:17], v[18:19], off offset:1024
	global_load_dwordx2 v[12:13], v[18:19], off offset:1536
	global_load_dwordx2 v[14:15], v[18:19], off offset:2048
	global_load_dwordx2 v[10:11], v[18:19], off offset:2560
	global_load_dwordx2 v[8:9], v[18:19], off offset:3072
	global_load_dwordx2 v[4:5], v[18:19], off offset:3584
	v_lshlrev_b32_e32 v40, 2, v143
	s_cmp_eq_u32 s76, 0
	s_cbranch_scc1 .LBB0_222
	v_mov_b32_e32 v24, s72
	v_mov_b32_e32 v25, s73
	v_lshl_add_u64 v[24:25], s[8:9], 2, v[24:25]
	v_lshl_add_u64 v[24:25], v[24:25], 0, v[0:1]
	v_lshlrev_b32_e32 v0, 2, v40
	v_lshl_add_u64 v[26:27], s[86:87], 0, v[0:1]
	v_add_co_u32_e32 v28, vcc, 0x58400000, v24
	s_nop 1
	v_addc_co_u32_e32 v29, vcc, 0, v25, vcc
	v_add_co_u32_e32 v30, vcc, 0x58c00000, v24
	s_nop 1
	v_addc_co_u32_e32 v31, vcc, 0, v25, vcc
	v_add_co_u32_e32 v32, vcc, 0x59400000, v24
	s_nop 1
	v_addc_co_u32_e32 v33, vcc, 0, v25, vcc
	v_add_co_u32_e32 v34, vcc, 0x59c00000, v24
	s_nop 1
	v_addc_co_u32_e32 v35, vcc, 0, v25, vcc
	v_add_co_u32_e32 v36, vcc, 0x58401000, v24
	s_nop 1
	v_addc_co_u32_e32 v37, vcc, 0, v25, vcc
	v_add_co_u32_e32 v38, vcc, 0x58c01000, v24
	s_nop 1
	v_addc_co_u32_e32 v39, vcc, 0, v25, vcc
	v_add_co_u32_e32 v42, vcc, 0x59401000, v24
	s_nop 1
	v_addc_co_u32_e32 v43, vcc, 0, v25, vcc
	v_add_co_u32_e32 v44, vcc, 0x59c01000, v24
	s_nop 1
	v_addc_co_u32_e32 v45, vcc, 0, v25, vcc
	v_add_co_u32_e32 v48, vcc, 0xffffe000, v26
	s_nop 1
	v_addc_co_u32_e32 v49, vcc, -1, v27, vcc
	v_add_co_u32_e32 v50, vcc, 0xfffff000, v26
	s_nop 1
	v_addc_co_u32_e32 v51, vcc, -1, v27, vcc
	global_load_dwordx4 v[94:97], v[28:29], off
	global_load_dwordx4 v[98:101], v[30:31], off
	global_load_dwordx4 v[102:105], v[32:33], off
	global_load_dwordx4 v[106:109], v[34:35], off
	global_load_dwordx4 v[110:113], v[48:49], off
	global_load_dwordx4 v[114:117], v[28:29], off offset:1024
	global_load_dwordx4 v[118:121], v[30:31], off offset:1024
	global_load_dwordx4 v[122:125], v[32:33], off offset:1024
	global_load_dwordx4 v[126:129], v[34:35], off offset:1024
	global_load_dwordx4 v[130:133], v[48:49], off offset:1024
	global_load_dwordx4 v[134:137], v[28:29], off offset:2048
	global_load_dwordx4 v[138:141], v[30:31], off offset:2048
	global_load_dwordx4 v[142:145], v[32:33], off offset:2048
	global_load_dwordx4 v[146:149], v[34:35], off offset:2048
	global_load_dwordx4 v[150:153], v[48:49], off offset:2048
	global_load_dwordx4 v[154:157], v[28:29], off offset:3072
	global_load_dwordx4 v[158:161], v[30:31], off offset:3072
	global_load_dwordx4 v[162:165], v[32:33], off offset:3072
	global_load_dwordx4 v[170:173], v[34:35], off offset:3072
	global_load_dwordx4 v[174:177], v[48:49], off offset:3072
	s_waitcnt vmcnt(15)
; #define GAS __attribute__((address_space(1)))
; __device__ __forceinline__ unsigned xpk2(float lo, float hi) { if (XRES_F16) { const f32x2_t v = {lo, hi}; const f16x2_t h = __builtin_convertvector(v, f16x2_t); return __builtin_bit_cast(unsigned, h); } return pk2(lo, hi); }
; __device__ __forceinline__ float xlo(unsigned w) { if (XRES_F16) { const f16x2_t h = __builtin_bit_cast(f16x2_t, w); return (float)h[0]; } return __builtin_bit_cast(float, w << 16); }
; __device__ __forceinline__ float xhi(unsigned w) { if (XRES_F16) { const f16x2_t h = __builtin_bit_cast(f16x2_t, w); return (float)h[1]; } return __builtin_bit_cast(float, w & 0xffff0000u); }
; __device__ __forceinline__ void norm_mod_phase2(const Args& a, Frame& F, const float* gain, const float* modl, int sh_off, int sc_off, int nrows, const float* slab_gate) {
;     ...
;         if (slab_gate != nullptr) { const GAS f32x4* sl = (const GAS f32x4*)((const float*)(a.ws + WS_SLAB) + (size_t)rc * D) + F.lane;
; #pragma unroll
;             for (int j = 0; j < 8; ++j) { const f32x4 p = (sl[64 * j] + sl[64 * j + (size_t)MC * D / 4]) + (sl[64 * j + 2 * ((size_t)MC * D / 4)] + sl[64 * j + 3 * ((size_t)MC * D / 4)]);
;                 const f32x4 x = (f32x4){xlo(r0[j].x), xhi(r0[j].x), xlo(r0[j].y), xhi(r0[j].y)} + *(const GAS f32x4*)(slab_gate + 256 * j + 4 * F.lane) * p;
;                 v2u w; w.x = xpk2(x[0], x[1]); w.y = xpk2(x[2], x[3]); ((GAS v2u*)(X + (size_t)r * D) + F.lane)[64 * j] = w; r0[j] = w; } }
	v_pk_add_f32 v[220:221], v[94:95], v[98:99]
	v_pk_add_f32 v[222:223], v[96:97], v[100:101]
	v_pk_add_f32 v[224:225], v[102:103], v[106:107]
	v_pk_add_f32 v[226:227], v[104:105], v[108:109]
	v_cvt_f32_f16_e32 v232, v22
	v_cvt_f32_f16_sdwa v233, v22 dst_sel:DWORD dst_unused:UNUSED_PAD src0_sel:WORD_1
	v_cvt_f32_f16_e32 v234, v23
	v_cvt_f32_f16_sdwa v235, v23 dst_sel:DWORD dst_unused:UNUSED_PAD src0_sel:WORD_1
	v_pk_add_f32 v[228:229], v[220:221], v[224:225]
	v_pk_add_f32 v[230:231], v[222:223], v[226:227]
	s_nop 1
	v_pk_fma_f32 v[236:237], v[110:111], v[228:229], v[232:233]
	v_pk_fma_f32 v[238:239], v[112:113], v[230:231], v[234:235]
	s_nop 1
	v_cvt_pk_f16_f32 v22, v236, v237
	v_cvt_pk_f16_f32 v23, v238, v239
	global_store_dwordx2 v[18:19], v[22:23], off
	global_load_dwordx4 v[94:97], v[36:37], off
	global_load_dwordx4 v[98:101], v[38:39], off
	global_load_dwordx4 v[102:105], v[42:43], off
	global_load_dwordx4 v[106:109], v[44:45], off
	global_load_dwordx4 v[110:113], v[50:51], off
	s_waitcnt vmcnt(16)
	v_pk_add_f32 v[220:221], v[114:115], v[118:119]
	v_pk_add_f32 v[222:223], v[116:117], v[120:121]
	v_pk_add_f32 v[224:225], v[122:123], v[126:127]
	v_pk_add_f32 v[226:227], v[124:125], v[128:129]
	v_cvt_f32_f16_e32 v232, v20
	v_cvt_f32_f16_sdwa v233, v20 dst_sel:DWORD dst_unused:UNUSED_PAD src0_sel:WORD_1
	v_cvt_f32_f16_e32 v234, v21
	v_cvt_f32_f16_sdwa v235, v21 dst_sel:DWORD dst_unused:UNUSED_PAD src0_sel:WORD_1
	v_pk_add_f32 v[228:229], v[220:221], v[224:225]
	v_pk_add_f32 v[230:231], v[222:223], v[226:227]
	s_nop 1
	v_pk_fma_f32 v[236:237], v[130:131], v[228:229], v[232:233]
	v_pk_fma_f32 v[238:239], v[132:133], v[230:231], v[234:235]
	s_nop 1
	v_cvt_pk_f16_f32 v20, v236, v237
	v_cvt_pk_f16_f32 v21, v238, v239
	global_store_dwordx2 v[18:19], v[20:21], off offset:512
	global_load_dwordx4 v[114:117], v[36:37], off offset:1024
	global_load_dwordx4 v[118:121], v[38:39], off offset:1024
	global_load_dwordx4 v[122:125], v[42:43], off offset:1024
	global_load_dwordx4 v[126:129], v[44:45], off offset:1024
	global_load_dwordx4 v[130:133], v[50:51], off offset:1024
	s_waitcnt vmcnt(17)
	v_pk_add_f32 v[220:221], v[134:135], v[138:139]
	v_pk_add_f32 v[222:223], v[136:137], v[140:141]
	v_pk_add_f32 v[224:225], v[142:143], v[146:147]
	v_pk_add_f32 v[226:227], v[144:145], v[148:149]
	v_cvt_f32_f16_e32 v232, v16
	v_cvt_f32_f16_sdwa v233, v16 dst_sel:DWORD dst_unused:UNUSED_PAD src0_sel:WORD_1
	v_cvt_f32_f16_e32 v234, v17
	v_cvt_f32_f16_sdwa v235, v17 dst_sel:DWORD dst_unused:UNUSED_PAD src0_sel:WORD_1
	v_pk_add_f32 v[228:229], v[220:221], v[224:225]
	v_pk_add_f32 v[230:231], v[222:223], v[226:227]
	s_nop 1
	v_pk_fma_f32 v[236:237], v[150:151], v[228:229], v[232:233]
	v_pk_fma_f32 v[238:239], v[152:153], v[230:231], v[234:235]
	s_nop 1
	v_cvt_pk_f16_f32 v16, v236, v237
	v_cvt_pk_f16_f32 v17, v238, v239
	global_store_dwordx2 v[18:19], v[16:17], off offset:1024
	global_load_dwordx4 v[134:137], v[36:37], off offset:2048
	global_load_dwordx4 v[138:141], v[38:39], off offset:2048
	global_load_dwordx4 v[142:145], v[42:43], off offset:2048
	global_load_dwordx4 v[146:149], v[44:45], off offset:2048
	global_load_dwordx4 v[150:153], v[50:51], off offset:2048
	s_waitcnt vmcnt(18)
	v_pk_add_f32 v[220:221], v[154:155], v[158:159]
	v_pk_add_f32 v[222:223], v[156:157], v[160:161]
	v_pk_add_f32 v[224:225], v[162:163], v[170:171]
	v_pk_add_f32 v[226:227], v[164:165], v[172:173]
	v_cvt_f32_f16_e32 v232, v12
	v_cvt_f32_f16_sdwa v233, v12 dst_sel:DWORD dst_unused:UNUSED_PAD src0_sel:WORD_1
	v_cvt_f32_f16_e32 v234, v13
	v_cvt_f32_f16_sdwa v235, v13 dst_sel:DWORD dst_unused:UNUSED_PAD src0_sel:WORD_1
	v_pk_add_f32 v[228:229], v[220:221], v[224:225]
	v_pk_add_f32 v[230:231], v[222:223], v[226:227]
	s_nop 1
	v_pk_fma_f32 v[236:237], v[174:175], v[228:229], v[232:233]
	v_pk_fma_f32 v[238:239], v[176:177], v[230:231], v[234:235]
	s_nop 1
	v_cvt_pk_f16_f32 v12, v236, v237
	v_cvt_pk_f16_f32 v13, v238, v239
	global_store_dwordx2 v[18:19], v[12:13], off offset:1536
	global_load_dwordx4 v[154:157], v[36:37], off offset:3072
	global_load_dwordx4 v[158:161], v[38:39], off offset:3072
	global_load_dwordx4 v[162:165], v[42:43], off offset:3072
	global_load_dwordx4 v[170:173], v[44:45], off offset:3072
	global_load_dwordx4 v[174:177], v[50:51], off offset:3072
	s_waitcnt vmcnt(18)
	v_pk_add_f32 v[220:221], v[94:95], v[98:99]
	v_pk_add_f32 v[222:223], v[96:97], v[100:101]
	v_pk_add_f32 v[224:225], v[102:103], v[106:107]
	v_pk_add_f32 v[226:227], v[104:105], v[108:109]
	v_cvt_f32_f16_e32 v232, v14
	v_cvt_f32_f16_sdwa v233, v14 dst_sel:DWORD dst_unused:UNUSED_PAD src0_sel:WORD_1
	v_cvt_f32_f16_e32 v234, v15
	v_cvt_f32_f16_sdwa v235, v15 dst_sel:DWORD dst_unused:UNUSED_PAD src0_sel:WORD_1
	v_pk_add_f32 v[228:229], v[220:221], v[224:225]
	v_pk_add_f32 v[230:231], v[222:223], v[226:227]
	s_nop 1
	v_pk_fma_f32 v[236:237], v[110:111], v[228:229], v[232:233]
	v_pk_fma_f32 v[238:239], v[112:113], v[230:231], v[234:235]
	s_nop 1
	v_cvt_pk_f16_f32 v14, v236, v237
	v_cvt_pk_f16_f32 v15, v238, v239
	global_store_dwordx2 v[18:19], v[14:15], off offset:2048
	s_waitcnt vmcnt(13)
	v_pk_add_f32 v[220:221], v[114:115], v[118:119]
	v_pk_add_f32 v[222:223], v[116:117], v[120:121]
	v_pk_add_f32 v[224:225], v[122:123], v[126:127]
	v_pk_add_f32 v[226:227], v[124:125], v[128:129]
	v_cvt_f32_f16_e32 v232, v10
	v_cvt_f32_f16_sdwa v233, v10 dst_sel:DWORD dst_unused:UNUSED_PAD src0_sel:WORD_1
	v_cvt_f32_f16_e32 v234, v11
	v_cvt_f32_f16_sdwa v235, v11 dst_sel:DWORD dst_unused:UNUSED_PAD src0_sel:WORD_1
	v_pk_add_f32 v[228:229], v[220:221], v[224:225]
	v_pk_add_f32 v[230:231], v[222:223], v[226:227]
	s_nop 1
	v_pk_fma_f32 v[236:237], v[130:131], v[228:229], v[232:233]
	v_pk_fma_f32 v[238:239], v[132:133], v[230:231], v[234:235]
	s_nop 1
	v_cvt_pk_f16_f32 v10, v236, v237
	v_cvt_pk_f16_f32 v11, v238, v239
	global_store_dwordx2 v[18:19], v[10:11], off offset:2560
	s_waitcnt vmcnt(8)
; #define GAS __attribute__((address_space(1)))
; __device__ __forceinline__ unsigned xpk2(float lo, float hi) { if (XRES_F16) { const f32x2_t v = {lo, hi}; const f16x2_t h = __builtin_convertvector(v, f16x2_t); return __builtin_bit_cast(unsigned, h); } return pk2(lo, hi); }
; __device__ __forceinline__ float xlo(unsigned w) { if (XRES_F16) { const f16x2_t h = __builtin_bit_cast(f16x2_t, w); return (float)h[0]; } return __builtin_bit_cast(float, w << 16); }
; __device__ __forceinline__ float xhi(unsigned w) { if (XRES_F16) { const f16x2_t h = __builtin_bit_cast(f16x2_t, w); return (float)h[1]; } return __builtin_bit_cast(float, w & 0xffff0000u); }
; __device__ __forceinline__ void norm_mod_phase2(const Args& a, Frame& F, const float* gain, const float* modl, int sh_off, int sc_off, int nrows, const float* slab_gate) {
;     ...
;             for (int j = 0; j < 8; ++j) { const f32x4 p = (sl[64 * j] + sl[64 * j + (size_t)MC * D / 4]) + (sl[64 * j + 2 * ((size_t)MC * D / 4)] + sl[64 * j + 3 * ((size_t)MC * D / 4)]);
;                 const f32x4 x = (f32x4){xlo(r0[j].x), xhi(r0[j].x), xlo(r0[j].y), xhi(r0[j].y)} + *(const GAS f32x4*)(slab_gate + 256 * j + 4 * F.lane) * p;
;                 v2u w; w.x = xpk2(x[0], x[1]); w.y = xpk2(x[2], x[3]); ((GAS v2u*)(X + (size_t)r * D) + F.lane)[64 * j] = w; r0[j] = w; } }
;         NR_FINISH(r0, r, 4);
	v_pk_add_f32 v[220:221], v[134:135], v[138:139]
	v_pk_add_f32 v[222:223], v[136:137], v[140:141]
	v_pk_add_f32 v[224:225], v[142:143], v[146:147]
	v_pk_add_f32 v[226:227], v[144:145], v[148:149]
	v_cvt_f32_f16_e32 v232, v8
	v_cvt_f32_f16_sdwa v233, v8 dst_sel:DWORD dst_unused:UNUSED_PAD src0_sel:WORD_1
	v_cvt_f32_f16_e32 v234, v9
	v_cvt_f32_f16_sdwa v235, v9 dst_sel:DWORD dst_unused:UNUSED_PAD src0_sel:WORD_1
	v_pk_add_f32 v[228:229], v[220:221], v[224:225]
	v_pk_add_f32 v[230:231], v[222:223], v[226:227]
	s_nop 1
	v_pk_fma_f32 v[236:237], v[150:151], v[228:229], v[232:233]
	v_pk_fma_f32 v[238:239], v[152:153], v[230:231], v[234:235]
	s_nop 1
	v_cvt_pk_f16_f32 v8, v236, v237
	v_cvt_pk_f16_f32 v9, v238, v239
	global_store_dwordx2 v[18:19], v[8:9], off offset:3072
	s_waitcnt vmcnt(3)
	v_pk_add_f32 v[220:221], v[154:155], v[158:159]
	v_pk_add_f32 v[222:223], v[156:157], v[160:161]
	v_pk_add_f32 v[224:225], v[162:163], v[170:171]
	v_pk_add_f32 v[226:227], v[164:165], v[172:173]
	v_cvt_f32_f16_e32 v232, v4
	v_cvt_f32_f16_sdwa v233, v4 dst_sel:DWORD dst_unused:UNUSED_PAD src0_sel:WORD_1
	v_cvt_f32_f16_e32 v234, v5
	v_cvt_f32_f16_sdwa v235, v5 dst_sel:DWORD dst_unused:UNUSED_PAD src0_sel:WORD_1
	v_pk_add_f32 v[228:229], v[220:221], v[224:225]
	v_pk_add_f32 v[230:231], v[222:223], v[226:227]
	s_nop 1
	v_pk_fma_f32 v[236:237], v[174:175], v[228:229], v[232:233]
	v_pk_fma_f32 v[238:239], v[176:177], v[230:231], v[234:235]
	s_nop 1
	v_cvt_pk_f16_f32 v4, v236, v237
	v_cvt_pk_f16_f32 v5, v238, v239
	global_store_dwordx2 v[18:19], v[4:5], off offset:3584
.LBB0_222:
	s_waitcnt vmcnt(7)
	v_cvt_f32_f16_sdwa v37, v22 dst_sel:DWORD dst_unused:UNUSED_PAD src0_sel:WORD_1
	s_waitcnt vmcnt(6)
	v_cvt_f32_f16_sdwa v33, v20 dst_sel:DWORD dst_unused:UNUSED_PAD src0_sel:WORD_1
	v_cvt_f32_f16_e32 v36, v22
	v_cvt_f32_f16_sdwa v39, v23 dst_sel:DWORD dst_unused:UNUSED_PAD src0_sel:WORD_1
	v_cvt_f32_f16_e32 v32, v20
	v_cvt_f32_f16_sdwa v35, v21 dst_sel:DWORD dst_unused:UNUSED_PAD src0_sel:WORD_1
	v_cvt_f32_f16_e32 v38, v23
	v_cvt_f32_f16_e32 v34, v21
	v_mov_b32_e32 v20, v37
	v_mov_b32_e32 v21, v33
	v_mov_b32_e32 v18, v36
	v_mov_b32_e32 v19, v32
	v_pk_mul_f32 v[20:21], v[20:21], v[20:21]
	v_mov_b32_e32 v22, v39
	v_mov_b32_e32 v23, v35
	s_waitcnt vmcnt(5)
	v_cvt_f32_f16_sdwa v25, v16 dst_sel:DWORD dst_unused:UNUSED_PAD src0_sel:WORD_1
	v_cvt_f32_f16_sdwa v27, v17 dst_sel:DWORD dst_unused:UNUSED_PAD src0_sel:WORD_1
	v_pk_fma_f32 v[18:19], v[18:19], v[18:19], v[20:21]
	v_mov_b32_e32 v20, v38
	v_mov_b32_e32 v21, v34
	v_pk_mul_f32 v[22:23], v[22:23], v[22:23]
	v_cvt_f32_f16_e32 v24, v16
	v_cvt_f32_f16_e32 v26, v17
	v_pk_fma_f32 v[20:21], v[20:21], v[20:21], v[22:23]
	s_waitcnt vmcnt(4)
	v_cvt_f32_f16_e32 v28, v12
	v_pk_add_f32 v[18:19], v[18:19], v[20:21]
	v_mov_b32_e32 v16, v24
	v_pk_add_f32 v[20:21], v[18:19], v[18:19] op_sel_hi:[0,1]
	v_mov_b32_e32 v18, v25
	v_mov_b32_e32 v19, v27
	v_mov_b32_e32 v17, v26
	v_pk_mul_f32 v[18:19], v[18:19], v[18:19]
	v_cvt_f32_f16_sdwa v29, v12 dst_sel:DWORD dst_unused:UNUSED_PAD src0_sel:WORD_1
	v_pk_fma_f32 v[16:17], v[16:17], v[16:17], v[18:19]
	v_cvt_f32_f16_e32 v30, v13
	s_waitcnt vmcnt(3)
	v_cvt_f32_f16_sdwa v19, v15 dst_sel:DWORD dst_unused:UNUSED_PAD src0_sel:WORD_1
	v_cvt_f32_f16_e32 v18, v15
	v_pk_add_f32 v[22:23], v[16:17], v[16:17] op_sel_hi:[0,1]
	v_cvt_f32_f16_sdwa v31, v13 dst_sel:DWORD dst_unused:UNUSED_PAD src0_sel:WORD_1
	v_cvt_f32_f16_sdwa v17, v14 dst_sel:DWORD dst_unused:UNUSED_PAD src0_sel:WORD_1
	v_cvt_f32_f16_e32 v16, v14
	v_mul_f32_e32 v0, v28, v28
	v_pk_fma_f32 v[12:13], v[28:29], v[28:29], v[0:1] op_sel_hi:[1,1,0]
	v_mul_f32_e32 v0, v30, v30
	v_pk_mul_f32 v[44:45], v[18:19], v[18:19]
	v_pk_fma_f32 v[42:43], v[30:31], v[30:31], v[0:1] op_sel_hi:[1,1,0]
	v_pk_mul_f32 v[14:15], v[16:17], v[16:17]
	v_mov_b32_e32 v22, v44
	v_mov_b32_e32 v20, v45
	v_mov_b32_e32 v12, v14
	v_mov_b32_e32 v42, v15
	v_pk_add_f32 v[14:15], v[22:23], v[20:21]
	s_waitcnt vmcnt(2)
	v_cvt_f32_f16_sdwa v21, v10 dst_sel:DWORD dst_unused:UNUSED_PAD src0_sel:WORD_1
	v_cvt_f32_f16_sdwa v23, v11 dst_sel:DWORD dst_unused:UNUSED_PAD src0_sel:WORD_1
	v_cvt_f32_f16_e32 v20, v10
	v_cvt_f32_f16_e32 v22, v11
	v_pk_add_f32 v[12:13], v[12:13], v[42:43]
	s_lshl_b64 s[4:5], s[4:5], 11
	v_pk_add_f32 v[12:13], v[12:13], v[14:15]
	v_mov_b32_e32 v10, v20
	v_pk_add_f32 v[42:43], v[12:13], v[12:13] op_sel_hi:[0,1]
	v_mov_b32_e32 v12, v21
	v_mov_b32_e32 v13, v23
	v_mov_b32_e32 v11, v22
	v_pk_mul_f32 v[12:13], v[12:13], v[12:13]
	s_waitcnt vmcnt(0)
; __device__ __forceinline__ void norm_mod_phase2(const Args& a, Frame& F, const float* gain, const float* modl, int sh_off, int sc_off, int nrows, const float* slab_gate) {
;     ...
;         NR_FINISH(r0, r, 4);
	v_cvt_f32_f16_sdwa v15, v5 dst_sel:DWORD dst_unused:UNUSED_PAD src0_sel:WORD_1
	v_pk_fma_f32 v[10:11], v[10:11], v[10:11], v[12:13]
	v_cvt_f32_f16_e32 v12, v9
	v_pk_add_f32 v[44:45], v[10:11], v[10:11] op_sel_hi:[0,1]
	v_cvt_f32_f16_e32 v10, v8
	v_cvt_f32_f16_sdwa v11, v8 dst_sel:DWORD dst_unused:UNUSED_PAD src0_sel:WORD_1
	v_cvt_f32_f16_sdwa v13, v9 dst_sel:DWORD dst_unused:UNUSED_PAD src0_sel:WORD_1
	v_cvt_f32_f16_sdwa v9, v4 dst_sel:DWORD dst_unused:UNUSED_PAD src0_sel:WORD_1
	v_cvt_f32_f16_e32 v8, v4
	v_cvt_f32_f16_e32 v14, v5
	v_mul_f32_e32 v0, v10, v10
	v_pk_fma_f32 v[46:47], v[10:11], v[10:11], v[0:1] op_sel_hi:[1,1,0]
	v_mul_f32_e32 v0, v12, v12
	v_pk_fma_f32 v[48:49], v[12:13], v[12:13], v[0:1] op_sel_hi:[1,1,0]
	v_pk_mul_f32 v[4:5], v[8:9], v[8:9]
	v_pk_mul_f32 v[50:51], v[14:15], v[14:15]
	v_mov_b32_e32 v46, v4
	v_mov_b32_e32 v48, v5
	v_mov_b32_e32 v44, v50
	v_mov_b32_e32 v42, v51
	v_pk_add_f32 v[4:5], v[46:47], v[48:49]
	v_pk_add_f32 v[42:43], v[44:45], v[42:43]
	v_lshl_add_u32 v40, v40, 2, 0
	v_pk_add_f32 v[4:5], v[4:5], v[42:43]
	v_lshl_add_u64 v[2:3], s[4:5], 1, v[2:3]
	v_add_f32_e32 v0, v4, v5
	s_nop 1
	v_add_f32_dpp v0, v0, v0 quad_perm:[1,0,3,2] row_mask:0xf bank_mask:0xf bound_ctrl:1
	s_nop 1
	v_add_f32_dpp v0, v0, v0 quad_perm:[2,3,0,1] row_mask:0xf bank_mask:0xf bound_ctrl:1
	s_nop 1
	v_add_f32_dpp v0, v0, v0 row_half_mirror row_mask:0xf bank_mask:0xf bound_ctrl:1
	s_nop 1
	v_add_f32_dpp v0, v0, v0 row_mirror row_mask:0xf bank_mask:0xf bound_ctrl:1
	s_nop 0
	v_readlane_b32 s8, v0, 16
	v_readlane_b32 s9, v0, 48
	v_readlane_b32 s6, v0, 0
	v_readlane_b32 s7, v0, 32
	v_mov_b32_e32 v4, s8
	v_mov_b32_e32 v5, s9
	v_pk_add_f32 v[4:5], s[6:7], v[4:5]
	s_nop 0
	v_add_f32_e32 v0, v4, v5
	v_fmamk_f32 v0, v0, 0x3a000000, v252
	v_cmp_gt_f32_e32 vcc, s55, v0
	v_mul_f32_e32 v4, 0x4f800000, v0
	s_nop 0
	v_cndmask_b32_e32 v0, v0, v4, vcc
	v_sqrt_f32_e32 v4, v0
	s_nop 0
	v_add_u32_e32 v5, -1, v4
	v_fma_f32 v7, -v5, v4, v0
	v_cmp_ge_f32_e64 s[6:7], 0, v7
	v_add_u32_e32 v7, 1, v4
	s_nop 0
	v_cndmask_b32_e64 v5, v4, v5, s[6:7]
	v_fma_f32 v4, -v7, v4, v0
	v_cmp_lt_f32_e64 s[6:7], 0, v4
	s_nop 1
	v_cndmask_b32_e64 v4, v5, v7, s[6:7]
	v_mul_f32_e32 v5, 0x37800000, v4
	v_cndmask_b32_e32 v4, v4, v5, vcc
	v_cmp_class_f32_e32 vcc, v0, v253
	s_nop 1
	v_cndmask_b32_e32 v0, v4, v0, vcc
	v_div_scale_f32 v4, s[6:7], v0, v0, 1.0
	v_rcp_f32_e32 v5, v4
	s_nop 0
	v_fma_f32 v7, -v4, v5, 1.0
	v_fmac_f32_e32 v5, v7, v5
	v_div_scale_f32 v7, vcc, 1.0, v0, 1.0
	v_mul_f32_e32 v41, v7, v5
	v_fma_f32 v42, -v4, v41, v7
	v_fmac_f32_e32 v41, v42, v5
	v_fma_f32 v4, -v4, v41, v7
	v_div_fmas_f32 v4, v4, v5, v41
	v_div_fixup_f32 v0, v4, v0, 1.0
	v_mov_b32_e32 v7, v1
	v_add_u32_e32 v41, 0x12000, v40
	v_lshl_add_u64 v[2:3], v[2:3], 0, v[6:7]
	v_pk_mul_f32 v[42:43], v[36:37], v[0:1] op_sel_hi:[1,0]
	v_pk_mul_f32 v[44:45], v[38:39], v[0:1] op_sel_hi:[1,0]
	ds_read_b128 v[4:7], v40 offset:32768
	ds_read_b128 v[36:39], v41
	v_pk_mul_f32 v[28:29], v[28:29], v[0:1] op_sel_hi:[1,0]
	v_pk_mul_f32 v[30:31], v[30:31], v[0:1] op_sel_hi:[1,0]
	v_pk_mul_f32 v[20:21], v[20:21], v[0:1] op_sel_hi:[1,0]
	v_pk_mul_f32 v[22:23], v[22:23], v[0:1] op_sel_hi:[1,0]
	s_waitcnt lgkmcnt(0)
	v_pk_fma_f32 v[6:7], v[6:7], v[44:45], v[38:39]
	v_pk_fma_f32 v[4:5], v[4:5], v[42:43], v[36:37]
	v_pk_mul_f32 v[36:37], v[32:33], v[0:1] op_sel_hi:[1,0]
	v_cvt_pk_bf16_f32 v4, v4, v5
	v_cvt_pk_bf16_f32 v5, v6, v7
	global_store_dwordx2 v[2:3], v[4:5], off nt
	v_pk_mul_f32 v[38:39], v[34:35], v[0:1] op_sel_hi:[1,0]
	ds_read_b128 v[4:7], v40 offset:33792
	ds_read_b128 v[32:35], v41 offset:1024
	v_pk_mul_f32 v[14:15], v[14:15], v[0:1] op_sel_hi:[1,0]
	s_waitcnt lgkmcnt(0)
	v_pk_fma_f32 v[6:7], v[6:7], v[38:39], v[34:35]
	v_pk_fma_f32 v[4:5], v[4:5], v[36:37], v[32:33]
	v_pk_mul_f32 v[32:33], v[24:25], v[0:1] op_sel_hi:[1,0]
	v_cvt_pk_bf16_f32 v4, v4, v5
	v_cvt_pk_bf16_f32 v5, v6, v7
	global_store_dwordx2 v[2:3], v[4:5], off offset:512 nt
	v_pk_mul_f32 v[34:35], v[26:27], v[0:1] op_sel_hi:[1,0]
	ds_read_b128 v[4:7], v40 offset:34816
	ds_read_b128 v[24:27], v41 offset:2048
	s_waitcnt lgkmcnt(0)
	v_pk_fma_f32 v[6:7], v[6:7], v[34:35], v[26:27]
	v_pk_fma_f32 v[4:5], v[4:5], v[32:33], v[24:25]
	s_nop 0
	v_cvt_pk_bf16_f32 v4, v4, v5
	v_cvt_pk_bf16_f32 v5, v6, v7
	global_store_dwordx2 v[2:3], v[4:5], off offset:1024 nt
	ds_read_b128 v[4:7], v40 offset:35840
	ds_read_b128 v[24:27], v41 offset:3072
	s_waitcnt lgkmcnt(0)
	v_pk_fma_f32 v[6:7], v[30:31], v[6:7], v[26:27]
	v_pk_fma_f32 v[4:5], v[28:29], v[4:5], v[24:25]
	v_pk_mul_f32 v[24:25], v[16:17], v[0:1] op_sel_hi:[1,0]
	v_cvt_pk_bf16_f32 v4, v4, v5
	v_cvt_pk_bf16_f32 v5, v6, v7
	global_store_dwordx2 v[2:3], v[4:5], off offset:1536 nt
	v_pk_mul_f32 v[26:27], v[18:19], v[0:1] op_sel_hi:[1,0]
	ds_read_b128 v[4:7], v40 offset:36864
	ds_read_b128 v[16:19], v41 offset:4096
	s_waitcnt lgkmcnt(0)
	v_pk_fma_f32 v[6:7], v[26:27], v[6:7], v[18:19]
	v_pk_fma_f32 v[4:5], v[24:25], v[4:5], v[16:17]
	s_nop 0
	v_cvt_pk_bf16_f32 v4, v4, v5
	v_cvt_pk_bf16_f32 v5, v6, v7
	global_store_dwordx2 v[2:3], v[4:5], off offset:2048 nt
	ds_read_b128 v[4:7], v40 offset:37888
	ds_read_b128 v[16:19], v41 offset:5120
	s_waitcnt lgkmcnt(0)
	v_pk_fma_f32 v[6:7], v[22:23], v[6:7], v[18:19]
	v_pk_fma_f32 v[4:5], v[20:21], v[4:5], v[16:17]
	v_pk_mul_f32 v[16:17], v[10:11], v[0:1] op_sel_hi:[1,0]
	v_cvt_pk_bf16_f32 v4, v4, v5
	v_cvt_pk_bf16_f32 v5, v6, v7
	global_store_dwordx2 v[2:3], v[4:5], off offset:2560 nt
	v_pk_mul_f32 v[18:19], v[12:13], v[0:1] op_sel_hi:[1,0]
	ds_read_b128 v[4:7], v40 offset:38912
	ds_read_b128 v[10:13], v41 offset:6144
	s_waitcnt lgkmcnt(0)
	v_pk_fma_f32 v[6:7], v[18:19], v[6:7], v[12:13]
	v_pk_fma_f32 v[4:5], v[16:17], v[4:5], v[10:11]
	v_pk_mul_f32 v[12:13], v[8:9], v[0:1] op_sel_hi:[1,0]
	v_cvt_pk_bf16_f32 v4, v4, v5
	v_cvt_pk_bf16_f32 v5, v6, v7
	global_store_dwordx2 v[2:3], v[4:5], off offset:3072 nt
	ds_read_b128 v[4:7], v40 offset:39936
	ds_read_b128 v[8:11], v41 offset:7168
	s_waitcnt lgkmcnt(0)
	v_pk_fma_f32 v[6:7], v[14:15], v[6:7], v[10:11]
	v_pk_fma_f32 v[4:5], v[12:13], v[4:5], v[8:9]
	s_nop 0
	v_cvt_pk_bf16_f32 v4, v4, v5
	v_cvt_pk_bf16_f32 v5, v6, v7
	global_store_dwordx2 v[2:3], v[4:5], off offset:3584 nt

; #define GAS __attribute__((address_space(1)))
; #define LAS __attribute__((address_space(3)))
; __device__ __forceinline__ void relaunder(Frame& F) { int t = mk_tid(); asm volatile("" : "+v"(t)); F.tid = t; F.lane = t & 63; F.wave = __builtin_amdgcn_readfirstlane(t >> 6); }
; template <bool HG>
; __device__ __forceinline__ void readout_phase2(const Args& a, Frame& F, const float* gain, int nrows) {
;     relaunder(F);
;     const int nw = F.vcu * NWAVES + F.wave;
;     const bf16* OF = (const bf16*)(a.ws + WS_OF); const bf16* OB = (const bf16*)(a.ws + WS_OB);
;     const bf16* G = (const bf16*)(a.ws + WS_ACT) + (size_t)(HG ? 6 : 3) * ACT_STRIDE; bf16* HN = (bf16*)(a.ws + WS_HN);
;     LAS float* GL = (LAS float*)F.lds;
;     v2u f0[8], b0[8], g0[8], f1[8], b1[8], g1[8], f2[8], b2[8], g2[8];
;     ...
;     RO_LOAD(f0, b0, g0, nw); RO_LOAD(f1, b1, g1, nw + 2048); RO_LOAD(f2, b2, g2, nw + 2 * 2048);
;     if (HG) { for (int q = F.tid; q < D / 4; q += NWAVES * 64) ((LAS f32x4*)GL)[q] = ((const GAS f32x4*)gain)[q];
.LBB0_576:
	s_andn2_b64 vcc, exec, s[8:9]
	s_cbranch_vccnz .LBB0_583
	s_getreg_b32 s6, hwreg(HW_REG_HW_ID, 0, 6)
	s_lshl_b32 s6, s6, 2
	s_add_i32 s6, s6, 0
	s_add_i32 s6, s6, 0x20540
	v_mov_b32_e32 v0, s6
	ds_read_b32 v0, v0
	v_mov_b64_e32 v[2:3], s[0:1]
	s_waitcnt lgkmcnt(0)
	v_readfirstlane_b32 s6, v0
	v_mbcnt_lo_u32_b32 v0, -1, 0
	v_mbcnt_hi_u32_b32 v0, -1, v0
	s_nop 1
	v_lshl_add_u32 v100, s6, 6, v0
	v_mov_b32_e32 v2, s72
	v_mov_b32_e32 v3, s73
	v_readfirstlane_b32 s6, v100
	s_ashr_i32 s6, s6, 6
	s_add_i32 s10, s6, s91
	s_mov_b64 s[6:7], 0x2ac00000
	s_ashr_i32 s11, s10, 31
	v_and_b32_e32 v166, 63, v100
	v_lshlrev_b32_e32 v0, 3, v166
	s_add_i32 s8, s10, 0x800
	s_ashr_i32 s9, s8, 31
	s_add_i32 s12, s10, 0x1000
	s_ashr_i32 s13, s12, 31
	s_waitcnt vmcnt(0) lgkmcnt(0)
	v_lshl_add_u64 v[36:37], v[2:3], 0, s[6:7]
	s_mov_b64 s[6:7], 0x33400000
	v_lshl_add_u64 v[38:39], v[2:3], 0, s[6:7]
	s_mov_b64 s[6:7], 0x26800000
	v_lshl_add_u64 v[40:41], v[2:3], 0, s[6:7]
	s_lshl_b64 s[6:7], s[10:11], 12
	v_lshl_add_u64 v[8:9], v[38:39], 0, s[6:7]
	v_lshl_add_u64 v[4:5], v[36:37], 0, s[6:7]
	v_lshl_add_u64 v[42:43], v[8:9], 0, v[0:1]
	v_lshl_add_u64 v[8:9], v[40:41], 0, s[6:7]
	v_lshl_add_u64 v[4:5], v[4:5], 0, v[0:1]
	v_lshl_add_u64 v[44:45], v[8:9], 0, v[0:1]
	s_lshl_b64 s[6:7], s[8:9], 12
	v_lshl_add_u64 v[184:185], s[84:85], 2, v[6:7]
	v_mov_b32_e32 v186, v100
	v_mov_b32_e32 v187, 0
	v_lshl_add_u64 v[184:185], v[186:187], 4, v[184:185]
	global_load_dwordx4 v[188:191], v[184:185], off
	global_load_dwordx2 v[156:157], v[4:5], off nt
	global_load_dwordx2 v[154:155], v[42:43], off nt
	global_load_dwordx2 v[8:9], v[44:45], off nt
	global_load_dwordx2 v[152:153], v[4:5], off offset:512 nt
	global_load_dwordx2 v[150:151], v[42:43], off offset:512 nt
	global_load_dwordx2 v[10:11], v[44:45], off offset:512 nt
	global_load_dwordx2 v[148:149], v[4:5], off offset:1024 nt
	global_load_dwordx2 v[140:141], v[42:43], off offset:1024 nt
	global_load_dwordx2 v[14:15], v[44:45], off offset:1024 nt
	global_load_dwordx2 v[90:91], v[4:5], off offset:1536 nt
	global_load_dwordx2 v[80:81], v[42:43], off offset:1536 nt
	global_load_dwordx2 v[18:19], v[44:45], off offset:1536 nt
	global_load_dwordx2 v[34:35], v[4:5], off offset:2048 nt
	global_load_dwordx2 v[32:33], v[42:43], off offset:2048 nt
	global_load_dwordx2 v[22:23], v[44:45], off offset:2048 nt
	global_load_dwordx2 v[28:29], v[4:5], off offset:2560 nt
	global_load_dwordx2 v[24:25], v[42:43], off offset:2560 nt
	global_load_dwordx2 v[26:27], v[44:45], off offset:2560 nt
	global_load_dwordx2 v[20:21], v[4:5], off offset:3072 nt
	global_load_dwordx2 v[16:17], v[42:43], off offset:3072 nt
	global_load_dwordx2 v[30:31], v[44:45], off offset:3072 nt
	global_load_dwordx2 v[12:13], v[4:5], off offset:3584 nt
	s_nop 0
	global_load_dwordx2 v[4:5], v[42:43], off offset:3584 nt
	global_load_dwordx2 v[76:77], v[44:45], off offset:3584 nt
	v_lshl_add_u64 v[42:43], v[36:37], 0, s[6:7]
	v_lshl_add_u64 v[44:45], v[38:39], 0, s[6:7]
	v_lshl_add_u64 v[42:43], v[42:43], 0, v[0:1]
	v_lshl_add_u64 v[48:49], v[44:45], 0, v[0:1]
	v_lshl_add_u64 v[44:45], v[40:41], 0, s[6:7]
	s_lshl_b64 s[6:7], s[12:13], 12
	v_lshl_add_u64 v[50:51], v[44:45], 0, v[0:1]
	global_load_dwordx2 v[146:147], v[42:43], off nt
	global_load_dwordx2 v[144:145], v[48:49], off nt
	global_load_dwordx2 v[72:73], v[50:51], off nt
	global_load_dwordx2 v[142:143], v[42:43], off offset:512 nt
	global_load_dwordx2 v[138:139], v[48:49], off offset:512 nt
	global_load_dwordx2 v[70:71], v[50:51], off offset:512 nt
	global_load_dwordx2 v[128:129], v[42:43], off offset:1024 nt
	global_load_dwordx2 v[126:127], v[48:49], off offset:1024 nt
	global_load_dwordx2 v[66:67], v[50:51], off offset:1024 nt
	global_load_dwordx2 v[120:121], v[42:43], off offset:1536 nt
	global_load_dwordx2 v[118:119], v[48:49], off offset:1536 nt
	global_load_dwordx2 v[60:61], v[50:51], off offset:1536 nt
	global_load_dwordx2 v[108:109], v[42:43], off offset:2048 nt
	global_load_dwordx2 v[106:107], v[48:49], off offset:2048 nt
	global_load_dwordx2 v[54:55], v[50:51], off offset:2048 nt
	global_load_dwordx2 v[98:99], v[42:43], off offset:2560 nt
	global_load_dwordx2 v[96:97], v[48:49], off offset:2560 nt
	global_load_dwordx2 v[46:47], v[50:51], off offset:2560 nt
	global_load_dwordx2 v[84:85], v[42:43], off offset:3072 nt
	global_load_dwordx2 v[82:83], v[48:49], off offset:3072 nt
	global_load_dwordx2 v[44:45], v[50:51], off offset:3072 nt
	global_load_dwordx2 v[78:79], v[42:43], off offset:3584 nt
	global_load_dwordx2 v[74:75], v[48:49], off offset:3584 nt
	s_nop 0
	global_load_dwordx2 v[42:43], v[50:51], off offset:3584 nt
	v_lshl_add_u64 v[48:49], v[36:37], 0, s[6:7]
	v_lshl_add_u64 v[86:87], v[48:49], 0, v[0:1]
	v_lshl_add_u64 v[48:49], v[38:39], 0, s[6:7]
	v_lshl_add_u64 v[50:51], v[48:49], 0, v[0:1]
	v_lshl_add_u64 v[48:49], v[40:41], 0, s[6:7]
	v_lshl_add_u64 v[158:159], v[48:49], 0, v[0:1]
	global_load_dwordx2 v[136:137], v[86:87], off nt
	global_load_dwordx2 v[134:135], v[50:51], off nt
	global_load_dwordx2 v[68:69], v[158:159], off nt
	global_load_dwordx2 v[132:133], v[86:87], off offset:512 nt
	global_load_dwordx2 v[130:131], v[50:51], off offset:512 nt
	global_load_dwordx2 v[64:65], v[158:159], off offset:512 nt
	global_load_dwordx2 v[124:125], v[86:87], off offset:1024 nt
	global_load_dwordx2 v[122:123], v[50:51], off offset:1024 nt
	global_load_dwordx2 v[58:59], v[158:159], off offset:1024 nt
	global_load_dwordx2 v[114:115], v[86:87], off offset:1536 nt
	global_load_dwordx2 v[116:117], v[50:51], off offset:1536 nt
	global_load_dwordx2 v[62:63], v[158:159], off offset:1536 nt
	global_load_dwordx2 v[112:113], v[86:87], off offset:2048 nt
	global_load_dwordx2 v[110:111], v[50:51], off offset:2048 nt
	global_load_dwordx2 v[56:57], v[158:159], off offset:2048 nt
	global_load_dwordx2 v[104:105], v[86:87], off offset:2560 nt
	global_load_dwordx2 v[102:103], v[50:51], off offset:2560 nt
	global_load_dwordx2 v[52:53], v[158:159], off offset:2560 nt
	global_load_dwordx2 v[94:95], v[86:87], off offset:3072 nt
	global_load_dwordx2 v[92:93], v[50:51], off offset:3072 nt
	global_load_dwordx2 v[48:49], v[158:159], off offset:3072 nt
	s_nop 0
	global_load_dwordx2 v[86:87], v[86:87], off offset:3584 nt
	s_nop 0
	global_load_dwordx2 v[88:89], v[50:51], off offset:3584 nt
	s_nop 0
	global_load_dwordx2 v[50:51], v[158:159], off offset:3584 nt
	s_waitcnt vmcnt(62)
; #define GAS __attribute__((address_space(1)))
; #define LAS __attribute__((address_space(3)))
; template <bool HG>
; __device__ __forceinline__ void readout_phase2(const Args& a, Frame& F, const float* gain, int nrows) {
;     ...
;     RO_LOAD(f0, b0, g0, nw); RO_LOAD(f1, b1, g1, nw + 2048); RO_LOAD(f2, b2, g2, nw + 2 * 2048);
;     if (HG) { for (int q = F.tid; q < D / 4; q += NWAVES * 64) ((LAS f32x4*)GL)[q] = ((const GAS f32x4*)gain)[q];
	v_lshl_add_u32 v184, v100, 4, 0
	ds_write_b128 v184, v[188:191]
	s_waitcnt vmcnt(62)
	v_lshlrev_b32_e32 v6, 16, v156
	v_and_b32_e32 v7, 0xffff0000, v156
	v_lshlrev_b32_e32 v100, 16, v154
	v_and_b32_e32 v101, 0xffff0000, v154
	v_pk_add_f32 v[6:7], v[6:7], v[100:101]
	v_lshlrev_b32_e32 v100, 16, v157
	v_and_b32_e32 v101, 0xffff0000, v157
	v_lshlrev_b32_e32 v154, 16, v155
	v_and_b32_e32 v155, 0xffff0000, v155
	v_pk_add_f32 v[154:155], v[100:101], v[154:155]
	v_lshlrev_b32_e32 v100, 16, v152
	v_and_b32_e32 v101, 0xffff0000, v152
	v_lshlrev_b32_e32 v156, 16, v150
	v_and_b32_e32 v157, 0xffff0000, v150
	v_pk_add_f32 v[100:101], v[100:101], v[156:157]
	v_lshlrev_b32_e32 v152, 16, v153
	v_and_b32_e32 v153, 0xffff0000, v153
	v_lshlrev_b32_e32 v150, 16, v151
	v_and_b32_e32 v151, 0xffff0000, v151
	v_pk_add_f32 v[150:151], v[152:153], v[150:151]
	v_mov_b32_e32 v156, v7
	v_mov_b32_e32 v157, v101
	v_mov_b32_e32 v152, v6
	v_mov_b32_e32 v153, v100
	v_pk_mul_f32 v[156:157], v[156:157], v[156:157]
	v_mov_b32_e32 v158, v155
	v_mov_b32_e32 v159, v151
	v_pk_fma_f32 v[152:153], v[152:153], v[152:153], v[156:157]
	v_mov_b32_e32 v156, v154
	v_mov_b32_e32 v157, v150
	v_pk_mul_f32 v[158:159], v[158:159], v[158:159]
	s_lshl_b64 s[18:19], s[8:9], 11
	v_pk_fma_f32 v[156:157], v[156:157], v[156:157], v[158:159]
	s_waitcnt vmcnt(58)
	v_lshlrev_b32_e32 v158, 16, v32
	v_pk_add_f32 v[152:153], v[152:153], v[156:157]
	v_lshlrev_b32_e32 v156, 16, v140
	v_pk_add_f32 v[160:161], v[152:153], v[152:153] op_sel:[0,1] op_sel_hi:[1,0]
	v_lshlrev_b32_e32 v152, 16, v148
	v_and_b32_e32 v153, 0xffff0000, v148
	v_and_b32_e32 v157, 0xffff0000, v140
	v_lshlrev_b32_e32 v148, 16, v149
	v_and_b32_e32 v149, 0xffff0000, v149
	v_lshlrev_b32_e32 v140, 16, v141
	v_and_b32_e32 v141, 0xffff0000, v141
	v_pk_add_f32 v[152:153], v[152:153], v[156:157]
	v_pk_add_f32 v[156:157], v[148:149], v[140:141]
	v_mov_b32_e32 v148, v153
	v_mov_b32_e32 v149, v157
	v_mov_b32_e32 v140, v152
	v_mov_b32_e32 v141, v156
	v_pk_mul_f32 v[148:149], v[148:149], v[148:149]
	v_and_b32_e32 v159, 0xffff0000, v32
	v_pk_fma_f32 v[140:141], v[140:141], v[140:141], v[148:149]
	v_lshlrev_b32_e32 v148, 16, v80
	v_pk_add_f32 v[162:163], v[140:141], v[140:141] op_sel:[0,1] op_sel_hi:[1,0]
	v_lshlrev_b32_e32 v140, 16, v90
	v_and_b32_e32 v141, 0xffff0000, v90
	v_and_b32_e32 v149, 0xffff0000, v80
	v_pk_add_f32 v[140:141], v[140:141], v[148:149]
	v_lshlrev_b32_e32 v90, 16, v91
	v_and_b32_e32 v91, 0xffff0000, v91
	v_lshlrev_b32_e32 v80, 16, v81
	v_and_b32_e32 v81, 0xffff0000, v81
	v_pk_add_f32 v[148:149], v[90:91], v[80:81]
	v_mul_f32_e32 v80, v141, v141
	v_pk_fma_f32 v[90:91], v[140:141], v[140:141], v[80:81] op_sel_hi:[1,1,0]
	v_mul_f32_e32 v80, v149, v149
	v_pk_fma_f32 v[164:165], v[148:149], v[148:149], v[80:81] op_sel_hi:[1,1,0]
	v_lshlrev_b32_e32 v80, 16, v34
	v_and_b32_e32 v81, 0xffff0000, v34
	v_lshlrev_b32_e32 v34, 16, v35
	v_and_b32_e32 v35, 0xffff0000, v35
	v_lshlrev_b32_e32 v32, 16, v33
	v_and_b32_e32 v33, 0xffff0000, v33
	v_pk_add_f32 v[80:81], v[80:81], v[158:159]
	v_pk_add_f32 v[158:159], v[34:35], v[32:33]
	v_pk_mul_f32 v[32:33], v[80:81], v[80:81]
	v_pk_mul_f32 v[34:35], v[158:159], v[158:159]
	v_mov_b32_e32 v161, v32
	v_mov_b32_e32 v163, v33
	v_mov_b32_e32 v91, v34
	v_mov_b32_e32 v165, v35
	v_pk_add_f32 v[32:33], v[160:161], v[162:163]
	v_pk_add_f32 v[34:35], v[90:91], v[164:165]
	s_waitcnt vmcnt(55)
	v_lshlrev_b32_e32 v90, 16, v24
	v_pk_add_f32 v[32:33], v[32:33], v[34:35]
	v_and_b32_e32 v91, 0xffff0000, v24
	v_pk_add_f32 v[34:35], v[32:33], v[32:33] op_sel:[0,1] op_sel_hi:[1,0]
	v_lshlrev_b32_e32 v32, 16, v28
	v_and_b32_e32 v33, 0xffff0000, v28
	v_lshlrev_b32_e32 v28, 16, v29
	v_and_b32_e32 v29, 0xffff0000, v29
	v_lshlrev_b32_e32 v24, 16, v25
	v_and_b32_e32 v25, 0xffff0000, v25
	v_pk_add_f32 v[32:33], v[32:33], v[90:91]
	v_pk_add_f32 v[28:29], v[28:29], v[24:25]
	v_mov_b32_e32 v90, v33
	v_mov_b32_e32 v91, v29
	v_mov_b32_e32 v24, v32
	v_mov_b32_e32 v25, v28
	v_pk_mul_f32 v[90:91], v[90:91], v[90:91]
	s_waitcnt vmcnt(52)
	v_lshlrev_b32_e32 v160, 16, v16
	v_pk_fma_f32 v[24:25], v[24:25], v[24:25], v[90:91]
	v_lshlrev_b32_e32 v90, 16, v20
	v_and_b32_e32 v91, 0xffff0000, v20
	v_and_b32_e32 v161, 0xffff0000, v16
	v_lshlrev_b32_e32 v20, 16, v21
	v_and_b32_e32 v21, 0xffff0000, v21
	v_lshlrev_b32_e32 v16, 16, v17
	v_and_b32_e32 v17, 0xffff0000, v17
	v_pk_add_f32 v[160:161], v[90:91], v[160:161]
	v_pk_add_f32 v[164:165], v[20:21], v[16:17]
	s_waitcnt vmcnt(50)
	v_lshlrev_b32_e32 v90, 16, v12
	v_and_b32_e32 v91, 0xffff0000, v12
	s_waitcnt vmcnt(49)
	v_lshlrev_b32_e32 v162, 16, v4
	v_and_b32_e32 v163, 0xffff0000, v4
	v_lshlrev_b32_e32 v12, 16, v13
	v_and_b32_e32 v13, 0xffff0000, v13
	v_lshlrev_b32_e32 v4, 16, v5
	v_and_b32_e32 v5, 0xffff0000, v5
	v_mul_f32_e32 v16, v161, v161
	v_mul_f32_e32 v20, v165, v165
	v_pk_add_f32 v[90:91], v[90:91], v[162:163]
	v_pk_add_f32 v[162:163], v[12:13], v[4:5]
	v_pk_add_f32 v[24:25], v[24:25], v[24:25] op_sel:[0,1] op_sel_hi:[1,0]
	v_pk_fma_f32 v[16:17], v[160:161], v[160:161], v[16:17] op_sel_hi:[1,1,0]
	v_pk_fma_f32 v[20:21], v[164:165], v[164:165], v[20:21] op_sel_hi:[1,1,0]
	v_pk_mul_f32 v[4:5], v[90:91], v[90:91]
	v_pk_mul_f32 v[12:13], v[162:163], v[162:163]
	v_mov_b32_e32 v35, v4
	v_mov_b32_e32 v25, v5
	v_mov_b32_e32 v17, v12
	v_mov_b32_e32 v21, v13
	v_pk_add_f32 v[4:5], v[34:35], v[24:25]
	v_pk_add_f32 v[12:13], v[16:17], v[20:21]
	s_waitcnt vmcnt(47)
	v_lshlrev_b32_e32 v172, 16, v146
	v_pk_add_f32 v[4:5], v[4:5], v[12:13]
	v_and_b32_e32 v173, 0xffff0000, v146
	v_add_f32_e32 v4, v4, v5
	s_waitcnt vmcnt(46)
; #define GAS __attribute__((address_space(1)))
; #define LAS __attribute__((address_space(3)))
; template <bool HG>
; __device__ __forceinline__ void readout_phase2(const Args& a, Frame& F, const float* gain, int nrows) {
;     ...
;     RO_LOAD(f0, b0, g0, nw); RO_LOAD(f1, b1, g1, nw + 2048); RO_LOAD(f2, b2, g2, nw + 2 * 2048);
;     if (HG) { for (int q = F.tid; q < D / 4; q += NWAVES * 64) ((LAS f32x4*)GL)[q] = ((const GAS f32x4*)gain)[q];
;               asm volatile("s_waitcnt lgkmcnt(0)" ::: "memory"); __builtin_amdgcn_s_barrier(); asm volatile("" ::: "memory"); }
;     RO_FINISH(f0, b0, g0, nw);            RO_LOAD(f0, b0, g0, nw + 3 * 2048);
	v_lshlrev_b32_e32 v176, 16, v144
	v_and_b32_e32 v177, 0xffff0000, v144
	v_add_f32_dpp v4, v4, v4 quad_perm:[1,0,3,2] row_mask:0xf bank_mask:0xf bound_ctrl:1
	v_lshlrev_b32_e32 v146, 16, v147
	v_and_b32_e32 v147, 0xffff0000, v147
	v_add_f32_dpp v4, v4, v4 quad_perm:[2,3,0,1] row_mask:0xf bank_mask:0xf bound_ctrl:1
	v_lshlrev_b32_e32 v144, 16, v145
	v_and_b32_e32 v145, 0xffff0000, v145
	v_add_f32_dpp v4, v4, v4 row_half_mirror row_mask:0xf bank_mask:0xf bound_ctrl:1
	v_pk_add_f32 v[172:173], v[172:173], v[176:177]
	v_pk_add_f32 v[146:147], v[146:147], v[144:145]
	v_add_f32_dpp v4, v4, v4 row_mirror row_mask:0xf bank_mask:0xf bound_ctrl:1
	s_waitcnt vmcnt(44)
	v_lshlrev_b32_e32 v144, 16, v142
	v_readlane_b32 s8, v4, 16
	v_readlane_b32 s9, v4, 48
	v_readlane_b32 s6, v4, 0
	v_readlane_b32 s7, v4, 32
	v_mov_b32_e32 v4, s8
	v_mov_b32_e32 v5, s9
	v_pk_add_f32 v[4:5], s[6:7], v[4:5]
	s_mov_b64 s[6:7], 0x8c00000
	v_add_f32_e32 v4, v4, v5
	v_fmamk_f32 v4, v4, 0x3a000000, v252
	v_mul_f32_e32 v5, 0x4f800000, v4
	v_cmp_gt_f32_e32 vcc, s55, v4
	v_lshl_add_u64 v[34:35], v[2:3], 0, s[6:7]
	v_and_b32_e32 v145, 0xffff0000, v142
	v_cndmask_b32_e32 v4, v4, v5, vcc
	v_sqrt_f32_e32 v5, v4
	s_waitcnt vmcnt(43)
	v_lshlrev_b32_e32 v176, 16, v138
	v_and_b32_e32 v177, 0xffff0000, v138
	v_pk_add_f32 v[144:145], v[144:145], v[176:177]
	v_add_u32_e32 v2, -1, v5
	v_fma_f32 v3, -v2, v5, v4
	v_cmp_ge_f32_e64 s[8:9], 0, v3
	v_add_u32_e32 v3, 1, v5
	v_lshlrev_b32_e32 v142, 16, v143
	v_cndmask_b32_e64 v2, v5, v2, s[8:9]
	v_fma_f32 v5, -v3, v5, v4
	v_cmp_lt_f32_e64 s[8:9], 0, v5
	v_and_b32_e32 v143, 0xffff0000, v143
	v_lshlrev_b32_e32 v138, 16, v139
	v_cndmask_b32_e64 v2, v2, v3, s[8:9]
	v_mul_f32_e32 v3, 0x37800000, v2
	v_cndmask_b32_e32 v2, v2, v3, vcc
	v_cmp_class_f32_e32 vcc, v4, v253
	v_and_b32_e32 v139, 0xffff0000, v139
	v_pk_add_f32 v[138:139], v[142:143], v[138:139]
	v_cndmask_b32_e32 v2, v2, v4, vcc
	v_div_scale_f32 v3, s[6:7], v2, v2, 1.0
	v_rcp_f32_e32 v4, v3
	v_mov_b32_e32 v176, v173
	v_mov_b32_e32 v177, v145
	v_mov_b32_e32 v142, v172
	v_fma_f32 v5, -v3, v4, 1.0
	v_fmac_f32_e32 v4, v5, v4
	v_div_scale_f32 v5, vcc, 1.0, v2, 1.0
	v_mul_f32_e32 v12, v5, v4
	v_fma_f32 v13, -v3, v12, v5
	v_mov_b32_e32 v143, v144
	v_pk_mul_f32 v[176:177], v[176:177], v[176:177]
	v_mov_b32_e32 v178, v147
	v_mov_b32_e32 v179, v139
	v_fmac_f32_e32 v12, v13, v4
	v_pk_fma_f32 v[142:143], v[142:143], v[142:143], v[176:177]
	v_mov_b32_e32 v176, v146
	v_mov_b32_e32 v177, v138
	v_pk_mul_f32 v[178:179], v[178:179], v[178:179]
	v_fma_f32 v3, -v3, v12, v5
	v_pk_fma_f32 v[176:177], v[176:177], v[176:177], v[178:179]
	s_lshl_b64 s[16:17], s[10:11], 11
	v_div_fmas_f32 v3, v3, v4, v12
	v_pk_add_f32 v[142:143], v[142:143], v[176:177]
	s_waitcnt lgkmcnt(0)
	s_barrier
	v_div_fixup_f32 v168, v3, v2, 1.0
	v_lshl_add_u64 v[2:3], s[16:17], 1, v[34:35]
	v_lshl_add_u32 v166, v166, 4, 0
	v_pk_add_f32 v[176:177], v[142:143], v[142:143] op_sel:[0,1] op_sel_hi:[1,0]
	s_waitcnt vmcnt(41)
	v_lshlrev_b32_e32 v142, 16, v128
	v_and_b32_e32 v143, 0xffff0000, v128
	s_waitcnt vmcnt(40)
	v_lshlrev_b32_e32 v178, 16, v126
	v_and_b32_e32 v179, 0xffff0000, v126
	v_lshlrev_b32_e32 v128, 16, v129
	v_and_b32_e32 v129, 0xffff0000, v129
	v_lshlrev_b32_e32 v126, 16, v127
	v_and_b32_e32 v127, 0xffff0000, v127
	v_lshl_add_u64 v[170:171], v[2:3], 0, v[0:1]
	ds_read_b128 v[2:5], v166
	v_pk_add_f32 v[142:143], v[142:143], v[178:179]
	v_pk_add_f32 v[178:179], v[128:129], v[126:127]
	v_mov_b32_e32 v128, v143
	v_mov_b32_e32 v129, v179
	v_mov_b32_e32 v126, v142
	v_mov_b32_e32 v127, v178
	v_pk_mul_f32 v[128:129], v[128:129], v[128:129]
	v_lshlrev_b32_e32 v12, 16, v8
	v_and_b32_e32 v13, 0xffff0000, v8
	v_lshlrev_b32_e32 v16, 16, v9
	v_and_b32_e32 v17, 0xffff0000, v9
	v_pk_mul_f32 v[24:25], v[6:7], v[168:169] op_sel_hi:[1,0]
	ds_read_b128 v[6:9], v166 offset:1024
	v_pk_fma_f32 v[126:127], v[126:127], v[126:127], v[128:129]
	s_waitcnt vmcnt(38)
	v_lshlrev_b32_e32 v128, 16, v120
	v_and_b32_e32 v129, 0xffff0000, v120
	s_waitcnt vmcnt(37)
	v_lshlrev_b32_e32 v180, 16, v118
	v_and_b32_e32 v181, 0xffff0000, v118
	v_lshlrev_b32_e32 v120, 16, v121
	v_and_b32_e32 v121, 0xffff0000, v121
	v_lshlrev_b32_e32 v118, 16, v119
	v_and_b32_e32 v119, 0xffff0000, v119
	v_pk_mul_f32 v[20:21], v[154:155], v[168:169] op_sel_hi:[1,0]
	v_pk_add_f32 v[128:129], v[128:129], v[180:181]
	v_pk_add_f32 v[118:119], v[120:121], v[118:119]
	s_waitcnt vmcnt(35)
	v_lshlrev_b32_e32 v184, 16, v108
	v_and_b32_e32 v185, 0xffff0000, v108
	s_waitcnt vmcnt(34)
	v_lshlrev_b32_e32 v186, 16, v106
	v_and_b32_e32 v187, 0xffff0000, v106
	v_lshlrev_b32_e32 v108, 16, v109
	v_and_b32_e32 v109, 0xffff0000, v109
	v_lshlrev_b32_e32 v106, 16, v107
	v_and_b32_e32 v107, 0xffff0000, v107
	s_waitcnt lgkmcnt(1)
	v_pk_mul_f32 v[24:25], v[2:3], v[24:25]
	v_pk_mul_f32 v[20:21], v[4:5], v[20:21]
	v_mul_f32_e32 v120, v129, v129
	v_mul_f32_e32 v180, v119, v119
	v_pk_add_f32 v[186:187], v[184:185], v[186:187]
	v_pk_add_f32 v[106:107], v[108:109], v[106:107]
	v_pk_mul_f32 v[16:17], v[20:21], v[16:17]
	v_pk_mul_f32 v[12:13], v[24:25], v[12:13]
	v_pk_add_f32 v[126:127], v[126:127], v[126:127] op_sel:[0,1] op_sel_hi:[1,0]
	v_pk_fma_f32 v[120:121], v[128:129], v[128:129], v[120:121] op_sel_hi:[1,1,0]
	v_pk_fma_f32 v[180:181], v[118:119], v[118:119], v[180:181] op_sel_hi:[1,1,0]
	v_pk_mul_f32 v[108:109], v[186:187], v[186:187]
	v_pk_mul_f32 v[184:185], v[106:107], v[106:107]
	v_cvt_pk_bf16_f32 v12, v12, v13
	v_cvt_pk_bf16_f32 v13, v16, v17
	v_pk_mul_f32 v[16:17], v[150:151], v[168:169] op_sel_hi:[1,0]
	v_pk_mul_f32 v[20:21], v[100:101], v[168:169] op_sel_hi:[1,0]
	v_mov_b32_e32 v177, v108
	v_mov_b32_e32 v127, v109
	v_mov_b32_e32 v121, v184
	v_mov_b32_e32 v181, v185
	global_store_dwordx2 v[170:171], v[12:13], off nt
	v_lshlrev_b32_e32 v12, 16, v10
	v_and_b32_e32 v13, 0xffff0000, v10
	v_lshlrev_b32_e32 v10, 16, v11
	v_and_b32_e32 v11, 0xffff0000, v11
	s_waitcnt lgkmcnt(0)
; #define GAS __attribute__((address_space(1)))
; #define LAS __attribute__((address_space(3)))
; template <bool HG>
; __device__ __forceinline__ void readout_phase2(const Args& a, Frame& F, const float* gain, int nrows) {
;     ...
;     RO_LOAD(f0, b0, g0, nw); RO_LOAD(f1, b1, g1, nw + 2048); RO_LOAD(f2, b2, g2, nw + 2 * 2048);
;     if (HG) { for (int q = F.tid; q < D / 4; q += NWAVES * 64) ((LAS f32x4*)GL)[q] = ((const GAS f32x4*)gain)[q];
;               asm volatile("s_waitcnt lgkmcnt(0)" ::: "memory"); __builtin_amdgcn_s_barrier(); asm volatile("" ::: "memory"); }
;     RO_FINISH(f0, b0, g0, nw);            RO_LOAD(f0, b0, g0, nw + 3 * 2048);
;     RO_FINISH(f1, b1, g1, nw + 2048);     RO_LOAD(f1, b1, g1, nw + 4 * 2048);
	v_pk_mul_f32 v[20:21], v[6:7], v[20:21]
	v_pk_mul_f32 v[16:17], v[8:9], v[16:17]
	v_pk_add_f32 v[108:109], v[176:177], v[126:127]
	v_pk_add_f32 v[120:121], v[120:121], v[180:181]
	v_pk_mul_f32 v[10:11], v[16:17], v[10:11]
	v_pk_mul_f32 v[12:13], v[20:21], v[12:13]
	v_pk_add_f32 v[108:109], v[108:109], v[120:121]
	s_waitcnt vmcnt(33)
	v_lshlrev_b32_e32 v120, 16, v98
	v_and_b32_e32 v121, 0xffff0000, v98
	s_waitcnt vmcnt(32)
	v_lshlrev_b32_e32 v126, 16, v96
	v_and_b32_e32 v127, 0xffff0000, v96
	v_lshlrev_b32_e32 v98, 16, v99
	v_and_b32_e32 v99, 0xffff0000, v99
	v_lshlrev_b32_e32 v96, 16, v97
	v_and_b32_e32 v97, 0xffff0000, v97
	v_cvt_pk_bf16_f32 v12, v12, v13
	v_cvt_pk_bf16_f32 v13, v10, v11
	v_pk_add_f32 v[120:121], v[120:121], v[126:127]
	v_pk_add_f32 v[96:97], v[98:99], v[96:97]
	global_store_dwordx2 v[170:171], v[12:13], off offset:512 nt
	ds_read_b128 v[10:13], v166 offset:2048
	v_mov_b32_e32 v126, v121
	v_mov_b32_e32 v127, v97
	v_mov_b32_e32 v98, v120
	v_mov_b32_e32 v99, v96
	v_pk_mul_f32 v[126:127], v[126:127], v[126:127]
	s_waitcnt vmcnt(30)
	v_lshlrev_b32_e32 v176, 16, v82
	v_pk_fma_f32 v[98:99], v[98:99], v[98:99], v[126:127]
	v_lshlrev_b32_e32 v126, 16, v84
	v_and_b32_e32 v127, 0xffff0000, v84
	v_and_b32_e32 v177, 0xffff0000, v82
	v_lshlrev_b32_e32 v84, 16, v85
	v_and_b32_e32 v85, 0xffff0000, v85
	v_lshlrev_b32_e32 v82, 16, v83
	v_and_b32_e32 v83, 0xffff0000, v83
	v_lshlrev_b32_e32 v20, 16, v14
	v_and_b32_e32 v21, 0xffff0000, v14
	v_lshlrev_b32_e32 v24, 16, v15
	v_and_b32_e32 v25, 0xffff0000, v15
	ds_read_b128 v[14:17], v166 offset:3072
	v_pk_add_f32 v[176:177], v[126:127], v[176:177]
	v_pk_add_f32 v[82:83], v[84:85], v[82:83]
	s_waitcnt vmcnt(28)
	v_lshlrev_b32_e32 v180, 16, v78
	v_and_b32_e32 v181, 0xffff0000, v78
	s_waitcnt vmcnt(27)
	v_lshlrev_b32_e32 v184, 16, v74
	v_and_b32_e32 v185, 0xffff0000, v74
	v_lshlrev_b32_e32 v78, 16, v79
	v_and_b32_e32 v79, 0xffff0000, v79
	v_lshlrev_b32_e32 v74, 16, v75
	v_and_b32_e32 v75, 0xffff0000, v75
	v_pk_mul_f32 v[100:101], v[156:157], v[168:169] op_sel_hi:[1,0]
	v_pk_mul_f32 v[150:151], v[152:153], v[168:169] op_sel_hi:[1,0]
	v_mul_f32_e32 v84, v177, v177
	v_mul_f32_e32 v126, v83, v83
	v_pk_add_f32 v[180:181], v[180:181], v[184:185]
	v_pk_add_f32 v[78:79], v[78:79], v[74:75]
	s_waitcnt lgkmcnt(1)
	v_pk_mul_f32 v[150:151], v[10:11], v[150:151]
	v_pk_mul_f32 v[100:101], v[12:13], v[100:101]
	v_pk_add_f32 v[108:109], v[108:109], v[108:109] op_sel:[0,1] op_sel_hi:[1,0]
	v_pk_add_f32 v[98:99], v[98:99], v[98:99] op_sel:[0,1] op_sel_hi:[1,0]
	v_pk_fma_f32 v[84:85], v[176:177], v[176:177], v[84:85] op_sel_hi:[1,1,0]
	v_pk_fma_f32 v[126:127], v[82:83], v[82:83], v[126:127] op_sel_hi:[1,1,0]
	v_pk_mul_f32 v[74:75], v[180:181], v[180:181]
	v_pk_mul_f32 v[184:185], v[78:79], v[78:79]
	v_pk_mul_f32 v[24:25], v[100:101], v[24:25]
	v_pk_mul_f32 v[20:21], v[150:151], v[20:21]
	v_mov_b32_e32 v109, v74
	v_mov_b32_e32 v99, v75
	v_mov_b32_e32 v85, v184
	v_mov_b32_e32 v127, v185
	v_cvt_pk_bf16_f32 v20, v20, v21
	v_cvt_pk_bf16_f32 v21, v24, v25
	v_pk_mul_f32 v[24:25], v[148:149], v[168:169] op_sel_hi:[1,0]
	v_pk_mul_f32 v[100:101], v[140:141], v[168:169] op_sel_hi:[1,0]
	v_pk_add_f32 v[74:75], v[108:109], v[98:99]
	v_pk_add_f32 v[84:85], v[84:85], v[126:127]
	global_store_dwordx2 v[170:171], v[20:21], off offset:1024 nt
	v_lshlrev_b32_e32 v20, 16, v18
	v_and_b32_e32 v21, 0xffff0000, v18
	v_lshlrev_b32_e32 v18, 16, v19
	v_and_b32_e32 v19, 0xffff0000, v19
	s_waitcnt lgkmcnt(0)
	v_pk_mul_f32 v[100:101], v[14:15], v[100:101]
	v_pk_mul_f32 v[24:25], v[16:17], v[24:25]
	v_pk_add_f32 v[74:75], v[74:75], v[84:85]
	v_pk_mul_f32 v[18:19], v[24:25], v[18:19]
	v_pk_mul_f32 v[20:21], v[100:101], v[20:21]
	v_add_f32_e32 v74, v74, v75
	v_cvt_pk_bf16_f32 v20, v20, v21
	v_cvt_pk_bf16_f32 v21, v18, v19
	v_add_f32_dpp v74, v74, v74 quad_perm:[1,0,3,2] row_mask:0xf bank_mask:0xf bound_ctrl:1
	global_store_dwordx2 v[170:171], v[20:21], off offset:1536 nt
	ds_read_b128 v[18:21], v166 offset:4096
	v_add_f32_dpp v74, v74, v74 quad_perm:[2,3,0,1] row_mask:0xf bank_mask:0xf bound_ctrl:1
	v_lshlrev_b32_e32 v100, 16, v22
	v_and_b32_e32 v101, 0xffff0000, v22
	v_add_f32_dpp v74, v74, v74 row_half_mirror row_mask:0xf bank_mask:0xf bound_ctrl:1
	v_lshlrev_b32_e32 v140, 16, v23
	v_and_b32_e32 v141, 0xffff0000, v23
	v_add_f32_dpp v74, v74, v74 row_mirror row_mask:0xf bank_mask:0xf bound_ctrl:1
	ds_read_b128 v[22:25], v166 offset:5120
	v_readlane_b32 s8, v74, 16
	v_readlane_b32 s9, v74, 48
	v_pk_mul_f32 v[148:149], v[158:159], v[168:169] op_sel_hi:[1,0]
	v_pk_mul_f32 v[80:81], v[80:81], v[168:169] op_sel_hi:[1,0]
	v_readlane_b32 s6, v74, 0
	v_readlane_b32 s7, v74, 32
	v_mov_b32_e32 v74, s8
	v_mov_b32_e32 v75, s9
	s_waitcnt lgkmcnt(1)
	v_pk_mul_f32 v[80:81], v[18:19], v[80:81]
	v_pk_mul_f32 v[148:149], v[20:21], v[148:149]
	v_pk_add_f32 v[74:75], s[6:7], v[74:75]
	v_pk_mul_f32 v[140:141], v[148:149], v[140:141]
	v_pk_mul_f32 v[80:81], v[80:81], v[100:101]
	v_add_f32_e32 v74, v74, v75
	v_cvt_pk_bf16_f32 v80, v80, v81
	v_cvt_pk_bf16_f32 v81, v140, v141
	v_pk_mul_f32 v[28:29], v[28:29], v[168:169] op_sel_hi:[1,0]
	v_pk_mul_f32 v[32:33], v[32:33], v[168:169] op_sel_hi:[1,0]
	v_fmamk_f32 v74, v74, 0x3a000000, v252
	global_store_dwordx2 v[170:171], v[80:81], off offset:2048 nt
	v_lshlrev_b32_e32 v80, 16, v26
	v_and_b32_e32 v81, 0xffff0000, v26
	v_lshlrev_b32_e32 v26, 16, v27
	v_and_b32_e32 v27, 0xffff0000, v27
	s_waitcnt lgkmcnt(0)
; #define GAS __attribute__((address_space(1)))
; #define LAS __attribute__((address_space(3)))
; template <bool HG>
; __device__ __forceinline__ void readout_phase2(const Args& a, Frame& F, const float* gain, int nrows) {
;     ...
;     RO_LOAD(f0, b0, g0, nw); RO_LOAD(f1, b1, g1, nw + 2048); RO_LOAD(f2, b2, g2, nw + 2 * 2048);
;     if (HG) { for (int q = F.tid; q < D / 4; q += NWAVES * 64) ((LAS f32x4*)GL)[q] = ((const GAS f32x4*)gain)[q];
;               asm volatile("s_waitcnt lgkmcnt(0)" ::: "memory"); __builtin_amdgcn_s_barrier(); asm volatile("" ::: "memory"); }
;     RO_FINISH(f0, b0, g0, nw);            RO_LOAD(f0, b0, g0, nw + 3 * 2048);
;     RO_FINISH(f1, b1, g1, nw + 2048);     RO_LOAD(f1, b1, g1, nw + 4 * 2048);
	v_pk_mul_f32 v[32:33], v[32:33], v[22:23]
	v_pk_mul_f32 v[28:29], v[28:29], v[24:25]
	v_mul_f32_e32 v75, 0x4f800000, v74
	v_cmp_gt_f32_e32 vcc, s55, v74
	v_pk_mul_f32 v[26:27], v[28:29], v[26:27]
	v_pk_mul_f32 v[28:29], v[32:33], v[80:81]
	v_cndmask_b32_e32 v74, v74, v75, vcc
	v_cvt_pk_bf16_f32 v28, v28, v29
	v_cvt_pk_bf16_f32 v29, v26, v27
	v_sqrt_f32_e32 v75, v74
	global_store_dwordx2 v[170:171], v[28:29], off offset:2560 nt
	ds_read_b128 v[26:29], v166 offset:6144
	v_lshlrev_b32_e32 v80, 16, v30
	v_and_b32_e32 v81, 0xffff0000, v30
	v_lshlrev_b32_e32 v100, 16, v31
	v_and_b32_e32 v101, 0xffff0000, v31
	ds_read_b128 v[30:33], v166 offset:7168
	v_add_u32_e32 v84, -1, v75
	v_pk_mul_f32 v[140:141], v[164:165], v[168:169] op_sel_hi:[1,0]
	v_pk_mul_f32 v[148:149], v[160:161], v[168:169] op_sel_hi:[1,0]
	v_fma_f32 v85, -v84, v75, v74
	s_waitcnt lgkmcnt(1)
	v_pk_mul_f32 v[148:149], v[148:149], v[26:27]
	v_pk_mul_f32 v[140:141], v[140:141], v[28:29]
	v_cmp_ge_f32_e64 s[8:9], 0, v85
	v_add_u32_e32 v85, 1, v75
	v_pk_mul_f32 v[100:101], v[140:141], v[100:101]
	v_pk_mul_f32 v[80:81], v[148:149], v[80:81]
	v_cndmask_b32_e64 v84, v75, v84, s[8:9]
	v_fma_f32 v75, -v85, v75, v74
	s_lshl_b64 s[14:15], s[12:13], 11
	v_cvt_pk_bf16_f32 v80, v80, v81
	v_cvt_pk_bf16_f32 v81, v100, v101
	v_pk_mul_f32 v[100:101], v[162:163], v[168:169] op_sel_hi:[1,0]
	v_pk_mul_f32 v[90:91], v[90:91], v[168:169] op_sel_hi:[1,0]
	s_lshl_b64 s[12:13], s[10:11], 12
	v_cmp_lt_f32_e64 s[8:9], 0, v75
	global_store_dwordx2 v[170:171], v[80:81], off offset:3072 nt
	v_lshlrev_b32_e32 v80, 16, v76
	v_and_b32_e32 v81, 0xffff0000, v76
	v_lshlrev_b32_e32 v76, 16, v77
	v_and_b32_e32 v77, 0xffff0000, v77
	s_waitcnt lgkmcnt(0)
	v_pk_mul_f32 v[90:91], v[90:91], v[30:31]
	v_pk_mul_f32 v[100:101], v[100:101], v[32:33]
	s_add_u32 s16, s12, 0x1800000
	v_cndmask_b32_e64 v75, v84, v85, s[8:9]
	v_pk_mul_f32 v[76:77], v[100:101], v[76:77]
	v_pk_mul_f32 v[80:81], v[90:91], v[80:81]
	s_addc_u32 s17, s13, 0
	v_mul_f32_e32 v84, 0x37800000, v75
	v_cvt_pk_bf16_f32 v80, v80, v81
	v_cvt_pk_bf16_f32 v81, v76, v77
	v_lshl_add_u64 v[76:77], v[36:37], 0, s[16:17]
	v_cndmask_b32_e32 v75, v75, v84, vcc
	v_cmp_class_f32_e32 vcc, v74, v253
	v_lshl_add_u64 v[140:141], v[76:77], 0, v[0:1]
	v_lshl_add_u64 v[76:77], v[38:39], 0, s[16:17]
	v_cndmask_b32_e32 v84, v75, v74, vcc
	global_store_dwordx2 v[170:171], v[80:81], off offset:3584 nt
	v_lshl_add_u64 v[170:171], v[76:77], 0, v[0:1]
	v_lshl_add_u64 v[76:77], v[40:41], 0, s[16:17]
	v_div_scale_f32 v85, s[6:7], v84, v84, 1.0
	v_lshl_add_u64 v[166:167], v[76:77], 0, v[0:1]
	global_load_dwordx2 v[168:169], v[140:141], off nt
	global_load_dwordx2 v[162:163], v[140:141], off offset:512 nt
	global_load_dwordx2 v[158:159], v[140:141], off offset:1024 nt
	global_load_dwordx2 v[154:155], v[140:141], off offset:1536 nt
	global_load_dwordx2 v[174:175], v[170:171], off nt
	global_load_dwordx2 v[164:165], v[170:171], off offset:512 nt
	global_load_dwordx2 v[160:161], v[170:171], off offset:1024 nt
	global_load_dwordx2 v[156:157], v[170:171], off offset:1536 nt
	global_load_dwordx2 v[100:101], v[166:167], off nt
	global_load_dwordx2 v[90:91], v[166:167], off offset:512 nt
	global_load_dwordx2 v[80:81], v[166:167], off offset:1024 nt
	global_load_dwordx2 v[76:77], v[166:167], off offset:1536 nt
	global_load_dwordx2 v[152:153], v[140:141], off offset:2048 nt
	global_load_dwordx2 v[150:151], v[140:141], off offset:2560 nt
	global_load_dwordx2 v[148:149], v[140:141], off offset:3072 nt
	s_nop 0
	global_load_dwordx2 v[140:141], v[140:141], off offset:3584 nt
	s_nop 0
	global_load_dwordx2 v[196:197], v[170:171], off offset:2048 nt
	global_load_dwordx2 v[192:193], v[170:171], off offset:2560 nt
	global_load_dwordx2 v[188:189], v[170:171], off offset:3072 nt
	global_load_dwordx2 v[184:185], v[170:171], off offset:3584 nt
	v_rcp_f32_e32 v170, v85
	global_load_dwordx2 v[126:127], v[166:167], off offset:2048 nt
	global_load_dwordx2 v[108:109], v[166:167], off offset:2560 nt
	global_load_dwordx2 v[98:99], v[166:167], off offset:3072 nt
	global_load_dwordx2 v[74:75], v[166:167], off offset:3584 nt
	v_fma_f32 v166, -v85, v170, 1.0
	v_fmac_f32_e32 v170, v166, v170
	v_div_scale_f32 v166, vcc, 1.0, v84, 1.0
	v_mul_f32_e32 v167, v166, v170
	v_fma_f32 v171, -v85, v167, v166
	v_fmac_f32_e32 v167, v171, v170
	v_fma_f32 v85, -v85, v167, v166
	v_div_fmas_f32 v85, v85, v170, v167
	v_div_fixup_f32 v84, v85, v84, 1.0
	v_pk_mul_f32 v[146:147], v[146:147], v[84:85] op_sel_hi:[1,0]
	v_pk_mul_f32 v[172:173], v[172:173], v[84:85] op_sel_hi:[1,0]
	v_lshlrev_b32_e32 v170, 16, v72
	v_and_b32_e32 v171, 0xffff0000, v72
	v_lshlrev_b32_e32 v72, 16, v73
	v_and_b32_e32 v73, 0xffff0000, v73
	v_pk_mul_f32 v[172:173], v[2:3], v[172:173]
	v_pk_mul_f32 v[146:147], v[4:5], v[146:147]
	v_pk_mul_f32 v[138:139], v[138:139], v[84:85] op_sel_hi:[1,0]
	v_pk_mul_f32 v[72:73], v[146:147], v[72:73]
	v_pk_mul_f32 v[146:147], v[172:173], v[170:171]
	v_pk_mul_f32 v[144:145], v[144:145], v[84:85] op_sel_hi:[1,0]
	v_cvt_pk_bf16_f32 v146, v146, v147
	v_cvt_pk_bf16_f32 v147, v72, v73
	v_lshlrev_b32_e32 v72, 16, v70
	v_and_b32_e32 v73, 0xffff0000, v70
	v_lshlrev_b32_e32 v70, 16, v71
	v_and_b32_e32 v71, 0xffff0000, v71
	v_pk_mul_f32 v[144:145], v[6:7], v[144:145]
	v_pk_mul_f32 v[138:139], v[8:9], v[138:139]
	v_lshl_add_u64 v[166:167], s[18:19], 1, v[34:35]
	v_pk_mul_f32 v[70:71], v[138:139], v[70:71]
	v_pk_mul_f32 v[72:73], v[144:145], v[72:73]
	v_lshl_add_u64 v[166:167], v[166:167], 0, v[0:1]
	v_cvt_pk_bf16_f32 v72, v72, v73
	v_cvt_pk_bf16_f32 v73, v70, v71
	global_store_dwordx2 v[166:167], v[72:73], off offset:512 nt
; #define GAS __attribute__((address_space(1)))
; #define LAS __attribute__((address_space(3)))
; template <bool HG>
; __device__ __forceinline__ void readout_phase2(const Args& a, Frame& F, const float* gain, int nrows) {
;     ...
;     RO_LOAD(f0, b0, g0, nw); RO_LOAD(f1, b1, g1, nw + 2048); RO_LOAD(f2, b2, g2, nw + 2 * 2048);
;     if (HG) { for (int q = F.tid; q < D / 4; q += NWAVES * 64) ((LAS f32x4*)GL)[q] = ((const GAS f32x4*)gain)[q];
;               asm volatile("s_waitcnt lgkmcnt(0)" ::: "memory"); __builtin_amdgcn_s_barrier(); asm volatile("" ::: "memory"); }
;     RO_FINISH(f0, b0, g0, nw);            RO_LOAD(f0, b0, g0, nw + 3 * 2048);
;     RO_FINISH(f1, b1, g1, nw + 2048);     RO_LOAD(f1, b1, g1, nw + 4 * 2048);
	v_pk_mul_f32 v[72:73], v[178:179], v[84:85] op_sel_hi:[1,0]
	v_pk_mul_f32 v[138:139], v[142:143], v[84:85] op_sel_hi:[1,0]
	v_lshlrev_b32_e32 v70, 16, v66
	v_and_b32_e32 v71, 0xffff0000, v66
	v_lshlrev_b32_e32 v66, 16, v67
	v_and_b32_e32 v67, 0xffff0000, v67
	v_pk_mul_f32 v[138:139], v[10:11], v[138:139]
	v_pk_mul_f32 v[72:73], v[12:13], v[72:73]
	v_pk_mul_f32 v[70:71], v[138:139], v[70:71]
	v_pk_mul_f32 v[66:67], v[72:73], v[66:67]
	v_cvt_pk_bf16_f32 v70, v70, v71
	v_cvt_pk_bf16_f32 v71, v66, v67
	global_store_dwordx2 v[166:167], v[70:71], off offset:1024 nt
	v_pk_mul_f32 v[70:71], v[118:119], v[84:85] op_sel_hi:[1,0]
	v_pk_mul_f32 v[72:73], v[128:129], v[84:85] op_sel_hi:[1,0]
	v_lshlrev_b32_e32 v66, 16, v60
	v_and_b32_e32 v67, 0xffff0000, v60
	v_lshlrev_b32_e32 v60, 16, v61
	v_and_b32_e32 v61, 0xffff0000, v61
	v_pk_mul_f32 v[72:73], v[14:15], v[72:73]
	v_pk_mul_f32 v[70:71], v[16:17], v[70:71]
	v_pk_mul_f32 v[66:67], v[72:73], v[66:67]
	v_pk_mul_f32 v[60:61], v[70:71], v[60:61]
	v_cvt_pk_bf16_f32 v66, v66, v67
	v_cvt_pk_bf16_f32 v67, v60, v61
	global_store_dwordx2 v[166:167], v[66:67], off offset:1536 nt
	v_pk_mul_f32 v[66:67], v[106:107], v[84:85] op_sel_hi:[1,0]
	v_pk_mul_f32 v[70:71], v[186:187], v[84:85] op_sel_hi:[1,0]
	v_lshlrev_b32_e32 v60, 16, v54
	v_and_b32_e32 v61, 0xffff0000, v54
	v_lshlrev_b32_e32 v54, 16, v55
	v_and_b32_e32 v55, 0xffff0000, v55
	v_pk_mul_f32 v[70:71], v[18:19], v[70:71]
	v_pk_mul_f32 v[66:67], v[20:21], v[66:67]
	v_pk_mul_f32 v[60:61], v[70:71], v[60:61]
	v_pk_mul_f32 v[54:55], v[66:67], v[54:55]
	v_cvt_pk_bf16_f32 v60, v60, v61
	v_cvt_pk_bf16_f32 v61, v54, v55
	global_store_dwordx2 v[166:167], v[60:61], off offset:2048 nt
	v_pk_mul_f32 v[60:61], v[96:97], v[84:85] op_sel_hi:[1,0]
	v_pk_mul_f32 v[66:67], v[120:121], v[84:85] op_sel_hi:[1,0]
	v_lshlrev_b32_e32 v54, 16, v46
	v_and_b32_e32 v55, 0xffff0000, v46
	v_lshlrev_b32_e32 v46, 16, v47
	v_and_b32_e32 v47, 0xffff0000, v47
	v_pk_mul_f32 v[66:67], v[22:23], v[66:67]
	v_pk_mul_f32 v[60:61], v[24:25], v[60:61]
	v_pk_mul_f32 v[54:55], v[66:67], v[54:55]
	v_pk_mul_f32 v[46:47], v[60:61], v[46:47]
	v_cvt_pk_bf16_f32 v54, v54, v55
	v_cvt_pk_bf16_f32 v55, v46, v47
	global_store_dwordx2 v[166:167], v[54:55], off offset:2560 nt
	v_pk_mul_f32 v[54:55], v[82:83], v[84:85] op_sel_hi:[1,0]
	v_pk_mul_f32 v[60:61], v[176:177], v[84:85] op_sel_hi:[1,0]
	v_lshlrev_b32_e32 v46, 16, v44
	v_and_b32_e32 v47, 0xffff0000, v44
	v_lshlrev_b32_e32 v44, 16, v45
	v_and_b32_e32 v45, 0xffff0000, v45
	v_pk_mul_f32 v[60:61], v[26:27], v[60:61]
	v_pk_mul_f32 v[54:55], v[28:29], v[54:55]
	v_pk_mul_f32 v[46:47], v[60:61], v[46:47]
	v_pk_mul_f32 v[44:45], v[54:55], v[44:45]
	v_cvt_pk_bf16_f32 v46, v46, v47
	v_cvt_pk_bf16_f32 v47, v44, v45
	global_store_dwordx2 v[166:167], v[46:47], off offset:3072 nt
	v_pk_mul_f32 v[46:47], v[78:79], v[84:85] op_sel_hi:[1,0]
	v_pk_mul_f32 v[54:55], v[180:181], v[84:85] op_sel_hi:[1,0]
	s_waitcnt vmcnt(62)
	v_lshlrev_b32_e32 v44, 16, v42
	v_and_b32_e32 v45, 0xffff0000, v42
	v_lshlrev_b32_e32 v42, 16, v43
	v_and_b32_e32 v43, 0xffff0000, v43
	v_pk_mul_f32 v[54:55], v[30:31], v[54:55]
	v_pk_mul_f32 v[46:47], v[32:33], v[46:47]
	s_add_u32 s18, s12, 0x2000000
	v_pk_mul_f32 v[42:43], v[46:47], v[42:43]
	v_pk_mul_f32 v[44:45], v[54:55], v[44:45]
	s_addc_u32 s19, s13, 0
	v_cvt_pk_bf16_f32 v44, v44, v45
	v_cvt_pk_bf16_f32 v45, v42, v43
	v_lshl_add_u64 v[42:43], v[36:37], 0, s[18:19]
	v_lshl_add_u64 v[70:71], v[42:43], 0, v[0:1]
	v_lshl_add_u64 v[42:43], v[38:39], 0, s[18:19]
	global_store_dwordx2 v[166:167], v[146:147], off nt
	global_store_dwordx2 v[166:167], v[44:45], off offset:3584 nt
	v_lshl_add_u64 v[44:45], v[42:43], 0, v[0:1]
	v_lshl_add_u64 v[42:43], v[40:41], 0, s[18:19]
	v_lshl_add_u64 v[42:43], v[42:43], 0, v[0:1]
	global_load_dwordx2 v[170:171], v[70:71], off nt
	global_load_dwordx2 v[144:145], v[70:71], off offset:512 nt
	global_load_dwordx2 v[138:139], v[70:71], off offset:1024 nt
	global_load_dwordx2 v[118:119], v[70:71], off offset:1536 nt
	global_load_dwordx2 v[176:177], v[44:45], off nt
	global_load_dwordx2 v[146:147], v[44:45], off offset:512 nt
	global_load_dwordx2 v[142:143], v[44:45], off offset:1024 nt
	global_load_dwordx2 v[120:121], v[44:45], off offset:1536 nt
	global_load_dwordx2 v[66:67], v[42:43], off nt
	global_load_dwordx2 v[60:61], v[42:43], off offset:512 nt
	global_load_dwordx2 v[54:55], v[42:43], off offset:1024 nt
	global_load_dwordx2 v[46:47], v[42:43], off offset:1536 nt
	global_load_dwordx2 v[106:107], v[70:71], off offset:2048 nt
	global_load_dwordx2 v[96:97], v[70:71], off offset:2560 nt
	global_load_dwordx2 v[82:83], v[70:71], off offset:3072 nt
	global_load_dwordx2 v[72:73], v[70:71], off offset:3584 nt
	s_waitcnt vmcnt(62)
; #define GAS __attribute__((address_space(1)))
; #define LAS __attribute__((address_space(3)))
; template <bool HG>
; __device__ __forceinline__ void readout_phase2(const Args& a, Frame& F, const float* gain, int nrows) {
;     ...
;     RO_LOAD(f0, b0, g0, nw); RO_LOAD(f1, b1, g1, nw + 2048); RO_LOAD(f2, b2, g2, nw + 2 * 2048);
;     if (HG) { for (int q = F.tid; q < D / 4; q += NWAVES * 64) ((LAS f32x4*)GL)[q] = ((const GAS f32x4*)gain)[q];
;               asm volatile("s_waitcnt lgkmcnt(0)" ::: "memory"); __builtin_amdgcn_s_barrier(); asm volatile("" ::: "memory"); }
;     RO_FINISH(f0, b0, g0, nw);            RO_LOAD(f0, b0, g0, nw + 3 * 2048);
;     RO_FINISH(f1, b1, g1, nw + 2048);     RO_LOAD(f1, b1, g1, nw + 4 * 2048);
;     RO_FINISH(f2, b2, g2, nw + 2 * 2048); RO_LOAD(f2, b2, g2, nw + 5 * 2048);
	v_lshlrev_b32_e32 v70, 16, v136
	v_and_b32_e32 v71, 0xffff0000, v136
	v_lshlrev_b32_e32 v78, 16, v134
	v_and_b32_e32 v79, 0xffff0000, v134
	v_pk_add_f32 v[78:79], v[70:71], v[78:79]
	v_lshlrev_b32_e32 v70, 16, v137
	v_and_b32_e32 v71, 0xffff0000, v137
	v_lshlrev_b32_e32 v84, 16, v135
	v_and_b32_e32 v85, 0xffff0000, v135
	v_pk_add_f32 v[128:129], v[70:71], v[84:85]
	v_lshlrev_b32_e32 v70, 16, v132
	v_and_b32_e32 v71, 0xffff0000, v132
	v_lshlrev_b32_e32 v84, 16, v130
	v_and_b32_e32 v85, 0xffff0000, v130
	v_pk_add_f32 v[70:71], v[70:71], v[84:85]
	v_lshlrev_b32_e32 v84, 16, v133
	v_and_b32_e32 v85, 0xffff0000, v133
	v_lshlrev_b32_e32 v130, 16, v131
	v_and_b32_e32 v131, 0xffff0000, v131
	v_pk_add_f32 v[84:85], v[84:85], v[130:131]
	v_mov_b32_e32 v132, v79
	v_mov_b32_e32 v133, v71
	v_mov_b32_e32 v130, v78
	v_mov_b32_e32 v131, v70
	v_pk_mul_f32 v[132:133], v[132:133], v[132:133]
	v_mov_b32_e32 v134, v129
	v_mov_b32_e32 v135, v85
	v_pk_fma_f32 v[130:131], v[130:131], v[130:131], v[132:133]
	v_mov_b32_e32 v132, v128
	v_mov_b32_e32 v133, v84
	v_pk_mul_f32 v[134:135], v[134:135], v[134:135]
	v_lshlrev_b32_e32 v136, 16, v116
	v_pk_fma_f32 v[132:133], v[132:133], v[132:133], v[134:135]
	v_lshlrev_b32_e32 v134, 16, v122
	v_pk_add_f32 v[130:131], v[130:131], v[132:133]
	v_and_b32_e32 v135, 0xffff0000, v122
	v_pk_add_f32 v[132:133], v[130:131], v[130:131] op_sel:[0,1] op_sel_hi:[1,0]
	v_lshlrev_b32_e32 v130, 16, v124
	v_and_b32_e32 v131, 0xffff0000, v124
	v_lshlrev_b32_e32 v124, 16, v125
	v_and_b32_e32 v125, 0xffff0000, v125
	v_lshlrev_b32_e32 v122, 16, v123
	v_and_b32_e32 v123, 0xffff0000, v123
	v_pk_add_f32 v[130:131], v[130:131], v[134:135]
	v_pk_add_f32 v[134:135], v[124:125], v[122:123]
	v_mov_b32_e32 v124, v131
	v_mov_b32_e32 v125, v135
	v_mov_b32_e32 v122, v130
	v_mov_b32_e32 v123, v134
	v_pk_mul_f32 v[124:125], v[124:125], v[124:125]
	v_and_b32_e32 v137, 0xffff0000, v116
	v_pk_fma_f32 v[122:123], v[122:123], v[122:123], v[124:125]
	v_lshlrev_b32_e32 v124, 16, v114
	v_and_b32_e32 v125, 0xffff0000, v114
	v_lshlrev_b32_e32 v114, 16, v115
	v_and_b32_e32 v115, 0xffff0000, v115
	v_lshlrev_b32_e32 v116, 16, v117
	v_and_b32_e32 v117, 0xffff0000, v117
	v_pk_add_f32 v[124:125], v[124:125], v[136:137]
	v_pk_add_f32 v[114:115], v[114:115], v[116:117]
	v_lshlrev_b32_e32 v166, 16, v112
	v_and_b32_e32 v167, 0xffff0000, v112
	v_lshlrev_b32_e32 v172, 16, v110
	v_and_b32_e32 v173, 0xffff0000, v110
	v_lshlrev_b32_e32 v112, 16, v113
	v_and_b32_e32 v113, 0xffff0000, v113
	v_lshlrev_b32_e32 v110, 16, v111
	v_and_b32_e32 v111, 0xffff0000, v111
	v_mul_f32_e32 v116, v125, v125
	v_mul_f32_e32 v136, v115, v115
	v_pk_add_f32 v[166:167], v[166:167], v[172:173]
	v_pk_add_f32 v[112:113], v[112:113], v[110:111]
	v_pk_add_f32 v[122:123], v[122:123], v[122:123] op_sel:[0,1] op_sel_hi:[1,0]
	v_pk_fma_f32 v[116:117], v[124:125], v[124:125], v[116:117] op_sel_hi:[1,1,0]
	v_pk_fma_f32 v[136:137], v[114:115], v[114:115], v[136:137] op_sel_hi:[1,1,0]
	v_pk_mul_f32 v[110:111], v[166:167], v[166:167]
	v_pk_mul_f32 v[172:173], v[112:113], v[112:113]
	v_mov_b32_e32 v133, v110
	v_mov_b32_e32 v123, v111
	v_mov_b32_e32 v117, v172
	v_mov_b32_e32 v137, v173
	v_pk_add_f32 v[110:111], v[132:133], v[122:123]
	v_pk_add_f32 v[116:117], v[116:117], v[136:137]
	v_lshlrev_b32_e32 v122, 16, v102
	v_pk_add_f32 v[110:111], v[110:111], v[116:117]
	v_lshlrev_b32_e32 v116, 16, v104
	v_and_b32_e32 v117, 0xffff0000, v104
	v_and_b32_e32 v123, 0xffff0000, v102
	v_lshlrev_b32_e32 v104, 16, v105
	v_and_b32_e32 v105, 0xffff0000, v105
	v_lshlrev_b32_e32 v102, 16, v103
	v_and_b32_e32 v103, 0xffff0000, v103
	v_pk_add_f32 v[116:117], v[116:117], v[122:123]
	v_pk_add_f32 v[102:103], v[104:105], v[102:103]
	v_mov_b32_e32 v122, v117
	v_mov_b32_e32 v123, v103
	v_mov_b32_e32 v104, v116
	v_mov_b32_e32 v105, v102
	v_pk_mul_f32 v[122:123], v[122:123], v[122:123]
	s_waitcnt vmcnt(60)
	v_lshlrev_b32_e32 v132, 16, v92
	v_pk_fma_f32 v[104:105], v[104:105], v[104:105], v[122:123]
	v_lshlrev_b32_e32 v122, 16, v94
	v_and_b32_e32 v123, 0xffff0000, v94
	v_and_b32_e32 v133, 0xffff0000, v92
	v_lshlrev_b32_e32 v94, 16, v95
	v_and_b32_e32 v95, 0xffff0000, v95
	v_lshlrev_b32_e32 v92, 16, v93
	v_and_b32_e32 v93, 0xffff0000, v93
	v_pk_add_f32 v[132:133], v[122:123], v[132:133]
	v_pk_add_f32 v[92:93], v[94:95], v[92:93]
	s_waitcnt vmcnt(58)
	v_lshlrev_b32_e32 v136, 16, v86
	v_and_b32_e32 v137, 0xffff0000, v86
	s_waitcnt vmcnt(57)
; #define GAS __attribute__((address_space(1)))
; #define LAS __attribute__((address_space(3)))
; template <bool HG>
; __device__ __forceinline__ void readout_phase2(const Args& a, Frame& F, const float* gain, int nrows) {
;     ...
;     RO_LOAD(f0, b0, g0, nw); RO_LOAD(f1, b1, g1, nw + 2048); RO_LOAD(f2, b2, g2, nw + 2 * 2048);
;     if (HG) { for (int q = F.tid; q < D / 4; q += NWAVES * 64) ((LAS f32x4*)GL)[q] = ((const GAS f32x4*)gain)[q];
;               asm volatile("s_waitcnt lgkmcnt(0)" ::: "memory"); __builtin_amdgcn_s_barrier(); asm volatile("" ::: "memory"); }
;     RO_FINISH(f0, b0, g0, nw);            RO_LOAD(f0, b0, g0, nw + 3 * 2048);
;     RO_FINISH(f1, b1, g1, nw + 2048);     RO_LOAD(f1, b1, g1, nw + 4 * 2048);
;     RO_FINISH(f2, b2, g2, nw + 2 * 2048); RO_LOAD(f2, b2, g2, nw + 5 * 2048);
	v_lshlrev_b32_e32 v172, 16, v88
	v_and_b32_e32 v173, 0xffff0000, v88
	v_lshlrev_b32_e32 v86, 16, v87
	v_and_b32_e32 v87, 0xffff0000, v87
	v_lshlrev_b32_e32 v88, 16, v89
	v_and_b32_e32 v89, 0xffff0000, v89
	v_mul_f32_e32 v94, v133, v133
	v_mul_f32_e32 v122, v93, v93
	v_pk_add_f32 v[136:137], v[136:137], v[172:173]
	v_pk_add_f32 v[86:87], v[86:87], v[88:89]
	v_pk_add_f32 v[110:111], v[110:111], v[110:111] op_sel:[0,1] op_sel_hi:[1,0]
	v_pk_add_f32 v[104:105], v[104:105], v[104:105] op_sel:[0,1] op_sel_hi:[1,0]
	v_pk_fma_f32 v[94:95], v[132:133], v[132:133], v[94:95] op_sel_hi:[1,1,0]
	v_pk_fma_f32 v[122:123], v[92:93], v[92:93], v[122:123] op_sel_hi:[1,1,0]
	v_pk_mul_f32 v[88:89], v[136:137], v[136:137]
	v_pk_mul_f32 v[172:173], v[86:87], v[86:87]
	v_mov_b32_e32 v111, v88
	v_mov_b32_e32 v105, v89
	v_mov_b32_e32 v95, v172
	v_mov_b32_e32 v123, v173
	v_pk_add_f32 v[88:89], v[110:111], v[104:105]
	v_pk_add_f32 v[94:95], v[94:95], v[122:123]
	global_load_dwordx2 v[198:199], v[44:45], off offset:2048 nt
	global_load_dwordx2 v[194:195], v[44:45], off offset:2560 nt
	global_load_dwordx2 v[190:191], v[44:45], off offset:3072 nt
	global_load_dwordx2 v[186:187], v[44:45], off offset:3584 nt
	v_pk_add_f32 v[88:89], v[88:89], v[94:95]
	s_nop 0
	v_add_f32_e32 v88, v88, v89
	s_nop 1
	v_add_f32_dpp v88, v88, v88 quad_perm:[1,0,3,2] row_mask:0xf bank_mask:0xf bound_ctrl:1
	s_nop 1
	v_add_f32_dpp v88, v88, v88 quad_perm:[2,3,0,1] row_mask:0xf bank_mask:0xf bound_ctrl:1
	s_nop 1
	v_add_f32_dpp v88, v88, v88 row_half_mirror row_mask:0xf bank_mask:0xf bound_ctrl:1
	s_nop 1
	v_add_f32_dpp v88, v88, v88 row_mirror row_mask:0xf bank_mask:0xf bound_ctrl:1
	s_nop 0
	v_readlane_b32 s8, v88, 16
	v_readlane_b32 s9, v88, 48
	v_readlane_b32 s6, v88, 0
	v_readlane_b32 s7, v88, 32
	v_mov_b32_e32 v88, s8
	v_mov_b32_e32 v89, s9
	v_pk_add_f32 v[88:89], s[6:7], v[88:89]
	s_nop 0
	v_add_f32_e32 v88, v88, v89
	v_fmamk_f32 v88, v88, 0x3a000000, v252
	v_mul_f32_e32 v89, 0x4f800000, v88
	v_cmp_gt_f32_e32 vcc, s55, v88
	s_nop 1
	v_cndmask_b32_e32 v88, v88, v89, vcc
	v_sqrt_f32_e32 v89, v88
	s_nop 0
	v_add_u32_e32 v44, -1, v89
	v_fma_f32 v45, -v44, v89, v88
	v_cmp_ge_f32_e64 s[8:9], 0, v45
	v_add_u32_e32 v45, 1, v89
	s_nop 0
	v_cndmask_b32_e64 v44, v89, v44, s[8:9]
	v_fma_f32 v89, -v45, v89, v88
	v_cmp_lt_f32_e64 s[8:9], 0, v89
	s_nop 1
	v_cndmask_b32_e64 v44, v44, v45, s[8:9]
	v_mul_f32_e32 v45, 0x37800000, v44
	v_cndmask_b32_e32 v44, v44, v45, vcc
	v_cmp_class_f32_e32 vcc, v88, v253
	s_nop 1
	v_cndmask_b32_e32 v44, v44, v88, vcc
	v_div_scale_f32 v45, s[6:7], v44, v44, 1.0
	v_rcp_f32_e32 v104, v45
	global_load_dwordx2 v[122:123], v[42:43], off offset:2048 nt
	global_load_dwordx2 v[110:111], v[42:43], off offset:2560 nt
	global_load_dwordx2 v[94:95], v[42:43], off offset:3072 nt
	global_load_dwordx2 v[88:89], v[42:43], off offset:3584 nt
	v_fma_f32 v42, -v45, v104, 1.0
	v_fmac_f32_e32 v104, v42, v104
	v_div_scale_f32 v42, vcc, 1.0, v44, 1.0
	v_mul_f32_e32 v43, v42, v104
	v_fma_f32 v105, -v45, v43, v42
	v_fmac_f32_e32 v43, v105, v104
	v_fma_f32 v42, -v45, v43, v42
	v_div_fmas_f32 v42, v42, v104, v43
	v_div_fixup_f32 v42, v42, v44, 1.0
	v_pk_mul_f32 v[128:129], v[128:129], v[42:43] op_sel_hi:[1,0]
	v_pk_mul_f32 v[78:79], v[78:79], v[42:43] op_sel_hi:[1,0]
	v_lshlrev_b32_e32 v104, 16, v68
	v_and_b32_e32 v105, 0xffff0000, v68
	v_lshlrev_b32_e32 v68, 16, v69
	v_and_b32_e32 v69, 0xffff0000, v69
	v_pk_mul_f32 v[78:79], v[2:3], v[78:79]
	v_pk_mul_f32 v[128:129], v[4:5], v[128:129]
	v_lshl_add_u64 v[44:45], s[14:15], 1, v[34:35]
	v_pk_mul_f32 v[68:69], v[128:129], v[68:69]
	v_pk_mul_f32 v[78:79], v[78:79], v[104:105]
	v_lshl_add_u64 v[44:45], v[44:45], 0, v[0:1]
	v_cvt_pk_bf16_f32 v78, v78, v79
	v_cvt_pk_bf16_f32 v79, v68, v69
	global_store_dwordx2 v[44:45], v[78:79], off nt
	v_pk_mul_f32 v[78:79], v[84:85], v[42:43] op_sel_hi:[1,0]
	v_pk_mul_f32 v[70:71], v[70:71], v[42:43] op_sel_hi:[1,0]
	v_lshlrev_b32_e32 v68, 16, v64
	v_and_b32_e32 v69, 0xffff0000, v64
	v_lshlrev_b32_e32 v64, 16, v65
	v_and_b32_e32 v65, 0xffff0000, v65
	v_pk_mul_f32 v[70:71], v[6:7], v[70:71]
	v_pk_mul_f32 v[78:79], v[8:9], v[78:79]
	v_pk_mul_f32 v[68:69], v[70:71], v[68:69]
	v_pk_mul_f32 v[64:65], v[78:79], v[64:65]
	v_cvt_pk_bf16_f32 v68, v68, v69
	v_cvt_pk_bf16_f32 v69, v64, v65
	global_store_dwordx2 v[44:45], v[68:69], off offset:512 nt
	v_pk_mul_f32 v[68:69], v[134:135], v[42:43] op_sel_hi:[1,0]
	v_pk_mul_f32 v[70:71], v[130:131], v[42:43] op_sel_hi:[1,0]
	v_lshlrev_b32_e32 v64, 16, v58
	v_and_b32_e32 v65, 0xffff0000, v58
	v_lshlrev_b32_e32 v58, 16, v59
	v_and_b32_e32 v59, 0xffff0000, v59
	v_pk_mul_f32 v[70:71], v[10:11], v[70:71]
	v_pk_mul_f32 v[68:69], v[12:13], v[68:69]
	v_pk_mul_f32 v[64:65], v[70:71], v[64:65]
	v_pk_mul_f32 v[58:59], v[68:69], v[58:59]
	v_cvt_pk_bf16_f32 v64, v64, v65
	v_cvt_pk_bf16_f32 v65, v58, v59
	global_store_dwordx2 v[44:45], v[64:65], off offset:1024 nt
	v_pk_mul_f32 v[64:65], v[114:115], v[42:43] op_sel_hi:[1,0]
	v_pk_mul_f32 v[68:69], v[124:125], v[42:43] op_sel_hi:[1,0]
	v_lshlrev_b32_e32 v58, 16, v62
	v_and_b32_e32 v59, 0xffff0000, v62
	v_lshlrev_b32_e32 v62, 16, v63
	v_and_b32_e32 v63, 0xffff0000, v63
	v_pk_mul_f32 v[68:69], v[14:15], v[68:69]
	v_pk_mul_f32 v[64:65], v[16:17], v[64:65]
	v_pk_mul_f32 v[58:59], v[68:69], v[58:59]
	v_pk_mul_f32 v[62:63], v[64:65], v[62:63]
	v_cvt_pk_bf16_f32 v58, v58, v59
	v_cvt_pk_bf16_f32 v59, v62, v63
	v_pk_mul_f32 v[62:63], v[112:113], v[42:43] op_sel_hi:[1,0]
	v_pk_mul_f32 v[64:65], v[166:167], v[42:43] op_sel_hi:[1,0]
	global_store_dwordx2 v[44:45], v[58:59], off offset:1536 nt
	v_lshlrev_b32_e32 v58, 16, v56
	v_and_b32_e32 v59, 0xffff0000, v56
; #define GAS __attribute__((address_space(1)))
; #define LAS __attribute__((address_space(3)))
; template <bool HG>
; __device__ __forceinline__ void readout_phase2(const Args& a, Frame& F, const float* gain, int nrows) {
;     ...
;     RO_LOAD(f0, b0, g0, nw); RO_LOAD(f1, b1, g1, nw + 2048); RO_LOAD(f2, b2, g2, nw + 2 * 2048);
;     if (HG) { for (int q = F.tid; q < D / 4; q += NWAVES * 64) ((LAS f32x4*)GL)[q] = ((const GAS f32x4*)gain)[q];
;               asm volatile("s_waitcnt lgkmcnt(0)" ::: "memory"); __builtin_amdgcn_s_barrier(); asm volatile("" ::: "memory"); }
;     RO_FINISH(f0, b0, g0, nw);            RO_LOAD(f0, b0, g0, nw + 3 * 2048);
;     RO_FINISH(f1, b1, g1, nw + 2048);     RO_LOAD(f1, b1, g1, nw + 4 * 2048);
;     RO_FINISH(f2, b2, g2, nw + 2 * 2048); RO_LOAD(f2, b2, g2, nw + 5 * 2048);
;     RO_FINISH(f0, b0, g0, nw + 3 * 2048); RO_LOAD(f0, b0, g0, nw + 6 * 2048);
	v_lshlrev_b32_e32 v56, 16, v57
	v_and_b32_e32 v57, 0xffff0000, v57
	v_pk_mul_f32 v[64:65], v[18:19], v[64:65]
	v_pk_mul_f32 v[62:63], v[20:21], v[62:63]
	v_pk_mul_f32 v[58:59], v[64:65], v[58:59]
	v_pk_mul_f32 v[56:57], v[62:63], v[56:57]
	v_cvt_pk_bf16_f32 v58, v58, v59
	v_cvt_pk_bf16_f32 v59, v56, v57
	global_store_dwordx2 v[44:45], v[58:59], off offset:2048 nt
	v_pk_mul_f32 v[58:59], v[102:103], v[42:43] op_sel_hi:[1,0]
	v_pk_mul_f32 v[62:63], v[116:117], v[42:43] op_sel_hi:[1,0]
	v_lshlrev_b32_e32 v56, 16, v52
	v_and_b32_e32 v57, 0xffff0000, v52
	v_lshlrev_b32_e32 v52, 16, v53
	v_and_b32_e32 v53, 0xffff0000, v53
	v_pk_mul_f32 v[62:63], v[22:23], v[62:63]
	v_pk_mul_f32 v[58:59], v[24:25], v[58:59]
	v_pk_mul_f32 v[56:57], v[62:63], v[56:57]
	v_pk_mul_f32 v[52:53], v[58:59], v[52:53]
	v_cvt_pk_bf16_f32 v56, v56, v57
	v_cvt_pk_bf16_f32 v57, v52, v53
	global_store_dwordx2 v[44:45], v[56:57], off offset:2560 nt
	v_pk_mul_f32 v[56:57], v[92:93], v[42:43] op_sel_hi:[1,0]
	v_pk_mul_f32 v[58:59], v[132:133], v[42:43] op_sel_hi:[1,0]
	v_lshlrev_b32_e32 v52, 16, v48
	v_and_b32_e32 v53, 0xffff0000, v48
	v_lshlrev_b32_e32 v48, 16, v49
	v_and_b32_e32 v49, 0xffff0000, v49
	v_pk_mul_f32 v[58:59], v[26:27], v[58:59]
	v_pk_mul_f32 v[56:57], v[28:29], v[56:57]
	v_pk_mul_f32 v[52:53], v[58:59], v[52:53]
	v_pk_mul_f32 v[48:49], v[56:57], v[48:49]
	v_cvt_pk_bf16_f32 v52, v52, v53
	v_cvt_pk_bf16_f32 v53, v48, v49
	global_store_dwordx2 v[44:45], v[52:53], off offset:3072 nt
	v_pk_mul_f32 v[52:53], v[86:87], v[42:43] op_sel_hi:[1,0]
	v_pk_mul_f32 v[42:43], v[136:137], v[42:43] op_sel_hi:[1,0]
	s_waitcnt vmcnt(62)
	v_lshlrev_b32_e32 v48, 16, v50
	v_and_b32_e32 v49, 0xffff0000, v50
	v_lshlrev_b32_e32 v50, 16, v51
	v_and_b32_e32 v51, 0xffff0000, v51
	v_pk_mul_f32 v[42:43], v[30:31], v[42:43]
	v_pk_mul_f32 v[52:53], v[32:33], v[52:53]
	v_pk_mul_f32 v[42:43], v[42:43], v[48:49]
	v_pk_mul_f32 v[50:51], v[52:53], v[50:51]
	s_add_u32 s14, s12, 0x2800000
	v_cvt_pk_bf16_f32 v42, v42, v43
	v_cvt_pk_bf16_f32 v43, v50, v51
	s_addc_u32 s15, s13, 0
	global_store_dwordx2 v[44:45], v[42:43], off offset:3584 nt
	v_lshl_add_u64 v[42:43], v[36:37], 0, s[14:15]
	v_lshl_add_u64 v[52:53], v[42:43], 0, v[0:1]
	v_lshl_add_u64 v[42:43], v[38:39], 0, s[14:15]
	v_lshl_add_u64 v[48:49], v[42:43], 0, v[0:1]
	v_lshl_add_u64 v[42:43], v[40:41], 0, s[14:15]
	v_lshl_add_u64 v[42:43], v[42:43], 0, v[0:1]
	global_load_dwordx2 v[166:167], v[52:53], off nt
	global_load_dwordx2 v[134:135], v[52:53], off offset:512 nt
	global_load_dwordx2 v[128:129], v[52:53], off offset:1024 nt
	global_load_dwordx2 v[112:113], v[52:53], off offset:1536 nt
	global_load_dwordx2 v[172:173], v[48:49], off nt
	global_load_dwordx2 v[136:137], v[48:49], off offset:512 nt
	global_load_dwordx2 v[130:131], v[48:49], off offset:1024 nt
	global_load_dwordx2 v[114:115], v[48:49], off offset:1536 nt
	global_load_dwordx2 v[62:63], v[42:43], off nt
	global_load_dwordx2 v[56:57], v[42:43], off offset:512 nt
	global_load_dwordx2 v[50:51], v[42:43], off offset:1024 nt
	global_load_dwordx2 v[44:45], v[42:43], off offset:1536 nt
	global_load_dwordx2 v[102:103], v[52:53], off offset:2048 nt
	global_load_dwordx2 v[84:85], v[52:53], off offset:2560 nt
	global_load_dwordx2 v[78:79], v[52:53], off offset:3072 nt
	global_load_dwordx2 v[70:71], v[52:53], off offset:3584 nt
	v_lshlrev_b32_e32 v52, 16, v168
	v_and_b32_e32 v53, 0xffff0000, v168
	s_waitcnt vmcnt(62)
	v_lshlrev_b32_e32 v58, 16, v174
	v_and_b32_e32 v59, 0xffff0000, v174
	v_pk_add_f32 v[58:59], v[52:53], v[58:59]
	v_lshlrev_b32_e32 v52, 16, v169
	v_and_b32_e32 v53, 0xffff0000, v169
	v_lshlrev_b32_e32 v64, 16, v175
	v_and_b32_e32 v65, 0xffff0000, v175
	v_pk_add_f32 v[68:69], v[52:53], v[64:65]
	v_lshlrev_b32_e32 v52, 16, v162
	v_and_b32_e32 v53, 0xffff0000, v162
	v_lshlrev_b32_e32 v64, 16, v164
	v_and_b32_e32 v65, 0xffff0000, v164
	v_pk_add_f32 v[52:53], v[52:53], v[64:65]
	v_lshlrev_b32_e32 v64, 16, v163
	v_and_b32_e32 v65, 0xffff0000, v163
	v_lshlrev_b32_e32 v86, 16, v165
	v_and_b32_e32 v87, 0xffff0000, v165
	v_pk_add_f32 v[64:65], v[64:65], v[86:87]
	v_mov_b32_e32 v92, v59
	v_mov_b32_e32 v93, v53
	v_mov_b32_e32 v86, v58
	v_mov_b32_e32 v87, v52
	v_pk_mul_f32 v[92:93], v[92:93], v[92:93]
	v_mov_b32_e32 v104, v69
	v_mov_b32_e32 v105, v65
	v_pk_fma_f32 v[86:87], v[86:87], v[86:87], v[92:93]
	v_mov_b32_e32 v92, v68
	v_mov_b32_e32 v93, v64
	v_pk_mul_f32 v[104:105], v[104:105], v[104:105]
	v_lshlrev_b32_e32 v116, 16, v156
	v_pk_fma_f32 v[92:93], v[92:93], v[92:93], v[104:105]
	v_lshlrev_b32_e32 v104, 16, v160
	v_pk_add_f32 v[86:87], v[86:87], v[92:93]
	v_lshlrev_b32_e32 v92, 16, v158
	v_and_b32_e32 v93, 0xffff0000, v158
	v_and_b32_e32 v105, 0xffff0000, v160
	v_pk_add_f32 v[124:125], v[92:93], v[104:105]
	v_lshlrev_b32_e32 v92, 16, v159
	v_and_b32_e32 v93, 0xffff0000, v159
	v_lshlrev_b32_e32 v104, 16, v161
	v_and_b32_e32 v105, 0xffff0000, v161
	v_pk_add_f32 v[158:159], v[92:93], v[104:105]
	v_mov_b32_e32 v104, v125
	v_mov_b32_e32 v105, v159
	v_mov_b32_e32 v92, v124
	v_mov_b32_e32 v93, v158
	v_pk_mul_f32 v[104:105], v[104:105], v[104:105]
	v_and_b32_e32 v117, 0xffff0000, v156
	v_pk_fma_f32 v[92:93], v[92:93], v[92:93], v[104:105]
	v_lshlrev_b32_e32 v104, 16, v154
	v_and_b32_e32 v105, 0xffff0000, v154
	v_pk_add_f32 v[132:133], v[104:105], v[116:117]
	v_lshlrev_b32_e32 v104, 16, v155
	v_and_b32_e32 v105, 0xffff0000, v155
	v_lshlrev_b32_e32 v116, 16, v157
	v_and_b32_e32 v117, 0xffff0000, v157
	v_lshlrev_b32_e32 v156, 16, v152
	v_and_b32_e32 v157, 0xffff0000, v152
	v_lshlrev_b32_e32 v160, 16, v196
	v_and_b32_e32 v161, 0xffff0000, v196
	v_pk_add_f32 v[154:155], v[104:105], v[116:117]
; #define GAS __attribute__((address_space(1)))
; #define LAS __attribute__((address_space(3)))
; template <bool HG>
; __device__ __forceinline__ void readout_phase2(const Args& a, Frame& F, const float* gain, int nrows) {
;     ...
;     RO_LOAD(f0, b0, g0, nw); RO_LOAD(f1, b1, g1, nw + 2048); RO_LOAD(f2, b2, g2, nw + 2 * 2048);
;     if (HG) { for (int q = F.tid; q < D / 4; q += NWAVES * 64) ((LAS f32x4*)GL)[q] = ((const GAS f32x4*)gain)[q];
;               asm volatile("s_waitcnt lgkmcnt(0)" ::: "memory"); __builtin_amdgcn_s_barrier(); asm volatile("" ::: "memory"); }
;     RO_FINISH(f0, b0, g0, nw);            RO_LOAD(f0, b0, g0, nw + 3 * 2048);
;     RO_FINISH(f1, b1, g1, nw + 2048);     RO_LOAD(f1, b1, g1, nw + 4 * 2048);
;     RO_FINISH(f2, b2, g2, nw + 2 * 2048); RO_LOAD(f2, b2, g2, nw + 5 * 2048);
;     RO_FINISH(f0, b0, g0, nw + 3 * 2048); RO_LOAD(f0, b0, g0, nw + 6 * 2048);
	v_pk_add_f32 v[162:163], v[156:157], v[160:161]
	v_lshlrev_b32_e32 v152, 16, v153
	v_and_b32_e32 v153, 0xffff0000, v153
	v_lshlrev_b32_e32 v156, 16, v197
	v_and_b32_e32 v157, 0xffff0000, v197
	v_mul_f32_e32 v104, v133, v133
	v_mul_f32_e32 v116, v155, v155
	v_pk_add_f32 v[168:169], v[152:153], v[156:157]
	v_pk_add_f32 v[86:87], v[86:87], v[86:87] op_sel:[0,1] op_sel_hi:[1,0]
	v_pk_add_f32 v[92:93], v[92:93], v[92:93] op_sel:[0,1] op_sel_hi:[1,0]
	v_pk_fma_f32 v[104:105], v[132:133], v[132:133], v[104:105] op_sel_hi:[1,1,0]
	v_pk_fma_f32 v[116:117], v[154:155], v[154:155], v[116:117] op_sel_hi:[1,1,0]
	v_pk_mul_f32 v[152:153], v[162:163], v[162:163]
	v_pk_mul_f32 v[156:157], v[168:169], v[168:169]
	v_mov_b32_e32 v87, v152
	v_mov_b32_e32 v93, v153
	v_mov_b32_e32 v105, v156
	v_mov_b32_e32 v117, v157
	v_pk_add_f32 v[86:87], v[86:87], v[92:93]
	v_pk_add_f32 v[92:93], v[104:105], v[116:117]
	v_lshlrev_b32_e32 v104, 16, v192
	v_pk_add_f32 v[86:87], v[86:87], v[92:93]
	v_lshlrev_b32_e32 v92, 16, v150
	v_and_b32_e32 v93, 0xffff0000, v150
	v_and_b32_e32 v105, 0xffff0000, v192
	v_pk_add_f32 v[174:175], v[92:93], v[104:105]
	v_lshlrev_b32_e32 v92, 16, v151
	v_and_b32_e32 v93, 0xffff0000, v151
	v_lshlrev_b32_e32 v104, 16, v193
	v_and_b32_e32 v105, 0xffff0000, v193
	v_pk_add_f32 v[150:151], v[92:93], v[104:105]
	v_mov_b32_e32 v104, v175
	v_mov_b32_e32 v105, v151
	v_mov_b32_e32 v92, v174
	v_mov_b32_e32 v93, v150
	v_pk_mul_f32 v[104:105], v[104:105], v[104:105]
	s_waitcnt vmcnt(61)
	v_lshlrev_b32_e32 v116, 16, v188
	v_pk_fma_f32 v[92:93], v[92:93], v[92:93], v[104:105]
	v_lshlrev_b32_e32 v104, 16, v148
	v_and_b32_e32 v105, 0xffff0000, v148
	v_and_b32_e32 v117, 0xffff0000, v188
	v_pk_add_f32 v[178:179], v[104:105], v[116:117]
	v_lshlrev_b32_e32 v104, 16, v149
	v_and_b32_e32 v105, 0xffff0000, v149
	v_lshlrev_b32_e32 v116, 16, v189
	v_and_b32_e32 v117, 0xffff0000, v189
	v_lshlrev_b32_e32 v152, 16, v140
	v_and_b32_e32 v153, 0xffff0000, v140
	s_waitcnt vmcnt(60)
	v_lshlrev_b32_e32 v156, 16, v184
	v_and_b32_e32 v157, 0xffff0000, v184
	v_pk_add_f32 v[148:149], v[104:105], v[116:117]
	v_pk_add_f32 v[180:181], v[152:153], v[156:157]
	v_lshlrev_b32_e32 v140, 16, v141
	v_and_b32_e32 v141, 0xffff0000, v141
	v_lshlrev_b32_e32 v152, 16, v185
	v_and_b32_e32 v153, 0xffff0000, v185
	v_mul_f32_e32 v104, v179, v179
	v_mul_f32_e32 v116, v149, v149
	v_pk_add_f32 v[140:141], v[140:141], v[152:153]
	v_pk_add_f32 v[86:87], v[86:87], v[86:87] op_sel:[0,1] op_sel_hi:[1,0]
	v_pk_add_f32 v[92:93], v[92:93], v[92:93] op_sel:[0,1] op_sel_hi:[1,0]
	v_pk_fma_f32 v[104:105], v[178:179], v[178:179], v[104:105] op_sel_hi:[1,1,0]
	v_pk_fma_f32 v[116:117], v[148:149], v[148:149], v[116:117] op_sel_hi:[1,1,0]
	v_pk_mul_f32 v[152:153], v[180:181], v[180:181]
	v_pk_mul_f32 v[156:157], v[140:141], v[140:141]
	v_mov_b32_e32 v87, v152
	v_mov_b32_e32 v93, v153
	v_mov_b32_e32 v105, v156
	v_mov_b32_e32 v117, v157
	v_pk_add_f32 v[86:87], v[86:87], v[92:93]
	v_pk_add_f32 v[92:93], v[104:105], v[116:117]
	global_load_dwordx2 v[164:165], v[48:49], off offset:2048 nt
	global_load_dwordx2 v[160:161], v[48:49], off offset:2560 nt
	global_load_dwordx2 v[156:157], v[48:49], off offset:3072 nt
	global_load_dwordx2 v[152:153], v[48:49], off offset:3584 nt
	v_pk_add_f32 v[86:87], v[86:87], v[92:93]
	s_add_u32 s12, s12, 0x3000000
	v_add_f32_e32 v86, v86, v87
	s_addc_u32 s13, s13, 0
	s_nop 0
	v_add_f32_dpp v86, v86, v86 quad_perm:[1,0,3,2] row_mask:0xf bank_mask:0xf bound_ctrl:1
	s_nop 1
	v_add_f32_dpp v86, v86, v86 quad_perm:[2,3,0,1] row_mask:0xf bank_mask:0xf bound_ctrl:1
	s_nop 1
	v_add_f32_dpp v86, v86, v86 row_half_mirror row_mask:0xf bank_mask:0xf bound_ctrl:1
	s_nop 1
	v_add_f32_dpp v86, v86, v86 row_mirror row_mask:0xf bank_mask:0xf bound_ctrl:1
	s_nop 0
	v_readlane_b32 s8, v86, 16
	v_readlane_b32 s9, v86, 48
	v_readlane_b32 s6, v86, 0
	v_readlane_b32 s7, v86, 32
	v_mov_b32_e32 v86, s8
	v_mov_b32_e32 v87, s9
	v_pk_add_f32 v[86:87], s[6:7], v[86:87]
	s_nop 0
	v_add_f32_e32 v86, v86, v87
	v_fmamk_f32 v86, v86, 0x3a000000, v252
	v_mul_f32_e32 v87, 0x4f800000, v86
	v_cmp_gt_f32_e32 vcc, s55, v86
	s_nop 1
	v_cndmask_b32_e32 v86, v86, v87, vcc
	v_sqrt_f32_e32 v87, v86
	s_nop 0
	v_add_u32_e32 v48, -1, v87
	v_fma_f32 v49, -v48, v87, v86
	v_cmp_ge_f32_e64 s[8:9], 0, v49
	v_add_u32_e32 v49, 1, v87
	s_nop 0
	v_cndmask_b32_e64 v48, v87, v48, s[8:9]
	v_fma_f32 v87, -v49, v87, v86
	v_cmp_lt_f32_e64 s[8:9], 0, v87
	s_nop 1
	v_cndmask_b32_e64 v48, v48, v49, s[8:9]
	v_mul_f32_e32 v49, 0x37800000, v48
	v_cndmask_b32_e32 v48, v48, v49, vcc
	v_cmp_class_f32_e32 vcc, v86, v253
	s_nop 1
	v_cndmask_b32_e32 v48, v48, v86, vcc
	v_div_scale_f32 v49, s[6:7], v48, v48, 1.0
	v_rcp_f32_e32 v184, v49
	global_load_dwordx2 v[116:117], v[42:43], off offset:2048 nt
	global_load_dwordx2 v[104:105], v[42:43], off offset:2560 nt
	global_load_dwordx2 v[92:93], v[42:43], off offset:3072 nt
	global_load_dwordx2 v[86:87], v[42:43], off offset:3584 nt
	v_fma_f32 v42, -v49, v184, 1.0
	v_fmac_f32_e32 v184, v42, v184
	v_div_scale_f32 v42, vcc, 1.0, v48, 1.0
	v_mul_f32_e32 v43, v42, v184
	v_fma_f32 v185, -v49, v43, v42
	v_fmac_f32_e32 v43, v185, v184
	v_fma_f32 v42, -v49, v43, v42
	v_div_fmas_f32 v42, v42, v184, v43
	v_div_fixup_f32 v42, v42, v48, 1.0
	v_pk_mul_f32 v[68:69], v[68:69], v[42:43] op_sel_hi:[1,0]
	v_pk_mul_f32 v[58:59], v[58:59], v[42:43] op_sel_hi:[1,0]
	v_lshlrev_b32_e32 v184, 16, v100
	v_and_b32_e32 v185, 0xffff0000, v100
	v_lshlrev_b32_e32 v100, 16, v101
	v_and_b32_e32 v101, 0xffff0000, v101
	v_pk_mul_f32 v[58:59], v[2:3], v[58:59]
	v_pk_mul_f32 v[68:69], v[4:5], v[68:69]
	v_lshl_add_u64 v[48:49], v[34:35], 0, s[16:17]
; #define GAS __attribute__((address_space(1)))
; #define LAS __attribute__((address_space(3)))
; template <bool HG>
; __device__ __forceinline__ void readout_phase2(const Args& a, Frame& F, const float* gain, int nrows) {
;     ...
;     RO_LOAD(f0, b0, g0, nw); RO_LOAD(f1, b1, g1, nw + 2048); RO_LOAD(f2, b2, g2, nw + 2 * 2048);
;     if (HG) { for (int q = F.tid; q < D / 4; q += NWAVES * 64) ((LAS f32x4*)GL)[q] = ((const GAS f32x4*)gain)[q];
;               asm volatile("s_waitcnt lgkmcnt(0)" ::: "memory"); __builtin_amdgcn_s_barrier(); asm volatile("" ::: "memory"); }
;     RO_FINISH(f0, b0, g0, nw);            RO_LOAD(f0, b0, g0, nw + 3 * 2048);
;     RO_FINISH(f1, b1, g1, nw + 2048);     RO_LOAD(f1, b1, g1, nw + 4 * 2048);
;     RO_FINISH(f2, b2, g2, nw + 2 * 2048); RO_LOAD(f2, b2, g2, nw + 5 * 2048);
;     RO_FINISH(f0, b0, g0, nw + 3 * 2048); RO_LOAD(f0, b0, g0, nw + 6 * 2048);
;     RO_FINISH(f1, b1, g1, nw + 4 * 2048); RO_LOAD(f1, b1, g1, nw + 7 * 2048);
	v_pk_mul_f32 v[68:69], v[68:69], v[100:101]
	v_pk_mul_f32 v[58:59], v[58:59], v[184:185]
	v_lshl_add_u64 v[48:49], v[48:49], 0, v[0:1]
	v_cvt_pk_bf16_f32 v58, v58, v59
	v_cvt_pk_bf16_f32 v59, v68, v69
	v_pk_mul_f32 v[64:65], v[64:65], v[42:43] op_sel_hi:[1,0]
	v_pk_mul_f32 v[52:53], v[52:53], v[42:43] op_sel_hi:[1,0]
	global_store_dwordx2 v[48:49], v[58:59], off nt
	v_lshlrev_b32_e32 v58, 16, v90
	v_and_b32_e32 v59, 0xffff0000, v90
	v_lshlrev_b32_e32 v68, 16, v91
	v_and_b32_e32 v69, 0xffff0000, v91
	v_pk_mul_f32 v[52:53], v[6:7], v[52:53]
	v_pk_mul_f32 v[64:65], v[8:9], v[64:65]
	v_pk_mul_f32 v[52:53], v[52:53], v[58:59]
	v_pk_mul_f32 v[64:65], v[64:65], v[68:69]
	v_cvt_pk_bf16_f32 v52, v52, v53
	v_cvt_pk_bf16_f32 v53, v64, v65
	v_pk_mul_f32 v[64:65], v[158:159], v[42:43] op_sel_hi:[1,0]
	v_pk_mul_f32 v[68:69], v[124:125], v[42:43] op_sel_hi:[1,0]
	global_store_dwordx2 v[48:49], v[52:53], off offset:512 nt
	v_lshlrev_b32_e32 v52, 16, v80
	v_and_b32_e32 v53, 0xffff0000, v80
	v_lshlrev_b32_e32 v58, 16, v81
	v_and_b32_e32 v59, 0xffff0000, v81
	v_pk_mul_f32 v[68:69], v[10:11], v[68:69]
	v_pk_mul_f32 v[64:65], v[12:13], v[64:65]
	v_pk_mul_f32 v[52:53], v[68:69], v[52:53]
	v_pk_mul_f32 v[58:59], v[64:65], v[58:59]
	v_cvt_pk_bf16_f32 v52, v52, v53
	v_cvt_pk_bf16_f32 v53, v58, v59
	v_pk_mul_f32 v[64:65], v[154:155], v[42:43] op_sel_hi:[1,0]
	v_pk_mul_f32 v[68:69], v[132:133], v[42:43] op_sel_hi:[1,0]
	global_store_dwordx2 v[48:49], v[52:53], off offset:1024 nt
	v_lshlrev_b32_e32 v52, 16, v76
	v_and_b32_e32 v53, 0xffff0000, v76
	v_lshlrev_b32_e32 v58, 16, v77
	v_and_b32_e32 v59, 0xffff0000, v77
	v_pk_mul_f32 v[68:69], v[14:15], v[68:69]
	v_pk_mul_f32 v[64:65], v[16:17], v[64:65]
	v_pk_mul_f32 v[52:53], v[68:69], v[52:53]
	v_pk_mul_f32 v[58:59], v[64:65], v[58:59]
	v_pk_mul_f32 v[64:65], v[168:169], v[42:43] op_sel_hi:[1,0]
	v_cvt_pk_bf16_f32 v52, v52, v53
	v_cvt_pk_bf16_f32 v53, v58, v59
	s_waitcnt vmcnt(62)
	v_lshlrev_b32_e32 v58, 16, v127
	v_and_b32_e32 v59, 0xffff0000, v127
	v_pk_mul_f32 v[68:69], v[162:163], v[42:43] op_sel_hi:[1,0]
	v_pk_mul_f32 v[64:65], v[20:21], v[64:65]
	global_store_dwordx2 v[48:49], v[52:53], off offset:1536 nt
	v_lshlrev_b32_e32 v52, 16, v126
	v_and_b32_e32 v53, 0xffff0000, v126
	v_pk_mul_f32 v[68:69], v[18:19], v[68:69]
	v_pk_mul_f32 v[58:59], v[64:65], v[58:59]
	v_pk_mul_f32 v[64:65], v[150:151], v[42:43] op_sel_hi:[1,0]
	s_waitcnt vmcnt(59)
	v_lshlrev_b32_e32 v150, 16, v170
	v_and_b32_e32 v151, 0xffff0000, v170
	s_waitcnt vmcnt(55)
	v_lshlrev_b32_e32 v154, 16, v176
	v_and_b32_e32 v155, 0xffff0000, v176
	v_pk_mul_f32 v[52:53], v[68:69], v[52:53]
	v_pk_mul_f32 v[68:69], v[174:175], v[42:43] op_sel_hi:[1,0]
	v_pk_add_f32 v[174:175], v[150:151], v[154:155]
	v_lshlrev_b32_e32 v150, 16, v171
	v_and_b32_e32 v151, 0xffff0000, v171
	v_lshlrev_b32_e32 v154, 16, v177
	v_and_b32_e32 v155, 0xffff0000, v177
	v_pk_add_f32 v[170:171], v[150:151], v[154:155]
	v_lshlrev_b32_e32 v150, 16, v144
	v_and_b32_e32 v151, 0xffff0000, v144
	s_waitcnt vmcnt(54)
	v_lshlrev_b32_e32 v154, 16, v146
	v_and_b32_e32 v155, 0xffff0000, v146
	v_pk_add_f32 v[168:169], v[150:151], v[154:155]
	v_lshlrev_b32_e32 v144, 16, v145
	v_and_b32_e32 v145, 0xffff0000, v145
	v_lshlrev_b32_e32 v146, 16, v147
	v_and_b32_e32 v147, 0xffff0000, v147
	v_pk_add_f32 v[144:145], v[144:145], v[146:147]
	v_mov_b32_e32 v150, v175
	v_mov_b32_e32 v151, v169
	v_mov_b32_e32 v146, v174
	v_mov_b32_e32 v147, v168
	v_pk_mul_f32 v[150:151], v[150:151], v[150:151]
	v_mov_b32_e32 v154, v171
	v_mov_b32_e32 v155, v145
	v_pk_fma_f32 v[146:147], v[146:147], v[146:147], v[150:151]
	v_mov_b32_e32 v150, v170
	v_mov_b32_e32 v151, v144
	v_pk_mul_f32 v[154:155], v[154:155], v[154:155]
	v_cvt_pk_bf16_f32 v52, v52, v53
	v_pk_fma_f32 v[150:151], v[150:151], v[150:151], v[154:155]
	s_waitcnt vmcnt(53)
	v_lshlrev_b32_e32 v154, 16, v142
	v_pk_add_f32 v[146:147], v[146:147], v[150:151]
	v_and_b32_e32 v155, 0xffff0000, v142
	v_pk_add_f32 v[150:151], v[146:147], v[146:147] op_sel:[0,1] op_sel_hi:[1,0]
	v_lshlrev_b32_e32 v146, 16, v138
	v_and_b32_e32 v147, 0xffff0000, v138
	v_lshlrev_b32_e32 v138, 16, v139
	v_and_b32_e32 v139, 0xffff0000, v139
	v_lshlrev_b32_e32 v142, 16, v143
	v_and_b32_e32 v143, 0xffff0000, v143
	v_pk_add_f32 v[146:147], v[146:147], v[154:155]
	v_pk_add_f32 v[142:143], v[138:139], v[142:143]
	v_mov_b32_e32 v154, v147
	v_mov_b32_e32 v155, v143
	v_mov_b32_e32 v138, v146
	v_mov_b32_e32 v139, v142
	v_pk_mul_f32 v[154:155], v[154:155], v[154:155]
	v_cvt_pk_bf16_f32 v53, v58, v59
	v_pk_fma_f32 v[138:139], v[138:139], v[138:139], v[154:155]
	s_waitcnt vmcnt(52)
	v_lshlrev_b32_e32 v158, 16, v120
	v_pk_add_f32 v[154:155], v[138:139], v[138:139] op_sel:[0,1] op_sel_hi:[1,0]
	v_lshlrev_b32_e32 v138, 16, v118
	v_and_b32_e32 v139, 0xffff0000, v118
	v_and_b32_e32 v159, 0xffff0000, v120
	v_lshlrev_b32_e32 v118, 16, v119
	v_and_b32_e32 v119, 0xffff0000, v119
	v_lshlrev_b32_e32 v120, 16, v121
	v_and_b32_e32 v121, 0xffff0000, v121
	s_waitcnt vmcnt(47)
	v_lshlrev_b32_e32 v162, 16, v106
	v_and_b32_e32 v163, 0xffff0000, v106
	s_waitcnt vmcnt(43)
; #define GAS __attribute__((address_space(1)))
; #define LAS __attribute__((address_space(3)))
; template <bool HG>
; __device__ __forceinline__ void readout_phase2(const Args& a, Frame& F, const float* gain, int nrows) {
;     ...
;     RO_LOAD(f0, b0, g0, nw); RO_LOAD(f1, b1, g1, nw + 2048); RO_LOAD(f2, b2, g2, nw + 2 * 2048);
;     if (HG) { for (int q = F.tid; q < D / 4; q += NWAVES * 64) ((LAS f32x4*)GL)[q] = ((const GAS f32x4*)gain)[q];
;               asm volatile("s_waitcnt lgkmcnt(0)" ::: "memory"); __builtin_amdgcn_s_barrier(); asm volatile("" ::: "memory"); }
;     RO_FINISH(f0, b0, g0, nw);            RO_LOAD(f0, b0, g0, nw + 3 * 2048);
;     RO_FINISH(f1, b1, g1, nw + 2048);     RO_LOAD(f1, b1, g1, nw + 4 * 2048);
;     RO_FINISH(f2, b2, g2, nw + 2 * 2048); RO_LOAD(f2, b2, g2, nw + 5 * 2048);
;     RO_FINISH(f0, b0, g0, nw + 3 * 2048); RO_LOAD(f0, b0, g0, nw + 6 * 2048);
;     RO_FINISH(f1, b1, g1, nw + 4 * 2048); RO_LOAD(f1, b1, g1, nw + 7 * 2048);
	v_lshlrev_b32_e32 v176, 16, v198
	v_and_b32_e32 v177, 0xffff0000, v198
	global_store_dwordx2 v[48:49], v[52:53], off offset:2048 nt
	v_lshlrev_b32_e32 v52, 16, v108
	v_and_b32_e32 v53, 0xffff0000, v108
	v_pk_mul_f32 v[68:69], v[22:23], v[68:69]
	v_pk_add_f32 v[138:139], v[138:139], v[158:159]
	v_pk_add_f32 v[118:119], v[118:119], v[120:121]
	v_pk_add_f32 v[176:177], v[162:163], v[176:177]
	v_lshlrev_b32_e32 v106, 16, v107
	v_and_b32_e32 v107, 0xffff0000, v107
	v_lshlrev_b32_e32 v162, 16, v199
	v_and_b32_e32 v163, 0xffff0000, v199
	v_pk_mul_f32 v[52:53], v[68:69], v[52:53]
	v_pk_mul_f32 v[68:69], v[178:179], v[42:43] op_sel_hi:[1,0]
	v_mul_f32_e32 v120, v139, v139
	v_mul_f32_e32 v158, v119, v119
	v_pk_add_f32 v[178:179], v[106:107], v[162:163]
	v_pk_fma_f32 v[120:121], v[138:139], v[138:139], v[120:121] op_sel_hi:[1,1,0]
	v_pk_fma_f32 v[158:159], v[118:119], v[118:119], v[158:159] op_sel_hi:[1,1,0]
	v_pk_mul_f32 v[106:107], v[176:177], v[176:177]
	v_pk_mul_f32 v[162:163], v[178:179], v[178:179]
	v_mov_b32_e32 v151, v106
	v_mov_b32_e32 v155, v107
	v_mov_b32_e32 v121, v162
	v_mov_b32_e32 v159, v163
	v_lshlrev_b32_e32 v58, 16, v109
	v_and_b32_e32 v59, 0xffff0000, v109
	v_pk_mul_f32 v[64:65], v[24:25], v[64:65]
	v_pk_add_f32 v[106:107], v[150:151], v[154:155]
	v_pk_add_f32 v[120:121], v[120:121], v[158:159]
	v_pk_mul_f32 v[58:59], v[64:65], v[58:59]
	v_pk_mul_f32 v[64:65], v[148:149], v[42:43] op_sel_hi:[1,0]
	v_pk_add_f32 v[106:107], v[106:107], v[120:121]
	v_lshlrev_b32_e32 v120, 16, v96
	v_and_b32_e32 v121, 0xffff0000, v96
	s_waitcnt vmcnt(43)
	v_lshlrev_b32_e32 v150, 16, v194
	v_and_b32_e32 v151, 0xffff0000, v194
	v_cvt_pk_bf16_f32 v52, v52, v53
	v_cvt_pk_bf16_f32 v53, v58, v59
	v_lshlrev_b32_e32 v58, 16, v99
	v_and_b32_e32 v59, 0xffff0000, v99
	v_pk_mul_f32 v[64:65], v[28:29], v[64:65]
	v_pk_add_f32 v[120:121], v[120:121], v[150:151]
	v_lshlrev_b32_e32 v96, 16, v97
	v_and_b32_e32 v97, 0xffff0000, v97
	v_lshlrev_b32_e32 v150, 16, v195
	v_and_b32_e32 v151, 0xffff0000, v195
	v_pk_mul_f32 v[58:59], v[64:65], v[58:59]
	v_pk_mul_f32 v[64:65], v[140:141], v[42:43] op_sel_hi:[1,0]
	v_pk_mul_f32 v[42:43], v[180:181], v[42:43] op_sel_hi:[1,0]
	v_pk_add_f32 v[180:181], v[96:97], v[150:151]
	v_mov_b32_e32 v150, v121
	v_mov_b32_e32 v151, v181
	v_mov_b32_e32 v96, v120
	v_mov_b32_e32 v97, v180
	v_pk_mul_f32 v[150:151], v[150:151], v[150:151]
	s_waitcnt vmcnt(42)
	v_lshlrev_b32_e32 v154, 16, v190
	v_pk_fma_f32 v[96:97], v[96:97], v[96:97], v[150:151]
	v_lshlrev_b32_e32 v150, 16, v82
	v_and_b32_e32 v151, 0xffff0000, v82
	v_and_b32_e32 v155, 0xffff0000, v190
	v_pk_add_f32 v[184:185], v[150:151], v[154:155]
	v_lshlrev_b32_e32 v82, 16, v83
	v_and_b32_e32 v83, 0xffff0000, v83
	v_lshlrev_b32_e32 v150, 16, v191
	v_and_b32_e32 v151, 0xffff0000, v191
	v_lshlrev_b32_e32 v154, 16, v72
	v_and_b32_e32 v155, 0xffff0000, v72
	s_waitcnt vmcnt(41)
	v_lshlrev_b32_e32 v158, 16, v186
	v_and_b32_e32 v159, 0xffff0000, v186
	v_pk_add_f32 v[188:189], v[82:83], v[150:151]
	v_pk_add_f32 v[190:191], v[154:155], v[158:159]
	v_lshlrev_b32_e32 v72, 16, v73
	v_and_b32_e32 v73, 0xffff0000, v73
	v_lshlrev_b32_e32 v154, 16, v187
	v_and_b32_e32 v155, 0xffff0000, v187
	v_mul_f32_e32 v82, v185, v185
	v_mul_f32_e32 v150, v189, v189
	v_pk_add_f32 v[186:187], v[72:73], v[154:155]
	v_pk_add_f32 v[106:107], v[106:107], v[106:107] op_sel:[0,1] op_sel_hi:[1,0]
	v_pk_add_f32 v[96:97], v[96:97], v[96:97] op_sel:[0,1] op_sel_hi:[1,0]
	v_pk_fma_f32 v[82:83], v[184:185], v[184:185], v[82:83] op_sel_hi:[1,1,0]
	v_pk_fma_f32 v[150:151], v[188:189], v[188:189], v[150:151] op_sel_hi:[1,1,0]
	v_pk_mul_f32 v[72:73], v[190:191], v[190:191]
	v_pk_mul_f32 v[154:155], v[186:187], v[186:187]
	v_mov_b32_e32 v107, v72
	v_mov_b32_e32 v97, v73
	v_mov_b32_e32 v83, v154
	v_mov_b32_e32 v151, v155
	v_pk_add_f32 v[72:73], v[106:107], v[96:97]
	v_pk_add_f32 v[82:83], v[82:83], v[150:151]
	global_store_dwordx2 v[48:49], v[52:53], off offset:2560 nt
	v_pk_add_f32 v[72:73], v[72:73], v[82:83]
	v_lshlrev_b32_e32 v52, 16, v98
	v_add_f32_e32 v72, v72, v73
	v_and_b32_e32 v53, 0xffff0000, v98
	v_pk_mul_f32 v[68:69], v[26:27], v[68:69]
	v_add_f32_dpp v72, v72, v72 quad_perm:[1,0,3,2] row_mask:0xf bank_mask:0xf bound_ctrl:1
	v_pk_mul_f32 v[52:53], v[68:69], v[52:53]
	v_pk_mul_f32 v[42:43], v[30:31], v[42:43]
	v_add_f32_dpp v72, v72, v72 quad_perm:[2,3,0,1] row_mask:0xf bank_mask:0xf bound_ctrl:1
	v_cvt_pk_bf16_f32 v52, v52, v53
	v_cvt_pk_bf16_f32 v53, v58, v59
	v_add_f32_dpp v72, v72, v72 row_half_mirror row_mask:0xf bank_mask:0xf bound_ctrl:1
	global_store_dwordx2 v[48:49], v[52:53], off offset:3072 nt
	v_lshlrev_b32_e32 v52, 16, v74
	v_add_f32_dpp v72, v72, v72 row_mirror row_mask:0xf bank_mask:0xf bound_ctrl:1
	v_and_b32_e32 v53, 0xffff0000, v74
	v_readlane_b32 s8, v72, 16
	v_readlane_b32 s9, v72, 48
	v_readlane_b32 s6, v72, 0
	v_readlane_b32 s7, v72, 32
	v_mov_b32_e32 v72, s8
	v_mov_b32_e32 v73, s9
	v_pk_add_f32 v[72:73], s[6:7], v[72:73]
	v_lshlrev_b32_e32 v58, 16, v75
	v_add_f32_e32 v72, v72, v73
	v_fmamk_f32 v72, v72, 0x3a000000, v252
	v_and_b32_e32 v59, 0xffff0000, v75
	v_pk_mul_f32 v[64:65], v[32:33], v[64:65]
	v_mul_f32_e32 v73, 0x4f800000, v72
	v_cmp_gt_f32_e32 vcc, s55, v72
	v_pk_mul_f32 v[58:59], v[64:65], v[58:59]
	v_pk_mul_f32 v[42:43], v[42:43], v[52:53]
	v_cndmask_b32_e32 v72, v72, v73, vcc
	v_cvt_pk_bf16_f32 v42, v42, v43
	v_cvt_pk_bf16_f32 v43, v58, v59
	v_sqrt_f32_e32 v73, v72
	global_store_dwordx2 v[48:49], v[42:43], off offset:3584 nt
	v_lshl_add_u64 v[42:43], v[36:37], 0, s[12:13]
	v_lshl_add_u64 v[68:69], v[42:43], 0, v[0:1]
	v_lshl_add_u64 v[42:43], v[38:39], 0, s[12:13]
	v_lshl_add_u64 v[80:81], v[42:43], 0, v[0:1]
; #define GAS __attribute__((address_space(1)))
; #define LAS __attribute__((address_space(3)))
; template <bool HG>
; __device__ __forceinline__ void readout_phase2(const Args& a, Frame& F, const float* gain, int nrows) {
;     ...
;     RO_LOAD(f0, b0, g0, nw); RO_LOAD(f1, b1, g1, nw + 2048); RO_LOAD(f2, b2, g2, nw + 2 * 2048);
;     if (HG) { for (int q = F.tid; q < D / 4; q += NWAVES * 64) ((LAS f32x4*)GL)[q] = ((const GAS f32x4*)gain)[q];
;               asm volatile("s_waitcnt lgkmcnt(0)" ::: "memory"); __builtin_amdgcn_s_barrier(); asm volatile("" ::: "memory"); }
;     RO_FINISH(f0, b0, g0, nw);            RO_LOAD(f0, b0, g0, nw + 3 * 2048);
;     RO_FINISH(f1, b1, g1, nw + 2048);     RO_LOAD(f1, b1, g1, nw + 4 * 2048);
;     RO_FINISH(f2, b2, g2, nw + 2 * 2048); RO_LOAD(f2, b2, g2, nw + 5 * 2048);
;     RO_FINISH(f0, b0, g0, nw + 3 * 2048); RO_LOAD(f0, b0, g0, nw + 6 * 2048);
;     RO_FINISH(f1, b1, g1, nw + 4 * 2048); RO_LOAD(f1, b1, g1, nw + 7 * 2048);
	v_lshl_add_u64 v[42:43], v[40:41], 0, s[12:13]
	v_lshl_add_u64 v[64:65], v[42:43], 0, v[0:1]
	global_load_dwordx2 v[140:141], v[68:69], off nt
	global_load_dwordx2 v[126:127], v[68:69], off offset:512 nt
	global_load_dwordx2 v[108:109], v[68:69], off offset:1024 nt
	global_load_dwordx2 v[98:99], v[68:69], off offset:1536 nt
	global_load_dwordx2 v[148:149], v[80:81], off nt
	global_load_dwordx2 v[132:133], v[80:81], off offset:512 nt
	global_load_dwordx2 v[124:125], v[80:81], off offset:1024 nt
	global_load_dwordx2 v[100:101], v[80:81], off offset:1536 nt
	global_load_dwordx2 v[58:59], v[64:65], off nt
	global_load_dwordx2 v[52:53], v[64:65], off offset:512 nt
	global_load_dwordx2 v[48:49], v[64:65], off offset:1024 nt
	global_load_dwordx2 v[42:43], v[64:65], off offset:1536 nt
	global_load_dwordx2 v[90:91], v[68:69], off offset:2048 nt
	global_load_dwordx2 v[76:77], v[68:69], off offset:2560 nt
	global_load_dwordx2 v[74:75], v[68:69], off offset:3072 nt
	s_nop 0
	global_load_dwordx2 v[68:69], v[68:69], off offset:3584 nt
	s_nop 0
	global_load_dwordx2 v[162:163], v[80:81], off offset:2048 nt
	global_load_dwordx2 v[158:159], v[80:81], off offset:2560 nt
	global_load_dwordx2 v[154:155], v[80:81], off offset:3072 nt
	global_load_dwordx2 v[150:151], v[80:81], off offset:3584 nt
	v_add_u32_e32 v80, -1, v73
	v_fma_f32 v81, -v80, v73, v72
	v_cmp_ge_f32_e64 s[8:9], 0, v81
	v_add_u32_e32 v81, 1, v73
	s_nop 0
	v_cndmask_b32_e64 v80, v73, v80, s[8:9]
	v_fma_f32 v73, -v81, v73, v72
	v_cmp_lt_f32_e64 s[8:9], 0, v73
	s_nop 1
	v_cndmask_b32_e64 v73, v80, v81, s[8:9]
	v_mul_f32_e32 v80, 0x37800000, v73
	v_cndmask_b32_e32 v73, v73, v80, vcc
	v_cmp_class_f32_e32 vcc, v72, v253
	s_nop 1
	v_cndmask_b32_e32 v80, v73, v72, vcc
	v_div_scale_f32 v81, s[6:7], v80, v80, 1.0
	v_rcp_f32_e32 v192, v81
	global_load_dwordx2 v[106:107], v[64:65], off offset:2048 nt
	global_load_dwordx2 v[96:97], v[64:65], off offset:2560 nt
	global_load_dwordx2 v[82:83], v[64:65], off offset:3072 nt
	global_load_dwordx2 v[72:73], v[64:65], off offset:3584 nt
	v_fma_f32 v64, -v81, v192, 1.0
	v_fmac_f32_e32 v192, v64, v192
	v_div_scale_f32 v64, vcc, 1.0, v80, 1.0
	v_mul_f32_e32 v65, v64, v192
	v_fma_f32 v193, -v81, v65, v64
	v_fmac_f32_e32 v65, v193, v192
	v_fma_f32 v64, -v81, v65, v64
	v_div_fmas_f32 v64, v64, v192, v65
	v_div_fixup_f32 v64, v64, v80, 1.0
	v_pk_mul_f32 v[170:171], v[170:171], v[64:65] op_sel_hi:[1,0]
	v_pk_mul_f32 v[174:175], v[174:175], v[64:65] op_sel_hi:[1,0]
	v_lshlrev_b32_e32 v192, 16, v66
	v_and_b32_e32 v193, 0xffff0000, v66
	v_lshlrev_b32_e32 v66, 16, v67
	v_and_b32_e32 v67, 0xffff0000, v67
	v_pk_mul_f32 v[174:175], v[2:3], v[174:175]
	v_pk_mul_f32 v[170:171], v[4:5], v[170:171]
	v_pk_mul_f32 v[144:145], v[144:145], v[64:65] op_sel_hi:[1,0]
	v_pk_mul_f32 v[66:67], v[170:171], v[66:67]
	v_pk_mul_f32 v[170:171], v[174:175], v[192:193]
	v_pk_mul_f32 v[168:169], v[168:169], v[64:65] op_sel_hi:[1,0]
	v_cvt_pk_bf16_f32 v170, v170, v171
	v_cvt_pk_bf16_f32 v171, v66, v67
	v_lshlrev_b32_e32 v66, 16, v60
	v_and_b32_e32 v67, 0xffff0000, v60
	v_lshlrev_b32_e32 v60, 16, v61
	v_and_b32_e32 v61, 0xffff0000, v61
	v_pk_mul_f32 v[168:169], v[6:7], v[168:169]
	v_pk_mul_f32 v[144:145], v[8:9], v[144:145]
	v_lshl_add_u64 v[80:81], v[34:35], 0, s[18:19]
	v_pk_mul_f32 v[60:61], v[144:145], v[60:61]
	v_pk_mul_f32 v[66:67], v[168:169], v[66:67]
	v_lshl_add_u64 v[80:81], v[80:81], 0, v[0:1]
	v_cvt_pk_bf16_f32 v66, v66, v67
	v_cvt_pk_bf16_f32 v67, v60, v61
	global_store_dwordx2 v[80:81], v[66:67], off offset:512 nt
	v_pk_mul_f32 v[66:67], v[142:143], v[64:65] op_sel_hi:[1,0]
	v_pk_mul_f32 v[142:143], v[146:147], v[64:65] op_sel_hi:[1,0]
	v_lshlrev_b32_e32 v60, 16, v54
	v_and_b32_e32 v61, 0xffff0000, v54
	v_lshlrev_b32_e32 v54, 16, v55
	v_and_b32_e32 v55, 0xffff0000, v55
	v_pk_mul_f32 v[142:143], v[10:11], v[142:143]
	v_pk_mul_f32 v[66:67], v[12:13], v[66:67]
	v_pk_mul_f32 v[60:61], v[142:143], v[60:61]
	v_pk_mul_f32 v[54:55], v[66:67], v[54:55]
	v_pk_mul_f32 v[66:67], v[138:139], v[64:65] op_sel_hi:[1,0]
	v_cvt_pk_bf16_f32 v60, v60, v61
	v_cvt_pk_bf16_f32 v61, v54, v55
	v_lshlrev_b32_e32 v54, 16, v46
	v_and_b32_e32 v55, 0xffff0000, v46
	v_pk_mul_f32 v[66:67], v[14:15], v[66:67]
	s_waitcnt vmcnt(56)
	v_lshlrev_b32_e32 v174, 16, v166
	v_pk_mul_f32 v[54:55], v[66:67], v[54:55]
	v_pk_mul_f32 v[66:67], v[176:177], v[64:65] op_sel_hi:[1,0]
	v_and_b32_e32 v175, 0xffff0000, v166
	s_waitcnt vmcnt(52)
	v_lshlrev_b32_e32 v176, 16, v172
	v_and_b32_e32 v177, 0xffff0000, v172
	v_lshlrev_b32_e32 v166, 16, v167
	v_and_b32_e32 v167, 0xffff0000, v167
	v_lshlrev_b32_e32 v172, 16, v173
	v_and_b32_e32 v173, 0xffff0000, v173
	v_pk_add_f32 v[174:175], v[174:175], v[176:177]
	v_pk_add_f32 v[172:173], v[166:167], v[172:173]
	v_lshlrev_b32_e32 v166, 16, v134
	v_and_b32_e32 v167, 0xffff0000, v134
	s_waitcnt vmcnt(51)
	v_lshlrev_b32_e32 v176, 16, v136
	v_and_b32_e32 v177, 0xffff0000, v136
	global_store_dwordx2 v[80:81], v[60:61], off offset:1024 nt
	v_pk_mul_f32 v[60:61], v[118:119], v[64:65] op_sel_hi:[1,0]
	v_pk_add_f32 v[166:167], v[166:167], v[176:177]
	v_lshlrev_b32_e32 v134, 16, v135
	v_and_b32_e32 v135, 0xffff0000, v135
	v_lshlrev_b32_e32 v136, 16, v137
	v_and_b32_e32 v137, 0xffff0000, v137
	v_lshlrev_b32_e32 v46, 16, v47
	v_and_b32_e32 v47, 0xffff0000, v47
	v_pk_mul_f32 v[60:61], v[16:17], v[60:61]
	v_pk_add_f32 v[134:135], v[134:135], v[136:137]
	v_mov_b32_e32 v176, v175
	v_mov_b32_e32 v177, v167
	v_pk_mul_f32 v[46:47], v[60:61], v[46:47]
	v_pk_mul_f32 v[60:61], v[178:179], v[64:65] op_sel_hi:[1,0]
	v_mov_b32_e32 v136, v174
	v_mov_b32_e32 v137, v166
	v_pk_mul_f32 v[176:177], v[176:177], v[176:177]
	v_mov_b32_e32 v178, v173
	v_mov_b32_e32 v179, v135
	v_pk_fma_f32 v[136:137], v[136:137], v[136:137], v[176:177]
	v_mov_b32_e32 v176, v172
	v_mov_b32_e32 v177, v134
	v_pk_mul_f32 v[178:179], v[178:179], v[178:179]
	v_cvt_pk_bf16_f32 v54, v54, v55
	v_cvt_pk_bf16_f32 v55, v46, v47
	v_pk_fma_f32 v[176:177], v[176:177], v[176:177], v[178:179]
	global_store_dwordx2 v[80:81], v[54:55], off offset:1536 nt
	v_lshlrev_b32_e32 v46, 16, v122
	v_and_b32_e32 v47, 0xffff0000, v122
	v_lshlrev_b32_e32 v54, 16, v123
	v_and_b32_e32 v55, 0xffff0000, v123
	v_pk_mul_f32 v[66:67], v[18:19], v[66:67]
	v_pk_mul_f32 v[60:61], v[20:21], v[60:61]
	v_pk_add_f32 v[136:137], v[136:137], v[176:177]
	v_lshlrev_b32_e32 v176, 16, v128
	v_and_b32_e32 v177, 0xffff0000, v128
	s_waitcnt vmcnt(52)
; #define GAS __attribute__((address_space(1)))
; #define LAS __attribute__((address_space(3)))
; template <bool HG>
; __device__ __forceinline__ void readout_phase2(const Args& a, Frame& F, const float* gain, int nrows) {
;     ...
;     RO_LOAD(f0, b0, g0, nw); RO_LOAD(f1, b1, g1, nw + 2048); RO_LOAD(f2, b2, g2, nw + 2 * 2048);
;     if (HG) { for (int q = F.tid; q < D / 4; q += NWAVES * 64) ((LAS f32x4*)GL)[q] = ((const GAS f32x4*)gain)[q];
;               asm volatile("s_waitcnt lgkmcnt(0)" ::: "memory"); __builtin_amdgcn_s_barrier(); asm volatile("" ::: "memory"); }
;     RO_FINISH(f0, b0, g0, nw);            RO_LOAD(f0, b0, g0, nw + 3 * 2048);
;     RO_FINISH(f1, b1, g1, nw + 2048);     RO_LOAD(f1, b1, g1, nw + 4 * 2048);
;     RO_FINISH(f2, b2, g2, nw + 2 * 2048); RO_LOAD(f2, b2, g2, nw + 5 * 2048);
;     RO_FINISH(f0, b0, g0, nw + 3 * 2048); RO_LOAD(f0, b0, g0, nw + 6 * 2048);
;     RO_FINISH(f1, b1, g1, nw + 4 * 2048); RO_LOAD(f1, b1, g1, nw + 7 * 2048);
;     RO_FINISH(f2, b2, g2, nw + 5 * 2048);
	v_lshlrev_b32_e32 v178, 16, v130
	v_and_b32_e32 v179, 0xffff0000, v130
	v_lshlrev_b32_e32 v128, 16, v129
	v_and_b32_e32 v129, 0xffff0000, v129
	v_lshlrev_b32_e32 v130, 16, v131
	v_and_b32_e32 v131, 0xffff0000, v131
	v_pk_mul_f32 v[54:55], v[60:61], v[54:55]
	v_pk_mul_f32 v[46:47], v[66:67], v[46:47]
	v_pk_add_f32 v[176:177], v[176:177], v[178:179]
	v_pk_add_f32 v[130:131], v[128:129], v[130:131]
	v_cvt_pk_bf16_f32 v46, v46, v47
	v_cvt_pk_bf16_f32 v47, v54, v55
	v_pk_mul_f32 v[60:61], v[180:181], v[64:65] op_sel_hi:[1,0]
	v_pk_mul_f32 v[66:67], v[120:121], v[64:65] op_sel_hi:[1,0]
	v_mov_b32_e32 v178, v177
	v_mov_b32_e32 v179, v131
	global_store_dwordx2 v[80:81], v[46:47], off offset:2048 nt
	v_lshlrev_b32_e32 v46, 16, v110
	v_and_b32_e32 v47, 0xffff0000, v110
	v_lshlrev_b32_e32 v54, 16, v111
	v_and_b32_e32 v55, 0xffff0000, v111
	v_pk_mul_f32 v[66:67], v[22:23], v[66:67]
	v_pk_mul_f32 v[60:61], v[24:25], v[60:61]
	v_mov_b32_e32 v128, v176
	v_mov_b32_e32 v129, v130
	v_pk_mul_f32 v[178:179], v[178:179], v[178:179]
	v_pk_mul_f32 v[54:55], v[60:61], v[54:55]
	v_pk_mul_f32 v[46:47], v[66:67], v[46:47]
	v_pk_mul_f32 v[60:61], v[188:189], v[64:65] op_sel_hi:[1,0]
	v_pk_fma_f32 v[128:129], v[128:129], v[128:129], v[178:179]
	v_cvt_pk_bf16_f32 v46, v46, v47
	v_cvt_pk_bf16_f32 v47, v54, v55
	v_lshlrev_b32_e32 v54, 16, v95
	v_and_b32_e32 v55, 0xffff0000, v95
	v_pk_mul_f32 v[60:61], v[28:29], v[60:61]
	v_pk_add_f32 v[178:179], v[128:129], v[128:129] op_sel:[0,1] op_sel_hi:[1,0]
	v_lshlrev_b32_e32 v128, 16, v112
	v_and_b32_e32 v129, 0xffff0000, v112
	s_waitcnt vmcnt(52)
	v_lshlrev_b32_e32 v180, 16, v114
	v_and_b32_e32 v181, 0xffff0000, v114
	v_lshlrev_b32_e32 v112, 16, v113
	v_and_b32_e32 v113, 0xffff0000, v113
	v_lshlrev_b32_e32 v114, 16, v115
	v_and_b32_e32 v115, 0xffff0000, v115
	v_pk_mul_f32 v[66:67], v[184:185], v[64:65] op_sel_hi:[1,0]
	v_pk_mul_f32 v[54:55], v[60:61], v[54:55]
	v_pk_mul_f32 v[60:61], v[186:187], v[64:65] op_sel_hi:[1,0]
	v_pk_add_f32 v[128:129], v[128:129], v[180:181]
	v_pk_add_f32 v[112:113], v[112:113], v[114:115]
	s_waitcnt vmcnt(47)
	v_lshlrev_b32_e32 v184, 16, v102
	v_and_b32_e32 v185, 0xffff0000, v102
	s_waitcnt vmcnt(43)
	v_lshlrev_b32_e32 v186, 16, v164
	v_and_b32_e32 v187, 0xffff0000, v164
	v_lshlrev_b32_e32 v102, 16, v103
	v_and_b32_e32 v103, 0xffff0000, v103
	v_lshlrev_b32_e32 v164, 16, v165
	v_and_b32_e32 v165, 0xffff0000, v165
	v_mul_f32_e32 v114, v129, v129
	v_mul_f32_e32 v180, v113, v113
	v_pk_add_f32 v[184:185], v[184:185], v[186:187]
	v_pk_add_f32 v[164:165], v[102:103], v[164:165]
	v_pk_add_f32 v[136:137], v[136:137], v[136:137] op_sel:[0,1] op_sel_hi:[1,0]
	v_pk_fma_f32 v[114:115], v[128:129], v[128:129], v[114:115] op_sel_hi:[1,1,0]
	v_pk_fma_f32 v[180:181], v[112:113], v[112:113], v[180:181] op_sel_hi:[1,1,0]
	v_pk_mul_f32 v[102:103], v[184:185], v[184:185]
	v_pk_mul_f32 v[186:187], v[164:165], v[164:165]
	v_mov_b32_e32 v137, v102
	v_mov_b32_e32 v179, v103
	v_mov_b32_e32 v115, v186
	v_mov_b32_e32 v181, v187
	v_pk_add_f32 v[102:103], v[136:137], v[178:179]
	v_pk_add_f32 v[114:115], v[114:115], v[180:181]
	s_waitcnt vmcnt(42)
	v_lshlrev_b32_e32 v136, 16, v160
	v_pk_add_f32 v[102:103], v[102:103], v[114:115]
	v_lshlrev_b32_e32 v114, 16, v84
	v_and_b32_e32 v115, 0xffff0000, v84
	v_and_b32_e32 v137, 0xffff0000, v160
	v_pk_add_f32 v[114:115], v[114:115], v[136:137]
	v_lshlrev_b32_e32 v84, 16, v85
	v_and_b32_e32 v85, 0xffff0000, v85
	v_lshlrev_b32_e32 v136, 16, v161
	v_and_b32_e32 v137, 0xffff0000, v161
	v_pk_add_f32 v[178:179], v[84:85], v[136:137]
	v_mov_b32_e32 v136, v115
	v_mov_b32_e32 v137, v179
	v_mov_b32_e32 v84, v114
	v_mov_b32_e32 v85, v178
	v_pk_mul_f32 v[136:137], v[136:137], v[136:137]
	s_waitcnt vmcnt(41)
	v_lshlrev_b32_e32 v160, 16, v156
	v_pk_fma_f32 v[84:85], v[84:85], v[84:85], v[136:137]
	v_lshlrev_b32_e32 v136, 16, v78
	v_and_b32_e32 v137, 0xffff0000, v78
	v_and_b32_e32 v161, 0xffff0000, v156
	v_pk_add_f32 v[180:181], v[136:137], v[160:161]
	v_lshlrev_b32_e32 v78, 16, v79
	v_and_b32_e32 v79, 0xffff0000, v79
	v_lshlrev_b32_e32 v136, 16, v157
	v_and_b32_e32 v137, 0xffff0000, v157
	v_pk_add_f32 v[186:187], v[78:79], v[136:137]
	v_lshlrev_b32_e32 v156, 16, v70
	v_and_b32_e32 v157, 0xffff0000, v70
	s_waitcnt vmcnt(40)
; #define GAS __attribute__((address_space(1)))
; #define LAS __attribute__((address_space(3)))
; template <bool HG>
; __device__ __forceinline__ void readout_phase2(const Args& a, Frame& F, const float* gain, int nrows) {
;     ...
;     RO_LOAD(f0, b0, g0, nw); RO_LOAD(f1, b1, g1, nw + 2048); RO_LOAD(f2, b2, g2, nw + 2 * 2048);
;     if (HG) { for (int q = F.tid; q < D / 4; q += NWAVES * 64) ((LAS f32x4*)GL)[q] = ((const GAS f32x4*)gain)[q];
;               asm volatile("s_waitcnt lgkmcnt(0)" ::: "memory"); __builtin_amdgcn_s_barrier(); asm volatile("" ::: "memory"); }
;     RO_FINISH(f0, b0, g0, nw);            RO_LOAD(f0, b0, g0, nw + 3 * 2048);
;     RO_FINISH(f1, b1, g1, nw + 2048);     RO_LOAD(f1, b1, g1, nw + 4 * 2048);
;     RO_FINISH(f2, b2, g2, nw + 2 * 2048); RO_LOAD(f2, b2, g2, nw + 5 * 2048);
;     RO_FINISH(f0, b0, g0, nw + 3 * 2048); RO_LOAD(f0, b0, g0, nw + 6 * 2048);
;     RO_FINISH(f1, b1, g1, nw + 4 * 2048); RO_LOAD(f1, b1, g1, nw + 7 * 2048);
;     RO_FINISH(f2, b2, g2, nw + 5 * 2048);
;     const bool cx = ML + nw < nrows;
	v_lshlrev_b32_e32 v160, 16, v152
	v_and_b32_e32 v161, 0xffff0000, v152
	v_lshlrev_b32_e32 v70, 16, v71
	v_and_b32_e32 v71, 0xffff0000, v71
	v_lshlrev_b32_e32 v152, 16, v153
	v_and_b32_e32 v153, 0xffff0000, v153
	v_pk_mul_f32 v[64:65], v[190:191], v[64:65] op_sel_hi:[1,0]
	v_mul_f32_e32 v78, v181, v181
	v_mul_f32_e32 v136, v187, v187
	v_pk_add_f32 v[188:189], v[156:157], v[160:161]
	v_pk_add_f32 v[190:191], v[70:71], v[152:153]
	v_pk_add_f32 v[102:103], v[102:103], v[102:103] op_sel:[0,1] op_sel_hi:[1,0]
	v_pk_add_f32 v[84:85], v[84:85], v[84:85] op_sel:[0,1] op_sel_hi:[1,0]
	v_pk_fma_f32 v[78:79], v[180:181], v[180:181], v[78:79] op_sel_hi:[1,1,0]
	v_pk_fma_f32 v[136:137], v[186:187], v[186:187], v[136:137] op_sel_hi:[1,1,0]
	v_pk_mul_f32 v[70:71], v[188:189], v[188:189]
	v_pk_mul_f32 v[152:153], v[190:191], v[190:191]
	v_mov_b32_e32 v103, v70
	v_mov_b32_e32 v85, v71
	v_mov_b32_e32 v79, v152
	v_mov_b32_e32 v137, v153
	v_pk_add_f32 v[70:71], v[102:103], v[84:85]
	v_pk_add_f32 v[78:79], v[78:79], v[136:137]
	global_store_dwordx2 v[80:81], v[46:47], off offset:2560 nt
	v_pk_add_f32 v[70:71], v[70:71], v[78:79]
	v_lshlrev_b32_e32 v46, 16, v94
	v_add_f32_e32 v70, v70, v71
	v_and_b32_e32 v47, 0xffff0000, v94
	v_pk_mul_f32 v[66:67], v[26:27], v[66:67]
	v_add_f32_dpp v70, v70, v70 quad_perm:[1,0,3,2] row_mask:0xf bank_mask:0xf bound_ctrl:1
	v_pk_mul_f32 v[46:47], v[66:67], v[46:47]
	v_pk_mul_f32 v[64:65], v[30:31], v[64:65]
	v_add_f32_dpp v70, v70, v70 quad_perm:[2,3,0,1] row_mask:0xf bank_mask:0xf bound_ctrl:1
	v_cvt_pk_bf16_f32 v46, v46, v47
	v_cvt_pk_bf16_f32 v47, v54, v55
	v_add_f32_dpp v70, v70, v70 row_half_mirror row_mask:0xf bank_mask:0xf bound_ctrl:1
	global_store_dwordx2 v[80:81], v[46:47], off offset:3072 nt
	v_lshlrev_b32_e32 v46, 16, v88
	v_add_f32_dpp v70, v70, v70 row_mirror row_mask:0xf bank_mask:0xf bound_ctrl:1
	v_and_b32_e32 v47, 0xffff0000, v88
	v_readlane_b32 s8, v70, 16
	v_readlane_b32 s9, v70, 48
	v_readlane_b32 s6, v70, 0
	v_readlane_b32 s7, v70, 32
	v_mov_b32_e32 v70, s8
	v_mov_b32_e32 v71, s9
	v_pk_add_f32 v[70:71], s[6:7], v[70:71]
	v_lshlrev_b32_e32 v54, 16, v89
	v_add_f32_e32 v70, v70, v71
	v_fmamk_f32 v70, v70, 0x3a000000, v252
	v_mul_f32_e32 v71, 0x4f800000, v70
	v_cmp_gt_f32_e32 vcc, s55, v70
	v_and_b32_e32 v55, 0xffff0000, v89
	v_pk_mul_f32 v[60:61], v[32:33], v[60:61]
	v_cndmask_b32_e32 v70, v70, v71, vcc
	v_sqrt_f32_e32 v71, v70
	s_add_i32 s18, s10, 0x3800
	v_pk_mul_f32 v[54:55], v[60:61], v[54:55]
	v_pk_mul_f32 v[46:47], v[64:65], v[46:47]
	v_add_u32_e32 v78, -1, v71
	v_fma_f32 v79, -v78, v71, v70
	v_cmp_ge_f32_e64 s[8:9], 0, v79
	v_add_u32_e32 v79, 1, v71
	s_ashr_i32 s19, s18, 31
	v_cndmask_b32_e64 v78, v71, v78, s[8:9]
	v_fma_f32 v71, -v79, v71, v70
	v_cvt_pk_bf16_f32 v46, v46, v47
	v_cvt_pk_bf16_f32 v47, v54, v55
	s_lshl_b64 s[16:17], s[18:19], 12
	v_cmp_lt_f32_e64 s[8:9], 0, v71
	global_store_dwordx2 v[80:81], v[46:47], off offset:3584 nt
	v_lshl_add_u64 v[46:47], v[36:37], 0, s[16:17]
	v_cndmask_b32_e64 v71, v78, v79, s[8:9]
	v_lshl_add_u64 v[66:67], v[46:47], 0, v[0:1]
	v_lshl_add_u64 v[46:47], v[38:39], 0, s[16:17]
	v_mul_f32_e32 v78, 0x37800000, v71
	global_store_dwordx2 v[80:81], v[170:171], off nt
	v_lshl_add_u64 v[170:171], v[46:47], 0, v[0:1]
	v_lshl_add_u64 v[46:47], v[40:41], 0, s[16:17]
	v_cndmask_b32_e32 v71, v71, v78, vcc
	v_cmp_class_f32_e32 vcc, v70, v253
	v_lshl_add_u64 v[168:169], v[46:47], 0, v[0:1]
	global_load_dwordx2 v[144:145], v[66:67], off nt
	global_load_dwordx2 v[138:139], v[66:67], off offset:512 nt
	global_load_dwordx2 v[120:121], v[66:67], off offset:1024 nt
	global_load_dwordx2 v[110:111], v[66:67], off offset:1536 nt
	global_load_dwordx2 v[146:147], v[170:171], off nt
	global_load_dwordx2 v[142:143], v[170:171], off offset:512 nt
	global_load_dwordx2 v[122:123], v[170:171], off offset:1024 nt
	global_load_dwordx2 v[118:119], v[170:171], off offset:1536 nt
	global_load_dwordx2 v[64:65], v[168:169], off nt
	global_load_dwordx2 v[60:61], v[168:169], off offset:512 nt
	global_load_dwordx2 v[54:55], v[168:169], off offset:1024 nt
	global_load_dwordx2 v[46:47], v[168:169], off offset:1536 nt
	global_load_dwordx2 v[94:95], v[66:67], off offset:2048 nt
	global_load_dwordx2 v[88:89], v[66:67], off offset:2560 nt
	global_load_dwordx2 v[80:81], v[66:67], off offset:3072 nt
	s_nop 0
	global_load_dwordx2 v[66:67], v[66:67], off offset:3584 nt
	s_nop 0
	global_load_dwordx2 v[160:161], v[170:171], off offset:2048 nt
	global_load_dwordx2 v[156:157], v[170:171], off offset:2560 nt
	global_load_dwordx2 v[152:153], v[170:171], off offset:3072 nt
	global_load_dwordx2 v[136:137], v[170:171], off offset:3584 nt
	v_cndmask_b32_e32 v170, v71, v70, vcc
	v_div_scale_f32 v171, s[6:7], v170, v170, 1.0
	v_rcp_f32_e32 v192, v171
	global_load_dwordx2 v[102:103], v[168:169], off offset:2048 nt
	global_load_dwordx2 v[84:85], v[168:169], off offset:2560 nt
	global_load_dwordx2 v[78:79], v[168:169], off offset:3072 nt
	global_load_dwordx2 v[70:71], v[168:169], off offset:3584 nt
	s_addk_i32 s10, 0x4000
	s_cmp_lt_i32 s10, s47
	v_fma_f32 v168, -v171, v192, 1.0
	v_fmac_f32_e32 v192, v168, v192
	v_div_scale_f32 v168, vcc, 1.0, v170, 1.0
	v_mul_f32_e32 v169, v168, v192
	v_fma_f32 v193, -v171, v169, v168
	v_fmac_f32_e32 v169, v193, v192
	v_fma_f32 v168, -v171, v169, v168
	v_div_fmas_f32 v168, v168, v192, v169
	v_div_fixup_f32 v168, v168, v170, 1.0
	v_pk_mul_f32 v[172:173], v[172:173], v[168:169] op_sel_hi:[1,0]
	v_pk_mul_f32 v[174:175], v[174:175], v[168:169] op_sel_hi:[1,0]
	v_lshlrev_b32_e32 v192, 16, v62
	v_and_b32_e32 v193, 0xffff0000, v62
	v_lshlrev_b32_e32 v62, 16, v63
	v_and_b32_e32 v63, 0xffff0000, v63
; #define GAS __attribute__((address_space(1)))
; #define LAS __attribute__((address_space(3)))
; template <bool HG>
; __device__ __forceinline__ void readout_phase2(const Args& a, Frame& F, const float* gain, int nrows) {
;     ...
;     RO_LOAD(f0, b0, g0, nw); RO_LOAD(f1, b1, g1, nw + 2048); RO_LOAD(f2, b2, g2, nw + 2 * 2048);
;     if (HG) { for (int q = F.tid; q < D / 4; q += NWAVES * 64) ((LAS f32x4*)GL)[q] = ((const GAS f32x4*)gain)[q];
;               asm volatile("s_waitcnt lgkmcnt(0)" ::: "memory"); __builtin_amdgcn_s_barrier(); asm volatile("" ::: "memory"); }
;     RO_FINISH(f0, b0, g0, nw);            RO_LOAD(f0, b0, g0, nw + 3 * 2048);
;     RO_FINISH(f1, b1, g1, nw + 2048);     RO_LOAD(f1, b1, g1, nw + 4 * 2048);
;     RO_FINISH(f2, b2, g2, nw + 2 * 2048); RO_LOAD(f2, b2, g2, nw + 5 * 2048);
;     RO_FINISH(f0, b0, g0, nw + 3 * 2048); RO_LOAD(f0, b0, g0, nw + 6 * 2048);
;     RO_FINISH(f1, b1, g1, nw + 4 * 2048); RO_LOAD(f1, b1, g1, nw + 7 * 2048);
;     RO_FINISH(f2, b2, g2, nw + 5 * 2048);
;     const bool cx = ML + nw < nrows;
;     RO_LOAD(f2, b2, g2, cx ? ML + nw : nw + 7 * 2048);
;     RO_FINISH(f0, b0, g0, nw + 6 * 2048);
	v_pk_mul_f32 v[174:175], v[2:3], v[174:175]
	v_pk_mul_f32 v[172:173], v[4:5], v[172:173]
	v_pk_mul_f32 v[134:135], v[134:135], v[168:169] op_sel_hi:[1,0]
	v_pk_mul_f32 v[62:63], v[172:173], v[62:63]
	v_pk_mul_f32 v[172:173], v[174:175], v[192:193]
	v_pk_mul_f32 v[166:167], v[166:167], v[168:169] op_sel_hi:[1,0]
	v_cvt_pk_bf16_f32 v172, v172, v173
	v_cvt_pk_bf16_f32 v173, v62, v63
	v_lshlrev_b32_e32 v62, 16, v56
	v_and_b32_e32 v63, 0xffff0000, v56
	v_lshlrev_b32_e32 v56, 16, v57
	v_and_b32_e32 v57, 0xffff0000, v57
	v_pk_mul_f32 v[166:167], v[6:7], v[166:167]
	v_pk_mul_f32 v[134:135], v[8:9], v[134:135]
	v_lshl_add_u64 v[170:171], v[34:35], 0, s[14:15]
	v_pk_mul_f32 v[56:57], v[134:135], v[56:57]
	v_pk_mul_f32 v[62:63], v[166:167], v[62:63]
	v_lshl_add_u64 v[170:171], v[170:171], 0, v[0:1]
	v_cvt_pk_bf16_f32 v62, v62, v63
	v_cvt_pk_bf16_f32 v63, v56, v57
	global_store_dwordx2 v[170:171], v[62:63], off offset:512 nt
	v_pk_mul_f32 v[62:63], v[130:131], v[168:169] op_sel_hi:[1,0]
	v_pk_mul_f32 v[130:131], v[176:177], v[168:169] op_sel_hi:[1,0]
	v_lshlrev_b32_e32 v56, 16, v50
	v_and_b32_e32 v57, 0xffff0000, v50
	v_lshlrev_b32_e32 v50, 16, v51
	v_and_b32_e32 v51, 0xffff0000, v51
	v_pk_mul_f32 v[130:131], v[10:11], v[130:131]
	v_pk_mul_f32 v[62:63], v[12:13], v[62:63]
	v_pk_mul_f32 v[56:57], v[130:131], v[56:57]
	v_pk_mul_f32 v[50:51], v[62:63], v[50:51]
	v_cvt_pk_bf16_f32 v56, v56, v57
	v_cvt_pk_bf16_f32 v57, v50, v51
	global_store_dwordx2 v[170:171], v[56:57], off offset:1024 nt
	v_pk_mul_f32 v[56:57], v[112:113], v[168:169] op_sel_hi:[1,0]
	v_pk_mul_f32 v[62:63], v[128:129], v[168:169] op_sel_hi:[1,0]
	v_lshlrev_b32_e32 v50, 16, v44
	v_and_b32_e32 v51, 0xffff0000, v44
	v_lshlrev_b32_e32 v44, 16, v45
	v_and_b32_e32 v45, 0xffff0000, v45
	v_pk_mul_f32 v[62:63], v[14:15], v[62:63]
	v_pk_mul_f32 v[56:57], v[16:17], v[56:57]
	v_pk_mul_f32 v[50:51], v[62:63], v[50:51]
	v_pk_mul_f32 v[44:45], v[56:57], v[44:45]
	v_cvt_pk_bf16_f32 v50, v50, v51
	v_cvt_pk_bf16_f32 v51, v44, v45
	v_pk_mul_f32 v[56:57], v[164:165], v[168:169] op_sel_hi:[1,0]
	v_pk_mul_f32 v[62:63], v[184:185], v[168:169] op_sel_hi:[1,0]
	global_store_dwordx2 v[170:171], v[50:51], off offset:1536 nt
	s_waitcnt vmcnt(62)
	v_lshlrev_b32_e32 v44, 16, v116
	v_and_b32_e32 v45, 0xffff0000, v116
	v_lshlrev_b32_e32 v50, 16, v117
	v_and_b32_e32 v51, 0xffff0000, v117
	v_pk_mul_f32 v[62:63], v[18:19], v[62:63]
	v_pk_mul_f32 v[56:57], v[20:21], v[56:57]
	v_pk_mul_f32 v[44:45], v[62:63], v[44:45]
	v_pk_mul_f32 v[50:51], v[56:57], v[50:51]
	v_cvt_pk_bf16_f32 v44, v44, v45
	v_cvt_pk_bf16_f32 v45, v50, v51
	v_pk_mul_f32 v[56:57], v[178:179], v[168:169] op_sel_hi:[1,0]
	v_pk_mul_f32 v[62:63], v[114:115], v[168:169] op_sel_hi:[1,0]
	global_store_dwordx2 v[170:171], v[44:45], off offset:2048 nt
	v_lshlrev_b32_e32 v44, 16, v104
	v_and_b32_e32 v45, 0xffff0000, v104
	v_lshlrev_b32_e32 v50, 16, v105
	v_and_b32_e32 v51, 0xffff0000, v105
	v_pk_mul_f32 v[62:63], v[22:23], v[62:63]
	v_pk_mul_f32 v[56:57], v[24:25], v[56:57]
	v_pk_mul_f32 v[44:45], v[62:63], v[44:45]
	v_pk_mul_f32 v[50:51], v[56:57], v[50:51]
	v_cvt_pk_bf16_f32 v44, v44, v45
	v_cvt_pk_bf16_f32 v45, v50, v51
	v_pk_mul_f32 v[56:57], v[186:187], v[168:169] op_sel_hi:[1,0]
	v_pk_mul_f32 v[62:63], v[180:181], v[168:169] op_sel_hi:[1,0]
	global_store_dwordx2 v[170:171], v[44:45], off offset:2560 nt
	v_lshlrev_b32_e32 v44, 16, v92
	v_and_b32_e32 v45, 0xffff0000, v92
	v_lshlrev_b32_e32 v50, 16, v93
	v_and_b32_e32 v51, 0xffff0000, v93
	v_pk_mul_f32 v[62:63], v[26:27], v[62:63]
	v_pk_mul_f32 v[56:57], v[28:29], v[56:57]
	v_pk_mul_f32 v[44:45], v[62:63], v[44:45]
	v_pk_mul_f32 v[50:51], v[56:57], v[50:51]
	v_cvt_pk_bf16_f32 v44, v44, v45
	v_cvt_pk_bf16_f32 v45, v50, v51
	v_pk_mul_f32 v[56:57], v[190:191], v[168:169] op_sel_hi:[1,0]
	v_pk_mul_f32 v[62:63], v[188:189], v[168:169] op_sel_hi:[1,0]
	global_store_dwordx2 v[170:171], v[44:45], off offset:3072 nt
	v_lshlrev_b32_e32 v44, 16, v86
	v_and_b32_e32 v45, 0xffff0000, v86
	v_lshlrev_b32_e32 v50, 16, v87
	v_and_b32_e32 v51, 0xffff0000, v87
	v_pk_mul_f32 v[62:63], v[30:31], v[62:63]
	v_pk_mul_f32 v[56:57], v[32:33], v[56:57]
	v_pk_mul_f32 v[44:45], v[62:63], v[44:45]
	v_pk_mul_f32 v[50:51], v[56:57], v[50:51]
	v_cvt_pk_bf16_f32 v44, v44, v45
	v_cvt_pk_bf16_f32 v45, v50, v51
	global_store_dwordx2 v[170:171], v[172:173], off nt
	global_store_dwordx2 v[170:171], v[44:45], off offset:3584 nt
	s_waitcnt vmcnt(62)
	v_lshlrev_b32_e32 v168, 16, v140
	v_and_b32_e32 v169, 0xffff0000, v140
	s_waitcnt vmcnt(59)
	v_lshlrev_b32_e32 v170, 16, v148
	v_and_b32_e32 v171, 0xffff0000, v148
	v_lshlrev_b32_e32 v140, 16, v141
	v_and_b32_e32 v141, 0xffff0000, v141
	v_lshlrev_b32_e32 v148, 16, v149
	v_and_b32_e32 v149, 0xffff0000, v149
	v_pk_add_f32 v[168:169], v[168:169], v[170:171]
	v_pk_add_f32 v[148:149], v[140:141], v[148:149]
	v_lshlrev_b32_e32 v140, 16, v126
	v_and_b32_e32 v141, 0xffff0000, v126
	s_waitcnt vmcnt(58)
	v_lshlrev_b32_e32 v170, 16, v132
	v_and_b32_e32 v171, 0xffff0000, v132
	v_pk_add_f32 v[140:141], v[140:141], v[170:171]
	v_lshlrev_b32_e32 v126, 16, v127
	v_and_b32_e32 v127, 0xffff0000, v127
	v_lshlrev_b32_e32 v132, 16, v133
	v_and_b32_e32 v133, 0xffff0000, v133
	v_pk_add_f32 v[132:133], v[126:127], v[132:133]
	v_mov_b32_e32 v170, v169
	v_mov_b32_e32 v171, v141
	v_mov_b32_e32 v126, v168
	v_mov_b32_e32 v127, v140
	v_pk_mul_f32 v[170:171], v[170:171], v[170:171]
	v_mov_b32_e32 v172, v149
	v_mov_b32_e32 v173, v133
	v_pk_fma_f32 v[126:127], v[126:127], v[126:127], v[170:171]
	v_mov_b32_e32 v170, v148
	v_mov_b32_e32 v171, v132
	v_pk_mul_f32 v[172:173], v[172:173], v[172:173]
	s_waitcnt vmcnt(47)
; #define GAS __attribute__((address_space(1)))
; #define LAS __attribute__((address_space(3)))
; template <bool HG>
; __device__ __forceinline__ void readout_phase2(const Args& a, Frame& F, const float* gain, int nrows) {
;     ...
;     RO_LOAD(f0, b0, g0, nw); RO_LOAD(f1, b1, g1, nw + 2048); RO_LOAD(f2, b2, g2, nw + 2 * 2048);
;     if (HG) { for (int q = F.tid; q < D / 4; q += NWAVES * 64) ((LAS f32x4*)GL)[q] = ((const GAS f32x4*)gain)[q];
;               asm volatile("s_waitcnt lgkmcnt(0)" ::: "memory"); __builtin_amdgcn_s_barrier(); asm volatile("" ::: "memory"); }
;     RO_FINISH(f0, b0, g0, nw);            RO_LOAD(f0, b0, g0, nw + 3 * 2048);
;     RO_FINISH(f1, b1, g1, nw + 2048);     RO_LOAD(f1, b1, g1, nw + 4 * 2048);
;     RO_FINISH(f2, b2, g2, nw + 2 * 2048); RO_LOAD(f2, b2, g2, nw + 5 * 2048);
;     RO_FINISH(f0, b0, g0, nw + 3 * 2048); RO_LOAD(f0, b0, g0, nw + 6 * 2048);
;     RO_FINISH(f1, b1, g1, nw + 4 * 2048); RO_LOAD(f1, b1, g1, nw + 7 * 2048);
;     RO_FINISH(f2, b2, g2, nw + 5 * 2048);
;     const bool cx = ML + nw < nrows;
;     RO_LOAD(f2, b2, g2, cx ? ML + nw : nw + 7 * 2048);
;     RO_FINISH(f0, b0, g0, nw + 6 * 2048);
	v_lshlrev_b32_e32 v178, 16, v162
	v_pk_fma_f32 v[170:171], v[170:171], v[170:171], v[172:173]
	v_lshlrev_b32_e32 v172, 16, v124
	v_pk_add_f32 v[126:127], v[126:127], v[170:171]
	v_lshlrev_b32_e32 v170, 16, v108
	v_and_b32_e32 v171, 0xffff0000, v108
	v_and_b32_e32 v173, 0xffff0000, v124
	v_lshlrev_b32_e32 v108, 16, v109
	v_and_b32_e32 v109, 0xffff0000, v109
	v_lshlrev_b32_e32 v124, 16, v125
	v_and_b32_e32 v125, 0xffff0000, v125
	v_pk_add_f32 v[170:171], v[170:171], v[172:173]
	v_pk_add_f32 v[174:175], v[108:109], v[124:125]
	v_mov_b32_e32 v124, v171
	v_mov_b32_e32 v125, v175
	v_mov_b32_e32 v108, v170
	v_mov_b32_e32 v109, v174
	v_pk_mul_f32 v[124:125], v[124:125], v[124:125]
	v_lshlrev_b32_e32 v172, 16, v100
	v_pk_fma_f32 v[108:109], v[108:109], v[108:109], v[124:125]
	v_lshlrev_b32_e32 v124, 16, v98
	v_and_b32_e32 v125, 0xffff0000, v98
	v_and_b32_e32 v173, 0xffff0000, v100
	v_pk_add_f32 v[172:173], v[124:125], v[172:173]
	v_lshlrev_b32_e32 v98, 16, v99
	v_and_b32_e32 v99, 0xffff0000, v99
	v_lshlrev_b32_e32 v100, 16, v101
	v_and_b32_e32 v101, 0xffff0000, v101
	v_lshlrev_b32_e32 v124, 16, v90
	v_and_b32_e32 v125, 0xffff0000, v90
	v_and_b32_e32 v179, 0xffff0000, v162
	v_pk_add_f32 v[176:177], v[98:99], v[100:101]
	v_pk_add_f32 v[178:179], v[124:125], v[178:179]
	v_lshlrev_b32_e32 v90, 16, v91
	v_and_b32_e32 v91, 0xffff0000, v91
	v_lshlrev_b32_e32 v124, 16, v163
	v_and_b32_e32 v125, 0xffff0000, v163
	v_mul_f32_e32 v98, v173, v173
	v_mul_f32_e32 v100, v177, v177
	v_pk_add_f32 v[162:163], v[90:91], v[124:125]
	v_pk_add_f32 v[126:127], v[126:127], v[126:127] op_sel:[0,1] op_sel_hi:[1,0]
	v_pk_add_f32 v[108:109], v[108:109], v[108:109] op_sel:[0,1] op_sel_hi:[1,0]
	v_pk_fma_f32 v[98:99], v[172:173], v[172:173], v[98:99] op_sel_hi:[1,1,0]
	v_pk_fma_f32 v[100:101], v[176:177], v[176:177], v[100:101] op_sel_hi:[1,1,0]
	v_pk_mul_f32 v[90:91], v[178:179], v[178:179]
	v_pk_mul_f32 v[124:125], v[162:163], v[162:163]
	v_mov_b32_e32 v127, v90
	v_mov_b32_e32 v109, v91
	v_mov_b32_e32 v99, v124
	v_mov_b32_e32 v101, v125
	v_pk_add_f32 v[90:91], v[126:127], v[108:109]
	v_pk_add_f32 v[98:99], v[98:99], v[100:101]
	s_waitcnt vmcnt(46)
	v_lshlrev_b32_e32 v100, 16, v158
	v_pk_add_f32 v[90:91], v[90:91], v[98:99]
	v_lshlrev_b32_e32 v98, 16, v76
	v_and_b32_e32 v99, 0xffff0000, v76
	v_and_b32_e32 v101, 0xffff0000, v158
	v_pk_add_f32 v[180:181], v[98:99], v[100:101]
	v_lshlrev_b32_e32 v76, 16, v77
	v_and_b32_e32 v77, 0xffff0000, v77
	v_lshlrev_b32_e32 v98, 16, v159
	v_and_b32_e32 v99, 0xffff0000, v159
	v_pk_add_f32 v[158:159], v[76:77], v[98:99]
	v_mov_b32_e32 v98, v181
	v_mov_b32_e32 v99, v159
	v_mov_b32_e32 v76, v180
	v_mov_b32_e32 v77, v158
	v_pk_mul_f32 v[98:99], v[98:99], v[98:99]
	s_waitcnt vmcnt(45)
	v_lshlrev_b32_e32 v100, 16, v154
	v_pk_fma_f32 v[76:77], v[76:77], v[76:77], v[98:99]
	v_lshlrev_b32_e32 v98, 16, v74
	v_and_b32_e32 v99, 0xffff0000, v74
	v_and_b32_e32 v101, 0xffff0000, v154
	v_pk_add_f32 v[184:185], v[98:99], v[100:101]
	v_lshlrev_b32_e32 v74, 16, v75
	v_and_b32_e32 v75, 0xffff0000, v75
	v_lshlrev_b32_e32 v98, 16, v155
	v_and_b32_e32 v99, 0xffff0000, v155
	v_lshlrev_b32_e32 v100, 16, v68
	v_and_b32_e32 v101, 0xffff0000, v68
	s_waitcnt vmcnt(44)
	v_lshlrev_b32_e32 v108, 16, v150
	v_and_b32_e32 v109, 0xffff0000, v150
	v_pk_add_f32 v[154:155], v[74:75], v[98:99]
	v_pk_add_f32 v[186:187], v[100:101], v[108:109]
	v_lshlrev_b32_e32 v68, 16, v69
	v_and_b32_e32 v69, 0xffff0000, v69
	v_lshlrev_b32_e32 v100, 16, v151
	v_and_b32_e32 v101, 0xffff0000, v151
	v_mul_f32_e32 v74, v185, v185
	v_mul_f32_e32 v98, v155, v155
	v_pk_add_f32 v[150:151], v[68:69], v[100:101]
	v_pk_add_f32 v[90:91], v[90:91], v[90:91] op_sel:[0,1] op_sel_hi:[1,0]
	v_pk_add_f32 v[76:77], v[76:77], v[76:77] op_sel:[0,1] op_sel_hi:[1,0]
	v_pk_fma_f32 v[74:75], v[184:185], v[184:185], v[74:75] op_sel_hi:[1,1,0]
	v_pk_fma_f32 v[98:99], v[154:155], v[154:155], v[98:99] op_sel_hi:[1,1,0]
	v_pk_mul_f32 v[68:69], v[186:187], v[186:187]
	v_pk_mul_f32 v[100:101], v[150:151], v[150:151]
	v_mov_b32_e32 v91, v68
	v_mov_b32_e32 v77, v69
	v_mov_b32_e32 v75, v100
	v_mov_b32_e32 v99, v101
	v_pk_add_f32 v[68:69], v[90:91], v[76:77]
	v_pk_add_f32 v[74:75], v[74:75], v[98:99]
	s_cselect_b64 s[14:15], -1, 0
	v_pk_add_f32 v[68:69], v[68:69], v[74:75]
	s_and_b64 s[6:7], s[14:15], exec
	v_add_f32_e32 v68, v68, v69
	s_cselect_b32 s6, s10, s18
	s_ashr_i32 s7, s6, 31
	v_add_f32_dpp v68, v68, v68 quad_perm:[1,0,3,2] row_mask:0xf bank_mask:0xf bound_ctrl:1
	s_lshl_b64 s[6:7], s[6:7], 12
	v_lshl_add_u64 v[36:37], v[36:37], 0, s[6:7]
	v_add_f32_dpp v68, v68, v68 quad_perm:[2,3,0,1] row_mask:0xf bank_mask:0xf bound_ctrl:1
	v_lshl_add_u64 v[50:51], v[36:37], 0, v[0:1]
	v_lshl_add_u64 v[36:37], v[38:39], 0, s[6:7]
	v_add_f32_dpp v68, v68, v68 row_half_mirror row_mask:0xf bank_mask:0xf bound_ctrl:1
	v_lshl_add_u64 v[166:167], v[36:37], 0, v[0:1]
	v_lshl_add_u64 v[36:37], v[40:41], 0, s[6:7]
	v_add_f32_dpp v68, v68, v68 row_mirror row_mask:0xf bank_mask:0xf bound_ctrl:1
	v_lshl_add_u64 v[164:165], v[36:37], 0, v[0:1]
	v_readlane_b32 s8, v68, 16
	v_readlane_b32 s9, v68, 48
	v_readlane_b32 s6, v68, 0
	v_readlane_b32 s7, v68, 32
	v_mov_b32_e32 v68, s8
	v_mov_b32_e32 v69, s9
	v_pk_add_f32 v[68:69], s[6:7], v[68:69]
	global_load_dwordx2 v[130:131], v[50:51], off nt
	global_load_dwordx2 v[116:117], v[50:51], off offset:512 nt
	global_load_dwordx2 v[112:113], v[50:51], off offset:1024 nt
	global_load_dwordx2 v[92:93], v[50:51], off offset:1536 nt
	global_load_dwordx2 v[134:135], v[166:167], off nt
	global_load_dwordx2 v[128:129], v[166:167], off offset:512 nt
	global_load_dwordx2 v[114:115], v[166:167], off offset:1024 nt
; #define GAS __attribute__((address_space(1)))
; #define LAS __attribute__((address_space(3)))
; template <bool HG>
; __device__ __forceinline__ void readout_phase2(const Args& a, Frame& F, const float* gain, int nrows) {
;     ...
;     RO_LOAD(f0, b0, g0, nw); RO_LOAD(f1, b1, g1, nw + 2048); RO_LOAD(f2, b2, g2, nw + 2 * 2048);
;     if (HG) { for (int q = F.tid; q < D / 4; q += NWAVES * 64) ((LAS f32x4*)GL)[q] = ((const GAS f32x4*)gain)[q];
;               asm volatile("s_waitcnt lgkmcnt(0)" ::: "memory"); __builtin_amdgcn_s_barrier(); asm volatile("" ::: "memory"); }
;     RO_FINISH(f0, b0, g0, nw);            RO_LOAD(f0, b0, g0, nw + 3 * 2048);
;     RO_FINISH(f1, b1, g1, nw + 2048);     RO_LOAD(f1, b1, g1, nw + 4 * 2048);
;     RO_FINISH(f2, b2, g2, nw + 2 * 2048); RO_LOAD(f2, b2, g2, nw + 5 * 2048);
;     RO_FINISH(f0, b0, g0, nw + 3 * 2048); RO_LOAD(f0, b0, g0, nw + 6 * 2048);
;     RO_FINISH(f1, b1, g1, nw + 4 * 2048); RO_LOAD(f1, b1, g1, nw + 7 * 2048);
;     RO_FINISH(f2, b2, g2, nw + 5 * 2048);
;     const bool cx = ML + nw < nrows;
;     RO_LOAD(f2, b2, g2, cx ? ML + nw : nw + 7 * 2048);
;     RO_FINISH(f0, b0, g0, nw + 6 * 2048);
	global_load_dwordx2 v[104:105], v[166:167], off offset:1536 nt
	global_load_dwordx2 v[44:45], v[164:165], off nt
	global_load_dwordx2 v[40:41], v[164:165], off offset:512 nt
	global_load_dwordx2 v[38:39], v[164:165], off offset:1024 nt
	global_load_dwordx2 v[36:37], v[164:165], off offset:1536 nt
	global_load_dwordx2 v[86:87], v[50:51], off offset:2048 nt
	global_load_dwordx2 v[62:63], v[50:51], off offset:2560 nt
	global_load_dwordx2 v[56:57], v[50:51], off offset:3072 nt
	s_nop 0
	global_load_dwordx2 v[50:51], v[50:51], off offset:3584 nt
	v_add_f32_e32 v68, v68, v69
	v_fmamk_f32 v68, v68, 0x3a000000, v252
	v_mul_f32_e32 v69, 0x4f800000, v68
	v_cmp_gt_f32_e32 vcc, s55, v68
	global_load_dwordx2 v[124:125], v[166:167], off offset:2048 nt
	global_load_dwordx2 v[108:109], v[166:167], off offset:2560 nt
	global_load_dwordx2 v[100:101], v[166:167], off offset:3072 nt
	global_load_dwordx2 v[98:99], v[166:167], off offset:3584 nt
	v_cndmask_b32_e32 v68, v68, v69, vcc
	v_sqrt_f32_e32 v69, v68
	s_nop 0
	v_add_u32_e32 v74, -1, v69
	v_fma_f32 v75, -v74, v69, v68
	v_cmp_ge_f32_e64 s[8:9], 0, v75
	v_add_u32_e32 v75, 1, v69
	s_nop 0
	v_cndmask_b32_e64 v74, v69, v74, s[8:9]
	v_fma_f32 v69, -v75, v69, v68
	v_cmp_lt_f32_e64 s[8:9], 0, v69
	s_nop 1
	v_cndmask_b32_e64 v69, v74, v75, s[8:9]
	v_mul_f32_e32 v74, 0x37800000, v69
	v_cndmask_b32_e32 v69, v69, v74, vcc
	v_cmp_class_f32_e32 vcc, v68, v253
	s_nop 1
	v_cndmask_b32_e32 v126, v69, v68, vcc
	v_div_scale_f32 v127, s[6:7], v126, v126, 1.0
	v_rcp_f32_e32 v166, v127
	global_load_dwordx2 v[90:91], v[164:165], off offset:2048 nt
	global_load_dwordx2 v[76:77], v[164:165], off offset:2560 nt
	global_load_dwordx2 v[74:75], v[164:165], off offset:3072 nt
	global_load_dwordx2 v[68:69], v[164:165], off offset:3584 nt
	v_fma_f32 v164, -v127, v166, 1.0
	v_fmac_f32_e32 v166, v164, v166
	v_div_scale_f32 v164, vcc, 1.0, v126, 1.0
	v_mul_f32_e32 v165, v164, v166
	v_fma_f32 v167, -v127, v165, v164
	v_fmac_f32_e32 v165, v167, v166
	v_fma_f32 v127, -v127, v165, v164
	v_div_fmas_f32 v127, v127, v166, v165
	v_div_fixup_f32 v164, v127, v126, 1.0
	v_pk_mul_f32 v[148:149], v[148:149], v[164:165] op_sel_hi:[1,0]
	v_pk_mul_f32 v[168:169], v[168:169], v[164:165] op_sel_hi:[1,0]
	v_lshlrev_b32_e32 v166, 16, v58
	v_and_b32_e32 v167, 0xffff0000, v58
	v_lshlrev_b32_e32 v58, 16, v59
	v_and_b32_e32 v59, 0xffff0000, v59
	v_pk_mul_f32 v[168:169], v[2:3], v[168:169]
	v_pk_mul_f32 v[148:149], v[4:5], v[148:149]
	v_pk_mul_f32 v[132:133], v[132:133], v[164:165] op_sel_hi:[1,0]
	v_pk_mul_f32 v[58:59], v[148:149], v[58:59]
	v_pk_mul_f32 v[148:149], v[168:169], v[166:167]
	v_pk_mul_f32 v[140:141], v[140:141], v[164:165] op_sel_hi:[1,0]
	v_cvt_pk_bf16_f32 v148, v148, v149
	v_cvt_pk_bf16_f32 v149, v58, v59
	v_lshlrev_b32_e32 v58, 16, v52
	v_and_b32_e32 v59, 0xffff0000, v52
	v_lshlrev_b32_e32 v52, 16, v53
	v_and_b32_e32 v53, 0xffff0000, v53
	v_pk_mul_f32 v[140:141], v[6:7], v[140:141]
	v_pk_mul_f32 v[132:133], v[8:9], v[132:133]
	v_lshl_add_u64 v[126:127], v[34:35], 0, s[12:13]
	v_pk_mul_f32 v[52:53], v[132:133], v[52:53]
	v_pk_mul_f32 v[58:59], v[140:141], v[58:59]
	v_lshl_add_u64 v[126:127], v[126:127], 0, v[0:1]
	v_cvt_pk_bf16_f32 v58, v58, v59
	v_cvt_pk_bf16_f32 v59, v52, v53
	global_store_dwordx2 v[126:127], v[58:59], off offset:512 nt
	v_pk_mul_f32 v[58:59], v[174:175], v[164:165] op_sel_hi:[1,0]
	v_pk_mul_f32 v[132:133], v[170:171], v[164:165] op_sel_hi:[1,0]
	v_lshlrev_b32_e32 v52, 16, v48
	v_and_b32_e32 v53, 0xffff0000, v48
	v_lshlrev_b32_e32 v48, 16, v49
	v_and_b32_e32 v49, 0xffff0000, v49
	v_pk_mul_f32 v[132:133], v[10:11], v[132:133]
	v_pk_mul_f32 v[58:59], v[12:13], v[58:59]
	v_pk_mul_f32 v[52:53], v[132:133], v[52:53]
	v_pk_mul_f32 v[48:49], v[58:59], v[48:49]
	v_cvt_pk_bf16_f32 v52, v52, v53
	v_cvt_pk_bf16_f32 v53, v48, v49
	global_store_dwordx2 v[126:127], v[52:53], off offset:1024 nt
	v_pk_mul_f32 v[52:53], v[176:177], v[164:165] op_sel_hi:[1,0]
	v_pk_mul_f32 v[58:59], v[172:173], v[164:165] op_sel_hi:[1,0]
	v_lshlrev_b32_e32 v48, 16, v42
	v_and_b32_e32 v49, 0xffff0000, v42
	v_lshlrev_b32_e32 v42, 16, v43
	v_and_b32_e32 v43, 0xffff0000, v43
	v_pk_mul_f32 v[58:59], v[14:15], v[58:59]
	v_pk_mul_f32 v[52:53], v[16:17], v[52:53]
	v_pk_mul_f32 v[48:49], v[58:59], v[48:49]
	v_pk_mul_f32 v[42:43], v[52:53], v[42:43]
	v_cvt_pk_bf16_f32 v48, v48, v49
	v_cvt_pk_bf16_f32 v49, v42, v43
	v_pk_mul_f32 v[52:53], v[162:163], v[164:165] op_sel_hi:[1,0]
	v_pk_mul_f32 v[58:59], v[178:179], v[164:165] op_sel_hi:[1,0]
	global_store_dwordx2 v[126:127], v[48:49], off offset:1536 nt
	s_waitcnt vmcnt(62)
	v_lshlrev_b32_e32 v42, 16, v106
	v_and_b32_e32 v43, 0xffff0000, v106
	v_lshlrev_b32_e32 v48, 16, v107
	v_and_b32_e32 v49, 0xffff0000, v107
	v_pk_mul_f32 v[58:59], v[18:19], v[58:59]
	v_pk_mul_f32 v[52:53], v[20:21], v[52:53]
	v_pk_mul_f32 v[42:43], v[58:59], v[42:43]
	v_pk_mul_f32 v[48:49], v[52:53], v[48:49]
	v_cvt_pk_bf16_f32 v42, v42, v43
	v_cvt_pk_bf16_f32 v43, v48, v49
	v_pk_mul_f32 v[52:53], v[158:159], v[164:165] op_sel_hi:[1,0]
	v_pk_mul_f32 v[58:59], v[180:181], v[164:165] op_sel_hi:[1,0]
	global_store_dwordx2 v[126:127], v[42:43], off offset:2048 nt
	v_lshlrev_b32_e32 v42, 16, v96
	v_and_b32_e32 v43, 0xffff0000, v96
	v_lshlrev_b32_e32 v48, 16, v97
	v_and_b32_e32 v49, 0xffff0000, v97
	v_pk_mul_f32 v[58:59], v[22:23], v[58:59]
	v_pk_mul_f32 v[52:53], v[24:25], v[52:53]
	v_pk_mul_f32 v[42:43], v[58:59], v[42:43]
	v_pk_mul_f32 v[48:49], v[52:53], v[48:49]
	v_cvt_pk_bf16_f32 v42, v42, v43
	v_cvt_pk_bf16_f32 v43, v48, v49
	v_pk_mul_f32 v[52:53], v[154:155], v[164:165] op_sel_hi:[1,0]
	v_pk_mul_f32 v[58:59], v[184:185], v[164:165] op_sel_hi:[1,0]
	global_store_dwordx2 v[126:127], v[42:43], off offset:2560 nt
	v_lshlrev_b32_e32 v42, 16, v82
	v_and_b32_e32 v43, 0xffff0000, v82
	v_lshlrev_b32_e32 v48, 16, v83
	v_and_b32_e32 v49, 0xffff0000, v83
	v_pk_mul_f32 v[58:59], v[26:27], v[58:59]
	v_pk_mul_f32 v[52:53], v[28:29], v[52:53]
	v_pk_mul_f32 v[42:43], v[58:59], v[42:43]
	v_pk_mul_f32 v[48:49], v[52:53], v[48:49]
	v_cvt_pk_bf16_f32 v42, v42, v43
	v_cvt_pk_bf16_f32 v43, v48, v49
	global_store_dwordx2 v[126:127], v[42:43], off offset:3072 nt
	v_pk_mul_f32 v[42:43], v[186:187], v[164:165] op_sel_hi:[1,0]
	s_waitcnt vmcnt(57)
; #define GAS __attribute__((address_space(1)))
; #define LAS __attribute__((address_space(3)))
; template <bool HG>
; __device__ __forceinline__ void readout_phase2(const Args& a, Frame& F, const float* gain, int nrows) {
;     ...
;     RO_LOAD(f0, b0, g0, nw); RO_LOAD(f1, b1, g1, nw + 2048); RO_LOAD(f2, b2, g2, nw + 2 * 2048);
;     if (HG) { for (int q = F.tid; q < D / 4; q += NWAVES * 64) ((LAS f32x4*)GL)[q] = ((const GAS f32x4*)gain)[q];
;               asm volatile("s_waitcnt lgkmcnt(0)" ::: "memory"); __builtin_amdgcn_s_barrier(); asm volatile("" ::: "memory"); }
;     RO_FINISH(f0, b0, g0, nw);            RO_LOAD(f0, b0, g0, nw + 3 * 2048);
;     RO_FINISH(f1, b1, g1, nw + 2048);     RO_LOAD(f1, b1, g1, nw + 4 * 2048);
;     RO_FINISH(f2, b2, g2, nw + 2 * 2048); RO_LOAD(f2, b2, g2, nw + 5 * 2048);
;     RO_FINISH(f0, b0, g0, nw + 3 * 2048); RO_LOAD(f0, b0, g0, nw + 6 * 2048);
;     RO_FINISH(f1, b1, g1, nw + 4 * 2048); RO_LOAD(f1, b1, g1, nw + 7 * 2048);
;     RO_FINISH(f2, b2, g2, nw + 5 * 2048);
;     const bool cx = ML + nw < nrows;
;     RO_LOAD(f2, b2, g2, cx ? ML + nw : nw + 7 * 2048);
;     RO_FINISH(f0, b0, g0, nw + 6 * 2048);
;     RO_FINISH(f1, b1, g1, nw + 7 * 2048);
	v_lshlrev_b32_e32 v48, 16, v146
	v_pk_mul_f32 v[132:133], v[30:31], v[42:43]
	v_lshlrev_b32_e32 v42, 16, v144
	v_and_b32_e32 v43, 0xffff0000, v144
	v_and_b32_e32 v49, 0xffff0000, v146
	v_pk_add_f32 v[48:49], v[42:43], v[48:49]
	v_lshlrev_b32_e32 v42, 16, v145
	v_and_b32_e32 v43, 0xffff0000, v145
	v_lshlrev_b32_e32 v52, 16, v147
	v_and_b32_e32 v53, 0xffff0000, v147
	v_pk_add_f32 v[58:59], v[42:43], v[52:53]
	v_lshlrev_b32_e32 v42, 16, v138
	v_and_b32_e32 v43, 0xffff0000, v138
	s_waitcnt vmcnt(56)
	v_lshlrev_b32_e32 v52, 16, v142
	v_and_b32_e32 v53, 0xffff0000, v142
	v_pk_add_f32 v[42:43], v[42:43], v[52:53]
	v_lshlrev_b32_e32 v52, 16, v139
	v_and_b32_e32 v53, 0xffff0000, v139
	v_lshlrev_b32_e32 v96, 16, v143
	v_and_b32_e32 v97, 0xffff0000, v143
	v_pk_add_f32 v[52:53], v[52:53], v[96:97]
	v_mov_b32_e32 v138, v49
	v_mov_b32_e32 v139, v43
	v_mov_b32_e32 v96, v48
	v_mov_b32_e32 v97, v42
	v_pk_mul_f32 v[138:139], v[138:139], v[138:139]
	v_mov_b32_e32 v140, v59
	v_mov_b32_e32 v141, v53
	v_pk_fma_f32 v[96:97], v[96:97], v[96:97], v[138:139]
	v_mov_b32_e32 v138, v58
	v_mov_b32_e32 v139, v52
	v_pk_mul_f32 v[140:141], v[140:141], v[140:141]
	s_waitcnt vmcnt(54)
	v_lshlrev_b32_e32 v142, 16, v118
	v_pk_fma_f32 v[138:139], v[138:139], v[138:139], v[140:141]
	v_lshlrev_b32_e32 v140, 16, v122
	v_pk_add_f32 v[96:97], v[96:97], v[138:139]
	v_and_b32_e32 v141, 0xffff0000, v122
	v_pk_add_f32 v[138:139], v[96:97], v[96:97] op_sel:[0,1] op_sel_hi:[1,0]
	v_lshlrev_b32_e32 v96, 16, v120
	v_and_b32_e32 v97, 0xffff0000, v120
	v_lshlrev_b32_e32 v120, 16, v121
	v_and_b32_e32 v121, 0xffff0000, v121
	v_lshlrev_b32_e32 v122, 16, v123
	v_and_b32_e32 v123, 0xffff0000, v123
	v_pk_add_f32 v[96:97], v[96:97], v[140:141]
	v_pk_add_f32 v[120:121], v[120:121], v[122:123]
	v_mov_b32_e32 v140, v97
	v_mov_b32_e32 v141, v121
	v_mov_b32_e32 v122, v96
	v_mov_b32_e32 v123, v120
	v_pk_mul_f32 v[140:141], v[140:141], v[140:141]
	v_and_b32_e32 v143, 0xffff0000, v118
	v_pk_fma_f32 v[122:123], v[122:123], v[122:123], v[140:141]
	v_lshlrev_b32_e32 v140, 16, v110
	v_and_b32_e32 v141, 0xffff0000, v110
	v_lshlrev_b32_e32 v110, 16, v111
	v_and_b32_e32 v111, 0xffff0000, v111
	v_lshlrev_b32_e32 v118, 16, v119
	v_and_b32_e32 v119, 0xffff0000, v119
	s_waitcnt vmcnt(49)
	v_lshlrev_b32_e32 v144, 16, v94
	v_and_b32_e32 v145, 0xffff0000, v94
	s_waitcnt vmcnt(45)
	v_lshlrev_b32_e32 v146, 16, v160
	v_and_b32_e32 v147, 0xffff0000, v160
	v_pk_add_f32 v[140:141], v[140:141], v[142:143]
	v_pk_add_f32 v[110:111], v[110:111], v[118:119]
	v_pk_add_f32 v[144:145], v[144:145], v[146:147]
	v_lshlrev_b32_e32 v94, 16, v95
	v_and_b32_e32 v95, 0xffff0000, v95
	v_lshlrev_b32_e32 v146, 16, v161
	v_and_b32_e32 v147, 0xffff0000, v161
	v_mul_f32_e32 v118, v141, v141
	v_mul_f32_e32 v142, v111, v111
	v_pk_add_f32 v[94:95], v[94:95], v[146:147]
	global_store_dwordx2 v[126:127], v[148:149], off nt
	v_pk_add_f32 v[122:123], v[122:123], v[122:123] op_sel:[0,1] op_sel_hi:[1,0]
	v_pk_fma_f32 v[118:119], v[140:141], v[140:141], v[118:119] op_sel_hi:[1,1,0]
	v_pk_fma_f32 v[142:143], v[110:111], v[110:111], v[142:143] op_sel_hi:[1,1,0]
	v_pk_mul_f32 v[146:147], v[144:145], v[144:145]
	v_pk_mul_f32 v[148:149], v[94:95], v[94:95]
	v_mov_b32_e32 v139, v146
	v_mov_b32_e32 v123, v147
	v_mov_b32_e32 v119, v148
	v_mov_b32_e32 v143, v149
	v_pk_add_f32 v[122:123], v[138:139], v[122:123]
	v_pk_add_f32 v[118:119], v[118:119], v[142:143]
	s_waitcnt vmcnt(45)
	v_lshlrev_b32_e32 v138, 16, v156
	v_pk_add_f32 v[118:119], v[122:123], v[118:119]
	v_lshlrev_b32_e32 v122, 16, v88
	v_and_b32_e32 v123, 0xffff0000, v88
	v_and_b32_e32 v139, 0xffff0000, v156
	v_pk_add_f32 v[122:123], v[122:123], v[138:139]
	v_lshlrev_b32_e32 v88, 16, v89
	v_and_b32_e32 v89, 0xffff0000, v89
	v_lshlrev_b32_e32 v138, 16, v157
	v_and_b32_e32 v139, 0xffff0000, v157
	v_pk_add_f32 v[88:89], v[88:89], v[138:139]
	v_mov_b32_e32 v142, v123
	v_mov_b32_e32 v143, v89
	v_mov_b32_e32 v138, v122
	v_mov_b32_e32 v139, v88
	v_pk_mul_f32 v[142:143], v[142:143], v[142:143]
	s_waitcnt vmcnt(44)
	v_lshlrev_b32_e32 v146, 16, v152
	v_pk_fma_f32 v[138:139], v[138:139], v[138:139], v[142:143]
	v_lshlrev_b32_e32 v142, 16, v80
	v_and_b32_e32 v143, 0xffff0000, v80
	v_and_b32_e32 v147, 0xffff0000, v152
	v_pk_add_f32 v[142:143], v[142:143], v[146:147]
	v_lshlrev_b32_e32 v80, 16, v81
	v_and_b32_e32 v81, 0xffff0000, v81
	v_lshlrev_b32_e32 v146, 16, v153
	v_and_b32_e32 v147, 0xffff0000, v153
	v_pk_mul_f32 v[106:107], v[150:151], v[164:165] op_sel_hi:[1,0]
	v_pk_add_f32 v[80:81], v[80:81], v[146:147]
	v_lshlrev_b32_e32 v150, 16, v66
	v_and_b32_e32 v151, 0xffff0000, v66
	s_waitcnt vmcnt(43)
; template <bool HG>
; __device__ __forceinline__ void readout_phase2(const Args& a, Frame& F, const float* gain, int nrows) {
;     ...
;     RO_FINISH(f0, b0, g0, nw + 6 * 2048);
;     RO_FINISH(f1, b1, g1, nw + 7 * 2048);
	v_lshlrev_b32_e32 v152, 16, v136
	v_and_b32_e32 v153, 0xffff0000, v136
	v_lshlrev_b32_e32 v66, 16, v67
	v_and_b32_e32 v67, 0xffff0000, v67
	v_lshlrev_b32_e32 v136, 16, v137
	v_and_b32_e32 v137, 0xffff0000, v137
	v_mul_f32_e32 v146, v143, v143
	v_mul_f32_e32 v148, v81, v81
	v_pk_add_f32 v[150:151], v[150:151], v[152:153]
	v_pk_add_f32 v[66:67], v[66:67], v[136:137]
	v_pk_add_f32 v[118:119], v[118:119], v[118:119] op_sel:[0,1] op_sel_hi:[1,0]
	v_pk_add_f32 v[138:139], v[138:139], v[138:139] op_sel:[0,1] op_sel_hi:[1,0]
	v_pk_fma_f32 v[146:147], v[142:143], v[142:143], v[146:147] op_sel_hi:[1,1,0]
	v_pk_fma_f32 v[148:149], v[80:81], v[80:81], v[148:149] op_sel_hi:[1,1,0]
	v_pk_mul_f32 v[136:137], v[150:151], v[150:151]
	v_pk_mul_f32 v[152:153], v[66:67], v[66:67]
	v_mov_b32_e32 v119, v136
	v_mov_b32_e32 v139, v137
	v_mov_b32_e32 v147, v152
	v_mov_b32_e32 v149, v153
	v_pk_add_f32 v[118:119], v[118:119], v[138:139]
	v_pk_add_f32 v[136:137], v[146:147], v[148:149]
	v_lshlrev_b32_e32 v82, 16, v72
	v_pk_add_f32 v[118:119], v[118:119], v[136:137]
	v_and_b32_e32 v83, 0xffff0000, v72
	v_add_f32_e32 v118, v118, v119
	v_lshlrev_b32_e32 v72, 16, v73
	v_and_b32_e32 v73, 0xffff0000, v73
	v_add_f32_dpp v118, v118, v118 quad_perm:[1,0,3,2] row_mask:0xf bank_mask:0xf bound_ctrl:1
	v_pk_mul_f32 v[106:107], v[32:33], v[106:107]
	v_pk_mul_f32 v[82:83], v[132:133], v[82:83]
	v_add_f32_dpp v118, v118, v118 quad_perm:[2,3,0,1] row_mask:0xf bank_mask:0xf bound_ctrl:1
	v_pk_mul_f32 v[72:73], v[106:107], v[72:73]
	v_cvt_pk_bf16_f32 v82, v82, v83
	v_add_f32_dpp v118, v118, v118 row_half_mirror row_mask:0xf bank_mask:0xf bound_ctrl:1
	v_cvt_pk_bf16_f32 v83, v72, v73
	global_store_dwordx2 v[126:127], v[82:83], off offset:3584 nt
	v_add_f32_dpp v118, v118, v118 row_mirror row_mask:0xf bank_mask:0xf bound_ctrl:1
	s_nop 0
	v_readlane_b32 s8, v118, 16
	v_readlane_b32 s9, v118, 48
	v_readlane_b32 s6, v118, 0
	v_readlane_b32 s7, v118, 32
	v_mov_b32_e32 v118, s8
	v_mov_b32_e32 v119, s9
	v_pk_add_f32 v[118:119], s[6:7], v[118:119]
	s_nop 0
	v_add_f32_e32 v118, v118, v119
	v_fmamk_f32 v118, v118, 0x3a000000, v252
	v_mul_f32_e32 v119, 0x4f800000, v118
	v_cmp_gt_f32_e32 vcc, s55, v118
	s_nop 1
	v_cndmask_b32_e32 v118, v118, v119, vcc
	v_sqrt_f32_e32 v119, v118
	s_nop 0
	v_add_u32_e32 v106, -1, v119
	v_fma_f32 v107, -v106, v119, v118
	v_cmp_ge_f32_e64 s[8:9], 0, v107
	v_add_u32_e32 v107, 1, v119
	s_nop 0
	v_cndmask_b32_e64 v106, v119, v106, s[8:9]
	v_fma_f32 v119, -v107, v119, v118
	v_cmp_lt_f32_e64 s[8:9], 0, v119
	s_nop 1
	v_cndmask_b32_e64 v106, v106, v107, s[8:9]
	v_mul_f32_e32 v107, 0x37800000, v106
	v_cndmask_b32_e32 v106, v106, v107, vcc
	v_cmp_class_f32_e32 vcc, v118, v253
	s_nop 1
	v_cndmask_b32_e32 v106, v106, v118, vcc
	v_div_scale_f32 v107, s[6:7], v106, v106, 1.0
	v_rcp_f32_e32 v118, v107
	s_nop 0
	v_fma_f32 v72, -v107, v118, 1.0
	v_fmac_f32_e32 v118, v72, v118
	v_div_scale_f32 v72, vcc, 1.0, v106, 1.0
	v_mul_f32_e32 v73, v72, v118
	v_fma_f32 v82, -v107, v73, v72
	v_fmac_f32_e32 v73, v82, v118
	v_fma_f32 v72, -v107, v73, v72
	v_div_fmas_f32 v72, v72, v118, v73
	v_div_fixup_f32 v72, v72, v106, 1.0
	v_pk_mul_f32 v[58:59], v[58:59], v[72:73] op_sel_hi:[1,0]
	v_pk_mul_f32 v[48:49], v[48:49], v[72:73] op_sel_hi:[1,0]
	v_lshlrev_b32_e32 v106, 16, v64
	v_and_b32_e32 v107, 0xffff0000, v64
	v_lshlrev_b32_e32 v64, 16, v65
	v_and_b32_e32 v65, 0xffff0000, v65
	v_pk_mul_f32 v[48:49], v[2:3], v[48:49]
	v_pk_mul_f32 v[58:59], v[4:5], v[58:59]
	v_lshl_add_u64 v[82:83], v[34:35], 0, s[16:17]
	v_pk_mul_f32 v[58:59], v[58:59], v[64:65]
	v_pk_mul_f32 v[48:49], v[48:49], v[106:107]
	v_lshl_add_u64 v[82:83], v[82:83], 0, v[0:1]
	v_cvt_pk_bf16_f32 v48, v48, v49
	v_cvt_pk_bf16_f32 v49, v58, v59
	v_pk_mul_f32 v[52:53], v[52:53], v[72:73] op_sel_hi:[1,0]
	v_pk_mul_f32 v[42:43], v[42:43], v[72:73] op_sel_hi:[1,0]
	global_store_dwordx2 v[82:83], v[48:49], off nt
	v_lshlrev_b32_e32 v48, 16, v60
	v_and_b32_e32 v49, 0xffff0000, v60
	v_lshlrev_b32_e32 v58, 16, v61
	v_and_b32_e32 v59, 0xffff0000, v61
	v_pk_mul_f32 v[42:43], v[6:7], v[42:43]
	v_pk_mul_f32 v[52:53], v[8:9], v[52:53]
	v_pk_mul_f32 v[42:43], v[42:43], v[48:49]
	v_pk_mul_f32 v[52:53], v[52:53], v[58:59]
	v_cvt_pk_bf16_f32 v42, v42, v43
	v_cvt_pk_bf16_f32 v43, v52, v53
	global_store_dwordx2 v[82:83], v[42:43], off offset:512 nt
	v_lshlrev_b32_e32 v42, 16, v54
	v_and_b32_e32 v43, 0xffff0000, v54
	v_lshlrev_b32_e32 v48, 16, v55
	v_and_b32_e32 v49, 0xffff0000, v55
	v_pk_mul_f32 v[52:53], v[120:121], v[72:73] op_sel_hi:[1,0]
	v_pk_mul_f32 v[54:55], v[96:97], v[72:73] op_sel_hi:[1,0]
	v_pk_mul_f32 v[52:53], v[12:13], v[52:53]
	v_pk_mul_f32 v[54:55], v[10:11], v[54:55]
	v_pk_mul_f32 v[48:49], v[52:53], v[48:49]
	v_pk_mul_f32 v[42:43], v[54:55], v[42:43]
	v_pk_mul_f32 v[52:53], v[140:141], v[72:73] op_sel_hi:[1,0]
	v_cvt_pk_bf16_f32 v42, v42, v43
	v_cvt_pk_bf16_f32 v43, v48, v49
	v_pk_mul_f32 v[48:49], v[110:111], v[72:73] op_sel_hi:[1,0]
	global_store_dwordx2 v[82:83], v[42:43], off offset:1024 nt
	v_lshlrev_b32_e32 v42, 16, v46
	v_and_b32_e32 v43, 0xffff0000, v46
	v_lshlrev_b32_e32 v46, 16, v47
	v_and_b32_e32 v47, 0xffff0000, v47
	v_pk_mul_f32 v[52:53], v[14:15], v[52:53]
	v_pk_mul_f32 v[48:49], v[16:17], v[48:49]
	v_pk_mul_f32 v[42:43], v[52:53], v[42:43]
	v_pk_mul_f32 v[46:47], v[48:49], v[46:47]
	v_cvt_pk_bf16_f32 v42, v42, v43
	v_cvt_pk_bf16_f32 v43, v46, v47
	v_pk_mul_f32 v[48:49], v[94:95], v[72:73] op_sel_hi:[1,0]
	v_pk_mul_f32 v[52:53], v[144:145], v[72:73] op_sel_hi:[1,0]
	global_store_dwordx2 v[82:83], v[42:43], off offset:1536 nt
	s_waitcnt vmcnt(47)
; template <bool HG>
; __device__ __forceinline__ void readout_phase2(const Args& a, Frame& F, const float* gain, int nrows) {
;     ...
;     RO_FINISH(f1, b1, g1, nw + 7 * 2048);
;     if (cx) RO_FINISH(f2, b2, g2, ML + nw);
	v_lshlrev_b32_e32 v42, 16, v102
	v_and_b32_e32 v43, 0xffff0000, v102
	v_lshlrev_b32_e32 v46, 16, v103
	v_and_b32_e32 v47, 0xffff0000, v103
	v_pk_mul_f32 v[52:53], v[18:19], v[52:53]
	v_pk_mul_f32 v[48:49], v[20:21], v[48:49]
	v_pk_mul_f32 v[42:43], v[52:53], v[42:43]
	v_pk_mul_f32 v[46:47], v[48:49], v[46:47]
	v_cvt_pk_bf16_f32 v42, v42, v43
	v_cvt_pk_bf16_f32 v43, v46, v47
	v_pk_mul_f32 v[48:49], v[88:89], v[72:73] op_sel_hi:[1,0]
	v_pk_mul_f32 v[52:53], v[122:123], v[72:73] op_sel_hi:[1,0]
	global_store_dwordx2 v[82:83], v[42:43], off offset:2048 nt
	s_waitcnt vmcnt(47)
	v_lshlrev_b32_e32 v42, 16, v84
	v_and_b32_e32 v43, 0xffff0000, v84
	v_lshlrev_b32_e32 v46, 16, v85
	v_and_b32_e32 v47, 0xffff0000, v85
	v_pk_mul_f32 v[52:53], v[22:23], v[52:53]
	v_pk_mul_f32 v[48:49], v[24:25], v[48:49]
	v_pk_mul_f32 v[42:43], v[52:53], v[42:43]
	v_pk_mul_f32 v[46:47], v[48:49], v[46:47]
	v_cvt_pk_bf16_f32 v42, v42, v43
	v_cvt_pk_bf16_f32 v43, v46, v47
	v_pk_mul_f32 v[48:49], v[80:81], v[72:73] op_sel_hi:[1,0]
	v_pk_mul_f32 v[52:53], v[142:143], v[72:73] op_sel_hi:[1,0]
	global_store_dwordx2 v[82:83], v[42:43], off offset:2560 nt
	s_waitcnt vmcnt(47)
	v_lshlrev_b32_e32 v42, 16, v78
	v_and_b32_e32 v43, 0xffff0000, v78
	v_lshlrev_b32_e32 v46, 16, v79
	v_and_b32_e32 v47, 0xffff0000, v79
	v_pk_mul_f32 v[52:53], v[26:27], v[52:53]
	v_pk_mul_f32 v[48:49], v[28:29], v[48:49]
	v_pk_mul_f32 v[42:43], v[52:53], v[42:43]
	v_pk_mul_f32 v[46:47], v[48:49], v[46:47]
	v_cvt_pk_bf16_f32 v42, v42, v43
	v_cvt_pk_bf16_f32 v43, v46, v47
	v_pk_mul_f32 v[48:49], v[66:67], v[72:73] op_sel_hi:[1,0]
	v_pk_mul_f32 v[52:53], v[150:151], v[72:73] op_sel_hi:[1,0]
	global_store_dwordx2 v[82:83], v[42:43], off offset:3072 nt
	s_waitcnt vmcnt(47)
	v_lshlrev_b32_e32 v42, 16, v70
	v_and_b32_e32 v43, 0xffff0000, v70
	v_lshlrev_b32_e32 v46, 16, v71
	v_and_b32_e32 v47, 0xffff0000, v71
	v_pk_mul_f32 v[52:53], v[30:31], v[52:53]
	v_pk_mul_f32 v[48:49], v[32:33], v[48:49]
	v_pk_mul_f32 v[42:43], v[52:53], v[42:43]
	v_pk_mul_f32 v[46:47], v[48:49], v[46:47]
	v_cvt_pk_bf16_f32 v42, v42, v43
	v_cvt_pk_bf16_f32 v43, v46, v47
	s_and_b64 vcc, exec, s[14:15]
	global_store_dwordx2 v[82:83], v[42:43], off offset:3584 nt
	s_cbranch_vccz .LBB0_582
	s_waitcnt vmcnt(39)
	v_lshlrev_b32_e32 v42, 16, v130
	v_and_b32_e32 v43, 0xffff0000, v130
	s_waitcnt vmcnt(35)
	v_lshlrev_b32_e32 v46, 16, v134
	v_and_b32_e32 v47, 0xffff0000, v134
	v_pk_add_f32 v[46:47], v[42:43], v[46:47]
	v_lshlrev_b32_e32 v42, 16, v131
	v_and_b32_e32 v43, 0xffff0000, v131
	v_lshlrev_b32_e32 v48, 16, v135
	v_and_b32_e32 v49, 0xffff0000, v135
	v_pk_add_f32 v[52:53], v[42:43], v[48:49]
	v_lshlrev_b32_e32 v42, 16, v116
	v_and_b32_e32 v43, 0xffff0000, v116
	s_waitcnt vmcnt(34)
	v_lshlrev_b32_e32 v48, 16, v128
	v_and_b32_e32 v49, 0xffff0000, v128
	v_pk_add_f32 v[42:43], v[42:43], v[48:49]
	v_lshlrev_b32_e32 v48, 16, v117
	v_and_b32_e32 v49, 0xffff0000, v117
	v_lshlrev_b32_e32 v54, 16, v129
	v_and_b32_e32 v55, 0xffff0000, v129
	v_pk_add_f32 v[48:49], v[48:49], v[54:55]
	v_mov_b32_e32 v58, v47
	v_mov_b32_e32 v59, v43
	v_mov_b32_e32 v54, v46
	v_mov_b32_e32 v55, v42
	v_pk_mul_f32 v[58:59], v[58:59], v[58:59]
	v_mov_b32_e32 v60, v53
	v_mov_b32_e32 v61, v49
	v_pk_fma_f32 v[54:55], v[54:55], v[54:55], v[58:59]
	v_mov_b32_e32 v58, v52
	v_mov_b32_e32 v59, v48
	v_pk_mul_f32 v[60:61], v[60:61], v[60:61]
	s_waitcnt vmcnt(33)
	v_lshlrev_b32_e32 v64, 16, v115
	v_pk_fma_f32 v[58:59], v[58:59], v[58:59], v[60:61]
	v_lshlrev_b32_e32 v60, 16, v114
	v_pk_add_f32 v[54:55], v[54:55], v[58:59]
	v_and_b32_e32 v61, 0xffff0000, v114
	v_pk_add_f32 v[58:59], v[54:55], v[54:55] op_sel:[0,1] op_sel_hi:[1,0]
	v_lshlrev_b32_e32 v54, 16, v112
	v_and_b32_e32 v55, 0xffff0000, v112
	v_pk_add_f32 v[54:55], v[54:55], v[60:61]
	v_lshlrev_b32_e32 v60, 16, v113
	v_and_b32_e32 v61, 0xffff0000, v113
	v_and_b32_e32 v65, 0xffff0000, v115
	v_pk_add_f32 v[60:61], v[60:61], v[64:65]
	v_mov_b32_e32 v66, v55
	v_mov_b32_e32 v67, v61
	v_mov_b32_e32 v64, v54
	v_mov_b32_e32 v65, v60
	v_pk_mul_f32 v[66:67], v[66:67], v[66:67]
	s_waitcnt vmcnt(32)
	v_lshlrev_b32_e32 v70, 16, v104
	v_pk_fma_f32 v[64:65], v[64:65], v[64:65], v[66:67]
	v_lshlrev_b32_e32 v66, 16, v92
	v_and_b32_e32 v67, 0xffff0000, v92
	v_and_b32_e32 v71, 0xffff0000, v104
	v_pk_add_f32 v[66:67], v[66:67], v[70:71]
	v_lshlrev_b32_e32 v70, 16, v93
	v_and_b32_e32 v71, 0xffff0000, v93
	v_lshlrev_b32_e32 v72, 16, v105
	v_and_b32_e32 v73, 0xffff0000, v105
	s_waitcnt vmcnt(27)
	v_lshlrev_b32_e32 v80, 16, v86
	v_and_b32_e32 v81, 0xffff0000, v86
	s_waitcnt vmcnt(23)
	v_lshlrev_b32_e32 v82, 16, v124
	v_and_b32_e32 v83, 0xffff0000, v124
	v_pk_add_f32 v[70:71], v[70:71], v[72:73]
	v_pk_add_f32 v[80:81], v[80:81], v[82:83]
	v_lshlrev_b32_e32 v82, 16, v87
	v_and_b32_e32 v83, 0xffff0000, v87
	v_lshlrev_b32_e32 v84, 16, v125
	v_and_b32_e32 v85, 0xffff0000, v125
	v_mul_f32_e32 v72, v67, v67
	v_mul_f32_e32 v78, v71, v71
	v_pk_add_f32 v[82:83], v[82:83], v[84:85]
	v_pk_add_f32 v[64:65], v[64:65], v[64:65] op_sel:[0,1] op_sel_hi:[1,0]
	v_pk_fma_f32 v[72:73], v[66:67], v[66:67], v[72:73] op_sel_hi:[1,1,0]
	v_pk_fma_f32 v[78:79], v[70:71], v[70:71], v[78:79] op_sel_hi:[1,1,0]
	v_pk_mul_f32 v[84:85], v[80:81], v[80:81]
	v_pk_mul_f32 v[86:87], v[82:83], v[82:83]
	v_mov_b32_e32 v59, v84
	v_mov_b32_e32 v65, v85
	v_mov_b32_e32 v73, v86
	v_mov_b32_e32 v79, v87
	v_pk_add_f32 v[58:59], v[58:59], v[64:65]
	v_pk_add_f32 v[64:65], v[72:73], v[78:79]
	s_waitcnt vmcnt(22)
; template <bool HG>
; __device__ __forceinline__ void readout_phase2(const Args& a, Frame& F, const float* gain, int nrows) {
;     ...
;     if (cx) RO_FINISH(f2, b2, g2, ML + nw);
	v_lshlrev_b32_e32 v72, 16, v108
	v_pk_add_f32 v[58:59], v[58:59], v[64:65]
	v_lshlrev_b32_e32 v64, 16, v62
	v_and_b32_e32 v65, 0xffff0000, v62
	v_and_b32_e32 v73, 0xffff0000, v108
	v_pk_add_f32 v[64:65], v[64:65], v[72:73]
	v_lshlrev_b32_e32 v62, 16, v63
	v_and_b32_e32 v63, 0xffff0000, v63
	v_lshlrev_b32_e32 v72, 16, v109
	v_and_b32_e32 v73, 0xffff0000, v109
	v_pk_add_f32 v[62:63], v[62:63], v[72:73]
	v_mov_b32_e32 v78, v65
	v_mov_b32_e32 v79, v63
	v_mov_b32_e32 v72, v64
	v_mov_b32_e32 v73, v62
	v_pk_mul_f32 v[78:79], v[78:79], v[78:79]
	s_waitcnt vmcnt(21)
	v_lshlrev_b32_e32 v84, 16, v100
	v_pk_fma_f32 v[72:73], v[72:73], v[72:73], v[78:79]
	v_lshlrev_b32_e32 v78, 16, v56
	v_and_b32_e32 v79, 0xffff0000, v56
	v_and_b32_e32 v85, 0xffff0000, v100
	v_pk_add_f32 v[78:79], v[78:79], v[84:85]
	v_lshlrev_b32_e32 v56, 16, v57
	v_and_b32_e32 v57, 0xffff0000, v57
	v_lshlrev_b32_e32 v84, 16, v101
	v_and_b32_e32 v85, 0xffff0000, v101
	v_lshlrev_b32_e32 v88, 16, v50
	v_and_b32_e32 v89, 0xffff0000, v50
	s_waitcnt vmcnt(20)
	v_lshlrev_b32_e32 v92, 16, v98
	v_and_b32_e32 v93, 0xffff0000, v98
	v_pk_add_f32 v[56:57], v[56:57], v[84:85]
	v_pk_add_f32 v[88:89], v[88:89], v[92:93]
	v_lshlrev_b32_e32 v50, 16, v51
	v_and_b32_e32 v51, 0xffff0000, v51
	v_lshlrev_b32_e32 v92, 16, v99
	v_and_b32_e32 v93, 0xffff0000, v99
	v_mul_f32_e32 v84, v79, v79
	v_mul_f32_e32 v86, v57, v57
	v_pk_add_f32 v[50:51], v[50:51], v[92:93]
	v_pk_add_f32 v[58:59], v[58:59], v[58:59] op_sel:[0,1] op_sel_hi:[1,0]
	v_pk_add_f32 v[72:73], v[72:73], v[72:73] op_sel:[0,1] op_sel_hi:[1,0]
	v_pk_fma_f32 v[84:85], v[78:79], v[78:79], v[84:85] op_sel_hi:[1,1,0]
	v_pk_fma_f32 v[86:87], v[56:57], v[56:57], v[86:87] op_sel_hi:[1,1,0]
	v_pk_mul_f32 v[92:93], v[88:89], v[88:89]
	v_pk_mul_f32 v[94:95], v[50:51], v[50:51]
	v_mov_b32_e32 v59, v92
	v_mov_b32_e32 v73, v93
	v_mov_b32_e32 v85, v94
	v_mov_b32_e32 v87, v95
	v_pk_add_f32 v[58:59], v[58:59], v[72:73]
	v_pk_add_f32 v[72:73], v[84:85], v[86:87]
	s_ashr_i32 s11, s10, 31
	v_pk_add_f32 v[58:59], v[58:59], v[72:73]
	s_nop 0
	v_add_f32_e32 v58, v58, v59
	s_nop 1
	v_add_f32_dpp v58, v58, v58 quad_perm:[1,0,3,2] row_mask:0xf bank_mask:0xf bound_ctrl:1
	s_nop 1
	v_add_f32_dpp v58, v58, v58 quad_perm:[2,3,0,1] row_mask:0xf bank_mask:0xf bound_ctrl:1
	s_nop 1
	v_add_f32_dpp v58, v58, v58 row_half_mirror row_mask:0xf bank_mask:0xf bound_ctrl:1
	s_nop 1
	v_add_f32_dpp v58, v58, v58 row_mirror row_mask:0xf bank_mask:0xf bound_ctrl:1
	s_nop 0
	v_readlane_b32 s8, v58, 16
	v_readlane_b32 s9, v58, 48
	v_readlane_b32 s6, v58, 0
	v_readlane_b32 s7, v58, 32
	v_mov_b32_e32 v58, s8
	v_mov_b32_e32 v59, s9
	v_pk_add_f32 v[58:59], s[6:7], v[58:59]
	s_nop 0
	v_add_f32_e32 v58, v58, v59
	v_fmamk_f32 v58, v58, 0x3a000000, v252
	v_mul_f32_e32 v59, 0x4f800000, v58
	v_cmp_gt_f32_e32 vcc, s55, v58
	s_nop 1
	v_cndmask_b32_e32 v58, v58, v59, vcc
	v_sqrt_f32_e32 v59, v58
	s_nop 0
	v_add_u32_e32 v72, -1, v59
	v_fma_f32 v73, -v72, v59, v58
	v_cmp_ge_f32_e64 s[8:9], 0, v73
	v_add_u32_e32 v73, 1, v59
	s_nop 0
	v_cndmask_b32_e64 v72, v59, v72, s[8:9]
	v_fma_f32 v59, -v73, v59, v58
	v_cmp_lt_f32_e64 s[8:9], 0, v59
	s_nop 1
	v_cndmask_b32_e64 v59, v72, v73, s[8:9]
	v_mul_f32_e32 v72, 0x37800000, v59
	v_cndmask_b32_e32 v59, v59, v72, vcc
	v_cmp_class_f32_e32 vcc, v58, v253
	s_nop 1
	v_cndmask_b32_e32 v58, v59, v58, vcc
	v_div_scale_f32 v59, s[6:7], v58, v58, 1.0
	v_rcp_f32_e32 v72, v59
	s_lshl_b64 s[6:7], s[10:11], 12
	v_lshl_add_u64 v[34:35], v[34:35], 0, s[6:7]
	v_lshl_add_u64 v[34:35], v[34:35], 0, v[0:1]
	v_fma_f32 v73, -v59, v72, 1.0
	v_fmac_f32_e32 v72, v73, v72
	v_div_scale_f32 v73, vcc, 1.0, v58, 1.0
	v_mul_f32_e32 v84, v73, v72
	v_fma_f32 v85, -v59, v84, v73
	v_fmac_f32_e32 v84, v85, v72
	v_fma_f32 v59, -v59, v84, v73
	v_div_fmas_f32 v59, v59, v72, v84
	v_div_fixup_f32 v58, v59, v58, 1.0
	v_pk_mul_f32 v[52:53], v[52:53], v[58:59] op_sel_hi:[1,0]
	v_pk_mul_f32 v[46:47], v[46:47], v[58:59] op_sel_hi:[1,0]
	v_lshlrev_b32_e32 v72, 16, v44
	v_and_b32_e32 v73, 0xffff0000, v44
	v_lshlrev_b32_e32 v44, 16, v45
	v_and_b32_e32 v45, 0xffff0000, v45
	v_pk_mul_f32 v[2:3], v[2:3], v[46:47]
	v_pk_mul_f32 v[4:5], v[4:5], v[52:53]
	v_pk_mul_f32 v[2:3], v[2:3], v[72:73]
	v_pk_mul_f32 v[4:5], v[4:5], v[44:45]
	v_cvt_pk_bf16_f32 v2, v2, v3
	v_cvt_pk_bf16_f32 v3, v4, v5
	global_store_dwordx2 v[34:35], v[2:3], off nt
	v_lshlrev_b32_e32 v2, 16, v40
	v_and_b32_e32 v3, 0xffff0000, v40
	v_lshlrev_b32_e32 v4, 16, v41
	v_and_b32_e32 v5, 0xffff0000, v41
	v_pk_mul_f32 v[40:41], v[48:49], v[58:59] op_sel_hi:[1,0]
	v_pk_mul_f32 v[42:43], v[42:43], v[58:59] op_sel_hi:[1,0]
	v_pk_mul_f32 v[8:9], v[8:9], v[40:41]
	v_pk_mul_f32 v[6:7], v[6:7], v[42:43]
	v_pk_mul_f32 v[4:5], v[8:9], v[4:5]
	v_pk_mul_f32 v[2:3], v[6:7], v[2:3]
	v_pk_mul_f32 v[6:7], v[60:61], v[58:59] op_sel_hi:[1,0]
	v_cvt_pk_bf16_f32 v2, v2, v3
	v_cvt_pk_bf16_f32 v3, v4, v5
	v_pk_mul_f32 v[8:9], v[54:55], v[58:59] op_sel_hi:[1,0]
	global_store_dwordx2 v[34:35], v[2:3], off offset:512 nt
	v_lshlrev_b32_e32 v2, 16, v38
	v_and_b32_e32 v3, 0xffff0000, v38
	v_lshlrev_b32_e32 v4, 16, v39
	v_and_b32_e32 v5, 0xffff0000, v39
	v_pk_mul_f32 v[8:9], v[10:11], v[8:9]
	v_pk_mul_f32 v[6:7], v[12:13], v[6:7]
	v_pk_mul_f32 v[2:3], v[8:9], v[2:3]
	v_pk_mul_f32 v[4:5], v[6:7], v[4:5]
	v_cvt_pk_bf16_f32 v2, v2, v3
	v_cvt_pk_bf16_f32 v3, v4, v5
	v_pk_mul_f32 v[6:7], v[70:71], v[58:59] op_sel_hi:[1,0]
	v_pk_mul_f32 v[8:9], v[66:67], v[58:59] op_sel_hi:[1,0]
	global_store_dwordx2 v[34:35], v[2:3], off offset:1024 nt
	v_lshlrev_b32_e32 v2, 16, v36
	v_and_b32_e32 v3, 0xffff0000, v36
	v_lshlrev_b32_e32 v4, 16, v37
	v_and_b32_e32 v5, 0xffff0000, v37
	v_pk_mul_f32 v[8:9], v[14:15], v[8:9]
	v_pk_mul_f32 v[6:7], v[16:17], v[6:7]
	v_pk_mul_f32 v[2:3], v[8:9], v[2:3]
	v_pk_mul_f32 v[4:5], v[6:7], v[4:5]
	v_cvt_pk_bf16_f32 v2, v2, v3
	v_cvt_pk_bf16_f32 v3, v4, v5
	v_pk_mul_f32 v[6:7], v[82:83], v[58:59] op_sel_hi:[1,0]
	v_pk_mul_f32 v[8:9], v[80:81], v[58:59] op_sel_hi:[1,0]
	global_store_dwordx2 v[34:35], v[2:3], off offset:1536 nt
	s_waitcnt vmcnt(23)
; template <bool HG>
; __device__ __forceinline__ void readout_phase2(const Args& a, Frame& F, const float* gain, int nrows) {
;     ...
;     if (cx) RO_FINISH(f2, b2, g2, ML + nw);
	v_lshlrev_b32_e32 v2, 16, v90
	v_and_b32_e32 v3, 0xffff0000, v90
	v_lshlrev_b32_e32 v4, 16, v91
	v_and_b32_e32 v5, 0xffff0000, v91
	v_pk_mul_f32 v[8:9], v[18:19], v[8:9]
	v_pk_mul_f32 v[6:7], v[20:21], v[6:7]
	v_pk_mul_f32 v[2:3], v[8:9], v[2:3]
	v_pk_mul_f32 v[4:5], v[6:7], v[4:5]
	v_cvt_pk_bf16_f32 v2, v2, v3
	v_cvt_pk_bf16_f32 v3, v4, v5
	v_pk_mul_f32 v[6:7], v[62:63], v[58:59] op_sel_hi:[1,0]
	v_pk_mul_f32 v[8:9], v[64:65], v[58:59] op_sel_hi:[1,0]
	global_store_dwordx2 v[34:35], v[2:3], off offset:2048 nt
	s_waitcnt vmcnt(23)
	v_lshlrev_b32_e32 v2, 16, v76
	v_and_b32_e32 v3, 0xffff0000, v76
	v_lshlrev_b32_e32 v4, 16, v77
	v_and_b32_e32 v5, 0xffff0000, v77
	v_pk_mul_f32 v[8:9], v[22:23], v[8:9]
	v_pk_mul_f32 v[6:7], v[24:25], v[6:7]
	v_pk_mul_f32 v[2:3], v[8:9], v[2:3]
	v_pk_mul_f32 v[4:5], v[6:7], v[4:5]
	v_cvt_pk_bf16_f32 v2, v2, v3
	v_cvt_pk_bf16_f32 v3, v4, v5
	v_pk_mul_f32 v[6:7], v[56:57], v[58:59] op_sel_hi:[1,0]
	v_pk_mul_f32 v[8:9], v[78:79], v[58:59] op_sel_hi:[1,0]
	global_store_dwordx2 v[34:35], v[2:3], off offset:2560 nt
	s_waitcnt vmcnt(23)
	v_lshlrev_b32_e32 v2, 16, v74
	v_and_b32_e32 v3, 0xffff0000, v74
	v_lshlrev_b32_e32 v4, 16, v75
	v_and_b32_e32 v5, 0xffff0000, v75
	v_pk_mul_f32 v[8:9], v[26:27], v[8:9]
	v_pk_mul_f32 v[6:7], v[28:29], v[6:7]
	v_pk_mul_f32 v[2:3], v[8:9], v[2:3]
	v_pk_mul_f32 v[4:5], v[6:7], v[4:5]
	v_cvt_pk_bf16_f32 v2, v2, v3
	v_cvt_pk_bf16_f32 v3, v4, v5
	v_pk_mul_f32 v[6:7], v[50:51], v[58:59] op_sel_hi:[1,0]
	v_pk_mul_f32 v[8:9], v[88:89], v[58:59] op_sel_hi:[1,0]
	global_store_dwordx2 v[34:35], v[2:3], off offset:3072 nt
	s_waitcnt vmcnt(23)
	v_lshlrev_b32_e32 v2, 16, v68
	v_and_b32_e32 v3, 0xffff0000, v68
	v_lshlrev_b32_e32 v4, 16, v69
	v_and_b32_e32 v5, 0xffff0000, v69
	v_pk_mul_f32 v[8:9], v[30:31], v[8:9]
	v_pk_mul_f32 v[6:7], v[32:33], v[6:7]
	v_pk_mul_f32 v[2:3], v[8:9], v[2:3]
	v_pk_mul_f32 v[4:5], v[6:7], v[4:5]
	v_cvt_pk_bf16_f32 v2, v2, v3
	v_cvt_pk_bf16_f32 v3, v4, v5
	global_store_dwordx2 v[34:35], v[2:3], off offset:3584 nt

; __device__ __forceinline__ int mk_tid() { return mk_wave() * 64 + mk_lane(); }
; #define LAS __attribute__((address_space(3)))
; __device__ __forceinline__ void relaunder(Frame& F) { int t = mk_tid(); asm volatile("" : "+v"(t)); F.tid = t; F.lane = t & 63; F.wave = __builtin_amdgcn_readfirstlane(t >> 6); }
; template <bool HG>
; __device__ __forceinline__ void readout_phase2(const Args& a, Frame& F, const float* gain, int nrows) {
;     relaunder(F);
;     const int nw = F.vcu * NWAVES + F.wave;
;     const bf16* OF = (const bf16*)(a.ws + WS_OF); const bf16* OB = (const bf16*)(a.ws + WS_OB);
;     const bf16* G = (const bf16*)(a.ws + WS_ACT) + (size_t)(HG ? 6 : 3) * ACT_STRIDE; bf16* HN = (bf16*)(a.ws + WS_HN);
;     LAS float* GL = (LAS float*)F.lds;
;     v2u f0[8], b0[8], g0[8], f1[8], b1[8], g1[8], f2[8], b2[8], g2[8];
;     ...
;     RO_LOAD(f0, b0, g0, nw); RO_LOAD(f1, b1, g1, nw + 2048); RO_LOAD(f2, b2, g2, nw + 2 * 2048);
.LBB0_861:
	s_andn2_b64 vcc, exec, s[6:7]
	s_cbranch_vccnz .LBB0_864
	s_getreg_b32 s6, hwreg(HW_REG_HW_ID, 0, 6)
	s_lshl_b32 s6, s6, 2
	s_add_i32 s6, s6, 0
	s_add_i32 s6, s6, 0x20540
	v_mov_b32_e32 v0, s6
	ds_read_b32 v0, v0
	v_mov_b64_e32 v[2:3], s[0:1]
	s_waitcnt lgkmcnt(0)
	v_readfirstlane_b32 s6, v0
	v_mbcnt_lo_u32_b32 v0, -1, 0
	v_mbcnt_hi_u32_b32 v0, -1, v0
	s_nop 1
	v_lshl_add_u32 v0, s6, 6, v0
	v_mov_b32_e32 v2, s72
	v_mov_b32_e32 v3, s73
	v_readfirstlane_b32 s6, v0
	s_ashr_i32 s6, s6, 6
	s_add_i32 s8, s6, s91
	s_mov_b64 s[6:7], 0x2ac00000
	s_ashr_i32 s9, s8, 31
	v_and_b32_e32 v12, 63, v0
	s_lshl_b64 s[10:11], s[8:9], 12
	v_lshlrev_b32_e32 v0, 3, v12
	s_add_u32 s16, s10, 0x800000
	s_addc_u32 s17, s11, 0
	s_add_u32 s12, s10, 0x1000000
	s_addc_u32 s13, s11, 0
	s_waitcnt vmcnt(0) lgkmcnt(0)
	v_lshl_add_u64 v[4:5], v[2:3], 0, s[6:7]
	s_mov_b64 s[6:7], 0x33400000
	v_lshl_add_u64 v[6:7], v[2:3], 0, s[6:7]
	s_mov_b64 s[6:7], 0x19c00000
	v_lshl_add_u64 v[8:9], v[2:3], 0, s[6:7]
	v_lshl_add_u64 v[10:11], v[4:5], 0, s[10:11]
	v_lshl_add_u64 v[10:11], v[10:11], 0, v[0:1]
	v_lshl_add_u64 v[12:13], v[6:7], 0, s[10:11]
	v_lshl_add_u64 v[14:15], v[8:9], 0, s[10:11]
	v_lshl_add_u64 v[12:13], v[12:13], 0, v[0:1]
	v_lshl_add_u64 v[14:15], v[14:15], 0, v[0:1]
	global_load_dwordx2 v[152:153], v[10:11], off nt
	global_load_dwordx2 v[150:151], v[12:13], off nt
	global_load_dwordx2 v[64:65], v[14:15], off nt
	global_load_dwordx2 v[148:149], v[10:11], off offset:512 nt
	global_load_dwordx2 v[142:143], v[12:13], off offset:512 nt
	global_load_dwordx2 v[58:59], v[14:15], off offset:512 nt
	global_load_dwordx2 v[136:137], v[10:11], off offset:1024 nt
	global_load_dwordx2 v[130:131], v[12:13], off offset:1024 nt
	global_load_dwordx2 v[52:53], v[14:15], off offset:1024 nt
	global_load_dwordx2 v[126:127], v[10:11], off offset:1536 nt
	global_load_dwordx2 v[122:123], v[12:13], off offset:1536 nt
	global_load_dwordx2 v[46:47], v[14:15], off offset:1536 nt
	global_load_dwordx2 v[118:119], v[10:11], off offset:2048 nt
	global_load_dwordx2 v[114:115], v[12:13], off offset:2048 nt
	global_load_dwordx2 v[40:41], v[14:15], off offset:2048 nt
	global_load_dwordx2 v[110:111], v[10:11], off offset:2560 nt
	global_load_dwordx2 v[106:107], v[12:13], off offset:2560 nt
	global_load_dwordx2 v[24:25], v[14:15], off offset:2560 nt
	global_load_dwordx2 v[102:103], v[10:11], off offset:3072 nt
	global_load_dwordx2 v[98:99], v[12:13], off offset:3072 nt
	global_load_dwordx2 v[20:21], v[14:15], off offset:3072 nt
	global_load_dwordx2 v[94:95], v[10:11], off offset:3584 nt
	global_load_dwordx2 v[90:91], v[12:13], off offset:3584 nt
	global_load_dwordx2 v[16:17], v[14:15], off offset:3584 nt
	v_lshl_add_u64 v[10:11], v[4:5], 0, s[16:17]
	v_lshl_add_u64 v[10:11], v[10:11], 0, v[0:1]
	v_lshl_add_u64 v[12:13], v[6:7], 0, s[16:17]
	v_lshl_add_u64 v[14:15], v[8:9], 0, s[16:17]
	v_lshl_add_u64 v[12:13], v[12:13], 0, v[0:1]
	v_lshl_add_u64 v[14:15], v[14:15], 0, v[0:1]
	global_load_dwordx2 v[146:147], v[10:11], off nt
	global_load_dwordx2 v[144:145], v[12:13], off nt
	global_load_dwordx2 v[66:67], v[14:15], off nt
	global_load_dwordx2 v[140:141], v[10:11], off offset:512 nt
	global_load_dwordx2 v[138:139], v[12:13], off offset:512 nt
	global_load_dwordx2 v[60:61], v[14:15], off offset:512 nt
	global_load_dwordx2 v[134:135], v[10:11], off offset:1024 nt
	global_load_dwordx2 v[132:133], v[12:13], off offset:1024 nt
	global_load_dwordx2 v[54:55], v[14:15], off offset:1024 nt
	global_load_dwordx2 v[128:129], v[10:11], off offset:1536 nt
	global_load_dwordx2 v[124:125], v[12:13], off offset:1536 nt
	global_load_dwordx2 v[48:49], v[14:15], off offset:1536 nt
	global_load_dwordx2 v[120:121], v[10:11], off offset:2048 nt
	global_load_dwordx2 v[116:117], v[12:13], off offset:2048 nt
	global_load_dwordx2 v[42:43], v[14:15], off offset:2048 nt
	global_load_dwordx2 v[112:113], v[10:11], off offset:2560 nt
	global_load_dwordx2 v[108:109], v[12:13], off offset:2560 nt
	global_load_dwordx2 v[36:37], v[14:15], off offset:2560 nt
	global_load_dwordx2 v[104:105], v[10:11], off offset:3072 nt
	global_load_dwordx2 v[100:101], v[12:13], off offset:3072 nt
	global_load_dwordx2 v[32:33], v[14:15], off offset:3072 nt
	global_load_dwordx2 v[96:97], v[10:11], off offset:3584 nt
	global_load_dwordx2 v[92:93], v[12:13], off offset:3584 nt
	global_load_dwordx2 v[28:29], v[14:15], off offset:3584 nt
	v_lshl_add_u64 v[10:11], v[4:5], 0, s[12:13]
	v_lshl_add_u64 v[38:39], v[10:11], 0, v[0:1]
	v_lshl_add_u64 v[10:11], v[6:7], 0, s[12:13]
	v_lshl_add_u64 v[12:13], v[8:9], 0, s[12:13]
	v_lshl_add_u64 v[10:11], v[10:11], 0, v[0:1]
	v_lshl_add_u64 v[154:155], v[12:13], 0, v[0:1]
	global_load_dwordx2 v[88:89], v[38:39], off nt
	global_load_dwordx2 v[86:87], v[10:11], off nt
	global_load_dwordx2 v[34:35], v[154:155], off nt
	global_load_dwordx2 v[84:85], v[38:39], off offset:512 nt
	global_load_dwordx2 v[82:83], v[10:11], off offset:512 nt
	global_load_dwordx2 v[30:31], v[154:155], off offset:512 nt
	global_load_dwordx2 v[80:81], v[38:39], off offset:1024 nt
	global_load_dwordx2 v[78:79], v[10:11], off offset:1024 nt
	global_load_dwordx2 v[26:27], v[154:155], off offset:1024 nt
	global_load_dwordx2 v[74:75], v[38:39], off offset:1536 nt
	global_load_dwordx2 v[76:77], v[10:11], off offset:1536 nt
	global_load_dwordx2 v[22:23], v[154:155], off offset:1536 nt
	global_load_dwordx2 v[72:73], v[38:39], off offset:2048 nt
	global_load_dwordx2 v[70:71], v[10:11], off offset:2048 nt
	global_load_dwordx2 v[18:19], v[154:155], off offset:2048 nt
	global_load_dwordx2 v[68:69], v[38:39], off offset:2560 nt
	global_load_dwordx2 v[62:63], v[10:11], off offset:2560 nt
	global_load_dwordx2 v[14:15], v[154:155], off offset:2560 nt
	global_load_dwordx2 v[56:57], v[38:39], off offset:3072 nt
	global_load_dwordx2 v[50:51], v[10:11], off offset:3072 nt
	global_load_dwordx2 v[12:13], v[154:155], off offset:3072 nt
	s_nop 0
	global_load_dwordx2 v[38:39], v[38:39], off offset:3584 nt
	s_nop 0
	global_load_dwordx2 v[44:45], v[10:11], off offset:3584 nt
	s_nop 0
	global_load_dwordx2 v[10:11], v[154:155], off offset:3584 nt
	s_mov_b64 s[6:7], 0x8c00000
	v_lshl_add_u64 v[2:3], v[2:3], 0, s[6:7]
	s_waitcnt vmcnt(62)
	v_lshlrev_b32_e32 v154, 16, v152
	v_and_b32_e32 v155, 0xffff0000, v152
	v_lshlrev_b32_e32 v156, 16, v150
	v_and_b32_e32 v157, 0xffff0000, v150
	v_lshlrev_b32_e32 v152, 16, v153
	v_and_b32_e32 v153, 0xffff0000, v153
	v_lshlrev_b32_e32 v150, 16, v151
	v_and_b32_e32 v151, 0xffff0000, v151
	v_pk_add_f32 v[154:155], v[154:155], v[156:157]
	v_pk_add_f32 v[152:153], v[152:153], v[150:151]
	v_mov_b32_e32 v156, v155
	v_mov_b32_e32 v157, v153
	v_mov_b32_e32 v150, v154
	v_mov_b32_e32 v151, v152
	v_pk_mul_f32 v[156:157], v[156:157], v[156:157]
	s_waitcnt vmcnt(49)
	v_lshlrev_b32_e32 v162, 16, v90
	v_pk_fma_f32 v[150:151], v[150:151], v[150:151], v[156:157]
	v_lshlrev_b32_e32 v156, 16, v142
	v_add_f32_e32 v161, v150, v151
	v_lshlrev_b32_e32 v150, 16, v148
	v_and_b32_e32 v151, 0xffff0000, v148
	v_and_b32_e32 v157, 0xffff0000, v142
	v_lshlrev_b32_e32 v148, 16, v149
	v_and_b32_e32 v149, 0xffff0000, v149
	v_lshlrev_b32_e32 v142, 16, v143
	v_and_b32_e32 v143, 0xffff0000, v143
	v_pk_add_f32 v[150:151], v[150:151], v[156:157]
	v_pk_add_f32 v[148:149], v[148:149], v[142:143]
	v_mov_b32_e32 v156, v151
	v_mov_b32_e32 v157, v149
	v_mov_b32_e32 v142, v150
	v_mov_b32_e32 v143, v148
	v_pk_mul_f32 v[156:157], v[156:157], v[156:157]
	v_add_f32_dpp v161, v161, v161 quad_perm:[1,0,3,2] row_mask:0xf bank_mask:0xf bound_ctrl:1
	v_pk_fma_f32 v[142:143], v[142:143], v[142:143], v[156:157]
	v_lshlrev_b32_e32 v156, 16, v130
	v_add_f32_e32 v166, v142, v143
	v_lshlrev_b32_e32 v142, 16, v136
	v_and_b32_e32 v143, 0xffff0000, v136
	v_and_b32_e32 v157, 0xffff0000, v130
	v_lshlrev_b32_e32 v136, 16, v137
	v_and_b32_e32 v137, 0xffff0000, v137
	v_lshlrev_b32_e32 v130, 16, v131
	v_and_b32_e32 v131, 0xffff0000, v131
	v_pk_add_f32 v[142:143], v[142:143], v[156:157]
	v_pk_add_f32 v[136:137], v[136:137], v[130:131]
	v_mov_b32_e32 v156, v143
	v_mov_b32_e32 v157, v137
	v_mov_b32_e32 v130, v142
	v_mov_b32_e32 v131, v136
	v_pk_mul_f32 v[156:157], v[156:157], v[156:157]
	v_and_b32_e32 v163, 0xffff0000, v90
	v_pk_fma_f32 v[130:131], v[130:131], v[130:131], v[156:157]
	v_lshlrev_b32_e32 v156, 16, v122
	v_add_f32_e32 v160, v130, v131
	v_lshlrev_b32_e32 v130, 16, v126
	v_and_b32_e32 v131, 0xffff0000, v126
	v_and_b32_e32 v157, 0xffff0000, v122
	v_lshlrev_b32_e32 v126, 16, v127
	v_and_b32_e32 v127, 0xffff0000, v127
	v_lshlrev_b32_e32 v122, 16, v123
	v_and_b32_e32 v123, 0xffff0000, v123
	v_pk_add_f32 v[130:131], v[130:131], v[156:157]
	v_pk_add_f32 v[126:127], v[126:127], v[122:123]
	v_mov_b32_e32 v156, v131
	v_mov_b32_e32 v157, v127
	v_mov_b32_e32 v122, v130
	v_mov_b32_e32 v123, v126
	v_pk_mul_f32 v[156:157], v[156:157], v[156:157]
	v_lshlrev_b32_e32 v90, 16, v91
	v_pk_fma_f32 v[122:123], v[122:123], v[122:123], v[156:157]
	v_lshlrev_b32_e32 v156, 16, v114
	v_add_f32_e32 v167, v122, v123
	v_lshlrev_b32_e32 v122, 16, v118
	v_and_b32_e32 v123, 0xffff0000, v118
	v_and_b32_e32 v157, 0xffff0000, v114
	v_lshlrev_b32_e32 v118, 16, v119
	v_and_b32_e32 v119, 0xffff0000, v119
	v_lshlrev_b32_e32 v114, 16, v115
	v_and_b32_e32 v115, 0xffff0000, v115
	v_pk_add_f32 v[122:123], v[122:123], v[156:157]
	v_pk_add_f32 v[118:119], v[118:119], v[114:115]
	v_mov_b32_e32 v156, v123
	v_mov_b32_e32 v157, v119
	v_mov_b32_e32 v114, v122
	v_mov_b32_e32 v115, v118
	v_pk_mul_f32 v[156:157], v[156:157], v[156:157]
	v_and_b32_e32 v91, 0xffff0000, v91
	v_pk_fma_f32 v[114:115], v[114:115], v[114:115], v[156:157]
	v_lshlrev_b32_e32 v156, 16, v106
	v_add_f32_e32 v159, v114, v115
	v_lshlrev_b32_e32 v114, 16, v110
	v_and_b32_e32 v115, 0xffff0000, v110
	v_and_b32_e32 v157, 0xffff0000, v106
	v_lshlrev_b32_e32 v110, 16, v111
	v_and_b32_e32 v111, 0xffff0000, v111
	v_lshlrev_b32_e32 v106, 16, v107
	v_and_b32_e32 v107, 0xffff0000, v107
	v_pk_add_f32 v[114:115], v[114:115], v[156:157]
	v_pk_add_f32 v[110:111], v[110:111], v[106:107]
	v_mov_b32_e32 v156, v115
	v_mov_b32_e32 v157, v111
	v_mov_b32_e32 v106, v114
	v_mov_b32_e32 v107, v110
	v_pk_mul_f32 v[156:157], v[156:157], v[156:157]
	v_add_f32_dpp v161, v161, v161 quad_perm:[2,3,0,1] row_mask:0xf bank_mask:0xf bound_ctrl:1
	v_pk_fma_f32 v[106:107], v[106:107], v[106:107], v[156:157]
	v_lshlrev_b32_e32 v156, 16, v98
	v_add_f32_e32 v158, v106, v107
	v_lshlrev_b32_e32 v106, 16, v102
	v_and_b32_e32 v107, 0xffff0000, v102
	v_and_b32_e32 v157, 0xffff0000, v98
	v_lshlrev_b32_e32 v102, 16, v103
	v_and_b32_e32 v103, 0xffff0000, v103
	v_lshlrev_b32_e32 v98, 16, v99
	v_and_b32_e32 v99, 0xffff0000, v99
	v_pk_add_f32 v[106:107], v[106:107], v[156:157]
	v_pk_add_f32 v[102:103], v[102:103], v[98:99]
	v_mov_b32_e32 v156, v107
	v_mov_b32_e32 v157, v103
	v_mov_b32_e32 v98, v106
	v_mov_b32_e32 v99, v102
	v_pk_mul_f32 v[156:157], v[156:157], v[156:157]
	v_add_f32_dpp v161, v161, v161 row_half_mirror row_mask:0xf bank_mask:0xf bound_ctrl:1
	v_pk_fma_f32 v[98:99], v[98:99], v[98:99], v[156:157]
	s_nop 0
	v_add_f32_e32 v157, v98, v99
	v_lshlrev_b32_e32 v98, 16, v94
	v_and_b32_e32 v99, 0xffff0000, v94
	v_lshlrev_b32_e32 v94, 16, v95
	v_and_b32_e32 v95, 0xffff0000, v95
	v_pk_add_f32 v[98:99], v[98:99], v[162:163]
	v_pk_add_f32 v[90:91], v[94:95], v[90:91]
	v_mov_b32_e32 v162, v99
	v_mov_b32_e32 v163, v91
	v_add_f32_dpp v161, v161, v161 row_mirror row_mask:0xf bank_mask:0xf bound_ctrl:1
	v_mov_b32_e32 v94, v98
	v_mov_b32_e32 v95, v90
	v_pk_mul_f32 v[162:163], v[162:163], v[162:163]
	v_readlane_b32 s9, v161, 16
	v_readlane_b32 s14, v161, 48
	v_pk_fma_f32 v[94:95], v[94:95], v[94:95], v[162:163]
	v_readlane_b32 s6, v161, 0
	v_readlane_b32 s7, v161, 32
	v_mov_b32_e32 v162, s9
	v_mov_b32_e32 v163, s14
	v_pk_add_f32 v[162:163], s[6:7], v[162:163]
	v_add_f32_e32 v156, v94, v95
	v_add_f32_e32 v161, v162, v163
	v_fmamk_f32 v161, v161, 0x3b800000, v252
	v_cmp_gt_f32_e32 vcc, s55, v161
	v_mul_f32_e32 v162, 0x4f800000, v161
	v_lshl_add_u64 v[94:95], v[2:3], 0, s[10:11]
	v_cndmask_b32_e32 v161, v161, v162, vcc
	v_sqrt_f32_e32 v162, v161
	v_lshl_add_u64 v[94:95], v[94:95], 0, v[0:1]
	v_add_u32_e32 v163, -1, v162
	v_fma_f32 v164, -v163, v162, v161
	v_cmp_ge_f32_e64 s[6:7], 0, v164
	v_add_u32_e32 v164, 1, v162
	s_nop 0
	v_cndmask_b32_e64 v163, v162, v163, s[6:7]
	v_fma_f32 v162, -v164, v162, v161
	v_cmp_lt_f32_e64 s[6:7], 0, v162
	s_nop 1
	v_cndmask_b32_e64 v162, v163, v164, s[6:7]
	v_mul_f32_e32 v163, 0x37800000, v162
	v_cndmask_b32_e32 v162, v162, v163, vcc
	v_cmp_class_f32_e32 vcc, v161, v253
	s_nop 1
	v_cndmask_b32_e32 v161, v162, v161, vcc
	v_div_scale_f32 v162, s[6:7], v161, v161, 1.0
	v_rcp_f32_e32 v163, v162
	s_nop 0
	v_fma_f32 v164, -v162, v163, 1.0
	v_fmac_f32_e32 v163, v164, v163
	v_div_scale_f32 v164, vcc, 1.0, v161, 1.0
	v_mul_f32_e32 v165, v164, v163
	v_fma_f32 v168, -v162, v165, v164
	v_fmac_f32_e32 v165, v168, v163
	v_fma_f32 v162, -v162, v165, v164
	v_div_fmas_f32 v162, v162, v163, v165
	v_div_fixup_f32 v162, v162, v161, 1.0
	v_lshlrev_b32_e32 v164, 16, v64
	v_and_b32_e32 v165, 0xffff0000, v64
	v_lshlrev_b32_e32 v64, 16, v65
	v_and_b32_e32 v65, 0xffff0000, v65
	v_pk_mul_f32 v[154:155], v[154:155], v[162:163] op_sel_hi:[1,0]
	v_pk_mul_f32 v[152:153], v[152:153], v[162:163] op_sel_hi:[1,0]
	s_nop 0
	v_pk_mul_f32 v[64:65], v[152:153], v[64:65]
	v_pk_mul_f32 v[152:153], v[154:155], v[164:165]
	s_nop 0
	v_cvt_pk_bf16_f32 v152, v152, v153
	v_cvt_pk_bf16_f32 v153, v64, v65
	v_add_f32_dpp v64, v166, v166 quad_perm:[1,0,3,2] row_mask:0xf bank_mask:0xf bound_ctrl:1
	global_store_dwordx2 v[94:95], v[152:153], off nt
	s_nop 0
	v_add_f32_dpp v64, v64, v64 quad_perm:[2,3,0,1] row_mask:0xf bank_mask:0xf bound_ctrl:1
	s_nop 1
	v_add_f32_dpp v64, v64, v64 row_half_mirror row_mask:0xf bank_mask:0xf bound_ctrl:1
	s_nop 1
	v_add_f32_dpp v64, v64, v64 row_mirror row_mask:0xf bank_mask:0xf bound_ctrl:1
	s_nop 0
	v_readlane_b32 s9, v64, 16
	v_readlane_b32 s14, v64, 48
	v_readlane_b32 s6, v64, 0
	v_readlane_b32 s7, v64, 32
	v_mov_b32_e32 v64, s9
	v_mov_b32_e32 v65, s14
	v_pk_add_f32 v[64:65], s[6:7], v[64:65]
	s_nop 0
	v_add_f32_e32 v64, v64, v65
	v_fmamk_f32 v64, v64, 0x3b800000, v252
	v_cmp_gt_f32_e32 vcc, s55, v64
	v_mul_f32_e32 v65, 0x4f800000, v64
	s_nop 0
	v_cndmask_b32_e32 v64, v64, v65, vcc
	v_sqrt_f32_e32 v65, v64
	s_nop 0
	v_add_u32_e32 v152, -1, v65
	v_fma_f32 v153, -v152, v65, v64
	v_cmp_ge_f32_e64 s[6:7], 0, v153
	v_add_u32_e32 v153, 1, v65
	s_nop 0
	v_cndmask_b32_e64 v152, v65, v152, s[6:7]
	v_fma_f32 v65, -v153, v65, v64
	v_cmp_lt_f32_e64 s[6:7], 0, v65
	s_nop 1
	v_cndmask_b32_e64 v65, v152, v153, s[6:7]
	v_mul_f32_e32 v152, 0x37800000, v65
	v_cndmask_b32_e32 v65, v65, v152, vcc
	v_cmp_class_f32_e32 vcc, v64, v253
	s_nop 1
	v_cndmask_b32_e32 v64, v65, v64, vcc
	v_div_scale_f32 v65, s[6:7], v64, v64, 1.0
	v_rcp_f32_e32 v152, v65
	s_nop 0
	v_fma_f32 v153, -v65, v152, 1.0
	v_fmac_f32_e32 v152, v153, v152
	v_div_scale_f32 v153, vcc, 1.0, v64, 1.0
	v_mul_f32_e32 v154, v153, v152
	v_fma_f32 v155, -v65, v154, v153
	v_fmac_f32_e32 v154, v155, v152
	v_fma_f32 v65, -v65, v154, v153
	v_div_fmas_f32 v65, v65, v152, v154
	v_div_fixup_f32 v64, v65, v64, 1.0
	v_lshlrev_b32_e32 v152, 16, v58
	v_and_b32_e32 v153, 0xffff0000, v58
	v_lshlrev_b32_e32 v58, 16, v59
	v_and_b32_e32 v59, 0xffff0000, v59
	v_pk_mul_f32 v[150:151], v[150:151], v[64:65] op_sel_hi:[1,0]
	v_pk_mul_f32 v[64:65], v[148:149], v[64:65] op_sel_hi:[1,0]
	s_nop 0
	v_pk_mul_f32 v[58:59], v[64:65], v[58:59]
	v_pk_mul_f32 v[64:65], v[150:151], v[152:153]
	s_waitcnt vmcnt(47)
	v_lshlrev_b32_e32 v152, 16, v144
	v_cvt_pk_bf16_f32 v64, v64, v65
	v_cvt_pk_bf16_f32 v65, v58, v59
	v_add_f32_dpp v58, v160, v160 quad_perm:[1,0,3,2] row_mask:0xf bank_mask:0xf bound_ctrl:1
	global_store_dwordx2 v[94:95], v[64:65], off offset:512 nt
	v_and_b32_e32 v153, 0xffff0000, v144
	v_add_f32_dpp v58, v58, v58 quad_perm:[2,3,0,1] row_mask:0xf bank_mask:0xf bound_ctrl:1
	v_lshlrev_b32_e32 v144, 16, v145
	v_and_b32_e32 v145, 0xffff0000, v145
	v_add_f32_dpp v58, v58, v58 row_half_mirror row_mask:0xf bank_mask:0xf bound_ctrl:1
	s_nop 1
	v_add_f32_dpp v58, v58, v58 row_mirror row_mask:0xf bank_mask:0xf bound_ctrl:1
	s_nop 0
	v_readlane_b32 s9, v58, 16
	v_readlane_b32 s14, v58, 48
	v_readlane_b32 s6, v58, 0
	v_readlane_b32 s7, v58, 32
	v_mov_b32_e32 v58, s9
	v_mov_b32_e32 v59, s14
	v_pk_add_f32 v[58:59], s[6:7], v[58:59]
	s_nop 0
	v_add_f32_e32 v58, v58, v59
	v_fmamk_f32 v58, v58, 0x3b800000, v252
	v_cmp_gt_f32_e32 vcc, s55, v58
	v_mul_f32_e32 v59, 0x4f800000, v58
	s_nop 0
	v_cndmask_b32_e32 v58, v58, v59, vcc
	v_sqrt_f32_e32 v59, v58
	s_nop 0
	v_add_u32_e32 v64, -1, v59
	v_fma_f32 v65, -v64, v59, v58
	v_cmp_ge_f32_e64 s[6:7], 0, v65
	v_add_u32_e32 v65, 1, v59
	s_nop 0
	v_cndmask_b32_e64 v64, v59, v64, s[6:7]
	v_fma_f32 v59, -v65, v59, v58
	v_cmp_lt_f32_e64 s[6:7], 0, v59
	s_nop 1
	v_cndmask_b32_e64 v59, v64, v65, s[6:7]
	v_mul_f32_e32 v64, 0x37800000, v59
	v_cndmask_b32_e32 v59, v59, v64, vcc
	v_cmp_class_f32_e32 vcc, v58, v253
	s_nop 1
	v_cndmask_b32_e32 v58, v59, v58, vcc
	v_div_scale_f32 v59, s[6:7], v58, v58, 1.0
	v_rcp_f32_e32 v64, v59
	s_nop 0
	v_fma_f32 v65, -v59, v64, 1.0
	v_fmac_f32_e32 v64, v65, v64
	v_div_scale_f32 v65, vcc, 1.0, v58, 1.0
	v_mul_f32_e32 v148, v65, v64
	v_fma_f32 v149, -v59, v148, v65
	v_fmac_f32_e32 v148, v149, v64
	v_fma_f32 v59, -v59, v148, v65
	v_div_fmas_f32 v59, v59, v64, v148
	v_div_fixup_f32 v58, v59, v58, 1.0
	v_lshlrev_b32_e32 v64, 16, v52
	v_and_b32_e32 v65, 0xffff0000, v52
	v_lshlrev_b32_e32 v52, 16, v53
	v_and_b32_e32 v53, 0xffff0000, v53
	v_pk_mul_f32 v[142:143], v[142:143], v[58:59] op_sel_hi:[1,0]
	v_pk_mul_f32 v[58:59], v[136:137], v[58:59] op_sel_hi:[1,0]
	s_nop 0
	v_pk_mul_f32 v[52:53], v[58:59], v[52:53]
	v_pk_mul_f32 v[58:59], v[142:143], v[64:65]
	s_nop 0
	v_cvt_pk_bf16_f32 v58, v58, v59
	v_cvt_pk_bf16_f32 v59, v52, v53
	v_add_f32_dpp v52, v167, v167 quad_perm:[1,0,3,2] row_mask:0xf bank_mask:0xf bound_ctrl:1
	global_store_dwordx2 v[94:95], v[58:59], off offset:1024 nt
	s_nop 0
	v_add_f32_dpp v52, v52, v52 quad_perm:[2,3,0,1] row_mask:0xf bank_mask:0xf bound_ctrl:1
	s_nop 1
	v_add_f32_dpp v52, v52, v52 row_half_mirror row_mask:0xf bank_mask:0xf bound_ctrl:1
	s_nop 1
	v_add_f32_dpp v52, v52, v52 row_mirror row_mask:0xf bank_mask:0xf bound_ctrl:1
	s_nop 0
	v_readlane_b32 s9, v52, 16
	v_readlane_b32 s14, v52, 48
	v_readlane_b32 s6, v52, 0
	v_readlane_b32 s7, v52, 32
	v_mov_b32_e32 v52, s9
	v_mov_b32_e32 v53, s14
	v_pk_add_f32 v[52:53], s[6:7], v[52:53]
	s_nop 0
	v_add_f32_e32 v52, v52, v53
	v_fmamk_f32 v52, v52, 0x3b800000, v252
	v_cmp_gt_f32_e32 vcc, s55, v52
	v_mul_f32_e32 v53, 0x4f800000, v52
	s_nop 0
	v_cndmask_b32_e32 v52, v52, v53, vcc
	v_sqrt_f32_e32 v53, v52
	s_nop 0
	v_add_u32_e32 v58, -1, v53
	v_fma_f32 v59, -v58, v53, v52
	v_cmp_ge_f32_e64 s[6:7], 0, v59
	v_add_u32_e32 v59, 1, v53
	s_nop 0
	v_cndmask_b32_e64 v58, v53, v58, s[6:7]
	v_fma_f32 v53, -v59, v53, v52
	v_cmp_lt_f32_e64 s[6:7], 0, v53
	s_nop 1
	v_cndmask_b32_e64 v53, v58, v59, s[6:7]
	v_mul_f32_e32 v58, 0x37800000, v53
	v_cndmask_b32_e32 v53, v53, v58, vcc
	v_cmp_class_f32_e32 vcc, v52, v253
	s_nop 1
	v_cndmask_b32_e32 v52, v53, v52, vcc
	v_div_scale_f32 v53, s[6:7], v52, v52, 1.0
	v_rcp_f32_e32 v58, v53
	s_nop 0
	v_fma_f32 v59, -v53, v58, 1.0
	v_fmac_f32_e32 v58, v59, v58
	v_div_scale_f32 v59, vcc, 1.0, v52, 1.0
	v_mul_f32_e32 v64, v59, v58
	v_fma_f32 v65, -v53, v64, v59
	v_fmac_f32_e32 v64, v65, v58
	v_fma_f32 v53, -v53, v64, v59
	v_div_fmas_f32 v53, v53, v58, v64
	v_div_fixup_f32 v52, v53, v52, 1.0
	v_lshlrev_b32_e32 v58, 16, v46
	v_and_b32_e32 v59, 0xffff0000, v46
	v_lshlrev_b32_e32 v46, 16, v47
	v_and_b32_e32 v47, 0xffff0000, v47
	v_pk_mul_f32 v[64:65], v[130:131], v[52:53] op_sel_hi:[1,0]
	v_pk_mul_f32 v[52:53], v[126:127], v[52:53] op_sel_hi:[1,0]
	s_nop 0
	v_pk_mul_f32 v[46:47], v[52:53], v[46:47]
	v_pk_mul_f32 v[52:53], v[64:65], v[58:59]
	s_nop 0
	v_cvt_pk_bf16_f32 v52, v52, v53
	v_cvt_pk_bf16_f32 v53, v46, v47
	v_add_f32_dpp v46, v159, v159 quad_perm:[1,0,3,2] row_mask:0xf bank_mask:0xf bound_ctrl:1
	global_store_dwordx2 v[94:95], v[52:53], off offset:1536 nt
	s_waitcnt vmcnt(29)
	v_and_b32_e32 v159, 0xffff0000, v92
	v_add_f32_dpp v46, v46, v46 quad_perm:[2,3,0,1] row_mask:0xf bank_mask:0xf bound_ctrl:1
	s_nop 1
	v_add_f32_dpp v46, v46, v46 row_half_mirror row_mask:0xf bank_mask:0xf bound_ctrl:1
	s_nop 1
	v_add_f32_dpp v46, v46, v46 row_mirror row_mask:0xf bank_mask:0xf bound_ctrl:1
	s_nop 0
	v_readlane_b32 s9, v46, 16
	v_readlane_b32 s14, v46, 48
	v_readlane_b32 s6, v46, 0
	v_readlane_b32 s7, v46, 32
	v_mov_b32_e32 v46, s9
	v_mov_b32_e32 v47, s14
	v_pk_add_f32 v[46:47], s[6:7], v[46:47]
	s_nop 0
	v_add_f32_e32 v46, v46, v47
	v_fmamk_f32 v46, v46, 0x3b800000, v252
	v_cmp_gt_f32_e32 vcc, s55, v46
	v_mul_f32_e32 v47, 0x4f800000, v46
	s_nop 0
	v_cndmask_b32_e32 v46, v46, v47, vcc
	v_sqrt_f32_e32 v47, v46
	s_nop 0
	v_add_u32_e32 v52, -1, v47
	v_fma_f32 v53, -v52, v47, v46
	v_cmp_ge_f32_e64 s[6:7], 0, v53
	v_add_u32_e32 v53, 1, v47
	s_nop 0
	v_cndmask_b32_e64 v52, v47, v52, s[6:7]
	v_fma_f32 v47, -v53, v47, v46
	v_cmp_lt_f32_e64 s[6:7], 0, v47
	s_nop 1
	v_cndmask_b32_e64 v47, v52, v53, s[6:7]
	v_mul_f32_e32 v52, 0x37800000, v47
	v_cndmask_b32_e32 v47, v47, v52, vcc
	v_cmp_class_f32_e32 vcc, v46, v253
	s_nop 1
	v_cndmask_b32_e32 v46, v47, v46, vcc
	v_div_scale_f32 v47, s[6:7], v46, v46, 1.0
	v_rcp_f32_e32 v52, v47
	s_nop 0
	v_fma_f32 v53, -v47, v52, 1.0
	v_fmac_f32_e32 v52, v53, v52
	v_div_scale_f32 v53, vcc, 1.0, v46, 1.0
	v_mul_f32_e32 v58, v53, v52
	v_fma_f32 v59, -v47, v58, v53
	v_fmac_f32_e32 v58, v59, v52
	v_fma_f32 v47, -v47, v58, v53
	v_div_fmas_f32 v47, v47, v52, v58
	v_div_fixup_f32 v46, v47, v46, 1.0
	v_lshlrev_b32_e32 v52, 16, v40
	v_and_b32_e32 v53, 0xffff0000, v40
	v_lshlrev_b32_e32 v40, 16, v41
	v_and_b32_e32 v41, 0xffff0000, v41
	v_pk_mul_f32 v[58:59], v[122:123], v[46:47] op_sel_hi:[1,0]
	v_pk_mul_f32 v[46:47], v[118:119], v[46:47] op_sel_hi:[1,0]
	s_nop 0
	v_pk_mul_f32 v[40:41], v[46:47], v[40:41]
	v_pk_mul_f32 v[46:47], v[58:59], v[52:53]
	s_nop 0
	v_cvt_pk_bf16_f32 v46, v46, v47
	v_cvt_pk_bf16_f32 v47, v40, v41
	v_add_f32_dpp v40, v158, v158 quad_perm:[1,0,3,2] row_mask:0xf bank_mask:0xf bound_ctrl:1
	global_store_dwordx2 v[94:95], v[46:47], off offset:2048 nt
	v_lshlrev_b32_e32 v158, 16, v92
	v_add_f32_dpp v40, v40, v40 quad_perm:[2,3,0,1] row_mask:0xf bank_mask:0xf bound_ctrl:1
	v_lshlrev_b32_e32 v92, 16, v93
	v_and_b32_e32 v93, 0xffff0000, v93
	v_add_f32_dpp v40, v40, v40 row_half_mirror row_mask:0xf bank_mask:0xf bound_ctrl:1
	s_nop 1
	v_add_f32_dpp v40, v40, v40 row_mirror row_mask:0xf bank_mask:0xf bound_ctrl:1
	s_nop 0
	v_readlane_b32 s9, v40, 16
	v_readlane_b32 s14, v40, 48
	v_readlane_b32 s6, v40, 0
	v_readlane_b32 s7, v40, 32
	v_mov_b32_e32 v40, s9
	v_mov_b32_e32 v41, s14
	v_pk_add_f32 v[40:41], s[6:7], v[40:41]
	s_nop 0
	v_add_f32_e32 v40, v40, v41
	v_fmamk_f32 v40, v40, 0x3b800000, v252
	v_cmp_gt_f32_e32 vcc, s55, v40
	v_mul_f32_e32 v41, 0x4f800000, v40
	s_nop 0
	v_cndmask_b32_e32 v40, v40, v41, vcc
	v_sqrt_f32_e32 v41, v40
	s_nop 0
	v_add_u32_e32 v46, -1, v41
	v_fma_f32 v47, -v46, v41, v40
; template <bool HG>
; __device__ __forceinline__ void readout_phase2(const Args& a, Frame& F, const float* gain, int nrows) {
;     ...
;     RO_FINISH(f0, b0, g0, nw);            RO_LOAD(f0, b0, g0, nw + 3 * 2048);
	v_cmp_ge_f32_e64 s[6:7], 0, v47
	v_add_u32_e32 v47, 1, v41
	s_nop 0
	v_cndmask_b32_e64 v46, v41, v46, s[6:7]
	v_fma_f32 v41, -v47, v41, v40
	v_cmp_lt_f32_e64 s[6:7], 0, v41
	s_nop 1
	v_cndmask_b32_e64 v41, v46, v47, s[6:7]
	v_mul_f32_e32 v46, 0x37800000, v41
	v_cndmask_b32_e32 v41, v41, v46, vcc
	v_cmp_class_f32_e32 vcc, v40, v253
	s_nop 1
	v_cndmask_b32_e32 v40, v41, v40, vcc
	v_div_scale_f32 v41, s[6:7], v40, v40, 1.0
	v_rcp_f32_e32 v46, v41
	s_nop 0
	v_fma_f32 v47, -v41, v46, 1.0
	v_fmac_f32_e32 v46, v47, v46
	v_div_scale_f32 v47, vcc, 1.0, v40, 1.0
	v_mul_f32_e32 v52, v47, v46
	v_fma_f32 v53, -v41, v52, v47
	v_fmac_f32_e32 v52, v53, v46
	v_fma_f32 v41, -v41, v52, v47
	v_div_fmas_f32 v41, v41, v46, v52
	v_div_fixup_f32 v40, v41, v40, 1.0
	v_lshlrev_b32_e32 v46, 16, v24
	v_and_b32_e32 v47, 0xffff0000, v24
	v_lshlrev_b32_e32 v24, 16, v25
	v_and_b32_e32 v25, 0xffff0000, v25
	v_pk_mul_f32 v[52:53], v[114:115], v[40:41] op_sel_hi:[1,0]
	v_pk_mul_f32 v[40:41], v[110:111], v[40:41] op_sel_hi:[1,0]
	s_nop 0
	v_pk_mul_f32 v[24:25], v[40:41], v[24:25]
	v_pk_mul_f32 v[40:41], v[52:53], v[46:47]
	s_nop 0
	v_cvt_pk_bf16_f32 v40, v40, v41
	v_cvt_pk_bf16_f32 v41, v24, v25
	v_add_f32_dpp v24, v157, v157 quad_perm:[1,0,3,2] row_mask:0xf bank_mask:0xf bound_ctrl:1
	global_store_dwordx2 v[94:95], v[40:41], off offset:2560 nt
	s_nop 0
	v_add_f32_dpp v24, v24, v24 quad_perm:[2,3,0,1] row_mask:0xf bank_mask:0xf bound_ctrl:1
	s_nop 1
	v_add_f32_dpp v24, v24, v24 row_half_mirror row_mask:0xf bank_mask:0xf bound_ctrl:1
	s_nop 1
	v_add_f32_dpp v24, v24, v24 row_mirror row_mask:0xf bank_mask:0xf bound_ctrl:1
	s_nop 0
	v_readlane_b32 s9, v24, 16
	v_readlane_b32 s14, v24, 48
	v_readlane_b32 s6, v24, 0
	v_readlane_b32 s7, v24, 32
	v_mov_b32_e32 v24, s9
	v_mov_b32_e32 v25, s14
	v_pk_add_f32 v[24:25], s[6:7], v[24:25]
	s_nop 0
	v_add_f32_e32 v24, v24, v25
	v_fmamk_f32 v24, v24, 0x3b800000, v252
	v_cmp_gt_f32_e32 vcc, s55, v24
	v_mul_f32_e32 v25, 0x4f800000, v24
	s_nop 0
	v_cndmask_b32_e32 v24, v24, v25, vcc
	v_sqrt_f32_e32 v25, v24
	s_nop 0
	v_add_u32_e32 v40, -1, v25
	v_fma_f32 v41, -v40, v25, v24
	v_cmp_ge_f32_e64 s[6:7], 0, v41
	v_add_u32_e32 v41, 1, v25
	s_nop 0
	v_cndmask_b32_e64 v40, v25, v40, s[6:7]
	v_fma_f32 v25, -v41, v25, v24
	v_cmp_lt_f32_e64 s[6:7], 0, v25
	s_nop 1
	v_cndmask_b32_e64 v25, v40, v41, s[6:7]
	v_mul_f32_e32 v40, 0x37800000, v25
	v_cndmask_b32_e32 v25, v25, v40, vcc
	v_cmp_class_f32_e32 vcc, v24, v253
	s_nop 1
	v_cndmask_b32_e32 v24, v25, v24, vcc
	v_div_scale_f32 v25, s[6:7], v24, v24, 1.0
	v_rcp_f32_e32 v40, v25
	s_nop 0
	v_fma_f32 v41, -v25, v40, 1.0
	v_fmac_f32_e32 v40, v41, v40
	v_div_scale_f32 v41, vcc, 1.0, v24, 1.0
	v_mul_f32_e32 v46, v41, v40
	v_fma_f32 v47, -v25, v46, v41
	v_fmac_f32_e32 v46, v47, v40
	v_fma_f32 v25, -v25, v46, v41
	v_div_fmas_f32 v25, v25, v40, v46
	v_div_fixup_f32 v24, v25, v24, 1.0
	v_lshlrev_b32_e32 v40, 16, v20
	v_and_b32_e32 v41, 0xffff0000, v20
	v_lshlrev_b32_e32 v20, 16, v21
	v_and_b32_e32 v21, 0xffff0000, v21
	v_pk_mul_f32 v[46:47], v[106:107], v[24:25] op_sel_hi:[1,0]
	v_pk_mul_f32 v[24:25], v[102:103], v[24:25] op_sel_hi:[1,0]
	s_nop 0
	v_pk_mul_f32 v[20:21], v[24:25], v[20:21]
	v_pk_mul_f32 v[24:25], v[46:47], v[40:41]
	s_nop 0
	v_cvt_pk_bf16_f32 v24, v24, v25
	v_cvt_pk_bf16_f32 v25, v20, v21
	v_add_f32_dpp v20, v156, v156 quad_perm:[1,0,3,2] row_mask:0xf bank_mask:0xf bound_ctrl:1
	global_store_dwordx2 v[94:95], v[24:25], off offset:3072 nt
	s_nop 0
	v_add_f32_dpp v20, v20, v20 quad_perm:[2,3,0,1] row_mask:0xf bank_mask:0xf bound_ctrl:1
	s_nop 1
	v_add_f32_dpp v20, v20, v20 row_half_mirror row_mask:0xf bank_mask:0xf bound_ctrl:1
	s_nop 1
	v_add_f32_dpp v20, v20, v20 row_mirror row_mask:0xf bank_mask:0xf bound_ctrl:1
	s_nop 0
	v_readlane_b32 s9, v20, 16
	v_readlane_b32 s14, v20, 48
	v_readlane_b32 s6, v20, 0
	v_readlane_b32 s7, v20, 32
	v_mov_b32_e32 v20, s9
	v_mov_b32_e32 v21, s14
	v_pk_add_f32 v[20:21], s[6:7], v[20:21]
	s_add_u32 s14, s10, 0x1800000
	v_add_f32_e32 v20, v20, v21
	v_fmamk_f32 v20, v20, 0x3b800000, v252
	v_cmp_gt_f32_e32 vcc, s55, v20
	v_mul_f32_e32 v21, 0x4f800000, v20
	s_addc_u32 s15, s11, 0
	v_cndmask_b32_e32 v20, v20, v21, vcc
	v_sqrt_f32_e32 v21, v20
	s_nop 0
	v_add_u32_e32 v24, -1, v21
	v_fma_f32 v25, -v24, v21, v20
	v_cmp_ge_f32_e64 s[6:7], 0, v25
	v_add_u32_e32 v25, 1, v21
	s_nop 0
	v_cndmask_b32_e64 v24, v21, v24, s[6:7]
	v_fma_f32 v21, -v25, v21, v20
	v_cmp_lt_f32_e64 s[6:7], 0, v21
	s_nop 1
	v_cndmask_b32_e64 v21, v24, v25, s[6:7]
	v_mul_f32_e32 v24, 0x37800000, v21
	v_cndmask_b32_e32 v21, v21, v24, vcc
	v_cmp_class_f32_e32 vcc, v20, v253
	s_nop 1
	v_cndmask_b32_e32 v20, v21, v20, vcc
	v_div_scale_f32 v21, s[6:7], v20, v20, 1.0
	v_rcp_f32_e32 v24, v21
	s_nop 0
	v_fma_f32 v25, -v21, v24, 1.0
	v_fmac_f32_e32 v24, v25, v24
	v_div_scale_f32 v25, vcc, 1.0, v20, 1.0
	v_mul_f32_e32 v40, v25, v24
	v_fma_f32 v41, -v21, v40, v25
	v_fmac_f32_e32 v40, v41, v24
	v_fma_f32 v21, -v21, v40, v25
	v_div_fmas_f32 v21, v21, v24, v40
	v_div_fixup_f32 v20, v21, v20, 1.0
	v_lshlrev_b32_e32 v24, 16, v16
	v_and_b32_e32 v25, 0xffff0000, v16
	v_lshlrev_b32_e32 v16, 16, v17
	v_and_b32_e32 v17, 0xffff0000, v17
	v_pk_mul_f32 v[40:41], v[98:99], v[20:21] op_sel_hi:[1,0]
	v_pk_mul_f32 v[20:21], v[90:91], v[20:21] op_sel_hi:[1,0]
	s_nop 0
	v_pk_mul_f32 v[16:17], v[20:21], v[16:17]
	v_pk_mul_f32 v[20:21], v[40:41], v[24:25]
	s_nop 0
	v_cvt_pk_bf16_f32 v20, v20, v21
	v_cvt_pk_bf16_f32 v21, v16, v17
	global_store_dwordx2 v[94:95], v[20:21], off offset:3584 nt
	v_lshl_add_u64 v[20:21], v[6:7], 0, s[14:15]
	v_lshl_add_u64 v[16:17], v[4:5], 0, s[14:15]
	v_lshl_add_u64 v[94:95], v[20:21], 0, v[0:1]
; template <bool HG>
; __device__ __forceinline__ void readout_phase2(const Args& a, Frame& F, const float* gain, int nrows) {
;     ...
;     RO_FINISH(f1, b1, g1, nw + 2048);     RO_LOAD(f1, b1, g1, nw + 4 * 2048);
	v_lshl_add_u64 v[20:21], v[8:9], 0, s[14:15]
	v_lshl_add_u64 v[16:17], v[16:17], 0, v[0:1]
	v_lshl_add_u64 v[150:151], v[20:21], 0, v[0:1]
	global_load_dwordx2 v[160:161], v[16:17], off nt
	global_load_dwordx2 v[154:155], v[94:95], off nt
	global_load_dwordx2 v[64:65], v[150:151], off nt
	global_load_dwordx2 v[148:149], v[16:17], off offset:512 nt
	global_load_dwordx2 v[142:143], v[94:95], off offset:512 nt
	global_load_dwordx2 v[58:59], v[150:151], off offset:512 nt
	global_load_dwordx2 v[136:137], v[16:17], off offset:1024 nt
	global_load_dwordx2 v[130:131], v[94:95], off offset:1024 nt
	global_load_dwordx2 v[52:53], v[150:151], off offset:1024 nt
	global_load_dwordx2 v[122:123], v[16:17], off offset:1536 nt
	global_load_dwordx2 v[126:127], v[94:95], off offset:1536 nt
	global_load_dwordx2 v[46:47], v[150:151], off offset:1536 nt
	global_load_dwordx2 v[118:119], v[16:17], off offset:2048 nt
	global_load_dwordx2 v[114:115], v[94:95], off offset:2048 nt
	global_load_dwordx2 v[40:41], v[150:151], off offset:2048 nt
	global_load_dwordx2 v[110:111], v[16:17], off offset:2560 nt
	global_load_dwordx2 v[106:107], v[94:95], off offset:2560 nt
	global_load_dwordx2 v[24:25], v[150:151], off offset:2560 nt
	global_load_dwordx2 v[102:103], v[16:17], off offset:3072 nt
	global_load_dwordx2 v[98:99], v[94:95], off offset:3072 nt
	global_load_dwordx2 v[20:21], v[150:151], off offset:3072 nt
	global_load_dwordx2 v[90:91], v[16:17], off offset:3584 nt
	s_nop 0
	global_load_dwordx2 v[94:95], v[94:95], off offset:3584 nt
	s_nop 0
	global_load_dwordx2 v[16:17], v[150:151], off offset:3584 nt
	v_lshlrev_b32_e32 v150, 16, v146
	v_and_b32_e32 v151, 0xffff0000, v146
	v_lshlrev_b32_e32 v146, 16, v147
	v_and_b32_e32 v147, 0xffff0000, v147
	v_pk_add_f32 v[150:151], v[150:151], v[152:153]
	v_pk_add_f32 v[146:147], v[146:147], v[144:145]
	v_mov_b32_e32 v152, v151
	v_mov_b32_e32 v153, v147
	v_mov_b32_e32 v144, v150
	v_mov_b32_e32 v145, v146
	v_pk_mul_f32 v[152:153], v[152:153], v[152:153]
	s_nop 0
	v_pk_fma_f32 v[144:145], v[144:145], v[144:145], v[152:153]
	v_lshlrev_b32_e32 v152, 16, v138
	v_add_f32_e32 v162, v144, v145
	v_lshlrev_b32_e32 v144, 16, v140
	v_and_b32_e32 v145, 0xffff0000, v140
	v_and_b32_e32 v153, 0xffff0000, v138
	v_lshlrev_b32_e32 v140, 16, v141
	v_and_b32_e32 v141, 0xffff0000, v141
	v_lshlrev_b32_e32 v138, 16, v139
	v_and_b32_e32 v139, 0xffff0000, v139
	v_pk_add_f32 v[144:145], v[144:145], v[152:153]
	v_pk_add_f32 v[140:141], v[140:141], v[138:139]
	v_mov_b32_e32 v152, v145
	v_mov_b32_e32 v153, v141
	v_mov_b32_e32 v138, v144
	v_mov_b32_e32 v139, v140
	v_pk_mul_f32 v[152:153], v[152:153], v[152:153]
	s_nop 0
	v_pk_fma_f32 v[138:139], v[138:139], v[138:139], v[152:153]
	v_lshlrev_b32_e32 v152, 16, v132
	v_add_f32_e32 v164, v138, v139
	v_lshlrev_b32_e32 v138, 16, v134
	v_and_b32_e32 v139, 0xffff0000, v134
	v_and_b32_e32 v153, 0xffff0000, v132
	v_lshlrev_b32_e32 v134, 16, v135
	v_and_b32_e32 v135, 0xffff0000, v135
	v_lshlrev_b32_e32 v132, 16, v133
	v_and_b32_e32 v133, 0xffff0000, v133
	v_pk_add_f32 v[138:139], v[138:139], v[152:153]
	v_pk_add_f32 v[134:135], v[134:135], v[132:133]
	v_mov_b32_e32 v152, v139
	v_mov_b32_e32 v153, v135
	v_mov_b32_e32 v132, v138
	v_mov_b32_e32 v133, v134
	v_pk_mul_f32 v[152:153], v[152:153], v[152:153]
	s_nop 0
	v_pk_fma_f32 v[132:133], v[132:133], v[132:133], v[152:153]
	v_lshlrev_b32_e32 v152, 16, v124
	v_add_f32_e32 v165, v132, v133
	v_lshlrev_b32_e32 v132, 16, v128
	v_and_b32_e32 v133, 0xffff0000, v128
	v_and_b32_e32 v153, 0xffff0000, v124
	v_lshlrev_b32_e32 v128, 16, v129
	v_and_b32_e32 v129, 0xffff0000, v129
	v_lshlrev_b32_e32 v124, 16, v125
	v_and_b32_e32 v125, 0xffff0000, v125
	v_pk_add_f32 v[132:133], v[132:133], v[152:153]
	v_pk_add_f32 v[128:129], v[128:129], v[124:125]
	v_mov_b32_e32 v152, v133
	v_mov_b32_e32 v153, v129
	v_mov_b32_e32 v124, v132
	v_mov_b32_e32 v125, v128
	v_pk_mul_f32 v[152:153], v[152:153], v[152:153]
	s_nop 0
	v_pk_fma_f32 v[124:125], v[124:125], v[124:125], v[152:153]
	v_lshlrev_b32_e32 v152, 16, v116
	v_add_f32_e32 v166, v124, v125
	v_lshlrev_b32_e32 v124, 16, v120
	v_and_b32_e32 v125, 0xffff0000, v120
	v_and_b32_e32 v153, 0xffff0000, v116
	v_lshlrev_b32_e32 v120, 16, v121
	v_and_b32_e32 v121, 0xffff0000, v121
	v_lshlrev_b32_e32 v116, 16, v117
	v_and_b32_e32 v117, 0xffff0000, v117
	v_pk_add_f32 v[124:125], v[124:125], v[152:153]
	v_pk_add_f32 v[120:121], v[120:121], v[116:117]
	v_mov_b32_e32 v152, v125
	v_mov_b32_e32 v153, v121
	v_mov_b32_e32 v116, v124
	v_mov_b32_e32 v117, v120
	v_pk_mul_f32 v[152:153], v[152:153], v[152:153]
	s_nop 0
	v_pk_fma_f32 v[116:117], v[116:117], v[116:117], v[152:153]
	v_lshlrev_b32_e32 v152, 16, v108
	v_add_f32_e32 v157, v116, v117
	v_lshlrev_b32_e32 v116, 16, v112
	v_and_b32_e32 v117, 0xffff0000, v112
	v_and_b32_e32 v153, 0xffff0000, v108
	v_lshlrev_b32_e32 v112, 16, v113
	v_and_b32_e32 v113, 0xffff0000, v113
	v_lshlrev_b32_e32 v108, 16, v109
	v_and_b32_e32 v109, 0xffff0000, v109
	v_pk_add_f32 v[116:117], v[116:117], v[152:153]
	v_pk_add_f32 v[112:113], v[112:113], v[108:109]
	v_mov_b32_e32 v152, v117
	v_mov_b32_e32 v153, v113
	v_mov_b32_e32 v108, v116
	v_mov_b32_e32 v109, v112
	v_pk_mul_f32 v[152:153], v[152:153], v[152:153]
	s_nop 0
	v_pk_fma_f32 v[108:109], v[108:109], v[108:109], v[152:153]
	v_lshlrev_b32_e32 v152, 16, v100
	v_add_f32_e32 v156, v108, v109
	v_lshlrev_b32_e32 v108, 16, v104
	v_and_b32_e32 v109, 0xffff0000, v104
	v_and_b32_e32 v153, 0xffff0000, v100
	v_lshlrev_b32_e32 v104, 16, v105
	v_and_b32_e32 v105, 0xffff0000, v105
	v_lshlrev_b32_e32 v100, 16, v101
	v_and_b32_e32 v101, 0xffff0000, v101
	v_pk_add_f32 v[108:109], v[108:109], v[152:153]
	v_pk_add_f32 v[104:105], v[104:105], v[100:101]
	v_mov_b32_e32 v152, v109
	v_mov_b32_e32 v153, v105
	v_mov_b32_e32 v100, v108
	v_mov_b32_e32 v101, v104
	v_pk_mul_f32 v[152:153], v[152:153], v[152:153]
	s_nop 0
	v_pk_fma_f32 v[100:101], v[100:101], v[100:101], v[152:153]
	s_nop 0
	v_add_f32_e32 v153, v100, v101
	v_lshlrev_b32_e32 v100, 16, v96
	v_and_b32_e32 v101, 0xffff0000, v96
	v_lshlrev_b32_e32 v96, 16, v97
	v_and_b32_e32 v97, 0xffff0000, v97
	v_pk_add_f32 v[100:101], v[100:101], v[158:159]
	v_pk_add_f32 v[92:93], v[96:97], v[92:93]
	v_mov_b32_e32 v158, v101
	v_mov_b32_e32 v159, v93
	v_mov_b32_e32 v96, v100
	v_mov_b32_e32 v97, v92
	v_pk_mul_f32 v[158:159], v[158:159], v[158:159]
	s_nop 0
	v_pk_fma_f32 v[96:97], v[96:97], v[96:97], v[158:159]
	v_add_f32_dpp v158, v162, v162 quad_perm:[1,0,3,2] row_mask:0xf bank_mask:0xf bound_ctrl:1
	v_add_f32_e32 v152, v96, v97
	v_lshl_add_u64 v[96:97], v[2:3], 0, s[16:17]
	v_add_f32_dpp v158, v158, v158 quad_perm:[2,3,0,1] row_mask:0xf bank_mask:0xf bound_ctrl:1
	v_lshl_add_u64 v[96:97], v[96:97], 0, v[0:1]
	s_nop 0
	v_add_f32_dpp v158, v158, v158 row_half_mirror row_mask:0xf bank_mask:0xf bound_ctrl:1
	s_nop 1
	v_add_f32_dpp v158, v158, v158 row_mirror row_mask:0xf bank_mask:0xf bound_ctrl:1
	s_nop 0
	v_readlane_b32 s9, v158, 16
	v_readlane_b32 s16, v158, 48
	v_readlane_b32 s6, v158, 0
	v_readlane_b32 s7, v158, 32
	v_mov_b32_e32 v158, s9
	v_mov_b32_e32 v159, s16
	v_pk_add_f32 v[158:159], s[6:7], v[158:159]
	s_nop 0
	v_add_f32_e32 v158, v158, v159
	v_fmamk_f32 v158, v158, 0x3b800000, v252
	v_cmp_gt_f32_e32 vcc, s55, v158
	v_mul_f32_e32 v159, 0x4f800000, v158
	s_nop 0
	v_cndmask_b32_e32 v158, v158, v159, vcc
	v_sqrt_f32_e32 v159, v158
	s_nop 0
	v_add_u32_e32 v162, -1, v159
	v_fma_f32 v163, -v162, v159, v158
	v_cmp_ge_f32_e64 s[6:7], 0, v163
	v_add_u32_e32 v163, 1, v159
	s_nop 0
	v_cndmask_b32_e64 v162, v159, v162, s[6:7]
	v_fma_f32 v159, -v163, v159, v158
	v_cmp_lt_f32_e64 s[6:7], 0, v159
	s_nop 1
	v_cndmask_b32_e64 v159, v162, v163, s[6:7]
	v_mul_f32_e32 v162, 0x37800000, v159
	v_cndmask_b32_e32 v159, v159, v162, vcc
	v_cmp_class_f32_e32 vcc, v158, v253
	s_nop 1
	v_cndmask_b32_e32 v158, v159, v158, vcc
	v_div_scale_f32 v159, s[6:7], v158, v158, 1.0
	v_rcp_f32_e32 v162, v159
	s_nop 0
	v_fma_f32 v163, -v159, v162, 1.0
	v_fmac_f32_e32 v162, v163, v162
	v_div_scale_f32 v163, vcc, 1.0, v158, 1.0
	v_mul_f32_e32 v167, v163, v162
	v_fma_f32 v168, -v159, v167, v163
	v_fmac_f32_e32 v167, v168, v162
	v_fma_f32 v159, -v159, v167, v163
	v_div_fmas_f32 v159, v159, v162, v167
	v_div_fixup_f32 v158, v159, v158, 1.0
	v_lshlrev_b32_e32 v162, 16, v66
	v_and_b32_e32 v163, 0xffff0000, v66
	v_lshlrev_b32_e32 v66, 16, v67
	v_and_b32_e32 v67, 0xffff0000, v67
	v_pk_mul_f32 v[150:151], v[150:151], v[158:159] op_sel_hi:[1,0]
	v_pk_mul_f32 v[146:147], v[146:147], v[158:159] op_sel_hi:[1,0]
	s_nop 0
	v_pk_mul_f32 v[66:67], v[146:147], v[66:67]
	v_pk_mul_f32 v[146:147], v[150:151], v[162:163]
	s_nop 0
	v_cvt_pk_bf16_f32 v146, v146, v147
	v_cvt_pk_bf16_f32 v147, v66, v67
	v_add_f32_dpp v66, v164, v164 quad_perm:[1,0,3,2] row_mask:0xf bank_mask:0xf bound_ctrl:1
	global_store_dwordx2 v[96:97], v[146:147], off nt
	s_nop 0
	v_add_f32_dpp v66, v66, v66 quad_perm:[2,3,0,1] row_mask:0xf bank_mask:0xf bound_ctrl:1
	s_nop 1
	v_add_f32_dpp v66, v66, v66 row_half_mirror row_mask:0xf bank_mask:0xf bound_ctrl:1
	s_nop 1
	v_add_f32_dpp v66, v66, v66 row_mirror row_mask:0xf bank_mask:0xf bound_ctrl:1
	s_nop 0
	v_readlane_b32 s9, v66, 16
	v_readlane_b32 s16, v66, 48
	v_readlane_b32 s6, v66, 0
	v_readlane_b32 s7, v66, 32
	v_mov_b32_e32 v66, s9
	v_mov_b32_e32 v67, s16
	v_pk_add_f32 v[66:67], s[6:7], v[66:67]
	s_nop 0
	v_add_f32_e32 v66, v66, v67
	v_fmamk_f32 v66, v66, 0x3b800000, v252
	v_cmp_gt_f32_e32 vcc, s55, v66
	v_mul_f32_e32 v67, 0x4f800000, v66
	s_nop 0
	v_cndmask_b32_e32 v66, v66, v67, vcc
	v_sqrt_f32_e32 v67, v66
	s_nop 0
	v_add_u32_e32 v146, -1, v67
	v_fma_f32 v147, -v146, v67, v66
	v_cmp_ge_f32_e64 s[6:7], 0, v147
	v_add_u32_e32 v147, 1, v67
	s_nop 0
	v_cndmask_b32_e64 v146, v67, v146, s[6:7]
	v_fma_f32 v67, -v147, v67, v66
	v_cmp_lt_f32_e64 s[6:7], 0, v67
	s_nop 1
	v_cndmask_b32_e64 v67, v146, v147, s[6:7]
	v_mul_f32_e32 v146, 0x37800000, v67
	v_cndmask_b32_e32 v67, v67, v146, vcc
	v_cmp_class_f32_e32 vcc, v66, v253
	s_nop 1
	v_cndmask_b32_e32 v66, v67, v66, vcc
	v_div_scale_f32 v67, s[6:7], v66, v66, 1.0
	v_rcp_f32_e32 v146, v67
	s_nop 0
	v_fma_f32 v147, -v67, v146, 1.0
	v_fmac_f32_e32 v146, v147, v146
	v_div_scale_f32 v147, vcc, 1.0, v66, 1.0
	v_mul_f32_e32 v150, v147, v146
	v_fma_f32 v151, -v67, v150, v147
	v_fmac_f32_e32 v150, v151, v146
	v_fma_f32 v67, -v67, v150, v147
	v_div_fmas_f32 v67, v67, v146, v150
	v_div_fixup_f32 v66, v67, v66, 1.0
	v_lshlrev_b32_e32 v146, 16, v60
	v_and_b32_e32 v147, 0xffff0000, v60
	v_lshlrev_b32_e32 v60, 16, v61
	v_and_b32_e32 v61, 0xffff0000, v61
	v_pk_mul_f32 v[144:145], v[144:145], v[66:67] op_sel_hi:[1,0]
	v_pk_mul_f32 v[66:67], v[140:141], v[66:67] op_sel_hi:[1,0]
	s_nop 0
	v_pk_mul_f32 v[60:61], v[66:67], v[60:61]
	v_pk_mul_f32 v[66:67], v[144:145], v[146:147]
	s_nop 0
	v_cvt_pk_bf16_f32 v66, v66, v67
	v_cvt_pk_bf16_f32 v67, v60, v61
	v_add_f32_dpp v60, v165, v165 quad_perm:[1,0,3,2] row_mask:0xf bank_mask:0xf bound_ctrl:1
	global_store_dwordx2 v[96:97], v[66:67], off offset:512 nt
	s_nop 0
	v_add_f32_dpp v60, v60, v60 quad_perm:[2,3,0,1] row_mask:0xf bank_mask:0xf bound_ctrl:1
	s_nop 1
	v_add_f32_dpp v60, v60, v60 row_half_mirror row_mask:0xf bank_mask:0xf bound_ctrl:1
	s_nop 1
	v_add_f32_dpp v60, v60, v60 row_mirror row_mask:0xf bank_mask:0xf bound_ctrl:1
	s_nop 0
	v_readlane_b32 s9, v60, 16
	v_readlane_b32 s16, v60, 48
	v_readlane_b32 s6, v60, 0
	v_readlane_b32 s7, v60, 32
	v_mov_b32_e32 v60, s9
	v_mov_b32_e32 v61, s16
	v_pk_add_f32 v[60:61], s[6:7], v[60:61]
	s_nop 0
	v_add_f32_e32 v60, v60, v61
	v_fmamk_f32 v60, v60, 0x3b800000, v252
	v_cmp_gt_f32_e32 vcc, s55, v60
	v_mul_f32_e32 v61, 0x4f800000, v60
	s_nop 0
	v_cndmask_b32_e32 v60, v60, v61, vcc
	v_sqrt_f32_e32 v61, v60
	s_nop 0
	v_add_u32_e32 v66, -1, v61
	v_fma_f32 v67, -v66, v61, v60
	v_cmp_ge_f32_e64 s[6:7], 0, v67
	v_add_u32_e32 v67, 1, v61
	s_nop 0
	v_cndmask_b32_e64 v66, v61, v66, s[6:7]
	v_fma_f32 v61, -v67, v61, v60
	v_cmp_lt_f32_e64 s[6:7], 0, v61
	s_nop 1
	v_cndmask_b32_e64 v61, v66, v67, s[6:7]
	v_mul_f32_e32 v66, 0x37800000, v61
	v_cndmask_b32_e32 v61, v61, v66, vcc
	v_cmp_class_f32_e32 vcc, v60, v253
	s_nop 1
	v_cndmask_b32_e32 v60, v61, v60, vcc
	v_div_scale_f32 v61, s[6:7], v60, v60, 1.0
	v_rcp_f32_e32 v66, v61
	s_nop 0
	v_fma_f32 v67, -v61, v66, 1.0
	v_fmac_f32_e32 v66, v67, v66
	v_div_scale_f32 v67, vcc, 1.0, v60, 1.0
	v_mul_f32_e32 v140, v67, v66
	v_fma_f32 v141, -v61, v140, v67
	v_fmac_f32_e32 v140, v141, v66
	v_fma_f32 v61, -v61, v140, v67
	v_div_fmas_f32 v61, v61, v66, v140
	v_div_fixup_f32 v60, v61, v60, 1.0
	v_lshlrev_b32_e32 v66, 16, v54
	v_and_b32_e32 v67, 0xffff0000, v54
	v_lshlrev_b32_e32 v54, 16, v55
	v_and_b32_e32 v55, 0xffff0000, v55
	v_pk_mul_f32 v[138:139], v[138:139], v[60:61] op_sel_hi:[1,0]
	v_pk_mul_f32 v[60:61], v[134:135], v[60:61] op_sel_hi:[1,0]
	s_waitcnt vmcnt(56)
	v_lshlrev_b32_e32 v140, 16, v86
	v_pk_mul_f32 v[54:55], v[60:61], v[54:55]
	v_pk_mul_f32 v[60:61], v[138:139], v[66:67]
	v_and_b32_e32 v141, 0xffff0000, v86
	v_cvt_pk_bf16_f32 v60, v60, v61
	v_cvt_pk_bf16_f32 v61, v54, v55
	v_add_f32_dpp v54, v166, v166 quad_perm:[1,0,3,2] row_mask:0xf bank_mask:0xf bound_ctrl:1
	global_store_dwordx2 v[96:97], v[60:61], off offset:1024 nt
	v_lshlrev_b32_e32 v86, 16, v87
	v_add_f32_dpp v54, v54, v54 quad_perm:[2,3,0,1] row_mask:0xf bank_mask:0xf bound_ctrl:1
	v_and_b32_e32 v87, 0xffff0000, v87
	s_nop 0
	v_add_f32_dpp v54, v54, v54 row_half_mirror row_mask:0xf bank_mask:0xf bound_ctrl:1
	s_nop 1
	v_add_f32_dpp v54, v54, v54 row_mirror row_mask:0xf bank_mask:0xf bound_ctrl:1
	s_nop 0
	v_readlane_b32 s9, v54, 16
	v_readlane_b32 s16, v54, 48
	v_readlane_b32 s6, v54, 0
	v_readlane_b32 s7, v54, 32
	v_mov_b32_e32 v54, s9
	v_mov_b32_e32 v55, s16
	v_pk_add_f32 v[54:55], s[6:7], v[54:55]
	s_nop 0
	v_add_f32_e32 v54, v54, v55
	v_fmamk_f32 v54, v54, 0x3b800000, v252
	v_cmp_gt_f32_e32 vcc, s55, v54
	v_mul_f32_e32 v55, 0x4f800000, v54
	s_nop 0
	v_cndmask_b32_e32 v54, v54, v55, vcc
	v_sqrt_f32_e32 v55, v54
	s_nop 0
	v_add_u32_e32 v60, -1, v55
	v_fma_f32 v61, -v60, v55, v54
	v_cmp_ge_f32_e64 s[6:7], 0, v61
	v_add_u32_e32 v61, 1, v55
	s_nop 0
	v_cndmask_b32_e64 v60, v55, v60, s[6:7]
	v_fma_f32 v55, -v61, v55, v54
	v_cmp_lt_f32_e64 s[6:7], 0, v55
	s_nop 1
	v_cndmask_b32_e64 v55, v60, v61, s[6:7]
	v_mul_f32_e32 v60, 0x37800000, v55
	v_cndmask_b32_e32 v55, v55, v60, vcc
	v_cmp_class_f32_e32 vcc, v54, v253
	s_nop 1
	v_cndmask_b32_e32 v54, v55, v54, vcc
	v_div_scale_f32 v55, s[6:7], v54, v54, 1.0
	v_rcp_f32_e32 v60, v55
	s_nop 0
	v_fma_f32 v61, -v55, v60, 1.0
	v_fmac_f32_e32 v60, v61, v60
	v_div_scale_f32 v61, vcc, 1.0, v54, 1.0
	v_mul_f32_e32 v66, v61, v60
	v_fma_f32 v67, -v55, v66, v61
	v_fmac_f32_e32 v66, v67, v60
	v_fma_f32 v55, -v55, v66, v61
	v_div_fmas_f32 v55, v55, v60, v66
	v_div_fixup_f32 v54, v55, v54, 1.0
	v_lshlrev_b32_e32 v60, 16, v48
	v_and_b32_e32 v61, 0xffff0000, v48
	v_lshlrev_b32_e32 v48, 16, v49
	v_and_b32_e32 v49, 0xffff0000, v49
	v_pk_mul_f32 v[66:67], v[132:133], v[54:55] op_sel_hi:[1,0]
	v_pk_mul_f32 v[54:55], v[128:129], v[54:55] op_sel_hi:[1,0]
	s_nop 0
	v_pk_mul_f32 v[48:49], v[54:55], v[48:49]
	v_pk_mul_f32 v[54:55], v[66:67], v[60:61]
	s_nop 0
	v_cvt_pk_bf16_f32 v54, v54, v55
	v_cvt_pk_bf16_f32 v55, v48, v49
	v_add_f32_dpp v48, v157, v157 quad_perm:[1,0,3,2] row_mask:0xf bank_mask:0xf bound_ctrl:1
	global_store_dwordx2 v[96:97], v[54:55], off offset:1536 nt
	s_nop 0
	v_add_f32_dpp v48, v48, v48 quad_perm:[2,3,0,1] row_mask:0xf bank_mask:0xf bound_ctrl:1
	s_nop 1
	v_add_f32_dpp v48, v48, v48 row_half_mirror row_mask:0xf bank_mask:0xf bound_ctrl:1
	s_nop 1
	v_add_f32_dpp v48, v48, v48 row_mirror row_mask:0xf bank_mask:0xf bound_ctrl:1
	s_nop 0
	v_readlane_b32 s9, v48, 16
	v_readlane_b32 s16, v48, 48
	v_readlane_b32 s6, v48, 0
	v_readlane_b32 s7, v48, 32
	v_mov_b32_e32 v48, s9
	v_mov_b32_e32 v49, s16
	v_pk_add_f32 v[48:49], s[6:7], v[48:49]
	s_nop 0
	v_add_f32_e32 v48, v48, v49
	v_fmamk_f32 v48, v48, 0x3b800000, v252
	v_cmp_gt_f32_e32 vcc, s55, v48
	v_mul_f32_e32 v49, 0x4f800000, v48
	s_nop 0
	v_cndmask_b32_e32 v48, v48, v49, vcc
	v_sqrt_f32_e32 v49, v48
	s_nop 0
	v_add_u32_e32 v54, -1, v49
	v_fma_f32 v55, -v54, v49, v48
	v_cmp_ge_f32_e64 s[6:7], 0, v55
	v_add_u32_e32 v55, 1, v49
	s_nop 0
	v_cndmask_b32_e64 v54, v49, v54, s[6:7]
	v_fma_f32 v49, -v55, v49, v48
	v_cmp_lt_f32_e64 s[6:7], 0, v49
	s_nop 1
	v_cndmask_b32_e64 v49, v54, v55, s[6:7]
	v_mul_f32_e32 v54, 0x37800000, v49
	v_cndmask_b32_e32 v49, v49, v54, vcc
	v_cmp_class_f32_e32 vcc, v48, v253
	s_nop 1
	v_cndmask_b32_e32 v48, v49, v48, vcc
	v_div_scale_f32 v49, s[6:7], v48, v48, 1.0
	v_rcp_f32_e32 v54, v49
	s_nop 0
	v_fma_f32 v55, -v49, v54, 1.0
	v_fmac_f32_e32 v54, v55, v54
	v_div_scale_f32 v55, vcc, 1.0, v48, 1.0
	v_mul_f32_e32 v60, v55, v54
	v_fma_f32 v61, -v49, v60, v55
	v_fmac_f32_e32 v60, v61, v54
	v_fma_f32 v49, -v49, v60, v55
	v_div_fmas_f32 v49, v49, v54, v60
	v_div_fixup_f32 v48, v49, v48, 1.0
	v_lshlrev_b32_e32 v54, 16, v42
	v_and_b32_e32 v55, 0xffff0000, v42
; template <bool HG>
; __device__ __forceinline__ void readout_phase2(const Args& a, Frame& F, const float* gain, int nrows) {
;     ...
;     RO_FINISH(f2, b2, g2, nw + 2 * 2048); RO_LOAD(f2, b2, g2, nw + 5 * 2048);
	v_lshlrev_b32_e32 v42, 16, v43
	v_and_b32_e32 v43, 0xffff0000, v43
	v_pk_mul_f32 v[60:61], v[124:125], v[48:49] op_sel_hi:[1,0]
	v_pk_mul_f32 v[48:49], v[120:121], v[48:49] op_sel_hi:[1,0]
	s_nop 0
	v_pk_mul_f32 v[42:43], v[48:49], v[42:43]
	v_pk_mul_f32 v[48:49], v[60:61], v[54:55]
	s_nop 0
	v_cvt_pk_bf16_f32 v48, v48, v49
	v_cvt_pk_bf16_f32 v49, v42, v43
	v_add_f32_dpp v42, v156, v156 quad_perm:[1,0,3,2] row_mask:0xf bank_mask:0xf bound_ctrl:1
	global_store_dwordx2 v[96:97], v[48:49], off offset:2048 nt
	s_nop 0
	v_add_f32_dpp v42, v42, v42 quad_perm:[2,3,0,1] row_mask:0xf bank_mask:0xf bound_ctrl:1
	s_nop 1
	v_add_f32_dpp v42, v42, v42 row_half_mirror row_mask:0xf bank_mask:0xf bound_ctrl:1
	s_nop 1
	v_add_f32_dpp v42, v42, v42 row_mirror row_mask:0xf bank_mask:0xf bound_ctrl:1
	s_nop 0
	v_readlane_b32 s9, v42, 16
	v_readlane_b32 s16, v42, 48
	v_readlane_b32 s6, v42, 0
	v_readlane_b32 s7, v42, 32
	v_mov_b32_e32 v42, s9
	v_mov_b32_e32 v43, s16
	v_pk_add_f32 v[42:43], s[6:7], v[42:43]
	s_nop 0
	v_add_f32_e32 v42, v42, v43
	v_fmamk_f32 v42, v42, 0x3b800000, v252
	v_cmp_gt_f32_e32 vcc, s55, v42
	v_mul_f32_e32 v43, 0x4f800000, v42
	s_nop 0
	v_cndmask_b32_e32 v42, v42, v43, vcc
	v_sqrt_f32_e32 v43, v42
	s_nop 0
	v_add_u32_e32 v48, -1, v43
	v_fma_f32 v49, -v48, v43, v42
	v_cmp_ge_f32_e64 s[6:7], 0, v49
	v_add_u32_e32 v49, 1, v43
	s_nop 0
	v_cndmask_b32_e64 v48, v43, v48, s[6:7]
	v_fma_f32 v43, -v49, v43, v42
	v_cmp_lt_f32_e64 s[6:7], 0, v43
	s_nop 1
	v_cndmask_b32_e64 v43, v48, v49, s[6:7]
	v_mul_f32_e32 v48, 0x37800000, v43
	v_cndmask_b32_e32 v43, v43, v48, vcc
	v_cmp_class_f32_e32 vcc, v42, v253
	s_nop 1
	v_cndmask_b32_e32 v42, v43, v42, vcc
	v_div_scale_f32 v43, s[6:7], v42, v42, 1.0
	v_rcp_f32_e32 v48, v43
	s_nop 0
	v_fma_f32 v49, -v43, v48, 1.0
	v_fmac_f32_e32 v48, v49, v48
	v_div_scale_f32 v49, vcc, 1.0, v42, 1.0
	v_mul_f32_e32 v54, v49, v48
	v_fma_f32 v55, -v43, v54, v49
	v_fmac_f32_e32 v54, v55, v48
	v_fma_f32 v43, -v43, v54, v49
	v_div_fmas_f32 v43, v43, v48, v54
	v_div_fixup_f32 v42, v43, v42, 1.0
	v_lshlrev_b32_e32 v48, 16, v36
	v_and_b32_e32 v49, 0xffff0000, v36
	v_lshlrev_b32_e32 v36, 16, v37
	v_and_b32_e32 v37, 0xffff0000, v37
	v_pk_mul_f32 v[54:55], v[116:117], v[42:43] op_sel_hi:[1,0]
	v_pk_mul_f32 v[42:43], v[112:113], v[42:43] op_sel_hi:[1,0]
	s_nop 0
	v_pk_mul_f32 v[36:37], v[42:43], v[36:37]
	v_pk_mul_f32 v[42:43], v[54:55], v[48:49]
	s_nop 0
	v_cvt_pk_bf16_f32 v42, v42, v43
	v_cvt_pk_bf16_f32 v43, v36, v37
	v_add_f32_dpp v36, v153, v153 quad_perm:[1,0,3,2] row_mask:0xf bank_mask:0xf bound_ctrl:1
	global_store_dwordx2 v[96:97], v[42:43], off offset:2560 nt
	s_waitcnt vmcnt(39)
	v_and_b32_e32 v153, 0xffff0000, v44
	v_add_f32_dpp v36, v36, v36 quad_perm:[2,3,0,1] row_mask:0xf bank_mask:0xf bound_ctrl:1
	s_nop 1
	v_add_f32_dpp v36, v36, v36 row_half_mirror row_mask:0xf bank_mask:0xf bound_ctrl:1
	s_nop 1
	v_add_f32_dpp v36, v36, v36 row_mirror row_mask:0xf bank_mask:0xf bound_ctrl:1
	s_nop 0
	v_readlane_b32 s9, v36, 16
	v_readlane_b32 s16, v36, 48
	v_readlane_b32 s6, v36, 0
	v_readlane_b32 s7, v36, 32
	v_mov_b32_e32 v36, s9
	v_mov_b32_e32 v37, s16
	v_pk_add_f32 v[36:37], s[6:7], v[36:37]
	s_nop 0
	v_add_f32_e32 v36, v36, v37
	v_fmamk_f32 v36, v36, 0x3b800000, v252
	v_cmp_gt_f32_e32 vcc, s55, v36
	v_mul_f32_e32 v37, 0x4f800000, v36
	s_nop 0
	v_cndmask_b32_e32 v36, v36, v37, vcc
	v_sqrt_f32_e32 v37, v36
	s_nop 0
	v_add_u32_e32 v42, -1, v37
	v_fma_f32 v43, -v42, v37, v36
	v_cmp_ge_f32_e64 s[6:7], 0, v43
	v_add_u32_e32 v43, 1, v37
	s_nop 0
	v_cndmask_b32_e64 v42, v37, v42, s[6:7]
	v_fma_f32 v37, -v43, v37, v36
	v_cmp_lt_f32_e64 s[6:7], 0, v37
	s_nop 1
	v_cndmask_b32_e64 v37, v42, v43, s[6:7]
	v_mul_f32_e32 v42, 0x37800000, v37
	v_cndmask_b32_e32 v37, v37, v42, vcc
	v_cmp_class_f32_e32 vcc, v36, v253
	s_nop 1
	v_cndmask_b32_e32 v36, v37, v36, vcc
	v_div_scale_f32 v37, s[6:7], v36, v36, 1.0
	v_rcp_f32_e32 v42, v37
	s_nop 0
	v_fma_f32 v43, -v37, v42, 1.0
	v_fmac_f32_e32 v42, v43, v42
	v_div_scale_f32 v43, vcc, 1.0, v36, 1.0
	v_mul_f32_e32 v48, v43, v42
	v_fma_f32 v49, -v37, v48, v43
	v_fmac_f32_e32 v48, v49, v42
	v_fma_f32 v37, -v37, v48, v43
	v_div_fmas_f32 v37, v37, v42, v48
	v_div_fixup_f32 v36, v37, v36, 1.0
	v_lshlrev_b32_e32 v42, 16, v32
	v_and_b32_e32 v43, 0xffff0000, v32
	v_lshlrev_b32_e32 v32, 16, v33
	v_and_b32_e32 v33, 0xffff0000, v33
	v_pk_mul_f32 v[48:49], v[108:109], v[36:37] op_sel_hi:[1,0]
	v_pk_mul_f32 v[36:37], v[104:105], v[36:37] op_sel_hi:[1,0]
	s_nop 0
	v_pk_mul_f32 v[32:33], v[36:37], v[32:33]
	v_pk_mul_f32 v[36:37], v[48:49], v[42:43]
	s_nop 0
	v_cvt_pk_bf16_f32 v36, v36, v37
	v_cvt_pk_bf16_f32 v37, v32, v33
	v_add_f32_dpp v32, v152, v152 quad_perm:[1,0,3,2] row_mask:0xf bank_mask:0xf bound_ctrl:1
	global_store_dwordx2 v[96:97], v[36:37], off offset:3072 nt
	v_lshlrev_b32_e32 v152, 16, v44
	v_add_f32_dpp v32, v32, v32 quad_perm:[2,3,0,1] row_mask:0xf bank_mask:0xf bound_ctrl:1
	v_lshlrev_b32_e32 v44, 16, v45
	v_and_b32_e32 v45, 0xffff0000, v45
	v_add_f32_dpp v32, v32, v32 row_half_mirror row_mask:0xf bank_mask:0xf bound_ctrl:1
	s_nop 1
	v_add_f32_dpp v32, v32, v32 row_mirror row_mask:0xf bank_mask:0xf bound_ctrl:1
	s_nop 0
	v_readlane_b32 s9, v32, 16
	v_readlane_b32 s16, v32, 48
	v_readlane_b32 s6, v32, 0
	v_readlane_b32 s7, v32, 32
	v_mov_b32_e32 v32, s9
	v_mov_b32_e32 v33, s16
	v_pk_add_f32 v[32:33], s[6:7], v[32:33]
	s_add_u32 s16, s10, 0x2000000
	v_add_f32_e32 v32, v32, v33
	v_fmamk_f32 v32, v32, 0x3b800000, v252
	v_cmp_gt_f32_e32 vcc, s55, v32
	v_mul_f32_e32 v33, 0x4f800000, v32
	s_addc_u32 s17, s11, 0
	v_cndmask_b32_e32 v32, v32, v33, vcc
	v_sqrt_f32_e32 v33, v32
	s_nop 0
	v_add_u32_e32 v36, -1, v33
; template <bool HG>
; __device__ __forceinline__ void readout_phase2(const Args& a, Frame& F, const float* gain, int nrows) {
;     ...
;     RO_FINISH(f2, b2, g2, nw + 2 * 2048); RO_LOAD(f2, b2, g2, nw + 5 * 2048);
	v_fma_f32 v37, -v36, v33, v32
	v_cmp_ge_f32_e64 s[6:7], 0, v37
	v_add_u32_e32 v37, 1, v33
	s_nop 0
	v_cndmask_b32_e64 v36, v33, v36, s[6:7]
	v_fma_f32 v33, -v37, v33, v32
	v_cmp_lt_f32_e64 s[6:7], 0, v33
	s_nop 1
	v_cndmask_b32_e64 v33, v36, v37, s[6:7]
	v_mul_f32_e32 v36, 0x37800000, v33
	v_cndmask_b32_e32 v33, v33, v36, vcc
	v_cmp_class_f32_e32 vcc, v32, v253
	s_nop 1
	v_cndmask_b32_e32 v32, v33, v32, vcc
	v_div_scale_f32 v33, s[6:7], v32, v32, 1.0
	v_rcp_f32_e32 v36, v33
	s_nop 0
	v_fma_f32 v37, -v33, v36, 1.0
	v_fmac_f32_e32 v36, v37, v36
	v_div_scale_f32 v37, vcc, 1.0, v32, 1.0
	v_mul_f32_e32 v42, v37, v36
	v_fma_f32 v43, -v33, v42, v37
	v_fmac_f32_e32 v42, v43, v36
	v_fma_f32 v33, -v33, v42, v37
	v_div_fmas_f32 v33, v33, v36, v42
	v_div_fixup_f32 v32, v33, v32, 1.0
	v_lshlrev_b32_e32 v36, 16, v28
	v_and_b32_e32 v37, 0xffff0000, v28
	v_lshlrev_b32_e32 v28, 16, v29
	v_and_b32_e32 v29, 0xffff0000, v29
	v_pk_mul_f32 v[42:43], v[100:101], v[32:33] op_sel_hi:[1,0]
	v_pk_mul_f32 v[32:33], v[92:93], v[32:33] op_sel_hi:[1,0]
	s_nop 0
	v_pk_mul_f32 v[28:29], v[32:33], v[28:29]
	v_pk_mul_f32 v[32:33], v[42:43], v[36:37]
	s_nop 0
	v_cvt_pk_bf16_f32 v32, v32, v33
	v_cvt_pk_bf16_f32 v33, v28, v29
	global_store_dwordx2 v[96:97], v[32:33], off offset:3584 nt
	v_lshl_add_u64 v[32:33], v[6:7], 0, s[16:17]
	v_lshl_add_u64 v[28:29], v[4:5], 0, s[16:17]
	v_lshl_add_u64 v[96:97], v[32:33], 0, v[0:1]
	v_lshl_add_u64 v[32:33], v[8:9], 0, s[16:17]
	v_lshl_add_u64 v[28:29], v[28:29], 0, v[0:1]
	v_lshl_add_u64 v[134:135], v[32:33], 0, v[0:1]
	global_load_dwordx2 v[162:163], v[28:29], off nt
	global_load_dwordx2 v[156:157], v[96:97], off nt
	global_load_dwordx2 v[66:67], v[134:135], off nt
	global_load_dwordx2 v[150:151], v[28:29], off offset:512 nt
	global_load_dwordx2 v[144:145], v[96:97], off offset:512 nt
	global_load_dwordx2 v[60:61], v[134:135], off offset:512 nt
	global_load_dwordx2 v[138:139], v[28:29], off offset:1024 nt
	global_load_dwordx2 v[132:133], v[96:97], off offset:1024 nt
	global_load_dwordx2 v[54:55], v[134:135], off offset:1024 nt
	global_load_dwordx2 v[124:125], v[28:29], off offset:1536 nt
	global_load_dwordx2 v[128:129], v[96:97], off offset:1536 nt
	global_load_dwordx2 v[48:49], v[134:135], off offset:1536 nt
	global_load_dwordx2 v[120:121], v[28:29], off offset:2048 nt
	global_load_dwordx2 v[116:117], v[96:97], off offset:2048 nt
	global_load_dwordx2 v[42:43], v[134:135], off offset:2048 nt
	global_load_dwordx2 v[112:113], v[28:29], off offset:2560 nt
	global_load_dwordx2 v[108:109], v[96:97], off offset:2560 nt
	global_load_dwordx2 v[36:37], v[134:135], off offset:2560 nt
	global_load_dwordx2 v[104:105], v[28:29], off offset:3072 nt
	global_load_dwordx2 v[100:101], v[96:97], off offset:3072 nt
	global_load_dwordx2 v[32:33], v[134:135], off offset:3072 nt
	global_load_dwordx2 v[92:93], v[28:29], off offset:3584 nt
	s_nop 0
	global_load_dwordx2 v[96:97], v[96:97], off offset:3584 nt
	s_nop 0
	global_load_dwordx2 v[28:29], v[134:135], off offset:3584 nt
	v_lshlrev_b32_e32 v134, 16, v88
	v_and_b32_e32 v135, 0xffff0000, v88
	v_lshlrev_b32_e32 v88, 16, v89
	v_and_b32_e32 v89, 0xffff0000, v89
	v_pk_add_f32 v[134:135], v[134:135], v[140:141]
	v_pk_add_f32 v[88:89], v[88:89], v[86:87]
	v_mov_b32_e32 v140, v135
	v_mov_b32_e32 v141, v89
	v_mov_b32_e32 v86, v134
	v_mov_b32_e32 v87, v88
	v_pk_mul_f32 v[140:141], v[140:141], v[140:141]
	s_nop 0
	v_pk_fma_f32 v[86:87], v[86:87], v[86:87], v[140:141]
	v_lshlrev_b32_e32 v140, 16, v82
	v_add_f32_e32 v158, v86, v87
	v_lshlrev_b32_e32 v86, 16, v84
	v_and_b32_e32 v87, 0xffff0000, v84
	v_and_b32_e32 v141, 0xffff0000, v82
	v_lshlrev_b32_e32 v84, 16, v85
	v_and_b32_e32 v85, 0xffff0000, v85
	v_lshlrev_b32_e32 v82, 16, v83
	v_and_b32_e32 v83, 0xffff0000, v83
	v_pk_add_f32 v[86:87], v[86:87], v[140:141]
	v_pk_add_f32 v[84:85], v[84:85], v[82:83]
	v_mov_b32_e32 v140, v87
	v_mov_b32_e32 v141, v85
	v_mov_b32_e32 v82, v86
	v_mov_b32_e32 v83, v84
	v_pk_mul_f32 v[140:141], v[140:141], v[140:141]
	s_nop 0
	v_pk_fma_f32 v[82:83], v[82:83], v[82:83], v[140:141]
	v_lshlrev_b32_e32 v140, 16, v78
	v_add_f32_e32 v164, v82, v83
	v_lshlrev_b32_e32 v82, 16, v80
	v_and_b32_e32 v83, 0xffff0000, v80
	v_and_b32_e32 v141, 0xffff0000, v78
	v_lshlrev_b32_e32 v80, 16, v81
	v_and_b32_e32 v81, 0xffff0000, v81
	v_lshlrev_b32_e32 v78, 16, v79
	v_and_b32_e32 v79, 0xffff0000, v79
	v_pk_add_f32 v[82:83], v[82:83], v[140:141]
	v_pk_add_f32 v[80:81], v[80:81], v[78:79]
	v_mov_b32_e32 v140, v83
	v_mov_b32_e32 v141, v81
	v_mov_b32_e32 v78, v82
	v_mov_b32_e32 v79, v80
	v_pk_mul_f32 v[140:141], v[140:141], v[140:141]
	s_nop 0
	v_pk_fma_f32 v[78:79], v[78:79], v[78:79], v[140:141]
	v_lshlrev_b32_e32 v140, 16, v76
	v_add_f32_e32 v165, v78, v79
	v_lshlrev_b32_e32 v78, 16, v74
	v_and_b32_e32 v79, 0xffff0000, v74
	v_and_b32_e32 v141, 0xffff0000, v76
	v_lshlrev_b32_e32 v74, 16, v75
	v_and_b32_e32 v75, 0xffff0000, v75
	v_lshlrev_b32_e32 v76, 16, v77
	v_and_b32_e32 v77, 0xffff0000, v77
	v_pk_add_f32 v[78:79], v[78:79], v[140:141]
	v_pk_add_f32 v[76:77], v[74:75], v[76:77]
	v_mov_b32_e32 v140, v79
	v_mov_b32_e32 v141, v77
	v_mov_b32_e32 v74, v78
	v_mov_b32_e32 v75, v76
	v_pk_mul_f32 v[140:141], v[140:141], v[140:141]
	s_nop 0
	v_pk_fma_f32 v[74:75], v[74:75], v[74:75], v[140:141]
	v_lshlrev_b32_e32 v140, 16, v70
	v_add_f32_e32 v166, v74, v75
	v_lshlrev_b32_e32 v74, 16, v72
	v_and_b32_e32 v75, 0xffff0000, v72
	v_and_b32_e32 v141, 0xffff0000, v70
	v_lshlrev_b32_e32 v72, 16, v73
	v_and_b32_e32 v73, 0xffff0000, v73
	v_lshlrev_b32_e32 v70, 16, v71
	v_and_b32_e32 v71, 0xffff0000, v71
	v_pk_add_f32 v[74:75], v[74:75], v[140:141]
	v_pk_add_f32 v[72:73], v[72:73], v[70:71]
	v_mov_b32_e32 v140, v75
	v_mov_b32_e32 v141, v73
	v_mov_b32_e32 v70, v74
	v_mov_b32_e32 v71, v72
	v_pk_mul_f32 v[140:141], v[140:141], v[140:141]
	s_nop 0
	v_pk_fma_f32 v[70:71], v[70:71], v[70:71], v[140:141]
	v_lshlrev_b32_e32 v140, 16, v62
	v_add_f32_e32 v147, v70, v71
	v_lshlrev_b32_e32 v70, 16, v68
	v_and_b32_e32 v71, 0xffff0000, v68
	v_and_b32_e32 v141, 0xffff0000, v62
	v_lshlrev_b32_e32 v68, 16, v69
	v_and_b32_e32 v69, 0xffff0000, v69
	v_lshlrev_b32_e32 v62, 16, v63
	v_and_b32_e32 v63, 0xffff0000, v63
	v_pk_add_f32 v[70:71], v[70:71], v[140:141]
	v_pk_add_f32 v[68:69], v[68:69], v[62:63]
	v_mov_b32_e32 v140, v71
	v_mov_b32_e32 v141, v69
	v_mov_b32_e32 v62, v70
	v_mov_b32_e32 v63, v68
	v_pk_mul_f32 v[140:141], v[140:141], v[140:141]
	s_nop 0
	v_pk_fma_f32 v[62:63], v[62:63], v[62:63], v[140:141]
	v_lshlrev_b32_e32 v140, 16, v50
	v_add_f32_e32 v146, v62, v63
	v_lshlrev_b32_e32 v62, 16, v56
	v_and_b32_e32 v63, 0xffff0000, v56
	v_and_b32_e32 v141, 0xffff0000, v50
	v_lshlrev_b32_e32 v56, 16, v57
	v_and_b32_e32 v57, 0xffff0000, v57
	v_lshlrev_b32_e32 v50, 16, v51
	v_and_b32_e32 v51, 0xffff0000, v51
	v_pk_add_f32 v[62:63], v[62:63], v[140:141]
	v_pk_add_f32 v[56:57], v[56:57], v[50:51]
	v_mov_b32_e32 v140, v63
	v_mov_b32_e32 v141, v57
	v_mov_b32_e32 v50, v62
	v_mov_b32_e32 v51, v56
	v_pk_mul_f32 v[140:141], v[140:141], v[140:141]
	s_nop 0
	v_pk_fma_f32 v[50:51], v[50:51], v[50:51], v[140:141]
	s_nop 0
	v_add_f32_e32 v141, v50, v51
	v_lshlrev_b32_e32 v50, 16, v38
	v_and_b32_e32 v51, 0xffff0000, v38
	v_lshlrev_b32_e32 v38, 16, v39
	v_and_b32_e32 v39, 0xffff0000, v39
	v_pk_add_f32 v[50:51], v[50:51], v[152:153]
	v_pk_add_f32 v[38:39], v[38:39], v[44:45]
	v_mov_b32_e32 v152, v51
	v_mov_b32_e32 v153, v39
	v_mov_b32_e32 v44, v50
	v_mov_b32_e32 v45, v38
	v_pk_mul_f32 v[152:153], v[152:153], v[152:153]
	s_nop 0
	v_pk_fma_f32 v[44:45], v[44:45], v[44:45], v[152:153]
	v_add_f32_dpp v152, v158, v158 quad_perm:[1,0,3,2] row_mask:0xf bank_mask:0xf bound_ctrl:1
	v_add_f32_e32 v140, v44, v45
	v_lshl_add_u64 v[44:45], v[2:3], 0, s[12:13]
	v_add_f32_dpp v152, v152, v152 quad_perm:[2,3,0,1] row_mask:0xf bank_mask:0xf bound_ctrl:1
	v_lshl_add_u64 v[44:45], v[44:45], 0, v[0:1]
	s_nop 0
	v_add_f32_dpp v152, v152, v152 row_half_mirror row_mask:0xf bank_mask:0xf bound_ctrl:1
	s_nop 1
	v_add_f32_dpp v152, v152, v152 row_mirror row_mask:0xf bank_mask:0xf bound_ctrl:1
	s_nop 0
	v_readlane_b32 s9, v152, 16
	v_readlane_b32 s12, v152, 48
	v_readlane_b32 s6, v152, 0
	v_readlane_b32 s7, v152, 32
	v_mov_b32_e32 v152, s9
	v_mov_b32_e32 v153, s12
	v_pk_add_f32 v[152:153], s[6:7], v[152:153]
	s_nop 0
	v_add_f32_e32 v152, v152, v153
	v_fmamk_f32 v152, v152, 0x3b800000, v252
	v_cmp_gt_f32_e32 vcc, s55, v152
	v_mul_f32_e32 v153, 0x4f800000, v152
	s_nop 0
	v_cndmask_b32_e32 v152, v152, v153, vcc
	v_sqrt_f32_e32 v153, v152
	s_nop 0
	v_add_u32_e32 v158, -1, v153
	v_fma_f32 v159, -v158, v153, v152
	v_cmp_ge_f32_e64 s[6:7], 0, v159
	v_add_u32_e32 v159, 1, v153
	s_nop 0
	v_cndmask_b32_e64 v158, v153, v158, s[6:7]
	v_fma_f32 v153, -v159, v153, v152
	v_cmp_lt_f32_e64 s[6:7], 0, v153
	s_nop 1
	v_cndmask_b32_e64 v153, v158, v159, s[6:7]
	v_mul_f32_e32 v158, 0x37800000, v153
	v_cndmask_b32_e32 v153, v153, v158, vcc
	v_cmp_class_f32_e32 vcc, v152, v253
	s_nop 1
	v_cndmask_b32_e32 v152, v153, v152, vcc
	v_div_scale_f32 v153, s[6:7], v152, v152, 1.0
	v_rcp_f32_e32 v158, v153
	s_nop 0
	v_fma_f32 v159, -v153, v158, 1.0
	v_fmac_f32_e32 v158, v159, v158
	v_div_scale_f32 v159, vcc, 1.0, v152, 1.0
	v_mul_f32_e32 v167, v159, v158
	v_fma_f32 v168, -v153, v167, v159
	v_fmac_f32_e32 v167, v168, v158
	v_fma_f32 v153, -v153, v167, v159
	v_div_fmas_f32 v153, v153, v158, v167
	v_div_fixup_f32 v152, v153, v152, 1.0
	v_lshlrev_b32_e32 v158, 16, v34
	v_and_b32_e32 v159, 0xffff0000, v34
	v_lshlrev_b32_e32 v34, 16, v35
	v_and_b32_e32 v35, 0xffff0000, v35
	v_pk_mul_f32 v[134:135], v[134:135], v[152:153] op_sel_hi:[1,0]
	v_pk_mul_f32 v[88:89], v[88:89], v[152:153] op_sel_hi:[1,0]
	s_nop 0
	v_pk_mul_f32 v[34:35], v[88:89], v[34:35]
	v_pk_mul_f32 v[88:89], v[134:135], v[158:159]
	s_nop 0
	v_cvt_pk_bf16_f32 v88, v88, v89
	v_cvt_pk_bf16_f32 v89, v34, v35
	v_add_f32_dpp v34, v164, v164 quad_perm:[1,0,3,2] row_mask:0xf bank_mask:0xf bound_ctrl:1
	global_store_dwordx2 v[44:45], v[88:89], off nt
	s_nop 0
	v_add_f32_dpp v34, v34, v34 quad_perm:[2,3,0,1] row_mask:0xf bank_mask:0xf bound_ctrl:1
	s_nop 1
	v_add_f32_dpp v34, v34, v34 row_half_mirror row_mask:0xf bank_mask:0xf bound_ctrl:1
	s_nop 1
	v_add_f32_dpp v34, v34, v34 row_mirror row_mask:0xf bank_mask:0xf bound_ctrl:1
	s_nop 0
	v_readlane_b32 s9, v34, 16
	v_readlane_b32 s12, v34, 48
	v_readlane_b32 s6, v34, 0
	v_readlane_b32 s7, v34, 32
	v_mov_b32_e32 v34, s9
	v_mov_b32_e32 v35, s12
	v_pk_add_f32 v[34:35], s[6:7], v[34:35]
	s_nop 0
	v_add_f32_e32 v34, v34, v35
	v_fmamk_f32 v34, v34, 0x3b800000, v252
	v_cmp_gt_f32_e32 vcc, s55, v34
	v_mul_f32_e32 v35, 0x4f800000, v34
	s_nop 0
	v_cndmask_b32_e32 v34, v34, v35, vcc
	v_sqrt_f32_e32 v35, v34
	s_nop 0
	v_add_u32_e32 v88, -1, v35
	v_fma_f32 v89, -v88, v35, v34
	v_cmp_ge_f32_e64 s[6:7], 0, v89
	v_add_u32_e32 v89, 1, v35
	s_nop 0
	v_cndmask_b32_e64 v88, v35, v88, s[6:7]
	v_fma_f32 v35, -v89, v35, v34
	v_cmp_lt_f32_e64 s[6:7], 0, v35
	s_nop 1
	v_cndmask_b32_e64 v35, v88, v89, s[6:7]
	v_mul_f32_e32 v88, 0x37800000, v35
	v_cndmask_b32_e32 v35, v35, v88, vcc
	v_cmp_class_f32_e32 vcc, v34, v253
	s_nop 1
	v_cndmask_b32_e32 v34, v35, v34, vcc
	v_div_scale_f32 v35, s[6:7], v34, v34, 1.0
	v_rcp_f32_e32 v88, v35
	s_nop 0
	v_fma_f32 v89, -v35, v88, 1.0
	v_fmac_f32_e32 v88, v89, v88
	v_div_scale_f32 v89, vcc, 1.0, v34, 1.0
	v_mul_f32_e32 v134, v89, v88
	v_fma_f32 v135, -v35, v134, v89
	v_fmac_f32_e32 v134, v135, v88
	v_fma_f32 v35, -v35, v134, v89
	v_div_fmas_f32 v35, v35, v88, v134
	v_div_fixup_f32 v34, v35, v34, 1.0
	v_lshlrev_b32_e32 v88, 16, v30
	v_and_b32_e32 v89, 0xffff0000, v30
	v_lshlrev_b32_e32 v30, 16, v31
	v_and_b32_e32 v31, 0xffff0000, v31
	v_pk_mul_f32 v[86:87], v[86:87], v[34:35] op_sel_hi:[1,0]
	v_pk_mul_f32 v[34:35], v[84:85], v[34:35] op_sel_hi:[1,0]
	s_nop 0
	v_pk_mul_f32 v[30:31], v[34:35], v[30:31]
	v_pk_mul_f32 v[34:35], v[86:87], v[88:89]
	s_nop 0
	v_cvt_pk_bf16_f32 v34, v34, v35
	v_cvt_pk_bf16_f32 v35, v30, v31
	v_add_f32_dpp v30, v165, v165 quad_perm:[1,0,3,2] row_mask:0xf bank_mask:0xf bound_ctrl:1
	global_store_dwordx2 v[44:45], v[34:35], off offset:512 nt
	s_nop 0
	v_add_f32_dpp v30, v30, v30 quad_perm:[2,3,0,1] row_mask:0xf bank_mask:0xf bound_ctrl:1
	s_nop 1
	v_add_f32_dpp v30, v30, v30 row_half_mirror row_mask:0xf bank_mask:0xf bound_ctrl:1
	s_nop 1
	v_add_f32_dpp v30, v30, v30 row_mirror row_mask:0xf bank_mask:0xf bound_ctrl:1
	s_nop 0
	v_readlane_b32 s9, v30, 16
	v_readlane_b32 s12, v30, 48
	v_readlane_b32 s6, v30, 0
	v_readlane_b32 s7, v30, 32
	v_mov_b32_e32 v30, s9
	v_mov_b32_e32 v31, s12
	v_pk_add_f32 v[30:31], s[6:7], v[30:31]
	s_nop 0
	v_add_f32_e32 v30, v30, v31
	v_fmamk_f32 v30, v30, 0x3b800000, v252
	v_cmp_gt_f32_e32 vcc, s55, v30
	v_mul_f32_e32 v31, 0x4f800000, v30
	s_nop 0
	v_cndmask_b32_e32 v30, v30, v31, vcc
	v_sqrt_f32_e32 v31, v30
	s_nop 0
	v_add_u32_e32 v34, -1, v31
	v_fma_f32 v35, -v34, v31, v30
	v_cmp_ge_f32_e64 s[6:7], 0, v35
	v_add_u32_e32 v35, 1, v31
	s_nop 0
	v_cndmask_b32_e64 v34, v31, v34, s[6:7]
	v_fma_f32 v31, -v35, v31, v30
	v_cmp_lt_f32_e64 s[6:7], 0, v31
	s_nop 1
	v_cndmask_b32_e64 v31, v34, v35, s[6:7]
	v_mul_f32_e32 v34, 0x37800000, v31
	v_cndmask_b32_e32 v31, v31, v34, vcc
	v_cmp_class_f32_e32 vcc, v30, v253
	s_nop 1
	v_cndmask_b32_e32 v30, v31, v30, vcc
	v_div_scale_f32 v31, s[6:7], v30, v30, 1.0
	v_rcp_f32_e32 v34, v31
	s_nop 0
	v_fma_f32 v35, -v31, v34, 1.0
	v_fmac_f32_e32 v34, v35, v34
	v_div_scale_f32 v35, vcc, 1.0, v30, 1.0
	v_mul_f32_e32 v84, v35, v34
	v_fma_f32 v85, -v31, v84, v35
	v_fmac_f32_e32 v84, v85, v34
	v_fma_f32 v31, -v31, v84, v35
	v_div_fmas_f32 v31, v31, v34, v84
	v_div_fixup_f32 v30, v31, v30, 1.0
	v_lshlrev_b32_e32 v34, 16, v26
	v_and_b32_e32 v35, 0xffff0000, v26
	v_lshlrev_b32_e32 v26, 16, v27
	v_and_b32_e32 v27, 0xffff0000, v27
	v_pk_mul_f32 v[82:83], v[82:83], v[30:31] op_sel_hi:[1,0]
	v_pk_mul_f32 v[30:31], v[80:81], v[30:31] op_sel_hi:[1,0]
	s_nop 0
	v_pk_mul_f32 v[26:27], v[30:31], v[26:27]
	v_pk_mul_f32 v[30:31], v[82:83], v[34:35]
	s_nop 0
	v_cvt_pk_bf16_f32 v30, v30, v31
	v_cvt_pk_bf16_f32 v31, v26, v27
	v_add_f32_dpp v26, v166, v166 quad_perm:[1,0,3,2] row_mask:0xf bank_mask:0xf bound_ctrl:1
	global_store_dwordx2 v[44:45], v[30:31], off offset:1024 nt
	s_nop 0
	v_add_f32_dpp v26, v26, v26 quad_perm:[2,3,0,1] row_mask:0xf bank_mask:0xf bound_ctrl:1
	s_nop 1
	v_add_f32_dpp v26, v26, v26 row_half_mirror row_mask:0xf bank_mask:0xf bound_ctrl:1
	s_nop 1
	v_add_f32_dpp v26, v26, v26 row_mirror row_mask:0xf bank_mask:0xf bound_ctrl:1
	s_nop 0
	v_readlane_b32 s9, v26, 16
	v_readlane_b32 s12, v26, 48
	v_readlane_b32 s6, v26, 0
	v_readlane_b32 s7, v26, 32
	v_mov_b32_e32 v26, s9
	v_mov_b32_e32 v27, s12
	v_pk_add_f32 v[26:27], s[6:7], v[26:27]
	s_nop 0
	v_add_f32_e32 v26, v26, v27
	v_fmamk_f32 v26, v26, 0x3b800000, v252
	v_cmp_gt_f32_e32 vcc, s55, v26
	v_mul_f32_e32 v27, 0x4f800000, v26
	s_nop 0
	v_cndmask_b32_e32 v26, v26, v27, vcc
	v_sqrt_f32_e32 v27, v26
	s_nop 0
	v_add_u32_e32 v30, -1, v27
	v_fma_f32 v31, -v30, v27, v26
	v_cmp_ge_f32_e64 s[6:7], 0, v31
	v_add_u32_e32 v31, 1, v27
	s_nop 0
	v_cndmask_b32_e64 v30, v27, v30, s[6:7]
	v_fma_f32 v27, -v31, v27, v26
	v_cmp_lt_f32_e64 s[6:7], 0, v27
	s_nop 1
	v_cndmask_b32_e64 v27, v30, v31, s[6:7]
	v_mul_f32_e32 v30, 0x37800000, v27
	v_cndmask_b32_e32 v27, v27, v30, vcc
	v_cmp_class_f32_e32 vcc, v26, v253
	s_nop 1
	v_cndmask_b32_e32 v26, v27, v26, vcc
	v_div_scale_f32 v27, s[6:7], v26, v26, 1.0
	v_rcp_f32_e32 v30, v27
	s_nop 0
	v_fma_f32 v31, -v27, v30, 1.0
	v_fmac_f32_e32 v30, v31, v30
	v_div_scale_f32 v31, vcc, 1.0, v26, 1.0
	v_mul_f32_e32 v34, v31, v30
	v_fma_f32 v35, -v27, v34, v31
	v_fmac_f32_e32 v34, v35, v30
	v_fma_f32 v27, -v27, v34, v31
	v_div_fmas_f32 v27, v27, v30, v34
	v_div_fixup_f32 v26, v27, v26, 1.0
	v_lshlrev_b32_e32 v30, 16, v22
	v_and_b32_e32 v31, 0xffff0000, v22
	v_lshlrev_b32_e32 v22, 16, v23
	v_and_b32_e32 v23, 0xffff0000, v23
	v_pk_mul_f32 v[34:35], v[78:79], v[26:27] op_sel_hi:[1,0]
	v_pk_mul_f32 v[26:27], v[76:77], v[26:27] op_sel_hi:[1,0]
	s_nop 0
	v_pk_mul_f32 v[22:23], v[26:27], v[22:23]
	v_pk_mul_f32 v[26:27], v[34:35], v[30:31]
	s_nop 0
	v_cvt_pk_bf16_f32 v26, v26, v27
	v_cvt_pk_bf16_f32 v27, v22, v23
	v_add_f32_dpp v22, v147, v147 quad_perm:[1,0,3,2] row_mask:0xf bank_mask:0xf bound_ctrl:1
	global_store_dwordx2 v[44:45], v[26:27], off offset:1536 nt
	s_nop 0
	v_add_f32_dpp v22, v22, v22 quad_perm:[2,3,0,1] row_mask:0xf bank_mask:0xf bound_ctrl:1
	s_nop 1
	v_add_f32_dpp v22, v22, v22 row_half_mirror row_mask:0xf bank_mask:0xf bound_ctrl:1
	s_nop 1
	v_add_f32_dpp v22, v22, v22 row_mirror row_mask:0xf bank_mask:0xf bound_ctrl:1
	s_nop 0
	v_readlane_b32 s9, v22, 16
	v_readlane_b32 s12, v22, 48
	v_readlane_b32 s6, v22, 0
	v_readlane_b32 s7, v22, 32
	v_mov_b32_e32 v22, s9
	v_mov_b32_e32 v23, s12
	v_pk_add_f32 v[22:23], s[6:7], v[22:23]
	s_nop 0
	v_add_f32_e32 v22, v22, v23
	v_fmamk_f32 v22, v22, 0x3b800000, v252
	v_cmp_gt_f32_e32 vcc, s55, v22
	v_mul_f32_e32 v23, 0x4f800000, v22
	s_nop 0
	v_cndmask_b32_e32 v22, v22, v23, vcc
	v_sqrt_f32_e32 v23, v22
	s_nop 0
	v_add_u32_e32 v26, -1, v23
	v_fma_f32 v27, -v26, v23, v22
	v_cmp_ge_f32_e64 s[6:7], 0, v27
	v_add_u32_e32 v27, 1, v23
	s_nop 0
	v_cndmask_b32_e64 v26, v23, v26, s[6:7]
	v_fma_f32 v23, -v27, v23, v22
	v_cmp_lt_f32_e64 s[6:7], 0, v23
	s_nop 1
	v_cndmask_b32_e64 v23, v26, v27, s[6:7]
	v_mul_f32_e32 v26, 0x37800000, v23
	v_cndmask_b32_e32 v23, v23, v26, vcc
	v_cmp_class_f32_e32 vcc, v22, v253
	s_nop 1
	v_cndmask_b32_e32 v22, v23, v22, vcc
	v_div_scale_f32 v23, s[6:7], v22, v22, 1.0
	v_rcp_f32_e32 v26, v23
	s_nop 0
	v_fma_f32 v27, -v23, v26, 1.0
	v_fmac_f32_e32 v26, v27, v26
	v_div_scale_f32 v27, vcc, 1.0, v22, 1.0
	v_mul_f32_e32 v30, v27, v26
	v_fma_f32 v31, -v23, v30, v27
	v_fmac_f32_e32 v30, v31, v26
	v_fma_f32 v23, -v23, v30, v27
	v_div_fmas_f32 v23, v23, v26, v30
	v_div_fixup_f32 v22, v23, v22, 1.0
	v_lshlrev_b32_e32 v26, 16, v18
	v_and_b32_e32 v27, 0xffff0000, v18
	v_lshlrev_b32_e32 v18, 16, v19
	v_and_b32_e32 v19, 0xffff0000, v19
	v_pk_mul_f32 v[30:31], v[74:75], v[22:23] op_sel_hi:[1,0]
	v_pk_mul_f32 v[22:23], v[72:73], v[22:23] op_sel_hi:[1,0]
	s_nop 0
	v_pk_mul_f32 v[18:19], v[22:23], v[18:19]
	v_pk_mul_f32 v[22:23], v[30:31], v[26:27]
	s_nop 0
	v_cvt_pk_bf16_f32 v22, v22, v23
	v_cvt_pk_bf16_f32 v23, v18, v19
	v_add_f32_dpp v18, v146, v146 quad_perm:[1,0,3,2] row_mask:0xf bank_mask:0xf bound_ctrl:1
	global_store_dwordx2 v[44:45], v[22:23], off offset:2048 nt
	s_nop 0
	v_add_f32_dpp v18, v18, v18 quad_perm:[2,3,0,1] row_mask:0xf bank_mask:0xf bound_ctrl:1
	s_nop 1
	v_add_f32_dpp v18, v18, v18 row_half_mirror row_mask:0xf bank_mask:0xf bound_ctrl:1
	s_nop 1
	v_add_f32_dpp v18, v18, v18 row_mirror row_mask:0xf bank_mask:0xf bound_ctrl:1
	s_nop 0
	v_readlane_b32 s9, v18, 16
	v_readlane_b32 s12, v18, 48
	v_readlane_b32 s6, v18, 0
	v_readlane_b32 s7, v18, 32
	v_mov_b32_e32 v18, s9
	v_mov_b32_e32 v19, s12
	v_pk_add_f32 v[18:19], s[6:7], v[18:19]
	s_nop 0
	v_add_f32_e32 v18, v18, v19
	v_fmamk_f32 v18, v18, 0x3b800000, v252
	v_cmp_gt_f32_e32 vcc, s55, v18
	v_mul_f32_e32 v19, 0x4f800000, v18
	s_nop 0
	v_cndmask_b32_e32 v18, v18, v19, vcc
	v_sqrt_f32_e32 v19, v18
	s_nop 0
	v_add_u32_e32 v22, -1, v19
	v_fma_f32 v23, -v22, v19, v18
	v_cmp_ge_f32_e64 s[6:7], 0, v23
	v_add_u32_e32 v23, 1, v19
	s_nop 0
	v_cndmask_b32_e64 v22, v19, v22, s[6:7]
	v_fma_f32 v19, -v23, v19, v18
	v_cmp_lt_f32_e64 s[6:7], 0, v19
	s_nop 1
	v_cndmask_b32_e64 v19, v22, v23, s[6:7]
	v_mul_f32_e32 v22, 0x37800000, v19
	v_cndmask_b32_e32 v19, v19, v22, vcc
	v_cmp_class_f32_e32 vcc, v18, v253
	s_nop 1
	v_cndmask_b32_e32 v18, v19, v18, vcc
	v_div_scale_f32 v19, s[6:7], v18, v18, 1.0
	v_rcp_f32_e32 v22, v19
	s_nop 0
	v_fma_f32 v23, -v19, v22, 1.0
	v_fmac_f32_e32 v22, v23, v22
	v_div_scale_f32 v23, vcc, 1.0, v18, 1.0
	v_mul_f32_e32 v26, v23, v22
	v_fma_f32 v27, -v19, v26, v23
	v_fmac_f32_e32 v26, v27, v22
	v_fma_f32 v19, -v19, v26, v23
	v_div_fmas_f32 v19, v19, v22, v26
	v_div_fixup_f32 v18, v19, v18, 1.0
	v_lshlrev_b32_e32 v22, 16, v14
	v_and_b32_e32 v23, 0xffff0000, v14
	v_lshlrev_b32_e32 v14, 16, v15
	v_and_b32_e32 v15, 0xffff0000, v15
	v_pk_mul_f32 v[26:27], v[70:71], v[18:19] op_sel_hi:[1,0]
	v_pk_mul_f32 v[18:19], v[68:69], v[18:19] op_sel_hi:[1,0]
	s_nop 0
	v_pk_mul_f32 v[14:15], v[18:19], v[14:15]
	v_pk_mul_f32 v[18:19], v[26:27], v[22:23]
	s_nop 0
	v_cvt_pk_bf16_f32 v18, v18, v19
	v_cvt_pk_bf16_f32 v19, v14, v15
	v_add_f32_dpp v14, v141, v141 quad_perm:[1,0,3,2] row_mask:0xf bank_mask:0xf bound_ctrl:1
	global_store_dwordx2 v[44:45], v[18:19], off offset:2560 nt
	s_nop 0
	v_add_f32_dpp v14, v14, v14 quad_perm:[2,3,0,1] row_mask:0xf bank_mask:0xf bound_ctrl:1
	s_nop 1
	v_add_f32_dpp v14, v14, v14 row_half_mirror row_mask:0xf bank_mask:0xf bound_ctrl:1
	s_nop 1
	v_add_f32_dpp v14, v14, v14 row_mirror row_mask:0xf bank_mask:0xf bound_ctrl:1
	s_nop 0
	v_readlane_b32 s9, v14, 16
	v_readlane_b32 s12, v14, 48
	v_readlane_b32 s6, v14, 0
	v_readlane_b32 s7, v14, 32
	v_mov_b32_e32 v14, s9
	v_mov_b32_e32 v15, s12
	v_pk_add_f32 v[14:15], s[6:7], v[14:15]
	s_nop 0
	v_add_f32_e32 v14, v14, v15
	v_fmamk_f32 v14, v14, 0x3b800000, v252
	v_cmp_gt_f32_e32 vcc, s55, v14
	v_mul_f32_e32 v15, 0x4f800000, v14
	s_nop 0
	v_cndmask_b32_e32 v14, v14, v15, vcc
	v_sqrt_f32_e32 v15, v14
	s_nop 0
	v_add_u32_e32 v18, -1, v15
	v_fma_f32 v19, -v18, v15, v14
	v_cmp_ge_f32_e64 s[6:7], 0, v19
	v_add_u32_e32 v19, 1, v15
	s_nop 0
	v_cndmask_b32_e64 v18, v15, v18, s[6:7]
	v_fma_f32 v15, -v19, v15, v14
	v_cmp_lt_f32_e64 s[6:7], 0, v15
	s_nop 1
	v_cndmask_b32_e64 v15, v18, v19, s[6:7]
	v_mul_f32_e32 v18, 0x37800000, v15
	v_cndmask_b32_e32 v15, v15, v18, vcc
	v_cmp_class_f32_e32 vcc, v14, v253
	s_nop 1
	v_cndmask_b32_e32 v14, v15, v14, vcc
	v_div_scale_f32 v15, s[6:7], v14, v14, 1.0
	v_rcp_f32_e32 v18, v15
	s_nop 0
	v_fma_f32 v19, -v15, v18, 1.0
	v_fmac_f32_e32 v18, v19, v18
	v_div_scale_f32 v19, vcc, 1.0, v14, 1.0
	v_mul_f32_e32 v22, v19, v18
	v_fma_f32 v23, -v15, v22, v19
	v_fmac_f32_e32 v22, v23, v18
	v_fma_f32 v15, -v15, v22, v19
	v_div_fmas_f32 v15, v15, v18, v22
	v_div_fixup_f32 v14, v15, v14, 1.0
	v_lshlrev_b32_e32 v18, 16, v12
	v_and_b32_e32 v19, 0xffff0000, v12
	v_lshlrev_b32_e32 v12, 16, v13
	v_and_b32_e32 v13, 0xffff0000, v13
	v_pk_mul_f32 v[22:23], v[62:63], v[14:15] op_sel_hi:[1,0]
	v_pk_mul_f32 v[14:15], v[56:57], v[14:15] op_sel_hi:[1,0]
	s_nop 0
	v_pk_mul_f32 v[12:13], v[14:15], v[12:13]
	v_pk_mul_f32 v[14:15], v[22:23], v[18:19]
	s_nop 0
	v_cvt_pk_bf16_f32 v14, v14, v15
	v_cvt_pk_bf16_f32 v15, v12, v13
	v_add_f32_dpp v12, v140, v140 quad_perm:[1,0,3,2] row_mask:0xf bank_mask:0xf bound_ctrl:1
	global_store_dwordx2 v[44:45], v[14:15], off offset:3072 nt
; template <bool HG>
; __device__ __forceinline__ void readout_phase2(const Args& a, Frame& F, const float* gain, int nrows) {
;     ...
;     RO_FINISH(f0, b0, g0, nw + 3 * 2048); RO_LOAD(f0, b0, g0, nw + 6 * 2048);
	s_nop 0
	v_add_f32_dpp v12, v12, v12 quad_perm:[2,3,0,1] row_mask:0xf bank_mask:0xf bound_ctrl:1
	s_nop 1
	v_add_f32_dpp v12, v12, v12 row_half_mirror row_mask:0xf bank_mask:0xf bound_ctrl:1
	s_nop 1
	v_add_f32_dpp v12, v12, v12 row_mirror row_mask:0xf bank_mask:0xf bound_ctrl:1
	s_nop 0
	v_readlane_b32 s9, v12, 16
	v_readlane_b32 s12, v12, 48
	v_readlane_b32 s6, v12, 0
	v_readlane_b32 s7, v12, 32
	v_mov_b32_e32 v12, s9
	v_mov_b32_e32 v13, s12
	v_pk_add_f32 v[12:13], s[6:7], v[12:13]
	s_add_u32 s12, s10, 0x2800000
	v_add_f32_e32 v12, v12, v13
	v_fmamk_f32 v12, v12, 0x3b800000, v252
	v_cmp_gt_f32_e32 vcc, s55, v12
	v_mul_f32_e32 v13, 0x4f800000, v12
	s_addc_u32 s13, s11, 0
	v_cndmask_b32_e32 v12, v12, v13, vcc
	v_sqrt_f32_e32 v13, v12
	s_add_u32 s40, s10, 0x3000000
	s_addc_u32 s41, s11, 0
	s_add_i32 s82, s8, 0x4000
	v_add_u32_e32 v14, -1, v13
	v_fma_f32 v15, -v14, v13, v12
	v_cmp_ge_f32_e64 s[6:7], 0, v15
	v_add_u32_e32 v15, 1, v13
	s_nop 0
	v_cndmask_b32_e64 v14, v13, v14, s[6:7]
	v_fma_f32 v13, -v15, v13, v12
	v_cmp_lt_f32_e64 s[6:7], 0, v13
	s_nop 1
	v_cndmask_b32_e64 v13, v14, v15, s[6:7]
	v_mul_f32_e32 v14, 0x37800000, v13
	v_cndmask_b32_e32 v13, v13, v14, vcc
	v_cmp_class_f32_e32 vcc, v12, v253
	s_nop 1
	v_cndmask_b32_e32 v12, v13, v12, vcc
	v_div_scale_f32 v13, s[6:7], v12, v12, 1.0
	v_rcp_f32_e32 v14, v13
	s_nop 0
	v_fma_f32 v15, -v13, v14, 1.0
	v_fmac_f32_e32 v14, v15, v14
	v_div_scale_f32 v15, vcc, 1.0, v12, 1.0
	v_mul_f32_e32 v18, v15, v14
	v_fma_f32 v19, -v13, v18, v15
	v_fmac_f32_e32 v18, v19, v14
	v_fma_f32 v13, -v13, v18, v15
	v_div_fmas_f32 v13, v13, v14, v18
	v_div_fixup_f32 v12, v13, v12, 1.0
	s_waitcnt vmcnt(62)
	v_lshlrev_b32_e32 v14, 16, v10
	v_and_b32_e32 v15, 0xffff0000, v10
	v_lshlrev_b32_e32 v10, 16, v11
	v_and_b32_e32 v11, 0xffff0000, v11
	v_pk_mul_f32 v[18:19], v[50:51], v[12:13] op_sel_hi:[1,0]
	v_pk_mul_f32 v[12:13], v[38:39], v[12:13] op_sel_hi:[1,0]
	s_nop 0
	v_pk_mul_f32 v[10:11], v[12:13], v[10:11]
	v_pk_mul_f32 v[12:13], v[18:19], v[14:15]
	v_lshl_add_u64 v[14:15], v[8:9], 0, s[12:13]
	v_cvt_pk_bf16_f32 v12, v12, v13
	v_cvt_pk_bf16_f32 v13, v10, v11
	global_store_dwordx2 v[44:45], v[12:13], off offset:3584 nt
	v_lshl_add_u64 v[10:11], v[4:5], 0, s[12:13]
	v_lshl_add_u64 v[12:13], v[6:7], 0, s[12:13]
	v_lshl_add_u64 v[10:11], v[10:11], 0, v[0:1]
	v_lshl_add_u64 v[12:13], v[12:13], 0, v[0:1]
	v_lshl_add_u64 v[14:15], v[14:15], 0, v[0:1]
	global_load_dwordx2 v[158:159], v[10:11], off nt
	global_load_dwordx2 v[152:153], v[12:13], off nt
	global_load_dwordx2 v[62:63], v[14:15], off nt
	global_load_dwordx2 v[146:147], v[10:11], off offset:512 nt
	global_load_dwordx2 v[140:141], v[12:13], off offset:512 nt
	global_load_dwordx2 v[56:57], v[14:15], off offset:512 nt
	global_load_dwordx2 v[134:135], v[10:11], off offset:1024 nt
	global_load_dwordx2 v[88:89], v[12:13], off offset:1024 nt
	global_load_dwordx2 v[50:51], v[14:15], off offset:1024 nt
	global_load_dwordx2 v[84:85], v[10:11], off offset:1536 nt
	global_load_dwordx2 v[86:87], v[12:13], off offset:1536 nt
	global_load_dwordx2 v[44:45], v[14:15], off offset:1536 nt
	global_load_dwordx2 v[82:83], v[10:11], off offset:2048 nt
	global_load_dwordx2 v[80:81], v[12:13], off offset:2048 nt
	global_load_dwordx2 v[38:39], v[14:15], off offset:2048 nt
	global_load_dwordx2 v[78:79], v[10:11], off offset:2560 nt
	global_load_dwordx2 v[76:77], v[12:13], off offset:2560 nt
	global_load_dwordx2 v[34:35], v[14:15], off offset:2560 nt
	global_load_dwordx2 v[74:75], v[10:11], off offset:3072 nt
	global_load_dwordx2 v[72:73], v[12:13], off offset:3072 nt
	global_load_dwordx2 v[30:31], v[14:15], off offset:3072 nt
	global_load_dwordx2 v[68:69], v[10:11], off offset:3584 nt
	global_load_dwordx2 v[70:71], v[12:13], off offset:3584 nt
	global_load_dwordx2 v[26:27], v[14:15], off offset:3584 nt
	v_lshlrev_b32_e32 v10, 16, v160
	v_and_b32_e32 v11, 0xffff0000, v160
	s_waitcnt vmcnt(62)
	v_lshlrev_b32_e32 v12, 16, v154
	v_and_b32_e32 v13, 0xffff0000, v154
	v_pk_add_f32 v[164:165], v[10:11], v[12:13]
	v_lshlrev_b32_e32 v10, 16, v161
	v_and_b32_e32 v11, 0xffff0000, v161
	v_lshlrev_b32_e32 v12, 16, v155
	v_and_b32_e32 v13, 0xffff0000, v155
	v_pk_add_f32 v[160:161], v[10:11], v[12:13]
	v_mov_b32_e32 v12, v165
	v_mov_b32_e32 v13, v161
	v_mov_b32_e32 v10, v164
	v_mov_b32_e32 v11, v160
	v_pk_mul_f32 v[12:13], v[12:13], v[12:13]
	v_lshlrev_b32_e32 v14, 16, v95
	v_pk_fma_f32 v[10:11], v[10:11], v[10:11], v[12:13]
	v_lshlrev_b32_e32 v12, 16, v142
	v_add_f32_e32 v167, v10, v11
	v_lshlrev_b32_e32 v10, 16, v148
	v_and_b32_e32 v11, 0xffff0000, v148
	v_and_b32_e32 v13, 0xffff0000, v142
	v_pk_add_f32 v[154:155], v[10:11], v[12:13]
	v_lshlrev_b32_e32 v10, 16, v149
	v_and_b32_e32 v11, 0xffff0000, v149
	v_lshlrev_b32_e32 v12, 16, v143
	v_and_b32_e32 v13, 0xffff0000, v143
	v_pk_add_f32 v[148:149], v[10:11], v[12:13]
	v_mov_b32_e32 v12, v155
	v_mov_b32_e32 v13, v149
	v_mov_b32_e32 v10, v154
	v_mov_b32_e32 v11, v148
	v_pk_mul_f32 v[12:13], v[12:13], v[12:13]
	v_and_b32_e32 v15, 0xffff0000, v95
	v_pk_fma_f32 v[10:11], v[10:11], v[10:11], v[12:13]
	v_lshlrev_b32_e32 v12, 16, v130
	v_add_f32_e32 v168, v10, v11
	v_lshlrev_b32_e32 v10, 16, v136
	v_and_b32_e32 v11, 0xffff0000, v136
	v_and_b32_e32 v13, 0xffff0000, v130
	v_pk_add_f32 v[142:143], v[10:11], v[12:13]
	v_lshlrev_b32_e32 v10, 16, v137
	v_and_b32_e32 v11, 0xffff0000, v137
	v_lshlrev_b32_e32 v12, 16, v131
	v_and_b32_e32 v13, 0xffff0000, v131
	v_pk_add_f32 v[136:137], v[10:11], v[12:13]
	v_mov_b32_e32 v12, v143
	v_mov_b32_e32 v13, v137
	v_mov_b32_e32 v10, v142
	v_mov_b32_e32 v11, v136
	v_pk_mul_f32 v[12:13], v[12:13], v[12:13]
	s_nop 0
	v_pk_fma_f32 v[10:11], v[10:11], v[10:11], v[12:13]
	v_lshlrev_b32_e32 v12, 16, v126
	v_add_f32_e32 v169, v10, v11
	v_lshlrev_b32_e32 v10, 16, v122
	v_and_b32_e32 v11, 0xffff0000, v122
	v_and_b32_e32 v13, 0xffff0000, v126
	v_pk_add_f32 v[130:131], v[10:11], v[12:13]
	v_lshlrev_b32_e32 v10, 16, v123
	v_and_b32_e32 v11, 0xffff0000, v123
	v_lshlrev_b32_e32 v12, 16, v127
	v_and_b32_e32 v13, 0xffff0000, v127
	v_pk_add_f32 v[126:127], v[10:11], v[12:13]
	v_mov_b32_e32 v12, v131
	v_mov_b32_e32 v13, v127
	v_mov_b32_e32 v10, v130
	v_mov_b32_e32 v11, v126
	v_pk_mul_f32 v[12:13], v[12:13], v[12:13]
	s_nop 0
	v_pk_fma_f32 v[10:11], v[10:11], v[10:11], v[12:13]
	v_lshlrev_b32_e32 v12, 16, v114
	v_add_f32_e32 v170, v10, v11
	v_lshlrev_b32_e32 v10, 16, v118
	v_and_b32_e32 v11, 0xffff0000, v118
	v_and_b32_e32 v13, 0xffff0000, v114
	v_pk_add_f32 v[122:123], v[10:11], v[12:13]
	v_lshlrev_b32_e32 v10, 16, v119
	v_and_b32_e32 v11, 0xffff0000, v119
	v_lshlrev_b32_e32 v12, 16, v115
	v_and_b32_e32 v13, 0xffff0000, v115
	v_pk_add_f32 v[118:119], v[10:11], v[12:13]
	v_mov_b32_e32 v12, v123
	v_mov_b32_e32 v13, v119
	v_mov_b32_e32 v10, v122
	v_mov_b32_e32 v11, v118
	v_pk_mul_f32 v[12:13], v[12:13], v[12:13]
	s_nop 0
	v_pk_fma_f32 v[10:11], v[10:11], v[10:11], v[12:13]
	v_lshlrev_b32_e32 v12, 16, v106
	v_add_f32_e32 v166, v10, v11
	v_lshlrev_b32_e32 v10, 16, v110
	v_and_b32_e32 v11, 0xffff0000, v110
	v_and_b32_e32 v13, 0xffff0000, v106
	v_pk_add_f32 v[114:115], v[10:11], v[12:13]
	v_lshlrev_b32_e32 v10, 16, v111
	v_and_b32_e32 v11, 0xffff0000, v111
	v_lshlrev_b32_e32 v12, 16, v107
	v_and_b32_e32 v13, 0xffff0000, v107
	v_pk_add_f32 v[106:107], v[10:11], v[12:13]
	v_mov_b32_e32 v12, v115
	v_mov_b32_e32 v13, v107
	v_mov_b32_e32 v10, v114
	v_mov_b32_e32 v11, v106
	v_pk_mul_f32 v[12:13], v[12:13], v[12:13]
	s_nop 0
	v_pk_fma_f32 v[10:11], v[10:11], v[10:11], v[12:13]
	v_lshlrev_b32_e32 v12, 16, v98
	v_add_f32_e32 v110, v10, v11
	v_lshlrev_b32_e32 v10, 16, v102
	v_and_b32_e32 v11, 0xffff0000, v102
	v_and_b32_e32 v13, 0xffff0000, v98
	v_pk_add_f32 v[18:19], v[10:11], v[12:13]
	v_lshlrev_b32_e32 v10, 16, v103
	v_and_b32_e32 v11, 0xffff0000, v103
	v_lshlrev_b32_e32 v12, 16, v99
	v_and_b32_e32 v13, 0xffff0000, v99
	v_pk_add_f32 v[22:23], v[10:11], v[12:13]
	v_mov_b32_e32 v12, v19
	v_mov_b32_e32 v13, v23
	v_mov_b32_e32 v10, v18
	v_mov_b32_e32 v11, v22
	v_pk_mul_f32 v[12:13], v[12:13], v[12:13]
	s_nop 0
	v_pk_fma_f32 v[10:11], v[10:11], v[10:11], v[12:13]
	v_lshlrev_b32_e32 v12, 16, v94
	v_add_f32_e32 v98, v10, v11
	v_lshlrev_b32_e32 v10, 16, v90
	v_and_b32_e32 v11, 0xffff0000, v90
	v_and_b32_e32 v13, 0xffff0000, v94
	v_pk_add_f32 v[10:11], v[10:11], v[12:13]
	v_lshlrev_b32_e32 v12, 16, v91
	v_and_b32_e32 v13, 0xffff0000, v91
	v_pk_add_f32 v[12:13], v[12:13], v[14:15]
	v_mov_b32_e32 v90, v11
	v_mov_b32_e32 v91, v13
	v_mov_b32_e32 v14, v10
	v_mov_b32_e32 v15, v12
	v_pk_mul_f32 v[90:91], v[90:91], v[90:91]
	s_nop 0
	v_pk_fma_f32 v[14:15], v[14:15], v[14:15], v[90:91]
	v_add_f32_dpp v91, v167, v167 quad_perm:[1,0,3,2] row_mask:0xf bank_mask:0xf bound_ctrl:1
	v_add_f32_e32 v90, v14, v15
	v_lshl_add_u64 v[14:15], v[2:3], 0, s[14:15]
	v_add_f32_dpp v91, v91, v91 quad_perm:[2,3,0,1] row_mask:0xf bank_mask:0xf bound_ctrl:1
	v_lshl_add_u64 v[14:15], v[14:15], 0, v[0:1]
	s_nop 0
	v_add_f32_dpp v91, v91, v91 row_half_mirror row_mask:0xf bank_mask:0xf bound_ctrl:1
	s_nop 1
	v_add_f32_dpp v91, v91, v91 row_mirror row_mask:0xf bank_mask:0xf bound_ctrl:1
	s_nop 0
	v_readlane_b32 s9, v91, 16
	v_readlane_b32 s14, v91, 48
	v_readlane_b32 s6, v91, 0
	v_readlane_b32 s7, v91, 32
	v_mov_b32_e32 v94, s9
	v_mov_b32_e32 v95, s14
	v_pk_add_f32 v[94:95], s[6:7], v[94:95]
	s_nop 0
	v_add_f32_e32 v91, v94, v95
	v_fmamk_f32 v91, v91, 0x3b800000, v252
	v_cmp_gt_f32_e32 vcc, s55, v91
	v_mul_f32_e32 v94, 0x4f800000, v91
	s_nop 0
	v_cndmask_b32_e32 v91, v91, v94, vcc
	v_sqrt_f32_e32 v94, v91
	s_nop 0
	v_add_u32_e32 v95, -1, v94
	v_fma_f32 v99, -v95, v94, v91
	v_cmp_ge_f32_e64 s[6:7], 0, v99
	v_add_u32_e32 v99, 1, v94
	s_nop 0
	v_cndmask_b32_e64 v95, v94, v95, s[6:7]
	v_fma_f32 v94, -v99, v94, v91
	v_cmp_lt_f32_e64 s[6:7], 0, v94
	s_nop 1
	v_cndmask_b32_e64 v94, v95, v99, s[6:7]
	v_mul_f32_e32 v95, 0x37800000, v94
	v_cndmask_b32_e32 v94, v94, v95, vcc
	v_cmp_class_f32_e32 vcc, v91, v253
	s_nop 1
	v_cndmask_b32_e32 v91, v94, v91, vcc
	v_div_scale_f32 v94, s[6:7], v91, v91, 1.0
	v_rcp_f32_e32 v95, v94
	s_nop 0
	v_fma_f32 v99, -v94, v95, 1.0
	v_fmac_f32_e32 v95, v99, v95
	v_div_scale_f32 v99, vcc, 1.0, v91, 1.0
	v_mul_f32_e32 v102, v99, v95
	v_fma_f32 v103, -v94, v102, v99
	v_fmac_f32_e32 v102, v103, v95
	v_fma_f32 v94, -v94, v102, v99
	v_div_fmas_f32 v94, v94, v95, v102
	v_div_fixup_f32 v94, v94, v91, 1.0
	v_lshlrev_b32_e32 v102, 16, v64
	v_and_b32_e32 v103, 0xffff0000, v64
	v_lshlrev_b32_e32 v64, 16, v65
	v_and_b32_e32 v65, 0xffff0000, v65
	v_pk_mul_f32 v[164:165], v[164:165], v[94:95] op_sel_hi:[1,0]
	v_pk_mul_f32 v[94:95], v[160:161], v[94:95] op_sel_hi:[1,0]
	s_nop 0
	v_pk_mul_f32 v[64:65], v[94:95], v[64:65]
	v_pk_mul_f32 v[94:95], v[164:165], v[102:103]
	s_nop 0
	v_cvt_pk_bf16_f32 v94, v94, v95
	v_cvt_pk_bf16_f32 v95, v64, v65
	v_add_f32_dpp v64, v168, v168 quad_perm:[1,0,3,2] row_mask:0xf bank_mask:0xf bound_ctrl:1
	global_store_dwordx2 v[14:15], v[94:95], off nt
	s_nop 0
	v_add_f32_dpp v64, v64, v64 quad_perm:[2,3,0,1] row_mask:0xf bank_mask:0xf bound_ctrl:1
	s_nop 1
	v_add_f32_dpp v64, v64, v64 row_half_mirror row_mask:0xf bank_mask:0xf bound_ctrl:1
	s_nop 1
	v_add_f32_dpp v64, v64, v64 row_mirror row_mask:0xf bank_mask:0xf bound_ctrl:1
	s_nop 0
	v_readlane_b32 s9, v64, 16
	v_readlane_b32 s14, v64, 48
	v_readlane_b32 s6, v64, 0
	v_readlane_b32 s7, v64, 32
	v_mov_b32_e32 v64, s9
	v_mov_b32_e32 v65, s14
	v_pk_add_f32 v[64:65], s[6:7], v[64:65]
	s_nop 0
	v_add_f32_e32 v64, v64, v65
	v_fmamk_f32 v64, v64, 0x3b800000, v252
	v_cmp_gt_f32_e32 vcc, s55, v64
	v_mul_f32_e32 v65, 0x4f800000, v64
	s_nop 0
	v_cndmask_b32_e32 v64, v64, v65, vcc
	v_sqrt_f32_e32 v65, v64
	s_nop 0
	v_add_u32_e32 v91, -1, v65
	v_fma_f32 v94, -v91, v65, v64
	v_cmp_ge_f32_e64 s[6:7], 0, v94
	v_add_u32_e32 v94, 1, v65
	s_nop 0
	v_cndmask_b32_e64 v91, v65, v91, s[6:7]
	v_fma_f32 v65, -v94, v65, v64
	v_cmp_lt_f32_e64 s[6:7], 0, v65
	s_nop 1
	v_cndmask_b32_e64 v65, v91, v94, s[6:7]
	v_mul_f32_e32 v91, 0x37800000, v65
	v_cndmask_b32_e32 v65, v65, v91, vcc
	v_cmp_class_f32_e32 vcc, v64, v253
	s_nop 1
	v_cndmask_b32_e32 v64, v65, v64, vcc
	v_div_scale_f32 v65, s[6:7], v64, v64, 1.0
	v_rcp_f32_e32 v91, v65
	s_nop 0
	v_fma_f32 v94, -v65, v91, 1.0
	v_fmac_f32_e32 v91, v94, v91
	v_div_scale_f32 v94, vcc, 1.0, v64, 1.0
	v_mul_f32_e32 v95, v94, v91
	v_fma_f32 v99, -v65, v95, v94
	v_fmac_f32_e32 v95, v99, v91
	v_fma_f32 v65, -v65, v95, v94
	v_div_fmas_f32 v65, v65, v91, v95
	v_div_fixup_f32 v64, v65, v64, 1.0
	v_lshlrev_b32_e32 v94, 16, v58
	v_and_b32_e32 v95, 0xffff0000, v58
	v_lshlrev_b32_e32 v58, 16, v59
	v_and_b32_e32 v59, 0xffff0000, v59
	v_pk_mul_f32 v[102:103], v[154:155], v[64:65] op_sel_hi:[1,0]
	v_pk_mul_f32 v[64:65], v[148:149], v[64:65] op_sel_hi:[1,0]
	s_nop 0
	v_pk_mul_f32 v[58:59], v[64:65], v[58:59]
	v_pk_mul_f32 v[64:65], v[102:103], v[94:95]
	s_nop 0
	v_cvt_pk_bf16_f32 v64, v64, v65
	v_cvt_pk_bf16_f32 v65, v58, v59
	v_add_f32_dpp v58, v169, v169 quad_perm:[1,0,3,2] row_mask:0xf bank_mask:0xf bound_ctrl:1
	global_store_dwordx2 v[14:15], v[64:65], off offset:512 nt
	s_nop 0
	v_add_f32_dpp v58, v58, v58 quad_perm:[2,3,0,1] row_mask:0xf bank_mask:0xf bound_ctrl:1
	s_nop 1
	v_add_f32_dpp v58, v58, v58 row_half_mirror row_mask:0xf bank_mask:0xf bound_ctrl:1
	s_nop 1
	v_add_f32_dpp v58, v58, v58 row_mirror row_mask:0xf bank_mask:0xf bound_ctrl:1
	s_nop 0
	v_readlane_b32 s9, v58, 16
	v_readlane_b32 s14, v58, 48
	v_readlane_b32 s6, v58, 0
	v_readlane_b32 s7, v58, 32
	v_mov_b32_e32 v58, s9
	v_mov_b32_e32 v59, s14
	v_pk_add_f32 v[58:59], s[6:7], v[58:59]
	s_nop 0
	v_add_f32_e32 v58, v58, v59
	v_fmamk_f32 v58, v58, 0x3b800000, v252
	v_cmp_gt_f32_e32 vcc, s55, v58
	v_mul_f32_e32 v59, 0x4f800000, v58
	s_nop 0
	v_cndmask_b32_e32 v58, v58, v59, vcc
	v_sqrt_f32_e32 v59, v58
	s_nop 0
	v_add_u32_e32 v64, -1, v59
	v_fma_f32 v65, -v64, v59, v58
	v_cmp_ge_f32_e64 s[6:7], 0, v65
	v_add_u32_e32 v65, 1, v59
	s_nop 0
	v_cndmask_b32_e64 v64, v59, v64, s[6:7]
	v_fma_f32 v59, -v65, v59, v58
	v_cmp_lt_f32_e64 s[6:7], 0, v59
	s_nop 1
	v_cndmask_b32_e64 v59, v64, v65, s[6:7]
	v_mul_f32_e32 v64, 0x37800000, v59
	v_cndmask_b32_e32 v59, v59, v64, vcc
	v_cmp_class_f32_e32 vcc, v58, v253
	s_nop 1
	v_cndmask_b32_e32 v58, v59, v58, vcc
	v_div_scale_f32 v59, s[6:7], v58, v58, 1.0
	v_rcp_f32_e32 v64, v59
	s_nop 0
	v_fma_f32 v65, -v59, v64, 1.0
	v_fmac_f32_e32 v64, v65, v64
	v_div_scale_f32 v65, vcc, 1.0, v58, 1.0
	v_mul_f32_e32 v91, v65, v64
	v_fma_f32 v94, -v59, v91, v65
	v_fmac_f32_e32 v91, v94, v64
	v_fma_f32 v59, -v59, v91, v65
	v_div_fmas_f32 v59, v59, v64, v91
	v_div_fixup_f32 v58, v59, v58, 1.0
	v_lshlrev_b32_e32 v64, 16, v52
	v_and_b32_e32 v65, 0xffff0000, v52
	v_lshlrev_b32_e32 v52, 16, v53
	v_and_b32_e32 v53, 0xffff0000, v53
	v_pk_mul_f32 v[94:95], v[142:143], v[58:59] op_sel_hi:[1,0]
	v_pk_mul_f32 v[58:59], v[136:137], v[58:59] op_sel_hi:[1,0]
	s_nop 0
	v_pk_mul_f32 v[52:53], v[58:59], v[52:53]
	v_pk_mul_f32 v[58:59], v[94:95], v[64:65]
	s_nop 0
	v_cvt_pk_bf16_f32 v58, v58, v59
	v_cvt_pk_bf16_f32 v59, v52, v53
	v_add_f32_dpp v52, v170, v170 quad_perm:[1,0,3,2] row_mask:0xf bank_mask:0xf bound_ctrl:1
	global_store_dwordx2 v[14:15], v[58:59], off offset:1024 nt
	s_nop 0
	v_add_f32_dpp v52, v52, v52 quad_perm:[2,3,0,1] row_mask:0xf bank_mask:0xf bound_ctrl:1
	s_nop 1
	v_add_f32_dpp v52, v52, v52 row_half_mirror row_mask:0xf bank_mask:0xf bound_ctrl:1
	s_nop 1
	v_add_f32_dpp v52, v52, v52 row_mirror row_mask:0xf bank_mask:0xf bound_ctrl:1
	s_nop 0
	v_readlane_b32 s9, v52, 16
	v_readlane_b32 s14, v52, 48
	v_readlane_b32 s6, v52, 0
	v_readlane_b32 s7, v52, 32
	v_mov_b32_e32 v52, s9
	v_mov_b32_e32 v53, s14
	v_pk_add_f32 v[52:53], s[6:7], v[52:53]
	s_nop 0
	v_add_f32_e32 v52, v52, v53
	v_fmamk_f32 v52, v52, 0x3b800000, v252
	v_cmp_gt_f32_e32 vcc, s55, v52
	v_mul_f32_e32 v53, 0x4f800000, v52
	s_nop 0
	v_cndmask_b32_e32 v52, v52, v53, vcc
	v_sqrt_f32_e32 v53, v52
	s_nop 0
	v_add_u32_e32 v58, -1, v53
	v_fma_f32 v59, -v58, v53, v52
	v_cmp_ge_f32_e64 s[6:7], 0, v59
	v_add_u32_e32 v59, 1, v53
	s_nop 0
	v_cndmask_b32_e64 v58, v53, v58, s[6:7]
	v_fma_f32 v53, -v59, v53, v52
	v_cmp_lt_f32_e64 s[6:7], 0, v53
	s_nop 1
	v_cndmask_b32_e64 v53, v58, v59, s[6:7]
	v_mul_f32_e32 v58, 0x37800000, v53
	v_cndmask_b32_e32 v53, v53, v58, vcc
	v_cmp_class_f32_e32 vcc, v52, v253
	s_nop 1
	v_cndmask_b32_e32 v52, v53, v52, vcc
	v_div_scale_f32 v53, s[6:7], v52, v52, 1.0
	v_rcp_f32_e32 v58, v53
	s_nop 0
	v_fma_f32 v59, -v53, v58, 1.0
	v_fmac_f32_e32 v58, v59, v58
	v_div_scale_f32 v59, vcc, 1.0, v52, 1.0
	v_mul_f32_e32 v64, v59, v58
	v_fma_f32 v65, -v53, v64, v59
	v_fmac_f32_e32 v64, v65, v58
	v_fma_f32 v53, -v53, v64, v59
	v_div_fmas_f32 v53, v53, v58, v64
	v_div_fixup_f32 v52, v53, v52, 1.0
	v_lshlrev_b32_e32 v58, 16, v46
	v_and_b32_e32 v59, 0xffff0000, v46
	v_lshlrev_b32_e32 v46, 16, v47
	v_and_b32_e32 v47, 0xffff0000, v47
	v_pk_mul_f32 v[64:65], v[130:131], v[52:53] op_sel_hi:[1,0]
	v_pk_mul_f32 v[52:53], v[126:127], v[52:53] op_sel_hi:[1,0]
; template <int CTRL> __device__ __forceinline__ float dpp_mov(float v) { return __builtin_bit_cast(float, __builtin_amdgcn_update_dpp(0, __builtin_bit_cast(int, v), CTRL, 0xF, 0xF, true)); }
; __device__ __forceinline__ float wave_sum(float v) {
;     v += dpp_mov<0xB1>(v);
;     v += dpp_mov<0x4E>(v);
;     v += dpp_mov<0x141>(v);
;     v += dpp_mov<0x140>(v);
;     const int iv = __builtin_bit_cast(int, v);
;     const float a = __builtin_bit_cast(float, __builtin_amdgcn_readlane(iv, 0)), b = __builtin_bit_cast(float, __builtin_amdgcn_readlane(iv, 16));
;     const float c = __builtin_bit_cast(float, __builtin_amdgcn_readlane(iv, 32)), d = __builtin_bit_cast(float, __builtin_amdgcn_readlane(iv, 48));
;     return (a + b) + (c + d);
; }
	s_nop 0
	v_pk_mul_f32 v[46:47], v[52:53], v[46:47]
	v_pk_mul_f32 v[52:53], v[64:65], v[58:59]
	s_nop 0
	v_cvt_pk_bf16_f32 v52, v52, v53
	v_cvt_pk_bf16_f32 v53, v46, v47
	v_add_f32_dpp v46, v166, v166 quad_perm:[1,0,3,2] row_mask:0xf bank_mask:0xf bound_ctrl:1
	global_store_dwordx2 v[14:15], v[52:53], off offset:1536 nt
	s_nop 0
	v_add_f32_dpp v46, v46, v46 quad_perm:[2,3,0,1] row_mask:0xf bank_mask:0xf bound_ctrl:1
	s_nop 1
	v_add_f32_dpp v46, v46, v46 row_half_mirror row_mask:0xf bank_mask:0xf bound_ctrl:1
	s_nop 1
	v_add_f32_dpp v46, v46, v46 row_mirror row_mask:0xf bank_mask:0xf bound_ctrl:1
	s_nop 0
	v_readlane_b32 s9, v46, 16
	v_readlane_b32 s14, v46, 48
	v_readlane_b32 s6, v46, 0
	v_readlane_b32 s7, v46, 32
	v_mov_b32_e32 v46, s9
	v_mov_b32_e32 v47, s14
	v_pk_add_f32 v[46:47], s[6:7], v[46:47]
	s_nop 0
	v_add_f32_e32 v46, v46, v47
	v_fmamk_f32 v46, v46, 0x3b800000, v252
	v_cmp_gt_f32_e32 vcc, s55, v46
	v_mul_f32_e32 v47, 0x4f800000, v46
	s_nop 0
	v_cndmask_b32_e32 v46, v46, v47, vcc
	v_sqrt_f32_e32 v47, v46
	s_nop 0
	v_add_u32_e32 v52, -1, v47
	v_fma_f32 v53, -v52, v47, v46
	v_cmp_ge_f32_e64 s[6:7], 0, v53
	v_add_u32_e32 v53, 1, v47
	s_nop 0
	v_cndmask_b32_e64 v52, v47, v52, s[6:7]
	v_fma_f32 v47, -v53, v47, v46
	v_cmp_lt_f32_e64 s[6:7], 0, v47
	s_nop 1
	v_cndmask_b32_e64 v47, v52, v53, s[6:7]
	v_mul_f32_e32 v52, 0x37800000, v47
	v_cndmask_b32_e32 v47, v47, v52, vcc
	v_cmp_class_f32_e32 vcc, v46, v253
	s_nop 1
	v_cndmask_b32_e32 v46, v47, v46, vcc
	v_div_scale_f32 v47, s[6:7], v46, v46, 1.0
	v_rcp_f32_e32 v52, v47
	s_nop 0
	v_fma_f32 v53, -v47, v52, 1.0
	v_fmac_f32_e32 v52, v53, v52
	v_div_scale_f32 v53, vcc, 1.0, v46, 1.0
	v_mul_f32_e32 v58, v53, v52
	v_fma_f32 v59, -v47, v58, v53
	v_fmac_f32_e32 v58, v59, v52
	v_fma_f32 v47, -v47, v58, v53
	v_div_fmas_f32 v47, v47, v52, v58
	v_div_fixup_f32 v46, v47, v46, 1.0
	v_lshlrev_b32_e32 v52, 16, v40
	v_and_b32_e32 v53, 0xffff0000, v40
	v_lshlrev_b32_e32 v40, 16, v41
	v_and_b32_e32 v41, 0xffff0000, v41
	v_pk_mul_f32 v[58:59], v[122:123], v[46:47] op_sel_hi:[1,0]
	v_pk_mul_f32 v[46:47], v[118:119], v[46:47] op_sel_hi:[1,0]
	s_nop 0
	v_pk_mul_f32 v[40:41], v[46:47], v[40:41]
	v_pk_mul_f32 v[46:47], v[58:59], v[52:53]
	s_nop 0
	v_cvt_pk_bf16_f32 v46, v46, v47
	v_cvt_pk_bf16_f32 v47, v40, v41
	v_add_f32_dpp v40, v110, v110 quad_perm:[1,0,3,2] row_mask:0xf bank_mask:0xf bound_ctrl:1
	global_store_dwordx2 v[14:15], v[46:47], off offset:2048 nt
	s_nop 0
	v_add_f32_dpp v40, v40, v40 quad_perm:[2,3,0,1] row_mask:0xf bank_mask:0xf bound_ctrl:1
	s_nop 1
	v_add_f32_dpp v40, v40, v40 row_half_mirror row_mask:0xf bank_mask:0xf bound_ctrl:1
	s_nop 1
	v_add_f32_dpp v40, v40, v40 row_mirror row_mask:0xf bank_mask:0xf bound_ctrl:1
	s_nop 0
	v_readlane_b32 s9, v40, 16
	v_readlane_b32 s14, v40, 48
	v_readlane_b32 s6, v40, 0
	v_readlane_b32 s7, v40, 32
	v_mov_b32_e32 v40, s9
	v_mov_b32_e32 v41, s14
	v_pk_add_f32 v[40:41], s[6:7], v[40:41]
	s_nop 0
	v_add_f32_e32 v40, v40, v41
	v_fmamk_f32 v40, v40, 0x3b800000, v252
	v_cmp_gt_f32_e32 vcc, s55, v40
	v_mul_f32_e32 v41, 0x4f800000, v40
	s_nop 0
	v_cndmask_b32_e32 v40, v40, v41, vcc
	v_sqrt_f32_e32 v41, v40
	s_nop 0
	v_add_u32_e32 v46, -1, v41
	v_fma_f32 v47, -v46, v41, v40
	v_cmp_ge_f32_e64 s[6:7], 0, v47
	v_add_u32_e32 v47, 1, v41
	s_nop 0
	v_cndmask_b32_e64 v46, v41, v46, s[6:7]
	v_fma_f32 v41, -v47, v41, v40
	v_cmp_lt_f32_e64 s[6:7], 0, v41
	s_nop 1
	v_cndmask_b32_e64 v41, v46, v47, s[6:7]
	v_mul_f32_e32 v46, 0x37800000, v41
	v_cndmask_b32_e32 v41, v41, v46, vcc
	v_cmp_class_f32_e32 vcc, v40, v253
	s_nop 1
	v_cndmask_b32_e32 v40, v41, v40, vcc
	v_div_scale_f32 v41, s[6:7], v40, v40, 1.0
	v_rcp_f32_e32 v46, v41
	s_nop 0
	v_fma_f32 v47, -v41, v46, 1.0
	v_fmac_f32_e32 v46, v47, v46
	v_div_scale_f32 v47, vcc, 1.0, v40, 1.0
	v_mul_f32_e32 v52, v47, v46
	v_fma_f32 v53, -v41, v52, v47
	v_fmac_f32_e32 v52, v53, v46
	v_fma_f32 v41, -v41, v52, v47
	v_div_fmas_f32 v41, v41, v46, v52
	v_div_fixup_f32 v40, v41, v40, 1.0
	v_lshlrev_b32_e32 v46, 16, v24
	v_and_b32_e32 v47, 0xffff0000, v24
	v_lshlrev_b32_e32 v24, 16, v25
	v_and_b32_e32 v25, 0xffff0000, v25
	v_pk_mul_f32 v[52:53], v[114:115], v[40:41] op_sel_hi:[1,0]
	v_pk_mul_f32 v[40:41], v[106:107], v[40:41] op_sel_hi:[1,0]
	s_nop 0
	v_pk_mul_f32 v[24:25], v[40:41], v[24:25]
	v_pk_mul_f32 v[40:41], v[52:53], v[46:47]
	s_waitcnt vmcnt(38)
	v_lshlrev_b32_e32 v52, 16, v97
	v_cvt_pk_bf16_f32 v40, v40, v41
	v_cvt_pk_bf16_f32 v41, v24, v25
	v_add_f32_dpp v24, v98, v98 quad_perm:[1,0,3,2] row_mask:0xf bank_mask:0xf bound_ctrl:1
	global_store_dwordx2 v[14:15], v[40:41], off offset:2560 nt
	v_and_b32_e32 v53, 0xffff0000, v97
	v_add_f32_dpp v24, v24, v24 quad_perm:[2,3,0,1] row_mask:0xf bank_mask:0xf bound_ctrl:1
	s_nop 1
	v_add_f32_dpp v24, v24, v24 row_half_mirror row_mask:0xf bank_mask:0xf bound_ctrl:1
	s_nop 1
	v_add_f32_dpp v24, v24, v24 row_mirror row_mask:0xf bank_mask:0xf bound_ctrl:1
	s_nop 0
	v_readlane_b32 s9, v24, 16
	v_readlane_b32 s14, v24, 48
	v_readlane_b32 s6, v24, 0
	v_readlane_b32 s7, v24, 32
	v_mov_b32_e32 v24, s9
	v_mov_b32_e32 v25, s14
	v_pk_add_f32 v[24:25], s[6:7], v[24:25]
	s_nop 0
	v_add_f32_e32 v24, v24, v25
	v_fmamk_f32 v24, v24, 0x3b800000, v252
	v_cmp_gt_f32_e32 vcc, s55, v24
	v_mul_f32_e32 v25, 0x4f800000, v24
	s_nop 0
	v_cndmask_b32_e32 v24, v24, v25, vcc
	v_sqrt_f32_e32 v25, v24
	s_nop 0
	v_add_u32_e32 v40, -1, v25
	v_fma_f32 v41, -v40, v25, v24
	v_cmp_ge_f32_e64 s[6:7], 0, v41
	v_add_u32_e32 v41, 1, v25
	s_nop 0
	v_cndmask_b32_e64 v40, v25, v40, s[6:7]
	v_fma_f32 v25, -v41, v25, v24
	v_cmp_lt_f32_e64 s[6:7], 0, v25
	s_nop 1
	v_cndmask_b32_e64 v25, v40, v41, s[6:7]
	v_mul_f32_e32 v40, 0x37800000, v25
	v_cndmask_b32_e32 v25, v25, v40, vcc
	v_cmp_class_f32_e32 vcc, v24, v253
	s_nop 1
	v_cndmask_b32_e32 v24, v25, v24, vcc
	v_div_scale_f32 v25, s[6:7], v24, v24, 1.0
	v_rcp_f32_e32 v40, v25
	s_nop 0
	v_fma_f32 v41, -v25, v40, 1.0
	v_fmac_f32_e32 v40, v41, v40
	v_div_scale_f32 v41, vcc, 1.0, v24, 1.0
	v_mul_f32_e32 v46, v41, v40
	v_fma_f32 v47, -v25, v46, v41
	v_fmac_f32_e32 v46, v47, v40
	v_fma_f32 v25, -v25, v46, v41
	v_div_fmas_f32 v25, v25, v40, v46
	v_div_fixup_f32 v24, v25, v24, 1.0
	v_lshlrev_b32_e32 v40, 16, v20
	v_and_b32_e32 v41, 0xffff0000, v20
	v_lshlrev_b32_e32 v20, 16, v21
	v_and_b32_e32 v21, 0xffff0000, v21
	v_pk_mul_f32 v[18:19], v[18:19], v[24:25] op_sel_hi:[1,0]
	v_pk_mul_f32 v[22:23], v[22:23], v[24:25] op_sel_hi:[1,0]
	v_pk_mul_f32 v[18:19], v[18:19], v[40:41]
	v_pk_mul_f32 v[20:21], v[22:23], v[20:21]
	v_cvt_pk_bf16_f32 v18, v18, v19
	v_cvt_pk_bf16_f32 v19, v20, v21
	global_store_dwordx2 v[14:15], v[18:19], off offset:3072 nt
	v_add_f32_dpp v18, v90, v90 quad_perm:[1,0,3,2] row_mask:0xf bank_mask:0xf bound_ctrl:1
	s_nop 1
	v_add_f32_dpp v18, v18, v18 quad_perm:[2,3,0,1] row_mask:0xf bank_mask:0xf bound_ctrl:1
	s_nop 1
	v_add_f32_dpp v18, v18, v18 row_half_mirror row_mask:0xf bank_mask:0xf bound_ctrl:1
	s_nop 1
	v_add_f32_dpp v18, v18, v18 row_mirror row_mask:0xf bank_mask:0xf bound_ctrl:1
	s_nop 0
	v_readlane_b32 s9, v18, 16
	v_readlane_b32 s14, v18, 48
	v_readlane_b32 s6, v18, 0
	v_readlane_b32 s7, v18, 32
	v_mov_b32_e32 v18, s9
	v_mov_b32_e32 v19, s14
	v_pk_add_f32 v[18:19], s[6:7], v[18:19]
	s_nop 0
	v_add_f32_e32 v18, v18, v19
	v_fmamk_f32 v18, v18, 0x3b800000, v252
	v_cmp_gt_f32_e32 vcc, s55, v18
	v_mul_f32_e32 v19, 0x4f800000, v18
	s_nop 0
	v_cndmask_b32_e32 v18, v18, v19, vcc
	v_sqrt_f32_e32 v19, v18
	s_nop 0
	v_add_u32_e32 v20, -1, v19
	v_fma_f32 v21, -v20, v19, v18
	v_cmp_ge_f32_e64 s[6:7], 0, v21
	v_add_u32_e32 v21, 1, v19
	s_nop 0
	v_cndmask_b32_e64 v20, v19, v20, s[6:7]
	v_fma_f32 v19, -v21, v19, v18
	v_cmp_lt_f32_e64 s[6:7], 0, v19
	s_nop 1
	v_cndmask_b32_e64 v19, v20, v21, s[6:7]
	v_mul_f32_e32 v20, 0x37800000, v19
	v_cndmask_b32_e32 v19, v19, v20, vcc
	v_cmp_class_f32_e32 vcc, v18, v253
	s_nop 1
	v_cndmask_b32_e32 v18, v19, v18, vcc
	v_div_scale_f32 v19, s[6:7], v18, v18, 1.0
	v_rcp_f32_e32 v20, v19
	s_nop 0
	v_fma_f32 v21, -v19, v20, 1.0
	v_fmac_f32_e32 v20, v21, v20
	v_div_scale_f32 v21, vcc, 1.0, v18, 1.0
	v_mul_f32_e32 v22, v21, v20
	v_fma_f32 v23, -v19, v22, v21
	v_fmac_f32_e32 v22, v23, v20
	v_fma_f32 v19, -v19, v22, v21
	v_div_fmas_f32 v19, v19, v20, v22
	v_div_fixup_f32 v18, v19, v18, 1.0
	v_lshlrev_b32_e32 v20, 16, v16
	v_and_b32_e32 v21, 0xffff0000, v16
	v_lshlrev_b32_e32 v16, 16, v17
	v_and_b32_e32 v17, 0xffff0000, v17
	v_pk_mul_f32 v[10:11], v[10:11], v[18:19] op_sel_hi:[1,0]
	v_pk_mul_f32 v[12:13], v[12:13], v[18:19] op_sel_hi:[1,0]
	v_pk_mul_f32 v[10:11], v[10:11], v[20:21]
	v_pk_mul_f32 v[12:13], v[12:13], v[16:17]
	v_cvt_pk_bf16_f32 v10, v10, v11
	v_cvt_pk_bf16_f32 v11, v12, v13
	v_lshl_add_u64 v[12:13], v[6:7], 0, s[40:41]
	global_store_dwordx2 v[14:15], v[10:11], off offset:3584 nt
	v_lshl_add_u64 v[10:11], v[4:5], 0, s[40:41]
	v_lshl_add_u64 v[40:41], v[12:13], 0, v[0:1]
	v_lshl_add_u64 v[12:13], v[8:9], 0, s[40:41]
	v_lshl_add_u64 v[10:11], v[10:11], 0, v[0:1]
	v_lshl_add_u64 v[46:47], v[12:13], 0, v[0:1]
	global_load_dwordx2 v[148:149], v[10:11], off nt
	global_load_dwordx2 v[142:143], v[40:41], off nt
	global_load_dwordx2 v[24:25], v[46:47], off nt
	global_load_dwordx2 v[136:137], v[10:11], off offset:512 nt
	global_load_dwordx2 v[130:131], v[40:41], off offset:512 nt
	global_load_dwordx2 v[22:23], v[46:47], off offset:512 nt
	global_load_dwordx2 v[126:127], v[10:11], off offset:1024 nt
	global_load_dwordx2 v[122:123], v[40:41], off offset:1024 nt
	global_load_dwordx2 v[20:21], v[46:47], off offset:1024 nt
	global_load_dwordx2 v[114:115], v[10:11], off offset:1536 nt
	global_load_dwordx2 v[118:119], v[40:41], off offset:1536 nt
	global_load_dwordx2 v[18:19], v[46:47], off offset:1536 nt
	global_load_dwordx2 v[110:111], v[10:11], off offset:2048 nt
	global_load_dwordx2 v[106:107], v[40:41], off offset:2048 nt
	global_load_dwordx2 v[16:17], v[46:47], off offset:2048 nt
	global_load_dwordx2 v[102:103], v[10:11], off offset:2560 nt
	global_load_dwordx2 v[98:99], v[40:41], off offset:2560 nt
	global_load_dwordx2 v[14:15], v[46:47], off offset:2560 nt
	global_load_dwordx2 v[94:95], v[10:11], off offset:3072 nt
	global_load_dwordx2 v[90:91], v[40:41], off offset:3072 nt
	global_load_dwordx2 v[12:13], v[46:47], off offset:3072 nt
	global_load_dwordx2 v[58:59], v[10:11], off offset:3584 nt
	global_load_dwordx2 v[64:65], v[40:41], off offset:3584 nt
	s_nop 0
	global_load_dwordx2 v[10:11], v[46:47], off offset:3584 nt
	v_lshlrev_b32_e32 v40, 16, v162
	v_and_b32_e32 v41, 0xffff0000, v162
	v_lshlrev_b32_e32 v46, 16, v156
	v_and_b32_e32 v47, 0xffff0000, v156
	v_pk_add_f32 v[160:161], v[40:41], v[46:47]
	v_lshlrev_b32_e32 v40, 16, v163
	v_and_b32_e32 v41, 0xffff0000, v163
	v_lshlrev_b32_e32 v46, 16, v157
	v_and_b32_e32 v47, 0xffff0000, v157
	v_pk_add_f32 v[156:157], v[40:41], v[46:47]
	v_mov_b32_e32 v46, v161
	v_mov_b32_e32 v47, v157
	v_mov_b32_e32 v40, v160
	v_mov_b32_e32 v41, v156
	v_pk_mul_f32 v[46:47], v[46:47], v[46:47]
	s_nop 0
	v_pk_fma_f32 v[40:41], v[40:41], v[40:41], v[46:47]
	v_lshlrev_b32_e32 v46, 16, v144
	v_add_f32_e32 v164, v40, v41
	v_lshlrev_b32_e32 v40, 16, v150
	v_and_b32_e32 v41, 0xffff0000, v150
	v_and_b32_e32 v47, 0xffff0000, v144
	v_pk_add_f32 v[154:155], v[40:41], v[46:47]
	v_lshlrev_b32_e32 v40, 16, v151
	v_and_b32_e32 v41, 0xffff0000, v151
	v_lshlrev_b32_e32 v46, 16, v145
	v_and_b32_e32 v47, 0xffff0000, v145
	v_pk_add_f32 v[150:151], v[40:41], v[46:47]
	v_mov_b32_e32 v46, v155
	v_mov_b32_e32 v47, v151
	v_mov_b32_e32 v40, v154
	v_mov_b32_e32 v41, v150
	v_pk_mul_f32 v[46:47], v[46:47], v[46:47]
	s_nop 0
	v_pk_fma_f32 v[40:41], v[40:41], v[40:41], v[46:47]
	v_lshlrev_b32_e32 v46, 16, v132
	v_add_f32_e32 v166, v40, v41
	v_lshlrev_b32_e32 v40, 16, v138
	v_and_b32_e32 v41, 0xffff0000, v138
	v_and_b32_e32 v47, 0xffff0000, v132
	v_pk_add_f32 v[144:145], v[40:41], v[46:47]
	v_lshlrev_b32_e32 v40, 16, v139
	v_and_b32_e32 v41, 0xffff0000, v139
	v_lshlrev_b32_e32 v46, 16, v133
	v_and_b32_e32 v47, 0xffff0000, v133
	v_pk_add_f32 v[138:139], v[40:41], v[46:47]
	v_mov_b32_e32 v46, v145
	v_mov_b32_e32 v47, v139
	v_mov_b32_e32 v40, v144
	v_mov_b32_e32 v41, v138
	v_pk_mul_f32 v[46:47], v[46:47], v[46:47]
	s_nop 0
	v_pk_fma_f32 v[40:41], v[40:41], v[40:41], v[46:47]
	v_lshlrev_b32_e32 v46, 16, v128
	v_add_f32_e32 v167, v40, v41
	v_lshlrev_b32_e32 v40, 16, v124
	v_and_b32_e32 v41, 0xffff0000, v124
	v_and_b32_e32 v47, 0xffff0000, v128
	v_pk_add_f32 v[132:133], v[40:41], v[46:47]
	v_lshlrev_b32_e32 v40, 16, v125
	v_and_b32_e32 v41, 0xffff0000, v125
	v_lshlrev_b32_e32 v46, 16, v129
	v_and_b32_e32 v47, 0xffff0000, v129
	v_pk_add_f32 v[128:129], v[40:41], v[46:47]
	v_mov_b32_e32 v46, v133
	v_mov_b32_e32 v47, v129
	v_mov_b32_e32 v40, v132
	v_mov_b32_e32 v41, v128
	v_pk_mul_f32 v[46:47], v[46:47], v[46:47]
	s_nop 0
	v_pk_fma_f32 v[40:41], v[40:41], v[40:41], v[46:47]
	v_lshlrev_b32_e32 v46, 16, v116
	v_add_f32_e32 v168, v40, v41
	v_lshlrev_b32_e32 v40, 16, v120
	v_and_b32_e32 v41, 0xffff0000, v120
	v_and_b32_e32 v47, 0xffff0000, v116
	v_pk_add_f32 v[124:125], v[40:41], v[46:47]
	v_lshlrev_b32_e32 v40, 16, v121
	v_and_b32_e32 v41, 0xffff0000, v121
	v_lshlrev_b32_e32 v46, 16, v117
	v_and_b32_e32 v47, 0xffff0000, v117
	v_pk_add_f32 v[120:121], v[40:41], v[46:47]
	v_mov_b32_e32 v46, v125
	v_mov_b32_e32 v47, v121
	v_mov_b32_e32 v40, v124
	v_mov_b32_e32 v41, v120
	v_pk_mul_f32 v[46:47], v[46:47], v[46:47]
	s_nop 0
	v_pk_fma_f32 v[40:41], v[40:41], v[40:41], v[46:47]
	v_lshlrev_b32_e32 v46, 16, v108
	v_add_f32_e32 v163, v40, v41
	v_lshlrev_b32_e32 v40, 16, v112
	v_and_b32_e32 v41, 0xffff0000, v112
	v_and_b32_e32 v47, 0xffff0000, v108
	v_pk_add_f32 v[116:117], v[40:41], v[46:47]
	v_lshlrev_b32_e32 v40, 16, v113
	v_and_b32_e32 v41, 0xffff0000, v113
	v_lshlrev_b32_e32 v46, 16, v109
	v_and_b32_e32 v47, 0xffff0000, v109
	v_pk_add_f32 v[112:113], v[40:41], v[46:47]
	v_mov_b32_e32 v46, v117
	v_mov_b32_e32 v47, v113
	v_mov_b32_e32 v40, v116
	v_mov_b32_e32 v41, v112
	v_pk_mul_f32 v[46:47], v[46:47], v[46:47]
	s_nop 0
	v_pk_fma_f32 v[40:41], v[40:41], v[40:41], v[46:47]
	v_lshlrev_b32_e32 v46, 16, v100
	v_add_f32_e32 v162, v40, v41
	v_lshlrev_b32_e32 v40, 16, v104
	v_and_b32_e32 v41, 0xffff0000, v104
	v_and_b32_e32 v47, 0xffff0000, v100
	v_pk_add_f32 v[108:109], v[40:41], v[46:47]
	v_lshlrev_b32_e32 v40, 16, v105
	v_and_b32_e32 v41, 0xffff0000, v105
	v_lshlrev_b32_e32 v46, 16, v101
	v_and_b32_e32 v47, 0xffff0000, v101
	v_pk_add_f32 v[100:101], v[40:41], v[46:47]
	v_mov_b32_e32 v46, v109
	v_mov_b32_e32 v47, v101
	v_mov_b32_e32 v40, v108
	v_mov_b32_e32 v41, v100
	v_pk_mul_f32 v[46:47], v[46:47], v[46:47]
	s_nop 0
	v_pk_fma_f32 v[40:41], v[40:41], v[40:41], v[46:47]
	v_lshlrev_b32_e32 v46, 16, v96
	v_add_f32_e32 v104, v40, v41
	v_lshlrev_b32_e32 v40, 16, v92
	v_and_b32_e32 v41, 0xffff0000, v92
	v_and_b32_e32 v47, 0xffff0000, v96
	v_pk_add_f32 v[40:41], v[40:41], v[46:47]
	v_lshlrev_b32_e32 v46, 16, v93
	v_and_b32_e32 v47, 0xffff0000, v93
	v_pk_add_f32 v[46:47], v[46:47], v[52:53]
	v_mov_b32_e32 v92, v41
	v_mov_b32_e32 v93, v47
	v_mov_b32_e32 v52, v40
	v_mov_b32_e32 v53, v46
	v_pk_mul_f32 v[92:93], v[92:93], v[92:93]
	s_nop 0
	v_pk_fma_f32 v[52:53], v[52:53], v[52:53], v[92:93]
	v_add_f32_dpp v93, v164, v164 quad_perm:[1,0,3,2] row_mask:0xf bank_mask:0xf bound_ctrl:1
	v_add_f32_e32 v92, v52, v53
	v_lshl_add_u64 v[52:53], v[2:3], 0, s[16:17]
	v_add_f32_dpp v93, v93, v93 quad_perm:[2,3,0,1] row_mask:0xf bank_mask:0xf bound_ctrl:1
	v_lshl_add_u64 v[52:53], v[52:53], 0, v[0:1]
	s_nop 0
	v_add_f32_dpp v93, v93, v93 row_half_mirror row_mask:0xf bank_mask:0xf bound_ctrl:1
	s_nop 1
	v_add_f32_dpp v93, v93, v93 row_mirror row_mask:0xf bank_mask:0xf bound_ctrl:1
; template <int CTRL> __device__ __forceinline__ float dpp_mov(float v) { return __builtin_bit_cast(float, __builtin_amdgcn_update_dpp(0, __builtin_bit_cast(int, v), CTRL, 0xF, 0xF, true)); }
; __device__ __forceinline__ float wave_sum(float v) {
;     v += dpp_mov<0xB1>(v);
;     v += dpp_mov<0x4E>(v);
;     v += dpp_mov<0x141>(v);
;     v += dpp_mov<0x140>(v);
;     const int iv = __builtin_bit_cast(int, v);
;     const float a = __builtin_bit_cast(float, __builtin_amdgcn_readlane(iv, 0)), b = __builtin_bit_cast(float, __builtin_amdgcn_readlane(iv, 16));
;     const float c = __builtin_bit_cast(float, __builtin_amdgcn_readlane(iv, 32)), d = __builtin_bit_cast(float, __builtin_amdgcn_readlane(iv, 48));
;     return (a + b) + (c + d);
; }
	s_nop 0
	v_readlane_b32 s9, v93, 16
	v_readlane_b32 s10, v93, 48
	v_readlane_b32 s6, v93, 0
	v_readlane_b32 s7, v93, 32
	v_mov_b32_e32 v96, s9
	v_mov_b32_e32 v97, s10
	v_pk_add_f32 v[96:97], s[6:7], v[96:97]
	s_nop 0
	v_add_f32_e32 v93, v96, v97
	v_fmamk_f32 v93, v93, 0x3b800000, v252
	v_cmp_gt_f32_e32 vcc, s55, v93
	v_mul_f32_e32 v96, 0x4f800000, v93
	s_nop 0
	v_cndmask_b32_e32 v93, v93, v96, vcc
	v_sqrt_f32_e32 v96, v93
	s_nop 0
	v_add_u32_e32 v97, -1, v96
	v_fma_f32 v105, -v97, v96, v93
	v_cmp_ge_f32_e64 s[6:7], 0, v105
	v_add_u32_e32 v105, 1, v96
	s_nop 0
	v_cndmask_b32_e64 v97, v96, v97, s[6:7]
	v_fma_f32 v96, -v105, v96, v93
	v_cmp_lt_f32_e64 s[6:7], 0, v96
	s_nop 1
	v_cndmask_b32_e64 v96, v97, v105, s[6:7]
	v_mul_f32_e32 v97, 0x37800000, v96
	v_cndmask_b32_e32 v96, v96, v97, vcc
	v_cmp_class_f32_e32 vcc, v93, v253
	s_nop 1
	v_cndmask_b32_e32 v93, v96, v93, vcc
	v_div_scale_f32 v96, s[6:7], v93, v93, 1.0
	v_rcp_f32_e32 v97, v96
	s_nop 0
	v_fma_f32 v105, -v96, v97, 1.0
	v_fmac_f32_e32 v97, v105, v97
	v_div_scale_f32 v105, vcc, 1.0, v93, 1.0
	v_mul_f32_e32 v164, v105, v97
	v_fma_f32 v165, -v96, v164, v105
	v_fmac_f32_e32 v164, v165, v97
	v_fma_f32 v96, -v96, v164, v105
	v_div_fmas_f32 v96, v96, v97, v164
	v_div_fixup_f32 v96, v96, v93, 1.0
	v_lshlrev_b32_e32 v164, 16, v66
	v_and_b32_e32 v165, 0xffff0000, v66
	v_lshlrev_b32_e32 v66, 16, v67
	v_and_b32_e32 v67, 0xffff0000, v67
	v_pk_mul_f32 v[160:161], v[160:161], v[96:97] op_sel_hi:[1,0]
	v_pk_mul_f32 v[96:97], v[156:157], v[96:97] op_sel_hi:[1,0]
	s_nop 0
	v_pk_mul_f32 v[66:67], v[96:97], v[66:67]
	v_pk_mul_f32 v[96:97], v[160:161], v[164:165]
	s_waitcnt vmcnt(33)
	v_lshlrev_b32_e32 v160, 16, v70
	v_cvt_pk_bf16_f32 v96, v96, v97
	v_cvt_pk_bf16_f32 v97, v66, v67
	v_add_f32_dpp v66, v166, v166 quad_perm:[1,0,3,2] row_mask:0xf bank_mask:0xf bound_ctrl:1
	global_store_dwordx2 v[52:53], v[96:97], off nt
	v_and_b32_e32 v161, 0xffff0000, v70
	v_add_f32_dpp v66, v66, v66 quad_perm:[2,3,0,1] row_mask:0xf bank_mask:0xf bound_ctrl:1
	v_lshlrev_b32_e32 v70, 16, v71
	v_and_b32_e32 v71, 0xffff0000, v71
	v_add_f32_dpp v66, v66, v66 row_half_mirror row_mask:0xf bank_mask:0xf bound_ctrl:1
	s_nop 1
	v_add_f32_dpp v66, v66, v66 row_mirror row_mask:0xf bank_mask:0xf bound_ctrl:1
	s_nop 0
	v_readlane_b32 s9, v66, 16
	v_readlane_b32 s10, v66, 48
	v_readlane_b32 s6, v66, 0
	v_readlane_b32 s7, v66, 32
	v_mov_b32_e32 v66, s9
	v_mov_b32_e32 v67, s10
	v_pk_add_f32 v[66:67], s[6:7], v[66:67]
	s_nop 0
	v_add_f32_e32 v66, v66, v67
	v_fmamk_f32 v66, v66, 0x3b800000, v252
	v_cmp_gt_f32_e32 vcc, s55, v66
	v_mul_f32_e32 v67, 0x4f800000, v66
	s_nop 0
	v_cndmask_b32_e32 v66, v66, v67, vcc
	v_sqrt_f32_e32 v67, v66
	s_nop 0
	v_add_u32_e32 v93, -1, v67
	v_fma_f32 v96, -v93, v67, v66
	v_cmp_ge_f32_e64 s[6:7], 0, v96
	v_add_u32_e32 v96, 1, v67
	s_nop 0
	v_cndmask_b32_e64 v93, v67, v93, s[6:7]
	v_fma_f32 v67, -v96, v67, v66
	v_cmp_lt_f32_e64 s[6:7], 0, v67
	s_nop 1
	v_cndmask_b32_e64 v67, v93, v96, s[6:7]
	v_mul_f32_e32 v93, 0x37800000, v67
	v_cndmask_b32_e32 v67, v67, v93, vcc
	v_cmp_class_f32_e32 vcc, v66, v253
	s_nop 1
	v_cndmask_b32_e32 v66, v67, v66, vcc
	v_div_scale_f32 v67, s[6:7], v66, v66, 1.0
	v_rcp_f32_e32 v93, v67
	s_nop 0
	v_fma_f32 v96, -v67, v93, 1.0
	v_fmac_f32_e32 v93, v96, v93
	v_div_scale_f32 v96, vcc, 1.0, v66, 1.0
	v_mul_f32_e32 v97, v96, v93
	v_fma_f32 v105, -v67, v97, v96
	v_fmac_f32_e32 v97, v105, v93
	v_fma_f32 v67, -v67, v97, v96
	v_div_fmas_f32 v67, v67, v93, v97
	v_div_fixup_f32 v66, v67, v66, 1.0
	v_lshlrev_b32_e32 v96, 16, v60
	v_and_b32_e32 v97, 0xffff0000, v60
	v_lshlrev_b32_e32 v60, 16, v61
	v_and_b32_e32 v61, 0xffff0000, v61
	v_pk_mul_f32 v[154:155], v[154:155], v[66:67] op_sel_hi:[1,0]
	v_pk_mul_f32 v[66:67], v[150:151], v[66:67] op_sel_hi:[1,0]
	s_nop 0
	v_pk_mul_f32 v[60:61], v[66:67], v[60:61]
	v_pk_mul_f32 v[66:67], v[154:155], v[96:97]
	v_lshlrev_b32_e32 v154, 16, v152
	v_cvt_pk_bf16_f32 v66, v66, v67
	v_cvt_pk_bf16_f32 v67, v60, v61
	v_add_f32_dpp v60, v167, v167 quad_perm:[1,0,3,2] row_mask:0xf bank_mask:0xf bound_ctrl:1
	global_store_dwordx2 v[52:53], v[66:67], off offset:512 nt
	v_and_b32_e32 v155, 0xffff0000, v152
	v_add_f32_dpp v60, v60, v60 quad_perm:[2,3,0,1] row_mask:0xf bank_mask:0xf bound_ctrl:1
	v_lshlrev_b32_e32 v152, 16, v153
	v_and_b32_e32 v153, 0xffff0000, v153
	v_add_f32_dpp v60, v60, v60 row_half_mirror row_mask:0xf bank_mask:0xf bound_ctrl:1
	s_nop 1
	v_add_f32_dpp v60, v60, v60 row_mirror row_mask:0xf bank_mask:0xf bound_ctrl:1
	s_nop 0
	v_readlane_b32 s9, v60, 16
	v_readlane_b32 s10, v60, 48
	v_readlane_b32 s6, v60, 0
	v_readlane_b32 s7, v60, 32
	v_mov_b32_e32 v60, s9
	v_mov_b32_e32 v61, s10
	v_pk_add_f32 v[60:61], s[6:7], v[60:61]
	s_nop 0
	v_add_f32_e32 v60, v60, v61
	v_fmamk_f32 v60, v60, 0x3b800000, v252
	v_cmp_gt_f32_e32 vcc, s55, v60
	v_mul_f32_e32 v61, 0x4f800000, v60
	s_nop 0
	v_cndmask_b32_e32 v60, v60, v61, vcc
	v_sqrt_f32_e32 v61, v60
	s_nop 0
	v_add_u32_e32 v66, -1, v61
	v_fma_f32 v67, -v66, v61, v60
	v_cmp_ge_f32_e64 s[6:7], 0, v67
	v_add_u32_e32 v67, 1, v61
	s_nop 0
	v_cndmask_b32_e64 v66, v61, v66, s[6:7]
	v_fma_f32 v61, -v67, v61, v60
	v_cmp_lt_f32_e64 s[6:7], 0, v61
	s_nop 1
	v_cndmask_b32_e64 v61, v66, v67, s[6:7]
	v_mul_f32_e32 v66, 0x37800000, v61
	v_cndmask_b32_e32 v61, v61, v66, vcc
	v_cmp_class_f32_e32 vcc, v60, v253
	s_nop 1
	v_cndmask_b32_e32 v60, v61, v60, vcc
	v_div_scale_f32 v61, s[6:7], v60, v60, 1.0
	v_rcp_f32_e32 v66, v61
	s_nop 0
	v_fma_f32 v67, -v61, v66, 1.0
	v_fmac_f32_e32 v66, v67, v66
	v_div_scale_f32 v67, vcc, 1.0, v60, 1.0
	v_mul_f32_e32 v93, v67, v66
	v_fma_f32 v96, -v61, v93, v67
	v_fmac_f32_e32 v93, v96, v66
	v_fma_f32 v61, -v61, v93, v67
	v_div_fmas_f32 v61, v61, v66, v93
	v_div_fixup_f32 v60, v61, v60, 1.0
	v_lshlrev_b32_e32 v66, 16, v54
	v_and_b32_e32 v67, 0xffff0000, v54
	v_lshlrev_b32_e32 v54, 16, v55
	v_and_b32_e32 v55, 0xffff0000, v55
	v_pk_mul_f32 v[96:97], v[144:145], v[60:61] op_sel_hi:[1,0]
	v_pk_mul_f32 v[60:61], v[138:139], v[60:61] op_sel_hi:[1,0]
	s_nop 0
	v_pk_mul_f32 v[54:55], v[60:61], v[54:55]
	v_pk_mul_f32 v[60:61], v[96:97], v[66:67]
	s_nop 0
	v_cvt_pk_bf16_f32 v60, v60, v61
	v_cvt_pk_bf16_f32 v61, v54, v55
	v_add_f32_dpp v54, v168, v168 quad_perm:[1,0,3,2] row_mask:0xf bank_mask:0xf bound_ctrl:1
	global_store_dwordx2 v[52:53], v[60:61], off offset:1024 nt
	s_nop 0
	v_add_f32_dpp v54, v54, v54 quad_perm:[2,3,0,1] row_mask:0xf bank_mask:0xf bound_ctrl:1
	s_nop 1
	v_add_f32_dpp v54, v54, v54 row_half_mirror row_mask:0xf bank_mask:0xf bound_ctrl:1
	s_nop 1
	v_add_f32_dpp v54, v54, v54 row_mirror row_mask:0xf bank_mask:0xf bound_ctrl:1
	s_nop 0
	v_readlane_b32 s9, v54, 16
	v_readlane_b32 s10, v54, 48
	v_readlane_b32 s6, v54, 0
	v_readlane_b32 s7, v54, 32
	v_mov_b32_e32 v54, s9
	v_mov_b32_e32 v55, s10
	v_pk_add_f32 v[54:55], s[6:7], v[54:55]
	s_nop 0
	v_add_f32_e32 v54, v54, v55
	v_fmamk_f32 v54, v54, 0x3b800000, v252
	v_cmp_gt_f32_e32 vcc, s55, v54
	v_mul_f32_e32 v55, 0x4f800000, v54
	s_nop 0
	v_cndmask_b32_e32 v54, v54, v55, vcc
	v_sqrt_f32_e32 v55, v54
	s_nop 0
	v_add_u32_e32 v60, -1, v55
	v_fma_f32 v61, -v60, v55, v54
	v_cmp_ge_f32_e64 s[6:7], 0, v61
	v_add_u32_e32 v61, 1, v55
	s_nop 0
	v_cndmask_b32_e64 v60, v55, v60, s[6:7]
	v_fma_f32 v55, -v61, v55, v54
	v_cmp_lt_f32_e64 s[6:7], 0, v55
	s_nop 1
	v_cndmask_b32_e64 v55, v60, v61, s[6:7]
	v_mul_f32_e32 v60, 0x37800000, v55
	v_cndmask_b32_e32 v55, v55, v60, vcc
	v_cmp_class_f32_e32 vcc, v54, v253
	s_nop 1
	v_cndmask_b32_e32 v54, v55, v54, vcc
	v_div_scale_f32 v55, s[6:7], v54, v54, 1.0
	v_rcp_f32_e32 v60, v55
	s_nop 0
	v_fma_f32 v61, -v55, v60, 1.0
	v_fmac_f32_e32 v60, v61, v60
	v_div_scale_f32 v61, vcc, 1.0, v54, 1.0
	v_mul_f32_e32 v66, v61, v60
	v_fma_f32 v67, -v55, v66, v61
	v_fmac_f32_e32 v66, v67, v60
	v_fma_f32 v55, -v55, v66, v61
	v_div_fmas_f32 v55, v55, v60, v66
	v_div_fixup_f32 v54, v55, v54, 1.0
	v_lshlrev_b32_e32 v60, 16, v48
	v_and_b32_e32 v61, 0xffff0000, v48
	v_lshlrev_b32_e32 v48, 16, v49
	v_and_b32_e32 v49, 0xffff0000, v49
	v_pk_mul_f32 v[66:67], v[132:133], v[54:55] op_sel_hi:[1,0]
	v_pk_mul_f32 v[54:55], v[128:129], v[54:55] op_sel_hi:[1,0]
	s_nop 0
	v_pk_mul_f32 v[48:49], v[54:55], v[48:49]
	v_pk_mul_f32 v[54:55], v[66:67], v[60:61]
	s_nop 0
	v_cvt_pk_bf16_f32 v54, v54, v55
	v_cvt_pk_bf16_f32 v55, v48, v49
	v_add_f32_dpp v48, v163, v163 quad_perm:[1,0,3,2] row_mask:0xf bank_mask:0xf bound_ctrl:1
	global_store_dwordx2 v[52:53], v[54:55], off offset:1536 nt
	s_nop 0
	v_add_f32_dpp v48, v48, v48 quad_perm:[2,3,0,1] row_mask:0xf bank_mask:0xf bound_ctrl:1
	s_nop 1
	v_add_f32_dpp v48, v48, v48 row_half_mirror row_mask:0xf bank_mask:0xf bound_ctrl:1
	s_nop 1
	v_add_f32_dpp v48, v48, v48 row_mirror row_mask:0xf bank_mask:0xf bound_ctrl:1
	s_nop 0
	v_readlane_b32 s9, v48, 16
	v_readlane_b32 s10, v48, 48
	v_readlane_b32 s6, v48, 0
	v_readlane_b32 s7, v48, 32
	v_mov_b32_e32 v48, s9
	v_mov_b32_e32 v49, s10
	v_pk_add_f32 v[48:49], s[6:7], v[48:49]
	s_nop 0
	v_add_f32_e32 v48, v48, v49
	v_fmamk_f32 v48, v48, 0x3b800000, v252
	v_cmp_gt_f32_e32 vcc, s55, v48
	v_mul_f32_e32 v49, 0x4f800000, v48
	s_nop 0
	v_cndmask_b32_e32 v48, v48, v49, vcc
	v_sqrt_f32_e32 v49, v48
	s_nop 0
	v_add_u32_e32 v54, -1, v49
	v_fma_f32 v55, -v54, v49, v48
	v_cmp_ge_f32_e64 s[6:7], 0, v55
	v_add_u32_e32 v55, 1, v49
	s_nop 0
	v_cndmask_b32_e64 v54, v49, v54, s[6:7]
	v_fma_f32 v49, -v55, v49, v48
	v_cmp_lt_f32_e64 s[6:7], 0, v49
	s_nop 1
	v_cndmask_b32_e64 v49, v54, v55, s[6:7]
	v_mul_f32_e32 v54, 0x37800000, v49
	v_cndmask_b32_e32 v49, v49, v54, vcc
	v_cmp_class_f32_e32 vcc, v48, v253
	s_nop 1
	v_cndmask_b32_e32 v48, v49, v48, vcc
	v_div_scale_f32 v49, s[6:7], v48, v48, 1.0
	v_rcp_f32_e32 v54, v49
	s_nop 0
	v_fma_f32 v55, -v49, v54, 1.0
	v_fmac_f32_e32 v54, v55, v54
	v_div_scale_f32 v55, vcc, 1.0, v48, 1.0
	v_mul_f32_e32 v60, v55, v54
	v_fma_f32 v61, -v49, v60, v55
	v_fmac_f32_e32 v60, v61, v54
	v_fma_f32 v49, -v49, v60, v55
	v_div_fmas_f32 v49, v49, v54, v60
	v_div_fixup_f32 v48, v49, v48, 1.0
	v_lshlrev_b32_e32 v54, 16, v42
	v_and_b32_e32 v55, 0xffff0000, v42
	v_lshlrev_b32_e32 v42, 16, v43
	v_and_b32_e32 v43, 0xffff0000, v43
	v_pk_mul_f32 v[60:61], v[124:125], v[48:49] op_sel_hi:[1,0]
	v_pk_mul_f32 v[48:49], v[120:121], v[48:49] op_sel_hi:[1,0]
	s_nop 0
	v_pk_mul_f32 v[42:43], v[48:49], v[42:43]
	v_pk_mul_f32 v[48:49], v[60:61], v[54:55]
	s_nop 0
	v_cvt_pk_bf16_f32 v48, v48, v49
	v_cvt_pk_bf16_f32 v49, v42, v43
	v_add_f32_dpp v42, v162, v162 quad_perm:[1,0,3,2] row_mask:0xf bank_mask:0xf bound_ctrl:1
	global_store_dwordx2 v[52:53], v[48:49], off offset:2048 nt
	s_nop 0
	v_add_f32_dpp v42, v42, v42 quad_perm:[2,3,0,1] row_mask:0xf bank_mask:0xf bound_ctrl:1
	s_nop 1
	v_add_f32_dpp v42, v42, v42 row_half_mirror row_mask:0xf bank_mask:0xf bound_ctrl:1
	s_nop 1
	v_add_f32_dpp v42, v42, v42 row_mirror row_mask:0xf bank_mask:0xf bound_ctrl:1
	s_nop 0
	v_readlane_b32 s9, v42, 16
	v_readlane_b32 s10, v42, 48
	v_readlane_b32 s6, v42, 0
	v_readlane_b32 s7, v42, 32
	v_mov_b32_e32 v42, s9
	v_mov_b32_e32 v43, s10
	v_pk_add_f32 v[42:43], s[6:7], v[42:43]
	s_nop 0
	v_add_f32_e32 v42, v42, v43
	v_fmamk_f32 v42, v42, 0x3b800000, v252
	v_cmp_gt_f32_e32 vcc, s55, v42
	v_mul_f32_e32 v43, 0x4f800000, v42
	s_nop 0
	v_cndmask_b32_e32 v42, v42, v43, vcc
	v_sqrt_f32_e32 v43, v42
	s_nop 0
	v_add_u32_e32 v48, -1, v43
; template <bool HG>
; __device__ __forceinline__ void readout_phase2(const Args& a, Frame& F, const float* gain, int nrows) {
;     ...
;     RO_FINISH(f1, b1, g1, nw + 4 * 2048); RO_LOAD(f1, b1, g1, nw + 7 * 2048);
	v_fma_f32 v49, -v48, v43, v42
	v_cmp_ge_f32_e64 s[6:7], 0, v49
	v_add_u32_e32 v49, 1, v43
	s_nop 0
	v_cndmask_b32_e64 v48, v43, v48, s[6:7]
	v_fma_f32 v43, -v49, v43, v42
	v_cmp_lt_f32_e64 s[6:7], 0, v43
	s_nop 1
	v_cndmask_b32_e64 v43, v48, v49, s[6:7]
	v_mul_f32_e32 v48, 0x37800000, v43
	v_cndmask_b32_e32 v43, v43, v48, vcc
	v_cmp_class_f32_e32 vcc, v42, v253
	s_nop 1
	v_cndmask_b32_e32 v42, v43, v42, vcc
	v_div_scale_f32 v43, s[6:7], v42, v42, 1.0
	v_rcp_f32_e32 v48, v43
	s_nop 0
	v_fma_f32 v49, -v43, v48, 1.0
	v_fmac_f32_e32 v48, v49, v48
	v_div_scale_f32 v49, vcc, 1.0, v42, 1.0
	v_mul_f32_e32 v54, v49, v48
	v_fma_f32 v55, -v43, v54, v49
	v_fmac_f32_e32 v54, v55, v48
	v_fma_f32 v43, -v43, v54, v49
	v_div_fmas_f32 v43, v43, v48, v54
	v_div_fixup_f32 v42, v43, v42, 1.0
	v_lshlrev_b32_e32 v48, 16, v36
	v_and_b32_e32 v49, 0xffff0000, v36
	v_lshlrev_b32_e32 v36, 16, v37
	v_and_b32_e32 v37, 0xffff0000, v37
	v_pk_mul_f32 v[54:55], v[116:117], v[42:43] op_sel_hi:[1,0]
	v_pk_mul_f32 v[42:43], v[112:113], v[42:43] op_sel_hi:[1,0]
	s_nop 0
	v_pk_mul_f32 v[36:37], v[42:43], v[36:37]
	v_pk_mul_f32 v[42:43], v[54:55], v[48:49]
	s_nop 0
	v_cvt_pk_bf16_f32 v42, v42, v43
	v_cvt_pk_bf16_f32 v43, v36, v37
	v_add_f32_dpp v36, v104, v104 quad_perm:[1,0,3,2] row_mask:0xf bank_mask:0xf bound_ctrl:1
	global_store_dwordx2 v[52:53], v[42:43], off offset:2560 nt
	s_nop 0
	v_add_f32_dpp v36, v36, v36 quad_perm:[2,3,0,1] row_mask:0xf bank_mask:0xf bound_ctrl:1
	s_nop 1
	v_add_f32_dpp v36, v36, v36 row_half_mirror row_mask:0xf bank_mask:0xf bound_ctrl:1
	s_nop 1
	v_add_f32_dpp v36, v36, v36 row_mirror row_mask:0xf bank_mask:0xf bound_ctrl:1
	s_nop 0
	v_readlane_b32 s9, v36, 16
	v_readlane_b32 s10, v36, 48
	v_readlane_b32 s6, v36, 0
	v_readlane_b32 s7, v36, 32
	v_mov_b32_e32 v36, s9
	v_mov_b32_e32 v37, s10
	v_pk_add_f32 v[36:37], s[6:7], v[36:37]
	s_nop 0
	v_add_f32_e32 v36, v36, v37
	v_fmamk_f32 v36, v36, 0x3b800000, v252
	v_cmp_gt_f32_e32 vcc, s55, v36
	v_mul_f32_e32 v37, 0x4f800000, v36
	s_nop 0
	v_cndmask_b32_e32 v36, v36, v37, vcc
	v_sqrt_f32_e32 v37, v36
	s_nop 0
	v_add_u32_e32 v42, -1, v37
	v_fma_f32 v43, -v42, v37, v36
	v_cmp_ge_f32_e64 s[6:7], 0, v43
	v_add_u32_e32 v43, 1, v37
	s_nop 0
	v_cndmask_b32_e64 v42, v37, v42, s[6:7]
	v_fma_f32 v37, -v43, v37, v36
	v_cmp_lt_f32_e64 s[6:7], 0, v37
	s_nop 1
	v_cndmask_b32_e64 v37, v42, v43, s[6:7]
	v_mul_f32_e32 v42, 0x37800000, v37
	v_cndmask_b32_e32 v37, v37, v42, vcc
	v_cmp_class_f32_e32 vcc, v36, v253
	s_nop 1
	v_cndmask_b32_e32 v36, v37, v36, vcc
	v_div_scale_f32 v37, s[6:7], v36, v36, 1.0
	v_rcp_f32_e32 v42, v37
	s_nop 0
	v_fma_f32 v43, -v37, v42, 1.0
	v_fmac_f32_e32 v42, v43, v42
	v_div_scale_f32 v43, vcc, 1.0, v36, 1.0
	v_mul_f32_e32 v48, v43, v42
	v_fma_f32 v49, -v37, v48, v43
	v_fmac_f32_e32 v48, v49, v42
	v_fma_f32 v37, -v37, v48, v43
	v_div_fmas_f32 v37, v37, v42, v48
	v_div_fixup_f32 v36, v37, v36, 1.0
	v_lshlrev_b32_e32 v42, 16, v32
	v_and_b32_e32 v43, 0xffff0000, v32
	v_lshlrev_b32_e32 v32, 16, v33
	v_and_b32_e32 v33, 0xffff0000, v33
	v_pk_mul_f32 v[48:49], v[108:109], v[36:37] op_sel_hi:[1,0]
	v_pk_mul_f32 v[36:37], v[100:101], v[36:37] op_sel_hi:[1,0]
	s_nop 0
	v_pk_mul_f32 v[32:33], v[36:37], v[32:33]
	v_pk_mul_f32 v[36:37], v[48:49], v[42:43]
	s_nop 0
	v_cvt_pk_bf16_f32 v36, v36, v37
	v_cvt_pk_bf16_f32 v37, v32, v33
	v_add_f32_dpp v32, v92, v92 quad_perm:[1,0,3,2] row_mask:0xf bank_mask:0xf bound_ctrl:1
	global_store_dwordx2 v[52:53], v[36:37], off offset:3072 nt
	s_nop 0
	v_add_f32_dpp v32, v32, v32 quad_perm:[2,3,0,1] row_mask:0xf bank_mask:0xf bound_ctrl:1
	s_nop 1
	v_add_f32_dpp v32, v32, v32 row_half_mirror row_mask:0xf bank_mask:0xf bound_ctrl:1
	s_nop 1
	v_add_f32_dpp v32, v32, v32 row_mirror row_mask:0xf bank_mask:0xf bound_ctrl:1
	s_nop 0
	v_readlane_b32 s9, v32, 16
	v_readlane_b32 s10, v32, 48
	v_readlane_b32 s6, v32, 0
	v_readlane_b32 s7, v32, 32
	v_mov_b32_e32 v32, s9
	v_mov_b32_e32 v33, s10
	v_pk_add_f32 v[32:33], s[6:7], v[32:33]
	s_add_i32 s10, s8, 0x3800
	v_add_f32_e32 v32, v32, v33
	v_fmamk_f32 v32, v32, 0x3b800000, v252
	v_cmp_gt_f32_e32 vcc, s55, v32
	v_mul_f32_e32 v33, 0x4f800000, v32
	s_ashr_i32 s11, s10, 31
	v_cndmask_b32_e32 v32, v32, v33, vcc
	v_sqrt_f32_e32 v33, v32
	s_lshl_b64 s[78:79], s[10:11], 12
	s_cmp_lt_i32 s82, s47
	v_add_u32_e32 v36, -1, v33
	v_fma_f32 v37, -v36, v33, v32
	v_cmp_ge_f32_e64 s[6:7], 0, v37
	v_add_u32_e32 v37, 1, v33
	s_nop 0
	v_cndmask_b32_e64 v36, v33, v36, s[6:7]
	v_fma_f32 v33, -v37, v33, v32
	v_cmp_lt_f32_e64 s[6:7], 0, v33
	s_nop 1
	v_cndmask_b32_e64 v33, v36, v37, s[6:7]
	v_mul_f32_e32 v36, 0x37800000, v33
	v_cndmask_b32_e32 v33, v33, v36, vcc
	v_cmp_class_f32_e32 vcc, v32, v253
	s_nop 1
	v_cndmask_b32_e32 v32, v33, v32, vcc
	v_div_scale_f32 v33, s[6:7], v32, v32, 1.0
	v_rcp_f32_e32 v36, v33
	s_nop 0
	v_fma_f32 v37, -v33, v36, 1.0
	v_fmac_f32_e32 v36, v37, v36
	v_div_scale_f32 v37, vcc, 1.0, v32, 1.0
	v_mul_f32_e32 v42, v37, v36
	v_fma_f32 v43, -v33, v42, v37
	v_fmac_f32_e32 v42, v43, v36
	v_fma_f32 v33, -v33, v42, v37
	v_div_fmas_f32 v33, v33, v36, v42
	v_div_fixup_f32 v32, v33, v32, 1.0
	v_lshlrev_b32_e32 v36, 16, v28
	v_and_b32_e32 v37, 0xffff0000, v28
	v_lshlrev_b32_e32 v28, 16, v29
	v_and_b32_e32 v29, 0xffff0000, v29
	v_pk_mul_f32 v[40:41], v[40:41], v[32:33] op_sel_hi:[1,0]
	v_pk_mul_f32 v[32:33], v[46:47], v[32:33] op_sel_hi:[1,0]
	s_nop 0
	v_pk_mul_f32 v[28:29], v[32:33], v[28:29]
	v_pk_mul_f32 v[32:33], v[40:41], v[36:37]
	s_nop 0
	v_cvt_pk_bf16_f32 v32, v32, v33
	v_cvt_pk_bf16_f32 v33, v28, v29
	global_store_dwordx2 v[52:53], v[32:33], off offset:3584 nt
	v_lshl_add_u64 v[32:33], v[6:7], 0, s[78:79]
	v_lshl_add_u64 v[28:29], v[4:5], 0, s[78:79]
	v_lshl_add_u64 v[60:61], v[32:33], 0, v[0:1]
	v_lshl_add_u64 v[32:33], v[8:9], 0, s[78:79]
	v_lshl_add_u64 v[28:29], v[28:29], 0, v[0:1]
	v_lshl_add_u64 v[150:151], v[32:33], 0, v[0:1]
	global_load_dwordx2 v[144:145], v[28:29], off nt
	global_load_dwordx2 v[138:139], v[60:61], off nt
	global_load_dwordx2 v[52:53], v[150:151], off nt
	global_load_dwordx2 v[132:133], v[28:29], off offset:512 nt
	global_load_dwordx2 v[128:129], v[60:61], off offset:512 nt
	global_load_dwordx2 v[48:49], v[150:151], off offset:512 nt
	global_load_dwordx2 v[124:125], v[28:29], off offset:1024 nt
	global_load_dwordx2 v[120:121], v[60:61], off offset:1024 nt
	global_load_dwordx2 v[46:47], v[150:151], off offset:1024 nt
	global_load_dwordx2 v[112:113], v[28:29], off offset:1536 nt
	global_load_dwordx2 v[116:117], v[60:61], off offset:1536 nt
	global_load_dwordx2 v[42:43], v[150:151], off offset:1536 nt
	global_load_dwordx2 v[108:109], v[28:29], off offset:2048 nt
	global_load_dwordx2 v[104:105], v[60:61], off offset:2048 nt
	global_load_dwordx2 v[40:41], v[150:151], off offset:2048 nt
	global_load_dwordx2 v[100:101], v[28:29], off offset:2560 nt
	global_load_dwordx2 v[96:97], v[60:61], off offset:2560 nt
	global_load_dwordx2 v[36:37], v[150:151], off offset:2560 nt
	global_load_dwordx2 v[92:93], v[28:29], off offset:3072 nt
	global_load_dwordx2 v[66:67], v[60:61], off offset:3072 nt
	global_load_dwordx2 v[32:33], v[150:151], off offset:3072 nt
	global_load_dwordx2 v[54:55], v[28:29], off offset:3584 nt
	s_nop 0
	global_load_dwordx2 v[60:61], v[60:61], off offset:3584 nt
	s_nop 0
	global_load_dwordx2 v[28:29], v[150:151], off offset:3584 nt
	v_lshlrev_b32_e32 v150, 16, v158
	v_and_b32_e32 v151, 0xffff0000, v158
	v_pk_add_f32 v[154:155], v[150:151], v[154:155]
	v_lshlrev_b32_e32 v150, 16, v159
	v_and_b32_e32 v151, 0xffff0000, v159
	v_pk_add_f32 v[152:153], v[150:151], v[152:153]
	v_mov_b32_e32 v156, v155
	v_mov_b32_e32 v157, v153
	v_mov_b32_e32 v150, v154
	v_mov_b32_e32 v151, v152
	v_pk_mul_f32 v[156:157], v[156:157], v[156:157]
	s_nop 0
	v_pk_fma_f32 v[150:151], v[150:151], v[150:151], v[156:157]
	v_lshlrev_b32_e32 v156, 16, v140
	v_add_f32_e32 v162, v150, v151
	v_lshlrev_b32_e32 v150, 16, v146
	v_and_b32_e32 v151, 0xffff0000, v146
	v_and_b32_e32 v157, 0xffff0000, v140
	v_lshlrev_b32_e32 v146, 16, v147
	v_and_b32_e32 v147, 0xffff0000, v147
	v_lshlrev_b32_e32 v140, 16, v141
	v_and_b32_e32 v141, 0xffff0000, v141
	v_pk_add_f32 v[150:151], v[150:151], v[156:157]
	v_pk_add_f32 v[146:147], v[146:147], v[140:141]
	v_mov_b32_e32 v156, v151
	v_mov_b32_e32 v157, v147
	v_mov_b32_e32 v140, v150
	v_mov_b32_e32 v141, v146
	v_pk_mul_f32 v[156:157], v[156:157], v[156:157]
	s_nop 0
	v_pk_fma_f32 v[140:141], v[140:141], v[140:141], v[156:157]
	v_lshlrev_b32_e32 v156, 16, v88
	v_add_f32_e32 v164, v140, v141
	v_lshlrev_b32_e32 v140, 16, v134
	v_and_b32_e32 v141, 0xffff0000, v134
	v_and_b32_e32 v157, 0xffff0000, v88
	v_lshlrev_b32_e32 v134, 16, v135
	v_and_b32_e32 v135, 0xffff0000, v135
	v_lshlrev_b32_e32 v88, 16, v89
	v_and_b32_e32 v89, 0xffff0000, v89
	v_pk_add_f32 v[140:141], v[140:141], v[156:157]
	v_pk_add_f32 v[134:135], v[134:135], v[88:89]
	v_mov_b32_e32 v156, v141
	v_mov_b32_e32 v157, v135
	v_mov_b32_e32 v88, v140
	v_mov_b32_e32 v89, v134
	v_pk_mul_f32 v[156:157], v[156:157], v[156:157]
	s_nop 0
	v_pk_fma_f32 v[88:89], v[88:89], v[88:89], v[156:157]
	v_lshlrev_b32_e32 v156, 16, v86
	v_add_f32_e32 v165, v88, v89
	v_lshlrev_b32_e32 v88, 16, v84
	v_and_b32_e32 v89, 0xffff0000, v84
	v_and_b32_e32 v157, 0xffff0000, v86
	v_lshlrev_b32_e32 v84, 16, v85
	v_and_b32_e32 v85, 0xffff0000, v85
	v_lshlrev_b32_e32 v86, 16, v87
	v_and_b32_e32 v87, 0xffff0000, v87
	v_pk_add_f32 v[88:89], v[88:89], v[156:157]
	v_pk_add_f32 v[86:87], v[84:85], v[86:87]
	v_mov_b32_e32 v156, v89
	v_mov_b32_e32 v157, v87
	v_mov_b32_e32 v84, v88
	v_mov_b32_e32 v85, v86
	v_pk_mul_f32 v[156:157], v[156:157], v[156:157]
	s_nop 0
	v_pk_fma_f32 v[84:85], v[84:85], v[84:85], v[156:157]
	v_lshlrev_b32_e32 v156, 16, v80
	v_add_f32_e32 v166, v84, v85
	v_lshlrev_b32_e32 v84, 16, v82
	v_and_b32_e32 v85, 0xffff0000, v82
	v_and_b32_e32 v157, 0xffff0000, v80
	v_lshlrev_b32_e32 v82, 16, v83
	v_and_b32_e32 v83, 0xffff0000, v83
	v_lshlrev_b32_e32 v80, 16, v81
	v_and_b32_e32 v81, 0xffff0000, v81
	v_pk_add_f32 v[84:85], v[84:85], v[156:157]
	v_pk_add_f32 v[82:83], v[82:83], v[80:81]
	v_mov_b32_e32 v156, v85
	v_mov_b32_e32 v157, v83
	v_mov_b32_e32 v80, v84
	v_mov_b32_e32 v81, v82
	v_pk_mul_f32 v[156:157], v[156:157], v[156:157]
	s_nop 0
	v_pk_fma_f32 v[80:81], v[80:81], v[80:81], v[156:157]
	v_lshlrev_b32_e32 v156, 16, v76
	v_add_f32_e32 v159, v80, v81
	v_lshlrev_b32_e32 v80, 16, v78
	v_and_b32_e32 v81, 0xffff0000, v78
	v_and_b32_e32 v157, 0xffff0000, v76
	v_lshlrev_b32_e32 v78, 16, v79
	v_and_b32_e32 v79, 0xffff0000, v79
	v_lshlrev_b32_e32 v76, 16, v77
	v_and_b32_e32 v77, 0xffff0000, v77
	v_pk_add_f32 v[80:81], v[80:81], v[156:157]
	v_pk_add_f32 v[78:79], v[78:79], v[76:77]
	v_mov_b32_e32 v156, v81
	v_mov_b32_e32 v157, v79
	v_mov_b32_e32 v76, v80
	v_mov_b32_e32 v77, v78
	v_pk_mul_f32 v[156:157], v[156:157], v[156:157]
	s_nop 0
	v_pk_fma_f32 v[76:77], v[76:77], v[76:77], v[156:157]
	v_lshlrev_b32_e32 v156, 16, v72
	v_add_f32_e32 v158, v76, v77
	v_lshlrev_b32_e32 v76, 16, v74
	v_and_b32_e32 v77, 0xffff0000, v74
	v_and_b32_e32 v157, 0xffff0000, v72
	v_lshlrev_b32_e32 v74, 16, v75
	v_and_b32_e32 v75, 0xffff0000, v75
	v_lshlrev_b32_e32 v72, 16, v73
	v_and_b32_e32 v73, 0xffff0000, v73
	v_pk_add_f32 v[76:77], v[76:77], v[156:157]
	v_pk_add_f32 v[74:75], v[74:75], v[72:73]
	v_mov_b32_e32 v156, v77
	v_mov_b32_e32 v157, v75
	v_mov_b32_e32 v72, v76
	v_mov_b32_e32 v73, v74
	v_pk_mul_f32 v[156:157], v[156:157], v[156:157]
	s_nop 0
	v_pk_fma_f32 v[72:73], v[72:73], v[72:73], v[156:157]
	s_nop 0
	v_add_f32_e32 v157, v72, v73
	v_lshlrev_b32_e32 v72, 16, v68
	v_and_b32_e32 v73, 0xffff0000, v68
	v_lshlrev_b32_e32 v68, 16, v69
	v_and_b32_e32 v69, 0xffff0000, v69
	v_pk_add_f32 v[72:73], v[72:73], v[160:161]
	v_pk_add_f32 v[68:69], v[68:69], v[70:71]
	v_mov_b32_e32 v160, v73
	v_mov_b32_e32 v161, v69
	v_mov_b32_e32 v70, v72
	v_mov_b32_e32 v71, v68
	v_pk_mul_f32 v[160:161], v[160:161], v[160:161]
	s_nop 0
	v_pk_fma_f32 v[70:71], v[70:71], v[70:71], v[160:161]
	v_add_f32_dpp v160, v162, v162 quad_perm:[1,0,3,2] row_mask:0xf bank_mask:0xf bound_ctrl:1
	v_add_f32_e32 v156, v70, v71
	v_lshl_add_u64 v[70:71], v[2:3], 0, s[12:13]
	v_add_f32_dpp v160, v160, v160 quad_perm:[2,3,0,1] row_mask:0xf bank_mask:0xf bound_ctrl:1
	v_lshl_add_u64 v[70:71], v[70:71], 0, v[0:1]
	s_nop 0
	v_add_f32_dpp v160, v160, v160 row_half_mirror row_mask:0xf bank_mask:0xf bound_ctrl:1
	s_nop 1
	v_add_f32_dpp v160, v160, v160 row_mirror row_mask:0xf bank_mask:0xf bound_ctrl:1
	s_nop 0
	v_readlane_b32 s9, v160, 16
	v_readlane_b32 s11, v160, 48
	v_readlane_b32 s6, v160, 0
	v_readlane_b32 s7, v160, 32
	v_mov_b32_e32 v160, s9
	v_mov_b32_e32 v161, s11
	v_pk_add_f32 v[160:161], s[6:7], v[160:161]
	s_nop 0
	v_add_f32_e32 v160, v160, v161
	v_fmamk_f32 v160, v160, 0x3b800000, v252
	v_cmp_gt_f32_e32 vcc, s55, v160
	v_mul_f32_e32 v161, 0x4f800000, v160
	s_nop 0
	v_cndmask_b32_e32 v160, v160, v161, vcc
	v_sqrt_f32_e32 v161, v160
	s_nop 0
	v_add_u32_e32 v162, -1, v161
	v_fma_f32 v163, -v162, v161, v160
	v_cmp_ge_f32_e64 s[6:7], 0, v163
	v_add_u32_e32 v163, 1, v161
	s_nop 0
	v_cndmask_b32_e64 v162, v161, v162, s[6:7]
	v_fma_f32 v161, -v163, v161, v160
	v_cmp_lt_f32_e64 s[6:7], 0, v161
	s_nop 1
	v_cndmask_b32_e64 v161, v162, v163, s[6:7]
	v_mul_f32_e32 v162, 0x37800000, v161
	v_cndmask_b32_e32 v161, v161, v162, vcc
	v_cmp_class_f32_e32 vcc, v160, v253
	s_nop 1
	v_cndmask_b32_e32 v160, v161, v160, vcc
	v_div_scale_f32 v161, s[6:7], v160, v160, 1.0
	v_rcp_f32_e32 v162, v161
	s_nop 0
	v_fma_f32 v163, -v161, v162, 1.0
	v_fmac_f32_e32 v162, v163, v162
	v_div_scale_f32 v163, vcc, 1.0, v160, 1.0
	v_mul_f32_e32 v167, v163, v162
	v_fma_f32 v168, -v161, v167, v163
	v_fmac_f32_e32 v167, v168, v162
	v_fma_f32 v161, -v161, v167, v163
	v_div_fmas_f32 v161, v161, v162, v167
	v_div_fixup_f32 v160, v161, v160, 1.0
	v_lshlrev_b32_e32 v162, 16, v62
	v_and_b32_e32 v163, 0xffff0000, v62
	v_lshlrev_b32_e32 v62, 16, v63
	v_and_b32_e32 v63, 0xffff0000, v63
	v_pk_mul_f32 v[154:155], v[154:155], v[160:161] op_sel_hi:[1,0]
	v_pk_mul_f32 v[152:153], v[152:153], v[160:161] op_sel_hi:[1,0]
	s_nop 0
	v_pk_mul_f32 v[62:63], v[152:153], v[62:63]
	v_pk_mul_f32 v[152:153], v[154:155], v[162:163]
	s_nop 0
	v_cvt_pk_bf16_f32 v152, v152, v153
	v_cvt_pk_bf16_f32 v153, v62, v63
	v_add_f32_dpp v62, v164, v164 quad_perm:[1,0,3,2] row_mask:0xf bank_mask:0xf bound_ctrl:1
	global_store_dwordx2 v[70:71], v[152:153], off nt
	s_nop 0
	v_add_f32_dpp v62, v62, v62 quad_perm:[2,3,0,1] row_mask:0xf bank_mask:0xf bound_ctrl:1
	s_nop 1
	v_add_f32_dpp v62, v62, v62 row_half_mirror row_mask:0xf bank_mask:0xf bound_ctrl:1
	s_nop 1
	v_add_f32_dpp v62, v62, v62 row_mirror row_mask:0xf bank_mask:0xf bound_ctrl:1
	s_nop 0
	v_readlane_b32 s9, v62, 16
	v_readlane_b32 s11, v62, 48
	v_readlane_b32 s6, v62, 0
	v_readlane_b32 s7, v62, 32
	v_mov_b32_e32 v62, s9
	v_mov_b32_e32 v63, s11
	v_pk_add_f32 v[62:63], s[6:7], v[62:63]
	s_nop 0
	v_add_f32_e32 v62, v62, v63
	v_fmamk_f32 v62, v62, 0x3b800000, v252
	v_cmp_gt_f32_e32 vcc, s55, v62
	v_mul_f32_e32 v63, 0x4f800000, v62
	s_nop 0
	v_cndmask_b32_e32 v62, v62, v63, vcc
	v_sqrt_f32_e32 v63, v62
	s_nop 0
	v_add_u32_e32 v152, -1, v63
	v_fma_f32 v153, -v152, v63, v62
	v_cmp_ge_f32_e64 s[6:7], 0, v153
	v_add_u32_e32 v153, 1, v63
	s_nop 0
	v_cndmask_b32_e64 v152, v63, v152, s[6:7]
	v_fma_f32 v63, -v153, v63, v62
	v_cmp_lt_f32_e64 s[6:7], 0, v63
	s_nop 1
	v_cndmask_b32_e64 v63, v152, v153, s[6:7]
	v_mul_f32_e32 v152, 0x37800000, v63
	v_cndmask_b32_e32 v63, v63, v152, vcc
	v_cmp_class_f32_e32 vcc, v62, v253
	s_nop 1
	v_cndmask_b32_e32 v62, v63, v62, vcc
	v_div_scale_f32 v63, s[6:7], v62, v62, 1.0
	v_rcp_f32_e32 v152, v63
	s_nop 0
	v_fma_f32 v153, -v63, v152, 1.0
	v_fmac_f32_e32 v152, v153, v152
	v_div_scale_f32 v153, vcc, 1.0, v62, 1.0
	v_mul_f32_e32 v154, v153, v152
	v_fma_f32 v155, -v63, v154, v153
	v_fmac_f32_e32 v154, v155, v152
	v_fma_f32 v63, -v63, v154, v153
	v_div_fmas_f32 v63, v63, v152, v154
	v_div_fixup_f32 v62, v63, v62, 1.0
	v_lshlrev_b32_e32 v152, 16, v56
	v_and_b32_e32 v153, 0xffff0000, v56
	v_lshlrev_b32_e32 v56, 16, v57
	v_and_b32_e32 v57, 0xffff0000, v57
	v_pk_mul_f32 v[150:151], v[150:151], v[62:63] op_sel_hi:[1,0]
	v_pk_mul_f32 v[62:63], v[146:147], v[62:63] op_sel_hi:[1,0]
	s_nop 0
	v_pk_mul_f32 v[56:57], v[62:63], v[56:57]
	v_pk_mul_f32 v[62:63], v[150:151], v[152:153]
	s_nop 0
	v_cvt_pk_bf16_f32 v62, v62, v63
	v_cvt_pk_bf16_f32 v63, v56, v57
	v_add_f32_dpp v56, v165, v165 quad_perm:[1,0,3,2] row_mask:0xf bank_mask:0xf bound_ctrl:1
	global_store_dwordx2 v[70:71], v[62:63], off offset:512 nt
	s_nop 0
	v_add_f32_dpp v56, v56, v56 quad_perm:[2,3,0,1] row_mask:0xf bank_mask:0xf bound_ctrl:1
	s_nop 1
	v_add_f32_dpp v56, v56, v56 row_half_mirror row_mask:0xf bank_mask:0xf bound_ctrl:1
	s_nop 1
	v_add_f32_dpp v56, v56, v56 row_mirror row_mask:0xf bank_mask:0xf bound_ctrl:1
	s_nop 0
	v_readlane_b32 s9, v56, 16
	v_readlane_b32 s11, v56, 48
	v_readlane_b32 s6, v56, 0
	v_readlane_b32 s7, v56, 32
	v_mov_b32_e32 v56, s9
	v_mov_b32_e32 v57, s11
	v_pk_add_f32 v[56:57], s[6:7], v[56:57]
	s_nop 0
	v_add_f32_e32 v56, v56, v57
	v_fmamk_f32 v56, v56, 0x3b800000, v252
	v_cmp_gt_f32_e32 vcc, s55, v56
	v_mul_f32_e32 v57, 0x4f800000, v56
	s_nop 0
	v_cndmask_b32_e32 v56, v56, v57, vcc
	v_sqrt_f32_e32 v57, v56
	s_nop 0
	v_add_u32_e32 v62, -1, v57
	v_fma_f32 v63, -v62, v57, v56
	v_cmp_ge_f32_e64 s[6:7], 0, v63
	v_add_u32_e32 v63, 1, v57
	s_nop 0
	v_cndmask_b32_e64 v62, v57, v62, s[6:7]
	v_fma_f32 v57, -v63, v57, v56
	v_cmp_lt_f32_e64 s[6:7], 0, v57
	s_nop 1
	v_cndmask_b32_e64 v57, v62, v63, s[6:7]
	v_mul_f32_e32 v62, 0x37800000, v57
	v_cndmask_b32_e32 v57, v57, v62, vcc
	v_cmp_class_f32_e32 vcc, v56, v253
	s_nop 1
	v_cndmask_b32_e32 v56, v57, v56, vcc
	v_div_scale_f32 v57, s[6:7], v56, v56, 1.0
	v_rcp_f32_e32 v62, v57
	s_nop 0
	v_fma_f32 v63, -v57, v62, 1.0
	v_fmac_f32_e32 v62, v63, v62
	v_div_scale_f32 v63, vcc, 1.0, v56, 1.0
	v_mul_f32_e32 v146, v63, v62
	v_fma_f32 v147, -v57, v146, v63
	v_fmac_f32_e32 v146, v147, v62
	v_fma_f32 v57, -v57, v146, v63
	v_div_fmas_f32 v57, v57, v62, v146
	v_div_fixup_f32 v56, v57, v56, 1.0
	v_lshlrev_b32_e32 v62, 16, v50
	v_and_b32_e32 v63, 0xffff0000, v50
	v_lshlrev_b32_e32 v50, 16, v51
	v_and_b32_e32 v51, 0xffff0000, v51
	v_pk_mul_f32 v[140:141], v[140:141], v[56:57] op_sel_hi:[1,0]
	v_pk_mul_f32 v[56:57], v[134:135], v[56:57] op_sel_hi:[1,0]
	s_nop 0
	v_pk_mul_f32 v[50:51], v[56:57], v[50:51]
	v_pk_mul_f32 v[56:57], v[140:141], v[62:63]
	s_nop 0
	v_cvt_pk_bf16_f32 v56, v56, v57
	v_cvt_pk_bf16_f32 v57, v50, v51
	v_add_f32_dpp v50, v166, v166 quad_perm:[1,0,3,2] row_mask:0xf bank_mask:0xf bound_ctrl:1
	global_store_dwordx2 v[70:71], v[56:57], off offset:1024 nt
	s_nop 0
	v_add_f32_dpp v50, v50, v50 quad_perm:[2,3,0,1] row_mask:0xf bank_mask:0xf bound_ctrl:1
	s_nop 1
	v_add_f32_dpp v50, v50, v50 row_half_mirror row_mask:0xf bank_mask:0xf bound_ctrl:1
	s_nop 1
	v_add_f32_dpp v50, v50, v50 row_mirror row_mask:0xf bank_mask:0xf bound_ctrl:1
	s_nop 0
	v_readlane_b32 s9, v50, 16
	v_readlane_b32 s11, v50, 48
	v_readlane_b32 s6, v50, 0
	v_readlane_b32 s7, v50, 32
	v_mov_b32_e32 v50, s9
	v_mov_b32_e32 v51, s11
	v_pk_add_f32 v[50:51], s[6:7], v[50:51]
	s_nop 0
	v_add_f32_e32 v50, v50, v51
	v_fmamk_f32 v50, v50, 0x3b800000, v252
	v_cmp_gt_f32_e32 vcc, s55, v50
	v_mul_f32_e32 v51, 0x4f800000, v50
	s_nop 0
	v_cndmask_b32_e32 v50, v50, v51, vcc
	v_sqrt_f32_e32 v51, v50
	s_nop 0
	v_add_u32_e32 v56, -1, v51
	v_fma_f32 v57, -v56, v51, v50
	v_cmp_ge_f32_e64 s[6:7], 0, v57
	v_add_u32_e32 v57, 1, v51
	s_nop 0
	v_cndmask_b32_e64 v56, v51, v56, s[6:7]
	v_fma_f32 v51, -v57, v51, v50
	v_cmp_lt_f32_e64 s[6:7], 0, v51
	s_nop 1
	v_cndmask_b32_e64 v51, v56, v57, s[6:7]
	v_mul_f32_e32 v56, 0x37800000, v51
	v_cndmask_b32_e32 v51, v51, v56, vcc
	v_cmp_class_f32_e32 vcc, v50, v253
	s_nop 1
	v_cndmask_b32_e32 v50, v51, v50, vcc
	v_div_scale_f32 v51, s[6:7], v50, v50, 1.0
	v_rcp_f32_e32 v56, v51
	s_nop 0
	v_fma_f32 v57, -v51, v56, 1.0
	v_fmac_f32_e32 v56, v57, v56
	v_div_scale_f32 v57, vcc, 1.0, v50, 1.0
	v_mul_f32_e32 v62, v57, v56
	v_fma_f32 v63, -v51, v62, v57
	v_fmac_f32_e32 v62, v63, v56
	v_fma_f32 v51, -v51, v62, v57
	v_div_fmas_f32 v51, v51, v56, v62
	v_div_fixup_f32 v50, v51, v50, 1.0
	v_lshlrev_b32_e32 v56, 16, v44
	v_and_b32_e32 v57, 0xffff0000, v44
	v_lshlrev_b32_e32 v44, 16, v45
	v_and_b32_e32 v45, 0xffff0000, v45
	v_pk_mul_f32 v[62:63], v[88:89], v[50:51] op_sel_hi:[1,0]
	v_pk_mul_f32 v[50:51], v[86:87], v[50:51] op_sel_hi:[1,0]
	s_nop 0
	v_pk_mul_f32 v[44:45], v[50:51], v[44:45]
	v_pk_mul_f32 v[50:51], v[62:63], v[56:57]
	s_nop 0
	v_cvt_pk_bf16_f32 v50, v50, v51
	v_cvt_pk_bf16_f32 v51, v44, v45
	v_add_f32_dpp v44, v159, v159 quad_perm:[1,0,3,2] row_mask:0xf bank_mask:0xf bound_ctrl:1
	global_store_dwordx2 v[70:71], v[50:51], off offset:1536 nt
	s_nop 0
	v_add_f32_dpp v44, v44, v44 quad_perm:[2,3,0,1] row_mask:0xf bank_mask:0xf bound_ctrl:1
	s_nop 1
	v_add_f32_dpp v44, v44, v44 row_half_mirror row_mask:0xf bank_mask:0xf bound_ctrl:1
	s_nop 1
	v_add_f32_dpp v44, v44, v44 row_mirror row_mask:0xf bank_mask:0xf bound_ctrl:1
	s_nop 0
	v_readlane_b32 s9, v44, 16
	v_readlane_b32 s11, v44, 48
	v_readlane_b32 s6, v44, 0
	v_readlane_b32 s7, v44, 32
	v_mov_b32_e32 v44, s9
	v_mov_b32_e32 v45, s11
	v_pk_add_f32 v[44:45], s[6:7], v[44:45]
	s_nop 0
	v_add_f32_e32 v44, v44, v45
	v_fmamk_f32 v44, v44, 0x3b800000, v252
	v_cmp_gt_f32_e32 vcc, s55, v44
	v_mul_f32_e32 v45, 0x4f800000, v44
	s_nop 0
	v_cndmask_b32_e32 v44, v44, v45, vcc
	v_sqrt_f32_e32 v45, v44
	s_nop 0
	v_add_u32_e32 v50, -1, v45
	v_fma_f32 v51, -v50, v45, v44
	v_cmp_ge_f32_e64 s[6:7], 0, v51
	v_add_u32_e32 v51, 1, v45
	s_nop 0
	v_cndmask_b32_e64 v50, v45, v50, s[6:7]
	v_fma_f32 v45, -v51, v45, v44
	v_cmp_lt_f32_e64 s[6:7], 0, v45
	s_nop 1
	v_cndmask_b32_e64 v45, v50, v51, s[6:7]
	v_mul_f32_e32 v50, 0x37800000, v45
	v_cndmask_b32_e32 v45, v45, v50, vcc
	v_cmp_class_f32_e32 vcc, v44, v253
	s_nop 1
	v_cndmask_b32_e32 v44, v45, v44, vcc
	v_div_scale_f32 v45, s[6:7], v44, v44, 1.0
	v_rcp_f32_e32 v50, v45
	s_nop 0
	v_fma_f32 v51, -v45, v50, 1.0
	v_fmac_f32_e32 v50, v51, v50
	v_div_scale_f32 v51, vcc, 1.0, v44, 1.0
	v_mul_f32_e32 v56, v51, v50
	v_fma_f32 v57, -v45, v56, v51
	v_fmac_f32_e32 v56, v57, v50
	v_fma_f32 v45, -v45, v56, v51
	v_div_fmas_f32 v45, v45, v50, v56
	v_div_fixup_f32 v44, v45, v44, 1.0
	v_lshlrev_b32_e32 v50, 16, v38
	v_and_b32_e32 v51, 0xffff0000, v38
	v_lshlrev_b32_e32 v38, 16, v39
	v_and_b32_e32 v39, 0xffff0000, v39
	v_pk_mul_f32 v[56:57], v[84:85], v[44:45] op_sel_hi:[1,0]
	v_pk_mul_f32 v[44:45], v[82:83], v[44:45] op_sel_hi:[1,0]
	s_nop 0
	v_pk_mul_f32 v[38:39], v[44:45], v[38:39]
	v_pk_mul_f32 v[44:45], v[56:57], v[50:51]
; template <bool HG>
; __device__ __forceinline__ void readout_phase2(const Args& a, Frame& F, const float* gain, int nrows) {
;     ...
;     const bool cx = ML + nw < nrows;
;     RO_LOAD(f2, b2, g2, cx ? ML + nw : nw + 7 * 2048);
	s_nop 0
	v_cvt_pk_bf16_f32 v44, v44, v45
	v_cvt_pk_bf16_f32 v45, v38, v39
	v_add_f32_dpp v38, v158, v158 quad_perm:[1,0,3,2] row_mask:0xf bank_mask:0xf bound_ctrl:1
	global_store_dwordx2 v[70:71], v[44:45], off offset:2048 nt
	s_nop 0
	v_add_f32_dpp v38, v38, v38 quad_perm:[2,3,0,1] row_mask:0xf bank_mask:0xf bound_ctrl:1
	s_nop 1
	v_add_f32_dpp v38, v38, v38 row_half_mirror row_mask:0xf bank_mask:0xf bound_ctrl:1
	s_nop 1
	v_add_f32_dpp v38, v38, v38 row_mirror row_mask:0xf bank_mask:0xf bound_ctrl:1
	s_nop 0
	v_readlane_b32 s9, v38, 16
	v_readlane_b32 s11, v38, 48
	v_readlane_b32 s6, v38, 0
	v_readlane_b32 s7, v38, 32
	v_mov_b32_e32 v38, s9
	v_mov_b32_e32 v39, s11
	v_pk_add_f32 v[38:39], s[6:7], v[38:39]
	s_nop 0
	v_add_f32_e32 v38, v38, v39
	v_fmamk_f32 v38, v38, 0x3b800000, v252
	v_cmp_gt_f32_e32 vcc, s55, v38
	v_mul_f32_e32 v39, 0x4f800000, v38
	s_nop 0
	v_cndmask_b32_e32 v38, v38, v39, vcc
	v_sqrt_f32_e32 v39, v38
	s_nop 0
	v_add_u32_e32 v44, -1, v39
	v_fma_f32 v45, -v44, v39, v38
	v_cmp_ge_f32_e64 s[6:7], 0, v45
	v_add_u32_e32 v45, 1, v39
	s_nop 0
	v_cndmask_b32_e64 v44, v39, v44, s[6:7]
	v_fma_f32 v39, -v45, v39, v38
	v_cmp_lt_f32_e64 s[6:7], 0, v39
	s_nop 1
	v_cndmask_b32_e64 v39, v44, v45, s[6:7]
	v_mul_f32_e32 v44, 0x37800000, v39
	v_cndmask_b32_e32 v39, v39, v44, vcc
	v_cmp_class_f32_e32 vcc, v38, v253
	s_nop 1
	v_cndmask_b32_e32 v38, v39, v38, vcc
	v_div_scale_f32 v39, s[6:7], v38, v38, 1.0
	v_rcp_f32_e32 v44, v39
	s_nop 0
	v_fma_f32 v45, -v39, v44, 1.0
	v_fmac_f32_e32 v44, v45, v44
	v_div_scale_f32 v45, vcc, 1.0, v38, 1.0
	v_mul_f32_e32 v50, v45, v44
	v_fma_f32 v51, -v39, v50, v45
	v_fmac_f32_e32 v50, v51, v44
	v_fma_f32 v39, -v39, v50, v45
	v_div_fmas_f32 v39, v39, v44, v50
	v_div_fixup_f32 v38, v39, v38, 1.0
	v_lshlrev_b32_e32 v44, 16, v34
	v_and_b32_e32 v45, 0xffff0000, v34
	v_lshlrev_b32_e32 v34, 16, v35
	v_and_b32_e32 v35, 0xffff0000, v35
	v_pk_mul_f32 v[50:51], v[80:81], v[38:39] op_sel_hi:[1,0]
	v_pk_mul_f32 v[38:39], v[78:79], v[38:39] op_sel_hi:[1,0]
	s_nop 0
	v_pk_mul_f32 v[34:35], v[38:39], v[34:35]
	v_pk_mul_f32 v[38:39], v[50:51], v[44:45]
	s_nop 0
	v_cvt_pk_bf16_f32 v38, v38, v39
	v_cvt_pk_bf16_f32 v39, v34, v35
	v_add_f32_dpp v34, v157, v157 quad_perm:[1,0,3,2] row_mask:0xf bank_mask:0xf bound_ctrl:1
	global_store_dwordx2 v[70:71], v[38:39], off offset:2560 nt
	s_nop 0
	v_add_f32_dpp v34, v34, v34 quad_perm:[2,3,0,1] row_mask:0xf bank_mask:0xf bound_ctrl:1
	s_nop 1
	v_add_f32_dpp v34, v34, v34 row_half_mirror row_mask:0xf bank_mask:0xf bound_ctrl:1
	s_nop 1
	v_add_f32_dpp v34, v34, v34 row_mirror row_mask:0xf bank_mask:0xf bound_ctrl:1
	s_nop 0
	v_readlane_b32 s9, v34, 16
	v_readlane_b32 s11, v34, 48
	v_readlane_b32 s6, v34, 0
	v_readlane_b32 s7, v34, 32
	v_mov_b32_e32 v34, s9
	v_mov_b32_e32 v35, s11
	v_pk_add_f32 v[34:35], s[6:7], v[34:35]
	s_nop 0
	v_add_f32_e32 v34, v34, v35
	v_fmamk_f32 v34, v34, 0x3b800000, v252
	v_cmp_gt_f32_e32 vcc, s55, v34
	v_mul_f32_e32 v35, 0x4f800000, v34
	s_nop 0
	v_cndmask_b32_e32 v34, v34, v35, vcc
	v_sqrt_f32_e32 v35, v34
	s_nop 0
	v_add_u32_e32 v38, -1, v35
	v_fma_f32 v39, -v38, v35, v34
	v_cmp_ge_f32_e64 s[6:7], 0, v39
	v_add_u32_e32 v39, 1, v35
	s_nop 0
	v_cndmask_b32_e64 v38, v35, v38, s[6:7]
	v_fma_f32 v35, -v39, v35, v34
	v_cmp_lt_f32_e64 s[6:7], 0, v35
	s_nop 1
	v_cndmask_b32_e64 v35, v38, v39, s[6:7]
	v_mul_f32_e32 v38, 0x37800000, v35
	v_cndmask_b32_e32 v35, v35, v38, vcc
	v_cmp_class_f32_e32 vcc, v34, v253
	s_nop 1
	v_cndmask_b32_e32 v34, v35, v34, vcc
	v_div_scale_f32 v35, s[6:7], v34, v34, 1.0
	v_rcp_f32_e32 v38, v35
	s_nop 0
	v_fma_f32 v39, -v35, v38, 1.0
	v_fmac_f32_e32 v38, v39, v38
	v_div_scale_f32 v39, vcc, 1.0, v34, 1.0
	v_mul_f32_e32 v44, v39, v38
	v_fma_f32 v45, -v35, v44, v39
	v_fmac_f32_e32 v44, v45, v38
	v_fma_f32 v35, -v35, v44, v39
	v_div_fmas_f32 v35, v35, v38, v44
	v_div_fixup_f32 v34, v35, v34, 1.0
	v_lshlrev_b32_e32 v38, 16, v30
	v_and_b32_e32 v39, 0xffff0000, v30
	v_lshlrev_b32_e32 v30, 16, v31
	v_and_b32_e32 v31, 0xffff0000, v31
	v_pk_mul_f32 v[44:45], v[76:77], v[34:35] op_sel_hi:[1,0]
	v_pk_mul_f32 v[34:35], v[74:75], v[34:35] op_sel_hi:[1,0]
	s_nop 0
	v_pk_mul_f32 v[30:31], v[34:35], v[30:31]
	v_pk_mul_f32 v[34:35], v[44:45], v[38:39]
	s_nop 0
	v_cvt_pk_bf16_f32 v34, v34, v35
	v_cvt_pk_bf16_f32 v35, v30, v31
	v_add_f32_dpp v30, v156, v156 quad_perm:[1,0,3,2] row_mask:0xf bank_mask:0xf bound_ctrl:1
	global_store_dwordx2 v[70:71], v[34:35], off offset:3072 nt
	s_nop 0
	v_add_f32_dpp v30, v30, v30 quad_perm:[2,3,0,1] row_mask:0xf bank_mask:0xf bound_ctrl:1
	s_nop 1
	v_add_f32_dpp v30, v30, v30 row_half_mirror row_mask:0xf bank_mask:0xf bound_ctrl:1
	s_nop 1
	v_add_f32_dpp v30, v30, v30 row_mirror row_mask:0xf bank_mask:0xf bound_ctrl:1
	s_nop 0
	v_readlane_b32 s9, v30, 16
	v_readlane_b32 s11, v30, 48
	v_readlane_b32 s6, v30, 0
	v_readlane_b32 s7, v30, 32
	v_mov_b32_e32 v30, s9
	v_mov_b32_e32 v31, s11
	v_pk_add_f32 v[30:31], s[6:7], v[30:31]
	s_nop 0
	v_add_f32_e32 v30, v30, v31
	v_fmamk_f32 v30, v30, 0x3b800000, v252
	v_cmp_gt_f32_e32 vcc, s55, v30
	v_mul_f32_e32 v31, 0x4f800000, v30
	s_nop 0
	v_cndmask_b32_e32 v30, v30, v31, vcc
	v_sqrt_f32_e32 v31, v30
	s_nop 0
	v_add_u32_e32 v34, -1, v31
	v_fma_f32 v35, -v34, v31, v30
	v_cmp_ge_f32_e64 s[6:7], 0, v35
	v_add_u32_e32 v35, 1, v31
	s_nop 0
	v_cndmask_b32_e64 v34, v31, v34, s[6:7]
	v_fma_f32 v31, -v35, v31, v30
	v_cmp_lt_f32_e64 s[6:7], 0, v31
	s_nop 1
	v_cndmask_b32_e64 v31, v34, v35, s[6:7]
	v_mul_f32_e32 v34, 0x37800000, v31
	v_cndmask_b32_e32 v31, v31, v34, vcc
	v_cmp_class_f32_e32 vcc, v30, v253
	s_nop 1
	v_cndmask_b32_e32 v30, v31, v30, vcc
	v_div_scale_f32 v31, s[6:7], v30, v30, 1.0
	v_rcp_f32_e32 v34, v31
	s_cselect_b32 s6, s82, s10
	s_ashr_i32 s7, s6, 31
	s_lshl_b64 s[48:49], s[6:7], 12
	v_fma_f32 v35, -v31, v34, 1.0
	v_fmac_f32_e32 v34, v35, v34
	v_div_scale_f32 v35, vcc, 1.0, v30, 1.0
	v_mul_f32_e32 v38, v35, v34
	v_fma_f32 v39, -v31, v38, v35
	v_fmac_f32_e32 v38, v39, v34
	v_fma_f32 v31, -v31, v38, v35
	v_div_fmas_f32 v31, v31, v34, v38
	v_div_fixup_f32 v30, v31, v30, 1.0
	s_waitcnt vmcnt(62)
	v_lshlrev_b32_e32 v34, 16, v26
	v_and_b32_e32 v35, 0xffff0000, v26
	v_lshlrev_b32_e32 v26, 16, v27
	v_and_b32_e32 v27, 0xffff0000, v27
	v_pk_mul_f32 v[38:39], v[72:73], v[30:31] op_sel_hi:[1,0]
	v_pk_mul_f32 v[30:31], v[68:69], v[30:31] op_sel_hi:[1,0]
	v_lshl_add_u64 v[6:7], v[6:7], 0, s[48:49]
	v_pk_mul_f32 v[26:27], v[30:31], v[26:27]
	v_pk_mul_f32 v[30:31], v[38:39], v[34:35]
	v_lshl_add_u64 v[4:5], v[4:5], 0, s[48:49]
	v_cvt_pk_bf16_f32 v30, v30, v31
	v_cvt_pk_bf16_f32 v31, v26, v27
	global_store_dwordx2 v[70:71], v[30:31], off offset:3584 nt
	v_lshlrev_b32_e32 v26, 16, v148
	v_and_b32_e32 v27, 0xffff0000, v148
	s_waitcnt vmcnt(62)
	v_lshlrev_b32_e32 v30, 16, v142
	v_and_b32_e32 v31, 0xffff0000, v142
	v_pk_add_f32 v[140:141], v[26:27], v[30:31]
	v_lshlrev_b32_e32 v26, 16, v149
	v_and_b32_e32 v27, 0xffff0000, v149
	v_lshlrev_b32_e32 v30, 16, v143
	v_and_b32_e32 v31, 0xffff0000, v143
	v_pk_add_f32 v[142:143], v[26:27], v[30:31]
	v_mov_b32_e32 v30, v141
	v_mov_b32_e32 v31, v143
	v_mov_b32_e32 v26, v140
	v_mov_b32_e32 v27, v142
	v_pk_mul_f32 v[30:31], v[30:31], v[30:31]
	v_lshl_add_u64 v[4:5], v[4:5], 0, v[0:1]
	v_pk_fma_f32 v[26:27], v[26:27], v[26:27], v[30:31]
	s_waitcnt vmcnt(59)
	v_lshlrev_b32_e32 v30, 16, v130
	v_add_f32_e32 v34, v26, v27
	v_lshlrev_b32_e32 v26, 16, v136
	v_and_b32_e32 v27, 0xffff0000, v136
	v_and_b32_e32 v31, 0xffff0000, v130
	v_pk_add_f32 v[134:135], v[26:27], v[30:31]
	v_lshlrev_b32_e32 v26, 16, v137
	v_and_b32_e32 v27, 0xffff0000, v137
	v_lshlrev_b32_e32 v30, 16, v131
	v_and_b32_e32 v31, 0xffff0000, v131
	v_pk_add_f32 v[136:137], v[26:27], v[30:31]
	v_mov_b32_e32 v30, v135
	v_mov_b32_e32 v31, v137
	v_mov_b32_e32 v26, v134
	v_mov_b32_e32 v27, v136
	v_pk_mul_f32 v[30:31], v[30:31], v[30:31]
	s_cmp_ge_i32 s82, s47
	v_pk_fma_f32 v[26:27], v[26:27], v[26:27], v[30:31]
	s_waitcnt vmcnt(56)
	v_lshlrev_b32_e32 v30, 16, v122
	v_add_f32_e32 v35, v26, v27
	v_lshlrev_b32_e32 v26, 16, v126
	v_and_b32_e32 v27, 0xffff0000, v126
	v_and_b32_e32 v31, 0xffff0000, v122
	v_pk_add_f32 v[130:131], v[26:27], v[30:31]
	v_lshlrev_b32_e32 v26, 16, v127
	v_and_b32_e32 v27, 0xffff0000, v127
	v_lshlrev_b32_e32 v30, 16, v123
	v_and_b32_e32 v31, 0xffff0000, v123
	v_pk_add_f32 v[122:123], v[26:27], v[30:31]
	v_mov_b32_e32 v30, v131
	v_mov_b32_e32 v31, v123
	v_mov_b32_e32 v26, v130
	v_mov_b32_e32 v27, v122
	v_pk_mul_f32 v[30:31], v[30:31], v[30:31]
	s_nop 0
	v_pk_fma_f32 v[26:27], v[26:27], v[26:27], v[30:31]
	s_waitcnt vmcnt(53)
	v_lshlrev_b32_e32 v30, 16, v118
	v_add_f32_e32 v38, v26, v27
	v_lshlrev_b32_e32 v26, 16, v114
	v_and_b32_e32 v27, 0xffff0000, v114
	v_and_b32_e32 v31, 0xffff0000, v118
	v_pk_add_f32 v[86:87], v[26:27], v[30:31]
	v_lshlrev_b32_e32 v26, 16, v115
	v_and_b32_e32 v27, 0xffff0000, v115
	v_lshlrev_b32_e32 v30, 16, v119
	v_and_b32_e32 v31, 0xffff0000, v119
	v_pk_add_f32 v[88:89], v[26:27], v[30:31]
	v_mov_b32_e32 v30, v87
	v_mov_b32_e32 v31, v89
	v_mov_b32_e32 v26, v86
	v_mov_b32_e32 v27, v88
	v_pk_mul_f32 v[30:31], v[30:31], v[30:31]
	s_nop 0
	v_pk_fma_f32 v[26:27], v[26:27], v[26:27], v[30:31]
	s_waitcnt vmcnt(50)
	v_lshlrev_b32_e32 v30, 16, v106
	v_add_f32_e32 v39, v26, v27
	v_lshlrev_b32_e32 v26, 16, v110
	v_and_b32_e32 v27, 0xffff0000, v110
	v_and_b32_e32 v31, 0xffff0000, v106
	v_pk_add_f32 v[78:79], v[26:27], v[30:31]
	v_lshlrev_b32_e32 v26, 16, v111
	v_and_b32_e32 v27, 0xffff0000, v111
	v_lshlrev_b32_e32 v30, 16, v107
	v_and_b32_e32 v31, 0xffff0000, v107
	v_pk_add_f32 v[80:81], v[26:27], v[30:31]
	v_mov_b32_e32 v30, v79
	v_mov_b32_e32 v31, v81
	v_mov_b32_e32 v26, v78
	v_mov_b32_e32 v27, v80
	v_pk_mul_f32 v[30:31], v[30:31], v[30:31]
	s_nop 0
	v_pk_fma_f32 v[26:27], v[26:27], v[26:27], v[30:31]
	s_waitcnt vmcnt(47)
	v_lshlrev_b32_e32 v30, 16, v98
	v_add_f32_e32 v56, v26, v27
	v_lshlrev_b32_e32 v26, 16, v102
	v_and_b32_e32 v27, 0xffff0000, v102
	v_and_b32_e32 v31, 0xffff0000, v98
	v_pk_add_f32 v[70:71], v[26:27], v[30:31]
	v_lshlrev_b32_e32 v26, 16, v103
	v_and_b32_e32 v27, 0xffff0000, v103
	v_lshlrev_b32_e32 v30, 16, v99
	v_and_b32_e32 v31, 0xffff0000, v99
	v_pk_add_f32 v[72:73], v[26:27], v[30:31]
	v_mov_b32_e32 v30, v71
	v_mov_b32_e32 v31, v73
	v_mov_b32_e32 v26, v70
	v_mov_b32_e32 v27, v72
	v_pk_mul_f32 v[30:31], v[30:31], v[30:31]
	s_nop 0
	v_pk_fma_f32 v[26:27], v[26:27], v[26:27], v[30:31]
	s_waitcnt vmcnt(44)
	v_lshlrev_b32_e32 v30, 16, v90
	v_add_f32_e32 v57, v26, v27
	v_lshlrev_b32_e32 v26, 16, v94
	v_and_b32_e32 v27, 0xffff0000, v94
	v_and_b32_e32 v31, 0xffff0000, v90
	v_pk_add_f32 v[62:63], v[26:27], v[30:31]
	v_lshlrev_b32_e32 v26, 16, v95
	v_and_b32_e32 v27, 0xffff0000, v95
	v_lshlrev_b32_e32 v30, 16, v91
	v_and_b32_e32 v31, 0xffff0000, v91
	v_pk_add_f32 v[68:69], v[26:27], v[30:31]
	v_mov_b32_e32 v30, v63
	v_mov_b32_e32 v31, v69
	v_mov_b32_e32 v26, v62
	v_mov_b32_e32 v27, v68
	v_pk_mul_f32 v[30:31], v[30:31], v[30:31]
	s_nop 0
	v_pk_fma_f32 v[26:27], v[26:27], v[26:27], v[30:31]
	s_waitcnt vmcnt(41)
	v_lshlrev_b32_e32 v30, 16, v64
	v_add_f32_e32 v74, v26, v27
	v_lshlrev_b32_e32 v26, 16, v58
	v_and_b32_e32 v27, 0xffff0000, v58
	v_and_b32_e32 v31, 0xffff0000, v64
	v_pk_add_f32 v[44:45], v[26:27], v[30:31]
	v_lshlrev_b32_e32 v26, 16, v59
	v_and_b32_e32 v27, 0xffff0000, v59
	v_lshlrev_b32_e32 v30, 16, v65
	v_and_b32_e32 v31, 0xffff0000, v65
	v_pk_add_f32 v[50:51], v[26:27], v[30:31]
	v_mov_b32_e32 v30, v45
	v_mov_b32_e32 v31, v51
	v_mov_b32_e32 v26, v44
	v_mov_b32_e32 v27, v50
	v_pk_mul_f32 v[30:31], v[30:31], v[30:31]
	s_nop 0
	v_pk_fma_f32 v[26:27], v[26:27], v[26:27], v[30:31]
	s_waitcnt vmcnt(30)
; template <int CTRL> __device__ __forceinline__ float dpp_mov(float v) { return __builtin_bit_cast(float, __builtin_amdgcn_update_dpp(0, __builtin_bit_cast(int, v), CTRL, 0xF, 0xF, true)); }
; __device__ __forceinline__ float wave_sum(float v) {
;     v += dpp_mov<0xB1>(v);
;     v += dpp_mov<0x4E>(v);
;     v += dpp_mov<0x141>(v);
;     v += dpp_mov<0x140>(v);
;     const int iv = __builtin_bit_cast(int, v);
;     const float a = __builtin_bit_cast(float, __builtin_amdgcn_readlane(iv, 0)), b = __builtin_bit_cast(float, __builtin_amdgcn_readlane(iv, 16));
;     const float c = __builtin_bit_cast(float, __builtin_amdgcn_readlane(iv, 32)), d = __builtin_bit_cast(float, __builtin_amdgcn_readlane(iv, 48));
;     return (a + b) + (c + d);
; }
	v_and_b32_e32 v31, 0xffff0000, v138
	v_add_f32_e32 v30, v26, v27
	v_add_f32_dpp v26, v34, v34 quad_perm:[1,0,3,2] row_mask:0xf bank_mask:0xf bound_ctrl:1
	s_nop 1
	v_add_f32_dpp v26, v26, v26 quad_perm:[2,3,0,1] row_mask:0xf bank_mask:0xf bound_ctrl:1
	s_nop 1
	v_add_f32_dpp v26, v26, v26 row_half_mirror row_mask:0xf bank_mask:0xf bound_ctrl:1
	s_nop 1
	v_add_f32_dpp v26, v26, v26 row_mirror row_mask:0xf bank_mask:0xf bound_ctrl:1
	s_nop 0
	v_readlane_b32 s8, v26, 16
	v_readlane_b32 s9, v26, 48
	v_readlane_b32 s6, v26, 0
	v_readlane_b32 s7, v26, 32
	v_mov_b32_e32 v26, s8
	v_mov_b32_e32 v27, s9
	v_pk_add_f32 v[26:27], s[6:7], v[26:27]
	s_nop 0
	v_add_f32_e32 v26, v26, v27
	v_fmamk_f32 v26, v26, 0x3b800000, v252
	v_cmp_gt_f32_e32 vcc, s55, v26
	v_mul_f32_e32 v27, 0x4f800000, v26
	s_nop 0
	v_cndmask_b32_e32 v211, v26, v27, vcc
	v_add_f32_dpp v26, v35, v35 quad_perm:[1,0,3,2] row_mask:0xf bank_mask:0xf bound_ctrl:1
	v_sqrt_f32_e32 v214, v211
	s_nop 0
	v_add_f32_dpp v26, v26, v26 quad_perm:[2,3,0,1] row_mask:0xf bank_mask:0xf bound_ctrl:1
	v_add_u32_e32 v216, -1, v214
	s_nop 0
	v_add_f32_dpp v26, v26, v26 row_half_mirror row_mask:0xf bank_mask:0xf bound_ctrl:1
	v_add_u32_e32 v213, 1, v214
	v_fma_f32 v178, -v216, v214, v211
	v_add_f32_dpp v26, v26, v26 row_mirror row_mask:0xf bank_mask:0xf bound_ctrl:1
	v_fma_f32 v179, -v213, v214, v211
	v_readlane_b32 s8, v26, 16
	v_readlane_b32 s9, v26, 48
	v_readlane_b32 s6, v26, 0
	v_readlane_b32 s7, v26, 32
	v_mov_b32_e32 v26, s8
	v_mov_b32_e32 v27, s9
	v_pk_add_f32 v[26:27], s[6:7], v[26:27]
	s_nop 0
	v_add_f32_e32 v26, v26, v27
	v_fmamk_f32 v26, v26, 0x3b800000, v252
	v_cmp_gt_f32_e64 s[30:31], s55, v26
	v_mul_f32_e32 v27, 0x4f800000, v26
	s_nop 0
	v_cndmask_b32_e64 v202, v26, v27, s[30:31]
	v_add_f32_dpp v26, v38, v38 quad_perm:[1,0,3,2] row_mask:0xf bank_mask:0xf bound_ctrl:1
	v_sqrt_f32_e32 v205, v202
	s_nop 0
	v_add_f32_dpp v26, v26, v26 quad_perm:[2,3,0,1] row_mask:0xf bank_mask:0xf bound_ctrl:1
	v_add_u32_e32 v209, -1, v205
	s_nop 0
	v_add_f32_dpp v26, v26, v26 row_half_mirror row_mask:0xf bank_mask:0xf bound_ctrl:1
	v_add_u32_e32 v207, 1, v205
	s_nop 0
	v_add_f32_dpp v26, v26, v26 row_mirror row_mask:0xf bank_mask:0xf bound_ctrl:1
	s_nop 0
	v_readlane_b32 s8, v26, 16
	v_readlane_b32 s9, v26, 48
	v_readlane_b32 s6, v26, 0
	v_readlane_b32 s7, v26, 32
	v_mov_b32_e32 v26, s8
	v_mov_b32_e32 v27, s9
	v_pk_add_f32 v[26:27], s[6:7], v[26:27]
	s_nop 0
	v_add_f32_e32 v26, v26, v27
	v_fmamk_f32 v26, v26, 0x3b800000, v252
	v_cmp_gt_f32_e64 s[26:27], s55, v26
	v_mul_f32_e32 v27, 0x4f800000, v26
	s_nop 0
	v_cndmask_b32_e64 v194, v26, v27, s[26:27]
	v_add_f32_dpp v26, v39, v39 quad_perm:[1,0,3,2] row_mask:0xf bank_mask:0xf bound_ctrl:1
	v_sqrt_f32_e32 v197, v194
	s_nop 0
	v_add_f32_dpp v26, v26, v26 quad_perm:[2,3,0,1] row_mask:0xf bank_mask:0xf bound_ctrl:1
	v_add_u32_e32 v199, -1, v197
	s_nop 0
	v_add_f32_dpp v26, v26, v26 row_half_mirror row_mask:0xf bank_mask:0xf bound_ctrl:1
	v_add_u32_e32 v196, 1, v197
	s_nop 0
	v_add_f32_dpp v26, v26, v26 row_mirror row_mask:0xf bank_mask:0xf bound_ctrl:1
	s_nop 0
	v_readlane_b32 s8, v26, 16
	v_readlane_b32 s9, v26, 48
	v_readlane_b32 s6, v26, 0
	v_readlane_b32 s7, v26, 32
	v_mov_b32_e32 v26, s8
	v_mov_b32_e32 v27, s9
	v_pk_add_f32 v[26:27], s[6:7], v[26:27]
	s_nop 0
	v_add_f32_e32 v26, v26, v27
	v_fmamk_f32 v26, v26, 0x3b800000, v252
	v_cmp_gt_f32_e64 s[22:23], s55, v26
	v_mul_f32_e32 v27, 0x4f800000, v26
	s_nop 0
	v_cndmask_b32_e64 v186, v26, v27, s[22:23]
	v_add_f32_dpp v26, v56, v56 quad_perm:[1,0,3,2] row_mask:0xf bank_mask:0xf bound_ctrl:1
	v_sqrt_f32_e32 v189, v186
	s_nop 0
	v_add_f32_dpp v26, v26, v26 quad_perm:[2,3,0,1] row_mask:0xf bank_mask:0xf bound_ctrl:1
	v_add_u32_e32 v193, -1, v189
	s_nop 0
	v_add_f32_dpp v26, v26, v26 row_half_mirror row_mask:0xf bank_mask:0xf bound_ctrl:1
	v_add_u32_e32 v191, 1, v189
	s_nop 0
	v_add_f32_dpp v26, v26, v26 row_mirror row_mask:0xf bank_mask:0xf bound_ctrl:1
	s_nop 0
	v_readlane_b32 s8, v26, 16
	v_readlane_b32 s9, v26, 48
	v_readlane_b32 s6, v26, 0
	v_readlane_b32 s7, v26, 32
	v_mov_b32_e32 v26, s8
	v_mov_b32_e32 v27, s9
	v_pk_add_f32 v[26:27], s[6:7], v[26:27]
	s_nop 0
	v_add_f32_e32 v26, v26, v27
	v_fmamk_f32 v26, v26, 0x3b800000, v252
	v_cmp_gt_f32_e64 s[18:19], s55, v26
	v_mul_f32_e32 v27, 0x4f800000, v26
	s_nop 0
	v_cndmask_b32_e64 v172, v26, v27, s[18:19]
	v_add_f32_dpp v26, v57, v57 quad_perm:[1,0,3,2] row_mask:0xf bank_mask:0xf bound_ctrl:1
	v_sqrt_f32_e32 v175, v172
	s_nop 0
	v_add_f32_dpp v26, v26, v26 quad_perm:[2,3,0,1] row_mask:0xf bank_mask:0xf bound_ctrl:1
	v_add_u32_e32 v177, -1, v175
	s_nop 0
	v_add_f32_dpp v26, v26, v26 row_half_mirror row_mask:0xf bank_mask:0xf bound_ctrl:1
	v_add_u32_e32 v174, 1, v175
	s_nop 0
	v_add_f32_dpp v26, v26, v26 row_mirror row_mask:0xf bank_mask:0xf bound_ctrl:1
	s_nop 0
	v_readlane_b32 s8, v26, 16
	v_readlane_b32 s9, v26, 48
	v_readlane_b32 s6, v26, 0
	v_readlane_b32 s7, v26, 32
	v_mov_b32_e32 v26, s8
	v_mov_b32_e32 v27, s9
	v_pk_add_f32 v[26:27], s[6:7], v[26:27]
	s_nop 0
	v_add_f32_e32 v26, v26, v27
	v_fmamk_f32 v26, v26, 0x3b800000, v252
	v_cmp_gt_f32_e64 s[14:15], s55, v26
	v_mul_f32_e32 v27, 0x4f800000, v26
	s_nop 0
	v_cndmask_b32_e64 v164, v26, v27, s[14:15]
	v_add_f32_dpp v26, v74, v74 quad_perm:[1,0,3,2] row_mask:0xf bank_mask:0xf bound_ctrl:1
	v_sqrt_f32_e32 v167, v164
	s_nop 0
	v_add_f32_dpp v26, v26, v26 quad_perm:[2,3,0,1] row_mask:0xf bank_mask:0xf bound_ctrl:1
	v_add_u32_e32 v171, -1, v167
	s_nop 0
	v_add_f32_dpp v26, v26, v26 row_half_mirror row_mask:0xf bank_mask:0xf bound_ctrl:1
	v_add_u32_e32 v169, 1, v167
	s_nop 0
	v_add_f32_dpp v26, v26, v26 row_mirror row_mask:0xf bank_mask:0xf bound_ctrl:1
	s_nop 0
	v_readlane_b32 s8, v26, 16
	v_readlane_b32 s9, v26, 48
	v_readlane_b32 s6, v26, 0
	v_readlane_b32 s7, v26, 32
	v_mov_b32_e32 v26, s8
	v_mov_b32_e32 v27, s9
	v_pk_add_f32 v[26:27], s[6:7], v[26:27]
	s_nop 0
	v_add_f32_e32 v26, v26, v27
	v_fmamk_f32 v26, v26, 0x3b800000, v252
	v_cmp_gt_f32_e64 s[10:11], s55, v26
	v_mul_f32_e32 v27, 0x4f800000, v26
	s_nop 0
	v_cndmask_b32_e64 v156, v26, v27, s[10:11]
	v_add_f32_dpp v26, v30, v30 quad_perm:[1,0,3,2] row_mask:0xf bank_mask:0xf bound_ctrl:1
	v_lshlrev_b32_e32 v30, 16, v138
	v_sqrt_f32_e32 v159, v156
	v_add_f32_dpp v26, v26, v26 quad_perm:[2,3,0,1] row_mask:0xf bank_mask:0xf bound_ctrl:1
	v_add_u32_e32 v161, -1, v159
	s_nop 0
	v_add_f32_dpp v26, v26, v26 row_half_mirror row_mask:0xf bank_mask:0xf bound_ctrl:1
	v_add_u32_e32 v158, 1, v159
	s_nop 0
	v_add_f32_dpp v26, v26, v26 row_mirror row_mask:0xf bank_mask:0xf bound_ctrl:1
	s_nop 0
	v_readlane_b32 s8, v26, 16
	v_readlane_b32 s9, v26, 48
	v_readlane_b32 s6, v26, 0
	v_readlane_b32 s7, v26, 32
	v_mov_b32_e32 v26, s8
	v_mov_b32_e32 v27, s9
	v_pk_add_f32 v[26:27], s[6:7], v[26:27]
	s_nop 0
	v_add_f32_e32 v26, v26, v27
	v_fmamk_f32 v26, v26, 0x3b800000, v252
	v_cmp_gt_f32_e64 s[6:7], s55, v26
	v_mul_f32_e32 v27, 0x4f800000, v26
	s_nop 0
	v_cndmask_b32_e64 v150, v26, v27, s[6:7]
	v_lshlrev_b32_e32 v26, 16, v144
	v_and_b32_e32 v27, 0xffff0000, v144
	v_pk_add_f32 v[126:127], v[26:27], v[30:31]
	v_lshlrev_b32_e32 v26, 16, v145
	v_and_b32_e32 v27, 0xffff0000, v145
	v_lshlrev_b32_e32 v30, 16, v139
	v_and_b32_e32 v31, 0xffff0000, v139
	v_pk_add_f32 v[138:139], v[26:27], v[30:31]
	v_mov_b32_e32 v30, v127
	v_mov_b32_e32 v31, v139
	v_mov_b32_e32 v26, v126
	v_mov_b32_e32 v27, v138
	v_pk_mul_f32 v[30:31], v[30:31], v[30:31]
	v_sqrt_f32_e32 v151, v150
	v_pk_fma_f32 v[26:27], v[26:27], v[26:27], v[30:31]
	s_waitcnt vmcnt(27)
	v_lshlrev_b32_e32 v30, 16, v128
	v_add_f32_e32 v34, v26, v27
	v_lshlrev_b32_e32 v26, 16, v132
	v_and_b32_e32 v27, 0xffff0000, v132
	v_and_b32_e32 v31, 0xffff0000, v128
	v_pk_add_f32 v[114:115], v[26:27], v[30:31]
	v_lshlrev_b32_e32 v26, 16, v133
	v_and_b32_e32 v27, 0xffff0000, v133
	v_lshlrev_b32_e32 v30, 16, v129
	v_and_b32_e32 v31, 0xffff0000, v129
	v_pk_add_f32 v[118:119], v[26:27], v[30:31]
	v_mov_b32_e32 v30, v115
	v_mov_b32_e32 v31, v119
	v_mov_b32_e32 v26, v114
	v_mov_b32_e32 v27, v118
	v_pk_mul_f32 v[30:31], v[30:31], v[30:31]
	v_add_u32_e32 v155, -1, v151
	v_pk_fma_f32 v[26:27], v[26:27], v[26:27], v[30:31]
	s_waitcnt vmcnt(24)
	v_lshlrev_b32_e32 v30, 16, v120
	v_add_f32_e32 v35, v26, v27
	v_lshlrev_b32_e32 v26, 16, v124
	v_and_b32_e32 v27, 0xffff0000, v124
	v_and_b32_e32 v31, 0xffff0000, v120
	v_pk_add_f32 v[102:103], v[26:27], v[30:31]
	v_lshlrev_b32_e32 v26, 16, v125
	v_and_b32_e32 v27, 0xffff0000, v125
	v_lshlrev_b32_e32 v30, 16, v121
	v_and_b32_e32 v31, 0xffff0000, v121
	v_pk_add_f32 v[106:107], v[26:27], v[30:31]
	v_mov_b32_e32 v30, v103
	v_mov_b32_e32 v31, v107
	v_mov_b32_e32 v26, v102
	v_mov_b32_e32 v27, v106
	v_pk_mul_f32 v[30:31], v[30:31], v[30:31]
	v_add_u32_e32 v153, 1, v151
	v_pk_fma_f32 v[26:27], v[26:27], v[26:27], v[30:31]
	s_waitcnt vmcnt(21)
	v_lshlrev_b32_e32 v30, 16, v116
	v_add_f32_e32 v38, v26, v27
	v_lshlrev_b32_e32 v26, 16, v112
	v_and_b32_e32 v27, 0xffff0000, v112
	v_and_b32_e32 v31, 0xffff0000, v116
	v_pk_add_f32 v[90:91], v[26:27], v[30:31]
	v_lshlrev_b32_e32 v26, 16, v113
	v_and_b32_e32 v27, 0xffff0000, v113
	v_lshlrev_b32_e32 v30, 16, v117
	v_and_b32_e32 v31, 0xffff0000, v117
	v_pk_add_f32 v[94:95], v[26:27], v[30:31]
	v_mov_b32_e32 v30, v91
	v_mov_b32_e32 v31, v95
	v_mov_b32_e32 v26, v90
	v_mov_b32_e32 v27, v94
	v_pk_mul_f32 v[30:31], v[30:31], v[30:31]
	s_nop 0
	v_pk_fma_f32 v[26:27], v[26:27], v[26:27], v[30:31]
	s_waitcnt vmcnt(18)
	v_lshlrev_b32_e32 v30, 16, v104
	v_add_f32_e32 v39, v26, v27
	v_lshlrev_b32_e32 v26, 16, v108
	v_and_b32_e32 v27, 0xffff0000, v108
	v_and_b32_e32 v31, 0xffff0000, v104
	v_pk_add_f32 v[82:83], v[26:27], v[30:31]
	v_lshlrev_b32_e32 v26, 16, v109
	v_and_b32_e32 v27, 0xffff0000, v109
	v_lshlrev_b32_e32 v30, 16, v105
	v_and_b32_e32 v31, 0xffff0000, v105
	v_pk_add_f32 v[84:85], v[26:27], v[30:31]
	v_mov_b32_e32 v30, v83
	v_mov_b32_e32 v31, v85
	v_mov_b32_e32 v26, v82
	v_mov_b32_e32 v27, v84
	v_pk_mul_f32 v[30:31], v[30:31], v[30:31]
	s_nop 0
	v_pk_fma_f32 v[26:27], v[26:27], v[26:27], v[30:31]
	s_waitcnt vmcnt(15)
	v_lshlrev_b32_e32 v30, 16, v96
	v_add_f32_e32 v58, v26, v27
	v_lshlrev_b32_e32 v26, 16, v100
	v_and_b32_e32 v27, 0xffff0000, v100
	v_and_b32_e32 v31, 0xffff0000, v96
	v_pk_add_f32 v[74:75], v[26:27], v[30:31]
	v_lshlrev_b32_e32 v26, 16, v101
	v_and_b32_e32 v27, 0xffff0000, v101
	v_lshlrev_b32_e32 v30, 16, v97
	v_and_b32_e32 v31, 0xffff0000, v97
	v_pk_add_f32 v[76:77], v[26:27], v[30:31]
	v_mov_b32_e32 v30, v75
	v_mov_b32_e32 v31, v77
	v_mov_b32_e32 v26, v74
	v_mov_b32_e32 v27, v76
	v_pk_mul_f32 v[30:31], v[30:31], v[30:31]
	s_nop 0
	v_pk_fma_f32 v[26:27], v[26:27], v[26:27], v[30:31]
	s_waitcnt vmcnt(12)
	v_lshlrev_b32_e32 v30, 16, v66
	v_add_f32_e32 v59, v26, v27
	v_lshlrev_b32_e32 v26, 16, v92
	v_and_b32_e32 v27, 0xffff0000, v92
	v_and_b32_e32 v31, 0xffff0000, v66
	v_pk_add_f32 v[64:65], v[26:27], v[30:31]
	v_lshlrev_b32_e32 v26, 16, v93
	v_and_b32_e32 v27, 0xffff0000, v93
	v_lshlrev_b32_e32 v30, 16, v67
	v_and_b32_e32 v31, 0xffff0000, v67
	v_pk_add_f32 v[66:67], v[26:27], v[30:31]
	v_mov_b32_e32 v30, v65
	v_mov_b32_e32 v31, v67
	v_mov_b32_e32 v26, v64
	v_mov_b32_e32 v27, v66
	v_pk_mul_f32 v[30:31], v[30:31], v[30:31]
	s_nop 0
	v_pk_fma_f32 v[26:27], v[26:27], v[26:27], v[30:31]
	s_waitcnt vmcnt(9)
; template <int CTRL> __device__ __forceinline__ float dpp_mov(float v) { return __builtin_bit_cast(float, __builtin_amdgcn_update_dpp(0, __builtin_bit_cast(int, v), CTRL, 0xF, 0xF, true)); }
; __device__ __forceinline__ float wave_sum(float v) {
;     v += dpp_mov<0xB1>(v);
;     v += dpp_mov<0x4E>(v);
;     v += dpp_mov<0x141>(v);
;     v += dpp_mov<0x140>(v);
;     const int iv = __builtin_bit_cast(int, v);
;     const float a = __builtin_bit_cast(float, __builtin_amdgcn_readlane(iv, 0)), b = __builtin_bit_cast(float, __builtin_amdgcn_readlane(iv, 16));
;     const float c = __builtin_bit_cast(float, __builtin_amdgcn_readlane(iv, 32)), d = __builtin_bit_cast(float, __builtin_amdgcn_readlane(iv, 48));
;     return (a + b) + (c + d);
; }
	v_lshlrev_b32_e32 v30, 16, v60
	v_add_f32_e32 v92, v26, v27
	v_lshlrev_b32_e32 v26, 16, v54
	v_and_b32_e32 v27, 0xffff0000, v54
	v_and_b32_e32 v31, 0xffff0000, v60
	v_pk_add_f32 v[56:57], v[26:27], v[30:31]
	v_lshlrev_b32_e32 v26, 16, v55
	v_and_b32_e32 v27, 0xffff0000, v55
	v_lshlrev_b32_e32 v30, 16, v61
	v_and_b32_e32 v31, 0xffff0000, v61
	v_pk_add_f32 v[54:55], v[26:27], v[30:31]
	v_mov_b32_e32 v30, v57
	v_mov_b32_e32 v31, v55
	v_mov_b32_e32 v26, v56
	v_mov_b32_e32 v27, v54
	v_pk_mul_f32 v[30:31], v[30:31], v[30:31]
	v_lshl_add_u64 v[60:61], v[6:7], 0, v[0:1]
	v_pk_fma_f32 v[26:27], v[26:27], v[26:27], v[30:31]
	v_lshl_add_u64 v[6:7], v[8:9], 0, s[48:49]
	v_add_f32_e32 v30, v26, v27
	v_add_f32_dpp v26, v34, v34 quad_perm:[1,0,3,2] row_mask:0xf bank_mask:0xf bound_ctrl:1
	v_lshl_add_u64 v[148:149], v[6:7], 0, v[0:1]
	s_nop 0
	v_add_f32_dpp v26, v26, v26 quad_perm:[2,3,0,1] row_mask:0xf bank_mask:0xf bound_ctrl:1
	s_nop 1
	v_add_f32_dpp v26, v26, v26 row_half_mirror row_mask:0xf bank_mask:0xf bound_ctrl:1
	s_nop 1
	v_add_f32_dpp v26, v26, v26 row_mirror row_mask:0xf bank_mask:0xf bound_ctrl:1
	s_nop 0
	v_readlane_b32 s12, v26, 16
	v_readlane_b32 s13, v26, 48
	v_readlane_b32 s8, v26, 0
	v_readlane_b32 s9, v26, 32
	v_mov_b32_e32 v26, s12
	v_mov_b32_e32 v27, s13
	v_pk_add_f32 v[26:27], s[8:9], v[26:27]
	s_nop 0
	v_add_f32_e32 v26, v26, v27
	v_fmamk_f32 v26, v26, 0x3b800000, v252
	v_cmp_gt_f32_e64 s[36:37], s55, v26
	v_mul_f32_e32 v27, 0x4f800000, v26
	s_nop 0
	v_cndmask_b32_e64 v215, v26, v27, s[36:37]
	v_add_f32_dpp v26, v35, v35 quad_perm:[1,0,3,2] row_mask:0xf bank_mask:0xf bound_ctrl:1
	v_sqrt_f32_e32 v218, v215
	s_nop 0
	v_add_f32_dpp v26, v26, v26 quad_perm:[2,3,0,1] row_mask:0xf bank_mask:0xf bound_ctrl:1
	v_add_u32_e32 v219, -1, v218
	s_nop 0
	v_add_f32_dpp v26, v26, v26 row_half_mirror row_mask:0xf bank_mask:0xf bound_ctrl:1
	v_add_u32_e32 v217, 1, v218
	s_nop 0
	v_add_f32_dpp v26, v26, v26 row_mirror row_mask:0xf bank_mask:0xf bound_ctrl:1
	s_nop 0
	v_readlane_b32 s12, v26, 16
	v_readlane_b32 s13, v26, 48
	v_readlane_b32 s8, v26, 0
	v_readlane_b32 s9, v26, 32
	v_mov_b32_e32 v26, s12
	v_mov_b32_e32 v27, s13
	v_pk_add_f32 v[26:27], s[8:9], v[26:27]
	s_nop 0
	v_add_f32_e32 v26, v26, v27
	v_fmamk_f32 v26, v26, 0x3b800000, v252
	v_cmp_gt_f32_e64 s[34:35], s55, v26
	v_mul_f32_e32 v27, 0x4f800000, v26
	s_nop 0
	v_cndmask_b32_e64 v206, v26, v27, s[34:35]
	v_add_f32_dpp v26, v38, v38 quad_perm:[1,0,3,2] row_mask:0xf bank_mask:0xf bound_ctrl:1
	v_sqrt_f32_e32 v208, v206
	s_nop 0
	v_add_f32_dpp v26, v26, v26 quad_perm:[2,3,0,1] row_mask:0xf bank_mask:0xf bound_ctrl:1
	v_add_u32_e32 v212, -1, v208
	s_nop 0
	v_add_f32_dpp v26, v26, v26 row_half_mirror row_mask:0xf bank_mask:0xf bound_ctrl:1
	v_add_u32_e32 v210, 1, v208
	s_nop 0
	v_add_f32_dpp v26, v26, v26 row_mirror row_mask:0xf bank_mask:0xf bound_ctrl:1
	s_nop 0
	v_readlane_b32 s12, v26, 16
	v_readlane_b32 s13, v26, 48
	v_readlane_b32 s8, v26, 0
	v_readlane_b32 s9, v26, 32
	v_mov_b32_e32 v26, s12
	v_mov_b32_e32 v27, s13
	v_pk_add_f32 v[26:27], s[8:9], v[26:27]
	s_nop 0
	v_add_f32_e32 v26, v26, v27
	v_fmamk_f32 v26, v26, 0x3b800000, v252
	v_cmp_gt_f32_e64 s[28:29], s55, v26
	v_mul_f32_e32 v27, 0x4f800000, v26
	s_nop 0
	v_cndmask_b32_e64 v200, v26, v27, s[28:29]
	v_add_f32_dpp v26, v39, v39 quad_perm:[1,0,3,2] row_mask:0xf bank_mask:0xf bound_ctrl:1
	v_sqrt_f32_e32 v203, v200
	s_nop 0
	v_add_f32_dpp v26, v26, v26 quad_perm:[2,3,0,1] row_mask:0xf bank_mask:0xf bound_ctrl:1
	v_add_u32_e32 v204, -1, v203
	s_nop 0
	v_add_f32_dpp v26, v26, v26 row_half_mirror row_mask:0xf bank_mask:0xf bound_ctrl:1
	v_add_u32_e32 v201, 1, v203
	s_nop 0
	v_add_f32_dpp v26, v26, v26 row_mirror row_mask:0xf bank_mask:0xf bound_ctrl:1
	s_nop 0
	v_readlane_b32 s12, v26, 16
	v_readlane_b32 s13, v26, 48
	v_readlane_b32 s8, v26, 0
	v_readlane_b32 s9, v26, 32
	v_mov_b32_e32 v26, s12
	v_mov_b32_e32 v27, s13
	v_pk_add_f32 v[26:27], s[8:9], v[26:27]
	s_nop 0
	v_add_f32_e32 v26, v26, v27
	v_fmamk_f32 v26, v26, 0x3b800000, v252
	v_cmp_gt_f32_e64 s[24:25], s55, v26
	v_mul_f32_e32 v27, 0x4f800000, v26
	s_nop 0
	v_cndmask_b32_e64 v190, v26, v27, s[24:25]
	v_add_f32_dpp v26, v58, v58 quad_perm:[1,0,3,2] row_mask:0xf bank_mask:0xf bound_ctrl:1
	v_sqrt_f32_e32 v192, v190
	s_nop 0
	v_add_f32_dpp v26, v26, v26 quad_perm:[2,3,0,1] row_mask:0xf bank_mask:0xf bound_ctrl:1
	v_add_u32_e32 v198, -1, v192
	s_nop 0
	v_add_f32_dpp v26, v26, v26 row_half_mirror row_mask:0xf bank_mask:0xf bound_ctrl:1
	v_add_u32_e32 v195, 1, v192
	s_nop 0
	v_add_f32_dpp v26, v26, v26 row_mirror row_mask:0xf bank_mask:0xf bound_ctrl:1
	s_nop 0
	v_readlane_b32 s12, v26, 16
	v_readlane_b32 s13, v26, 48
	v_readlane_b32 s8, v26, 0
	v_readlane_b32 s9, v26, 32
	v_mov_b32_e32 v26, s12
	v_mov_b32_e32 v27, s13
	v_pk_add_f32 v[26:27], s[8:9], v[26:27]
	s_nop 0
	v_add_f32_e32 v26, v26, v27
	v_fmamk_f32 v26, v26, 0x3b800000, v252
	v_cmp_gt_f32_e64 s[20:21], s55, v26
	v_mul_f32_e32 v27, 0x4f800000, v26
	s_nop 0
	v_cndmask_b32_e64 v184, v26, v27, s[20:21]
	v_add_f32_dpp v26, v59, v59 quad_perm:[1,0,3,2] row_mask:0xf bank_mask:0xf bound_ctrl:1
	v_sqrt_f32_e32 v187, v184
	s_nop 0
	v_add_f32_dpp v26, v26, v26 quad_perm:[2,3,0,1] row_mask:0xf bank_mask:0xf bound_ctrl:1
	v_add_u32_e32 v188, -1, v187
	s_nop 0
	v_add_f32_dpp v26, v26, v26 row_half_mirror row_mask:0xf bank_mask:0xf bound_ctrl:1
	v_add_u32_e32 v185, 1, v187
	s_nop 0
	v_add_f32_dpp v26, v26, v26 row_mirror row_mask:0xf bank_mask:0xf bound_ctrl:1
	s_nop 0
	v_readlane_b32 s12, v26, 16
	v_readlane_b32 s13, v26, 48
	v_readlane_b32 s8, v26, 0
	v_readlane_b32 s9, v26, 32
	v_mov_b32_e32 v26, s12
	v_mov_b32_e32 v27, s13
; template <bool HG>
; __device__ __forceinline__ void readout_phase2(const Args& a, Frame& F, const float* gain, int nrows) {
;     ...
;     RO_LOAD(f2, b2, g2, cx ? ML + nw : nw + 7 * 2048);
	v_pk_add_f32 v[26:27], s[8:9], v[26:27]
	s_nop 0
	v_add_f32_e32 v26, v26, v27
	v_fmamk_f32 v26, v26, 0x3b800000, v252
	v_cmp_gt_f32_e64 s[16:17], s55, v26
	v_mul_f32_e32 v27, 0x4f800000, v26
	s_nop 0
	v_cndmask_b32_e64 v168, v26, v27, s[16:17]
	v_add_f32_dpp v26, v92, v92 quad_perm:[1,0,3,2] row_mask:0xf bank_mask:0xf bound_ctrl:1
	v_sqrt_f32_e32 v170, v168
	s_nop 0
	v_add_f32_dpp v26, v26, v26 quad_perm:[2,3,0,1] row_mask:0xf bank_mask:0xf bound_ctrl:1
	v_add_u32_e32 v176, -1, v170
	s_nop 0
	v_add_f32_dpp v26, v26, v26 row_half_mirror row_mask:0xf bank_mask:0xf bound_ctrl:1
	v_add_u32_e32 v173, 1, v170
	s_nop 0
	v_add_f32_dpp v26, v26, v26 row_mirror row_mask:0xf bank_mask:0xf bound_ctrl:1
	s_nop 0
	v_readlane_b32 s12, v26, 16
	v_readlane_b32 s13, v26, 48
	v_readlane_b32 s8, v26, 0
	v_readlane_b32 s9, v26, 32
	v_mov_b32_e32 v26, s12
	v_mov_b32_e32 v27, s13
	v_pk_add_f32 v[26:27], s[8:9], v[26:27]
	s_nop 0
	v_add_f32_e32 v26, v26, v27
	v_fmamk_f32 v26, v26, 0x3b800000, v252
	v_cmp_gt_f32_e64 s[12:13], s55, v26
	v_mul_f32_e32 v27, 0x4f800000, v26
	s_nop 0
	v_cndmask_b32_e64 v162, v26, v27, s[12:13]
	v_add_f32_dpp v26, v30, v30 quad_perm:[1,0,3,2] row_mask:0xf bank_mask:0xf bound_ctrl:1
	v_sqrt_f32_e32 v165, v162
	s_nop 0
	v_add_f32_dpp v26, v26, v26 quad_perm:[2,3,0,1] row_mask:0xf bank_mask:0xf bound_ctrl:1
	v_add_u32_e32 v166, -1, v165
	s_nop 0
	v_add_f32_dpp v26, v26, v26 row_half_mirror row_mask:0xf bank_mask:0xf bound_ctrl:1
	v_add_u32_e32 v163, 1, v165
	s_nop 0
	v_add_f32_dpp v26, v26, v26 row_mirror row_mask:0xf bank_mask:0xf bound_ctrl:1
	s_nop 0
	v_readlane_b32 s33, v26, 16
	v_readlane_b32 s44, v26, 48
	v_readlane_b32 s8, v26, 0
	v_readlane_b32 s9, v26, 32
	v_mov_b32_e32 v26, s33
	v_mov_b32_e32 v27, s44
	v_pk_add_f32 v[26:27], s[8:9], v[26:27]
	s_nop 0
	v_add_f32_e32 v26, v26, v27
	v_fmamk_f32 v26, v26, 0x3b800000, v252
	v_cmp_gt_f32_e64 s[8:9], s55, v26
	v_mul_f32_e32 v27, 0x4f800000, v26
	s_nop 0
	v_cndmask_b32_e64 v152, v26, v27, s[8:9]
	global_load_dwordx2 v[146:147], v[4:5], off nt
	global_load_dwordx2 v[144:145], v[60:61], off nt
	global_load_dwordx2 v[58:59], v[148:149], off nt
	global_load_dwordx2 v[132:133], v[4:5], off offset:512 nt
	global_load_dwordx2 v[128:129], v[60:61], off offset:512 nt
	global_load_dwordx2 v[38:39], v[148:149], off offset:512 nt
	global_load_dwordx2 v[124:125], v[4:5], off offset:1024 nt
	global_load_dwordx2 v[120:121], v[60:61], off offset:1024 nt
	global_load_dwordx2 v[34:35], v[148:149], off offset:1024 nt
	global_load_dwordx2 v[116:117], v[4:5], off offset:1536 nt
	global_load_dwordx2 v[112:113], v[60:61], off offset:1536 nt
	global_load_dwordx2 v[30:31], v[148:149], off offset:1536 nt
	global_load_dwordx2 v[110:111], v[4:5], off offset:2048 nt
	global_load_dwordx2 v[108:109], v[60:61], off offset:2048 nt
	global_load_dwordx2 v[26:27], v[148:149], off offset:2048 nt
	global_load_dwordx2 v[104:105], v[4:5], off offset:2560 nt
	global_load_dwordx2 v[100:101], v[60:61], off offset:2560 nt
	global_load_dwordx2 v[8:9], v[148:149], off offset:2560 nt
	global_load_dwordx2 v[98:99], v[4:5], off offset:3072 nt
	global_load_dwordx2 v[96:97], v[60:61], off offset:3072 nt
	global_load_dwordx2 v[6:7], v[148:149], off offset:3072 nt
	global_load_dwordx2 v[92:93], v[4:5], off offset:3584 nt
	s_nop 0
	global_load_dwordx2 v[60:61], v[60:61], off offset:3584 nt
	s_nop 0
	global_load_dwordx2 v[4:5], v[148:149], off offset:3584 nt
	v_lshl_add_u64 v[148:149], v[2:3], 0, s[40:41]
	v_cmp_ge_f32_e64 s[40:41], 0, v178
	v_lshl_add_u64 v[148:149], v[148:149], 0, v[0:1]
	v_sqrt_f32_e32 v154, v152
	v_cndmask_b32_e64 v178, v214, v216, s[40:41]
	v_cmp_lt_f32_e64 s[40:41], 0, v179
	v_add_u32_e32 v160, -1, v154
	s_nop 0
	v_cndmask_b32_e64 v178, v178, v213, s[40:41]
	v_mul_f32_e32 v179, 0x37800000, v178
	v_cndmask_b32_e32 v178, v178, v179, vcc
	v_cmp_class_f32_e32 vcc, v211, v253
	v_add_u32_e32 v157, 1, v154
	s_nop 0
	v_cndmask_b32_e32 v178, v178, v211, vcc
	v_div_scale_f32 v179, s[40:41], v178, v178, 1.0
	v_rcp_f32_e32 v180, v179
	s_nop 0
	v_fma_f32 v181, -v179, v180, 1.0
	v_fmac_f32_e32 v180, v181, v180
	v_div_scale_f32 v181, vcc, 1.0, v178, 1.0
	v_mul_f32_e32 v211, v181, v180
	v_fma_f32 v213, -v179, v211, v181
	v_fmac_f32_e32 v211, v213, v180
	v_fma_f32 v179, -v179, v211, v181
	v_div_fmas_f32 v179, v179, v180, v211
	v_div_fixup_f32 v178, v179, v178, 1.0
	v_lshlrev_b32_e32 v180, 16, v24
	v_and_b32_e32 v181, 0xffff0000, v24
	v_lshlrev_b32_e32 v24, 16, v25
	v_and_b32_e32 v25, 0xffff0000, v25
	v_pk_mul_f32 v[140:141], v[140:141], v[178:179] op_sel_hi:[1,0]
	v_pk_mul_f32 v[142:143], v[142:143], v[178:179] op_sel_hi:[1,0]
	v_pk_mul_f32 v[140:141], v[140:141], v[180:181]
	v_pk_mul_f32 v[24:25], v[142:143], v[24:25]
	v_cvt_pk_bf16_f32 v140, v140, v141
	v_cvt_pk_bf16_f32 v141, v24, v25
	v_fma_f32 v24, -v209, v205, v202
	v_cmp_ge_f32_e32 vcc, 0, v24
	v_fma_f32 v25, -v207, v205, v202
	global_store_dwordx2 v[148:149], v[140:141], off nt
	v_cndmask_b32_e32 v24, v205, v209, vcc
	v_cmp_lt_f32_e32 vcc, 0, v25
	s_nop 1
	v_cndmask_b32_e32 v24, v24, v207, vcc
	v_mul_f32_e32 v25, 0x37800000, v24
	v_cndmask_b32_e64 v24, v24, v25, s[30:31]
	v_cmp_class_f32_e32 vcc, v202, v253
	s_nop 1
	v_cndmask_b32_e32 v24, v24, v202, vcc
	v_div_scale_f32 v25, s[30:31], v24, v24, 1.0
	v_rcp_f32_e32 v140, v25
	s_nop 0
	v_fma_f32 v141, -v25, v140, 1.0
	v_fmac_f32_e32 v140, v141, v140
	v_div_scale_f32 v141, vcc, 1.0, v24, 1.0
	v_mul_f32_e32 v142, v141, v140
	v_fma_f32 v143, -v25, v142, v141
	v_fmac_f32_e32 v142, v143, v140
	v_fma_f32 v25, -v25, v142, v141
	v_div_fmas_f32 v25, v25, v140, v142
	v_div_fixup_f32 v24, v25, v24, 1.0
	v_lshlrev_b32_e32 v140, 16, v22
	v_and_b32_e32 v141, 0xffff0000, v22
	v_lshlrev_b32_e32 v22, 16, v23
	v_and_b32_e32 v23, 0xffff0000, v23
	v_pk_mul_f32 v[134:135], v[134:135], v[24:25] op_sel_hi:[1,0]
	v_pk_mul_f32 v[24:25], v[136:137], v[24:25] op_sel_hi:[1,0]
	s_nop 0
	v_pk_mul_f32 v[22:23], v[24:25], v[22:23]
	v_pk_mul_f32 v[24:25], v[134:135], v[140:141]
	s_nop 0
	v_cvt_pk_bf16_f32 v24, v24, v25
	v_cvt_pk_bf16_f32 v25, v22, v23
	v_fma_f32 v22, -v199, v197, v194
	v_cmp_ge_f32_e32 vcc, 0, v22
	v_fma_f32 v23, -v196, v197, v194
	global_store_dwordx2 v[148:149], v[24:25], off offset:512 nt
	v_cndmask_b32_e32 v22, v197, v199, vcc
	v_cmp_lt_f32_e32 vcc, 0, v23
	s_nop 1
	v_cndmask_b32_e32 v22, v22, v196, vcc
	v_mul_f32_e32 v23, 0x37800000, v22
	v_cndmask_b32_e64 v22, v22, v23, s[26:27]
	v_cmp_class_f32_e32 vcc, v194, v253
	s_nop 1
	v_cndmask_b32_e32 v22, v22, v194, vcc
	v_div_scale_f32 v23, s[26:27], v22, v22, 1.0
	v_rcp_f32_e32 v24, v23
	s_nop 0
	v_fma_f32 v25, -v23, v24, 1.0
	v_fmac_f32_e32 v24, v25, v24
	v_div_scale_f32 v25, vcc, 1.0, v22, 1.0
	v_mul_f32_e32 v134, v25, v24
	v_fma_f32 v135, -v23, v134, v25
	v_fmac_f32_e32 v134, v135, v24
	v_fma_f32 v23, -v23, v134, v25
	v_div_fmas_f32 v23, v23, v24, v134
	v_div_fixup_f32 v22, v23, v22, 1.0
	v_lshlrev_b32_e32 v24, 16, v20
	v_and_b32_e32 v25, 0xffff0000, v20
	v_lshlrev_b32_e32 v20, 16, v21
	v_and_b32_e32 v21, 0xffff0000, v21
	v_pk_mul_f32 v[130:131], v[130:131], v[22:23] op_sel_hi:[1,0]
	v_pk_mul_f32 v[22:23], v[122:123], v[22:23] op_sel_hi:[1,0]
	s_nop 0
	v_pk_mul_f32 v[20:21], v[22:23], v[20:21]
	v_pk_mul_f32 v[22:23], v[130:131], v[24:25]
	s_nop 0
	v_cvt_pk_bf16_f32 v22, v22, v23
	v_cvt_pk_bf16_f32 v23, v20, v21
	v_fma_f32 v20, -v193, v189, v186
	v_cmp_ge_f32_e32 vcc, 0, v20
	v_fma_f32 v21, -v191, v189, v186
	global_store_dwordx2 v[148:149], v[22:23], off offset:1024 nt
	v_cndmask_b32_e32 v20, v189, v193, vcc
	v_cmp_lt_f32_e32 vcc, 0, v21
	s_nop 1
	v_cndmask_b32_e32 v20, v20, v191, vcc
	v_mul_f32_e32 v21, 0x37800000, v20
	v_cndmask_b32_e64 v20, v20, v21, s[22:23]
	v_cmp_class_f32_e32 vcc, v186, v253
	s_nop 1
	v_cndmask_b32_e32 v20, v20, v186, vcc
	v_div_scale_f32 v21, s[22:23], v20, v20, 1.0
	v_rcp_f32_e32 v22, v21
	s_nop 0
	v_fma_f32 v23, -v21, v22, 1.0
	v_fmac_f32_e32 v22, v23, v22
	v_div_scale_f32 v23, vcc, 1.0, v20, 1.0
	v_mul_f32_e32 v24, v23, v22
	v_fma_f32 v25, -v21, v24, v23
	v_fmac_f32_e32 v24, v25, v22
	v_fma_f32 v21, -v21, v24, v23
	v_div_fmas_f32 v21, v21, v22, v24
	v_div_fixup_f32 v20, v21, v20, 1.0
	v_lshlrev_b32_e32 v22, 16, v18
	v_and_b32_e32 v23, 0xffff0000, v18
	v_lshlrev_b32_e32 v18, 16, v19
	v_and_b32_e32 v19, 0xffff0000, v19
	v_pk_mul_f32 v[24:25], v[86:87], v[20:21] op_sel_hi:[1,0]
	v_pk_mul_f32 v[20:21], v[88:89], v[20:21] op_sel_hi:[1,0]
	s_nop 0
	v_pk_mul_f32 v[18:19], v[20:21], v[18:19]
	v_pk_mul_f32 v[20:21], v[24:25], v[22:23]
	s_nop 0
	v_cvt_pk_bf16_f32 v20, v20, v21
	v_cvt_pk_bf16_f32 v21, v18, v19
	v_fma_f32 v18, -v177, v175, v172
	v_cmp_ge_f32_e32 vcc, 0, v18
	v_fma_f32 v19, -v174, v175, v172
	global_store_dwordx2 v[148:149], v[20:21], off offset:1536 nt
	v_cndmask_b32_e32 v18, v175, v177, vcc
	v_cmp_lt_f32_e32 vcc, 0, v19
	s_nop 1
	v_cndmask_b32_e32 v18, v18, v174, vcc
	v_mul_f32_e32 v19, 0x37800000, v18
	v_cndmask_b32_e64 v18, v18, v19, s[18:19]
	v_cmp_class_f32_e32 vcc, v172, v253
	s_nop 1
	v_cndmask_b32_e32 v18, v18, v172, vcc
	v_div_scale_f32 v19, s[18:19], v18, v18, 1.0
	v_rcp_f32_e32 v20, v19
	s_nop 0
	v_fma_f32 v21, -v19, v20, 1.0
	v_fmac_f32_e32 v20, v21, v20
	v_div_scale_f32 v21, vcc, 1.0, v18, 1.0
	v_mul_f32_e32 v22, v21, v20
	v_fma_f32 v23, -v19, v22, v21
	v_fmac_f32_e32 v22, v23, v20
	v_fma_f32 v19, -v19, v22, v21
	v_div_fmas_f32 v19, v19, v20, v22
	v_div_fixup_f32 v18, v19, v18, 1.0
	v_lshlrev_b32_e32 v20, 16, v16
	v_and_b32_e32 v21, 0xffff0000, v16
	v_lshlrev_b32_e32 v16, 16, v17
	v_and_b32_e32 v17, 0xffff0000, v17
	v_pk_mul_f32 v[22:23], v[78:79], v[18:19] op_sel_hi:[1,0]
	v_pk_mul_f32 v[18:19], v[80:81], v[18:19] op_sel_hi:[1,0]
	s_nop 0
	v_pk_mul_f32 v[16:17], v[18:19], v[16:17]
	v_pk_mul_f32 v[18:19], v[22:23], v[20:21]
	s_nop 0
	v_cvt_pk_bf16_f32 v18, v18, v19
	v_cvt_pk_bf16_f32 v19, v16, v17
	v_fma_f32 v16, -v171, v167, v164
	v_cmp_ge_f32_e32 vcc, 0, v16
	v_fma_f32 v17, -v169, v167, v164
	global_store_dwordx2 v[148:149], v[18:19], off offset:2048 nt
	v_cndmask_b32_e32 v16, v167, v171, vcc
	v_cmp_lt_f32_e32 vcc, 0, v17
	s_nop 1
	v_cndmask_b32_e32 v16, v16, v169, vcc
	v_mul_f32_e32 v17, 0x37800000, v16
	v_cndmask_b32_e64 v16, v16, v17, s[14:15]
	v_cmp_class_f32_e32 vcc, v164, v253
	s_nop 1
	v_cndmask_b32_e32 v16, v16, v164, vcc
	v_div_scale_f32 v17, s[14:15], v16, v16, 1.0
	v_rcp_f32_e32 v18, v17
	s_nop 0
	v_fma_f32 v19, -v17, v18, 1.0
	v_fmac_f32_e32 v18, v19, v18
	v_div_scale_f32 v19, vcc, 1.0, v16, 1.0
	v_mul_f32_e32 v20, v19, v18
	v_fma_f32 v21, -v17, v20, v19
	v_fmac_f32_e32 v20, v21, v18
	v_fma_f32 v17, -v17, v20, v19
	v_div_fmas_f32 v17, v17, v18, v20
	v_div_fixup_f32 v16, v17, v16, 1.0
	v_lshlrev_b32_e32 v18, 16, v14
	v_and_b32_e32 v19, 0xffff0000, v14
	v_lshlrev_b32_e32 v14, 16, v15
	v_and_b32_e32 v15, 0xffff0000, v15
	v_pk_mul_f32 v[20:21], v[70:71], v[16:17] op_sel_hi:[1,0]
	v_pk_mul_f32 v[16:17], v[72:73], v[16:17] op_sel_hi:[1,0]
	s_nop 0
	v_pk_mul_f32 v[14:15], v[16:17], v[14:15]
	v_pk_mul_f32 v[16:17], v[20:21], v[18:19]
	s_nop 0
	v_cvt_pk_bf16_f32 v16, v16, v17
	v_cvt_pk_bf16_f32 v17, v14, v15
	v_fma_f32 v14, -v161, v159, v156
	v_cmp_ge_f32_e32 vcc, 0, v14
	v_fma_f32 v15, -v158, v159, v156
	global_store_dwordx2 v[148:149], v[16:17], off offset:2560 nt
	v_cndmask_b32_e32 v14, v159, v161, vcc
	v_cmp_lt_f32_e32 vcc, 0, v15
	s_nop 1
	v_cndmask_b32_e32 v14, v14, v158, vcc
; template <bool HG>
; __device__ __forceinline__ void readout_phase2(const Args& a, Frame& F, const float* gain, int nrows) {
;     ...
;     RO_FINISH(f1, b1, g1, nw + 7 * 2048);
	v_mul_f32_e32 v15, 0x37800000, v14
	v_cndmask_b32_e64 v14, v14, v15, s[10:11]
	v_cmp_class_f32_e32 vcc, v156, v253
	s_nop 1
	v_cndmask_b32_e32 v14, v14, v156, vcc
	v_div_scale_f32 v15, s[10:11], v14, v14, 1.0
	v_rcp_f32_e32 v16, v15
	s_nop 0
	v_fma_f32 v17, -v15, v16, 1.0
	v_fmac_f32_e32 v16, v17, v16
	v_div_scale_f32 v17, vcc, 1.0, v14, 1.0
	v_mul_f32_e32 v18, v17, v16
	v_fma_f32 v19, -v15, v18, v17
	v_fmac_f32_e32 v18, v19, v16
	v_fma_f32 v15, -v15, v18, v17
	v_div_fmas_f32 v15, v15, v16, v18
	v_div_fixup_f32 v14, v15, v14, 1.0
	v_lshlrev_b32_e32 v16, 16, v12
	v_and_b32_e32 v17, 0xffff0000, v12
	v_lshlrev_b32_e32 v12, 16, v13
	v_and_b32_e32 v13, 0xffff0000, v13
	v_pk_mul_f32 v[18:19], v[62:63], v[14:15] op_sel_hi:[1,0]
	v_pk_mul_f32 v[14:15], v[68:69], v[14:15] op_sel_hi:[1,0]
	s_nop 0
	v_pk_mul_f32 v[12:13], v[14:15], v[12:13]
	v_pk_mul_f32 v[14:15], v[18:19], v[16:17]
	s_nop 0
	v_cvt_pk_bf16_f32 v14, v14, v15
	v_cvt_pk_bf16_f32 v15, v12, v13
	v_fma_f32 v12, -v155, v151, v150
	v_cmp_ge_f32_e32 vcc, 0, v12
	v_fma_f32 v13, -v153, v151, v150
	global_store_dwordx2 v[148:149], v[14:15], off offset:3072 nt
	v_cndmask_b32_e32 v12, v151, v155, vcc
	v_cmp_lt_f32_e32 vcc, 0, v13
	s_nop 1
	v_cndmask_b32_e32 v12, v12, v153, vcc
	v_mul_f32_e32 v13, 0x37800000, v12
	v_cndmask_b32_e64 v12, v12, v13, s[6:7]
	v_cmp_class_f32_e32 vcc, v150, v253
	s_nop 1
	v_cndmask_b32_e32 v12, v12, v150, vcc
	v_div_scale_f32 v13, s[6:7], v12, v12, 1.0
	v_rcp_f32_e32 v14, v13
	s_nop 0
	v_fma_f32 v15, -v13, v14, 1.0
	v_fmac_f32_e32 v14, v15, v14
	v_div_scale_f32 v15, vcc, 1.0, v12, 1.0
	v_mul_f32_e32 v16, v15, v14
	v_fma_f32 v17, -v13, v16, v15
	v_fmac_f32_e32 v16, v17, v14
	v_fma_f32 v13, -v13, v16, v15
	v_div_fmas_f32 v13, v13, v14, v16
	v_div_fixup_f32 v12, v13, v12, 1.0
	v_lshlrev_b32_e32 v14, 16, v10
	v_and_b32_e32 v15, 0xffff0000, v10
	v_lshlrev_b32_e32 v10, 16, v11
	v_and_b32_e32 v11, 0xffff0000, v11
	v_pk_mul_f32 v[16:17], v[44:45], v[12:13] op_sel_hi:[1,0]
	v_pk_mul_f32 v[12:13], v[50:51], v[12:13] op_sel_hi:[1,0]
	s_nop 0
	v_pk_mul_f32 v[10:11], v[12:13], v[10:11]
	v_pk_mul_f32 v[12:13], v[16:17], v[14:15]
	s_nop 0
	v_cvt_pk_bf16_f32 v12, v12, v13
	v_cvt_pk_bf16_f32 v13, v10, v11
	global_store_dwordx2 v[148:149], v[12:13], off offset:3584 nt
	v_fma_f32 v12, -v219, v218, v215
	v_cmp_ge_f32_e32 vcc, 0, v12
	v_fma_f32 v13, -v217, v218, v215
	v_lshl_add_u64 v[10:11], v[2:3], 0, s[78:79]
	v_cndmask_b32_e32 v12, v218, v219, vcc
	v_cmp_lt_f32_e32 vcc, 0, v13
	v_lshl_add_u64 v[10:11], v[10:11], 0, v[0:1]
	s_nop 0
	v_cndmask_b32_e32 v12, v12, v217, vcc
	v_mul_f32_e32 v13, 0x37800000, v12
	v_cndmask_b32_e64 v12, v12, v13, s[36:37]
	v_cmp_class_f32_e32 vcc, v215, v253
	s_nop 1
	v_cndmask_b32_e32 v12, v12, v215, vcc
	v_div_scale_f32 v13, s[6:7], v12, v12, 1.0
	v_rcp_f32_e32 v14, v13
	s_nop 0
	v_fma_f32 v15, -v13, v14, 1.0
	v_fmac_f32_e32 v14, v15, v14
	v_div_scale_f32 v15, vcc, 1.0, v12, 1.0
	v_mul_f32_e32 v16, v15, v14
	v_fma_f32 v17, -v13, v16, v15
	v_fmac_f32_e32 v16, v17, v14
	v_fma_f32 v13, -v13, v16, v15
	v_div_fmas_f32 v13, v13, v14, v16
	v_div_fixup_f32 v12, v13, v12, 1.0
	v_lshlrev_b32_e32 v14, 16, v52
	v_and_b32_e32 v15, 0xffff0000, v52
	v_lshlrev_b32_e32 v16, 16, v53
	v_and_b32_e32 v17, 0xffff0000, v53
	v_pk_mul_f32 v[18:19], v[126:127], v[12:13] op_sel_hi:[1,0]
	v_pk_mul_f32 v[12:13], v[138:139], v[12:13] op_sel_hi:[1,0]
	v_pk_mul_f32 v[14:15], v[18:19], v[14:15]
	v_pk_mul_f32 v[12:13], v[12:13], v[16:17]
	v_cvt_pk_bf16_f32 v14, v14, v15
	v_cvt_pk_bf16_f32 v15, v12, v13
	v_fma_f32 v12, -v212, v208, v206
	v_cmp_ge_f32_e32 vcc, 0, v12
	v_fma_f32 v13, -v210, v208, v206
	global_store_dwordx2 v[10:11], v[14:15], off nt
	v_cndmask_b32_e32 v12, v208, v212, vcc
	v_cmp_lt_f32_e32 vcc, 0, v13
	s_nop 1
	v_cndmask_b32_e32 v12, v12, v210, vcc
	v_mul_f32_e32 v13, 0x37800000, v12
	v_cndmask_b32_e64 v12, v12, v13, s[34:35]
	v_cmp_class_f32_e32 vcc, v206, v253
	s_nop 1
	v_cndmask_b32_e32 v12, v12, v206, vcc
	v_div_scale_f32 v13, s[6:7], v12, v12, 1.0
	v_rcp_f32_e32 v14, v13
	s_nop 0
	v_fma_f32 v15, -v13, v14, 1.0
	v_fmac_f32_e32 v14, v15, v14
	v_div_scale_f32 v15, vcc, 1.0, v12, 1.0
	v_mul_f32_e32 v16, v15, v14
	v_fma_f32 v17, -v13, v16, v15
	v_fmac_f32_e32 v16, v17, v14
	v_fma_f32 v13, -v13, v16, v15
	v_div_fmas_f32 v13, v13, v14, v16
	v_div_fixup_f32 v12, v13, v12, 1.0
	v_lshlrev_b32_e32 v14, 16, v48
	v_and_b32_e32 v15, 0xffff0000, v48
	v_lshlrev_b32_e32 v16, 16, v49
	v_and_b32_e32 v17, 0xffff0000, v49
	v_pk_mul_f32 v[18:19], v[114:115], v[12:13] op_sel_hi:[1,0]
	v_pk_mul_f32 v[12:13], v[118:119], v[12:13] op_sel_hi:[1,0]
	v_pk_mul_f32 v[14:15], v[18:19], v[14:15]
	v_pk_mul_f32 v[12:13], v[12:13], v[16:17]
	v_cvt_pk_bf16_f32 v14, v14, v15
	v_cvt_pk_bf16_f32 v15, v12, v13
	v_fma_f32 v12, -v204, v203, v200
	v_cmp_ge_f32_e32 vcc, 0, v12
	v_fma_f32 v13, -v201, v203, v200
	global_store_dwordx2 v[10:11], v[14:15], off offset:512 nt
	v_cndmask_b32_e32 v12, v203, v204, vcc
	v_cmp_lt_f32_e32 vcc, 0, v13
	s_nop 1
	v_cndmask_b32_e32 v12, v12, v201, vcc
	v_mul_f32_e32 v13, 0x37800000, v12
	v_cndmask_b32_e64 v12, v12, v13, s[28:29]
	v_cmp_class_f32_e32 vcc, v200, v253
	s_nop 1
	v_cndmask_b32_e32 v12, v12, v200, vcc
	v_div_scale_f32 v13, s[6:7], v12, v12, 1.0
	v_rcp_f32_e32 v14, v13
	s_nop 0
	v_fma_f32 v15, -v13, v14, 1.0
	v_fmac_f32_e32 v14, v15, v14
	v_div_scale_f32 v15, vcc, 1.0, v12, 1.0
	v_mul_f32_e32 v16, v15, v14
	v_fma_f32 v17, -v13, v16, v15
	v_fmac_f32_e32 v16, v17, v14
	v_fma_f32 v13, -v13, v16, v15
	v_div_fmas_f32 v13, v13, v14, v16
	v_div_fixup_f32 v12, v13, v12, 1.0
	v_lshlrev_b32_e32 v14, 16, v46
	v_and_b32_e32 v15, 0xffff0000, v46
	v_lshlrev_b32_e32 v16, 16, v47
; template <bool HG>
; __device__ __forceinline__ void readout_phase2(const Args& a, Frame& F, const float* gain, int nrows) {
;     ...
;     RO_FINISH(f1, b1, g1, nw + 7 * 2048);
;     if (cx) RO_FINISH(f2, b2, g2, ML + nw);
	v_and_b32_e32 v17, 0xffff0000, v47
	v_pk_mul_f32 v[18:19], v[102:103], v[12:13] op_sel_hi:[1,0]
	v_pk_mul_f32 v[12:13], v[106:107], v[12:13] op_sel_hi:[1,0]
	v_pk_mul_f32 v[14:15], v[18:19], v[14:15]
	v_pk_mul_f32 v[12:13], v[12:13], v[16:17]
	v_cvt_pk_bf16_f32 v14, v14, v15
	v_cvt_pk_bf16_f32 v15, v12, v13
	v_fma_f32 v12, -v198, v192, v190
	v_cmp_ge_f32_e32 vcc, 0, v12
	v_fma_f32 v13, -v195, v192, v190
	global_store_dwordx2 v[10:11], v[14:15], off offset:1024 nt
	v_cndmask_b32_e32 v12, v192, v198, vcc
	v_cmp_lt_f32_e32 vcc, 0, v13
	s_nop 1
	v_cndmask_b32_e32 v12, v12, v195, vcc
	v_mul_f32_e32 v13, 0x37800000, v12
	v_cndmask_b32_e64 v12, v12, v13, s[24:25]
	v_cmp_class_f32_e32 vcc, v190, v253
	s_nop 1
	v_cndmask_b32_e32 v12, v12, v190, vcc
	v_div_scale_f32 v13, s[6:7], v12, v12, 1.0
	v_rcp_f32_e32 v14, v13
	s_nop 0
	v_fma_f32 v15, -v13, v14, 1.0
	v_fmac_f32_e32 v14, v15, v14
	v_div_scale_f32 v15, vcc, 1.0, v12, 1.0
	v_mul_f32_e32 v16, v15, v14
	v_fma_f32 v17, -v13, v16, v15
	v_fmac_f32_e32 v16, v17, v14
	v_fma_f32 v13, -v13, v16, v15
	v_div_fmas_f32 v13, v13, v14, v16
	v_div_fixup_f32 v12, v13, v12, 1.0
	v_lshlrev_b32_e32 v14, 16, v42
	v_and_b32_e32 v15, 0xffff0000, v42
	v_lshlrev_b32_e32 v16, 16, v43
	v_and_b32_e32 v17, 0xffff0000, v43
	v_pk_mul_f32 v[18:19], v[90:91], v[12:13] op_sel_hi:[1,0]
	v_pk_mul_f32 v[12:13], v[94:95], v[12:13] op_sel_hi:[1,0]
	v_pk_mul_f32 v[14:15], v[18:19], v[14:15]
	v_pk_mul_f32 v[12:13], v[12:13], v[16:17]
	v_cvt_pk_bf16_f32 v14, v14, v15
	v_cvt_pk_bf16_f32 v15, v12, v13
	v_fma_f32 v12, -v188, v187, v184
	v_cmp_ge_f32_e32 vcc, 0, v12
	v_fma_f32 v13, -v185, v187, v184
	global_store_dwordx2 v[10:11], v[14:15], off offset:1536 nt
	v_cndmask_b32_e32 v12, v187, v188, vcc
	v_cmp_lt_f32_e32 vcc, 0, v13
	s_nop 1
	v_cndmask_b32_e32 v12, v12, v185, vcc
	v_mul_f32_e32 v13, 0x37800000, v12
	v_cndmask_b32_e64 v12, v12, v13, s[20:21]
	v_cmp_class_f32_e32 vcc, v184, v253
	s_nop 1
	v_cndmask_b32_e32 v12, v12, v184, vcc
	v_div_scale_f32 v13, s[6:7], v12, v12, 1.0
	v_rcp_f32_e32 v14, v13
	s_nop 0
	v_fma_f32 v15, -v13, v14, 1.0
	v_fmac_f32_e32 v14, v15, v14
	v_div_scale_f32 v15, vcc, 1.0, v12, 1.0
	v_mul_f32_e32 v16, v15, v14
	v_fma_f32 v17, -v13, v16, v15
	v_fmac_f32_e32 v16, v17, v14
	v_fma_f32 v13, -v13, v16, v15
	v_div_fmas_f32 v13, v13, v14, v16
	v_div_fixup_f32 v12, v13, v12, 1.0
	v_lshlrev_b32_e32 v14, 16, v40
	v_and_b32_e32 v15, 0xffff0000, v40
	v_lshlrev_b32_e32 v16, 16, v41
	v_and_b32_e32 v17, 0xffff0000, v41
	v_pk_mul_f32 v[18:19], v[82:83], v[12:13] op_sel_hi:[1,0]
	v_pk_mul_f32 v[12:13], v[84:85], v[12:13] op_sel_hi:[1,0]
	v_pk_mul_f32 v[14:15], v[18:19], v[14:15]
	v_pk_mul_f32 v[12:13], v[12:13], v[16:17]
	v_cvt_pk_bf16_f32 v14, v14, v15
	v_cvt_pk_bf16_f32 v15, v12, v13
	v_fma_f32 v12, -v176, v170, v168
	v_cmp_ge_f32_e32 vcc, 0, v12
	v_fma_f32 v13, -v173, v170, v168
	global_store_dwordx2 v[10:11], v[14:15], off offset:2048 nt
	v_cndmask_b32_e32 v12, v170, v176, vcc
	v_cmp_lt_f32_e32 vcc, 0, v13
	s_nop 1
	v_cndmask_b32_e32 v12, v12, v173, vcc
	v_mul_f32_e32 v13, 0x37800000, v12
	v_cndmask_b32_e64 v12, v12, v13, s[16:17]
	v_cmp_class_f32_e32 vcc, v168, v253
	s_nop 1
	v_cndmask_b32_e32 v12, v12, v168, vcc
	v_div_scale_f32 v13, s[6:7], v12, v12, 1.0
	v_rcp_f32_e32 v14, v13
	s_nop 0
	v_fma_f32 v15, -v13, v14, 1.0
	v_fmac_f32_e32 v14, v15, v14
	v_div_scale_f32 v15, vcc, 1.0, v12, 1.0
	v_mul_f32_e32 v16, v15, v14
	v_fma_f32 v17, -v13, v16, v15
	v_fmac_f32_e32 v16, v17, v14
	v_fma_f32 v13, -v13, v16, v15
	v_div_fmas_f32 v13, v13, v14, v16
	v_div_fixup_f32 v12, v13, v12, 1.0
	v_lshlrev_b32_e32 v14, 16, v36
	v_and_b32_e32 v15, 0xffff0000, v36
	v_lshlrev_b32_e32 v16, 16, v37
	v_and_b32_e32 v17, 0xffff0000, v37
	v_pk_mul_f32 v[18:19], v[74:75], v[12:13] op_sel_hi:[1,0]
	v_pk_mul_f32 v[12:13], v[76:77], v[12:13] op_sel_hi:[1,0]
	v_pk_mul_f32 v[14:15], v[18:19], v[14:15]
	v_pk_mul_f32 v[12:13], v[12:13], v[16:17]
	v_cvt_pk_bf16_f32 v14, v14, v15
	v_cvt_pk_bf16_f32 v15, v12, v13
	v_fma_f32 v12, -v166, v165, v162
	v_cmp_ge_f32_e32 vcc, 0, v12
	v_fma_f32 v13, -v163, v165, v162
	global_store_dwordx2 v[10:11], v[14:15], off offset:2560 nt
	v_cndmask_b32_e32 v12, v165, v166, vcc
	v_cmp_lt_f32_e32 vcc, 0, v13
	s_nop 1
	v_cndmask_b32_e32 v12, v12, v163, vcc
	v_mul_f32_e32 v13, 0x37800000, v12
	v_cndmask_b32_e64 v12, v12, v13, s[12:13]
	v_cmp_class_f32_e32 vcc, v162, v253
	s_nop 1
	v_cndmask_b32_e32 v12, v12, v162, vcc
	v_div_scale_f32 v13, s[6:7], v12, v12, 1.0
	v_rcp_f32_e32 v14, v13
	s_nop 0
	v_fma_f32 v15, -v13, v14, 1.0
	v_fmac_f32_e32 v14, v15, v14
	v_div_scale_f32 v15, vcc, 1.0, v12, 1.0
	v_mul_f32_e32 v16, v15, v14
	v_fma_f32 v17, -v13, v16, v15
	v_fmac_f32_e32 v16, v17, v14
	v_fma_f32 v13, -v13, v16, v15
	v_div_fmas_f32 v13, v13, v14, v16
	v_div_fixup_f32 v12, v13, v12, 1.0
	v_lshlrev_b32_e32 v14, 16, v32
	v_and_b32_e32 v15, 0xffff0000, v32
	v_lshlrev_b32_e32 v16, 16, v33
	v_and_b32_e32 v17, 0xffff0000, v33
	v_pk_mul_f32 v[18:19], v[64:65], v[12:13] op_sel_hi:[1,0]
	v_pk_mul_f32 v[12:13], v[66:67], v[12:13] op_sel_hi:[1,0]
	v_pk_mul_f32 v[14:15], v[18:19], v[14:15]
	v_pk_mul_f32 v[12:13], v[12:13], v[16:17]
	v_cvt_pk_bf16_f32 v14, v14, v15
	v_cvt_pk_bf16_f32 v15, v12, v13
	v_fma_f32 v12, -v160, v154, v152
	v_cmp_ge_f32_e32 vcc, 0, v12
	v_fma_f32 v13, -v157, v154, v152
	global_store_dwordx2 v[10:11], v[14:15], off offset:3072 nt
	v_cndmask_b32_e32 v12, v154, v160, vcc
	v_cmp_lt_f32_e32 vcc, 0, v13
	s_nop 1
	v_cndmask_b32_e32 v12, v12, v157, vcc
	v_mul_f32_e32 v13, 0x37800000, v12
	v_cndmask_b32_e64 v12, v12, v13, s[8:9]
	v_cmp_class_f32_e32 vcc, v152, v253
	s_nop 1
	v_cndmask_b32_e32 v12, v12, v152, vcc
	v_div_scale_f32 v13, s[6:7], v12, v12, 1.0
	v_rcp_f32_e32 v14, v13
	s_nop 0
	v_fma_f32 v15, -v13, v14, 1.0
	v_fmac_f32_e32 v14, v15, v14
	v_div_scale_f32 v15, vcc, 1.0, v12, 1.0
	v_mul_f32_e32 v16, v15, v14
	v_fma_f32 v17, -v13, v16, v15
	v_fmac_f32_e32 v16, v17, v14
	v_fma_f32 v13, -v13, v16, v15
	v_div_fmas_f32 v13, v13, v14, v16
	v_div_fixup_f32 v12, v13, v12, 1.0
	s_waitcnt vmcnt(47)
	v_lshlrev_b32_e32 v14, 16, v28
	v_and_b32_e32 v15, 0xffff0000, v28
	v_lshlrev_b32_e32 v16, 16, v29
	v_and_b32_e32 v17, 0xffff0000, v29
	v_pk_mul_f32 v[18:19], v[56:57], v[12:13] op_sel_hi:[1,0]
	v_pk_mul_f32 v[12:13], v[54:55], v[12:13] op_sel_hi:[1,0]
	v_pk_mul_f32 v[14:15], v[18:19], v[14:15]
	v_pk_mul_f32 v[12:13], v[12:13], v[16:17]
	v_cvt_pk_bf16_f32 v14, v14, v15
	v_cvt_pk_bf16_f32 v15, v12, v13
	global_store_dwordx2 v[10:11], v[14:15], off offset:3584 nt
	s_cbranch_scc1 .LBB0_864
; template <bool HG>
; __device__ __forceinline__ void readout_phase2(const Args& a, Frame& F, const float* gain, int nrows) {
;     ...
;     if (cx) RO_FINISH(f2, b2, g2, ML + nw);
	s_waitcnt vmcnt(39)
	v_lshlrev_b32_e32 v10, 16, v146
	v_and_b32_e32 v11, 0xffff0000, v146
	s_waitcnt vmcnt(38)
	v_lshlrev_b32_e32 v12, 16, v144
	v_and_b32_e32 v13, 0xffff0000, v144
	v_pk_add_f32 v[46:47], v[10:11], v[12:13]
	v_lshlrev_b32_e32 v10, 16, v147
	v_and_b32_e32 v11, 0xffff0000, v147
	v_lshlrev_b32_e32 v12, 16, v145
	v_and_b32_e32 v13, 0xffff0000, v145
	v_pk_add_f32 v[48:49], v[10:11], v[12:13]
	v_mov_b32_e32 v12, v47
	v_mov_b32_e32 v13, v49
	v_mov_b32_e32 v10, v46
	v_mov_b32_e32 v11, v48
	v_pk_mul_f32 v[12:13], v[12:13], v[12:13]
	s_ashr_i32 s83, s82, 31
	v_pk_fma_f32 v[10:11], v[10:11], v[10:11], v[12:13]
	s_waitcnt vmcnt(35)
	v_lshlrev_b32_e32 v12, 16, v128
	v_add_f32_e32 v62, v10, v11
	v_lshlrev_b32_e32 v10, 16, v132
	v_and_b32_e32 v11, 0xffff0000, v132
	v_and_b32_e32 v13, 0xffff0000, v128
	v_pk_add_f32 v[42:43], v[10:11], v[12:13]
	v_lshlrev_b32_e32 v10, 16, v133
	v_and_b32_e32 v11, 0xffff0000, v133
	v_lshlrev_b32_e32 v12, 16, v129
	v_and_b32_e32 v13, 0xffff0000, v129
	v_pk_add_f32 v[44:45], v[10:11], v[12:13]
	v_mov_b32_e32 v12, v43
	v_mov_b32_e32 v13, v45
	v_mov_b32_e32 v10, v42
	v_mov_b32_e32 v11, v44
	v_pk_mul_f32 v[12:13], v[12:13], v[12:13]
	s_lshl_b64 s[6:7], s[82:83], 12
	v_pk_fma_f32 v[10:11], v[10:11], v[10:11], v[12:13]
	s_waitcnt vmcnt(32)
	v_lshlrev_b32_e32 v12, 16, v120
	v_add_f32_e32 v63, v10, v11
	v_lshlrev_b32_e32 v10, 16, v124
	v_and_b32_e32 v11, 0xffff0000, v124
	v_and_b32_e32 v13, 0xffff0000, v120
	v_pk_add_f32 v[36:37], v[10:11], v[12:13]
	v_lshlrev_b32_e32 v10, 16, v125
	v_and_b32_e32 v11, 0xffff0000, v125
	v_lshlrev_b32_e32 v12, 16, v121
	v_and_b32_e32 v13, 0xffff0000, v121
	v_pk_add_f32 v[40:41], v[10:11], v[12:13]
	v_mov_b32_e32 v12, v37
	v_mov_b32_e32 v13, v41
	v_mov_b32_e32 v10, v36
	v_mov_b32_e32 v11, v40
	v_pk_mul_f32 v[12:13], v[12:13], v[12:13]
	v_lshl_add_u64 v[2:3], v[2:3], 0, s[6:7]
	v_pk_fma_f32 v[10:11], v[10:11], v[10:11], v[12:13]
	s_waitcnt vmcnt(29)
	v_lshlrev_b32_e32 v12, 16, v112
	v_add_f32_e32 v64, v10, v11
	v_lshlrev_b32_e32 v10, 16, v116
	v_and_b32_e32 v11, 0xffff0000, v116
	v_and_b32_e32 v13, 0xffff0000, v112
	v_pk_add_f32 v[28:29], v[10:11], v[12:13]
	v_lshlrev_b32_e32 v10, 16, v117
	v_and_b32_e32 v11, 0xffff0000, v117
	v_lshlrev_b32_e32 v12, 16, v113
	v_and_b32_e32 v13, 0xffff0000, v113
	v_pk_add_f32 v[32:33], v[10:11], v[12:13]
	v_mov_b32_e32 v12, v29
	v_mov_b32_e32 v13, v33
	v_mov_b32_e32 v10, v28
	v_mov_b32_e32 v11, v32
	v_pk_mul_f32 v[12:13], v[12:13], v[12:13]
	s_waitcnt vmcnt(17)
	v_lshlrev_b32_e32 v54, 16, v61
	v_pk_fma_f32 v[10:11], v[10:11], v[10:11], v[12:13]
	v_lshlrev_b32_e32 v12, 16, v108
	v_add_f32_e32 v65, v10, v11
	v_lshlrev_b32_e32 v10, 16, v110
	v_and_b32_e32 v11, 0xffff0000, v110
	v_and_b32_e32 v13, 0xffff0000, v108
	v_pk_add_f32 v[22:23], v[10:11], v[12:13]
	v_lshlrev_b32_e32 v10, 16, v111
	v_and_b32_e32 v11, 0xffff0000, v111
	v_lshlrev_b32_e32 v12, 16, v109
	v_and_b32_e32 v13, 0xffff0000, v109
	v_pk_add_f32 v[24:25], v[10:11], v[12:13]
	v_mov_b32_e32 v12, v23
	v_mov_b32_e32 v13, v25
	v_mov_b32_e32 v10, v22
	v_mov_b32_e32 v11, v24
	v_pk_mul_f32 v[12:13], v[12:13], v[12:13]
	v_and_b32_e32 v55, 0xffff0000, v61
	v_pk_fma_f32 v[10:11], v[10:11], v[10:11], v[12:13]
	v_lshlrev_b32_e32 v12, 16, v100
	v_add_f32_e32 v53, v10, v11
	v_lshlrev_b32_e32 v10, 16, v104
	v_and_b32_e32 v11, 0xffff0000, v104
	v_and_b32_e32 v13, 0xffff0000, v100
	v_pk_add_f32 v[18:19], v[10:11], v[12:13]
	v_lshlrev_b32_e32 v10, 16, v105
	v_and_b32_e32 v11, 0xffff0000, v105
	v_lshlrev_b32_e32 v12, 16, v101
	v_and_b32_e32 v13, 0xffff0000, v101
	v_pk_add_f32 v[20:21], v[10:11], v[12:13]
	v_mov_b32_e32 v12, v19
	v_mov_b32_e32 v13, v21
	v_mov_b32_e32 v10, v18
	v_mov_b32_e32 v11, v20
	v_pk_mul_f32 v[12:13], v[12:13], v[12:13]
	v_lshl_add_u64 v[2:3], v[2:3], 0, v[0:1]
	v_pk_fma_f32 v[10:11], v[10:11], v[10:11], v[12:13]
	v_lshlrev_b32_e32 v12, 16, v96
	v_add_f32_e32 v52, v10, v11
	v_lshlrev_b32_e32 v10, 16, v98
	v_and_b32_e32 v11, 0xffff0000, v98
	v_and_b32_e32 v13, 0xffff0000, v96
	v_pk_add_f32 v[14:15], v[10:11], v[12:13]
	v_lshlrev_b32_e32 v10, 16, v99
	v_and_b32_e32 v11, 0xffff0000, v99
	v_lshlrev_b32_e32 v12, 16, v97
	v_and_b32_e32 v13, 0xffff0000, v97
	v_pk_add_f32 v[16:17], v[10:11], v[12:13]
	v_mov_b32_e32 v12, v15
	v_mov_b32_e32 v13, v17
	v_mov_b32_e32 v10, v14
	v_mov_b32_e32 v11, v16
	v_pk_mul_f32 v[12:13], v[12:13], v[12:13]
	v_add_f32_dpp v0, v62, v62 quad_perm:[1,0,3,2] row_mask:0xf bank_mask:0xf bound_ctrl:1
	v_pk_fma_f32 v[10:11], v[10:11], v[10:11], v[12:13]
	v_lshlrev_b32_e32 v12, 16, v60
	v_add_f32_e32 v51, v10, v11
	v_lshlrev_b32_e32 v10, 16, v92
	v_and_b32_e32 v11, 0xffff0000, v92
	v_and_b32_e32 v13, 0xffff0000, v60
	v_pk_add_f32 v[10:11], v[10:11], v[12:13]
	v_lshlrev_b32_e32 v12, 16, v93
	v_and_b32_e32 v13, 0xffff0000, v93
	v_pk_add_f32 v[12:13], v[12:13], v[54:55]
	v_add_f32_dpp v0, v0, v0 quad_perm:[2,3,0,1] row_mask:0xf bank_mask:0xf bound_ctrl:1
	v_mov_b32_e32 v56, v11
	v_mov_b32_e32 v57, v13
	v_add_f32_dpp v0, v0, v0 row_half_mirror row_mask:0xf bank_mask:0xf bound_ctrl:1
	v_mov_b32_e32 v54, v10
	v_mov_b32_e32 v55, v12
	v_pk_mul_f32 v[56:57], v[56:57], v[56:57]
	v_add_f32_dpp v0, v0, v0 row_mirror row_mask:0xf bank_mask:0xf bound_ctrl:1
	v_pk_fma_f32 v[54:55], v[54:55], v[54:55], v[56:57]
	v_readlane_b32 s8, v0, 16
	v_readlane_b32 s9, v0, 48
	v_add_f32_e32 v50, v54, v55
	v_readlane_b32 s6, v0, 0
	v_readlane_b32 s7, v0, 32
	v_mov_b32_e32 v54, s8
	v_mov_b32_e32 v55, s9
	v_pk_add_f32 v[54:55], s[6:7], v[54:55]
	s_mov_b32 s83, 0x80000
	v_add_f32_e32 v0, v54, v55
	v_fmamk_f32 v0, v0, 0x3b800000, v252
	v_cmp_gt_f32_e32 vcc, s55, v0
	v_mul_f32_e32 v54, 0x4f800000, v0
	s_nop 0
; template <bool HG>
; __device__ __forceinline__ void readout_phase2(const Args& a, Frame& F, const float* gain, int nrows) {
;     ...
;     if (cx) RO_FINISH(f2, b2, g2, ML + nw);
	v_cndmask_b32_e32 v0, v0, v54, vcc
	v_sqrt_f32_e32 v54, v0
	s_nop 0
	v_add_u32_e32 v55, -1, v54
	v_fma_f32 v56, -v55, v54, v0
	v_cmp_ge_f32_e64 s[6:7], 0, v56
	v_add_u32_e32 v56, 1, v54
	s_nop 0
	v_cndmask_b32_e64 v55, v54, v55, s[6:7]
	v_fma_f32 v54, -v56, v54, v0
	v_cmp_lt_f32_e64 s[6:7], 0, v54
	s_nop 1
	v_cndmask_b32_e64 v54, v55, v56, s[6:7]
	v_mul_f32_e32 v55, 0x37800000, v54
	v_cndmask_b32_e32 v54, v54, v55, vcc
	v_cmp_class_f32_e32 vcc, v0, v253
	s_nop 1
	v_cndmask_b32_e32 v0, v54, v0, vcc
	v_div_scale_f32 v54, s[6:7], v0, v0, 1.0
	v_rcp_f32_e32 v55, v54
	s_nop 0
	v_fma_f32 v56, -v54, v55, 1.0
	v_fmac_f32_e32 v55, v56, v55
	v_div_scale_f32 v56, vcc, 1.0, v0, 1.0
	v_mul_f32_e32 v57, v56, v55
	v_fma_f32 v60, -v54, v57, v56
	v_fmac_f32_e32 v57, v60, v55
	v_fma_f32 v54, -v54, v57, v56
	v_div_fmas_f32 v54, v54, v55, v57
	v_div_fixup_f32 v0, v54, v0, 1.0
	v_pk_mul_f32 v[46:47], v[46:47], v[0:1] op_sel_hi:[1,0]
	v_pk_mul_f32 v[48:49], v[48:49], v[0:1] op_sel_hi:[1,0]
	v_add_f32_dpp v0, v63, v63 quad_perm:[1,0,3,2] row_mask:0xf bank_mask:0xf bound_ctrl:1
	v_lshlrev_b32_e32 v54, 16, v58
	v_and_b32_e32 v55, 0xffff0000, v58
	v_add_f32_dpp v0, v0, v0 quad_perm:[2,3,0,1] row_mask:0xf bank_mask:0xf bound_ctrl:1
	v_lshlrev_b32_e32 v56, 16, v59
	v_and_b32_e32 v57, 0xffff0000, v59
	v_add_f32_dpp v0, v0, v0 row_half_mirror row_mask:0xf bank_mask:0xf bound_ctrl:1
	v_pk_mul_f32 v[48:49], v[48:49], v[56:57]
	v_pk_mul_f32 v[46:47], v[46:47], v[54:55]
	v_add_f32_dpp v0, v0, v0 row_mirror row_mask:0xf bank_mask:0xf bound_ctrl:1
	v_cvt_pk_bf16_f32 v46, v46, v47
	v_cvt_pk_bf16_f32 v47, v48, v49
	v_readlane_b32 s8, v0, 16
	v_readlane_b32 s9, v0, 48
	global_store_dwordx2 v[2:3], v[46:47], off nt
	v_readlane_b32 s6, v0, 0
	v_readlane_b32 s7, v0, 32
	v_mov_b32_e32 v46, s8
	v_mov_b32_e32 v47, s9
	v_pk_add_f32 v[46:47], s[6:7], v[46:47]
	s_nop 0
	v_add_f32_e32 v0, v46, v47
	v_fmamk_f32 v0, v0, 0x3b800000, v252
	v_cmp_gt_f32_e32 vcc, s55, v0
	v_mul_f32_e32 v46, 0x4f800000, v0
	s_nop 0
	v_cndmask_b32_e32 v0, v0, v46, vcc
	v_sqrt_f32_e32 v46, v0
	s_nop 0
	v_add_u32_e32 v47, -1, v46
	v_fma_f32 v48, -v47, v46, v0
	v_cmp_ge_f32_e64 s[6:7], 0, v48
	v_add_u32_e32 v48, 1, v46
	s_nop 0
	v_cndmask_b32_e64 v47, v46, v47, s[6:7]
	v_fma_f32 v46, -v48, v46, v0
	v_cmp_lt_f32_e64 s[6:7], 0, v46
	s_nop 1
	v_cndmask_b32_e64 v46, v47, v48, s[6:7]
	v_mul_f32_e32 v47, 0x37800000, v46
	v_cndmask_b32_e32 v46, v46, v47, vcc
	v_cmp_class_f32_e32 vcc, v0, v253
	s_nop 1
	v_cndmask_b32_e32 v0, v46, v0, vcc
	v_div_scale_f32 v46, s[6:7], v0, v0, 1.0
	v_rcp_f32_e32 v47, v46
	s_nop 0
	v_fma_f32 v48, -v46, v47, 1.0
	v_fmac_f32_e32 v47, v48, v47
	v_div_scale_f32 v48, vcc, 1.0, v0, 1.0
	v_mul_f32_e32 v49, v48, v47
	v_fma_f32 v54, -v46, v49, v48
	v_fmac_f32_e32 v49, v54, v47
	v_fma_f32 v46, -v46, v49, v48
	v_div_fmas_f32 v46, v46, v47, v49
	v_div_fixup_f32 v0, v46, v0, 1.0
	v_pk_mul_f32 v[42:43], v[42:43], v[0:1] op_sel_hi:[1,0]
	v_pk_mul_f32 v[44:45], v[44:45], v[0:1] op_sel_hi:[1,0]
	v_add_f32_dpp v0, v64, v64 quad_perm:[1,0,3,2] row_mask:0xf bank_mask:0xf bound_ctrl:1
	v_lshlrev_b32_e32 v46, 16, v38
	v_and_b32_e32 v47, 0xffff0000, v38
	v_add_f32_dpp v0, v0, v0 quad_perm:[2,3,0,1] row_mask:0xf bank_mask:0xf bound_ctrl:1
	v_lshlrev_b32_e32 v38, 16, v39
	v_and_b32_e32 v39, 0xffff0000, v39
	v_add_f32_dpp v0, v0, v0 row_half_mirror row_mask:0xf bank_mask:0xf bound_ctrl:1
	v_pk_mul_f32 v[38:39], v[44:45], v[38:39]
	v_pk_mul_f32 v[42:43], v[42:43], v[46:47]
	v_add_f32_dpp v0, v0, v0 row_mirror row_mask:0xf bank_mask:0xf bound_ctrl:1
	v_cvt_pk_bf16_f32 v42, v42, v43
	v_readlane_b32 s8, v0, 16
	v_readlane_b32 s9, v0, 48
	v_cvt_pk_bf16_f32 v43, v38, v39
	v_readlane_b32 s6, v0, 0
	v_readlane_b32 s7, v0, 32
	v_mov_b32_e32 v38, s8
	v_mov_b32_e32 v39, s9
	v_pk_add_f32 v[38:39], s[6:7], v[38:39]
	global_store_dwordx2 v[2:3], v[42:43], off offset:512 nt
	v_add_f32_e32 v0, v38, v39
	v_fmamk_f32 v0, v0, 0x3b800000, v252
	v_cmp_gt_f32_e32 vcc, s55, v0
	v_mul_f32_e32 v38, 0x4f800000, v0
	s_nop 0
	v_cndmask_b32_e32 v0, v0, v38, vcc
	v_sqrt_f32_e32 v38, v0
	s_nop 0
	v_add_u32_e32 v39, -1, v38
	v_fma_f32 v42, -v39, v38, v0
	v_cmp_ge_f32_e64 s[6:7], 0, v42
	v_add_u32_e32 v42, 1, v38
	s_nop 0
	v_cndmask_b32_e64 v39, v38, v39, s[6:7]
	v_fma_f32 v38, -v42, v38, v0
	v_cmp_lt_f32_e64 s[6:7], 0, v38
	s_nop 1
	v_cndmask_b32_e64 v38, v39, v42, s[6:7]
	v_mul_f32_e32 v39, 0x37800000, v38
	v_cndmask_b32_e32 v38, v38, v39, vcc
	v_cmp_class_f32_e32 vcc, v0, v253
	s_nop 1
	v_cndmask_b32_e32 v0, v38, v0, vcc
	v_div_scale_f32 v38, s[6:7], v0, v0, 1.0
	v_rcp_f32_e32 v39, v38
	s_nop 0
	v_fma_f32 v42, -v38, v39, 1.0
	v_fmac_f32_e32 v39, v42, v39
	v_div_scale_f32 v42, vcc, 1.0, v0, 1.0
	v_mul_f32_e32 v43, v42, v39
	v_fma_f32 v44, -v38, v43, v42
	v_fmac_f32_e32 v43, v44, v39
	v_fma_f32 v38, -v38, v43, v42
	v_div_fmas_f32 v38, v38, v39, v43
	v_div_fixup_f32 v0, v38, v0, 1.0
	v_pk_mul_f32 v[36:37], v[36:37], v[0:1] op_sel_hi:[1,0]
	v_pk_mul_f32 v[40:41], v[40:41], v[0:1] op_sel_hi:[1,0]
	v_add_f32_dpp v0, v65, v65 quad_perm:[1,0,3,2] row_mask:0xf bank_mask:0xf bound_ctrl:1
	v_lshlrev_b32_e32 v38, 16, v34
	v_and_b32_e32 v39, 0xffff0000, v34
	v_add_f32_dpp v0, v0, v0 quad_perm:[2,3,0,1] row_mask:0xf bank_mask:0xf bound_ctrl:1
	v_lshlrev_b32_e32 v34, 16, v35
	v_and_b32_e32 v35, 0xffff0000, v35
	v_add_f32_dpp v0, v0, v0 row_half_mirror row_mask:0xf bank_mask:0xf bound_ctrl:1
	v_pk_mul_f32 v[34:35], v[40:41], v[34:35]
	v_pk_mul_f32 v[36:37], v[36:37], v[38:39]
	v_add_f32_dpp v0, v0, v0 row_mirror row_mask:0xf bank_mask:0xf bound_ctrl:1
	v_cvt_pk_bf16_f32 v36, v36, v37
	v_readlane_b32 s8, v0, 16
	v_readlane_b32 s9, v0, 48
	v_cvt_pk_bf16_f32 v37, v34, v35
	v_readlane_b32 s6, v0, 0
	v_readlane_b32 s7, v0, 32
	v_mov_b32_e32 v34, s8
	v_mov_b32_e32 v35, s9
	v_pk_add_f32 v[34:35], s[6:7], v[34:35]
	global_store_dwordx2 v[2:3], v[36:37], off offset:1024 nt
	v_add_f32_e32 v0, v34, v35
	v_fmamk_f32 v0, v0, 0x3b800000, v252
	v_cmp_gt_f32_e32 vcc, s55, v0
	v_mul_f32_e32 v34, 0x4f800000, v0
	s_nop 0
	v_cndmask_b32_e32 v0, v0, v34, vcc
	v_sqrt_f32_e32 v34, v0
	s_nop 0
	v_add_u32_e32 v35, -1, v34
	v_fma_f32 v36, -v35, v34, v0
	v_cmp_ge_f32_e64 s[6:7], 0, v36
	v_add_u32_e32 v36, 1, v34
	s_nop 0
	v_cndmask_b32_e64 v35, v34, v35, s[6:7]
	v_fma_f32 v34, -v36, v34, v0
	v_cmp_lt_f32_e64 s[6:7], 0, v34
	s_nop 1
	v_cndmask_b32_e64 v34, v35, v36, s[6:7]
	v_mul_f32_e32 v35, 0x37800000, v34
	v_cndmask_b32_e32 v34, v34, v35, vcc
	v_cmp_class_f32_e32 vcc, v0, v253
	s_nop 1
	v_cndmask_b32_e32 v0, v34, v0, vcc
	v_div_scale_f32 v34, s[6:7], v0, v0, 1.0
	v_rcp_f32_e32 v35, v34
	s_nop 0
	v_fma_f32 v36, -v34, v35, 1.0
	v_fmac_f32_e32 v35, v36, v35
	v_div_scale_f32 v36, vcc, 1.0, v0, 1.0
	v_mul_f32_e32 v37, v36, v35
	v_fma_f32 v38, -v34, v37, v36
	v_fmac_f32_e32 v37, v38, v35
	v_fma_f32 v34, -v34, v37, v36
	v_div_fmas_f32 v34, v34, v35, v37
	v_div_fixup_f32 v0, v34, v0, 1.0
	v_pk_mul_f32 v[28:29], v[28:29], v[0:1] op_sel_hi:[1,0]
	v_pk_mul_f32 v[32:33], v[32:33], v[0:1] op_sel_hi:[1,0]
	v_add_f32_dpp v0, v53, v53 quad_perm:[1,0,3,2] row_mask:0xf bank_mask:0xf bound_ctrl:1
	v_lshlrev_b32_e32 v34, 16, v30
	v_and_b32_e32 v35, 0xffff0000, v30
	v_add_f32_dpp v0, v0, v0 quad_perm:[2,3,0,1] row_mask:0xf bank_mask:0xf bound_ctrl:1
	v_lshlrev_b32_e32 v30, 16, v31
	v_and_b32_e32 v31, 0xffff0000, v31
	v_add_f32_dpp v0, v0, v0 row_half_mirror row_mask:0xf bank_mask:0xf bound_ctrl:1
	v_pk_mul_f32 v[30:31], v[32:33], v[30:31]
	v_pk_mul_f32 v[28:29], v[28:29], v[34:35]
	v_add_f32_dpp v0, v0, v0 row_mirror row_mask:0xf bank_mask:0xf bound_ctrl:1
	v_cvt_pk_bf16_f32 v28, v28, v29
	v_cvt_pk_bf16_f32 v29, v30, v31
	v_readlane_b32 s8, v0, 16
	v_readlane_b32 s9, v0, 48
	global_store_dwordx2 v[2:3], v[28:29], off offset:1536 nt
	v_readlane_b32 s6, v0, 0
	v_readlane_b32 s7, v0, 32
	v_mov_b32_e32 v28, s8
	v_mov_b32_e32 v29, s9
	v_pk_add_f32 v[28:29], s[6:7], v[28:29]
	s_nop 0
	v_add_f32_e32 v0, v28, v29
	v_fmamk_f32 v0, v0, 0x3b800000, v252
	v_cmp_gt_f32_e32 vcc, s55, v0
	v_mul_f32_e32 v28, 0x4f800000, v0
	s_nop 0
	v_cndmask_b32_e32 v0, v0, v28, vcc
	v_sqrt_f32_e32 v28, v0
	s_nop 0
	v_add_u32_e32 v29, -1, v28
	v_fma_f32 v30, -v29, v28, v0
	v_cmp_ge_f32_e64 s[6:7], 0, v30
	v_add_u32_e32 v30, 1, v28
	s_nop 0
	v_cndmask_b32_e64 v29, v28, v29, s[6:7]
	v_fma_f32 v28, -v30, v28, v0
	v_cmp_lt_f32_e64 s[6:7], 0, v28
	s_nop 1
	v_cndmask_b32_e64 v28, v29, v30, s[6:7]
	v_mul_f32_e32 v29, 0x37800000, v28
	v_cndmask_b32_e32 v28, v28, v29, vcc
	v_cmp_class_f32_e32 vcc, v0, v253
	s_nop 1
	v_cndmask_b32_e32 v0, v28, v0, vcc
	v_div_scale_f32 v28, s[6:7], v0, v0, 1.0
	v_rcp_f32_e32 v29, v28
	s_nop 0
	v_fma_f32 v30, -v28, v29, 1.0
	v_fmac_f32_e32 v29, v30, v29
	v_div_scale_f32 v30, vcc, 1.0, v0, 1.0
	v_mul_f32_e32 v31, v30, v29
	v_fma_f32 v32, -v28, v31, v30
	v_fmac_f32_e32 v31, v32, v29
	v_fma_f32 v28, -v28, v31, v30
	v_div_fmas_f32 v28, v28, v29, v31
	v_div_fixup_f32 v0, v28, v0, 1.0
	v_pk_mul_f32 v[22:23], v[22:23], v[0:1] op_sel_hi:[1,0]
	v_pk_mul_f32 v[24:25], v[24:25], v[0:1] op_sel_hi:[1,0]
	v_add_f32_dpp v0, v52, v52 quad_perm:[1,0,3,2] row_mask:0xf bank_mask:0xf bound_ctrl:1
	v_lshlrev_b32_e32 v28, 16, v26
	v_and_b32_e32 v29, 0xffff0000, v26
	v_add_f32_dpp v0, v0, v0 quad_perm:[2,3,0,1] row_mask:0xf bank_mask:0xf bound_ctrl:1
	v_lshlrev_b32_e32 v26, 16, v27
	v_and_b32_e32 v27, 0xffff0000, v27
	v_add_f32_dpp v0, v0, v0 row_half_mirror row_mask:0xf bank_mask:0xf bound_ctrl:1
	v_pk_mul_f32 v[24:25], v[24:25], v[26:27]
	v_pk_mul_f32 v[22:23], v[22:23], v[28:29]
	v_add_f32_dpp v0, v0, v0 row_mirror row_mask:0xf bank_mask:0xf bound_ctrl:1
	v_cvt_pk_bf16_f32 v22, v22, v23
	v_cvt_pk_bf16_f32 v23, v24, v25
	v_readlane_b32 s8, v0, 16
	v_readlane_b32 s9, v0, 48
	global_store_dwordx2 v[2:3], v[22:23], off offset:2048 nt
	v_readlane_b32 s6, v0, 0
	v_readlane_b32 s7, v0, 32
	v_mov_b32_e32 v22, s8
	v_mov_b32_e32 v23, s9
	v_pk_add_f32 v[22:23], s[6:7], v[22:23]
	s_nop 0
	v_add_f32_e32 v0, v22, v23
	v_fmamk_f32 v0, v0, 0x3b800000, v252
	v_cmp_gt_f32_e32 vcc, s55, v0
	v_mul_f32_e32 v22, 0x4f800000, v0
	s_nop 0
	v_cndmask_b32_e32 v0, v0, v22, vcc
	v_sqrt_f32_e32 v22, v0
	s_nop 0
	v_add_u32_e32 v23, -1, v22
	v_fma_f32 v24, -v23, v22, v0
	v_cmp_ge_f32_e64 s[6:7], 0, v24
	v_add_u32_e32 v24, 1, v22
	s_nop 0
	v_cndmask_b32_e64 v23, v22, v23, s[6:7]
	v_fma_f32 v22, -v24, v22, v0
	v_cmp_lt_f32_e64 s[6:7], 0, v22
	s_nop 1
	v_cndmask_b32_e64 v22, v23, v24, s[6:7]
	v_mul_f32_e32 v23, 0x37800000, v22
	v_cndmask_b32_e32 v22, v22, v23, vcc
	v_cmp_class_f32_e32 vcc, v0, v253
	s_nop 1
	v_cndmask_b32_e32 v0, v22, v0, vcc
	v_div_scale_f32 v22, s[6:7], v0, v0, 1.0
	v_rcp_f32_e32 v23, v22
	s_nop 0
	v_fma_f32 v24, -v22, v23, 1.0
	v_fmac_f32_e32 v23, v24, v23
	v_div_scale_f32 v24, vcc, 1.0, v0, 1.0
	v_mul_f32_e32 v25, v24, v23
	v_fma_f32 v26, -v22, v25, v24
	v_fmac_f32_e32 v25, v26, v23
	v_fma_f32 v22, -v22, v25, v24
	v_div_fmas_f32 v22, v22, v23, v25
	v_div_fixup_f32 v0, v22, v0, 1.0
	v_pk_mul_f32 v[18:19], v[18:19], v[0:1] op_sel_hi:[1,0]
	v_pk_mul_f32 v[20:21], v[20:21], v[0:1] op_sel_hi:[1,0]
	v_add_f32_dpp v0, v51, v51 quad_perm:[1,0,3,2] row_mask:0xf bank_mask:0xf bound_ctrl:1
	v_lshlrev_b32_e32 v22, 16, v8
	v_and_b32_e32 v23, 0xffff0000, v8
	v_add_f32_dpp v0, v0, v0 quad_perm:[2,3,0,1] row_mask:0xf bank_mask:0xf bound_ctrl:1
	v_lshlrev_b32_e32 v8, 16, v9
	v_and_b32_e32 v9, 0xffff0000, v9
	v_add_f32_dpp v0, v0, v0 row_half_mirror row_mask:0xf bank_mask:0xf bound_ctrl:1
	v_pk_mul_f32 v[8:9], v[20:21], v[8:9]
	v_pk_mul_f32 v[18:19], v[18:19], v[22:23]
	v_add_f32_dpp v0, v0, v0 row_mirror row_mask:0xf bank_mask:0xf bound_ctrl:1
	v_cvt_pk_bf16_f32 v18, v18, v19
	v_readlane_b32 s8, v0, 16
	v_readlane_b32 s9, v0, 48
	v_cvt_pk_bf16_f32 v19, v8, v9
	v_readlane_b32 s6, v0, 0
	v_readlane_b32 s7, v0, 32
	v_mov_b32_e32 v8, s8
	v_mov_b32_e32 v9, s9
	v_pk_add_f32 v[8:9], s[6:7], v[8:9]
	global_store_dwordx2 v[2:3], v[18:19], off offset:2560 nt
	v_add_f32_e32 v0, v8, v9
	v_fmamk_f32 v0, v0, 0x3b800000, v252
	v_cmp_gt_f32_e32 vcc, s55, v0
	v_mul_f32_e32 v8, 0x4f800000, v0
	s_nop 0
	v_cndmask_b32_e32 v0, v0, v8, vcc
	v_sqrt_f32_e32 v8, v0
	s_nop 0
	v_add_u32_e32 v9, -1, v8
	v_fma_f32 v18, -v9, v8, v0
	v_cmp_ge_f32_e64 s[6:7], 0, v18
	v_add_u32_e32 v18, 1, v8
	s_nop 0
	v_cndmask_b32_e64 v9, v8, v9, s[6:7]
	v_fma_f32 v8, -v18, v8, v0
	v_cmp_lt_f32_e64 s[6:7], 0, v8
	s_nop 1
	v_cndmask_b32_e64 v8, v9, v18, s[6:7]
	v_mul_f32_e32 v9, 0x37800000, v8
	v_cndmask_b32_e32 v8, v8, v9, vcc
	v_cmp_class_f32_e32 vcc, v0, v253
	s_nop 1
	v_cndmask_b32_e32 v0, v8, v0, vcc
	v_div_scale_f32 v8, s[6:7], v0, v0, 1.0
	v_rcp_f32_e32 v9, v8
	s_nop 0
	v_fma_f32 v18, -v8, v9, 1.0
	v_fmac_f32_e32 v9, v18, v9
	v_div_scale_f32 v18, vcc, 1.0, v0, 1.0
	v_mul_f32_e32 v19, v18, v9
	v_fma_f32 v20, -v8, v19, v18
	v_fmac_f32_e32 v19, v20, v9
	v_fma_f32 v8, -v8, v19, v18
	v_div_fmas_f32 v8, v8, v9, v19
	v_div_fixup_f32 v0, v8, v0, 1.0
	v_pk_mul_f32 v[14:15], v[14:15], v[0:1] op_sel_hi:[1,0]
	v_pk_mul_f32 v[16:17], v[16:17], v[0:1] op_sel_hi:[1,0]
	v_add_f32_dpp v0, v50, v50 quad_perm:[1,0,3,2] row_mask:0xf bank_mask:0xf bound_ctrl:1
	v_lshlrev_b32_e32 v8, 16, v6
	v_and_b32_e32 v9, 0xffff0000, v6
	v_add_f32_dpp v0, v0, v0 quad_perm:[2,3,0,1] row_mask:0xf bank_mask:0xf bound_ctrl:1
	v_lshlrev_b32_e32 v6, 16, v7
	v_and_b32_e32 v7, 0xffff0000, v7
	v_add_f32_dpp v0, v0, v0 row_half_mirror row_mask:0xf bank_mask:0xf bound_ctrl:1
	v_pk_mul_f32 v[6:7], v[16:17], v[6:7]
	v_pk_mul_f32 v[8:9], v[14:15], v[8:9]
	v_add_f32_dpp v0, v0, v0 row_mirror row_mask:0xf bank_mask:0xf bound_ctrl:1
	v_cvt_pk_bf16_f32 v8, v8, v9
	v_readlane_b32 s8, v0, 16
	v_readlane_b32 s9, v0, 48
	v_cvt_pk_bf16_f32 v9, v6, v7
	v_readlane_b32 s6, v0, 0
	v_readlane_b32 s7, v0, 32
	v_mov_b32_e32 v6, s8
	v_mov_b32_e32 v7, s9
	v_pk_add_f32 v[6:7], s[6:7], v[6:7]
	global_store_dwordx2 v[2:3], v[8:9], off offset:3072 nt
	v_add_f32_e32 v0, v6, v7
	v_fmamk_f32 v0, v0, 0x3b800000, v252
	v_cmp_gt_f32_e32 vcc, s55, v0
	v_mul_f32_e32 v6, 0x4f800000, v0
	s_nop 0
	v_cndmask_b32_e32 v0, v0, v6, vcc
	v_sqrt_f32_e32 v6, v0
	s_nop 0
	v_add_u32_e32 v7, -1, v6
	v_fma_f32 v8, -v7, v6, v0
	v_cmp_ge_f32_e64 s[6:7], 0, v8
	v_add_u32_e32 v8, 1, v6
	s_nop 0
	v_cndmask_b32_e64 v7, v6, v7, s[6:7]
	v_fma_f32 v6, -v8, v6, v0
	v_cmp_lt_f32_e64 s[6:7], 0, v6
	s_nop 1
	v_cndmask_b32_e64 v6, v7, v8, s[6:7]
	v_mul_f32_e32 v7, 0x37800000, v6
	v_cndmask_b32_e32 v6, v6, v7, vcc
	v_cmp_class_f32_e32 vcc, v0, v253
	s_nop 1
	v_cndmask_b32_e32 v0, v6, v0, vcc
	v_div_scale_f32 v6, s[6:7], v0, v0, 1.0
	v_rcp_f32_e32 v7, v6
	s_nop 0
	v_fma_f32 v8, -v6, v7, 1.0
	v_fmac_f32_e32 v7, v8, v7
	v_div_scale_f32 v8, vcc, 1.0, v0, 1.0
	v_mul_f32_e32 v9, v8, v7
	v_fma_f32 v14, -v6, v9, v8
	v_fmac_f32_e32 v9, v14, v7
	v_fma_f32 v6, -v6, v9, v8
	v_div_fmas_f32 v6, v6, v7, v9
	v_div_fixup_f32 v0, v6, v0, 1.0
	s_waitcnt vmcnt(23)
	v_lshlrev_b32_e32 v6, 16, v4
	v_and_b32_e32 v7, 0xffff0000, v4
	v_lshlrev_b32_e32 v4, 16, v5
	v_and_b32_e32 v5, 0xffff0000, v5
	v_pk_mul_f32 v[8:9], v[10:11], v[0:1] op_sel_hi:[1,0]
	v_pk_mul_f32 v[10:11], v[12:13], v[0:1] op_sel_hi:[1,0]
	v_pk_mul_f32 v[6:7], v[8:9], v[6:7]
	v_pk_mul_f32 v[4:5], v[10:11], v[4:5]
	v_cvt_pk_bf16_f32 v6, v6, v7
	v_cvt_pk_bf16_f32 v7, v4, v5
	global_store_dwordx2 v[2:3], v[6:7], off offset:3584 nt

; #define GAS __attribute__((address_space(1)))
; #define LAS __attribute__((address_space(3)))
; #define NR_LOAD(dst, k_) do { const GAS v2u* xr_ = (const GAS v2u*)(X + (size_t)(nw + 2048 * (k_)) * D) + F.lane; \
;         _Pragma("unroll") for (int j = 0; j < 8; ++j) dst[j] = __builtin_nontemporal_load(xr_ + 64 * j); } while (0)
; __device__ __forceinline__ void norm_mod_phase2(const Args& a, Frame& F, const float* gain, const float* modl, int sh_off, int sc_off, int nrows, const float* slab_gate) {
;     ...
;     NR_LOAD(r0, 0); NR_LOAD(r1, 1); NR_LOAD(r2, 2); NR_LOAD(r3, 3); NR_LOAD(r4, 4); NR_LOAD(r5, 5); NR_LOAD(r6, 6); NR_LOAD(r7, 7);
;     { const GAS f32x4* g4 = (const GAS f32x4*)gain;
;       for (int q = F.tid; q < 5 * D / 4; q += NWAVES * 64) { const int bq = q >> 9, cq = q & 511; const GAS f32x4* mb4 = (const GAS f32x4*)(modl + (size_t)bq * MOD_LD);
;           ((LAS f32x4*)CA)[q] = g4[cq] * (mb4[sc_off / 4 + cq] + 1.0f); ((LAS f32x4*)CB)[q] = mb4[sh_off / 4 + cq]; } }
.LBB0_1042:
	s_andn2_b64 vcc, exec, s[8:9]
	s_cbranch_vccnz .LBB0_1051
	s_getreg_b32 s6, hwreg(HW_REG_HW_ID, 0, 6)
	s_lshl_b32 s6, s6, 2
	s_add_i32 s6, s6, 0
	s_add_i32 s6, s6, 0x20540
	v_mov_b32_e32 v0, s6
	ds_read_b32 v0, v0
	v_mov_b64_e32 v[2:3], s[0:1]
	v_mov_b32_e32 v7, v1
	s_waitcnt lgkmcnt(0)
	v_readfirstlane_b32 s6, v0
	v_mbcnt_lo_u32_b32 v0, -1, 0
	v_mbcnt_hi_u32_b32 v0, -1, v0
	s_nop 1
	v_lshl_add_u32 v142, s6, 6, v0
	v_mov_b32_e32 v136, s72
	v_mov_b32_e32 v137, s73
	v_readfirstlane_b32 s6, v142
	s_ashr_i32 s6, s6, 6
	s_add_i32 s10, s6, s91
	s_mov_b64 s[6:7], 0x400000
	s_ashr_i32 s11, s10, 31
	v_and_b32_e32 v147, 63, v142
	s_add_i32 s78, s10, 0x800
	v_lshlrev_b32_e32 v6, 3, v147
	s_ashr_i32 s79, s78, 31
	s_add_i32 s36, s10, 0x1000
	s_ashr_i32 s37, s36, 31
	s_add_i32 s30, s10, 0x1800
	s_ashr_i32 s31, s30, 31
	s_add_i32 s26, s10, 0x2000
	s_ashr_i32 s27, s26, 31
	s_add_i32 s22, s10, 0x2800
	s_ashr_i32 s23, s22, 31
	s_add_i32 s18, s10, 0x3000
	s_ashr_i32 s19, s18, 31
	s_add_i32 s14, s10, 0x3800
	s_ashr_i32 s15, s14, 31
	s_waitcnt vmcnt(0) lgkmcnt(0)
	v_lshl_add_u64 v[8:9], v[136:137], 0, s[6:7]
	s_lshl_b64 s[6:7], s[10:11], 12
	v_lshl_add_u64 v[2:3], v[8:9], 0, s[6:7]
	v_lshl_add_u64 v[2:3], v[2:3], 0, v[6:7]
	s_lshl_b64 s[6:7], s[78:79], 12
	v_and_b32_e32 v184, 0x1ff, v142
	v_lshlrev_b32_e32 v184, 4, v184
	v_mov_b32_e32 v185, 0
	v_mov_b32_e32 v186, s76
	v_lshlrev_b32_e32 v186, 13, v186
	v_mov_b32_e32 v187, 0
	v_lshl_add_u64 v[188:189], v[74:75], 0, v[186:187]
	v_lshl_add_u64 v[188:189], v[188:189], 0, v[184:185]
	global_load_dwordx4 v[192:195], v[188:189], off
	v_add_u32_e32 v196, 0x8000, v184
	v_add_u32_e32 v201, 0x6000, v184
	v_add_u32_e32 v197, 0x14000, v184
	v_add_u32_e32 v202, 0x12000, v184
	v_add_u32_e32 v198, 0x20000, v184
	v_add_u32_e32 v203, 0x1e000, v184
	v_add_u32_e32 v199, 0x2c000, v184
	v_add_u32_e32 v204, 0x2a000, v184
	v_add_u32_e32 v200, 0x38000, v184
	v_add_u32_e32 v205, 0x36000, v184
	global_load_dwordx4 v[208:211], v196, s[86:87]
	global_load_dwordx4 v[228:231], v201, s[86:87]
	global_load_dwordx4 v[212:215], v197, s[86:87]
	global_load_dwordx4 v[232:235], v202, s[86:87]
	global_load_dwordx4 v[216:219], v198, s[86:87]
	global_load_dwordx4 v[236:239], v203, s[86:87]
	global_load_dwordx4 v[220:223], v199, s[86:87]
	global_load_dwordx4 v[240:243], v204, s[86:87]
	global_load_dwordx4 v[224:227], v200, s[86:87]
	global_load_dwordx4 v[244:247], v205, s[86:87]
	global_load_dwordx2 v[140:141], v[2:3], off nt
	global_load_dwordx2 v[138:139], v[2:3], off offset:512 nt
	global_load_dwordx2 v[134:135], v[2:3], off offset:1024 nt
	global_load_dwordx2 v[132:133], v[2:3], off offset:1536 nt
	global_load_dwordx2 v[130:131], v[2:3], off offset:2048 nt
	global_load_dwordx2 v[128:129], v[2:3], off offset:2560 nt
	global_load_dwordx2 v[126:127], v[2:3], off offset:3072 nt
	global_load_dwordx2 v[124:125], v[2:3], off offset:3584 nt
	v_lshl_add_u64 v[2:3], v[8:9], 0, s[6:7]
	v_lshl_add_u64 v[2:3], v[2:3], 0, v[6:7]
	s_lshl_b64 s[6:7], s[36:37], 12
	global_load_dwordx2 v[122:123], v[2:3], off nt
	global_load_dwordx2 v[120:121], v[2:3], off offset:512 nt
	global_load_dwordx2 v[118:119], v[2:3], off offset:1024 nt
	global_load_dwordx2 v[116:117], v[2:3], off offset:1536 nt
	global_load_dwordx2 v[114:115], v[2:3], off offset:2048 nt
	global_load_dwordx2 v[112:113], v[2:3], off offset:2560 nt
	global_load_dwordx2 v[110:111], v[2:3], off offset:3072 nt
	global_load_dwordx2 v[108:109], v[2:3], off offset:3584 nt
	v_lshl_add_u64 v[2:3], v[8:9], 0, s[6:7]
	v_lshl_add_u64 v[2:3], v[2:3], 0, v[6:7]
	s_lshl_b64 s[6:7], s[30:31], 12
	global_load_dwordx2 v[106:107], v[2:3], off nt
	global_load_dwordx2 v[104:105], v[2:3], off offset:512 nt
	global_load_dwordx2 v[102:103], v[2:3], off offset:1024 nt
	global_load_dwordx2 v[100:101], v[2:3], off offset:1536 nt
	global_load_dwordx2 v[98:99], v[2:3], off offset:2048 nt
	global_load_dwordx2 v[96:97], v[2:3], off offset:2560 nt
	global_load_dwordx2 v[94:95], v[2:3], off offset:3072 nt
	global_load_dwordx2 v[92:93], v[2:3], off offset:3584 nt
	v_lshl_add_u64 v[2:3], v[8:9], 0, s[6:7]
	v_lshl_add_u64 v[2:3], v[2:3], 0, v[6:7]
	s_lshl_b64 s[6:7], s[26:27], 12
	global_load_dwordx2 v[90:91], v[2:3], off nt
	global_load_dwordx2 v[88:89], v[2:3], off offset:512 nt
	global_load_dwordx2 v[86:87], v[2:3], off offset:1024 nt
	global_load_dwordx2 v[84:85], v[2:3], off offset:1536 nt
	global_load_dwordx2 v[82:83], v[2:3], off offset:2048 nt
	global_load_dwordx2 v[80:81], v[2:3], off offset:2560 nt
	global_load_dwordx2 v[78:79], v[2:3], off offset:3072 nt
	global_load_dwordx2 v[76:77], v[2:3], off offset:3584 nt
	v_lshl_add_u64 v[2:3], v[8:9], 0, s[6:7]
	v_lshl_add_u64 v[2:3], v[2:3], 0, v[6:7]
	s_lshl_b64 s[6:7], s[22:23], 12
	global_load_dwordx2 v[72:73], v[2:3], off nt
	global_load_dwordx2 v[70:71], v[2:3], off offset:512 nt
	global_load_dwordx2 v[68:69], v[2:3], off offset:1024 nt
	global_load_dwordx2 v[66:67], v[2:3], off offset:1536 nt
	global_load_dwordx2 v[64:65], v[2:3], off offset:2048 nt
	global_load_dwordx2 v[62:63], v[2:3], off offset:2560 nt
	global_load_dwordx2 v[60:61], v[2:3], off offset:3072 nt
	global_load_dwordx2 v[58:59], v[2:3], off offset:3584 nt
	v_lshl_add_u64 v[2:3], v[8:9], 0, s[6:7]
	v_lshl_add_u64 v[2:3], v[2:3], 0, v[6:7]
	s_lshl_b64 s[6:7], s[18:19], 12
	global_load_dwordx2 v[56:57], v[2:3], off nt
	global_load_dwordx2 v[54:55], v[2:3], off offset:512 nt
	global_load_dwordx2 v[52:53], v[2:3], off offset:1024 nt
	global_load_dwordx2 v[50:51], v[2:3], off offset:1536 nt
	global_load_dwordx2 v[48:49], v[2:3], off offset:2048 nt
	global_load_dwordx2 v[46:47], v[2:3], off offset:2560 nt
	global_load_dwordx2 v[44:45], v[2:3], off offset:3072 nt
	global_load_dwordx2 v[42:43], v[2:3], off offset:3584 nt
	v_lshl_add_u64 v[2:3], v[8:9], 0, s[6:7]
	v_lshl_add_u64 v[2:3], v[2:3], 0, v[6:7]
	s_lshl_b64 s[6:7], s[14:15], 12
	global_load_dwordx2 v[40:41], v[2:3], off nt
	global_load_dwordx2 v[38:39], v[2:3], off offset:512 nt
	global_load_dwordx2 v[36:37], v[2:3], off offset:1024 nt
	global_load_dwordx2 v[34:35], v[2:3], off offset:1536 nt
	global_load_dwordx2 v[32:33], v[2:3], off offset:2048 nt
	global_load_dwordx2 v[30:31], v[2:3], off offset:2560 nt
	global_load_dwordx2 v[28:29], v[2:3], off offset:3072 nt
	global_load_dwordx2 v[26:27], v[2:3], off offset:3584 nt
	v_lshl_add_u64 v[2:3], v[8:9], 0, s[6:7]
	v_lshl_add_u64 v[2:3], v[2:3], 0, v[6:7]
	global_load_dwordx2 v[24:25], v[2:3], off nt
	global_load_dwordx2 v[22:23], v[2:3], off offset:512 nt
	global_load_dwordx2 v[20:21], v[2:3], off offset:1024 nt
	global_load_dwordx2 v[18:19], v[2:3], off offset:1536 nt
	global_load_dwordx2 v[16:17], v[2:3], off offset:2048 nt
	global_load_dwordx2 v[14:15], v[2:3], off offset:2560 nt
	global_load_dwordx2 v[12:13], v[2:3], off offset:3072 nt
	global_load_dwordx2 v[10:11], v[2:3], off offset:3584 nt
	s_waitcnt vmcnt(62)
; #define GAS __attribute__((address_space(1)))
; #define LAS __attribute__((address_space(3)))
; #define NR_LOAD(dst, k_) do { const GAS v2u* xr_ = (const GAS v2u*)(X + (size_t)(nw + 2048 * (k_)) * D) + F.lane; \
;         _Pragma("unroll") for (int j = 0; j < 8; ++j) dst[j] = __builtin_nontemporal_load(xr_ + 64 * j); } while (0)
; __device__ __forceinline__ void norm_mod_phase2(const Args& a, Frame& F, const float* gain, const float* modl, int sh_off, int sc_off, int nrows, const float* slab_gate) {
;     ...
;     NR_LOAD(r0, 0); NR_LOAD(r1, 1); NR_LOAD(r2, 2); NR_LOAD(r3, 3); NR_LOAD(r4, 4); NR_LOAD(r5, 5); NR_LOAD(r6, 6); NR_LOAD(r7, 7);
;     { const GAS f32x4* g4 = (const GAS f32x4*)gain;
;       for (int q = F.tid; q < 5 * D / 4; q += NWAVES * 64) { const int bq = q >> 9, cq = q & 511; const GAS f32x4* mb4 = (const GAS f32x4*)(modl + (size_t)bq * MOD_LD);
;           ((LAS f32x4*)CA)[q] = g4[cq] * (mb4[sc_off / 4 + cq] + 1.0f); ((LAS f32x4*)CB)[q] = mb4[sh_off / 4 + cq]; } }
;     asm volatile("s_waitcnt lgkmcnt(0)" ::: "memory"); __builtin_amdgcn_s_barrier(); asm volatile("" ::: "memory");
	v_lshl_add_u32 v184, v142, 4, 0
	v_add_u32_e32 v185, 0xa000, v184
	v_pk_add_f32 v[210:211], v[210:211], 1.0 op_sel_hi:[1,0]
	v_pk_add_f32 v[208:209], v[208:209], 1.0 op_sel_hi:[1,0]
	v_pk_mul_f32 v[210:211], v[194:195], v[210:211]
	v_pk_mul_f32 v[208:209], v[192:193], v[208:209]
	ds_write_b128 v184, v[208:211]
	ds_write_b128 v185, v[228:231]
	v_pk_add_f32 v[214:215], v[214:215], 1.0 op_sel_hi:[1,0]
	v_pk_add_f32 v[212:213], v[212:213], 1.0 op_sel_hi:[1,0]
	v_pk_mul_f32 v[214:215], v[194:195], v[214:215]
	v_pk_mul_f32 v[212:213], v[192:193], v[212:213]
	ds_write_b128 v184, v[212:215] offset:8192
	ds_write_b128 v185, v[232:235] offset:8192
	v_pk_add_f32 v[218:219], v[218:219], 1.0 op_sel_hi:[1,0]
	v_pk_add_f32 v[216:217], v[216:217], 1.0 op_sel_hi:[1,0]
	v_pk_mul_f32 v[218:219], v[194:195], v[218:219]
	v_pk_mul_f32 v[216:217], v[192:193], v[216:217]
	ds_write_b128 v184, v[216:219] offset:16384
	ds_write_b128 v185, v[236:239] offset:16384
	v_pk_add_f32 v[222:223], v[222:223], 1.0 op_sel_hi:[1,0]
	v_pk_add_f32 v[220:221], v[220:221], 1.0 op_sel_hi:[1,0]
	v_pk_mul_f32 v[222:223], v[194:195], v[222:223]
	v_pk_mul_f32 v[220:221], v[192:193], v[220:221]
	ds_write_b128 v184, v[220:223] offset:24576
	ds_write_b128 v185, v[240:243] offset:24576
	v_pk_add_f32 v[226:227], v[226:227], 1.0 op_sel_hi:[1,0]
	v_pk_add_f32 v[224:225], v[224:225], 1.0 op_sel_hi:[1,0]
	v_pk_mul_f32 v[226:227], v[194:195], v[226:227]
	v_pk_mul_f32 v[224:225], v[192:193], v[224:225]
	ds_write_b128 v184, v[224:227] offset:32768
	ds_write_b128 v185, v[244:247] offset:32768
	s_waitcnt vmcnt(62)
	v_cvt_f32_f16_sdwa v153, v140 dst_sel:DWORD dst_unused:UNUSED_PAD src0_sel:WORD_1
	v_cvt_f32_f16_sdwa v149, v138 dst_sel:DWORD dst_unused:UNUSED_PAD src0_sel:WORD_1
	v_cvt_f32_f16_e32 v152, v140
	v_cvt_f32_f16_sdwa v155, v141 dst_sel:DWORD dst_unused:UNUSED_PAD src0_sel:WORD_1
	v_cvt_f32_f16_e32 v148, v138
	v_cvt_f32_f16_sdwa v151, v139 dst_sel:DWORD dst_unused:UNUSED_PAD src0_sel:WORD_1
	v_cvt_f32_f16_e32 v154, v141
	v_cvt_f32_f16_e32 v150, v139
	s_waitcnt vmcnt(61)
	v_cvt_f32_f16_sdwa v139, v134 dst_sel:DWORD dst_unused:UNUSED_PAD src0_sel:WORD_1
	v_cvt_f32_f16_sdwa v141, v135 dst_sel:DWORD dst_unused:UNUSED_PAD src0_sel:WORD_1
	s_mov_b64 s[6:7], 0x8c00000
	v_mov_b32_e32 v74, v153
	v_mov_b32_e32 v75, v149
	v_cvt_f32_f16_e32 v138, v134
	v_cvt_f32_f16_e32 v140, v135
	v_lshl_add_u64 v[2:3], v[136:137], 0, s[6:7]
	v_mov_b32_e32 v4, v152
	v_mov_b32_e32 v5, v148
	v_pk_mul_f32 v[74:75], v[74:75], v[74:75]
	v_mov_b32_e32 v136, v155
	v_mov_b32_e32 v137, v151
	v_pk_fma_f32 v[4:5], v[4:5], v[4:5], v[74:75]
	v_mov_b32_e32 v74, v154
	v_mov_b32_e32 v75, v150
	v_pk_mul_f32 v[136:137], v[136:137], v[136:137]
	v_mov_b32_e32 v134, v139
	v_pk_fma_f32 v[74:75], v[74:75], v[74:75], v[136:137]
	v_mov_b32_e32 v135, v141
	s_waitcnt vmcnt(60)
	v_cvt_f32_f16_sdwa v143, v132 dst_sel:DWORD dst_unused:UNUSED_PAD src0_sel:WORD_1
	v_pk_add_f32 v[4:5], v[4:5], v[74:75]
	v_mov_b32_e32 v74, v138
	v_mov_b32_e32 v75, v140
	v_pk_mul_f32 v[134:135], v[134:135], v[134:135]
	v_cvt_f32_f16_e32 v142, v132
	v_cvt_f32_f16_sdwa v145, v133 dst_sel:DWORD dst_unused:UNUSED_PAD src0_sel:WORD_1
	v_pk_fma_f32 v[74:75], v[74:75], v[74:75], v[134:135]
	v_cvt_f32_f16_e32 v144, v133
	s_waitcnt vmcnt(59)
	v_cvt_f32_f16_sdwa v133, v130 dst_sel:DWORD dst_unused:UNUSED_PAD src0_sel:WORD_1
	v_cvt_f32_f16_e32 v132, v130
	v_cvt_f32_f16_sdwa v135, v131 dst_sel:DWORD dst_unused:UNUSED_PAD src0_sel:WORD_1
	v_cvt_f32_f16_e32 v134, v131
	v_mul_f32_e32 v0, v143, v143
	v_pk_fma_f32 v[136:137], v[142:143], v[142:143], v[0:1] op_sel_hi:[1,1,0]
	v_mul_f32_e32 v0, v145, v145
	v_pk_add_f32 v[4:5], v[4:5], v[4:5] op_sel:[0,1] op_sel_hi:[1,0]
	v_pk_add_f32 v[74:75], v[74:75], v[74:75] op_sel:[0,1] op_sel_hi:[1,0]
	v_pk_fma_f32 v[156:157], v[144:145], v[144:145], v[0:1] op_sel_hi:[1,1,0]
	v_pk_mul_f32 v[130:131], v[132:133], v[132:133]
	v_pk_mul_f32 v[158:159], v[134:135], v[134:135]
	v_mov_b32_e32 v5, v130
	v_mov_b32_e32 v75, v131
	v_mov_b32_e32 v137, v158
	v_mov_b32_e32 v157, v159
	v_pk_add_f32 v[4:5], v[4:5], v[74:75]
	v_pk_add_f32 v[74:75], v[136:137], v[156:157]
	s_waitcnt vmcnt(58)
	v_cvt_f32_f16_sdwa v131, v128 dst_sel:DWORD dst_unused:UNUSED_PAD src0_sel:WORD_1
	v_cvt_f32_f16_sdwa v137, v129 dst_sel:DWORD dst_unused:UNUSED_PAD src0_sel:WORD_1
	v_cvt_f32_f16_e32 v130, v128
	v_cvt_f32_f16_e32 v136, v129
	v_pk_add_f32 v[4:5], v[4:5], v[74:75]
	v_mov_b32_e32 v74, v131
	v_mov_b32_e32 v75, v137
	v_pk_add_f32 v[156:157], v[4:5], v[4:5] op_sel:[0,1] op_sel_hi:[1,0]
	v_mov_b32_e32 v4, v130
	v_mov_b32_e32 v5, v136
	v_pk_mul_f32 v[74:75], v[74:75], v[74:75]
	s_waitcnt vmcnt(57)
	v_cvt_f32_f16_sdwa v129, v127 dst_sel:DWORD dst_unused:UNUSED_PAD src0_sel:WORD_1
	v_pk_fma_f32 v[4:5], v[4:5], v[4:5], v[74:75]
	v_cvt_f32_f16_e32 v128, v127
	v_pk_add_f32 v[158:159], v[4:5], v[4:5] op_sel:[0,1] op_sel_hi:[1,0]
	v_cvt_f32_f16_sdwa v5, v126 dst_sel:DWORD dst_unused:UNUSED_PAD src0_sel:WORD_1
	v_cvt_f32_f16_e32 v4, v126
	s_waitcnt vmcnt(56)
	v_cvt_f32_f16_sdwa v75, v124 dst_sel:DWORD dst_unused:UNUSED_PAD src0_sel:WORD_1
	v_cvt_f32_f16_e32 v74, v124
	v_cvt_f32_f16_sdwa v127, v125 dst_sel:DWORD dst_unused:UNUSED_PAD src0_sel:WORD_1
	v_cvt_f32_f16_e32 v126, v125
	v_mul_f32_e32 v0, v5, v5
	v_pk_fma_f32 v[160:161], v[4:5], v[4:5], v[0:1] op_sel_hi:[1,1,0]
	v_mul_f32_e32 v0, v129, v129
	v_pk_fma_f32 v[162:163], v[128:129], v[128:129], v[0:1] op_sel_hi:[1,1,0]
	v_pk_mul_f32 v[124:125], v[74:75], v[74:75]
	v_pk_mul_f32 v[164:165], v[126:127], v[126:127]
	v_mov_b32_e32 v157, v124
	v_mov_b32_e32 v159, v125
	v_mov_b32_e32 v161, v164
	v_mov_b32_e32 v163, v165
	v_pk_add_f32 v[124:125], v[156:157], v[158:159]
	v_pk_add_f32 v[156:157], v[160:161], v[162:163]
	s_waitcnt lgkmcnt(0)
	s_barrier
	v_pk_add_f32 v[124:125], v[124:125], v[156:157]
	s_lshl_b64 s[12:13], s[10:11], 11
	v_add_f32_e32 v0, v124, v125
	s_lshl_b64 s[48:49], s[78:79], 11
	s_lshl_b64 s[40:41], s[36:37], 11
	v_add_f32_dpp v0, v0, v0 quad_perm:[1,0,3,2] row_mask:0xf bank_mask:0xf bound_ctrl:1
	s_lshl_b64 s[34:35], s[30:31], 11
	s_lshl_b64 s[28:29], s[26:27], 11
	v_add_f32_dpp v0, v0, v0 quad_perm:[2,3,0,1] row_mask:0xf bank_mask:0xf bound_ctrl:1
	s_lshl_b64 s[24:25], s[22:23], 11
	s_lshl_b64 s[20:21], s[18:19], 11
	v_add_f32_dpp v0, v0, v0 row_half_mirror row_mask:0xf bank_mask:0xf bound_ctrl:1
	s_lshl_b64 s[16:17], s[14:15], 11
	s_nop 0
	v_add_f32_dpp v0, v0, v0 row_mirror row_mask:0xf bank_mask:0xf bound_ctrl:1
	s_nop 0
	v_readlane_b32 s8, v0, 16
	v_readlane_b32 s9, v0, 48
	v_readlane_b32 s6, v0, 0
	v_readlane_b32 s7, v0, 32
	v_mov_b32_e32 v124, s8
	v_mov_b32_e32 v125, s9
	v_pk_add_f32 v[124:125], s[6:7], v[124:125]
	s_nop 0
	v_add_f32_e32 v0, v124, v125
	v_fmamk_f32 v0, v0, 0x3a000000, v252
	v_cmp_gt_f32_e32 vcc, s55, v0
	v_mul_f32_e32 v7, 0x4f800000, v0
	s_nop 0
	v_cndmask_b32_e32 v0, v0, v7, vcc
	v_sqrt_f32_e32 v7, v0
	s_nop 0
	v_add_u32_e32 v124, -1, v7
	v_fma_f32 v125, -v124, v7, v0
	v_cmp_ge_f32_e64 s[8:9], 0, v125
	v_add_u32_e32 v125, 1, v7
	s_nop 0
	v_cndmask_b32_e64 v124, v7, v124, s[8:9]
	v_fma_f32 v7, -v125, v7, v0
	v_cmp_lt_f32_e64 s[8:9], 0, v7
	s_nop 1
	v_cndmask_b32_e64 v7, v124, v125, s[8:9]
	v_mul_f32_e32 v124, 0x37800000, v7
	v_cndmask_b32_e32 v7, v7, v124, vcc
	v_cmp_class_f32_e32 vcc, v0, v253
	s_nop 1
	v_cndmask_b32_e32 v0, v7, v0, vcc
	v_div_scale_f32 v7, s[6:7], v0, v0, 1.0
	v_rcp_f32_e32 v124, v7
	s_lshl_b32 s6, s10, 1
	s_and_b32 s6, s6, 0xffffe000
	s_add_i32 s6, s6, 0
	v_fma_f32 v125, -v7, v124, 1.0
	v_fmac_f32_e32 v124, v125, v124
	v_div_scale_f32 v125, vcc, 1.0, v0, 1.0
	v_mul_f32_e32 v146, v125, v124
	v_fma_f32 v156, -v7, v146, v125
	v_fmac_f32_e32 v146, v156, v124
	v_fma_f32 v7, -v7, v146, v125
	v_div_fmas_f32 v7, v7, v124, v146
	v_div_fixup_f32 v146, v7, v0, 1.0
	v_lshlrev_b32_e32 v0, 4, v147
	v_add_u32_e32 v164, s6, v0
	v_pk_mul_f32 v[160:161], v[152:153], v[146:147] op_sel_hi:[1,0]
	v_pk_mul_f32 v[162:163], v[154:155], v[146:147] op_sel_hi:[1,0]
	ds_read_b128 v[152:155], v164
	ds_read_b128 v[156:159], v164 offset:40960
	v_lshl_add_u64 v[124:125], s[12:13], 1, v[2:3]
	v_mov_b32_e32 v7, v1
	v_lshl_add_u64 v[124:125], v[124:125], 0, v[6:7]
	v_pk_mul_f32 v[4:5], v[4:5], v[146:147] op_sel_hi:[1,0]
	s_waitcnt lgkmcnt(0)
	v_pk_fma_f32 v[154:155], v[154:155], v[162:163], v[158:159]
	v_pk_fma_f32 v[152:153], v[152:153], v[160:161], v[156:157]
	v_pk_mul_f32 v[156:157], v[148:149], v[146:147] op_sel_hi:[1,0]
	v_cvt_pk_bf16_f32 v152, v152, v153
	v_cvt_pk_bf16_f32 v153, v154, v155
	global_store_dwordx2 v[124:125], v[152:153], off nt
	v_pk_mul_f32 v[158:159], v[150:151], v[146:147] op_sel_hi:[1,0]
	ds_read_b128 v[148:151], v164 offset:1024
	ds_read_b128 v[152:155], v164 offset:41984
	s_waitcnt lgkmcnt(0)
	v_pk_fma_f32 v[150:151], v[150:151], v[158:159], v[154:155]
	v_pk_fma_f32 v[148:149], v[148:149], v[156:157], v[152:153]
	v_pk_mul_f32 v[152:153], v[138:139], v[146:147] op_sel_hi:[1,0]
	v_cvt_pk_bf16_f32 v148, v148, v149
	v_cvt_pk_bf16_f32 v149, v150, v151
	global_store_dwordx2 v[124:125], v[148:149], off offset:512 nt
	v_pk_mul_f32 v[154:155], v[140:141], v[146:147] op_sel_hi:[1,0]
	ds_read_b128 v[138:141], v164 offset:2048
	ds_read_b128 v[148:151], v164 offset:43008
	s_waitcnt lgkmcnt(0)
	v_pk_fma_f32 v[140:141], v[140:141], v[154:155], v[150:151]
	v_pk_fma_f32 v[138:139], v[138:139], v[152:153], v[148:149]
	v_pk_mul_f32 v[148:149], v[142:143], v[146:147] op_sel_hi:[1,0]
	v_cvt_pk_bf16_f32 v138, v138, v139
	v_cvt_pk_bf16_f32 v139, v140, v141
	global_store_dwordx2 v[124:125], v[138:139], off offset:1024 nt
	v_pk_mul_f32 v[150:151], v[144:145], v[146:147] op_sel_hi:[1,0]
	ds_read_b128 v[138:141], v164 offset:3072
	ds_read_b128 v[142:145], v164 offset:44032
	s_waitcnt lgkmcnt(0)
	v_pk_fma_f32 v[140:141], v[150:151], v[140:141], v[144:145]
	v_pk_fma_f32 v[138:139], v[148:149], v[138:139], v[142:143]
	v_pk_mul_f32 v[142:143], v[132:133], v[146:147] op_sel_hi:[1,0]
	v_cvt_pk_bf16_f32 v138, v138, v139
	v_cvt_pk_bf16_f32 v139, v140, v141
	global_store_dwordx2 v[124:125], v[138:139], off offset:1536 nt
	v_pk_mul_f32 v[144:145], v[134:135], v[146:147] op_sel_hi:[1,0]
	ds_read_b128 v[132:135], v164 offset:4096
	ds_read_b128 v[138:141], v164 offset:45056
	s_waitcnt lgkmcnt(0)
	v_pk_fma_f32 v[134:135], v[144:145], v[134:135], v[140:141]
	v_pk_fma_f32 v[132:133], v[142:143], v[132:133], v[138:139]
	v_pk_mul_f32 v[138:139], v[130:131], v[146:147] op_sel_hi:[1,0]
	v_cvt_pk_bf16_f32 v132, v132, v133
	v_cvt_pk_bf16_f32 v133, v134, v135
	global_store_dwordx2 v[124:125], v[132:133], off offset:2048 nt
	v_pk_mul_f32 v[140:141], v[136:137], v[146:147] op_sel_hi:[1,0]
	ds_read_b128 v[130:133], v164 offset:5120
	ds_read_b128 v[134:137], v164 offset:46080
	s_waitcnt lgkmcnt(0)
	v_pk_fma_f32 v[132:133], v[140:141], v[132:133], v[136:137]
	v_pk_fma_f32 v[130:131], v[138:139], v[130:131], v[134:135]
	v_pk_mul_f32 v[136:137], v[128:129], v[146:147] op_sel_hi:[1,0]
	v_cvt_pk_bf16_f32 v130, v130, v131
	v_cvt_pk_bf16_f32 v131, v132, v133
	global_store_dwordx2 v[124:125], v[130:131], off offset:2560 nt
	ds_read_b128 v[128:131], v164 offset:6144
	ds_read_b128 v[132:135], v164 offset:47104
	s_waitcnt vmcnt(61)
	v_cvt_f32_f16_sdwa v139, v123 dst_sel:DWORD dst_unused:UNUSED_PAD src0_sel:WORD_1
	v_cvt_f32_f16_e32 v138, v123
	s_waitcnt vmcnt(59)
	v_cvt_f32_f16_sdwa v123, v118 dst_sel:DWORD dst_unused:UNUSED_PAD src0_sel:WORD_1
	s_waitcnt lgkmcnt(0)
	v_pk_fma_f32 v[130:131], v[136:137], v[130:131], v[134:135]
	v_pk_fma_f32 v[4:5], v[4:5], v[128:129], v[132:133]
	v_cvt_f32_f16_sdwa v137, v122 dst_sel:DWORD dst_unused:UNUSED_PAD src0_sel:WORD_1
	v_cvt_pk_bf16_f32 v4, v4, v5
	v_cvt_pk_bf16_f32 v5, v130, v131
	global_store_dwordx2 v[124:125], v[4:5], off offset:3072 nt
	v_pk_mul_f32 v[4:5], v[74:75], v[146:147] op_sel_hi:[1,0]
	v_pk_mul_f32 v[74:75], v[126:127], v[146:147] op_sel_hi:[1,0]
	ds_read_b128 v[126:129], v164 offset:7168
	ds_read_b128 v[130:133], v164 offset:48128
	v_cvt_f32_f16_e32 v136, v122
	v_cvt_f32_f16_sdwa v135, v121 dst_sel:DWORD dst_unused:UNUSED_PAD src0_sel:WORD_1
	v_cvt_f32_f16_e32 v134, v121
	v_cvt_f32_f16_e32 v122, v118
	s_waitcnt lgkmcnt(0)
	v_pk_fma_f32 v[74:75], v[74:75], v[128:129], v[132:133]
	v_cvt_f32_f16_sdwa v133, v120 dst_sel:DWORD dst_unused:UNUSED_PAD src0_sel:WORD_1
	v_pk_fma_f32 v[4:5], v[4:5], v[126:127], v[130:131]
	v_cvt_f32_f16_e32 v132, v120
	v_cvt_pk_bf16_f32 v4, v4, v5
	v_cvt_pk_bf16_f32 v5, v74, v75
	global_store_dwordx2 v[124:125], v[4:5], off offset:3584 nt
	v_cvt_f32_f16_sdwa v125, v119 dst_sel:DWORD dst_unused:UNUSED_PAD src0_sel:WORD_1
	s_waitcnt vmcnt(60)
	v_cvt_f32_f16_sdwa v127, v116 dst_sel:DWORD dst_unused:UNUSED_PAD src0_sel:WORD_1
	v_mov_b32_e32 v74, v137
	v_mov_b32_e32 v75, v133
	v_cvt_f32_f16_e32 v124, v119
	v_cvt_f32_f16_e32 v126, v116
	v_cvt_f32_f16_sdwa v129, v117 dst_sel:DWORD dst_unused:UNUSED_PAD src0_sel:WORD_1
	v_mov_b32_e32 v4, v136
	v_mov_b32_e32 v5, v132
	v_pk_mul_f32 v[74:75], v[74:75], v[74:75]
	v_mov_b32_e32 v120, v139
	v_mov_b32_e32 v121, v135
	v_cvt_f32_f16_e32 v128, v117
	v_pk_fma_f32 v[4:5], v[4:5], v[4:5], v[74:75]
	v_mov_b32_e32 v74, v138
	v_mov_b32_e32 v75, v134
	v_pk_mul_f32 v[120:121], v[120:121], v[120:121]
	v_mov_b32_e32 v118, v123
	v_pk_fma_f32 v[74:75], v[74:75], v[74:75], v[120:121]
	v_mov_b32_e32 v119, v125
	v_mul_f32_e32 v116, v127, v127
	v_pk_add_f32 v[4:5], v[4:5], v[74:75]
	v_mov_b32_e32 v74, v122
	v_mov_b32_e32 v75, v124
	v_pk_mul_f32 v[118:119], v[118:119], v[118:119]
	v_pk_fma_f32 v[120:121], v[126:127], v[126:127], v[116:117] op_sel_hi:[1,1,0]
	v_mul_f32_e32 v116, v129, v129
	v_pk_fma_f32 v[74:75], v[74:75], v[74:75], v[118:119]
	v_pk_fma_f32 v[130:131], v[128:129], v[128:129], v[116:117] op_sel_hi:[1,1,0]
	s_waitcnt vmcnt(59)
	v_cvt_f32_f16_sdwa v117, v114 dst_sel:DWORD dst_unused:UNUSED_PAD src0_sel:WORD_1
	v_cvt_f32_f16_e32 v116, v114
	v_cvt_f32_f16_sdwa v119, v115 dst_sel:DWORD dst_unused:UNUSED_PAD src0_sel:WORD_1
	v_cvt_f32_f16_e32 v118, v115
	v_pk_add_f32 v[4:5], v[4:5], v[4:5] op_sel:[0,1] op_sel_hi:[1,0]
	v_pk_add_f32 v[74:75], v[74:75], v[74:75] op_sel:[0,1] op_sel_hi:[1,0]
	v_pk_mul_f32 v[114:115], v[116:117], v[116:117]
	v_pk_mul_f32 v[140:141], v[118:119], v[118:119]
	v_mov_b32_e32 v5, v114
	v_mov_b32_e32 v75, v115
	v_mov_b32_e32 v121, v140
	v_mov_b32_e32 v131, v141
	v_pk_add_f32 v[4:5], v[4:5], v[74:75]
	v_pk_add_f32 v[74:75], v[120:121], v[130:131]
	s_waitcnt vmcnt(58)
	v_cvt_f32_f16_sdwa v115, v112 dst_sel:DWORD dst_unused:UNUSED_PAD src0_sel:WORD_1
	v_cvt_f32_f16_sdwa v121, v113 dst_sel:DWORD dst_unused:UNUSED_PAD src0_sel:WORD_1
	v_cvt_f32_f16_e32 v114, v112
	v_cvt_f32_f16_e32 v120, v113
	v_pk_add_f32 v[4:5], v[4:5], v[74:75]
	v_mov_b32_e32 v74, v115
	v_mov_b32_e32 v75, v121
	v_pk_add_f32 v[130:131], v[4:5], v[4:5] op_sel:[0,1] op_sel_hi:[1,0]
	v_mov_b32_e32 v4, v114
	v_mov_b32_e32 v5, v120
	v_pk_mul_f32 v[74:75], v[74:75], v[74:75]
	s_waitcnt vmcnt(57)
	v_cvt_f32_f16_sdwa v113, v111 dst_sel:DWORD dst_unused:UNUSED_PAD src0_sel:WORD_1
	v_pk_fma_f32 v[4:5], v[4:5], v[4:5], v[74:75]
	v_cvt_f32_f16_e32 v112, v111
	v_pk_add_f32 v[140:141], v[4:5], v[4:5] op_sel:[0,1] op_sel_hi:[1,0]
	v_cvt_f32_f16_sdwa v5, v110 dst_sel:DWORD dst_unused:UNUSED_PAD src0_sel:WORD_1
	v_cvt_f32_f16_e32 v4, v110
	s_waitcnt vmcnt(56)
	v_cvt_f32_f16_sdwa v111, v109 dst_sel:DWORD dst_unused:UNUSED_PAD src0_sel:WORD_1
	v_cvt_f32_f16_e32 v110, v109
	v_mul_f32_e32 v74, v5, v5
	v_pk_fma_f32 v[142:143], v[4:5], v[4:5], v[74:75] op_sel_hi:[1,1,0]
	v_mul_f32_e32 v74, v113, v113
	v_pk_fma_f32 v[144:145], v[112:113], v[112:113], v[74:75] op_sel_hi:[1,1,0]
	v_cvt_f32_f16_sdwa v75, v108 dst_sel:DWORD dst_unused:UNUSED_PAD src0_sel:WORD_1
	v_cvt_f32_f16_e32 v74, v108
	v_pk_mul_f32 v[148:149], v[110:111], v[110:111]
	v_pk_mul_f32 v[108:109], v[74:75], v[74:75]
	s_nop 0
	v_mov_b32_e32 v131, v108
	v_mov_b32_e32 v141, v109
	v_mov_b32_e32 v143, v148
	v_mov_b32_e32 v145, v149
	v_pk_add_f32 v[108:109], v[130:131], v[140:141]
	v_pk_add_f32 v[130:131], v[142:143], v[144:145]
	s_nop 0
	v_pk_add_f32 v[108:109], v[108:109], v[130:131]
	s_nop 0
	v_add_f32_e32 v108, v108, v109
	s_nop 1
	v_add_f32_dpp v108, v108, v108 quad_perm:[1,0,3,2] row_mask:0xf bank_mask:0xf bound_ctrl:1
	s_nop 1
	v_add_f32_dpp v108, v108, v108 quad_perm:[2,3,0,1] row_mask:0xf bank_mask:0xf bound_ctrl:1
	s_nop 1
	v_add_f32_dpp v108, v108, v108 row_half_mirror row_mask:0xf bank_mask:0xf bound_ctrl:1
	s_nop 1
	v_add_f32_dpp v108, v108, v108 row_mirror row_mask:0xf bank_mask:0xf bound_ctrl:1
	s_nop 0
	v_readlane_b32 s8, v108, 16
	v_readlane_b32 s9, v108, 48
	v_readlane_b32 s6, v108, 0
	v_readlane_b32 s7, v108, 32
	v_mov_b32_e32 v108, s8
	v_mov_b32_e32 v109, s9
	v_pk_add_f32 v[108:109], s[6:7], v[108:109]
	s_nop 0
	v_add_f32_e32 v108, v108, v109
	v_fmamk_f32 v108, v108, 0x3a000000, v252
	v_cmp_gt_f32_e32 vcc, s55, v108
	v_mul_f32_e32 v109, 0x4f800000, v108
	s_nop 0
	v_cndmask_b32_e32 v108, v108, v109, vcc
	v_sqrt_f32_e32 v109, v108
	s_nop 0
	v_add_u32_e32 v130, -1, v109
	v_fma_f32 v131, -v130, v109, v108
	v_cmp_ge_f32_e64 s[8:9], 0, v131
	v_add_u32_e32 v131, 1, v109
	s_nop 0
	v_cndmask_b32_e64 v130, v109, v130, s[8:9]
	v_fma_f32 v109, -v131, v109, v108
	v_cmp_lt_f32_e64 s[8:9], 0, v109
	s_nop 1
	v_cndmask_b32_e64 v109, v130, v131, s[8:9]
	v_mul_f32_e32 v130, 0x37800000, v109
	v_cndmask_b32_e32 v109, v109, v130, vcc
	v_cmp_class_f32_e32 vcc, v108, v253
	s_nop 1
	v_cndmask_b32_e32 v108, v109, v108, vcc
	v_div_scale_f32 v109, s[6:7], v108, v108, 1.0
	v_rcp_f32_e32 v130, v109
	s_lshl_b32 s6, s78, 1
	s_and_b32 s6, s6, 0xffffe000
	s_add_i32 s6, s6, 0
	v_fma_f32 v131, -v109, v130, 1.0
	v_fmac_f32_e32 v130, v131, v130
	v_div_scale_f32 v131, vcc, 1.0, v108, 1.0
	v_mul_f32_e32 v140, v131, v130
	v_fma_f32 v141, -v109, v140, v131
	v_fmac_f32_e32 v140, v141, v130
	v_fma_f32 v109, -v109, v140, v131
	v_div_fmas_f32 v109, v109, v130, v140
	v_div_fixup_f32 v130, v109, v108, 1.0
	v_pk_mul_f32 v[144:145], v[136:137], v[130:131] op_sel_hi:[1,0]
	v_pk_mul_f32 v[148:149], v[138:139], v[130:131] op_sel_hi:[1,0]
	v_add_u32_e32 v131, s6, v0
	ds_read_b128 v[136:139], v131
	ds_read_b128 v[140:143], v131 offset:40960
	v_lshl_add_u64 v[108:109], s[48:49], 1, v[2:3]
	v_lshl_add_u64 v[108:109], v[108:109], 0, v[6:7]
	v_pk_mul_f32 v[4:5], v[4:5], v[130:131] op_sel_hi:[1,0]
	s_waitcnt lgkmcnt(0)
	v_pk_fma_f32 v[138:139], v[138:139], v[148:149], v[142:143]
	v_pk_fma_f32 v[136:137], v[136:137], v[144:145], v[140:141]
	v_pk_mul_f32 v[140:141], v[132:133], v[130:131] op_sel_hi:[1,0]
	v_cvt_pk_bf16_f32 v136, v136, v137
	v_cvt_pk_bf16_f32 v137, v138, v139
	global_store_dwordx2 v[108:109], v[136:137], off nt
	v_pk_mul_f32 v[142:143], v[134:135], v[130:131] op_sel_hi:[1,0]
	ds_read_b128 v[132:135], v131 offset:1024
	ds_read_b128 v[136:139], v131 offset:41984
	s_waitcnt lgkmcnt(0)
	v_pk_fma_f32 v[134:135], v[134:135], v[142:143], v[138:139]
	v_pk_fma_f32 v[132:133], v[132:133], v[140:141], v[136:137]
	v_pk_mul_f32 v[136:137], v[122:123], v[130:131] op_sel_hi:[1,0]
	v_cvt_pk_bf16_f32 v132, v132, v133
	v_cvt_pk_bf16_f32 v133, v134, v135
	global_store_dwordx2 v[108:109], v[132:133], off offset:512 nt
	v_pk_mul_f32 v[138:139], v[124:125], v[130:131] op_sel_hi:[1,0]
	ds_read_b128 v[122:125], v131 offset:2048
	ds_read_b128 v[132:135], v131 offset:43008
	s_waitcnt lgkmcnt(0)
	v_pk_fma_f32 v[124:125], v[124:125], v[138:139], v[134:135]
	v_pk_fma_f32 v[122:123], v[122:123], v[136:137], v[132:133]
	v_pk_mul_f32 v[132:133], v[126:127], v[130:131] op_sel_hi:[1,0]
	v_cvt_pk_bf16_f32 v122, v122, v123
	v_cvt_pk_bf16_f32 v123, v124, v125
	global_store_dwordx2 v[108:109], v[122:123], off offset:1024 nt
	v_pk_mul_f32 v[134:135], v[128:129], v[130:131] op_sel_hi:[1,0]
	ds_read_b128 v[122:125], v131 offset:3072
	ds_read_b128 v[126:129], v131 offset:44032
	s_waitcnt lgkmcnt(0)
	v_pk_fma_f32 v[124:125], v[134:135], v[124:125], v[128:129]
	v_pk_fma_f32 v[122:123], v[132:133], v[122:123], v[126:127]
	v_pk_mul_f32 v[126:127], v[116:117], v[130:131] op_sel_hi:[1,0]
	v_cvt_pk_bf16_f32 v122, v122, v123
	v_cvt_pk_bf16_f32 v123, v124, v125
	global_store_dwordx2 v[108:109], v[122:123], off offset:1536 nt
	v_pk_mul_f32 v[128:129], v[118:119], v[130:131] op_sel_hi:[1,0]
	ds_read_b128 v[116:119], v131 offset:4096
	ds_read_b128 v[122:125], v131 offset:45056
	s_waitcnt lgkmcnt(0)
	v_pk_fma_f32 v[118:119], v[128:129], v[118:119], v[124:125]
	v_pk_fma_f32 v[116:117], v[126:127], v[116:117], v[122:123]
	v_pk_mul_f32 v[122:123], v[114:115], v[130:131] op_sel_hi:[1,0]
	v_cvt_pk_bf16_f32 v116, v116, v117
	v_cvt_pk_bf16_f32 v117, v118, v119
	global_store_dwordx2 v[108:109], v[116:117], off offset:2048 nt
	v_pk_mul_f32 v[124:125], v[120:121], v[130:131] op_sel_hi:[1,0]
	ds_read_b128 v[114:117], v131 offset:5120
	ds_read_b128 v[118:121], v131 offset:46080
	s_waitcnt lgkmcnt(0)
	v_pk_fma_f32 v[116:117], v[124:125], v[116:117], v[120:121]
	v_pk_fma_f32 v[114:115], v[122:123], v[114:115], v[118:119]
	v_pk_mul_f32 v[120:121], v[112:113], v[130:131] op_sel_hi:[1,0]
	v_cvt_pk_bf16_f32 v114, v114, v115
	v_cvt_pk_bf16_f32 v115, v116, v117
	global_store_dwordx2 v[108:109], v[114:115], off offset:2560 nt
	ds_read_b128 v[112:115], v131 offset:6144
	ds_read_b128 v[116:119], v131 offset:47104
	s_waitcnt vmcnt(61)
	v_cvt_f32_f16_sdwa v123, v107 dst_sel:DWORD dst_unused:UNUSED_PAD src0_sel:WORD_1
	v_cvt_f32_f16_e32 v122, v107
	s_waitcnt vmcnt(59)
	v_cvt_f32_f16_sdwa v107, v102 dst_sel:DWORD dst_unused:UNUSED_PAD src0_sel:WORD_1
	s_waitcnt lgkmcnt(0)
	v_pk_fma_f32 v[114:115], v[120:121], v[114:115], v[118:119]
	v_pk_fma_f32 v[4:5], v[4:5], v[112:113], v[116:117]
	v_cvt_f32_f16_sdwa v121, v106 dst_sel:DWORD dst_unused:UNUSED_PAD src0_sel:WORD_1
	v_cvt_pk_bf16_f32 v4, v4, v5
	v_cvt_pk_bf16_f32 v5, v114, v115
	global_store_dwordx2 v[108:109], v[4:5], off offset:3072 nt
	v_pk_mul_f32 v[4:5], v[74:75], v[130:131] op_sel_hi:[1,0]
	v_pk_mul_f32 v[74:75], v[110:111], v[130:131] op_sel_hi:[1,0]
	ds_read_b128 v[110:113], v131 offset:7168
	ds_read_b128 v[114:117], v131 offset:48128
	v_cvt_f32_f16_e32 v120, v106
	v_cvt_f32_f16_sdwa v119, v105 dst_sel:DWORD dst_unused:UNUSED_PAD src0_sel:WORD_1
	v_cvt_f32_f16_e32 v118, v105
	v_cvt_f32_f16_e32 v106, v102
	s_waitcnt lgkmcnt(0)
	v_pk_fma_f32 v[74:75], v[74:75], v[112:113], v[116:117]
	v_cvt_f32_f16_sdwa v117, v104 dst_sel:DWORD dst_unused:UNUSED_PAD src0_sel:WORD_1
	v_pk_fma_f32 v[4:5], v[4:5], v[110:111], v[114:115]
	v_cvt_f32_f16_e32 v116, v104
	v_cvt_pk_bf16_f32 v4, v4, v5
	v_cvt_pk_bf16_f32 v5, v74, v75
	global_store_dwordx2 v[108:109], v[4:5], off offset:3584 nt
	v_cvt_f32_f16_sdwa v109, v103 dst_sel:DWORD dst_unused:UNUSED_PAD src0_sel:WORD_1
	s_waitcnt vmcnt(60)
	v_cvt_f32_f16_sdwa v111, v100 dst_sel:DWORD dst_unused:UNUSED_PAD src0_sel:WORD_1
	v_mov_b32_e32 v74, v121
	v_mov_b32_e32 v75, v117
	v_cvt_f32_f16_e32 v108, v103
	v_cvt_f32_f16_e32 v110, v100
	v_cvt_f32_f16_sdwa v113, v101 dst_sel:DWORD dst_unused:UNUSED_PAD src0_sel:WORD_1
	v_mov_b32_e32 v4, v120
	v_mov_b32_e32 v5, v116
	v_pk_mul_f32 v[74:75], v[74:75], v[74:75]
	v_mov_b32_e32 v104, v123
	v_mov_b32_e32 v105, v119
	v_cvt_f32_f16_e32 v112, v101
	v_pk_fma_f32 v[4:5], v[4:5], v[4:5], v[74:75]
	v_mov_b32_e32 v74, v122
	v_mov_b32_e32 v75, v118
	v_pk_mul_f32 v[104:105], v[104:105], v[104:105]
	v_mov_b32_e32 v102, v107
	v_pk_fma_f32 v[74:75], v[74:75], v[74:75], v[104:105]
	v_mov_b32_e32 v103, v109
	v_mul_f32_e32 v100, v111, v111
	v_pk_add_f32 v[4:5], v[4:5], v[74:75]
	v_mov_b32_e32 v74, v106
	v_mov_b32_e32 v75, v108
	v_pk_mul_f32 v[102:103], v[102:103], v[102:103]
	v_pk_fma_f32 v[104:105], v[110:111], v[110:111], v[100:101] op_sel_hi:[1,1,0]
	v_mul_f32_e32 v100, v113, v113
	v_pk_fma_f32 v[74:75], v[74:75], v[74:75], v[102:103]
	v_pk_fma_f32 v[114:115], v[112:113], v[112:113], v[100:101] op_sel_hi:[1,1,0]
	s_waitcnt vmcnt(59)
	v_cvt_f32_f16_sdwa v101, v98 dst_sel:DWORD dst_unused:UNUSED_PAD src0_sel:WORD_1
	v_cvt_f32_f16_e32 v100, v98
	v_cvt_f32_f16_sdwa v103, v99 dst_sel:DWORD dst_unused:UNUSED_PAD src0_sel:WORD_1
	v_cvt_f32_f16_e32 v102, v99
	v_pk_add_f32 v[4:5], v[4:5], v[4:5] op_sel:[0,1] op_sel_hi:[1,0]
	v_pk_add_f32 v[74:75], v[74:75], v[74:75] op_sel:[0,1] op_sel_hi:[1,0]
	v_pk_mul_f32 v[98:99], v[100:101], v[100:101]
	v_pk_mul_f32 v[124:125], v[102:103], v[102:103]
	v_mov_b32_e32 v5, v98
	v_mov_b32_e32 v75, v99
	v_mov_b32_e32 v105, v124
	v_mov_b32_e32 v115, v125
	v_pk_add_f32 v[4:5], v[4:5], v[74:75]
	v_pk_add_f32 v[74:75], v[104:105], v[114:115]
	s_waitcnt vmcnt(58)
	v_cvt_f32_f16_sdwa v99, v96 dst_sel:DWORD dst_unused:UNUSED_PAD src0_sel:WORD_1
	v_cvt_f32_f16_sdwa v105, v97 dst_sel:DWORD dst_unused:UNUSED_PAD src0_sel:WORD_1
	v_cvt_f32_f16_e32 v98, v96
	v_cvt_f32_f16_e32 v104, v97
	v_pk_add_f32 v[4:5], v[4:5], v[74:75]
	v_mov_b32_e32 v74, v99
	v_mov_b32_e32 v75, v105
	v_pk_add_f32 v[114:115], v[4:5], v[4:5] op_sel:[0,1] op_sel_hi:[1,0]
	v_mov_b32_e32 v4, v98
	v_mov_b32_e32 v5, v104
	v_pk_mul_f32 v[74:75], v[74:75], v[74:75]
	s_waitcnt vmcnt(57)
	v_cvt_f32_f16_sdwa v97, v95 dst_sel:DWORD dst_unused:UNUSED_PAD src0_sel:WORD_1
	v_pk_fma_f32 v[4:5], v[4:5], v[4:5], v[74:75]
	v_cvt_f32_f16_e32 v96, v95
	v_pk_add_f32 v[124:125], v[4:5], v[4:5] op_sel:[0,1] op_sel_hi:[1,0]
	v_cvt_f32_f16_sdwa v5, v94 dst_sel:DWORD dst_unused:UNUSED_PAD src0_sel:WORD_1
	v_cvt_f32_f16_e32 v4, v94
	s_waitcnt vmcnt(56)
	v_cvt_f32_f16_sdwa v95, v93 dst_sel:DWORD dst_unused:UNUSED_PAD src0_sel:WORD_1
	v_cvt_f32_f16_e32 v94, v93
	v_mul_f32_e32 v74, v5, v5
	v_pk_fma_f32 v[126:127], v[4:5], v[4:5], v[74:75] op_sel_hi:[1,1,0]
	v_mul_f32_e32 v74, v97, v97
	v_pk_fma_f32 v[128:129], v[96:97], v[96:97], v[74:75] op_sel_hi:[1,1,0]
	v_cvt_f32_f16_sdwa v75, v92 dst_sel:DWORD dst_unused:UNUSED_PAD src0_sel:WORD_1
	v_cvt_f32_f16_e32 v74, v92
	v_pk_mul_f32 v[130:131], v[94:95], v[94:95]
	v_pk_mul_f32 v[92:93], v[74:75], v[74:75]
	s_nop 0
	v_mov_b32_e32 v115, v92
	v_mov_b32_e32 v125, v93
	v_mov_b32_e32 v127, v130
	v_mov_b32_e32 v129, v131
	v_pk_add_f32 v[92:93], v[114:115], v[124:125]
	v_pk_add_f32 v[114:115], v[126:127], v[128:129]
	s_nop 0
	v_pk_add_f32 v[92:93], v[92:93], v[114:115]
	s_nop 0
	v_add_f32_e32 v92, v92, v93
	s_nop 1
	v_add_f32_dpp v92, v92, v92 quad_perm:[1,0,3,2] row_mask:0xf bank_mask:0xf bound_ctrl:1
	s_nop 1
	v_add_f32_dpp v92, v92, v92 quad_perm:[2,3,0,1] row_mask:0xf bank_mask:0xf bound_ctrl:1
	s_nop 1
	v_add_f32_dpp v92, v92, v92 row_half_mirror row_mask:0xf bank_mask:0xf bound_ctrl:1
	s_nop 1
	v_add_f32_dpp v92, v92, v92 row_mirror row_mask:0xf bank_mask:0xf bound_ctrl:1
	s_nop 0
	v_readlane_b32 s8, v92, 16
	v_readlane_b32 s9, v92, 48
	v_readlane_b32 s6, v92, 0
	v_readlane_b32 s7, v92, 32
	v_mov_b32_e32 v92, s8
	v_mov_b32_e32 v93, s9
	v_pk_add_f32 v[92:93], s[6:7], v[92:93]
	s_nop 0
	v_add_f32_e32 v92, v92, v93
	v_fmamk_f32 v92, v92, 0x3a000000, v252
	v_cmp_gt_f32_e32 vcc, s55, v92
	v_mul_f32_e32 v93, 0x4f800000, v92
	s_nop 0
	v_cndmask_b32_e32 v92, v92, v93, vcc
	v_sqrt_f32_e32 v93, v92
	s_nop 0
	v_add_u32_e32 v114, -1, v93
	v_fma_f32 v115, -v114, v93, v92
	v_cmp_ge_f32_e64 s[8:9], 0, v115
	v_add_u32_e32 v115, 1, v93
	s_nop 0
	v_cndmask_b32_e64 v114, v93, v114, s[8:9]
	v_fma_f32 v93, -v115, v93, v92
	v_cmp_lt_f32_e64 s[8:9], 0, v93
	s_nop 1
	v_cndmask_b32_e64 v93, v114, v115, s[8:9]
	v_mul_f32_e32 v114, 0x37800000, v93
	v_cndmask_b32_e32 v93, v93, v114, vcc
	v_cmp_class_f32_e32 vcc, v92, v253
	s_nop 1
	v_cndmask_b32_e32 v92, v93, v92, vcc
	v_div_scale_f32 v93, s[6:7], v92, v92, 1.0
	v_rcp_f32_e32 v114, v93
	s_lshl_b32 s6, s36, 1
	s_and_b32 s6, s6, 0xffffe000
	s_add_i32 s6, s6, 0
	v_fma_f32 v115, -v93, v114, 1.0
	v_fmac_f32_e32 v114, v115, v114
	v_div_scale_f32 v115, vcc, 1.0, v92, 1.0
	v_mul_f32_e32 v124, v115, v114
	v_fma_f32 v125, -v93, v124, v115
	v_fmac_f32_e32 v124, v125, v114
	v_fma_f32 v93, -v93, v124, v115
	v_div_fmas_f32 v93, v93, v114, v124
	v_div_fixup_f32 v114, v93, v92, 1.0
	v_pk_mul_f32 v[128:129], v[120:121], v[114:115] op_sel_hi:[1,0]
	v_pk_mul_f32 v[130:131], v[122:123], v[114:115] op_sel_hi:[1,0]
	v_add_u32_e32 v115, s6, v0
	ds_read_b128 v[120:123], v115
	ds_read_b128 v[124:127], v115 offset:40960
	v_lshl_add_u64 v[92:93], s[40:41], 1, v[2:3]
	v_lshl_add_u64 v[92:93], v[92:93], 0, v[6:7]
	v_pk_mul_f32 v[4:5], v[4:5], v[114:115] op_sel_hi:[1,0]
	s_waitcnt lgkmcnt(0)
	v_pk_fma_f32 v[122:123], v[122:123], v[130:131], v[126:127]
	v_pk_fma_f32 v[120:121], v[120:121], v[128:129], v[124:125]
	v_pk_mul_f32 v[124:125], v[116:117], v[114:115] op_sel_hi:[1,0]
	v_cvt_pk_bf16_f32 v120, v120, v121
	v_cvt_pk_bf16_f32 v121, v122, v123
	global_store_dwordx2 v[92:93], v[120:121], off nt
	v_pk_mul_f32 v[126:127], v[118:119], v[114:115] op_sel_hi:[1,0]
	ds_read_b128 v[116:119], v115 offset:1024
	ds_read_b128 v[120:123], v115 offset:41984
	s_waitcnt lgkmcnt(0)
	v_pk_fma_f32 v[118:119], v[118:119], v[126:127], v[122:123]
	v_pk_fma_f32 v[116:117], v[116:117], v[124:125], v[120:121]
	v_pk_mul_f32 v[120:121], v[106:107], v[114:115] op_sel_hi:[1,0]
	v_cvt_pk_bf16_f32 v116, v116, v117
	v_cvt_pk_bf16_f32 v117, v118, v119
	global_store_dwordx2 v[92:93], v[116:117], off offset:512 nt
	v_pk_mul_f32 v[122:123], v[108:109], v[114:115] op_sel_hi:[1,0]
	ds_read_b128 v[106:109], v115 offset:2048
	ds_read_b128 v[116:119], v115 offset:43008
	s_waitcnt lgkmcnt(0)
	v_pk_fma_f32 v[108:109], v[108:109], v[122:123], v[118:119]
	v_pk_fma_f32 v[106:107], v[106:107], v[120:121], v[116:117]
	v_pk_mul_f32 v[116:117], v[110:111], v[114:115] op_sel_hi:[1,0]
	v_cvt_pk_bf16_f32 v106, v106, v107
	v_cvt_pk_bf16_f32 v107, v108, v109
	global_store_dwordx2 v[92:93], v[106:107], off offset:1024 nt
	v_pk_mul_f32 v[118:119], v[112:113], v[114:115] op_sel_hi:[1,0]
	ds_read_b128 v[106:109], v115 offset:3072
	ds_read_b128 v[110:113], v115 offset:44032
	s_waitcnt lgkmcnt(0)
	v_pk_fma_f32 v[108:109], v[118:119], v[108:109], v[112:113]
	v_pk_fma_f32 v[106:107], v[116:117], v[106:107], v[110:111]
	v_pk_mul_f32 v[110:111], v[100:101], v[114:115] op_sel_hi:[1,0]
	v_cvt_pk_bf16_f32 v106, v106, v107
	v_cvt_pk_bf16_f32 v107, v108, v109
	global_store_dwordx2 v[92:93], v[106:107], off offset:1536 nt
	v_pk_mul_f32 v[112:113], v[102:103], v[114:115] op_sel_hi:[1,0]
	ds_read_b128 v[100:103], v115 offset:4096
	ds_read_b128 v[106:109], v115 offset:45056
	s_waitcnt lgkmcnt(0)
	v_pk_fma_f32 v[102:103], v[112:113], v[102:103], v[108:109]
	v_pk_fma_f32 v[100:101], v[110:111], v[100:101], v[106:107]
	v_pk_mul_f32 v[106:107], v[98:99], v[114:115] op_sel_hi:[1,0]
	v_cvt_pk_bf16_f32 v100, v100, v101
	v_cvt_pk_bf16_f32 v101, v102, v103
	global_store_dwordx2 v[92:93], v[100:101], off offset:2048 nt
	v_pk_mul_f32 v[108:109], v[104:105], v[114:115] op_sel_hi:[1,0]
	ds_read_b128 v[98:101], v115 offset:5120
	ds_read_b128 v[102:105], v115 offset:46080
	s_waitcnt lgkmcnt(0)
	v_pk_fma_f32 v[100:101], v[108:109], v[100:101], v[104:105]
	v_pk_fma_f32 v[98:99], v[106:107], v[98:99], v[102:103]
	v_pk_mul_f32 v[104:105], v[96:97], v[114:115] op_sel_hi:[1,0]
	v_cvt_pk_bf16_f32 v98, v98, v99
	v_cvt_pk_bf16_f32 v99, v100, v101
	global_store_dwordx2 v[92:93], v[98:99], off offset:2560 nt
	ds_read_b128 v[96:99], v115 offset:6144
	ds_read_b128 v[100:103], v115 offset:47104
	s_waitcnt vmcnt(61)
	v_cvt_f32_f16_sdwa v107, v91 dst_sel:DWORD dst_unused:UNUSED_PAD src0_sel:WORD_1
	v_cvt_f32_f16_e32 v106, v91
	s_waitcnt vmcnt(59)
	v_cvt_f32_f16_sdwa v91, v86 dst_sel:DWORD dst_unused:UNUSED_PAD src0_sel:WORD_1
	s_waitcnt lgkmcnt(0)
	v_pk_fma_f32 v[98:99], v[104:105], v[98:99], v[102:103]
	v_pk_fma_f32 v[4:5], v[4:5], v[96:97], v[100:101]
	v_cvt_f32_f16_sdwa v105, v90 dst_sel:DWORD dst_unused:UNUSED_PAD src0_sel:WORD_1
	v_cvt_pk_bf16_f32 v4, v4, v5
	v_cvt_pk_bf16_f32 v5, v98, v99
	global_store_dwordx2 v[92:93], v[4:5], off offset:3072 nt
	v_pk_mul_f32 v[4:5], v[74:75], v[114:115] op_sel_hi:[1,0]
	v_pk_mul_f32 v[74:75], v[94:95], v[114:115] op_sel_hi:[1,0]
	ds_read_b128 v[94:97], v115 offset:7168
	ds_read_b128 v[98:101], v115 offset:48128
	v_cvt_f32_f16_e32 v104, v90
	v_cvt_f32_f16_sdwa v103, v89 dst_sel:DWORD dst_unused:UNUSED_PAD src0_sel:WORD_1
	v_cvt_f32_f16_e32 v102, v89
	v_cvt_f32_f16_e32 v90, v86
	s_waitcnt lgkmcnt(0)
	v_pk_fma_f32 v[74:75], v[74:75], v[96:97], v[100:101]
	v_cvt_f32_f16_sdwa v101, v88 dst_sel:DWORD dst_unused:UNUSED_PAD src0_sel:WORD_1
	v_pk_fma_f32 v[4:5], v[4:5], v[94:95], v[98:99]
	v_cvt_f32_f16_e32 v100, v88
	v_cvt_pk_bf16_f32 v4, v4, v5
	v_cvt_pk_bf16_f32 v5, v74, v75
	global_store_dwordx2 v[92:93], v[4:5], off offset:3584 nt
	v_cvt_f32_f16_sdwa v93, v87 dst_sel:DWORD dst_unused:UNUSED_PAD src0_sel:WORD_1
	s_waitcnt vmcnt(60)
	v_cvt_f32_f16_sdwa v95, v84 dst_sel:DWORD dst_unused:UNUSED_PAD src0_sel:WORD_1
	v_mov_b32_e32 v74, v105
	v_mov_b32_e32 v75, v101
	v_cvt_f32_f16_e32 v92, v87
	v_cvt_f32_f16_e32 v94, v84
	v_cvt_f32_f16_sdwa v97, v85 dst_sel:DWORD dst_unused:UNUSED_PAD src0_sel:WORD_1
	v_mov_b32_e32 v4, v104
	v_mov_b32_e32 v5, v100
	v_pk_mul_f32 v[74:75], v[74:75], v[74:75]
	v_mov_b32_e32 v88, v107
	v_mov_b32_e32 v89, v103
	v_cvt_f32_f16_e32 v96, v85
	v_pk_fma_f32 v[4:5], v[4:5], v[4:5], v[74:75]
	v_mov_b32_e32 v74, v106
	v_mov_b32_e32 v75, v102
	v_pk_mul_f32 v[88:89], v[88:89], v[88:89]
	v_mov_b32_e32 v86, v91
	v_pk_fma_f32 v[74:75], v[74:75], v[74:75], v[88:89]
	v_mov_b32_e32 v87, v93
	v_mul_f32_e32 v84, v95, v95
	v_pk_add_f32 v[4:5], v[4:5], v[74:75]
	v_mov_b32_e32 v74, v90
	v_mov_b32_e32 v75, v92
	v_pk_mul_f32 v[86:87], v[86:87], v[86:87]
	v_pk_fma_f32 v[88:89], v[94:95], v[94:95], v[84:85] op_sel_hi:[1,1,0]
	v_mul_f32_e32 v84, v97, v97
	v_pk_fma_f32 v[74:75], v[74:75], v[74:75], v[86:87]
	v_pk_fma_f32 v[98:99], v[96:97], v[96:97], v[84:85] op_sel_hi:[1,1,0]
	s_waitcnt vmcnt(59)
	v_cvt_f32_f16_sdwa v85, v82 dst_sel:DWORD dst_unused:UNUSED_PAD src0_sel:WORD_1
	v_cvt_f32_f16_e32 v84, v82
	v_cvt_f32_f16_sdwa v87, v83 dst_sel:DWORD dst_unused:UNUSED_PAD src0_sel:WORD_1
	v_cvt_f32_f16_e32 v86, v83
	v_pk_add_f32 v[4:5], v[4:5], v[4:5] op_sel:[0,1] op_sel_hi:[1,0]
	v_pk_add_f32 v[74:75], v[74:75], v[74:75] op_sel:[0,1] op_sel_hi:[1,0]
	v_pk_mul_f32 v[82:83], v[84:85], v[84:85]
	v_pk_mul_f32 v[108:109], v[86:87], v[86:87]
	v_mov_b32_e32 v5, v82
	v_mov_b32_e32 v75, v83
	v_mov_b32_e32 v89, v108
	v_mov_b32_e32 v99, v109
	v_pk_add_f32 v[4:5], v[4:5], v[74:75]
	v_pk_add_f32 v[74:75], v[88:89], v[98:99]
	s_waitcnt vmcnt(58)
	v_cvt_f32_f16_sdwa v83, v80 dst_sel:DWORD dst_unused:UNUSED_PAD src0_sel:WORD_1
	v_cvt_f32_f16_sdwa v89, v81 dst_sel:DWORD dst_unused:UNUSED_PAD src0_sel:WORD_1
	v_cvt_f32_f16_e32 v82, v80
	v_cvt_f32_f16_e32 v88, v81
	v_pk_add_f32 v[4:5], v[4:5], v[74:75]
	v_mov_b32_e32 v74, v83
	v_mov_b32_e32 v75, v89
	v_pk_add_f32 v[98:99], v[4:5], v[4:5] op_sel:[0,1] op_sel_hi:[1,0]
	v_mov_b32_e32 v4, v82
	v_mov_b32_e32 v5, v88
	v_pk_mul_f32 v[74:75], v[74:75], v[74:75]
	s_waitcnt vmcnt(57)
	v_cvt_f32_f16_sdwa v81, v79 dst_sel:DWORD dst_unused:UNUSED_PAD src0_sel:WORD_1
	v_pk_fma_f32 v[4:5], v[4:5], v[4:5], v[74:75]
	v_cvt_f32_f16_e32 v80, v79
	v_pk_add_f32 v[108:109], v[4:5], v[4:5] op_sel:[0,1] op_sel_hi:[1,0]
	v_cvt_f32_f16_sdwa v5, v78 dst_sel:DWORD dst_unused:UNUSED_PAD src0_sel:WORD_1
	v_cvt_f32_f16_e32 v4, v78
	s_waitcnt vmcnt(56)
	v_cvt_f32_f16_sdwa v79, v77 dst_sel:DWORD dst_unused:UNUSED_PAD src0_sel:WORD_1
	v_cvt_f32_f16_e32 v78, v77
	v_mul_f32_e32 v74, v5, v5
	v_pk_fma_f32 v[110:111], v[4:5], v[4:5], v[74:75] op_sel_hi:[1,1,0]
	v_mul_f32_e32 v74, v81, v81
	v_pk_fma_f32 v[112:113], v[80:81], v[80:81], v[74:75] op_sel_hi:[1,1,0]
	v_cvt_f32_f16_sdwa v75, v76 dst_sel:DWORD dst_unused:UNUSED_PAD src0_sel:WORD_1
	v_cvt_f32_f16_e32 v74, v76
	v_pk_mul_f32 v[114:115], v[78:79], v[78:79]
	v_pk_mul_f32 v[76:77], v[74:75], v[74:75]
	s_nop 0
	v_mov_b32_e32 v99, v76
	v_mov_b32_e32 v109, v77
	v_mov_b32_e32 v111, v114
	v_mov_b32_e32 v113, v115
	v_pk_add_f32 v[76:77], v[98:99], v[108:109]
	v_pk_add_f32 v[98:99], v[110:111], v[112:113]
	s_nop 0
	v_pk_add_f32 v[76:77], v[76:77], v[98:99]
	s_nop 0
	v_add_f32_e32 v76, v76, v77
	s_nop 1
	v_add_f32_dpp v76, v76, v76 quad_perm:[1,0,3,2] row_mask:0xf bank_mask:0xf bound_ctrl:1
	s_nop 1
	v_add_f32_dpp v76, v76, v76 quad_perm:[2,3,0,1] row_mask:0xf bank_mask:0xf bound_ctrl:1
	s_nop 1
	v_add_f32_dpp v76, v76, v76 row_half_mirror row_mask:0xf bank_mask:0xf bound_ctrl:1
	s_nop 1
	v_add_f32_dpp v76, v76, v76 row_mirror row_mask:0xf bank_mask:0xf bound_ctrl:1
	s_nop 0
	v_readlane_b32 s8, v76, 16
	v_readlane_b32 s9, v76, 48
	v_readlane_b32 s6, v76, 0
	v_readlane_b32 s7, v76, 32
	v_mov_b32_e32 v76, s8
	v_mov_b32_e32 v77, s9
	v_pk_add_f32 v[76:77], s[6:7], v[76:77]
	s_nop 0
	v_add_f32_e32 v76, v76, v77
	v_fmamk_f32 v76, v76, 0x3a000000, v252
	v_cmp_gt_f32_e32 vcc, s55, v76
	v_mul_f32_e32 v77, 0x4f800000, v76
	s_nop 0
	v_cndmask_b32_e32 v76, v76, v77, vcc
	v_sqrt_f32_e32 v77, v76
	s_nop 0
	v_add_u32_e32 v98, -1, v77
	v_fma_f32 v99, -v98, v77, v76
	v_cmp_ge_f32_e64 s[8:9], 0, v99
	v_add_u32_e32 v99, 1, v77
	s_nop 0
	v_cndmask_b32_e64 v98, v77, v98, s[8:9]
	v_fma_f32 v77, -v99, v77, v76
	v_cmp_lt_f32_e64 s[8:9], 0, v77
	s_nop 1
	v_cndmask_b32_e64 v77, v98, v99, s[8:9]
	v_mul_f32_e32 v98, 0x37800000, v77
	v_cndmask_b32_e32 v77, v77, v98, vcc
	v_cmp_class_f32_e32 vcc, v76, v253
	s_nop 1
	v_cndmask_b32_e32 v76, v77, v76, vcc
	v_div_scale_f32 v77, s[6:7], v76, v76, 1.0
	v_rcp_f32_e32 v98, v77
	s_lshl_b32 s6, s30, 1
	s_and_b32 s6, s6, 0xffffe000
	s_add_i32 s6, s6, 0
	v_fma_f32 v99, -v77, v98, 1.0
	v_fmac_f32_e32 v98, v99, v98
	v_div_scale_f32 v99, vcc, 1.0, v76, 1.0
	v_mul_f32_e32 v108, v99, v98
	v_fma_f32 v109, -v77, v108, v99
	v_fmac_f32_e32 v108, v109, v98
	v_fma_f32 v77, -v77, v108, v99
	v_div_fmas_f32 v77, v77, v98, v108
	v_div_fixup_f32 v98, v77, v76, 1.0
	v_pk_mul_f32 v[112:113], v[104:105], v[98:99] op_sel_hi:[1,0]
	v_pk_mul_f32 v[114:115], v[106:107], v[98:99] op_sel_hi:[1,0]
	v_add_u32_e32 v99, s6, v0
	ds_read_b128 v[104:107], v99
	ds_read_b128 v[108:111], v99 offset:40960
	v_lshl_add_u64 v[76:77], s[34:35], 1, v[2:3]
	v_lshl_add_u64 v[76:77], v[76:77], 0, v[6:7]
	v_pk_mul_f32 v[4:5], v[4:5], v[98:99] op_sel_hi:[1,0]
	s_waitcnt lgkmcnt(0)
	v_pk_fma_f32 v[106:107], v[106:107], v[114:115], v[110:111]
	v_pk_fma_f32 v[104:105], v[104:105], v[112:113], v[108:109]
	v_pk_mul_f32 v[108:109], v[100:101], v[98:99] op_sel_hi:[1,0]
	v_cvt_pk_bf16_f32 v104, v104, v105
	v_cvt_pk_bf16_f32 v105, v106, v107
	global_store_dwordx2 v[76:77], v[104:105], off nt
	v_pk_mul_f32 v[110:111], v[102:103], v[98:99] op_sel_hi:[1,0]
	ds_read_b128 v[100:103], v99 offset:1024
	ds_read_b128 v[104:107], v99 offset:41984
	s_waitcnt lgkmcnt(0)
	v_pk_fma_f32 v[102:103], v[102:103], v[110:111], v[106:107]
	v_pk_fma_f32 v[100:101], v[100:101], v[108:109], v[104:105]
	v_pk_mul_f32 v[104:105], v[90:91], v[98:99] op_sel_hi:[1,0]
	v_cvt_pk_bf16_f32 v100, v100, v101
	v_cvt_pk_bf16_f32 v101, v102, v103
	global_store_dwordx2 v[76:77], v[100:101], off offset:512 nt
	v_pk_mul_f32 v[106:107], v[92:93], v[98:99] op_sel_hi:[1,0]
	ds_read_b128 v[90:93], v99 offset:2048
	ds_read_b128 v[100:103], v99 offset:43008
	s_waitcnt lgkmcnt(0)
	v_pk_fma_f32 v[92:93], v[92:93], v[106:107], v[102:103]
	v_pk_fma_f32 v[90:91], v[90:91], v[104:105], v[100:101]
	v_pk_mul_f32 v[100:101], v[94:95], v[98:99] op_sel_hi:[1,0]
	v_cvt_pk_bf16_f32 v90, v90, v91
	v_cvt_pk_bf16_f32 v91, v92, v93
	global_store_dwordx2 v[76:77], v[90:91], off offset:1024 nt
	v_pk_mul_f32 v[102:103], v[96:97], v[98:99] op_sel_hi:[1,0]
	ds_read_b128 v[90:93], v99 offset:3072
	ds_read_b128 v[94:97], v99 offset:44032
	s_waitcnt lgkmcnt(0)
	v_pk_fma_f32 v[92:93], v[102:103], v[92:93], v[96:97]
	v_pk_fma_f32 v[90:91], v[100:101], v[90:91], v[94:95]
	v_pk_mul_f32 v[94:95], v[84:85], v[98:99] op_sel_hi:[1,0]
	v_cvt_pk_bf16_f32 v90, v90, v91
	v_cvt_pk_bf16_f32 v91, v92, v93
	global_store_dwordx2 v[76:77], v[90:91], off offset:1536 nt
	v_pk_mul_f32 v[96:97], v[86:87], v[98:99] op_sel_hi:[1,0]
	ds_read_b128 v[84:87], v99 offset:4096
	ds_read_b128 v[90:93], v99 offset:45056
	s_waitcnt lgkmcnt(0)
	v_pk_fma_f32 v[86:87], v[96:97], v[86:87], v[92:93]
	v_pk_fma_f32 v[84:85], v[94:95], v[84:85], v[90:91]
	v_pk_mul_f32 v[90:91], v[82:83], v[98:99] op_sel_hi:[1,0]
	v_cvt_pk_bf16_f32 v84, v84, v85
	v_cvt_pk_bf16_f32 v85, v86, v87
	global_store_dwordx2 v[76:77], v[84:85], off offset:2048 nt
	v_pk_mul_f32 v[92:93], v[88:89], v[98:99] op_sel_hi:[1,0]
	ds_read_b128 v[82:85], v99 offset:5120
	ds_read_b128 v[86:89], v99 offset:46080
	s_waitcnt lgkmcnt(0)
	v_pk_fma_f32 v[84:85], v[92:93], v[84:85], v[88:89]
	v_pk_fma_f32 v[82:83], v[90:91], v[82:83], v[86:87]
	v_pk_mul_f32 v[88:89], v[80:81], v[98:99] op_sel_hi:[1,0]
	v_cvt_pk_bf16_f32 v82, v82, v83
	v_cvt_pk_bf16_f32 v83, v84, v85
	global_store_dwordx2 v[76:77], v[82:83], off offset:2560 nt
	ds_read_b128 v[80:83], v99 offset:6144
	ds_read_b128 v[84:87], v99 offset:47104
	s_waitcnt vmcnt(61)
	v_cvt_f32_f16_sdwa v91, v73 dst_sel:DWORD dst_unused:UNUSED_PAD src0_sel:WORD_1
	v_cvt_f32_f16_e32 v90, v73
	s_waitcnt lgkmcnt(0)
	v_pk_fma_f32 v[82:83], v[88:89], v[82:83], v[86:87]
	v_pk_fma_f32 v[4:5], v[4:5], v[80:81], v[84:85]
	v_cvt_f32_f16_sdwa v89, v72 dst_sel:DWORD dst_unused:UNUSED_PAD src0_sel:WORD_1
	v_cvt_pk_bf16_f32 v4, v4, v5
	v_cvt_pk_bf16_f32 v5, v82, v83
	global_store_dwordx2 v[76:77], v[4:5], off offset:3072 nt
	v_pk_mul_f32 v[4:5], v[74:75], v[98:99] op_sel_hi:[1,0]
	v_pk_mul_f32 v[74:75], v[78:79], v[98:99] op_sel_hi:[1,0]
	ds_read_b128 v[78:81], v99 offset:7168
	ds_read_b128 v[82:85], v99 offset:48128
	v_cvt_f32_f16_e32 v88, v72
	s_waitcnt vmcnt(61)
	v_cvt_f32_f16_sdwa v87, v71 dst_sel:DWORD dst_unused:UNUSED_PAD src0_sel:WORD_1
	v_cvt_f32_f16_e32 v86, v71
	v_mov_b32_e32 v72, v91
	s_waitcnt lgkmcnt(0)
	v_pk_fma_f32 v[74:75], v[74:75], v[80:81], v[84:85]
	v_cvt_f32_f16_sdwa v85, v70 dst_sel:DWORD dst_unused:UNUSED_PAD src0_sel:WORD_1
	v_cvt_f32_f16_e32 v84, v70
	v_pk_fma_f32 v[4:5], v[4:5], v[78:79], v[82:83]
	v_mov_b32_e32 v70, v89
	v_cvt_pk_bf16_f32 v4, v4, v5
	v_cvt_pk_bf16_f32 v5, v74, v75
	global_store_dwordx2 v[76:77], v[4:5], off offset:3584 nt
	v_mov_b32_e32 v71, v85
	s_waitcnt vmcnt(61)
	v_cvt_f32_f16_sdwa v75, v68 dst_sel:DWORD dst_unused:UNUSED_PAD src0_sel:WORD_1
	v_cvt_f32_f16_sdwa v77, v69 dst_sel:DWORD dst_unused:UNUSED_PAD src0_sel:WORD_1
	v_mov_b32_e32 v4, v88
	v_mov_b32_e32 v5, v84
	v_pk_mul_f32 v[70:71], v[70:71], v[70:71]
	v_mov_b32_e32 v73, v87
	v_cvt_f32_f16_e32 v74, v68
	v_cvt_f32_f16_e32 v76, v69
	s_waitcnt vmcnt(60)
	v_cvt_f32_f16_sdwa v79, v66 dst_sel:DWORD dst_unused:UNUSED_PAD src0_sel:WORD_1
	v_pk_fma_f32 v[4:5], v[4:5], v[4:5], v[70:71]
	v_mov_b32_e32 v70, v90
	v_mov_b32_e32 v71, v86
	v_pk_mul_f32 v[72:73], v[72:73], v[72:73]
	v_cvt_f32_f16_e32 v78, v66
	v_cvt_f32_f16_sdwa v81, v67 dst_sel:DWORD dst_unused:UNUSED_PAD src0_sel:WORD_1
	v_pk_fma_f32 v[70:71], v[70:71], v[70:71], v[72:73]
	v_cvt_f32_f16_e32 v80, v67
	v_pk_add_f32 v[4:5], v[4:5], v[70:71]
	v_mov_b32_e32 v70, v75
	v_mov_b32_e32 v71, v77
	v_mov_b32_e32 v68, v74
	v_mov_b32_e32 v69, v76
	v_pk_mul_f32 v[70:71], v[70:71], v[70:71]
	v_mul_f32_e32 v66, v79, v79
	v_pk_fma_f32 v[68:69], v[68:69], v[68:69], v[70:71]
	v_pk_fma_f32 v[72:73], v[78:79], v[78:79], v[66:67] op_sel_hi:[1,1,0]
	v_mul_f32_e32 v66, v81, v81
	v_pk_add_f32 v[70:71], v[68:69], v[68:69] op_sel:[0,1] op_sel_hi:[1,0]
	v_pk_fma_f32 v[82:83], v[80:81], v[80:81], v[66:67] op_sel_hi:[1,1,0]
	s_waitcnt vmcnt(59)
	v_cvt_f32_f16_sdwa v67, v64 dst_sel:DWORD dst_unused:UNUSED_PAD src0_sel:WORD_1
	v_cvt_f32_f16_e32 v66, v64
	v_cvt_f32_f16_sdwa v69, v65 dst_sel:DWORD dst_unused:UNUSED_PAD src0_sel:WORD_1
	v_cvt_f32_f16_e32 v68, v65
	v_pk_add_f32 v[4:5], v[4:5], v[4:5] op_sel:[0,1] op_sel_hi:[1,0]
	v_pk_mul_f32 v[64:65], v[66:67], v[66:67]
	v_pk_mul_f32 v[92:93], v[68:69], v[68:69]
	v_mov_b32_e32 v5, v64
	v_mov_b32_e32 v71, v65
	v_mov_b32_e32 v73, v92
	v_mov_b32_e32 v83, v93
	v_pk_add_f32 v[4:5], v[4:5], v[70:71]
	v_pk_add_f32 v[64:65], v[72:73], v[82:83]
	s_waitcnt vmcnt(58)
	v_cvt_f32_f16_sdwa v71, v62 dst_sel:DWORD dst_unused:UNUSED_PAD src0_sel:WORD_1
	v_cvt_f32_f16_sdwa v73, v63 dst_sel:DWORD dst_unused:UNUSED_PAD src0_sel:WORD_1
	v_cvt_f32_f16_e32 v70, v62
	v_cvt_f32_f16_e32 v72, v63
	v_pk_add_f32 v[4:5], v[4:5], v[64:65]
	v_mov_b32_e32 v62, v71
	v_mov_b32_e32 v63, v73
	v_pk_add_f32 v[82:83], v[4:5], v[4:5] op_sel:[0,1] op_sel_hi:[1,0]
	v_mov_b32_e32 v4, v70
	v_mov_b32_e32 v5, v72
	v_pk_mul_f32 v[62:63], v[62:63], v[62:63]
	s_waitcnt vmcnt(56)
	v_cvt_f32_f16_sdwa v65, v59 dst_sel:DWORD dst_unused:UNUSED_PAD src0_sel:WORD_1
	v_pk_fma_f32 v[4:5], v[4:5], v[4:5], v[62:63]
	v_cvt_f32_f16_sdwa v63, v61 dst_sel:DWORD dst_unused:UNUSED_PAD src0_sel:WORD_1
	v_pk_add_f32 v[92:93], v[4:5], v[4:5] op_sel:[0,1] op_sel_hi:[1,0]
	v_cvt_f32_f16_sdwa v5, v60 dst_sel:DWORD dst_unused:UNUSED_PAD src0_sel:WORD_1
	v_cvt_f32_f16_e32 v4, v60
	v_cvt_f32_f16_e32 v62, v61
	v_cvt_f32_f16_e32 v64, v59
	v_mul_f32_e32 v60, v5, v5
	v_pk_fma_f32 v[94:95], v[4:5], v[4:5], v[60:61] op_sel_hi:[1,1,0]
	v_mul_f32_e32 v60, v63, v63
	v_pk_fma_f32 v[96:97], v[62:63], v[62:63], v[60:61] op_sel_hi:[1,1,0]
	v_cvt_f32_f16_sdwa v61, v58 dst_sel:DWORD dst_unused:UNUSED_PAD src0_sel:WORD_1
	v_cvt_f32_f16_e32 v60, v58
	v_pk_mul_f32 v[98:99], v[64:65], v[64:65]
	v_pk_mul_f32 v[58:59], v[60:61], v[60:61]
	s_nop 0
	v_mov_b32_e32 v83, v58
	v_mov_b32_e32 v93, v59
	v_mov_b32_e32 v95, v98
	v_mov_b32_e32 v97, v99
	v_pk_add_f32 v[58:59], v[82:83], v[92:93]
	v_pk_add_f32 v[82:83], v[94:95], v[96:97]
	s_nop 0
	v_pk_add_f32 v[58:59], v[58:59], v[82:83]
	s_nop 0
	v_add_f32_e32 v58, v58, v59
	s_nop 1
	v_add_f32_dpp v58, v58, v58 quad_perm:[1,0,3,2] row_mask:0xf bank_mask:0xf bound_ctrl:1
	s_nop 1
	v_add_f32_dpp v58, v58, v58 quad_perm:[2,3,0,1] row_mask:0xf bank_mask:0xf bound_ctrl:1
	s_nop 1
	v_add_f32_dpp v58, v58, v58 row_half_mirror row_mask:0xf bank_mask:0xf bound_ctrl:1
	s_nop 1
	v_add_f32_dpp v58, v58, v58 row_mirror row_mask:0xf bank_mask:0xf bound_ctrl:1
	s_nop 0
	v_readlane_b32 s8, v58, 16
	v_readlane_b32 s9, v58, 48
	v_readlane_b32 s6, v58, 0
	v_readlane_b32 s7, v58, 32
	v_mov_b32_e32 v58, s8
	v_mov_b32_e32 v59, s9
	v_pk_add_f32 v[58:59], s[6:7], v[58:59]
	s_nop 0
	v_add_f32_e32 v58, v58, v59
	v_fmamk_f32 v58, v58, 0x3a000000, v252
	v_cmp_gt_f32_e32 vcc, s55, v58
	v_mul_f32_e32 v59, 0x4f800000, v58
	s_nop 0
	v_cndmask_b32_e32 v58, v58, v59, vcc
	v_sqrt_f32_e32 v59, v58
	s_nop 0
	v_add_u32_e32 v82, -1, v59
	v_fma_f32 v83, -v82, v59, v58
	v_cmp_ge_f32_e64 s[8:9], 0, v83
	v_add_u32_e32 v83, 1, v59
	s_nop 0
	v_cndmask_b32_e64 v82, v59, v82, s[8:9]
	v_fma_f32 v59, -v83, v59, v58
	v_cmp_lt_f32_e64 s[8:9], 0, v59
	s_nop 1
	v_cndmask_b32_e64 v59, v82, v83, s[8:9]
	v_mul_f32_e32 v82, 0x37800000, v59
	v_cndmask_b32_e32 v59, v59, v82, vcc
	v_cmp_class_f32_e32 vcc, v58, v253
	s_nop 1
	v_cndmask_b32_e32 v58, v59, v58, vcc
	v_div_scale_f32 v59, s[6:7], v58, v58, 1.0
	v_rcp_f32_e32 v82, v59
	s_lshl_b32 s6, s26, 1
	s_and_b32 s6, s6, 0xffffe000
	s_add_i32 s6, s6, 0
	v_fma_f32 v83, -v59, v82, 1.0
	v_fmac_f32_e32 v82, v83, v82
	v_div_scale_f32 v83, vcc, 1.0, v58, 1.0
	v_mul_f32_e32 v92, v83, v82
	v_fma_f32 v93, -v59, v92, v83
	v_fmac_f32_e32 v92, v93, v82
	v_fma_f32 v59, -v59, v92, v83
	v_div_fmas_f32 v59, v59, v82, v92
	v_div_fixup_f32 v82, v59, v58, 1.0
	v_pk_mul_f32 v[96:97], v[88:89], v[82:83] op_sel_hi:[1,0]
	v_pk_mul_f32 v[98:99], v[90:91], v[82:83] op_sel_hi:[1,0]
	v_add_u32_e32 v83, s6, v0
	ds_read_b128 v[88:91], v83
	ds_read_b128 v[92:95], v83 offset:40960
	v_lshl_add_u64 v[58:59], s[28:29], 1, v[2:3]
	v_lshl_add_u64 v[58:59], v[58:59], 0, v[6:7]
	v_pk_mul_f32 v[4:5], v[4:5], v[82:83] op_sel_hi:[1,0]
	v_pk_mul_f32 v[62:63], v[62:63], v[82:83] op_sel_hi:[1,0]
	s_waitcnt lgkmcnt(0)
	v_pk_fma_f32 v[90:91], v[90:91], v[98:99], v[94:95]
	v_pk_fma_f32 v[88:89], v[88:89], v[96:97], v[92:93]
	v_pk_mul_f32 v[92:93], v[84:85], v[82:83] op_sel_hi:[1,0]
	v_cvt_pk_bf16_f32 v88, v88, v89
	v_cvt_pk_bf16_f32 v89, v90, v91
	global_store_dwordx2 v[58:59], v[88:89], off nt
	v_pk_mul_f32 v[94:95], v[86:87], v[82:83] op_sel_hi:[1,0]
	ds_read_b128 v[84:87], v83 offset:1024
	ds_read_b128 v[88:91], v83 offset:41984
	s_waitcnt lgkmcnt(0)
	v_pk_fma_f32 v[86:87], v[86:87], v[94:95], v[90:91]
	v_pk_fma_f32 v[84:85], v[84:85], v[92:93], v[88:89]
	v_pk_mul_f32 v[88:89], v[74:75], v[82:83] op_sel_hi:[1,0]
	v_cvt_pk_bf16_f32 v84, v84, v85
	v_cvt_pk_bf16_f32 v85, v86, v87
	global_store_dwordx2 v[58:59], v[84:85], off offset:512 nt
	v_pk_mul_f32 v[90:91], v[76:77], v[82:83] op_sel_hi:[1,0]
	ds_read_b128 v[74:77], v83 offset:2048
	ds_read_b128 v[84:87], v83 offset:43008
	s_waitcnt lgkmcnt(0)
	v_pk_fma_f32 v[76:77], v[76:77], v[90:91], v[86:87]
	v_pk_fma_f32 v[74:75], v[74:75], v[88:89], v[84:85]
	v_pk_mul_f32 v[84:85], v[78:79], v[82:83] op_sel_hi:[1,0]
	v_cvt_pk_bf16_f32 v74, v74, v75
	v_cvt_pk_bf16_f32 v75, v76, v77
	global_store_dwordx2 v[58:59], v[74:75], off offset:1024 nt
	v_pk_mul_f32 v[86:87], v[80:81], v[82:83] op_sel_hi:[1,0]
	ds_read_b128 v[74:77], v83 offset:3072
	ds_read_b128 v[78:81], v83 offset:44032
	s_waitcnt lgkmcnt(0)
	v_pk_fma_f32 v[76:77], v[86:87], v[76:77], v[80:81]
	v_pk_fma_f32 v[74:75], v[84:85], v[74:75], v[78:79]
	v_pk_mul_f32 v[78:79], v[66:67], v[82:83] op_sel_hi:[1,0]
	v_cvt_pk_bf16_f32 v74, v74, v75
	v_cvt_pk_bf16_f32 v75, v76, v77
	global_store_dwordx2 v[58:59], v[74:75], off offset:1536 nt
	v_pk_mul_f32 v[80:81], v[68:69], v[82:83] op_sel_hi:[1,0]
	ds_read_b128 v[66:69], v83 offset:4096
	ds_read_b128 v[74:77], v83 offset:45056
	s_waitcnt lgkmcnt(0)
	v_pk_fma_f32 v[68:69], v[80:81], v[68:69], v[76:77]
	v_pk_fma_f32 v[66:67], v[78:79], v[66:67], v[74:75]
	v_pk_mul_f32 v[74:75], v[70:71], v[82:83] op_sel_hi:[1,0]
	v_cvt_pk_bf16_f32 v66, v66, v67
	v_cvt_pk_bf16_f32 v67, v68, v69
	global_store_dwordx2 v[58:59], v[66:67], off offset:2048 nt
	v_pk_mul_f32 v[76:77], v[72:73], v[82:83] op_sel_hi:[1,0]
	ds_read_b128 v[66:69], v83 offset:5120
	ds_read_b128 v[70:73], v83 offset:46080
	s_waitcnt lgkmcnt(0)
	v_pk_fma_f32 v[68:69], v[76:77], v[68:69], v[72:73]
	v_pk_fma_f32 v[66:67], v[74:75], v[66:67], v[70:71]
	s_waitcnt vmcnt(60)
	v_cvt_f32_f16_sdwa v75, v57 dst_sel:DWORD dst_unused:UNUSED_PAD src0_sel:WORD_1
	v_cvt_pk_bf16_f32 v66, v66, v67
	v_cvt_pk_bf16_f32 v67, v68, v69
	global_store_dwordx2 v[58:59], v[66:67], off offset:2560 nt
	ds_read_b128 v[66:69], v83 offset:6144
	ds_read_b128 v[70:73], v83 offset:47104
	v_cvt_f32_f16_e32 v74, v57
	s_waitcnt lgkmcnt(0)
	v_pk_fma_f32 v[62:63], v[62:63], v[68:69], v[72:73]
	v_pk_fma_f32 v[4:5], v[4:5], v[66:67], v[70:71]
	v_pk_mul_f32 v[68:69], v[64:65], v[82:83] op_sel_hi:[1,0]
	v_cvt_pk_bf16_f32 v4, v4, v5
	v_cvt_pk_bf16_f32 v5, v62, v63
	global_store_dwordx2 v[58:59], v[4:5], off offset:3072 nt
	v_pk_mul_f32 v[4:5], v[60:61], v[82:83] op_sel_hi:[1,0]
	ds_read_b128 v[60:63], v83 offset:7168
	ds_read_b128 v[64:67], v83 offset:48128
	v_cvt_f32_f16_sdwa v73, v56 dst_sel:DWORD dst_unused:UNUSED_PAD src0_sel:WORD_1
	v_cvt_f32_f16_e32 v72, v56
	s_waitcnt vmcnt(61)
	v_cvt_f32_f16_sdwa v71, v55 dst_sel:DWORD dst_unused:UNUSED_PAD src0_sel:WORD_1
	v_cvt_f32_f16_e32 v70, v55
	s_waitcnt lgkmcnt(0)
	v_pk_fma_f32 v[62:63], v[68:69], v[62:63], v[66:67]
	v_cvt_f32_f16_sdwa v69, v54 dst_sel:DWORD dst_unused:UNUSED_PAD src0_sel:WORD_1
	v_cvt_f32_f16_e32 v68, v54
	v_pk_fma_f32 v[4:5], v[4:5], v[60:61], v[64:65]
	v_mov_b32_e32 v54, v73
	v_cvt_pk_bf16_f32 v4, v4, v5
	v_cvt_pk_bf16_f32 v5, v62, v63
	global_store_dwordx2 v[58:59], v[4:5], off offset:3584 nt
	v_mov_b32_e32 v55, v69
	s_waitcnt vmcnt(61)
	v_cvt_f32_f16_sdwa v59, v52 dst_sel:DWORD dst_unused:UNUSED_PAD src0_sel:WORD_1
	v_cvt_f32_f16_sdwa v61, v53 dst_sel:DWORD dst_unused:UNUSED_PAD src0_sel:WORD_1
	v_mov_b32_e32 v4, v72
	v_mov_b32_e32 v5, v68
	v_pk_mul_f32 v[54:55], v[54:55], v[54:55]
	v_mov_b32_e32 v56, v75
	v_mov_b32_e32 v57, v71
	v_cvt_f32_f16_e32 v58, v52
	v_cvt_f32_f16_e32 v60, v53
	s_waitcnt vmcnt(60)
	v_cvt_f32_f16_sdwa v63, v50 dst_sel:DWORD dst_unused:UNUSED_PAD src0_sel:WORD_1
	v_pk_fma_f32 v[4:5], v[4:5], v[4:5], v[54:55]
	v_mov_b32_e32 v54, v74
	v_mov_b32_e32 v55, v70
	v_pk_mul_f32 v[56:57], v[56:57], v[56:57]
	v_cvt_f32_f16_e32 v62, v50
	v_cvt_f32_f16_sdwa v65, v51 dst_sel:DWORD dst_unused:UNUSED_PAD src0_sel:WORD_1
	v_pk_fma_f32 v[54:55], v[54:55], v[54:55], v[56:57]
	v_cvt_f32_f16_e32 v64, v51
	v_pk_add_f32 v[4:5], v[4:5], v[54:55]
	v_mov_b32_e32 v54, v59
	v_mov_b32_e32 v55, v61
	v_mov_b32_e32 v52, v58
	v_mov_b32_e32 v53, v60
	v_pk_mul_f32 v[54:55], v[54:55], v[54:55]
	v_mul_f32_e32 v50, v63, v63
	v_pk_fma_f32 v[52:53], v[52:53], v[52:53], v[54:55]
	v_pk_fma_f32 v[56:57], v[62:63], v[62:63], v[50:51] op_sel_hi:[1,1,0]
	v_mul_f32_e32 v50, v65, v65
	v_pk_add_f32 v[54:55], v[52:53], v[52:53] op_sel:[0,1] op_sel_hi:[1,0]
	v_pk_fma_f32 v[66:67], v[64:65], v[64:65], v[50:51] op_sel_hi:[1,1,0]
	s_waitcnt vmcnt(59)
	v_cvt_f32_f16_sdwa v51, v48 dst_sel:DWORD dst_unused:UNUSED_PAD src0_sel:WORD_1
	v_cvt_f32_f16_e32 v50, v48
	v_cvt_f32_f16_sdwa v53, v49 dst_sel:DWORD dst_unused:UNUSED_PAD src0_sel:WORD_1
	v_cvt_f32_f16_e32 v52, v49
	v_pk_add_f32 v[4:5], v[4:5], v[4:5] op_sel:[0,1] op_sel_hi:[1,0]
	v_pk_mul_f32 v[48:49], v[50:51], v[50:51]
	v_pk_mul_f32 v[76:77], v[52:53], v[52:53]
	v_mov_b32_e32 v5, v48
	v_mov_b32_e32 v55, v49
	v_mov_b32_e32 v57, v76
	v_mov_b32_e32 v67, v77
	v_pk_add_f32 v[4:5], v[4:5], v[54:55]
	v_pk_add_f32 v[48:49], v[56:57], v[66:67]
	s_waitcnt vmcnt(58)
	v_cvt_f32_f16_sdwa v55, v46 dst_sel:DWORD dst_unused:UNUSED_PAD src0_sel:WORD_1
	v_cvt_f32_f16_sdwa v57, v47 dst_sel:DWORD dst_unused:UNUSED_PAD src0_sel:WORD_1
	v_cvt_f32_f16_e32 v54, v46
	v_cvt_f32_f16_e32 v56, v47
	v_pk_add_f32 v[4:5], v[4:5], v[48:49]
	v_mov_b32_e32 v46, v55
	v_mov_b32_e32 v47, v57
	v_pk_add_f32 v[66:67], v[4:5], v[4:5] op_sel:[0,1] op_sel_hi:[1,0]
	v_mov_b32_e32 v4, v54
	v_mov_b32_e32 v5, v56
	v_pk_mul_f32 v[46:47], v[46:47], v[46:47]
	s_waitcnt vmcnt(56)
	v_cvt_f32_f16_sdwa v49, v43 dst_sel:DWORD dst_unused:UNUSED_PAD src0_sel:WORD_1
	v_pk_fma_f32 v[4:5], v[4:5], v[4:5], v[46:47]
	v_cvt_f32_f16_sdwa v47, v45 dst_sel:DWORD dst_unused:UNUSED_PAD src0_sel:WORD_1
	v_pk_add_f32 v[76:77], v[4:5], v[4:5] op_sel:[0,1] op_sel_hi:[1,0]
	v_cvt_f32_f16_sdwa v5, v44 dst_sel:DWORD dst_unused:UNUSED_PAD src0_sel:WORD_1
	v_cvt_f32_f16_e32 v4, v44
	v_cvt_f32_f16_e32 v46, v45
	v_cvt_f32_f16_e32 v48, v43
	v_mul_f32_e32 v44, v5, v5
	v_pk_fma_f32 v[78:79], v[4:5], v[4:5], v[44:45] op_sel_hi:[1,1,0]
	v_mul_f32_e32 v44, v47, v47
	v_pk_fma_f32 v[80:81], v[46:47], v[46:47], v[44:45] op_sel_hi:[1,1,0]
	v_cvt_f32_f16_sdwa v45, v42 dst_sel:DWORD dst_unused:UNUSED_PAD src0_sel:WORD_1
	v_cvt_f32_f16_e32 v44, v42
	v_pk_mul_f32 v[82:83], v[48:49], v[48:49]
	v_pk_mul_f32 v[42:43], v[44:45], v[44:45]
	s_nop 0
	v_mov_b32_e32 v67, v42
	v_mov_b32_e32 v77, v43
	v_mov_b32_e32 v79, v82
	v_mov_b32_e32 v81, v83
	v_pk_add_f32 v[42:43], v[66:67], v[76:77]
	v_pk_add_f32 v[66:67], v[78:79], v[80:81]
	s_nop 0
	v_pk_add_f32 v[42:43], v[42:43], v[66:67]
	s_nop 0
	v_add_f32_e32 v42, v42, v43
	s_nop 1
	v_add_f32_dpp v42, v42, v42 quad_perm:[1,0,3,2] row_mask:0xf bank_mask:0xf bound_ctrl:1
	s_nop 1
	v_add_f32_dpp v42, v42, v42 quad_perm:[2,3,0,1] row_mask:0xf bank_mask:0xf bound_ctrl:1
	s_nop 1
	v_add_f32_dpp v42, v42, v42 row_half_mirror row_mask:0xf bank_mask:0xf bound_ctrl:1
	s_nop 1
	v_add_f32_dpp v42, v42, v42 row_mirror row_mask:0xf bank_mask:0xf bound_ctrl:1
	s_nop 0
	v_readlane_b32 s8, v42, 16
	v_readlane_b32 s9, v42, 48
	v_readlane_b32 s6, v42, 0
	v_readlane_b32 s7, v42, 32
	v_mov_b32_e32 v42, s8
	v_mov_b32_e32 v43, s9
	v_pk_add_f32 v[42:43], s[6:7], v[42:43]
	s_nop 0
	v_add_f32_e32 v42, v42, v43
	v_fmamk_f32 v42, v42, 0x3a000000, v252
	v_cmp_gt_f32_e32 vcc, s55, v42
	v_mul_f32_e32 v43, 0x4f800000, v42
	s_nop 0
	v_cndmask_b32_e32 v42, v42, v43, vcc
	v_sqrt_f32_e32 v43, v42
	s_nop 0
	v_add_u32_e32 v66, -1, v43
	v_fma_f32 v67, -v66, v43, v42
	v_cmp_ge_f32_e64 s[8:9], 0, v67
	v_add_u32_e32 v67, 1, v43
	s_nop 0
	v_cndmask_b32_e64 v66, v43, v66, s[8:9]
	v_fma_f32 v43, -v67, v43, v42
	v_cmp_lt_f32_e64 s[8:9], 0, v43
	s_nop 1
	v_cndmask_b32_e64 v43, v66, v67, s[8:9]
	v_mul_f32_e32 v66, 0x37800000, v43
	v_cndmask_b32_e32 v43, v43, v66, vcc
	v_cmp_class_f32_e32 vcc, v42, v253
	s_nop 1
	v_cndmask_b32_e32 v42, v43, v42, vcc
	v_div_scale_f32 v43, s[6:7], v42, v42, 1.0
	v_rcp_f32_e32 v66, v43
	s_lshl_b32 s6, s22, 1
	s_and_b32 s6, s6, 0xffffe000
	s_add_i32 s6, s6, 0
	v_fma_f32 v67, -v43, v66, 1.0
	v_fmac_f32_e32 v66, v67, v66
	v_div_scale_f32 v67, vcc, 1.0, v42, 1.0
	v_mul_f32_e32 v76, v67, v66
	v_fma_f32 v77, -v43, v76, v67
	v_fmac_f32_e32 v76, v77, v66
	v_fma_f32 v43, -v43, v76, v67
	v_div_fmas_f32 v43, v43, v66, v76
	v_div_fixup_f32 v66, v43, v42, 1.0
	v_pk_mul_f32 v[80:81], v[72:73], v[66:67] op_sel_hi:[1,0]
	v_pk_mul_f32 v[82:83], v[74:75], v[66:67] op_sel_hi:[1,0]
	v_add_u32_e32 v67, s6, v0
	ds_read_b128 v[72:75], v67
	ds_read_b128 v[76:79], v67 offset:40960
	v_lshl_add_u64 v[42:43], s[24:25], 1, v[2:3]
	v_lshl_add_u64 v[42:43], v[42:43], 0, v[6:7]
	v_pk_mul_f32 v[4:5], v[4:5], v[66:67] op_sel_hi:[1,0]
	v_pk_mul_f32 v[46:47], v[46:47], v[66:67] op_sel_hi:[1,0]
	s_waitcnt lgkmcnt(0)
	v_pk_fma_f32 v[74:75], v[74:75], v[82:83], v[78:79]
	v_pk_fma_f32 v[72:73], v[72:73], v[80:81], v[76:77]
	v_pk_mul_f32 v[76:77], v[68:69], v[66:67] op_sel_hi:[1,0]
	v_cvt_pk_bf16_f32 v72, v72, v73
	v_cvt_pk_bf16_f32 v73, v74, v75
	global_store_dwordx2 v[42:43], v[72:73], off nt
	v_pk_mul_f32 v[78:79], v[70:71], v[66:67] op_sel_hi:[1,0]
	ds_read_b128 v[68:71], v67 offset:1024
	ds_read_b128 v[72:75], v67 offset:41984
	s_waitcnt lgkmcnt(0)
	v_pk_fma_f32 v[70:71], v[70:71], v[78:79], v[74:75]
	v_pk_fma_f32 v[68:69], v[68:69], v[76:77], v[72:73]
	v_pk_mul_f32 v[72:73], v[58:59], v[66:67] op_sel_hi:[1,0]
	v_cvt_pk_bf16_f32 v68, v68, v69
	v_cvt_pk_bf16_f32 v69, v70, v71
	global_store_dwordx2 v[42:43], v[68:69], off offset:512 nt
	v_pk_mul_f32 v[74:75], v[60:61], v[66:67] op_sel_hi:[1,0]
	ds_read_b128 v[58:61], v67 offset:2048
	ds_read_b128 v[68:71], v67 offset:43008
	s_waitcnt lgkmcnt(0)
	v_pk_fma_f32 v[60:61], v[60:61], v[74:75], v[70:71]
	v_pk_fma_f32 v[58:59], v[58:59], v[72:73], v[68:69]
	v_pk_mul_f32 v[68:69], v[62:63], v[66:67] op_sel_hi:[1,0]
	v_cvt_pk_bf16_f32 v58, v58, v59
	v_cvt_pk_bf16_f32 v59, v60, v61
	global_store_dwordx2 v[42:43], v[58:59], off offset:1024 nt
	v_pk_mul_f32 v[70:71], v[64:65], v[66:67] op_sel_hi:[1,0]
	ds_read_b128 v[58:61], v67 offset:3072
	ds_read_b128 v[62:65], v67 offset:44032
	s_waitcnt lgkmcnt(0)
	v_pk_fma_f32 v[60:61], v[70:71], v[60:61], v[64:65]
	v_pk_fma_f32 v[58:59], v[68:69], v[58:59], v[62:63]
	v_pk_mul_f32 v[62:63], v[50:51], v[66:67] op_sel_hi:[1,0]
	v_cvt_pk_bf16_f32 v58, v58, v59
	v_cvt_pk_bf16_f32 v59, v60, v61
	global_store_dwordx2 v[42:43], v[58:59], off offset:1536 nt
	v_pk_mul_f32 v[64:65], v[52:53], v[66:67] op_sel_hi:[1,0]
	ds_read_b128 v[50:53], v67 offset:4096
	ds_read_b128 v[58:61], v67 offset:45056
	s_waitcnt lgkmcnt(0)
	v_pk_fma_f32 v[52:53], v[64:65], v[52:53], v[60:61]
	v_pk_fma_f32 v[50:51], v[62:63], v[50:51], v[58:59]
	v_pk_mul_f32 v[58:59], v[54:55], v[66:67] op_sel_hi:[1,0]
	v_cvt_pk_bf16_f32 v50, v50, v51
	v_cvt_pk_bf16_f32 v51, v52, v53
	global_store_dwordx2 v[42:43], v[50:51], off offset:2048 nt
	v_pk_mul_f32 v[60:61], v[56:57], v[66:67] op_sel_hi:[1,0]
	ds_read_b128 v[50:53], v67 offset:5120
	ds_read_b128 v[54:57], v67 offset:46080
	s_waitcnt lgkmcnt(0)
	v_pk_fma_f32 v[52:53], v[60:61], v[52:53], v[56:57]
	v_pk_fma_f32 v[50:51], v[58:59], v[50:51], v[54:55]
	s_waitcnt vmcnt(60)
	v_cvt_f32_f16_sdwa v59, v41 dst_sel:DWORD dst_unused:UNUSED_PAD src0_sel:WORD_1
	v_cvt_pk_bf16_f32 v50, v50, v51
	v_cvt_pk_bf16_f32 v51, v52, v53
	global_store_dwordx2 v[42:43], v[50:51], off offset:2560 nt
	ds_read_b128 v[50:53], v67 offset:6144
	ds_read_b128 v[54:57], v67 offset:47104
	v_cvt_f32_f16_e32 v58, v41
	s_waitcnt lgkmcnt(0)
	v_pk_fma_f32 v[46:47], v[46:47], v[52:53], v[56:57]
	v_pk_fma_f32 v[4:5], v[4:5], v[50:51], v[54:55]
	v_pk_mul_f32 v[52:53], v[48:49], v[66:67] op_sel_hi:[1,0]
	v_cvt_pk_bf16_f32 v4, v4, v5
	v_cvt_pk_bf16_f32 v5, v46, v47
	global_store_dwordx2 v[42:43], v[4:5], off offset:3072 nt
	v_pk_mul_f32 v[4:5], v[44:45], v[66:67] op_sel_hi:[1,0]
	ds_read_b128 v[44:47], v67 offset:7168
	ds_read_b128 v[48:51], v67 offset:48128
	v_cvt_f32_f16_sdwa v57, v40 dst_sel:DWORD dst_unused:UNUSED_PAD src0_sel:WORD_1
	v_cvt_f32_f16_e32 v56, v40
	s_waitcnt vmcnt(61)
	v_cvt_f32_f16_sdwa v55, v39 dst_sel:DWORD dst_unused:UNUSED_PAD src0_sel:WORD_1
	v_cvt_f32_f16_e32 v54, v39
	s_waitcnt lgkmcnt(0)
	v_pk_fma_f32 v[46:47], v[52:53], v[46:47], v[50:51]
	v_cvt_f32_f16_sdwa v53, v38 dst_sel:DWORD dst_unused:UNUSED_PAD src0_sel:WORD_1
	v_cvt_f32_f16_e32 v52, v38
	v_pk_fma_f32 v[4:5], v[4:5], v[44:45], v[48:49]
	v_mov_b32_e32 v38, v57
	v_cvt_pk_bf16_f32 v4, v4, v5
	v_cvt_pk_bf16_f32 v5, v46, v47
	global_store_dwordx2 v[42:43], v[4:5], off offset:3584 nt
	v_mov_b32_e32 v39, v53
	s_waitcnt vmcnt(61)
	v_cvt_f32_f16_sdwa v43, v36 dst_sel:DWORD dst_unused:UNUSED_PAD src0_sel:WORD_1
	v_cvt_f32_f16_sdwa v45, v37 dst_sel:DWORD dst_unused:UNUSED_PAD src0_sel:WORD_1
	v_mov_b32_e32 v4, v56
	v_mov_b32_e32 v5, v52
	v_pk_mul_f32 v[38:39], v[38:39], v[38:39]
	v_mov_b32_e32 v40, v59
	v_mov_b32_e32 v41, v55
	v_cvt_f32_f16_e32 v42, v36
	v_cvt_f32_f16_e32 v44, v37
	s_waitcnt vmcnt(60)
	v_cvt_f32_f16_sdwa v47, v34 dst_sel:DWORD dst_unused:UNUSED_PAD src0_sel:WORD_1
	v_pk_fma_f32 v[4:5], v[4:5], v[4:5], v[38:39]
	v_mov_b32_e32 v38, v58
	v_mov_b32_e32 v39, v54
	v_pk_mul_f32 v[40:41], v[40:41], v[40:41]
	v_cvt_f32_f16_e32 v46, v34
	v_cvt_f32_f16_sdwa v49, v35 dst_sel:DWORD dst_unused:UNUSED_PAD src0_sel:WORD_1
	v_pk_fma_f32 v[38:39], v[38:39], v[38:39], v[40:41]
	v_cvt_f32_f16_e32 v48, v35
	v_pk_add_f32 v[4:5], v[4:5], v[38:39]
	v_mov_b32_e32 v38, v43
	v_mov_b32_e32 v39, v45
	v_mov_b32_e32 v36, v42
	v_mov_b32_e32 v37, v44
	v_pk_mul_f32 v[38:39], v[38:39], v[38:39]
	v_mul_f32_e32 v34, v47, v47
	v_pk_fma_f32 v[36:37], v[36:37], v[36:37], v[38:39]
	v_pk_fma_f32 v[40:41], v[46:47], v[46:47], v[34:35] op_sel_hi:[1,1,0]
	v_mul_f32_e32 v34, v49, v49
	v_pk_add_f32 v[38:39], v[36:37], v[36:37] op_sel:[0,1] op_sel_hi:[1,0]
	v_pk_fma_f32 v[50:51], v[48:49], v[48:49], v[34:35] op_sel_hi:[1,1,0]
	s_waitcnt vmcnt(59)
	v_cvt_f32_f16_sdwa v35, v32 dst_sel:DWORD dst_unused:UNUSED_PAD src0_sel:WORD_1
	v_cvt_f32_f16_e32 v34, v32
	v_cvt_f32_f16_sdwa v37, v33 dst_sel:DWORD dst_unused:UNUSED_PAD src0_sel:WORD_1
	v_cvt_f32_f16_e32 v36, v33
	v_pk_add_f32 v[4:5], v[4:5], v[4:5] op_sel:[0,1] op_sel_hi:[1,0]
	v_pk_mul_f32 v[32:33], v[34:35], v[34:35]
	v_pk_mul_f32 v[60:61], v[36:37], v[36:37]
	v_mov_b32_e32 v5, v32
	v_mov_b32_e32 v39, v33
	v_mov_b32_e32 v41, v60
	v_mov_b32_e32 v51, v61
	v_pk_add_f32 v[4:5], v[4:5], v[38:39]
	v_pk_add_f32 v[32:33], v[40:41], v[50:51]
	s_waitcnt vmcnt(58)
	v_cvt_f32_f16_sdwa v39, v30 dst_sel:DWORD dst_unused:UNUSED_PAD src0_sel:WORD_1
	v_cvt_f32_f16_sdwa v41, v31 dst_sel:DWORD dst_unused:UNUSED_PAD src0_sel:WORD_1
	v_cvt_f32_f16_e32 v38, v30
	v_cvt_f32_f16_e32 v40, v31
	v_pk_add_f32 v[4:5], v[4:5], v[32:33]
	v_mov_b32_e32 v30, v39
	v_mov_b32_e32 v31, v41
	v_pk_add_f32 v[50:51], v[4:5], v[4:5] op_sel:[0,1] op_sel_hi:[1,0]
	v_mov_b32_e32 v4, v38
	v_mov_b32_e32 v5, v40
	v_pk_mul_f32 v[30:31], v[30:31], v[30:31]
	s_waitcnt vmcnt(56)
	v_cvt_f32_f16_sdwa v33, v27 dst_sel:DWORD dst_unused:UNUSED_PAD src0_sel:WORD_1
	v_pk_fma_f32 v[4:5], v[4:5], v[4:5], v[30:31]
	v_cvt_f32_f16_sdwa v31, v29 dst_sel:DWORD dst_unused:UNUSED_PAD src0_sel:WORD_1
	v_pk_add_f32 v[60:61], v[4:5], v[4:5] op_sel:[0,1] op_sel_hi:[1,0]
	v_cvt_f32_f16_sdwa v5, v28 dst_sel:DWORD dst_unused:UNUSED_PAD src0_sel:WORD_1
	v_cvt_f32_f16_e32 v4, v28
	v_cvt_f32_f16_e32 v30, v29
	v_cvt_f32_f16_e32 v32, v27
	v_mul_f32_e32 v28, v5, v5
	v_pk_fma_f32 v[62:63], v[4:5], v[4:5], v[28:29] op_sel_hi:[1,1,0]
	v_mul_f32_e32 v28, v31, v31
	v_pk_fma_f32 v[64:65], v[30:31], v[30:31], v[28:29] op_sel_hi:[1,1,0]
	v_cvt_f32_f16_sdwa v29, v26 dst_sel:DWORD dst_unused:UNUSED_PAD src0_sel:WORD_1
	v_cvt_f32_f16_e32 v28, v26
	v_pk_mul_f32 v[66:67], v[32:33], v[32:33]
	v_pk_mul_f32 v[26:27], v[28:29], v[28:29]
	s_nop 0
	v_mov_b32_e32 v51, v26
	v_mov_b32_e32 v61, v27
	v_mov_b32_e32 v63, v66
	v_mov_b32_e32 v65, v67
	v_pk_add_f32 v[26:27], v[50:51], v[60:61]
	v_pk_add_f32 v[50:51], v[62:63], v[64:65]
	s_nop 0
	v_pk_add_f32 v[26:27], v[26:27], v[50:51]
	s_nop 0
	v_add_f32_e32 v26, v26, v27
	s_nop 1
	v_add_f32_dpp v26, v26, v26 quad_perm:[1,0,3,2] row_mask:0xf bank_mask:0xf bound_ctrl:1
	s_nop 1
	v_add_f32_dpp v26, v26, v26 quad_perm:[2,3,0,1] row_mask:0xf bank_mask:0xf bound_ctrl:1
	s_nop 1
	v_add_f32_dpp v26, v26, v26 row_half_mirror row_mask:0xf bank_mask:0xf bound_ctrl:1
	s_nop 1
	v_add_f32_dpp v26, v26, v26 row_mirror row_mask:0xf bank_mask:0xf bound_ctrl:1
	s_nop 0
	v_readlane_b32 s8, v26, 16
	v_readlane_b32 s9, v26, 48
	v_readlane_b32 s6, v26, 0
	v_readlane_b32 s7, v26, 32
	v_mov_b32_e32 v26, s8
	v_mov_b32_e32 v27, s9
	v_pk_add_f32 v[26:27], s[6:7], v[26:27]
	s_nop 0
	v_add_f32_e32 v26, v26, v27
	v_fmamk_f32 v26, v26, 0x3a000000, v252
	v_cmp_gt_f32_e32 vcc, s55, v26
	v_mul_f32_e32 v27, 0x4f800000, v26
	s_nop 0
	v_cndmask_b32_e32 v26, v26, v27, vcc
	v_sqrt_f32_e32 v27, v26
	s_nop 0
	v_add_u32_e32 v50, -1, v27
	v_fma_f32 v51, -v50, v27, v26
	v_cmp_ge_f32_e64 s[8:9], 0, v51
	v_add_u32_e32 v51, 1, v27
	s_nop 0
	v_cndmask_b32_e64 v50, v27, v50, s[8:9]
	v_fma_f32 v27, -v51, v27, v26
	v_cmp_lt_f32_e64 s[8:9], 0, v27
	s_nop 1
	v_cndmask_b32_e64 v27, v50, v51, s[8:9]
	v_mul_f32_e32 v50, 0x37800000, v27
	v_cndmask_b32_e32 v27, v27, v50, vcc
	v_cmp_class_f32_e32 vcc, v26, v253
	s_nop 1
	v_cndmask_b32_e32 v26, v27, v26, vcc
	v_div_scale_f32 v27, s[6:7], v26, v26, 1.0
	v_rcp_f32_e32 v50, v27
	s_lshl_b32 s6, s18, 1
	s_and_b32 s6, s6, 0xffffe000
	s_add_i32 s6, s6, 0
	v_fma_f32 v51, -v27, v50, 1.0
	v_fmac_f32_e32 v50, v51, v50
	v_div_scale_f32 v51, vcc, 1.0, v26, 1.0
	v_mul_f32_e32 v60, v51, v50
	v_fma_f32 v61, -v27, v60, v51
	v_fmac_f32_e32 v60, v61, v50
	v_fma_f32 v27, -v27, v60, v51
	v_div_fmas_f32 v27, v27, v50, v60
	v_div_fixup_f32 v50, v27, v26, 1.0
	v_pk_mul_f32 v[64:65], v[56:57], v[50:51] op_sel_hi:[1,0]
	v_pk_mul_f32 v[66:67], v[58:59], v[50:51] op_sel_hi:[1,0]
	v_add_u32_e32 v51, s6, v0
	ds_read_b128 v[56:59], v51
	ds_read_b128 v[60:63], v51 offset:40960
	v_lshl_add_u64 v[26:27], s[20:21], 1, v[2:3]
	v_lshl_add_u64 v[26:27], v[26:27], 0, v[6:7]
	v_pk_mul_f32 v[4:5], v[4:5], v[50:51] op_sel_hi:[1,0]
	v_pk_mul_f32 v[30:31], v[30:31], v[50:51] op_sel_hi:[1,0]
	s_waitcnt lgkmcnt(0)
	v_pk_fma_f32 v[58:59], v[58:59], v[66:67], v[62:63]
	v_pk_fma_f32 v[56:57], v[56:57], v[64:65], v[60:61]
	v_pk_mul_f32 v[60:61], v[52:53], v[50:51] op_sel_hi:[1,0]
	v_cvt_pk_bf16_f32 v56, v56, v57
	v_cvt_pk_bf16_f32 v57, v58, v59
	global_store_dwordx2 v[26:27], v[56:57], off nt
	v_pk_mul_f32 v[62:63], v[54:55], v[50:51] op_sel_hi:[1,0]
	ds_read_b128 v[52:55], v51 offset:1024
	ds_read_b128 v[56:59], v51 offset:41984
	s_waitcnt lgkmcnt(0)
	v_pk_fma_f32 v[54:55], v[54:55], v[62:63], v[58:59]
	v_pk_fma_f32 v[52:53], v[52:53], v[60:61], v[56:57]
	v_pk_mul_f32 v[56:57], v[42:43], v[50:51] op_sel_hi:[1,0]
	v_cvt_pk_bf16_f32 v52, v52, v53
	v_cvt_pk_bf16_f32 v53, v54, v55
	global_store_dwordx2 v[26:27], v[52:53], off offset:512 nt
	v_pk_mul_f32 v[58:59], v[44:45], v[50:51] op_sel_hi:[1,0]
	ds_read_b128 v[42:45], v51 offset:2048
	ds_read_b128 v[52:55], v51 offset:43008
	s_waitcnt lgkmcnt(0)
	v_pk_fma_f32 v[44:45], v[44:45], v[58:59], v[54:55]
	v_pk_fma_f32 v[42:43], v[42:43], v[56:57], v[52:53]
	v_pk_mul_f32 v[52:53], v[46:47], v[50:51] op_sel_hi:[1,0]
	v_cvt_pk_bf16_f32 v42, v42, v43
	v_cvt_pk_bf16_f32 v43, v44, v45
	global_store_dwordx2 v[26:27], v[42:43], off offset:1024 nt
	v_pk_mul_f32 v[54:55], v[48:49], v[50:51] op_sel_hi:[1,0]
	ds_read_b128 v[42:45], v51 offset:3072
	ds_read_b128 v[46:49], v51 offset:44032
	s_waitcnt lgkmcnt(0)
	v_pk_fma_f32 v[44:45], v[54:55], v[44:45], v[48:49]
	v_pk_fma_f32 v[42:43], v[52:53], v[42:43], v[46:47]
	v_pk_mul_f32 v[46:47], v[34:35], v[50:51] op_sel_hi:[1,0]
	v_cvt_pk_bf16_f32 v42, v42, v43
	v_cvt_pk_bf16_f32 v43, v44, v45
	global_store_dwordx2 v[26:27], v[42:43], off offset:1536 nt
	v_pk_mul_f32 v[48:49], v[36:37], v[50:51] op_sel_hi:[1,0]
	ds_read_b128 v[34:37], v51 offset:4096
	ds_read_b128 v[42:45], v51 offset:45056
	s_waitcnt lgkmcnt(0)
	v_pk_fma_f32 v[36:37], v[48:49], v[36:37], v[44:45]
	v_pk_fma_f32 v[34:35], v[46:47], v[34:35], v[42:43]
	v_pk_mul_f32 v[42:43], v[38:39], v[50:51] op_sel_hi:[1,0]
	v_cvt_pk_bf16_f32 v34, v34, v35
	v_cvt_pk_bf16_f32 v35, v36, v37
	global_store_dwordx2 v[26:27], v[34:35], off offset:2048 nt
	v_pk_mul_f32 v[44:45], v[40:41], v[50:51] op_sel_hi:[1,0]
	ds_read_b128 v[34:37], v51 offset:5120
	ds_read_b128 v[38:41], v51 offset:46080
	s_waitcnt lgkmcnt(0)
	v_pk_fma_f32 v[36:37], v[44:45], v[36:37], v[40:41]
	v_pk_fma_f32 v[34:35], v[42:43], v[34:35], v[38:39]
	s_waitcnt vmcnt(60)
	v_cvt_f32_f16_sdwa v43, v25 dst_sel:DWORD dst_unused:UNUSED_PAD src0_sel:WORD_1
	v_cvt_pk_bf16_f32 v34, v34, v35
	v_cvt_pk_bf16_f32 v35, v36, v37
	global_store_dwordx2 v[26:27], v[34:35], off offset:2560 nt
	ds_read_b128 v[34:37], v51 offset:6144
	ds_read_b128 v[38:41], v51 offset:47104
	v_cvt_f32_f16_e32 v42, v25
	s_waitcnt lgkmcnt(0)
	v_pk_fma_f32 v[30:31], v[30:31], v[36:37], v[40:41]
	v_pk_fma_f32 v[4:5], v[4:5], v[34:35], v[38:39]
	v_pk_mul_f32 v[36:37], v[32:33], v[50:51] op_sel_hi:[1,0]
	v_cvt_pk_bf16_f32 v4, v4, v5
	v_cvt_pk_bf16_f32 v5, v30, v31
	global_store_dwordx2 v[26:27], v[4:5], off offset:3072 nt
	v_pk_mul_f32 v[4:5], v[28:29], v[50:51] op_sel_hi:[1,0]
	ds_read_b128 v[28:31], v51 offset:7168
	ds_read_b128 v[32:35], v51 offset:48128
	v_cvt_f32_f16_sdwa v41, v24 dst_sel:DWORD dst_unused:UNUSED_PAD src0_sel:WORD_1
	v_cvt_f32_f16_e32 v40, v24
	s_waitcnt vmcnt(61)
	v_cvt_f32_f16_sdwa v39, v23 dst_sel:DWORD dst_unused:UNUSED_PAD src0_sel:WORD_1
	v_cvt_f32_f16_e32 v38, v23
	s_waitcnt lgkmcnt(0)
	v_pk_fma_f32 v[30:31], v[36:37], v[30:31], v[34:35]
	v_cvt_f32_f16_sdwa v37, v22 dst_sel:DWORD dst_unused:UNUSED_PAD src0_sel:WORD_1
	v_cvt_f32_f16_e32 v36, v22
	v_pk_fma_f32 v[4:5], v[4:5], v[28:29], v[32:33]
	v_mov_b32_e32 v22, v41
	v_cvt_pk_bf16_f32 v4, v4, v5
	v_cvt_pk_bf16_f32 v5, v30, v31
	global_store_dwordx2 v[26:27], v[4:5], off offset:3584 nt
	v_mov_b32_e32 v23, v37
	s_waitcnt vmcnt(61)
	v_cvt_f32_f16_sdwa v27, v20 dst_sel:DWORD dst_unused:UNUSED_PAD src0_sel:WORD_1
	v_cvt_f32_f16_sdwa v29, v21 dst_sel:DWORD dst_unused:UNUSED_PAD src0_sel:WORD_1
	v_mov_b32_e32 v4, v40
	v_mov_b32_e32 v5, v36
	v_pk_mul_f32 v[22:23], v[22:23], v[22:23]
	v_mov_b32_e32 v24, v43
	v_mov_b32_e32 v25, v39
	v_cvt_f32_f16_e32 v26, v20
	v_cvt_f32_f16_e32 v28, v21
	s_waitcnt vmcnt(60)
	v_cvt_f32_f16_sdwa v31, v18 dst_sel:DWORD dst_unused:UNUSED_PAD src0_sel:WORD_1
	v_pk_fma_f32 v[4:5], v[4:5], v[4:5], v[22:23]
	v_mov_b32_e32 v22, v42
	v_mov_b32_e32 v23, v38
	v_pk_mul_f32 v[24:25], v[24:25], v[24:25]
	v_cvt_f32_f16_e32 v30, v18
	v_cvt_f32_f16_sdwa v33, v19 dst_sel:DWORD dst_unused:UNUSED_PAD src0_sel:WORD_1
	v_pk_fma_f32 v[22:23], v[22:23], v[22:23], v[24:25]
	v_cvt_f32_f16_e32 v32, v19
	v_pk_add_f32 v[4:5], v[4:5], v[22:23]
	v_mov_b32_e32 v22, v27
	v_mov_b32_e32 v23, v29
	v_mov_b32_e32 v20, v26
	v_mov_b32_e32 v21, v28
	v_pk_mul_f32 v[22:23], v[22:23], v[22:23]
	v_mul_f32_e32 v18, v31, v31
	v_pk_fma_f32 v[20:21], v[20:21], v[20:21], v[22:23]
	v_pk_fma_f32 v[24:25], v[30:31], v[30:31], v[18:19] op_sel_hi:[1,1,0]
	v_mul_f32_e32 v18, v33, v33
	v_pk_add_f32 v[22:23], v[20:21], v[20:21] op_sel:[0,1] op_sel_hi:[1,0]
	v_pk_fma_f32 v[34:35], v[32:33], v[32:33], v[18:19] op_sel_hi:[1,1,0]
	s_waitcnt vmcnt(59)
	v_cvt_f32_f16_sdwa v19, v16 dst_sel:DWORD dst_unused:UNUSED_PAD src0_sel:WORD_1
	v_cvt_f32_f16_e32 v18, v16
	v_cvt_f32_f16_sdwa v21, v17 dst_sel:DWORD dst_unused:UNUSED_PAD src0_sel:WORD_1
	v_cvt_f32_f16_e32 v20, v17
	v_pk_add_f32 v[4:5], v[4:5], v[4:5] op_sel:[0,1] op_sel_hi:[1,0]
	v_pk_mul_f32 v[16:17], v[18:19], v[18:19]
	v_pk_mul_f32 v[44:45], v[20:21], v[20:21]
	v_mov_b32_e32 v5, v16
	v_mov_b32_e32 v23, v17
	v_mov_b32_e32 v25, v44
	v_mov_b32_e32 v35, v45
	v_pk_add_f32 v[4:5], v[4:5], v[22:23]
	v_pk_add_f32 v[16:17], v[24:25], v[34:35]
	s_waitcnt vmcnt(58)
	v_cvt_f32_f16_sdwa v23, v14 dst_sel:DWORD dst_unused:UNUSED_PAD src0_sel:WORD_1
	v_cvt_f32_f16_sdwa v25, v15 dst_sel:DWORD dst_unused:UNUSED_PAD src0_sel:WORD_1
	v_cvt_f32_f16_e32 v22, v14
	v_cvt_f32_f16_e32 v24, v15
	v_pk_add_f32 v[4:5], v[4:5], v[16:17]
	v_mov_b32_e32 v14, v23
	v_mov_b32_e32 v15, v25
	v_pk_add_f32 v[34:35], v[4:5], v[4:5] op_sel:[0,1] op_sel_hi:[1,0]
	v_mov_b32_e32 v4, v22
	v_mov_b32_e32 v5, v24
	v_pk_mul_f32 v[14:15], v[14:15], v[14:15]
	s_waitcnt vmcnt(56)
	v_cvt_f32_f16_sdwa v17, v11 dst_sel:DWORD dst_unused:UNUSED_PAD src0_sel:WORD_1
	v_pk_fma_f32 v[4:5], v[4:5], v[4:5], v[14:15]
	v_cvt_f32_f16_sdwa v15, v13 dst_sel:DWORD dst_unused:UNUSED_PAD src0_sel:WORD_1
	v_pk_add_f32 v[44:45], v[4:5], v[4:5] op_sel:[0,1] op_sel_hi:[1,0]
	v_cvt_f32_f16_sdwa v5, v12 dst_sel:DWORD dst_unused:UNUSED_PAD src0_sel:WORD_1
	v_cvt_f32_f16_e32 v4, v12
	v_cvt_f32_f16_e32 v14, v13
	v_cvt_f32_f16_e32 v16, v11
	v_mul_f32_e32 v12, v5, v5
	v_pk_fma_f32 v[46:47], v[4:5], v[4:5], v[12:13] op_sel_hi:[1,1,0]
	v_mul_f32_e32 v12, v15, v15
	v_pk_fma_f32 v[48:49], v[14:15], v[14:15], v[12:13] op_sel_hi:[1,1,0]
	v_cvt_f32_f16_sdwa v13, v10 dst_sel:DWORD dst_unused:UNUSED_PAD src0_sel:WORD_1
	v_cvt_f32_f16_e32 v12, v10
	v_pk_mul_f32 v[50:51], v[16:17], v[16:17]
	v_pk_mul_f32 v[10:11], v[12:13], v[12:13]
	s_nop 0
	v_mov_b32_e32 v35, v10
	v_mov_b32_e32 v45, v11
	v_mov_b32_e32 v47, v50
	v_mov_b32_e32 v49, v51
	v_pk_add_f32 v[10:11], v[34:35], v[44:45]
	v_pk_add_f32 v[34:35], v[46:47], v[48:49]
	s_nop 0
	v_pk_add_f32 v[10:11], v[10:11], v[34:35]
	s_nop 0
	v_add_f32_e32 v10, v10, v11
	s_nop 1
	v_add_f32_dpp v10, v10, v10 quad_perm:[1,0,3,2] row_mask:0xf bank_mask:0xf bound_ctrl:1
	s_nop 1
	v_add_f32_dpp v10, v10, v10 quad_perm:[2,3,0,1] row_mask:0xf bank_mask:0xf bound_ctrl:1
	s_nop 1
	v_add_f32_dpp v10, v10, v10 row_half_mirror row_mask:0xf bank_mask:0xf bound_ctrl:1
	s_nop 1
	v_add_f32_dpp v10, v10, v10 row_mirror row_mask:0xf bank_mask:0xf bound_ctrl:1
	s_nop 0
	v_readlane_b32 s8, v10, 16
	v_readlane_b32 s9, v10, 48
	v_readlane_b32 s6, v10, 0
	v_readlane_b32 s7, v10, 32
	v_mov_b32_e32 v10, s8
	v_mov_b32_e32 v11, s9
	v_pk_add_f32 v[10:11], s[6:7], v[10:11]
	s_nop 0
	v_add_f32_e32 v10, v10, v11
	v_fmamk_f32 v10, v10, 0x3a000000, v252
	v_cmp_gt_f32_e32 vcc, s55, v10
	v_mul_f32_e32 v11, 0x4f800000, v10
	s_nop 0
	v_cndmask_b32_e32 v10, v10, v11, vcc
	v_sqrt_f32_e32 v11, v10
	s_nop 0
	v_add_u32_e32 v34, -1, v11
	v_fma_f32 v35, -v34, v11, v10
	v_cmp_ge_f32_e64 s[8:9], 0, v35
	v_add_u32_e32 v35, 1, v11
	s_nop 0
	v_cndmask_b32_e64 v34, v11, v34, s[8:9]
	v_fma_f32 v11, -v35, v11, v10
	v_cmp_lt_f32_e64 s[8:9], 0, v11
	s_nop 1
	v_cndmask_b32_e64 v11, v34, v35, s[8:9]
	v_mul_f32_e32 v34, 0x37800000, v11
	v_cndmask_b32_e32 v11, v11, v34, vcc
	v_cmp_class_f32_e32 vcc, v10, v253
	s_add_i32 s8, s10, 0x4000
	s_nop 0
	v_cndmask_b32_e32 v10, v11, v10, vcc
	v_div_scale_f32 v11, s[6:7], v10, v10, 1.0
	v_rcp_f32_e32 v34, v11
	s_lshl_b32 s6, s14, 1
	s_and_b32 s6, s6, 0xffffe000
	s_add_i32 s6, s6, 0
	v_fma_f32 v35, -v11, v34, 1.0
	v_fmac_f32_e32 v34, v35, v34
	v_div_scale_f32 v35, vcc, 1.0, v10, 1.0
	v_mul_f32_e32 v44, v35, v34
	v_fma_f32 v45, -v11, v44, v35
	v_fmac_f32_e32 v44, v45, v34
	v_fma_f32 v11, -v11, v44, v35
	v_div_fmas_f32 v11, v11, v34, v44
	v_div_fixup_f32 v34, v11, v10, 1.0
	v_pk_mul_f32 v[48:49], v[40:41], v[34:35] op_sel_hi:[1,0]
	v_pk_mul_f32 v[50:51], v[42:43], v[34:35] op_sel_hi:[1,0]
	v_add_u32_e32 v35, s6, v0
	ds_read_b128 v[40:43], v35
	ds_read_b128 v[44:47], v35 offset:40960
	v_lshl_add_u64 v[10:11], s[16:17], 1, v[2:3]
	v_lshl_add_u64 v[10:11], v[10:11], 0, v[6:7]
	v_pk_mul_f32 v[4:5], v[4:5], v[34:35] op_sel_hi:[1,0]
	v_pk_mul_f32 v[14:15], v[14:15], v[34:35] op_sel_hi:[1,0]
	s_waitcnt lgkmcnt(0)
; #define GAS __attribute__((address_space(1)))
; __device__ __forceinline__ unsigned xpk2(float lo, float hi) { if (XRES_F16) { const f32x2_t v = {lo, hi}; const f16x2_t h = __builtin_convertvector(v, f16x2_t); return __builtin_bit_cast(unsigned, h); } return pk2(lo, hi); }
; __device__ __forceinline__ float xlo(unsigned w) { if (XRES_F16) { const f16x2_t h = __builtin_bit_cast(f16x2_t, w); return (float)h[0]; } return __builtin_bit_cast(float, w << 16); }
; __device__ __forceinline__ float xhi(unsigned w) { if (XRES_F16) { const f16x2_t h = __builtin_bit_cast(f16x2_t, w); return (float)h[1]; } return __builtin_bit_cast(float, w & 0xffff0000u); }
; __device__ __forceinline__ void norm_mod_phase2(const Args& a, Frame& F, const float* gain, const float* modl, int sh_off, int sc_off, int nrows, const float* slab_gate) {
;     ...
;     if (ML + nw < nrows) {
;         const int r = ML + nw, rc = nw;
;         const GAS v2u* xr = (const GAS v2u*)(X + (size_t)r * D) + F.lane;
; #pragma unroll
;         for (int j = 0; j < 8; ++j) r0[j] = xr[64 * j];
;         if (slab_gate != nullptr) { const GAS f32x4* sl = (const GAS f32x4*)((const float*)(a.ws + WS_SLAB) + (size_t)rc * D) + F.lane;
; #pragma unroll
;             for (int j = 0; j < 8; ++j) { const f32x4 p = (sl[64 * j] + sl[64 * j + (size_t)MC * D / 4]) + (sl[64 * j + 2 * ((size_t)MC * D / 4)] + sl[64 * j + 3 * ((size_t)MC * D / 4)]);
;                 const f32x4 x = (f32x4){xlo(r0[j].x), xhi(r0[j].x), xlo(r0[j].y), xhi(r0[j].y)} + *(const GAS f32x4*)(slab_gate + 256 * j + 4 * F.lane) * p;
;                 v2u w; w.x = xpk2(x[0], x[1]); w.y = xpk2(x[2], x[3]); ((GAS v2u*)(X + (size_t)r * D) + F.lane)[64 * j] = w; r0[j] = w; } }
	v_pk_fma_f32 v[42:43], v[42:43], v[50:51], v[46:47]
	v_pk_fma_f32 v[40:41], v[40:41], v[48:49], v[44:45]
	v_pk_mul_f32 v[44:45], v[36:37], v[34:35] op_sel_hi:[1,0]
	v_cvt_pk_bf16_f32 v40, v40, v41
	v_cvt_pk_bf16_f32 v41, v42, v43
	global_store_dwordx2 v[10:11], v[40:41], off nt
	v_pk_mul_f32 v[46:47], v[38:39], v[34:35] op_sel_hi:[1,0]
	ds_read_b128 v[36:39], v35 offset:1024
	ds_read_b128 v[40:43], v35 offset:41984
	s_cmp_lt_i32 s8, s47
	s_waitcnt lgkmcnt(0)
	v_pk_fma_f32 v[38:39], v[38:39], v[46:47], v[42:43]
	v_pk_fma_f32 v[36:37], v[36:37], v[44:45], v[40:41]
	v_pk_mul_f32 v[40:41], v[26:27], v[34:35] op_sel_hi:[1,0]
	v_cvt_pk_bf16_f32 v36, v36, v37
	v_cvt_pk_bf16_f32 v37, v38, v39
	global_store_dwordx2 v[10:11], v[36:37], off offset:512 nt
	v_pk_mul_f32 v[42:43], v[28:29], v[34:35] op_sel_hi:[1,0]
	ds_read_b128 v[26:29], v35 offset:2048
	ds_read_b128 v[36:39], v35 offset:43008
	s_waitcnt lgkmcnt(0)
	v_pk_fma_f32 v[28:29], v[28:29], v[42:43], v[38:39]
	v_pk_fma_f32 v[26:27], v[26:27], v[40:41], v[36:37]
	v_pk_mul_f32 v[36:37], v[30:31], v[34:35] op_sel_hi:[1,0]
	v_cvt_pk_bf16_f32 v26, v26, v27
	v_cvt_pk_bf16_f32 v27, v28, v29
	global_store_dwordx2 v[10:11], v[26:27], off offset:1024 nt
	v_pk_mul_f32 v[38:39], v[32:33], v[34:35] op_sel_hi:[1,0]
	ds_read_b128 v[26:29], v35 offset:3072
	ds_read_b128 v[30:33], v35 offset:44032
	s_waitcnt lgkmcnt(0)
	v_pk_fma_f32 v[28:29], v[38:39], v[28:29], v[32:33]
	v_pk_fma_f32 v[26:27], v[36:37], v[26:27], v[30:31]
	v_pk_mul_f32 v[30:31], v[18:19], v[34:35] op_sel_hi:[1,0]
	v_cvt_pk_bf16_f32 v26, v26, v27
	v_cvt_pk_bf16_f32 v27, v28, v29
	global_store_dwordx2 v[10:11], v[26:27], off offset:1536 nt
	v_pk_mul_f32 v[32:33], v[20:21], v[34:35] op_sel_hi:[1,0]
	ds_read_b128 v[18:21], v35 offset:4096
	ds_read_b128 v[26:29], v35 offset:45056
	s_waitcnt lgkmcnt(0)
	v_pk_fma_f32 v[20:21], v[32:33], v[20:21], v[28:29]
	v_pk_fma_f32 v[18:19], v[30:31], v[18:19], v[26:27]
	v_pk_mul_f32 v[26:27], v[22:23], v[34:35] op_sel_hi:[1,0]
	v_cvt_pk_bf16_f32 v18, v18, v19
	v_cvt_pk_bf16_f32 v19, v20, v21
	global_store_dwordx2 v[10:11], v[18:19], off offset:2048 nt
	v_pk_mul_f32 v[28:29], v[24:25], v[34:35] op_sel_hi:[1,0]
	ds_read_b128 v[18:21], v35 offset:5120
	ds_read_b128 v[22:25], v35 offset:46080
	s_waitcnt lgkmcnt(0)
	v_pk_fma_f32 v[20:21], v[28:29], v[20:21], v[24:25]
	v_pk_fma_f32 v[18:19], v[26:27], v[18:19], v[22:23]
	s_nop 0
	v_cvt_pk_bf16_f32 v18, v18, v19
	v_cvt_pk_bf16_f32 v19, v20, v21
	global_store_dwordx2 v[10:11], v[18:19], off offset:2560 nt
	ds_read_b128 v[18:21], v35 offset:6144
	ds_read_b128 v[22:25], v35 offset:47104
	s_waitcnt lgkmcnt(0)
	v_pk_fma_f32 v[14:15], v[14:15], v[20:21], v[24:25]
	v_pk_fma_f32 v[4:5], v[4:5], v[18:19], v[22:23]
	v_pk_mul_f32 v[20:21], v[16:17], v[34:35] op_sel_hi:[1,0]
	v_cvt_pk_bf16_f32 v4, v4, v5
	v_cvt_pk_bf16_f32 v5, v14, v15
	global_store_dwordx2 v[10:11], v[4:5], off offset:3072 nt
	v_pk_mul_f32 v[4:5], v[12:13], v[34:35] op_sel_hi:[1,0]
	ds_read_b128 v[12:15], v35 offset:7168
	ds_read_b128 v[16:19], v35 offset:48128
	s_waitcnt lgkmcnt(0)
	v_pk_fma_f32 v[14:15], v[20:21], v[14:15], v[18:19]
	v_pk_fma_f32 v[4:5], v[4:5], v[12:13], v[16:17]
	s_nop 0
	v_cvt_pk_bf16_f32 v4, v4, v5
	v_cvt_pk_bf16_f32 v5, v14, v15
	global_store_dwordx2 v[10:11], v[4:5], off offset:3584 nt
	s_cbranch_scc0 .LBB0_1050
	s_ashr_i32 s9, s8, 31
	s_lshl_b64 s[6:7], s[8:9], 12
	v_lshl_add_u64 v[4:5], v[8:9], 0, s[6:7]
	v_lshl_add_u64 v[18:19], v[4:5], 0, v[6:7]
	global_load_dwordx2 v[22:23], v[18:19], off
	global_load_dwordx2 v[20:21], v[18:19], off offset:512
	global_load_dwordx2 v[16:17], v[18:19], off offset:1024
	global_load_dwordx2 v[12:13], v[18:19], off offset:1536
	global_load_dwordx2 v[14:15], v[18:19], off offset:2048
	global_load_dwordx2 v[10:11], v[18:19], off offset:2560
	global_load_dwordx2 v[8:9], v[18:19], off offset:3072
	global_load_dwordx2 v[4:5], v[18:19], off offset:3584
	s_andn2_b64 vcc, exec, s[4:5]
	v_lshlrev_b32_e32 v46, 2, v147
	s_cbranch_vccnz .LBB0_1049
	v_mov_b32_e32 v24, s72
	v_mov_b32_e32 v25, s73
	v_lshl_add_u64 v[24:25], s[12:13], 2, v[24:25]
	v_lshl_add_u64 v[24:25], v[24:25], 0, v[0:1]
	v_lshlrev_b32_e32 v0, 2, v46
	v_lshl_add_u64 v[26:27], s[86:87], 0, v[0:1]
	v_add_co_u32_e32 v28, vcc, 0x58400000, v24
	s_nop 1
	v_addc_co_u32_e32 v29, vcc, 0, v25, vcc
	v_add_co_u32_e32 v30, vcc, 0x58c00000, v24
	s_nop 1
	v_addc_co_u32_e32 v31, vcc, 0, v25, vcc
	v_add_co_u32_e32 v32, vcc, 0x59400000, v24
	s_nop 1
	v_addc_co_u32_e32 v33, vcc, 0, v25, vcc
	v_add_co_u32_e32 v34, vcc, 0x59c00000, v24
	s_nop 1
	v_addc_co_u32_e32 v35, vcc, 0, v25, vcc
	v_add_co_u32_e32 v36, vcc, 0x58401000, v24
	s_nop 1
	v_addc_co_u32_e32 v37, vcc, 0, v25, vcc
	v_add_co_u32_e32 v38, vcc, 0x58c01000, v24
	s_nop 1
	v_addc_co_u32_e32 v39, vcc, 0, v25, vcc
	v_add_co_u32_e32 v42, vcc, 0x59401000, v24
	s_nop 1
	v_addc_co_u32_e32 v43, vcc, 0, v25, vcc
	v_add_co_u32_e32 v44, vcc, 0x59c01000, v24
	s_nop 1
	v_addc_co_u32_e32 v45, vcc, 0, v25, vcc
	v_add_co_u32_e32 v48, vcc, 0x34000, v26
	s_nop 1
	v_addc_co_u32_e32 v49, vcc, 0, v27, vcc
	v_add_co_u32_e32 v50, vcc, 0x35000, v26
	s_nop 1
	v_addc_co_u32_e32 v51, vcc, 0, v27, vcc
	global_load_dwordx4 v[94:97], v[28:29], off
	global_load_dwordx4 v[98:101], v[30:31], off
	global_load_dwordx4 v[102:105], v[32:33], off
	global_load_dwordx4 v[106:109], v[34:35], off
	global_load_dwordx4 v[110:113], v[48:49], off
	global_load_dwordx4 v[114:117], v[28:29], off offset:1024
	global_load_dwordx4 v[118:121], v[30:31], off offset:1024
	global_load_dwordx4 v[122:125], v[32:33], off offset:1024
	global_load_dwordx4 v[126:129], v[34:35], off offset:1024
	global_load_dwordx4 v[130:133], v[48:49], off offset:1024
	global_load_dwordx4 v[134:137], v[28:29], off offset:2048
	global_load_dwordx4 v[138:141], v[30:31], off offset:2048
	global_load_dwordx4 v[142:145], v[32:33], off offset:2048
	global_load_dwordx4 v[146:149], v[34:35], off offset:2048
	global_load_dwordx4 v[150:153], v[48:49], off offset:2048
	global_load_dwordx4 v[154:157], v[28:29], off offset:3072
	global_load_dwordx4 v[158:161], v[30:31], off offset:3072
	global_load_dwordx4 v[162:165], v[32:33], off offset:3072
	global_load_dwordx4 v[170:173], v[34:35], off offset:3072
	global_load_dwordx4 v[174:177], v[48:49], off offset:3072
	s_waitcnt vmcnt(15)
; #define GAS __attribute__((address_space(1)))
; __device__ __forceinline__ unsigned xpk2(float lo, float hi) { if (XRES_F16) { const f32x2_t v = {lo, hi}; const f16x2_t h = __builtin_convertvector(v, f16x2_t); return __builtin_bit_cast(unsigned, h); } return pk2(lo, hi); }
; __device__ __forceinline__ float xlo(unsigned w) { if (XRES_F16) { const f16x2_t h = __builtin_bit_cast(f16x2_t, w); return (float)h[0]; } return __builtin_bit_cast(float, w << 16); }
; __device__ __forceinline__ float xhi(unsigned w) { if (XRES_F16) { const f16x2_t h = __builtin_bit_cast(f16x2_t, w); return (float)h[1]; } return __builtin_bit_cast(float, w & 0xffff0000u); }
; __device__ __forceinline__ void norm_mod_phase2(const Args& a, Frame& F, const float* gain, const float* modl, int sh_off, int sc_off, int nrows, const float* slab_gate) {
;     ...
;         if (slab_gate != nullptr) { const GAS f32x4* sl = (const GAS f32x4*)((const float*)(a.ws + WS_SLAB) + (size_t)rc * D) + F.lane;
; #pragma unroll
;             for (int j = 0; j < 8; ++j) { const f32x4 p = (sl[64 * j] + sl[64 * j + (size_t)MC * D / 4]) + (sl[64 * j + 2 * ((size_t)MC * D / 4)] + sl[64 * j + 3 * ((size_t)MC * D / 4)]);
;                 const f32x4 x = (f32x4){xlo(r0[j].x), xhi(r0[j].x), xlo(r0[j].y), xhi(r0[j].y)} + *(const GAS f32x4*)(slab_gate + 256 * j + 4 * F.lane) * p;
;                 v2u w; w.x = xpk2(x[0], x[1]); w.y = xpk2(x[2], x[3]); ((GAS v2u*)(X + (size_t)r * D) + F.lane)[64 * j] = w; r0[j] = w; } }
	v_pk_add_f32 v[220:221], v[94:95], v[98:99]
	v_pk_add_f32 v[222:223], v[96:97], v[100:101]
	v_pk_add_f32 v[224:225], v[102:103], v[106:107]
	v_pk_add_f32 v[226:227], v[104:105], v[108:109]
	v_cvt_f32_f16_e32 v232, v22
	v_cvt_f32_f16_sdwa v233, v22 dst_sel:DWORD dst_unused:UNUSED_PAD src0_sel:WORD_1
	v_cvt_f32_f16_e32 v234, v23
	v_cvt_f32_f16_sdwa v235, v23 dst_sel:DWORD dst_unused:UNUSED_PAD src0_sel:WORD_1
	v_pk_add_f32 v[228:229], v[220:221], v[224:225]
	v_pk_add_f32 v[230:231], v[222:223], v[226:227]
	s_nop 1
	v_pk_fma_f32 v[236:237], v[110:111], v[228:229], v[232:233]
	v_pk_fma_f32 v[238:239], v[112:113], v[230:231], v[234:235]
	s_nop 1
	v_cvt_pk_f16_f32 v22, v236, v237
	v_cvt_pk_f16_f32 v23, v238, v239
	global_store_dwordx2 v[18:19], v[22:23], off
	global_load_dwordx4 v[94:97], v[36:37], off
	global_load_dwordx4 v[98:101], v[38:39], off
	global_load_dwordx4 v[102:105], v[42:43], off
	global_load_dwordx4 v[106:109], v[44:45], off
	global_load_dwordx4 v[110:113], v[50:51], off
	s_waitcnt vmcnt(16)
	v_pk_add_f32 v[220:221], v[114:115], v[118:119]
	v_pk_add_f32 v[222:223], v[116:117], v[120:121]
	v_pk_add_f32 v[224:225], v[122:123], v[126:127]
	v_pk_add_f32 v[226:227], v[124:125], v[128:129]
	v_cvt_f32_f16_e32 v232, v20
	v_cvt_f32_f16_sdwa v233, v20 dst_sel:DWORD dst_unused:UNUSED_PAD src0_sel:WORD_1
	v_cvt_f32_f16_e32 v234, v21
	v_cvt_f32_f16_sdwa v235, v21 dst_sel:DWORD dst_unused:UNUSED_PAD src0_sel:WORD_1
	v_pk_add_f32 v[228:229], v[220:221], v[224:225]
	v_pk_add_f32 v[230:231], v[222:223], v[226:227]
	s_nop 1
	v_pk_fma_f32 v[236:237], v[130:131], v[228:229], v[232:233]
	v_pk_fma_f32 v[238:239], v[132:133], v[230:231], v[234:235]
	s_nop 1
	v_cvt_pk_f16_f32 v20, v236, v237
	v_cvt_pk_f16_f32 v21, v238, v239
	global_store_dwordx2 v[18:19], v[20:21], off offset:512
	global_load_dwordx4 v[114:117], v[36:37], off offset:1024
	global_load_dwordx4 v[118:121], v[38:39], off offset:1024
	global_load_dwordx4 v[122:125], v[42:43], off offset:1024
	global_load_dwordx4 v[126:129], v[44:45], off offset:1024
	global_load_dwordx4 v[130:133], v[50:51], off offset:1024
	s_waitcnt vmcnt(17)
	v_pk_add_f32 v[220:221], v[134:135], v[138:139]
	v_pk_add_f32 v[222:223], v[136:137], v[140:141]
	v_pk_add_f32 v[224:225], v[142:143], v[146:147]
	v_pk_add_f32 v[226:227], v[144:145], v[148:149]
	v_cvt_f32_f16_e32 v232, v16
	v_cvt_f32_f16_sdwa v233, v16 dst_sel:DWORD dst_unused:UNUSED_PAD src0_sel:WORD_1
	v_cvt_f32_f16_e32 v234, v17
	v_cvt_f32_f16_sdwa v235, v17 dst_sel:DWORD dst_unused:UNUSED_PAD src0_sel:WORD_1
	v_pk_add_f32 v[228:229], v[220:221], v[224:225]
	v_pk_add_f32 v[230:231], v[222:223], v[226:227]
	s_nop 1
	v_pk_fma_f32 v[236:237], v[150:151], v[228:229], v[232:233]
	v_pk_fma_f32 v[238:239], v[152:153], v[230:231], v[234:235]
	s_nop 1
	v_cvt_pk_f16_f32 v16, v236, v237
	v_cvt_pk_f16_f32 v17, v238, v239
	global_store_dwordx2 v[18:19], v[16:17], off offset:1024
	global_load_dwordx4 v[134:137], v[36:37], off offset:2048
	global_load_dwordx4 v[138:141], v[38:39], off offset:2048
	global_load_dwordx4 v[142:145], v[42:43], off offset:2048
	global_load_dwordx4 v[146:149], v[44:45], off offset:2048
	global_load_dwordx4 v[150:153], v[50:51], off offset:2048
	s_waitcnt vmcnt(18)
	v_pk_add_f32 v[220:221], v[154:155], v[158:159]
	v_pk_add_f32 v[222:223], v[156:157], v[160:161]
	v_pk_add_f32 v[224:225], v[162:163], v[170:171]
	v_pk_add_f32 v[226:227], v[164:165], v[172:173]
	v_cvt_f32_f16_e32 v232, v12
	v_cvt_f32_f16_sdwa v233, v12 dst_sel:DWORD dst_unused:UNUSED_PAD src0_sel:WORD_1
	v_cvt_f32_f16_e32 v234, v13
	v_cvt_f32_f16_sdwa v235, v13 dst_sel:DWORD dst_unused:UNUSED_PAD src0_sel:WORD_1
	v_pk_add_f32 v[228:229], v[220:221], v[224:225]
	v_pk_add_f32 v[230:231], v[222:223], v[226:227]
	s_nop 1
	v_pk_fma_f32 v[236:237], v[174:175], v[228:229], v[232:233]
	v_pk_fma_f32 v[238:239], v[176:177], v[230:231], v[234:235]
	s_nop 1
	v_cvt_pk_f16_f32 v12, v236, v237
	v_cvt_pk_f16_f32 v13, v238, v239
	global_store_dwordx2 v[18:19], v[12:13], off offset:1536
	global_load_dwordx4 v[154:157], v[36:37], off offset:3072
	global_load_dwordx4 v[158:161], v[38:39], off offset:3072
	global_load_dwordx4 v[162:165], v[42:43], off offset:3072
	global_load_dwordx4 v[170:173], v[44:45], off offset:3072
	global_load_dwordx4 v[174:177], v[50:51], off offset:3072
	s_waitcnt vmcnt(18)
	v_pk_add_f32 v[220:221], v[94:95], v[98:99]
	v_pk_add_f32 v[222:223], v[96:97], v[100:101]
	v_pk_add_f32 v[224:225], v[102:103], v[106:107]
	v_pk_add_f32 v[226:227], v[104:105], v[108:109]
	v_cvt_f32_f16_e32 v232, v14
	v_cvt_f32_f16_sdwa v233, v14 dst_sel:DWORD dst_unused:UNUSED_PAD src0_sel:WORD_1
	v_cvt_f32_f16_e32 v234, v15
	v_cvt_f32_f16_sdwa v235, v15 dst_sel:DWORD dst_unused:UNUSED_PAD src0_sel:WORD_1
	v_pk_add_f32 v[228:229], v[220:221], v[224:225]
	v_pk_add_f32 v[230:231], v[222:223], v[226:227]
	s_nop 1
	v_pk_fma_f32 v[236:237], v[110:111], v[228:229], v[232:233]
	v_pk_fma_f32 v[238:239], v[112:113], v[230:231], v[234:235]
	s_nop 1
	v_cvt_pk_f16_f32 v14, v236, v237
	v_cvt_pk_f16_f32 v15, v238, v239
	global_store_dwordx2 v[18:19], v[14:15], off offset:2048
	s_waitcnt vmcnt(13)
	v_pk_add_f32 v[220:221], v[114:115], v[118:119]
	v_pk_add_f32 v[222:223], v[116:117], v[120:121]
	v_pk_add_f32 v[224:225], v[122:123], v[126:127]
	v_pk_add_f32 v[226:227], v[124:125], v[128:129]
	v_cvt_f32_f16_e32 v232, v10
	v_cvt_f32_f16_sdwa v233, v10 dst_sel:DWORD dst_unused:UNUSED_PAD src0_sel:WORD_1
	v_cvt_f32_f16_e32 v234, v11
	v_cvt_f32_f16_sdwa v235, v11 dst_sel:DWORD dst_unused:UNUSED_PAD src0_sel:WORD_1
	v_pk_add_f32 v[228:229], v[220:221], v[224:225]
	v_pk_add_f32 v[230:231], v[222:223], v[226:227]
	s_nop 1
	v_pk_fma_f32 v[236:237], v[130:131], v[228:229], v[232:233]
	v_pk_fma_f32 v[238:239], v[132:133], v[230:231], v[234:235]
	s_nop 1
	v_cvt_pk_f16_f32 v10, v236, v237
	v_cvt_pk_f16_f32 v11, v238, v239
	global_store_dwordx2 v[18:19], v[10:11], off offset:2560
	s_waitcnt vmcnt(8)
; #define GAS __attribute__((address_space(1)))
; __device__ __forceinline__ unsigned xpk2(float lo, float hi) { if (XRES_F16) { const f32x2_t v = {lo, hi}; const f16x2_t h = __builtin_convertvector(v, f16x2_t); return __builtin_bit_cast(unsigned, h); } return pk2(lo, hi); }
; __device__ __forceinline__ float xlo(unsigned w) { if (XRES_F16) { const f16x2_t h = __builtin_bit_cast(f16x2_t, w); return (float)h[0]; } return __builtin_bit_cast(float, w << 16); }
; __device__ __forceinline__ float xhi(unsigned w) { if (XRES_F16) { const f16x2_t h = __builtin_bit_cast(f16x2_t, w); return (float)h[1]; } return __builtin_bit_cast(float, w & 0xffff0000u); }
; __device__ __forceinline__ void norm_mod_phase2(const Args& a, Frame& F, const float* gain, const float* modl, int sh_off, int sc_off, int nrows, const float* slab_gate) {
;     ...
;         if (slab_gate != nullptr) { const GAS f32x4* sl = (const GAS f32x4*)((const float*)(a.ws + WS_SLAB) + (size_t)rc * D) + F.lane;
; #pragma unroll
;             for (int j = 0; j < 8; ++j) { const f32x4 p = (sl[64 * j] + sl[64 * j + (size_t)MC * D / 4]) + (sl[64 * j + 2 * ((size_t)MC * D / 4)] + sl[64 * j + 3 * ((size_t)MC * D / 4)]);
;                 const f32x4 x = (f32x4){xlo(r0[j].x), xhi(r0[j].x), xlo(r0[j].y), xhi(r0[j].y)} + *(const GAS f32x4*)(slab_gate + 256 * j + 4 * F.lane) * p;
;                 v2u w; w.x = xpk2(x[0], x[1]); w.y = xpk2(x[2], x[3]); ((GAS v2u*)(X + (size_t)r * D) + F.lane)[64 * j] = w; r0[j] = w; } }
	v_pk_add_f32 v[220:221], v[134:135], v[138:139]
	v_pk_add_f32 v[222:223], v[136:137], v[140:141]
	v_pk_add_f32 v[224:225], v[142:143], v[146:147]
	v_pk_add_f32 v[226:227], v[144:145], v[148:149]
	v_cvt_f32_f16_e32 v232, v8
	v_cvt_f32_f16_sdwa v233, v8 dst_sel:DWORD dst_unused:UNUSED_PAD src0_sel:WORD_1
	v_cvt_f32_f16_e32 v234, v9
	v_cvt_f32_f16_sdwa v235, v9 dst_sel:DWORD dst_unused:UNUSED_PAD src0_sel:WORD_1
	v_pk_add_f32 v[228:229], v[220:221], v[224:225]
	v_pk_add_f32 v[230:231], v[222:223], v[226:227]
	s_nop 1
	v_pk_fma_f32 v[236:237], v[150:151], v[228:229], v[232:233]
	v_pk_fma_f32 v[238:239], v[152:153], v[230:231], v[234:235]
	s_nop 1
	v_cvt_pk_f16_f32 v8, v236, v237
	v_cvt_pk_f16_f32 v9, v238, v239
	global_store_dwordx2 v[18:19], v[8:9], off offset:3072
	s_waitcnt vmcnt(3)
	v_pk_add_f32 v[220:221], v[154:155], v[158:159]
	v_pk_add_f32 v[222:223], v[156:157], v[160:161]
	v_pk_add_f32 v[224:225], v[162:163], v[170:171]
	v_pk_add_f32 v[226:227], v[164:165], v[172:173]
	v_cvt_f32_f16_e32 v232, v4
	v_cvt_f32_f16_sdwa v233, v4 dst_sel:DWORD dst_unused:UNUSED_PAD src0_sel:WORD_1
	v_cvt_f32_f16_e32 v234, v5
	v_cvt_f32_f16_sdwa v235, v5 dst_sel:DWORD dst_unused:UNUSED_PAD src0_sel:WORD_1
	v_pk_add_f32 v[228:229], v[220:221], v[224:225]
	v_pk_add_f32 v[230:231], v[222:223], v[226:227]
	s_nop 1
	v_pk_fma_f32 v[236:237], v[174:175], v[228:229], v[232:233]
	v_pk_fma_f32 v[238:239], v[176:177], v[230:231], v[234:235]
	s_nop 1
	v_cvt_pk_f16_f32 v4, v236, v237
	v_cvt_pk_f16_f32 v5, v238, v239
	global_store_dwordx2 v[18:19], v[4:5], off offset:3584
.LBB0_1049:
	s_waitcnt vmcnt(7)
	v_cvt_f32_f16_sdwa v37, v22 dst_sel:DWORD dst_unused:UNUSED_PAD src0_sel:WORD_1
	s_waitcnt vmcnt(6)
	v_cvt_f32_f16_sdwa v33, v20 dst_sel:DWORD dst_unused:UNUSED_PAD src0_sel:WORD_1
	v_cvt_f32_f16_e32 v36, v22
	v_cvt_f32_f16_sdwa v39, v23 dst_sel:DWORD dst_unused:UNUSED_PAD src0_sel:WORD_1
	v_cvt_f32_f16_e32 v32, v20
	v_cvt_f32_f16_sdwa v35, v21 dst_sel:DWORD dst_unused:UNUSED_PAD src0_sel:WORD_1
	v_cvt_f32_f16_e32 v38, v23
	v_cvt_f32_f16_e32 v34, v21
	v_mov_b32_e32 v20, v37
	v_mov_b32_e32 v21, v33
	v_mov_b32_e32 v18, v36
	v_mov_b32_e32 v19, v32
	v_pk_mul_f32 v[20:21], v[20:21], v[20:21]
	v_mov_b32_e32 v22, v39
	v_mov_b32_e32 v23, v35
	s_waitcnt vmcnt(5)
	v_cvt_f32_f16_sdwa v25, v16 dst_sel:DWORD dst_unused:UNUSED_PAD src0_sel:WORD_1
	v_cvt_f32_f16_sdwa v27, v17 dst_sel:DWORD dst_unused:UNUSED_PAD src0_sel:WORD_1
	v_pk_fma_f32 v[18:19], v[18:19], v[18:19], v[20:21]
	v_mov_b32_e32 v20, v38
	v_mov_b32_e32 v21, v34
	v_pk_mul_f32 v[22:23], v[22:23], v[22:23]
	v_cvt_f32_f16_e32 v24, v16
	v_cvt_f32_f16_e32 v26, v17
	v_pk_fma_f32 v[20:21], v[20:21], v[20:21], v[22:23]
	s_waitcnt vmcnt(4)
	v_cvt_f32_f16_e32 v28, v12
	v_pk_add_f32 v[18:19], v[18:19], v[20:21]
	v_mov_b32_e32 v16, v24
	v_pk_add_f32 v[20:21], v[18:19], v[18:19] op_sel_hi:[0,1]
	v_mov_b32_e32 v18, v25
	v_mov_b32_e32 v19, v27
	v_mov_b32_e32 v17, v26
	v_pk_mul_f32 v[18:19], v[18:19], v[18:19]
	v_cvt_f32_f16_sdwa v29, v12 dst_sel:DWORD dst_unused:UNUSED_PAD src0_sel:WORD_1
	v_pk_fma_f32 v[16:17], v[16:17], v[16:17], v[18:19]
	v_cvt_f32_f16_e32 v30, v13
	s_waitcnt vmcnt(3)
	v_cvt_f32_f16_sdwa v19, v15 dst_sel:DWORD dst_unused:UNUSED_PAD src0_sel:WORD_1
	v_cvt_f32_f16_e32 v18, v15
	v_pk_add_f32 v[22:23], v[16:17], v[16:17] op_sel_hi:[0,1]
	v_cvt_f32_f16_sdwa v31, v13 dst_sel:DWORD dst_unused:UNUSED_PAD src0_sel:WORD_1
	v_cvt_f32_f16_sdwa v17, v14 dst_sel:DWORD dst_unused:UNUSED_PAD src0_sel:WORD_1
	v_cvt_f32_f16_e32 v16, v14
	v_mul_f32_e32 v0, v28, v28
	v_pk_fma_f32 v[12:13], v[28:29], v[28:29], v[0:1] op_sel_hi:[1,1,0]
	v_mul_f32_e32 v0, v30, v30
	v_pk_mul_f32 v[42:43], v[18:19], v[18:19]
	v_pk_fma_f32 v[40:41], v[30:31], v[30:31], v[0:1] op_sel_hi:[1,1,0]
	v_pk_mul_f32 v[14:15], v[16:17], v[16:17]
	v_mov_b32_e32 v22, v42
	v_mov_b32_e32 v20, v43
	v_mov_b32_e32 v12, v14
	v_mov_b32_e32 v40, v15
	v_pk_add_f32 v[14:15], v[22:23], v[20:21]
	s_waitcnt vmcnt(2)
	v_cvt_f32_f16_sdwa v21, v10 dst_sel:DWORD dst_unused:UNUSED_PAD src0_sel:WORD_1
	v_cvt_f32_f16_sdwa v23, v11 dst_sel:DWORD dst_unused:UNUSED_PAD src0_sel:WORD_1
	v_cvt_f32_f16_e32 v20, v10
	v_cvt_f32_f16_e32 v22, v11
	v_pk_add_f32 v[12:13], v[12:13], v[40:41]
	s_lshl_b64 s[10:11], s[8:9], 11
	v_pk_add_f32 v[12:13], v[12:13], v[14:15]
	v_mov_b32_e32 v10, v20
	v_pk_add_f32 v[40:41], v[12:13], v[12:13] op_sel_hi:[0,1]
	v_mov_b32_e32 v12, v21
	v_mov_b32_e32 v13, v23
	v_mov_b32_e32 v11, v22
	v_pk_mul_f32 v[12:13], v[12:13], v[12:13]
	s_waitcnt vmcnt(0)
	v_cvt_f32_f16_sdwa v15, v5 dst_sel:DWORD dst_unused:UNUSED_PAD src0_sel:WORD_1
	v_pk_fma_f32 v[10:11], v[10:11], v[10:11], v[12:13]
	v_cvt_f32_f16_e32 v12, v9
	v_pk_add_f32 v[42:43], v[10:11], v[10:11] op_sel_hi:[0,1]
	v_cvt_f32_f16_e32 v10, v8
	v_cvt_f32_f16_sdwa v11, v8 dst_sel:DWORD dst_unused:UNUSED_PAD src0_sel:WORD_1
	v_cvt_f32_f16_sdwa v13, v9 dst_sel:DWORD dst_unused:UNUSED_PAD src0_sel:WORD_1
	v_cvt_f32_f16_sdwa v9, v4 dst_sel:DWORD dst_unused:UNUSED_PAD src0_sel:WORD_1
	v_cvt_f32_f16_e32 v8, v4
	v_cvt_f32_f16_e32 v14, v5
	v_mul_f32_e32 v0, v10, v10
	v_pk_fma_f32 v[44:45], v[10:11], v[10:11], v[0:1] op_sel_hi:[1,1,0]
	v_mul_f32_e32 v0, v12, v12
	v_pk_fma_f32 v[48:49], v[12:13], v[12:13], v[0:1] op_sel_hi:[1,1,0]
	v_pk_mul_f32 v[4:5], v[8:9], v[8:9]
	v_pk_mul_f32 v[50:51], v[14:15], v[14:15]
	v_mov_b32_e32 v44, v4
	v_mov_b32_e32 v48, v5
	v_mov_b32_e32 v42, v50
	v_mov_b32_e32 v40, v51
	v_pk_add_f32 v[4:5], v[44:45], v[48:49]
	v_pk_add_f32 v[40:41], v[42:43], v[40:41]
	v_lshl_add_u32 v44, v46, 2, 0
	v_pk_add_f32 v[4:5], v[4:5], v[40:41]
	v_lshl_add_u64 v[2:3], s[10:11], 1, v[2:3]
	v_add_f32_e32 v0, v4, v5
	v_add_u32_e32 v45, 0x12000, v44
	s_nop 0
	v_add_f32_dpp v0, v0, v0 quad_perm:[1,0,3,2] row_mask:0xf bank_mask:0xf bound_ctrl:1
	s_nop 1
	v_add_f32_dpp v0, v0, v0 quad_perm:[2,3,0,1] row_mask:0xf bank_mask:0xf bound_ctrl:1
	s_nop 1
	v_add_f32_dpp v0, v0, v0 row_half_mirror row_mask:0xf bank_mask:0xf bound_ctrl:1
	s_nop 1
	v_add_f32_dpp v0, v0, v0 row_mirror row_mask:0xf bank_mask:0xf bound_ctrl:1
	s_nop 0
	v_readlane_b32 s8, v0, 16
	v_readlane_b32 s9, v0, 48
	v_readlane_b32 s6, v0, 0
	v_readlane_b32 s7, v0, 32
	v_mov_b32_e32 v4, s8
	v_mov_b32_e32 v5, s9
	v_pk_add_f32 v[4:5], s[6:7], v[4:5]
	s_nop 0
	v_add_f32_e32 v0, v4, v5
	v_fmamk_f32 v0, v0, 0x3a000000, v252
	v_cmp_gt_f32_e32 vcc, s55, v0
	v_mul_f32_e32 v4, 0x4f800000, v0
	s_nop 0
	v_cndmask_b32_e32 v0, v0, v4, vcc
	v_sqrt_f32_e32 v4, v0
	s_nop 0
	v_add_u32_e32 v5, -1, v4
	v_fma_f32 v7, -v5, v4, v0
	v_cmp_ge_f32_e64 s[8:9], 0, v7
	v_add_u32_e32 v7, 1, v4
	s_nop 0
	v_cndmask_b32_e64 v5, v4, v5, s[8:9]
	v_fma_f32 v4, -v7, v4, v0
	v_cmp_lt_f32_e64 s[8:9], 0, v4
	s_nop 1
	v_cndmask_b32_e64 v4, v5, v7, s[8:9]
	v_mul_f32_e32 v5, 0x37800000, v4
	v_cndmask_b32_e32 v4, v4, v5, vcc
	v_cmp_class_f32_e32 vcc, v0, v253
	s_nop 1
	v_cndmask_b32_e32 v0, v4, v0, vcc
	v_div_scale_f32 v4, s[6:7], v0, v0, 1.0
	v_rcp_f32_e32 v5, v4
	s_nop 0
	v_fma_f32 v7, -v4, v5, 1.0
	v_fmac_f32_e32 v5, v7, v5
	v_div_scale_f32 v7, vcc, 1.0, v0, 1.0
	v_mul_f32_e32 v40, v7, v5
	v_fma_f32 v41, -v4, v40, v7
	v_fmac_f32_e32 v40, v41, v5
	v_fma_f32 v4, -v4, v40, v7
	v_div_fmas_f32 v4, v4, v5, v40
	v_div_fixup_f32 v0, v4, v0, 1.0
	v_mov_b32_e32 v7, v1
	v_lshl_add_u64 v[2:3], v[2:3], 0, v[6:7]
	v_pk_mul_f32 v[40:41], v[36:37], v[0:1] op_sel_hi:[1,0]
	v_pk_mul_f32 v[42:43], v[38:39], v[0:1] op_sel_hi:[1,0]
	ds_read_b128 v[4:7], v44 offset:32768
	ds_read_b128 v[36:39], v45
	v_pk_mul_f32 v[28:29], v[28:29], v[0:1] op_sel_hi:[1,0]
	v_pk_mul_f32 v[30:31], v[30:31], v[0:1] op_sel_hi:[1,0]
	v_pk_mul_f32 v[20:21], v[20:21], v[0:1] op_sel_hi:[1,0]
	v_pk_mul_f32 v[22:23], v[22:23], v[0:1] op_sel_hi:[1,0]
	s_waitcnt lgkmcnt(0)
	v_pk_fma_f32 v[6:7], v[6:7], v[42:43], v[38:39]
	v_pk_fma_f32 v[4:5], v[4:5], v[40:41], v[36:37]
	v_pk_mul_f32 v[36:37], v[32:33], v[0:1] op_sel_hi:[1,0]
	v_cvt_pk_bf16_f32 v4, v4, v5
	v_cvt_pk_bf16_f32 v5, v6, v7
	global_store_dwordx2 v[2:3], v[4:5], off nt
	v_pk_mul_f32 v[38:39], v[34:35], v[0:1] op_sel_hi:[1,0]
	ds_read_b128 v[4:7], v44 offset:33792
	ds_read_b128 v[32:35], v45 offset:1024
	v_pk_mul_f32 v[14:15], v[14:15], v[0:1] op_sel_hi:[1,0]
	s_waitcnt lgkmcnt(0)
	v_pk_fma_f32 v[6:7], v[6:7], v[38:39], v[34:35]
	v_pk_fma_f32 v[4:5], v[4:5], v[36:37], v[32:33]
	v_pk_mul_f32 v[32:33], v[24:25], v[0:1] op_sel_hi:[1,0]
	v_cvt_pk_bf16_f32 v4, v4, v5
	v_cvt_pk_bf16_f32 v5, v6, v7
	global_store_dwordx2 v[2:3], v[4:5], off offset:512 nt
	v_pk_mul_f32 v[34:35], v[26:27], v[0:1] op_sel_hi:[1,0]
	ds_read_b128 v[4:7], v44 offset:34816
	ds_read_b128 v[24:27], v45 offset:2048
	s_waitcnt lgkmcnt(0)
	v_pk_fma_f32 v[6:7], v[6:7], v[34:35], v[26:27]
	v_pk_fma_f32 v[4:5], v[4:5], v[32:33], v[24:25]
	s_nop 0
	v_cvt_pk_bf16_f32 v4, v4, v5
	v_cvt_pk_bf16_f32 v5, v6, v7
	global_store_dwordx2 v[2:3], v[4:5], off offset:1024 nt
	ds_read_b128 v[4:7], v44 offset:35840
	ds_read_b128 v[24:27], v45 offset:3072
	s_waitcnt lgkmcnt(0)
	v_pk_fma_f32 v[6:7], v[30:31], v[6:7], v[26:27]
	v_pk_fma_f32 v[4:5], v[28:29], v[4:5], v[24:25]
	v_pk_mul_f32 v[24:25], v[16:17], v[0:1] op_sel_hi:[1,0]
	v_cvt_pk_bf16_f32 v4, v4, v5
	v_cvt_pk_bf16_f32 v5, v6, v7
	global_store_dwordx2 v[2:3], v[4:5], off offset:1536 nt
	v_pk_mul_f32 v[26:27], v[18:19], v[0:1] op_sel_hi:[1,0]
	ds_read_b128 v[4:7], v44 offset:36864
	ds_read_b128 v[16:19], v45 offset:4096
	s_waitcnt lgkmcnt(0)
	v_pk_fma_f32 v[6:7], v[26:27], v[6:7], v[18:19]
	v_pk_fma_f32 v[4:5], v[24:25], v[4:5], v[16:17]
	s_nop 0
	v_cvt_pk_bf16_f32 v4, v4, v5
	v_cvt_pk_bf16_f32 v5, v6, v7
	global_store_dwordx2 v[2:3], v[4:5], off offset:2048 nt
	ds_read_b128 v[4:7], v44 offset:37888
	ds_read_b128 v[16:19], v45 offset:5120
	s_waitcnt lgkmcnt(0)
	v_pk_fma_f32 v[6:7], v[22:23], v[6:7], v[18:19]
	v_pk_fma_f32 v[4:5], v[20:21], v[4:5], v[16:17]
	v_pk_mul_f32 v[16:17], v[10:11], v[0:1] op_sel_hi:[1,0]
	v_cvt_pk_bf16_f32 v4, v4, v5
	v_cvt_pk_bf16_f32 v5, v6, v7
	global_store_dwordx2 v[2:3], v[4:5], off offset:2560 nt
	v_pk_mul_f32 v[18:19], v[12:13], v[0:1] op_sel_hi:[1,0]
	ds_read_b128 v[4:7], v44 offset:38912
	ds_read_b128 v[10:13], v45 offset:6144
	s_waitcnt lgkmcnt(0)
	v_pk_fma_f32 v[6:7], v[18:19], v[6:7], v[12:13]
	v_pk_fma_f32 v[4:5], v[16:17], v[4:5], v[10:11]
	v_pk_mul_f32 v[12:13], v[8:9], v[0:1] op_sel_hi:[1,0]
	v_cvt_pk_bf16_f32 v4, v4, v5
	v_cvt_pk_bf16_f32 v5, v6, v7
	global_store_dwordx2 v[2:3], v[4:5], off offset:3072 nt
	ds_read_b128 v[4:7], v44 offset:39936
	ds_read_b128 v[8:11], v45 offset:7168
	s_waitcnt lgkmcnt(0)
	v_pk_fma_f32 v[6:7], v[14:15], v[6:7], v[10:11]
	v_pk_fma_f32 v[4:5], v[12:13], v[4:5], v[8:9]
	s_nop 0
	v_cvt_pk_bf16_f32 v4, v4, v5
	v_cvt_pk_bf16_f32 v5, v6, v7
	global_store_dwordx2 v[2:3], v[4:5], off offset:3584 nt

; #define GAS __attribute__((address_space(1)))
; __device__ __forceinline__ float xlo(unsigned w) { if (XRES_F16) { const f16x2_t h = __builtin_bit_cast(f16x2_t, w); return (float)h[0]; } return __builtin_bit_cast(float, w << 16); }
; __device__ __forceinline__ float xhi(unsigned w) { if (XRES_F16) { const f16x2_t h = __builtin_bit_cast(f16x2_t, w); return (float)h[1]; } return __builtin_bit_cast(float, w & 0xffff0000u); }
; __device__ __forceinline__ void final_norm_phase(const Args& a, Frame& F) {
;     ...
;     for (int r = gw; r < ML; r += NGW) {
;         const GAS v2u* xr = (const GAS v2u*)(X + (size_t)r * D) + F.lane;
;         f32x4 v[8]; float ss = 0.f;
; #pragma unroll
;         for (int j = 0; j < 8; ++j) { const v2u w = xr[64 * j]; v[j] = (f32x4){xlo(w.x), xhi(w.x), xlo(w.y), xhi(w.y)}; ss += (v[j][0] * v[j][0] + v[j][1] * v[j][1]) + (v[j][2] * v[j][2] + v[j][3] * v[j][3]); }
;         const float rstd = 1.0f / sqrtf(wave_sum(ss) * (1.0f / D) + EPS);
.LBB0_1333:
	global_load_dwordx2 v[20:21], v[12:13], off offset:-2048
	global_load_dwordx2 v[22:23], v[12:13], off offset:-1536
	global_load_dwordx2 v[24:25], v[12:13], off offset:-1024
	global_load_dwordx2 v[26:27], v[12:13], off offset:-512
	global_load_dwordx2 v[28:29], v[12:13], off
	global_load_dwordx2 v[30:31], v[12:13], off offset:512
	global_load_dwordx2 v[32:33], v[12:13], off offset:1024
	global_load_dwordx2 v[34:35], v[12:13], off offset:1536
	global_load_dwordx4 v[16:19], v[0:1], off
	s_add_i32 s4, s4, s42
	v_lshl_add_u64 v[12:13], v[12:13], 0, s[74:75]
	s_cmpk_lt_i32 s4, 0x4000
	s_waitcnt vmcnt(8)
	v_cvt_f32_f16_sdwa v37, v20 dst_sel:DWORD dst_unused:UNUSED_PAD src0_sel:WORD_1
	v_cvt_f32_f16_e32 v36, v20
	v_cvt_f32_f16_sdwa v39, v21 dst_sel:DWORD dst_unused:UNUSED_PAD src0_sel:WORD_1
	v_cvt_f32_f16_e32 v38, v21
	s_waitcnt vmcnt(7)
	v_cvt_f32_f16_e32 v21, v23
	v_cvt_f32_f16_e32 v20, v22
	v_cvt_f32_f16_sdwa v23, v23 dst_sel:DWORD dst_unused:UNUSED_PAD src0_sel:WORD_1
	v_cvt_f32_f16_sdwa v22, v22 dst_sel:DWORD dst_unused:UNUSED_PAD src0_sel:WORD_1
	s_waitcnt vmcnt(6)
	v_cvt_f32_f16_sdwa v41, v24 dst_sel:DWORD dst_unused:UNUSED_PAD src0_sel:WORD_1
	v_cvt_f32_f16_sdwa v43, v25 dst_sel:DWORD dst_unused:UNUSED_PAD src0_sel:WORD_1
	v_cvt_f32_f16_e32 v40, v24
	v_cvt_f32_f16_e32 v42, v25
	s_waitcnt vmcnt(5)
	v_cvt_f32_f16_sdwa v25, v26 dst_sel:DWORD dst_unused:UNUSED_PAD src0_sel:WORD_1
	v_cvt_f32_f16_e32 v24, v26
	v_cvt_f32_f16_sdwa v45, v27 dst_sel:DWORD dst_unused:UNUSED_PAD src0_sel:WORD_1
	v_cvt_f32_f16_e32 v44, v27
	s_waitcnt vmcnt(4)
	v_cvt_f32_f16_e32 v27, v29
	v_cvt_f32_f16_e32 v26, v28
	v_cvt_f32_f16_sdwa v29, v29 dst_sel:DWORD dst_unused:UNUSED_PAD src0_sel:WORD_1
	v_cvt_f32_f16_sdwa v28, v28 dst_sel:DWORD dst_unused:UNUSED_PAD src0_sel:WORD_1
	s_waitcnt vmcnt(2)
	v_cvt_f32_f16_sdwa v49, v32 dst_sel:DWORD dst_unused:UNUSED_PAD src0_sel:WORD_1
	v_cvt_f32_f16_e32 v48, v32
	v_cvt_f32_f16_sdwa v51, v33 dst_sel:DWORD dst_unused:UNUSED_PAD src0_sel:WORD_1
	v_cvt_f32_f16_e32 v50, v33
	s_waitcnt vmcnt(1)
	v_cvt_f32_f16_sdwa v33, v34 dst_sel:DWORD dst_unused:UNUSED_PAD src0_sel:WORD_1
	v_cvt_f32_f16_e32 v32, v34
	v_mul_f32_e32 v34, v37, v37
	v_mul_f32_e32 v54, v39, v39
	v_pk_mul_f32 v[56:57], v[22:23], v[22:23]
	v_cvt_f32_f16_e32 v47, v31
	v_cvt_f32_f16_e32 v46, v30
	v_cvt_f32_f16_sdwa v31, v31 dst_sel:DWORD dst_unused:UNUSED_PAD src0_sel:WORD_1
	v_cvt_f32_f16_sdwa v30, v30 dst_sel:DWORD dst_unused:UNUSED_PAD src0_sel:WORD_1
	v_cvt_f32_f16_sdwa v53, v35 dst_sel:DWORD dst_unused:UNUSED_PAD src0_sel:WORD_1
	v_cvt_f32_f16_e32 v52, v35
	v_mul_f32_e32 v58, v41, v41
	v_mul_f32_e32 v60, v43, v43
	v_pk_fma_f32 v[34:35], v[36:37], v[36:37], v[34:35] op_sel_hi:[1,1,0]
	v_pk_fma_f32 v[54:55], v[38:39], v[38:39], v[54:55] op_sel_hi:[1,1,0]
	v_pk_fma_f32 v[56:57], v[20:21], v[20:21], v[56:57]
	v_pk_mul_f32 v[62:63], v[24:25], v[24:25]
	v_pk_mul_f32 v[64:65], v[44:45], v[44:45]
	v_pk_fma_f32 v[58:59], v[40:41], v[40:41], v[58:59] op_sel_hi:[1,1,0]
	v_pk_fma_f32 v[60:61], v[42:43], v[42:43], v[60:61] op_sel_hi:[1,1,0]
	v_pk_add_f32 v[56:57], v[56:57], v[56:57] op_sel:[0,1] op_sel_hi:[1,0]
	v_pk_add_f32 v[34:35], v[34:35], v[54:55]
	v_mov_b32_e32 v59, v64
	v_mov_b32_e32 v61, v65
	v_mov_b32_e32 v35, v62
	v_mov_b32_e32 v57, v63
	v_pk_mul_f32 v[66:67], v[28:29], v[28:29]
	v_pk_add_f32 v[58:59], v[58:59], v[60:61]
	v_pk_add_f32 v[34:35], v[34:35], v[56:57]
	v_pk_mul_f32 v[68:69], v[30:31], v[30:31]
	v_pk_fma_f32 v[66:67], v[26:27], v[26:27], v[66:67]
	v_pk_add_f32 v[34:35], v[34:35], v[58:59]
	v_mul_f32_e32 v70, v49, v49
	v_mul_f32_e32 v72, v51, v51
	v_pk_fma_f32 v[68:69], v[46:47], v[46:47], v[68:69]
	v_pk_add_f32 v[54:55], v[66:67], v[66:67] op_sel:[0,1] op_sel_hi:[1,0]
	v_pk_add_f32 v[34:35], v[34:35], v[34:35] op_sel:[0,1] op_sel_hi:[1,0]
	v_pk_mul_f32 v[74:75], v[32:33], v[32:33]
	v_pk_mul_f32 v[76:77], v[52:53], v[52:53]
	v_pk_fma_f32 v[70:71], v[48:49], v[48:49], v[70:71] op_sel_hi:[1,1,0]
	v_pk_fma_f32 v[72:73], v[50:51], v[50:51], v[72:73] op_sel_hi:[1,1,0]
	v_pk_add_f32 v[64:65], v[68:69], v[68:69] op_sel:[0,1] op_sel_hi:[1,0]
	v_pk_add_f32 v[34:35], v[34:35], v[54:55]
	v_mov_b32_e32 v71, v76
	v_mov_b32_e32 v73, v77
	v_mov_b32_e32 v65, v75
	v_mov_b32_e32 v35, v74
	v_pk_add_f32 v[60:61], v[70:71], v[72:73]
	v_pk_add_f32 v[34:35], v[34:35], v[64:65]
	s_nop 0
	v_pk_add_f32 v[34:35], v[34:35], v[60:61]
	s_nop 0
	v_add_f32_e32 v34, v34, v35
	s_nop 1
	v_add_f32_dpp v34, v34, v34 quad_perm:[1,0,3,2] row_mask:0xf bank_mask:0xf bound_ctrl:1
	s_nop 1
	v_add_f32_dpp v34, v34, v34 quad_perm:[2,3,0,1] row_mask:0xf bank_mask:0xf bound_ctrl:1
	s_nop 1
	v_add_f32_dpp v34, v34, v34 row_half_mirror row_mask:0xf bank_mask:0xf bound_ctrl:1
	s_nop 1
	v_add_f32_dpp v34, v34, v34 row_mirror row_mask:0xf bank_mask:0xf bound_ctrl:1
	s_nop 0
	v_readlane_b32 s6, v34, 16
	v_readlane_b32 s7, v34, 48
	v_readlane_b32 s0, v34, 0
	v_readlane_b32 s1, v34, 32
	v_mov_b32_e32 v34, s6
	v_mov_b32_e32 v35, s7
	v_pk_add_f32 v[34:35], s[0:1], v[34:35]
	s_nop 0
	v_add_f32_e32 v34, v34, v35
	v_fmamk_f32 v34, v34, 0x3a000000, v14
	v_mul_f32_e32 v35, 0x4f800000, v34
	v_cmp_gt_f32_e32 vcc, s5, v34
	s_nop 1
	v_cndmask_b32_e32 v34, v34, v35, vcc
	v_sqrt_f32_e32 v35, v34
	s_nop 0
	v_add_u32_e32 v54, -1, v35
	v_add_u32_e32 v55, 1, v35
	v_fma_f32 v56, -v54, v35, v34
	v_fma_f32 v57, -v55, v35, v34
	v_cmp_ge_f32_e64 s[0:1], 0, v56
	s_nop 1
	v_cndmask_b32_e64 v35, v35, v54, s[0:1]
	v_cmp_lt_f32_e64 s[0:1], 0, v57
	s_nop 1
	v_cndmask_b32_e64 v35, v35, v55, s[0:1]
	v_mul_f32_e32 v54, 0x37800000, v35
	v_cndmask_b32_e32 v35, v35, v54, vcc
	v_cmp_class_f32_e32 vcc, v34, v15
	s_nop 1
	v_cndmask_b32_e32 v34, v35, v34, vcc
	v_div_scale_f32 v35, s[0:1], v34, v34, 1.0
	v_rcp_f32_e32 v55, v35
	v_div_scale_f32 v54, vcc, 1.0, v34, 1.0
	v_fma_f32 v56, -v35, v55, 1.0
	v_fmac_f32_e32 v55, v56, v55
	v_mul_f32_e32 v56, v54, v55
	v_fma_f32 v57, -v35, v56, v54
	v_fmac_f32_e32 v56, v57, v55
	v_fma_f32 v35, -v35, v56, v54
	v_div_fmas_f32 v35, v35, v55, v56
	v_div_fixup_f32 v34, v35, v34, 1.0
	v_pk_mul_f32 v[36:37], v[36:37], v[34:35] op_sel_hi:[1,0]
	v_pk_mul_f32 v[38:39], v[38:39], v[34:35] op_sel_hi:[1,0]
	s_waitcnt vmcnt(0)
; #define GAS __attribute__((address_space(1)))
; __device__ __forceinline__ void final_norm_phase(const Args& a, Frame& F) {
;     ...
;         const float rstd = 1.0f / sqrtf(wave_sum(ss) * (1.0f / D) + EPS);
;         GAS f32x4* o = (GAS f32x4*)(a.out + (size_t)r * D) + F.lane;
; #pragma unroll
;         for (int j = 0; j < 8; ++j) o[64 * j] = (v[j] * rstd) * *(const GAS f32x4*)(gain + 256 * j + 4 * F.lane);
	v_pk_mul_f32 v[16:17], v[16:17], v[36:37]
	v_pk_mul_f32 v[18:19], v[18:19], v[38:39]
	global_store_dwordx4 v[10:11], v[16:19], off offset:-4096 nt
	global_load_dwordx4 v[16:19], v[0:1], off offset:1024
	v_mov_b32_e32 v36, v21
	v_mov_b32_e32 v37, v23
	v_mov_b32_e32 v21, v22
	v_pk_mul_f32 v[22:23], v[36:37], v[34:35] op_sel_hi:[1,0]
	v_pk_mul_f32 v[20:21], v[20:21], v[34:35] op_sel_hi:[1,0]
	s_waitcnt vmcnt(0)
	v_pk_mul_f32 v[18:19], v[18:19], v[22:23]
	v_pk_mul_f32 v[16:17], v[16:17], v[20:21]
	global_store_dwordx4 v[10:11], v[16:19], off offset:-3072 nt
	global_load_dwordx4 v[16:19], v[0:1], off offset:2048
	v_pk_mul_f32 v[20:21], v[42:43], v[34:35] op_sel_hi:[1,0]
	v_pk_mul_f32 v[22:23], v[40:41], v[34:35] op_sel_hi:[1,0]
	s_waitcnt vmcnt(0)
	v_pk_mul_f32 v[18:19], v[18:19], v[20:21]
	v_pk_mul_f32 v[16:17], v[16:17], v[22:23]
	global_store_dwordx4 v[10:11], v[16:19], off offset:-2048 nt
	global_load_dwordx4 v[16:19], v[0:1], off offset:3072
	v_pk_mul_f32 v[20:21], v[44:45], v[34:35] op_sel_hi:[1,0]
	v_pk_mul_f32 v[22:23], v[24:25], v[34:35] op_sel_hi:[1,0]
	s_waitcnt vmcnt(0)
	v_pk_mul_f32 v[18:19], v[18:19], v[20:21]
	v_pk_mul_f32 v[16:17], v[16:17], v[22:23]
	global_store_dwordx4 v[10:11], v[16:19], off offset:-1024 nt
	global_load_dwordx4 v[16:19], v[2:3], off
	v_mov_b32_e32 v20, v27
	v_mov_b32_e32 v21, v29
	v_mov_b32_e32 v27, v28
	v_pk_mul_f32 v[20:21], v[20:21], v[34:35] op_sel_hi:[1,0]
	v_pk_mul_f32 v[22:23], v[26:27], v[34:35] op_sel_hi:[1,0]
	s_waitcnt vmcnt(0)
	v_pk_mul_f32 v[18:19], v[18:19], v[20:21]
	v_pk_mul_f32 v[16:17], v[16:17], v[22:23]
	global_store_dwordx4 v[10:11], v[16:19], off nt
	global_load_dwordx4 v[16:19], v[4:5], off
	v_mov_b32_e32 v20, v47
	v_mov_b32_e32 v21, v31
	v_mov_b32_e32 v47, v30
	v_pk_mul_f32 v[20:21], v[20:21], v[34:35] op_sel_hi:[1,0]
	v_pk_mul_f32 v[22:23], v[46:47], v[34:35] op_sel_hi:[1,0]
	s_waitcnt vmcnt(0)
	v_pk_mul_f32 v[18:19], v[20:21], v[18:19]
	v_pk_mul_f32 v[16:17], v[22:23], v[16:17]
	global_store_dwordx4 v[10:11], v[16:19], off offset:1024 nt
	global_load_dwordx4 v[16:19], v[6:7], off
	v_pk_mul_f32 v[20:21], v[50:51], v[34:35] op_sel_hi:[1,0]
	v_pk_mul_f32 v[22:23], v[48:49], v[34:35] op_sel_hi:[1,0]
	s_waitcnt vmcnt(0)
	v_pk_mul_f32 v[18:19], v[20:21], v[18:19]
	v_pk_mul_f32 v[16:17], v[22:23], v[16:17]
	global_store_dwordx4 v[10:11], v[16:19], off offset:2048 nt
	global_load_dwordx4 v[16:19], v[8:9], off
	v_pk_mul_f32 v[20:21], v[52:53], v[34:35] op_sel_hi:[1,0]
	v_pk_mul_f32 v[22:23], v[32:33], v[34:35] op_sel_hi:[1,0]
	s_waitcnt vmcnt(0)
	v_pk_mul_f32 v[18:19], v[20:21], v[18:19]
	v_pk_mul_f32 v[16:17], v[22:23], v[16:17]
	global_store_dwordx4 v[10:11], v[16:19], off offset:3072 nt
	v_lshl_add_u64 v[10:11], v[10:11], 0, s[2:3]
	s_cbranch_scc1 .LBB0_1333

; #define GAS __attribute__((address_space(1)))
; #define LAS __attribute__((address_space(3)))
; #define FN_LOAD(dst, k_) do { const GAS v2u* xr_ = (const GAS v2u*)(X + (size_t)(nw + 2048 * (k_)) * D) + F.lane; \
;         _Pragma("unroll") for (int j = 0; j < 8; ++j) dst[j] = __builtin_nontemporal_load(xr_ + 64 * j); } while (0)
; __device__ __forceinline__ void final_norm_phase2(const Args& a, Frame& F) {
;     ...
;     FN_LOAD(r0, 0); FN_LOAD(r1, 1); FN_LOAD(r2, 2); FN_LOAD(r3, 3); FN_LOAD(r4, 4); FN_LOAD(r5, 5); FN_LOAD(r6, 6); FN_LOAD(r7, 7);
;     for (int q = F.tid; q < D / 4; q += NWAVES * 64) ((LAS f32x4*)GL)[q] = ((const GAS f32x4*)gain)[q];
;     asm volatile("s_waitcnt lgkmcnt(0)" ::: "memory"); __builtin_amdgcn_s_barrier(); asm volatile("" ::: "memory");
;     FN_FINISH(r0, 0); FN_FINISH(r1, 1); FN_FINISH(r2, 2); FN_FINISH(r3, 3); FN_FINISH(r4, 4); FN_FINISH(r5, 5); FN_FINISH(r6, 6); FN_FINISH(r7, 7);
.LBB0_1339:
	s_or_b64 exec, exec, s[10:11]
	s_waitcnt vmcnt(0)
	v_cvt_f32_f16_sdwa v17, v14 dst_sel:DWORD dst_unused:UNUSED_PAD src0_sel:WORD_1
	v_cvt_f32_f16_sdwa v21, v15 dst_sel:DWORD dst_unused:UNUSED_PAD src0_sel:WORD_1
	v_cvt_f32_f16_e32 v20, v15
	v_cvt_f32_f16_sdwa v15, v12 dst_sel:DWORD dst_unused:UNUSED_PAD src0_sel:WORD_1
	v_cvt_f32_f16_e32 v16, v14
	v_cvt_f32_f16_e32 v14, v12
	v_cvt_f32_f16_sdwa v23, v13 dst_sel:DWORD dst_unused:UNUSED_PAD src0_sel:WORD_1
	v_cvt_f32_f16_e32 v22, v13
	v_mov_b32_e32 v24, v17
	v_mov_b32_e32 v25, v15
	v_mov_b32_e32 v12, v16
	v_mov_b32_e32 v13, v14
	v_pk_mul_f32 v[24:25], v[24:25], v[24:25]
	v_mov_b32_e32 v26, v21
	v_mov_b32_e32 v27, v23
	v_pk_fma_f32 v[12:13], v[12:13], v[12:13], v[24:25]
	v_mov_b32_e32 v24, v20
	v_mov_b32_e32 v25, v22
	v_pk_mul_f32 v[26:27], v[26:27], v[26:27]
	v_cvt_f32_f16_sdwa v31, v9 dst_sel:DWORD dst_unused:UNUSED_PAD src0_sel:WORD_1
	v_pk_fma_f32 v[24:25], v[24:25], v[24:25], v[26:27]
	v_cvt_f32_f16_sdwa v27, v11 dst_sel:DWORD dst_unused:UNUSED_PAD src0_sel:WORD_1
	v_pk_add_f32 v[12:13], v[12:13], v[24:25]
	v_cvt_f32_f16_sdwa v25, v10 dst_sel:DWORD dst_unused:UNUSED_PAD src0_sel:WORD_1
	v_cvt_f32_f16_e32 v24, v10
	v_cvt_f32_f16_e32 v26, v11
	v_mov_b32_e32 v29, v27
	v_mov_b32_e32 v28, v25
	v_mov_b32_e32 v10, v24
	v_mov_b32_e32 v11, v26
	v_pk_mul_f32 v[28:29], v[28:29], v[28:29]
	v_cvt_f32_f16_e32 v30, v9
	v_pk_fma_f32 v[10:11], v[10:11], v[10:11], v[28:29]
	v_cvt_f32_f16_sdwa v29, v8 dst_sel:DWORD dst_unused:UNUSED_PAD src0_sel:WORD_1
	v_cvt_f32_f16_e32 v28, v8
	v_cvt_f32_f16_sdwa v157, v7 dst_sel:DWORD dst_unused:UNUSED_PAD src0_sel:WORD_1
	v_cvt_f32_f16_e32 v156, v7
	v_cvt_f32_f16_sdwa v155, v6 dst_sel:DWORD dst_unused:UNUSED_PAD src0_sel:WORD_1
	v_cvt_f32_f16_e32 v154, v6
	v_cvt_f32_f16_sdwa v159, v4 dst_sel:DWORD dst_unused:UNUSED_PAD src0_sel:WORD_1
	v_cvt_f32_f16_sdwa v161, v5 dst_sel:DWORD dst_unused:UNUSED_PAD src0_sel:WORD_1
	v_mul_f32_e32 v8, v29, v29
	v_mul_f32_e32 v6, v31, v31
	v_cvt_f32_f16_e32 v158, v4
	v_cvt_f32_f16_e32 v160, v5
	v_pk_fma_f32 v[8:9], v[28:29], v[28:29], v[8:9] op_sel_hi:[1,1,0]
	v_pk_fma_f32 v[6:7], v[30:31], v[30:31], v[6:7] op_sel_hi:[1,1,0]
	v_pk_mul_f32 v[146:147], v[156:157], v[156:157]
	v_cvt_f32_f16_sdwa v163, v2 dst_sel:DWORD dst_unused:UNUSED_PAD src0_sel:WORD_1
	v_cvt_f32_f16_sdwa v165, v3 dst_sel:DWORD dst_unused:UNUSED_PAD src0_sel:WORD_1
	v_pk_add_f32 v[12:13], v[12:13], v[12:13] op_sel:[0,1] op_sel_hi:[1,0]
	v_pk_add_f32 v[10:11], v[10:11], v[10:11] op_sel:[0,1] op_sel_hi:[1,0]
	v_pk_mul_f32 v[48:49], v[154:155], v[154:155]
	v_mov_b32_e32 v9, v146
	v_mov_b32_e32 v7, v147
	v_cvt_f32_f16_e32 v162, v2
	v_cvt_f32_f16_e32 v164, v3
	v_cvt_f32_f16_sdwa v147, v0 dst_sel:DWORD dst_unused:UNUSED_PAD src0_sel:WORD_1
	v_cvt_f32_f16_e32 v146, v0
	v_cvt_f32_f16_sdwa v149, v1 dst_sel:DWORD dst_unused:UNUSED_PAD src0_sel:WORD_1
	v_cvt_f32_f16_e32 v148, v1
	v_mov_b32_e32 v13, v48
	v_mov_b32_e32 v11, v49
	v_pk_add_f32 v[6:7], v[8:9], v[6:7]
	v_mov_b32_e32 v8, v159
	v_mov_b32_e32 v9, v161
	v_pk_add_f32 v[10:11], v[12:13], v[10:11]
	v_mov_b32_e32 v4, v158
	v_mov_b32_e32 v5, v160
	v_pk_mul_f32 v[8:9], v[8:9], v[8:9]
	v_pk_add_f32 v[6:7], v[10:11], v[6:7]
	v_pk_fma_f32 v[4:5], v[4:5], v[4:5], v[8:9]
	v_mul_f32_e32 v2, v163, v163
	v_mul_f32_e32 v0, v165, v165
	v_pk_add_f32 v[6:7], v[6:7], v[6:7] op_sel:[0,1] op_sel_hi:[1,0]
	v_pk_add_f32 v[4:5], v[4:5], v[4:5] op_sel:[0,1] op_sel_hi:[1,0]
	v_pk_fma_f32 v[2:3], v[162:163], v[162:163], v[2:3] op_sel_hi:[1,1,0]
	v_pk_fma_f32 v[0:1], v[164:165], v[164:165], v[0:1] op_sel_hi:[1,1,0]
	v_pk_mul_f32 v[8:9], v[146:147], v[146:147]
	v_pk_mul_f32 v[10:11], v[148:149], v[148:149]
	v_mov_b32_e32 v7, v8
	v_mov_b32_e32 v5, v9
	v_mov_b32_e32 v3, v10
	v_mov_b32_e32 v1, v11
	v_pk_add_f32 v[4:5], v[6:7], v[4:5]
	v_pk_add_f32 v[0:1], v[2:3], v[0:1]
	s_lshl_b64 s[10:11], s[6:7], 11
	v_pk_add_f32 v[0:1], v[4:5], v[0:1]
	s_lshl_b64 s[6:7], s[18:19], 11
	v_add_f32_e32 v0, v0, v1
	s_lshl_b64 s[16:17], s[0:1], 11
	v_mov_b32_e32 v151, 0x358637bd
	v_add_f32_dpp v0, v0, v0 quad_perm:[1,0,3,2] row_mask:0xf bank_mask:0xf bound_ctrl:1
	v_mov_b32_e32 v152, 0x260
	v_lshlrev_b32_e32 v48, 4, v18
	v_add_f32_dpp v0, v0, v0 quad_perm:[2,3,0,1] row_mask:0xf bank_mask:0xf bound_ctrl:1
	s_waitcnt lgkmcnt(0)
	s_barrier
; #define GAS __attribute__((address_space(1)))
; #define LAS __attribute__((address_space(3)))
; #define FN_LOAD(dst, k_) do { const GAS v2u* xr_ = (const GAS v2u*)(X + (size_t)(nw + 2048 * (k_)) * D) + F.lane; \
;         _Pragma("unroll") for (int j = 0; j < 8; ++j) dst[j] = __builtin_nontemporal_load(xr_ + 64 * j); } while (0)
; __device__ __forceinline__ void final_norm_phase2(const Args& a, Frame& F) {
;     ...
;     FN_LOAD(r0, 0); FN_LOAD(r1, 1); FN_LOAD(r2, 2); FN_LOAD(r3, 3); FN_LOAD(r4, 4); FN_LOAD(r5, 5); FN_LOAD(r6, 6); FN_LOAD(r7, 7);
;     for (int q = F.tid; q < D / 4; q += NWAVES * 64) ((LAS f32x4*)GL)[q] = ((const GAS f32x4*)gain)[q];
;     asm volatile("s_waitcnt lgkmcnt(0)" ::: "memory"); __builtin_amdgcn_s_barrier(); asm volatile("" ::: "memory");
;     FN_FINISH(r0, 0); FN_FINISH(r1, 1); FN_FINISH(r2, 2); FN_FINISH(r3, 3); FN_FINISH(r4, 4); FN_FINISH(r5, 5); FN_FINISH(r6, 6); FN_FINISH(r7, 7);
	v_add_u32_e32 v153, 0, v48
	v_add_f32_dpp v0, v0, v0 row_half_mirror row_mask:0xf bank_mask:0xf bound_ctrl:1
	s_lshl_b64 s[14:15], s[2:3], 11
	s_lshl_b64 s[12:13], s[4:5], 11
	v_add_f32_dpp v0, v0, v0 row_mirror row_mask:0xf bank_mask:0xf bound_ctrl:1
	s_lshl_b64 s[8:9], s[8:9], 11
	v_readlane_b32 s18, v0, 16
	v_readlane_b32 s19, v0, 48
	v_readlane_b32 s0, v0, 0
	v_readlane_b32 s1, v0, 32
	v_mov_b32_e32 v0, s18
	v_mov_b32_e32 v1, s19
	v_pk_add_f32 v[0:1], s[0:1], v[0:1]
	s_mov_b32 s18, 0xf800000
	v_add_f32_e32 v0, v0, v1
	v_fmamk_f32 v0, v0, 0x3a000000, v151
	v_mul_f32_e32 v1, 0x4f800000, v0
	v_cmp_gt_f32_e32 vcc, s18, v0
	s_lshl_b64 s[4:5], s[20:21], 11
	s_lshl_b64 s[2:3], s[22:23], 11
	v_cndmask_b32_e32 v0, v0, v1, vcc
	v_sqrt_f32_e32 v1, v0
	v_mov_b32_e32 v49, 0
	v_cvt_f32_f16_sdwa v173, v139 dst_sel:DWORD dst_unused:UNUSED_PAD src0_sel:WORD_1
	v_cvt_f32_f16_e32 v172, v139
	v_add_u32_e32 v2, -1, v1
	v_fma_f32 v3, -v2, v1, v0
	v_cmp_ge_f32_e64 s[0:1], 0, v3
	v_add_u32_e32 v3, 1, v1
	v_cvt_f32_f16_sdwa v175, v136 dst_sel:DWORD dst_unused:UNUSED_PAD src0_sel:WORD_1
	v_cndmask_b32_e64 v2, v1, v2, s[0:1]
	v_fma_f32 v1, -v3, v1, v0
	v_cmp_lt_f32_e64 s[0:1], 0, v1
	v_cvt_f32_f16_e32 v174, v136
	v_cvt_f32_f16_sdwa v177, v137 dst_sel:DWORD dst_unused:UNUSED_PAD src0_sel:WORD_1
	v_cndmask_b32_e64 v1, v2, v3, s[0:1]
	v_mul_f32_e32 v2, 0x37800000, v1
	v_cndmask_b32_e32 v1, v1, v2, vcc
	v_cmp_class_f32_e32 vcc, v0, v152
	v_cvt_f32_f16_e32 v176, v137
	v_mul_f32_e32 v136, v173, v173
	v_cndmask_b32_e32 v0, v1, v0, vcc
	v_div_scale_f32 v1, s[0:1], v0, v0, 1.0
	v_rcp_f32_e32 v2, v1
	s_lshl_b64 s[0:1], s[16:17], 2
	s_add_u32 s0, s24, s0
	s_addc_u32 s1, s25, s1
	v_fma_f32 v3, -v1, v2, 1.0
	v_fmac_f32_e32 v2, v3, v2
	v_div_scale_f32 v3, vcc, 1.0, v0, 1.0
	v_mul_f32_e32 v4, v3, v2
	v_fma_f32 v5, -v1, v4, v3
	v_fmac_f32_e32 v4, v5, v2
	v_fma_f32 v1, -v1, v4, v3
	v_div_fmas_f32 v1, v1, v2, v4
	v_div_fixup_f32 v150, v1, v0, 1.0
	ds_read_b128 v[0:3], v153
	ds_read_b128 v[4:7], v153 offset:1024
	v_pk_mul_f32 v[8:9], v[16:17], v[150:151] op_sel_hi:[1,0]
	v_pk_mul_f32 v[10:11], v[20:21], v[150:151] op_sel_hi:[1,0]
	v_pk_mul_f32 v[16:17], v[24:25], v[150:151] op_sel_hi:[1,0]
	s_waitcnt lgkmcnt(1)
	v_pk_mul_f32 v[10:11], v[2:3], v[10:11]
	v_pk_mul_f32 v[8:9], v[0:1], v[8:9]
	global_store_dwordx4 v48, v[8:11], s[0:1] nt
	v_pk_mul_f32 v[18:19], v[26:27], v[150:151] op_sel_hi:[1,0]
	v_lshl_add_u64 v[166:167], s[0:1], 0, v[48:49]
	v_pk_mul_f32 v[8:9], v[14:15], v[150:151] op_sel_hi:[1,0]
	v_pk_mul_f32 v[10:11], v[22:23], v[150:151] op_sel_hi:[1,0]
	s_waitcnt lgkmcnt(0)
	v_pk_mul_f32 v[12:13], v[4:5], v[8:9]
	v_pk_mul_f32 v[14:15], v[6:7], v[10:11]
	ds_read_b128 v[8:11], v153 offset:2048
	global_store_dwordx4 v48, v[12:15], s[0:1] offset:1024 nt
	ds_read_b128 v[12:15], v153 offset:3072
	s_movk_i32 s16, 0x1000
	v_pk_mul_f32 v[24:25], v[154:155], v[150:151] op_sel_hi:[1,0]
	s_waitcnt lgkmcnt(1)
	v_pk_mul_f32 v[18:19], v[10:11], v[18:19]
	v_pk_mul_f32 v[16:17], v[8:9], v[16:17]
	global_store_dwordx4 v48, v[16:19], s[0:1] offset:2048 nt
	v_pk_mul_f32 v[26:27], v[156:157], v[150:151] op_sel_hi:[1,0]
	v_add_co_u32_e32 v166, vcc, s16, v166
	v_pk_mul_f32 v[16:17], v[28:29], v[150:151] op_sel_hi:[1,0]
	v_pk_mul_f32 v[18:19], v[30:31], v[150:151] op_sel_hi:[1,0]
	s_waitcnt lgkmcnt(0)
	v_pk_mul_f32 v[20:21], v[12:13], v[16:17]
	v_pk_mul_f32 v[22:23], v[14:15], v[18:19]
	ds_read_b128 v[16:19], v153 offset:4096
	global_store_dwordx4 v48, v[20:23], s[0:1] offset:3072 nt
	ds_read_b128 v[20:23], v153 offset:5120
	v_addc_co_u32_e32 v167, vcc, 0, v167, vcc
	s_waitcnt lgkmcnt(1)
	v_pk_mul_f32 v[26:27], v[18:19], v[26:27]
	v_pk_mul_f32 v[24:25], v[16:17], v[24:25]
	global_store_dwordx4 v[166:167], v[24:27], off nt
	v_pk_mul_f32 v[154:155], v[162:163], v[150:151] op_sel_hi:[1,0]
	v_cvt_f32_f16_sdwa v163, v143 dst_sel:DWORD dst_unused:UNUSED_PAD src0_sel:WORD_1
	v_pk_mul_f32 v[24:25], v[158:159], v[150:151] op_sel_hi:[1,0]
	v_pk_mul_f32 v[26:27], v[160:161], v[150:151] op_sel_hi:[1,0]
	v_cvt_f32_f16_sdwa v159, v144 dst_sel:DWORD dst_unused:UNUSED_PAD src0_sel:WORD_1
	v_cvt_f32_f16_sdwa v161, v145 dst_sel:DWORD dst_unused:UNUSED_PAD src0_sel:WORD_1
	v_cvt_f32_f16_e32 v160, v145
	v_cvt_f32_f16_sdwa v145, v142 dst_sel:DWORD dst_unused:UNUSED_PAD src0_sel:WORD_1
	v_cvt_f32_f16_e32 v158, v144
	v_cvt_f32_f16_e32 v144, v142
	v_cvt_f32_f16_e32 v162, v143
	v_pk_mul_f32 v[156:157], v[164:165], v[150:151] op_sel_hi:[1,0]
	v_mov_b32_e32 v164, v159
	v_mov_b32_e32 v165, v145
	v_mov_b32_e32 v142, v158
	v_mov_b32_e32 v143, v144
	v_pk_mul_f32 v[164:165], v[164:165], v[164:165]
	v_mov_b32_e32 v168, v161
	v_mov_b32_e32 v169, v163
	v_pk_fma_f32 v[142:143], v[142:143], v[142:143], v[164:165]
	v_mov_b32_e32 v164, v160
	v_mov_b32_e32 v165, v162
	v_pk_mul_f32 v[168:169], v[168:169], v[168:169]
	v_pk_fma_f32 v[136:137], v[172:173], v[172:173], v[136:137] op_sel_hi:[1,1,0]
	v_pk_fma_f32 v[164:165], v[164:165], v[164:165], v[168:169]
	v_cvt_f32_f16_sdwa v169, v141 dst_sel:DWORD dst_unused:UNUSED_PAD src0_sel:WORD_1
	v_pk_add_f32 v[142:143], v[142:143], v[164:165]
	v_cvt_f32_f16_sdwa v165, v140 dst_sel:DWORD dst_unused:UNUSED_PAD src0_sel:WORD_1
	v_cvt_f32_f16_e32 v164, v140
	v_cvt_f32_f16_e32 v168, v141
	v_mov_b32_e32 v171, v169
	v_mov_b32_e32 v170, v165
	v_mov_b32_e32 v140, v164
	v_mov_b32_e32 v141, v168
	v_pk_mul_f32 v[170:171], v[170:171], v[170:171]
	v_pk_add_f32 v[142:143], v[142:143], v[142:143] op_sel:[0,1] op_sel_hi:[1,0]
	v_pk_fma_f32 v[140:141], v[140:141], v[140:141], v[170:171]
	v_cvt_f32_f16_sdwa v171, v138 dst_sel:DWORD dst_unused:UNUSED_PAD src0_sel:WORD_1
	v_cvt_f32_f16_e32 v170, v138
; #define GAS __attribute__((address_space(1)))
; #define LAS __attribute__((address_space(3)))
; #define FN_LOAD(dst, k_) do { const GAS v2u* xr_ = (const GAS v2u*)(X + (size_t)(nw + 2048 * (k_)) * D) + F.lane; \
;         _Pragma("unroll") for (int j = 0; j < 8; ++j) dst[j] = __builtin_nontemporal_load(xr_ + 64 * j); } while (0)
; __device__ __forceinline__ void final_norm_phase2(const Args& a, Frame& F) {
;     ...
;     FN_LOAD(r0, 0); FN_LOAD(r1, 1); FN_LOAD(r2, 2); FN_LOAD(r3, 3); FN_LOAD(r4, 4); FN_LOAD(r5, 5); FN_LOAD(r6, 6); FN_LOAD(r7, 7);
;     for (int q = F.tid; q < D / 4; q += NWAVES * 64) ((LAS f32x4*)GL)[q] = ((const GAS f32x4*)gain)[q];
;     asm volatile("s_waitcnt lgkmcnt(0)" ::: "memory"); __builtin_amdgcn_s_barrier(); asm volatile("" ::: "memory");
;     FN_FINISH(r0, 0); FN_FINISH(r1, 1); FN_FINISH(r2, 2); FN_FINISH(r3, 3); FN_FINISH(r4, 4); FN_FINISH(r5, 5); FN_FINISH(r6, 6); FN_FINISH(r7, 7);
	v_pk_add_f32 v[140:141], v[140:141], v[140:141] op_sel:[0,1] op_sel_hi:[1,0]
	v_pk_mul_f32 v[178:179], v[174:175], v[174:175]
	v_mul_f32_e32 v138, v171, v171
	v_pk_fma_f32 v[138:139], v[170:171], v[170:171], v[138:139] op_sel_hi:[1,1,0]
	v_pk_mul_f32 v[180:181], v[176:177], v[176:177]
	v_mov_b32_e32 v143, v178
	v_mov_b32_e32 v141, v179
	v_mov_b32_e32 v139, v180
	v_mov_b32_e32 v137, v181
	v_pk_add_f32 v[140:141], v[142:143], v[140:141]
	v_pk_add_f32 v[136:137], v[138:139], v[136:137]
	v_cvt_f32_f16_sdwa v143, v135 dst_sel:DWORD dst_unused:UNUSED_PAD src0_sel:WORD_1
	v_pk_add_f32 v[136:137], v[140:141], v[136:137]
	v_cvt_f32_f16_sdwa v141, v134 dst_sel:DWORD dst_unused:UNUSED_PAD src0_sel:WORD_1
	v_cvt_f32_f16_e32 v140, v134
	v_cvt_f32_f16_e32 v142, v135
	v_cvt_f32_f16_sdwa v179, v132 dst_sel:DWORD dst_unused:UNUSED_PAD src0_sel:WORD_1
	v_cvt_f32_f16_e32 v178, v132
	v_mov_b32_e32 v138, v141
	v_mov_b32_e32 v139, v143
	v_mov_b32_e32 v134, v140
	v_mov_b32_e32 v135, v142
	v_pk_mul_f32 v[138:139], v[138:139], v[138:139]
	v_cvt_f32_f16_sdwa v181, v133 dst_sel:DWORD dst_unused:UNUSED_PAD src0_sel:WORD_1
	v_pk_fma_f32 v[134:135], v[134:135], v[134:135], v[138:139]
	v_mul_f32_e32 v132, v179, v179
	v_pk_add_f32 v[138:139], v[134:135], v[134:135] op_sel:[0,1] op_sel_hi:[1,0]
	v_cvt_f32_f16_e32 v180, v133
	v_pk_fma_f32 v[182:183], v[178:179], v[178:179], v[132:133] op_sel_hi:[1,1,0]
	v_cvt_f32_f16_sdwa v133, v130 dst_sel:DWORD dst_unused:UNUSED_PAD src0_sel:WORD_1
	v_cvt_f32_f16_e32 v132, v130
	v_cvt_f32_f16_sdwa v135, v131 dst_sel:DWORD dst_unused:UNUSED_PAD src0_sel:WORD_1
	v_cvt_f32_f16_e32 v134, v131
	v_mul_f32_e32 v130, v181, v181
	v_pk_add_f32 v[136:137], v[136:137], v[136:137] op_sel:[0,1] op_sel_hi:[1,0]
	v_pk_fma_f32 v[130:131], v[180:181], v[180:181], v[130:131] op_sel_hi:[1,1,0]
	v_pk_mul_f32 v[184:185], v[132:133], v[132:133]
	v_pk_mul_f32 v[186:187], v[134:135], v[134:135]
	v_mov_b32_e32 v137, v184
	v_mov_b32_e32 v139, v185
	v_mov_b32_e32 v183, v186
	v_mov_b32_e32 v131, v187
	v_pk_add_f32 v[136:137], v[136:137], v[138:139]
	v_pk_add_f32 v[130:131], v[182:183], v[130:131]
	s_waitcnt lgkmcnt(0)
	v_pk_mul_f32 v[30:31], v[26:27], v[22:23]
	v_pk_add_f32 v[130:131], v[136:137], v[130:131]
	v_pk_mul_f32 v[28:29], v[24:25], v[20:21]
	v_add_f32_e32 v130, v130, v131
	ds_read_b128 v[24:27], v153 offset:6144
	global_store_dwordx4 v[166:167], v[28:31], off offset:1024 nt
	v_add_f32_dpp v130, v130, v130 quad_perm:[1,0,3,2] row_mask:0xf bank_mask:0xf bound_ctrl:1
	ds_read_b128 v[28:31], v153 offset:7168
	v_pk_mul_f32 v[136:137], v[148:149], v[150:151] op_sel_hi:[1,0]
	v_add_f32_dpp v130, v130, v130 quad_perm:[2,3,0,1] row_mask:0xf bank_mask:0xf bound_ctrl:1
	s_waitcnt lgkmcnt(1)
	v_pk_mul_f32 v[156:157], v[156:157], v[26:27]
	v_pk_mul_f32 v[154:155], v[154:155], v[24:25]
	v_add_f32_dpp v130, v130, v130 row_half_mirror row_mask:0xf bank_mask:0xf bound_ctrl:1
	global_store_dwordx4 v[166:167], v[154:157], off offset:2048 nt
	s_nop 0
	v_add_f32_dpp v130, v130, v130 row_mirror row_mask:0xf bank_mask:0xf bound_ctrl:1
	s_nop 0
	v_readlane_b32 s17, v130, 16
	v_readlane_b32 s19, v130, 48
	v_readlane_b32 s0, v130, 0
	v_readlane_b32 s1, v130, 32
	v_mov_b32_e32 v130, s17
	v_mov_b32_e32 v131, s19
	v_pk_add_f32 v[130:131], s[0:1], v[130:131]
	s_nop 0
	v_add_f32_e32 v130, v130, v131
	v_fmamk_f32 v130, v130, 0x3a000000, v151
	v_mul_f32_e32 v131, 0x4f800000, v130
	v_cmp_gt_f32_e32 vcc, s18, v130
	s_nop 1
	v_cndmask_b32_e32 v138, v130, v131, vcc
	v_sqrt_f32_e32 v139, v138
	v_pk_mul_f32 v[130:131], v[146:147], v[150:151] op_sel_hi:[1,0]
	v_add_u32_e32 v146, -1, v139
	v_fma_f32 v147, -v146, v139, v138
	v_cmp_ge_f32_e64 s[0:1], 0, v147
	v_add_u32_e32 v147, 1, v139
	s_nop 0
	v_cndmask_b32_e64 v146, v139, v146, s[0:1]
	v_fma_f32 v139, -v147, v139, v138
	v_cmp_lt_f32_e64 s[0:1], 0, v139
	s_nop 1
	v_cndmask_b32_e64 v139, v146, v147, s[0:1]
	v_mul_f32_e32 v146, 0x37800000, v139
	v_cndmask_b32_e32 v139, v139, v146, vcc
	v_cmp_class_f32_e32 vcc, v138, v152
	s_nop 1
	v_cndmask_b32_e32 v146, v139, v138, vcc
	v_div_scale_f32 v147, s[0:1], v146, v146, 1.0
	v_rcp_f32_e32 v148, v147
	s_waitcnt lgkmcnt(0)
	v_pk_mul_f32 v[138:139], v[136:137], v[30:31]
	v_pk_mul_f32 v[136:137], v[130:131], v[28:29]
	global_store_dwordx4 v[166:167], v[136:139], off offset:3072 nt
	v_fma_f32 v130, -v147, v148, 1.0
	v_fmac_f32_e32 v148, v130, v148
	v_div_scale_f32 v130, vcc, 1.0, v146, 1.0
	v_mul_f32_e32 v131, v130, v148
	v_fma_f32 v136, -v147, v131, v130
	v_fmac_f32_e32 v131, v136, v148
	v_fma_f32 v130, -v147, v131, v130
	v_div_fmas_f32 v130, v130, v148, v131
	v_div_fixup_f32 v130, v130, v146, 1.0
	s_lshl_b64 s[0:1], s[14:15], 2
	s_add_u32 s0, s24, s0
	v_pk_mul_f32 v[136:137], v[158:159], v[130:131] op_sel_hi:[1,0]
	v_pk_mul_f32 v[138:139], v[160:161], v[130:131] op_sel_hi:[1,0]
	s_addc_u32 s1, s25, s1
	v_pk_mul_f32 v[138:139], v[2:3], v[138:139]
	v_pk_mul_f32 v[136:137], v[0:1], v[136:137]
	global_store_dwordx4 v48, v[136:139], s[0:1] nt
	v_lshl_add_u64 v[146:147], s[0:1], 0, v[48:49]
	v_cvt_f32_f16_sdwa v159, v123 dst_sel:DWORD dst_unused:UNUSED_PAD src0_sel:WORD_1
	v_pk_mul_f32 v[136:137], v[144:145], v[130:131] op_sel_hi:[1,0]
	v_pk_mul_f32 v[138:139], v[162:163], v[130:131] op_sel_hi:[1,0]
	v_pk_mul_f32 v[136:137], v[4:5], v[136:137]
	v_pk_mul_f32 v[138:139], v[6:7], v[138:139]
	global_store_dwordx4 v48, v[136:139], s[0:1] offset:1024 nt
	v_add_co_u32_e32 v144, vcc, s16, v146
	s_nop 0
	v_pk_mul_f32 v[136:137], v[164:165], v[130:131] op_sel_hi:[1,0]
	v_pk_mul_f32 v[138:139], v[168:169], v[130:131] op_sel_hi:[1,0]
	v_pk_mul_f32 v[136:137], v[8:9], v[136:137]
	v_pk_mul_f32 v[138:139], v[10:11], v[138:139]
; #define GAS __attribute__((address_space(1)))
; #define LAS __attribute__((address_space(3)))
; #define FN_LOAD(dst, k_) do { const GAS v2u* xr_ = (const GAS v2u*)(X + (size_t)(nw + 2048 * (k_)) * D) + F.lane; \
;         _Pragma("unroll") for (int j = 0; j < 8; ++j) dst[j] = __builtin_nontemporal_load(xr_ + 64 * j); } while (0)
; __device__ __forceinline__ void final_norm_phase2(const Args& a, Frame& F) {
;     ...
;     FN_LOAD(r0, 0); FN_LOAD(r1, 1); FN_LOAD(r2, 2); FN_LOAD(r3, 3); FN_LOAD(r4, 4); FN_LOAD(r5, 5); FN_LOAD(r6, 6); FN_LOAD(r7, 7);
;     for (int q = F.tid; q < D / 4; q += NWAVES * 64) ((LAS f32x4*)GL)[q] = ((const GAS f32x4*)gain)[q];
;     asm volatile("s_waitcnt lgkmcnt(0)" ::: "memory"); __builtin_amdgcn_s_barrier(); asm volatile("" ::: "memory");
;     FN_FINISH(r0, 0); FN_FINISH(r1, 1); FN_FINISH(r2, 2); FN_FINISH(r3, 3); FN_FINISH(r4, 4); FN_FINISH(r5, 5); FN_FINISH(r6, 6); FN_FINISH(r7, 7);
	global_store_dwordx4 v48, v[136:139], s[0:1] offset:2048 nt
	v_addc_co_u32_e32 v145, vcc, 0, v147, vcc
	s_nop 0
	v_pk_mul_f32 v[136:137], v[170:171], v[130:131] op_sel_hi:[1,0]
	v_pk_mul_f32 v[138:139], v[172:173], v[130:131] op_sel_hi:[1,0]
	v_pk_mul_f32 v[136:137], v[12:13], v[136:137]
	v_pk_mul_f32 v[138:139], v[14:15], v[138:139]
	global_store_dwordx4 v48, v[136:139], s[0:1] offset:3072 nt
	v_cvt_f32_f16_sdwa v147, v127 dst_sel:DWORD dst_unused:UNUSED_PAD src0_sel:WORD_1
	v_cvt_f32_f16_e32 v146, v127
	v_pk_mul_f32 v[136:137], v[174:175], v[130:131] op_sel_hi:[1,0]
	v_pk_mul_f32 v[138:139], v[176:177], v[130:131] op_sel_hi:[1,0]
	v_pk_mul_f32 v[136:137], v[16:17], v[136:137]
	v_pk_mul_f32 v[138:139], v[18:19], v[138:139]
	global_store_dwordx4 v[144:145], v[136:139], off nt
	v_mov_b32_e32 v155, v147
	v_cvt_f32_f16_e32 v158, v123
	v_pk_mul_f32 v[136:137], v[140:141], v[130:131] op_sel_hi:[1,0]
	v_pk_mul_f32 v[138:139], v[142:143], v[130:131] op_sel_hi:[1,0]
	v_cvt_f32_f16_sdwa v141, v128 dst_sel:DWORD dst_unused:UNUSED_PAD src0_sel:WORD_1
	v_cvt_f32_f16_sdwa v143, v129 dst_sel:DWORD dst_unused:UNUSED_PAD src0_sel:WORD_1
	v_cvt_f32_f16_e32 v142, v129
	v_cvt_f32_f16_sdwa v129, v126 dst_sel:DWORD dst_unused:UNUSED_PAD src0_sel:WORD_1
	v_cvt_f32_f16_e32 v140, v128
	v_cvt_f32_f16_e32 v128, v126
	v_mov_b32_e32 v148, v141
	v_mov_b32_e32 v149, v129
	v_mov_b32_e32 v126, v140
	v_mov_b32_e32 v127, v128
	v_pk_mul_f32 v[148:149], v[148:149], v[148:149]
	v_mov_b32_e32 v154, v143
	v_pk_fma_f32 v[126:127], v[126:127], v[126:127], v[148:149]
	v_mov_b32_e32 v148, v142
	v_mov_b32_e32 v149, v146
	v_pk_mul_f32 v[154:155], v[154:155], v[154:155]
	v_cvt_f32_f16_sdwa v161, v120 dst_sel:DWORD dst_unused:UNUSED_PAD src0_sel:WORD_1
	v_pk_fma_f32 v[148:149], v[148:149], v[148:149], v[154:155]
	v_cvt_f32_f16_sdwa v155, v125 dst_sel:DWORD dst_unused:UNUSED_PAD src0_sel:WORD_1
	v_pk_add_f32 v[126:127], v[126:127], v[148:149]
	v_cvt_f32_f16_sdwa v149, v124 dst_sel:DWORD dst_unused:UNUSED_PAD src0_sel:WORD_1
	v_cvt_f32_f16_e32 v148, v124
	v_cvt_f32_f16_e32 v154, v125
	v_mov_b32_e32 v157, v155
	v_mov_b32_e32 v156, v149
	v_mov_b32_e32 v124, v148
	v_mov_b32_e32 v125, v154
	v_pk_mul_f32 v[156:157], v[156:157], v[156:157]
	v_cvt_f32_f16_e32 v160, v120
	v_pk_fma_f32 v[124:125], v[124:125], v[124:125], v[156:157]
	v_cvt_f32_f16_sdwa v157, v122 dst_sel:DWORD dst_unused:UNUSED_PAD src0_sel:WORD_1
	v_cvt_f32_f16_e32 v156, v122
	v_cvt_f32_f16_sdwa v163, v121 dst_sel:DWORD dst_unused:UNUSED_PAD src0_sel:WORD_1
	v_cvt_f32_f16_e32 v162, v121
	v_mul_f32_e32 v122, v157, v157
	v_mul_f32_e32 v120, v159, v159
	v_pk_add_f32 v[126:127], v[126:127], v[126:127] op_sel:[0,1] op_sel_hi:[1,0]
	v_pk_add_f32 v[124:125], v[124:125], v[124:125] op_sel:[0,1] op_sel_hi:[1,0]
	v_pk_fma_f32 v[122:123], v[156:157], v[156:157], v[122:123] op_sel_hi:[1,1,0]
	v_pk_fma_f32 v[120:121], v[158:159], v[158:159], v[120:121] op_sel_hi:[1,1,0]
	v_pk_mul_f32 v[164:165], v[160:161], v[160:161]
	v_pk_mul_f32 v[166:167], v[162:163], v[162:163]
	v_mov_b32_e32 v127, v164
	v_mov_b32_e32 v125, v165
	v_mov_b32_e32 v123, v166
	v_mov_b32_e32 v121, v167
	v_pk_add_f32 v[124:125], v[126:127], v[124:125]
	v_pk_add_f32 v[120:121], v[122:123], v[120:121]
	v_cvt_f32_f16_sdwa v127, v119 dst_sel:DWORD dst_unused:UNUSED_PAD src0_sel:WORD_1
	v_pk_add_f32 v[120:121], v[124:125], v[120:121]
	v_cvt_f32_f16_sdwa v125, v118 dst_sel:DWORD dst_unused:UNUSED_PAD src0_sel:WORD_1
	v_cvt_f32_f16_e32 v124, v118
	v_cvt_f32_f16_e32 v126, v119
	v_cvt_f32_f16_sdwa v165, v116 dst_sel:DWORD dst_unused:UNUSED_PAD src0_sel:WORD_1
	v_cvt_f32_f16_e32 v164, v116
	v_mov_b32_e32 v122, v125
	v_mov_b32_e32 v123, v127
	v_mov_b32_e32 v118, v124
	v_mov_b32_e32 v119, v126
	v_pk_mul_f32 v[122:123], v[122:123], v[122:123]
	v_cvt_f32_f16_sdwa v167, v117 dst_sel:DWORD dst_unused:UNUSED_PAD src0_sel:WORD_1
	v_pk_fma_f32 v[118:119], v[118:119], v[118:119], v[122:123]
	v_mul_f32_e32 v116, v165, v165
	v_pk_add_f32 v[122:123], v[118:119], v[118:119] op_sel:[0,1] op_sel_hi:[1,0]
	v_cvt_f32_f16_e32 v166, v117
	v_pk_fma_f32 v[168:169], v[164:165], v[164:165], v[116:117] op_sel_hi:[1,1,0]
	v_cvt_f32_f16_sdwa v117, v114 dst_sel:DWORD dst_unused:UNUSED_PAD src0_sel:WORD_1
	v_cvt_f32_f16_e32 v116, v114
	v_cvt_f32_f16_sdwa v119, v115 dst_sel:DWORD dst_unused:UNUSED_PAD src0_sel:WORD_1
	v_cvt_f32_f16_e32 v118, v115
	v_mul_f32_e32 v114, v167, v167
	v_pk_add_f32 v[120:121], v[120:121], v[120:121] op_sel:[0,1] op_sel_hi:[1,0]
	v_pk_fma_f32 v[114:115], v[166:167], v[166:167], v[114:115] op_sel_hi:[1,1,0]
	v_pk_mul_f32 v[170:171], v[116:117], v[116:117]
	v_pk_mul_f32 v[172:173], v[118:119], v[118:119]
	v_mov_b32_e32 v121, v170
	v_mov_b32_e32 v123, v171
	v_mov_b32_e32 v169, v172
	v_mov_b32_e32 v115, v173
	v_pk_add_f32 v[120:121], v[120:121], v[122:123]
	v_pk_add_f32 v[114:115], v[168:169], v[114:115]
	v_pk_mul_f32 v[138:139], v[22:23], v[138:139]
	v_pk_add_f32 v[114:115], v[120:121], v[114:115]
	v_pk_mul_f32 v[136:137], v[20:21], v[136:137]
	v_add_f32_e32 v114, v114, v115
	global_store_dwordx4 v[144:145], v[136:139], off offset:1024 nt
	v_pk_mul_f32 v[120:121], v[134:135], v[130:131] op_sel_hi:[1,0]
	v_add_f32_dpp v114, v114, v114 quad_perm:[1,0,3,2] row_mask:0xf bank_mask:0xf bound_ctrl:1
	v_pk_mul_f32 v[136:137], v[178:179], v[130:131] op_sel_hi:[1,0]
	v_pk_mul_f32 v[138:139], v[180:181], v[130:131] op_sel_hi:[1,0]
	v_add_f32_dpp v114, v114, v114 quad_perm:[2,3,0,1] row_mask:0xf bank_mask:0xf bound_ctrl:1
	v_pk_mul_f32 v[138:139], v[26:27], v[138:139]
	v_pk_mul_f32 v[136:137], v[24:25], v[136:137]
	v_add_f32_dpp v114, v114, v114 row_half_mirror row_mask:0xf bank_mask:0xf bound_ctrl:1
; #define GAS __attribute__((address_space(1)))
; #define LAS __attribute__((address_space(3)))
; #define FN_LOAD(dst, k_) do { const GAS v2u* xr_ = (const GAS v2u*)(X + (size_t)(nw + 2048 * (k_)) * D) + F.lane; \
;         _Pragma("unroll") for (int j = 0; j < 8; ++j) dst[j] = __builtin_nontemporal_load(xr_ + 64 * j); } while (0)
; __device__ __forceinline__ void final_norm_phase2(const Args& a, Frame& F) {
;     ...
;     FN_LOAD(r0, 0); FN_LOAD(r1, 1); FN_LOAD(r2, 2); FN_LOAD(r3, 3); FN_LOAD(r4, 4); FN_LOAD(r5, 5); FN_LOAD(r6, 6); FN_LOAD(r7, 7);
;     for (int q = F.tid; q < D / 4; q += NWAVES * 64) ((LAS f32x4*)GL)[q] = ((const GAS f32x4*)gain)[q];
;     asm volatile("s_waitcnt lgkmcnt(0)" ::: "memory"); __builtin_amdgcn_s_barrier(); asm volatile("" ::: "memory");
;     FN_FINISH(r0, 0); FN_FINISH(r1, 1); FN_FINISH(r2, 2); FN_FINISH(r3, 3); FN_FINISH(r4, 4); FN_FINISH(r5, 5); FN_FINISH(r6, 6); FN_FINISH(r7, 7);
	global_store_dwordx4 v[144:145], v[136:139], off offset:2048 nt
	s_nop 0
	v_add_f32_dpp v114, v114, v114 row_mirror row_mask:0xf bank_mask:0xf bound_ctrl:1
	v_cvt_f32_f16_sdwa v139, v107 dst_sel:DWORD dst_unused:UNUSED_PAD src0_sel:WORD_1
	v_readlane_b32 s14, v114, 16
	v_readlane_b32 s15, v114, 48
	v_readlane_b32 s0, v114, 0
	v_readlane_b32 s1, v114, 32
	v_mov_b32_e32 v114, s14
	v_mov_b32_e32 v115, s15
	v_pk_add_f32 v[114:115], s[0:1], v[114:115]
	v_cvt_f32_f16_e32 v138, v107
	v_add_f32_e32 v114, v114, v115
	v_fmamk_f32 v114, v114, 0x3a000000, v151
	v_mul_f32_e32 v115, 0x4f800000, v114
	v_cmp_gt_f32_e32 vcc, s18, v114
	s_nop 1
	v_cndmask_b32_e32 v122, v114, v115, vcc
	v_sqrt_f32_e32 v123, v122
	v_pk_mul_f32 v[114:115], v[132:133], v[130:131] op_sel_hi:[1,0]
	v_add_u32_e32 v130, -1, v123
	v_fma_f32 v131, -v130, v123, v122
	v_cmp_ge_f32_e64 s[0:1], 0, v131
	v_add_u32_e32 v131, 1, v123
	s_nop 0
	v_cndmask_b32_e64 v130, v123, v130, s[0:1]
	v_fma_f32 v123, -v131, v123, v122
	v_cmp_lt_f32_e64 s[0:1], 0, v123
	s_nop 1
	v_cndmask_b32_e64 v123, v130, v131, s[0:1]
	v_mul_f32_e32 v130, 0x37800000, v123
	v_cndmask_b32_e32 v123, v123, v130, vcc
	v_cmp_class_f32_e32 vcc, v122, v152
	s_nop 1
	v_cndmask_b32_e32 v130, v123, v122, vcc
	v_div_scale_f32 v131, s[0:1], v130, v130, 1.0
	v_rcp_f32_e32 v132, v131
	v_pk_mul_f32 v[122:123], v[30:31], v[120:121]
	v_pk_mul_f32 v[120:121], v[28:29], v[114:115]
	global_store_dwordx4 v[144:145], v[120:123], off offset:3072 nt
	v_fma_f32 v114, -v131, v132, 1.0
	v_fmac_f32_e32 v132, v114, v132
	v_div_scale_f32 v114, vcc, 1.0, v130, 1.0
	v_mul_f32_e32 v115, v114, v132
	v_fma_f32 v120, -v131, v115, v114
	v_fmac_f32_e32 v115, v120, v132
	v_fma_f32 v114, -v131, v115, v114
	v_div_fmas_f32 v114, v114, v132, v115
	v_div_fixup_f32 v114, v114, v130, 1.0
	s_lshl_b64 s[0:1], s[12:13], 2
	s_add_u32 s0, s24, s0
	v_pk_mul_f32 v[120:121], v[140:141], v[114:115] op_sel_hi:[1,0]
	v_pk_mul_f32 v[122:123], v[142:143], v[114:115] op_sel_hi:[1,0]
	s_addc_u32 s1, s25, s1
	v_pk_mul_f32 v[122:123], v[2:3], v[122:123]
	v_pk_mul_f32 v[120:121], v[0:1], v[120:121]
	global_store_dwordx4 v48, v[120:123], s[0:1] nt
	v_lshl_add_u64 v[130:131], s[0:1], 0, v[48:49]
	v_cvt_f32_f16_sdwa v141, v104 dst_sel:DWORD dst_unused:UNUSED_PAD src0_sel:WORD_1
	v_pk_mul_f32 v[120:121], v[128:129], v[114:115] op_sel_hi:[1,0]
	v_pk_mul_f32 v[122:123], v[146:147], v[114:115] op_sel_hi:[1,0]
	v_pk_mul_f32 v[120:121], v[4:5], v[120:121]
	v_pk_mul_f32 v[122:123], v[6:7], v[122:123]
	global_store_dwordx4 v48, v[120:123], s[0:1] offset:1024 nt
	v_add_co_u32_e32 v128, vcc, s16, v130
	s_nop 0
	v_pk_mul_f32 v[120:121], v[148:149], v[114:115] op_sel_hi:[1,0]
	v_pk_mul_f32 v[122:123], v[154:155], v[114:115] op_sel_hi:[1,0]
	v_pk_mul_f32 v[120:121], v[8:9], v[120:121]
	v_pk_mul_f32 v[122:123], v[10:11], v[122:123]
	global_store_dwordx4 v48, v[120:123], s[0:1] offset:2048 nt
	v_addc_co_u32_e32 v129, vcc, 0, v131, vcc
	s_nop 0
	v_pk_mul_f32 v[120:121], v[156:157], v[114:115] op_sel_hi:[1,0]
	v_pk_mul_f32 v[122:123], v[158:159], v[114:115] op_sel_hi:[1,0]
	v_pk_mul_f32 v[120:121], v[12:13], v[120:121]
	v_pk_mul_f32 v[122:123], v[14:15], v[122:123]
	global_store_dwordx4 v48, v[120:123], s[0:1] offset:3072 nt
	v_cvt_f32_f16_sdwa v131, v111 dst_sel:DWORD dst_unused:UNUSED_PAD src0_sel:WORD_1
	v_cvt_f32_f16_e32 v130, v111
	v_pk_mul_f32 v[120:121], v[160:161], v[114:115] op_sel_hi:[1,0]
	v_pk_mul_f32 v[122:123], v[162:163], v[114:115] op_sel_hi:[1,0]
	v_pk_mul_f32 v[120:121], v[16:17], v[120:121]
	v_pk_mul_f32 v[122:123], v[18:19], v[122:123]
	global_store_dwordx4 v[128:129], v[120:123], off nt
	v_mov_b32_e32 v135, v131
	v_cvt_f32_f16_e32 v140, v104
	v_pk_mul_f32 v[120:121], v[124:125], v[114:115] op_sel_hi:[1,0]
	v_pk_mul_f32 v[122:123], v[126:127], v[114:115] op_sel_hi:[1,0]
	v_cvt_f32_f16_sdwa v125, v112 dst_sel:DWORD dst_unused:UNUSED_PAD src0_sel:WORD_1
	v_cvt_f32_f16_sdwa v127, v113 dst_sel:DWORD dst_unused:UNUSED_PAD src0_sel:WORD_1
	v_cvt_f32_f16_e32 v126, v113
	v_cvt_f32_f16_sdwa v113, v110 dst_sel:DWORD dst_unused:UNUSED_PAD src0_sel:WORD_1
	v_cvt_f32_f16_e32 v124, v112
	v_cvt_f32_f16_e32 v112, v110
	v_mov_b32_e32 v132, v125
	v_mov_b32_e32 v133, v113
	v_mov_b32_e32 v110, v124
	v_mov_b32_e32 v111, v112
	v_pk_mul_f32 v[132:133], v[132:133], v[132:133]
	v_mov_b32_e32 v134, v127
	v_pk_fma_f32 v[110:111], v[110:111], v[110:111], v[132:133]
	v_mov_b32_e32 v132, v126
	v_mov_b32_e32 v133, v130
	v_pk_mul_f32 v[134:135], v[134:135], v[134:135]
	v_cvt_f32_f16_sdwa v143, v105 dst_sel:DWORD dst_unused:UNUSED_PAD src0_sel:WORD_1
	v_pk_fma_f32 v[132:133], v[132:133], v[132:133], v[134:135]
	v_cvt_f32_f16_sdwa v135, v109 dst_sel:DWORD dst_unused:UNUSED_PAD src0_sel:WORD_1
	v_pk_add_f32 v[110:111], v[110:111], v[132:133]
	v_cvt_f32_f16_sdwa v133, v108 dst_sel:DWORD dst_unused:UNUSED_PAD src0_sel:WORD_1
	v_cvt_f32_f16_e32 v132, v108
	v_cvt_f32_f16_e32 v134, v109
	v_mov_b32_e32 v137, v135
	v_mov_b32_e32 v136, v133
	v_mov_b32_e32 v108, v132
	v_mov_b32_e32 v109, v134
	v_pk_mul_f32 v[136:137], v[136:137], v[136:137]
	v_cvt_f32_f16_e32 v142, v105
	v_pk_fma_f32 v[108:109], v[108:109], v[108:109], v[136:137]
	v_cvt_f32_f16_sdwa v137, v106 dst_sel:DWORD dst_unused:UNUSED_PAD src0_sel:WORD_1
	v_cvt_f32_f16_e32 v136, v106
	v_mul_f32_e32 v104, v139, v139
	v_pk_add_f32 v[110:111], v[110:111], v[110:111] op_sel:[0,1] op_sel_hi:[1,0]
	v_mul_f32_e32 v106, v137, v137
	v_pk_add_f32 v[108:109], v[108:109], v[108:109] op_sel:[0,1] op_sel_hi:[1,0]
	v_pk_fma_f32 v[106:107], v[136:137], v[136:137], v[106:107] op_sel_hi:[1,1,0]
	v_pk_fma_f32 v[104:105], v[138:139], v[138:139], v[104:105] op_sel_hi:[1,1,0]
; #define GAS __attribute__((address_space(1)))
; #define LAS __attribute__((address_space(3)))
; #define FN_LOAD(dst, k_) do { const GAS v2u* xr_ = (const GAS v2u*)(X + (size_t)(nw + 2048 * (k_)) * D) + F.lane; \
;         _Pragma("unroll") for (int j = 0; j < 8; ++j) dst[j] = __builtin_nontemporal_load(xr_ + 64 * j); } while (0)
; __device__ __forceinline__ void final_norm_phase2(const Args& a, Frame& F) {
;     ...
;     FN_LOAD(r0, 0); FN_LOAD(r1, 1); FN_LOAD(r2, 2); FN_LOAD(r3, 3); FN_LOAD(r4, 4); FN_LOAD(r5, 5); FN_LOAD(r6, 6); FN_LOAD(r7, 7);
;     for (int q = F.tid; q < D / 4; q += NWAVES * 64) ((LAS f32x4*)GL)[q] = ((const GAS f32x4*)gain)[q];
;     asm volatile("s_waitcnt lgkmcnt(0)" ::: "memory"); __builtin_amdgcn_s_barrier(); asm volatile("" ::: "memory");
;     FN_FINISH(r0, 0); FN_FINISH(r1, 1); FN_FINISH(r2, 2); FN_FINISH(r3, 3); FN_FINISH(r4, 4); FN_FINISH(r5, 5); FN_FINISH(r6, 6); FN_FINISH(r7, 7);
	v_pk_mul_f32 v[144:145], v[140:141], v[140:141]
	v_pk_mul_f32 v[146:147], v[142:143], v[142:143]
	v_mov_b32_e32 v111, v144
	v_mov_b32_e32 v109, v145
	v_mov_b32_e32 v107, v146
	v_mov_b32_e32 v105, v147
	v_pk_add_f32 v[108:109], v[110:111], v[108:109]
	v_pk_add_f32 v[104:105], v[106:107], v[104:105]
	v_cvt_f32_f16_sdwa v111, v103 dst_sel:DWORD dst_unused:UNUSED_PAD src0_sel:WORD_1
	v_pk_add_f32 v[104:105], v[108:109], v[104:105]
	v_cvt_f32_f16_sdwa v109, v102 dst_sel:DWORD dst_unused:UNUSED_PAD src0_sel:WORD_1
	v_cvt_f32_f16_e32 v108, v102
	v_cvt_f32_f16_e32 v110, v103
	v_cvt_f32_f16_sdwa v145, v100 dst_sel:DWORD dst_unused:UNUSED_PAD src0_sel:WORD_1
	v_cvt_f32_f16_e32 v144, v100
	v_mov_b32_e32 v106, v109
	v_mov_b32_e32 v107, v111
	v_mov_b32_e32 v102, v108
	v_mov_b32_e32 v103, v110
	v_pk_mul_f32 v[106:107], v[106:107], v[106:107]
	v_cvt_f32_f16_sdwa v147, v101 dst_sel:DWORD dst_unused:UNUSED_PAD src0_sel:WORD_1
	v_pk_fma_f32 v[102:103], v[102:103], v[102:103], v[106:107]
	v_mul_f32_e32 v100, v145, v145
	v_pk_add_f32 v[106:107], v[102:103], v[102:103] op_sel:[0,1] op_sel_hi:[1,0]
	v_cvt_f32_f16_e32 v146, v101
	v_pk_fma_f32 v[148:149], v[144:145], v[144:145], v[100:101] op_sel_hi:[1,1,0]
	v_cvt_f32_f16_sdwa v101, v98 dst_sel:DWORD dst_unused:UNUSED_PAD src0_sel:WORD_1
	v_cvt_f32_f16_e32 v100, v98
	v_cvt_f32_f16_sdwa v103, v99 dst_sel:DWORD dst_unused:UNUSED_PAD src0_sel:WORD_1
	v_cvt_f32_f16_e32 v102, v99
	v_mul_f32_e32 v98, v147, v147
	v_pk_add_f32 v[104:105], v[104:105], v[104:105] op_sel:[0,1] op_sel_hi:[1,0]
	v_pk_fma_f32 v[98:99], v[146:147], v[146:147], v[98:99] op_sel_hi:[1,1,0]
	v_pk_mul_f32 v[154:155], v[100:101], v[100:101]
	v_pk_mul_f32 v[156:157], v[102:103], v[102:103]
	v_mov_b32_e32 v105, v154
	v_mov_b32_e32 v107, v155
	v_mov_b32_e32 v149, v156
	v_mov_b32_e32 v99, v157
	v_pk_add_f32 v[104:105], v[104:105], v[106:107]
	v_pk_add_f32 v[98:99], v[148:149], v[98:99]
	v_pk_mul_f32 v[122:123], v[22:23], v[122:123]
	v_pk_add_f32 v[98:99], v[104:105], v[98:99]
	v_pk_mul_f32 v[120:121], v[20:21], v[120:121]
	v_add_f32_e32 v98, v98, v99
	global_store_dwordx4 v[128:129], v[120:123], off offset:1024 nt
	v_pk_mul_f32 v[104:105], v[118:119], v[114:115] op_sel_hi:[1,0]
	v_add_f32_dpp v98, v98, v98 quad_perm:[1,0,3,2] row_mask:0xf bank_mask:0xf bound_ctrl:1
	v_pk_mul_f32 v[120:121], v[164:165], v[114:115] op_sel_hi:[1,0]
	v_pk_mul_f32 v[122:123], v[166:167], v[114:115] op_sel_hi:[1,0]
	v_add_f32_dpp v98, v98, v98 quad_perm:[2,3,0,1] row_mask:0xf bank_mask:0xf bound_ctrl:1
	v_pk_mul_f32 v[122:123], v[26:27], v[122:123]
	v_pk_mul_f32 v[120:121], v[24:25], v[120:121]
	v_add_f32_dpp v98, v98, v98 row_half_mirror row_mask:0xf bank_mask:0xf bound_ctrl:1
	global_store_dwordx4 v[128:129], v[120:123], off offset:2048 nt
	s_nop 0
	v_add_f32_dpp v98, v98, v98 row_mirror row_mask:0xf bank_mask:0xf bound_ctrl:1
	v_cvt_f32_f16_sdwa v123, v91 dst_sel:DWORD dst_unused:UNUSED_PAD src0_sel:WORD_1
	v_readlane_b32 s12, v98, 16
	v_readlane_b32 s13, v98, 48
	v_readlane_b32 s0, v98, 0
	v_readlane_b32 s1, v98, 32
	v_mov_b32_e32 v98, s12
	v_mov_b32_e32 v99, s13
	v_pk_add_f32 v[98:99], s[0:1], v[98:99]
	v_cvt_f32_f16_e32 v122, v91
	v_add_f32_e32 v98, v98, v99
	v_fmamk_f32 v98, v98, 0x3a000000, v151
	v_mul_f32_e32 v99, 0x4f800000, v98
	v_cmp_gt_f32_e32 vcc, s18, v98
	s_nop 1
	v_cndmask_b32_e32 v106, v98, v99, vcc
	v_sqrt_f32_e32 v107, v106
	v_pk_mul_f32 v[98:99], v[116:117], v[114:115] op_sel_hi:[1,0]
	v_add_u32_e32 v114, -1, v107
	v_fma_f32 v115, -v114, v107, v106
	v_cmp_ge_f32_e64 s[0:1], 0, v115
	v_add_u32_e32 v115, 1, v107
	s_nop 0
	v_cndmask_b32_e64 v114, v107, v114, s[0:1]
	v_fma_f32 v107, -v115, v107, v106
	v_cmp_lt_f32_e64 s[0:1], 0, v107
	s_nop 1
	v_cndmask_b32_e64 v107, v114, v115, s[0:1]
	v_mul_f32_e32 v114, 0x37800000, v107
	v_cndmask_b32_e32 v107, v107, v114, vcc
	v_cmp_class_f32_e32 vcc, v106, v152
	s_nop 1
	v_cndmask_b32_e32 v114, v107, v106, vcc
	v_div_scale_f32 v115, s[0:1], v114, v114, 1.0
	v_rcp_f32_e32 v116, v115
	v_pk_mul_f32 v[106:107], v[30:31], v[104:105]
	v_pk_mul_f32 v[104:105], v[28:29], v[98:99]
	global_store_dwordx4 v[128:129], v[104:107], off offset:3072 nt
	v_fma_f32 v98, -v115, v116, 1.0
	v_fmac_f32_e32 v116, v98, v116
	v_div_scale_f32 v98, vcc, 1.0, v114, 1.0
	v_mul_f32_e32 v99, v98, v116
	v_fma_f32 v104, -v115, v99, v98
	v_fmac_f32_e32 v99, v104, v116
	v_fma_f32 v98, -v115, v99, v98
	v_div_fmas_f32 v98, v98, v116, v99
	v_div_fixup_f32 v98, v98, v114, 1.0
	s_lshl_b64 s[0:1], s[10:11], 2
	s_add_u32 s0, s24, s0
	v_pk_mul_f32 v[104:105], v[124:125], v[98:99] op_sel_hi:[1,0]
	v_pk_mul_f32 v[106:107], v[126:127], v[98:99] op_sel_hi:[1,0]
	s_addc_u32 s1, s25, s1
	v_pk_mul_f32 v[106:107], v[2:3], v[106:107]
	v_pk_mul_f32 v[104:105], v[0:1], v[104:105]
	global_store_dwordx4 v48, v[104:107], s[0:1] nt
	v_lshl_add_u64 v[114:115], s[0:1], 0, v[48:49]
	v_cvt_f32_f16_sdwa v125, v88 dst_sel:DWORD dst_unused:UNUSED_PAD src0_sel:WORD_1
	v_pk_mul_f32 v[104:105], v[112:113], v[98:99] op_sel_hi:[1,0]
	v_pk_mul_f32 v[106:107], v[130:131], v[98:99] op_sel_hi:[1,0]
	v_pk_mul_f32 v[104:105], v[4:5], v[104:105]
	v_pk_mul_f32 v[106:107], v[6:7], v[106:107]
	global_store_dwordx4 v48, v[104:107], s[0:1] offset:1024 nt
	v_add_co_u32_e32 v112, vcc, s16, v114
	s_nop 0
	v_pk_mul_f32 v[104:105], v[132:133], v[98:99] op_sel_hi:[1,0]
	v_pk_mul_f32 v[106:107], v[134:135], v[98:99] op_sel_hi:[1,0]
	v_pk_mul_f32 v[104:105], v[8:9], v[104:105]
	v_pk_mul_f32 v[106:107], v[10:11], v[106:107]
	global_store_dwordx4 v48, v[104:107], s[0:1] offset:2048 nt
	v_addc_co_u32_e32 v113, vcc, 0, v115, vcc
	s_nop 0
	v_pk_mul_f32 v[104:105], v[136:137], v[98:99] op_sel_hi:[1,0]
; #define GAS __attribute__((address_space(1)))
; #define LAS __attribute__((address_space(3)))
; #define FN_LOAD(dst, k_) do { const GAS v2u* xr_ = (const GAS v2u*)(X + (size_t)(nw + 2048 * (k_)) * D) + F.lane; \
;         _Pragma("unroll") for (int j = 0; j < 8; ++j) dst[j] = __builtin_nontemporal_load(xr_ + 64 * j); } while (0)
; __device__ __forceinline__ void final_norm_phase2(const Args& a, Frame& F) {
;     ...
;     FN_LOAD(r0, 0); FN_LOAD(r1, 1); FN_LOAD(r2, 2); FN_LOAD(r3, 3); FN_LOAD(r4, 4); FN_LOAD(r5, 5); FN_LOAD(r6, 6); FN_LOAD(r7, 7);
;     for (int q = F.tid; q < D / 4; q += NWAVES * 64) ((LAS f32x4*)GL)[q] = ((const GAS f32x4*)gain)[q];
;     asm volatile("s_waitcnt lgkmcnt(0)" ::: "memory"); __builtin_amdgcn_s_barrier(); asm volatile("" ::: "memory");
;     FN_FINISH(r0, 0); FN_FINISH(r1, 1); FN_FINISH(r2, 2); FN_FINISH(r3, 3); FN_FINISH(r4, 4); FN_FINISH(r5, 5); FN_FINISH(r6, 6); FN_FINISH(r7, 7);
	v_pk_mul_f32 v[106:107], v[138:139], v[98:99] op_sel_hi:[1,0]
	v_pk_mul_f32 v[104:105], v[12:13], v[104:105]
	v_pk_mul_f32 v[106:107], v[14:15], v[106:107]
	global_store_dwordx4 v48, v[104:107], s[0:1] offset:3072 nt
	v_cvt_f32_f16_sdwa v115, v95 dst_sel:DWORD dst_unused:UNUSED_PAD src0_sel:WORD_1
	v_cvt_f32_f16_e32 v114, v95
	v_pk_mul_f32 v[104:105], v[140:141], v[98:99] op_sel_hi:[1,0]
	v_pk_mul_f32 v[106:107], v[142:143], v[98:99] op_sel_hi:[1,0]
	v_pk_mul_f32 v[104:105], v[16:17], v[104:105]
	v_pk_mul_f32 v[106:107], v[18:19], v[106:107]
	global_store_dwordx4 v[112:113], v[104:107], off nt
	v_mov_b32_e32 v119, v115
	v_cvt_f32_f16_e32 v124, v88
	v_pk_mul_f32 v[104:105], v[108:109], v[98:99] op_sel_hi:[1,0]
	v_pk_mul_f32 v[106:107], v[110:111], v[98:99] op_sel_hi:[1,0]
	v_cvt_f32_f16_sdwa v109, v96 dst_sel:DWORD dst_unused:UNUSED_PAD src0_sel:WORD_1
	v_cvt_f32_f16_sdwa v111, v97 dst_sel:DWORD dst_unused:UNUSED_PAD src0_sel:WORD_1
	v_cvt_f32_f16_e32 v110, v97
	v_cvt_f32_f16_sdwa v97, v94 dst_sel:DWORD dst_unused:UNUSED_PAD src0_sel:WORD_1
	v_cvt_f32_f16_e32 v108, v96
	v_cvt_f32_f16_e32 v96, v94
	v_mov_b32_e32 v116, v109
	v_mov_b32_e32 v117, v97
	v_mov_b32_e32 v94, v108
	v_mov_b32_e32 v95, v96
	v_pk_mul_f32 v[116:117], v[116:117], v[116:117]
	v_mov_b32_e32 v118, v111
	v_pk_fma_f32 v[94:95], v[94:95], v[94:95], v[116:117]
	v_mov_b32_e32 v116, v110
	v_mov_b32_e32 v117, v114
	v_pk_mul_f32 v[118:119], v[118:119], v[118:119]
	v_cvt_f32_f16_sdwa v127, v89 dst_sel:DWORD dst_unused:UNUSED_PAD src0_sel:WORD_1
	v_pk_fma_f32 v[116:117], v[116:117], v[116:117], v[118:119]
	v_cvt_f32_f16_sdwa v119, v93 dst_sel:DWORD dst_unused:UNUSED_PAD src0_sel:WORD_1
	v_pk_add_f32 v[94:95], v[94:95], v[116:117]
	v_cvt_f32_f16_sdwa v117, v92 dst_sel:DWORD dst_unused:UNUSED_PAD src0_sel:WORD_1
	v_cvt_f32_f16_e32 v116, v92
	v_cvt_f32_f16_e32 v118, v93
	v_mov_b32_e32 v121, v119
	v_mov_b32_e32 v120, v117
	v_mov_b32_e32 v92, v116
	v_mov_b32_e32 v93, v118
	v_pk_mul_f32 v[120:121], v[120:121], v[120:121]
	v_cvt_f32_f16_e32 v126, v89
	v_pk_fma_f32 v[92:93], v[92:93], v[92:93], v[120:121]
	v_cvt_f32_f16_sdwa v121, v90 dst_sel:DWORD dst_unused:UNUSED_PAD src0_sel:WORD_1
	v_cvt_f32_f16_e32 v120, v90
	v_mul_f32_e32 v88, v123, v123
	v_pk_add_f32 v[94:95], v[94:95], v[94:95] op_sel:[0,1] op_sel_hi:[1,0]
	v_mul_f32_e32 v90, v121, v121
	v_pk_add_f32 v[92:93], v[92:93], v[92:93] op_sel:[0,1] op_sel_hi:[1,0]
	v_pk_fma_f32 v[90:91], v[120:121], v[120:121], v[90:91] op_sel_hi:[1,1,0]
	v_pk_fma_f32 v[88:89], v[122:123], v[122:123], v[88:89] op_sel_hi:[1,1,0]
	v_pk_mul_f32 v[128:129], v[124:125], v[124:125]
	v_pk_mul_f32 v[130:131], v[126:127], v[126:127]
	v_mov_b32_e32 v95, v128
	v_mov_b32_e32 v93, v129
	v_mov_b32_e32 v91, v130
	v_mov_b32_e32 v89, v131
	v_pk_add_f32 v[92:93], v[94:95], v[92:93]
	v_pk_add_f32 v[88:89], v[90:91], v[88:89]
	v_cvt_f32_f16_sdwa v95, v87 dst_sel:DWORD dst_unused:UNUSED_PAD src0_sel:WORD_1
	v_pk_add_f32 v[88:89], v[92:93], v[88:89]
	v_cvt_f32_f16_sdwa v93, v86 dst_sel:DWORD dst_unused:UNUSED_PAD src0_sel:WORD_1
	v_cvt_f32_f16_e32 v92, v86
	v_cvt_f32_f16_e32 v94, v87
	v_cvt_f32_f16_sdwa v129, v84 dst_sel:DWORD dst_unused:UNUSED_PAD src0_sel:WORD_1
	v_cvt_f32_f16_e32 v128, v84
	v_mov_b32_e32 v90, v93
	v_mov_b32_e32 v91, v95
	v_mov_b32_e32 v86, v92
	v_mov_b32_e32 v87, v94
	v_pk_mul_f32 v[90:91], v[90:91], v[90:91]
	v_cvt_f32_f16_sdwa v131, v85 dst_sel:DWORD dst_unused:UNUSED_PAD src0_sel:WORD_1
	v_pk_fma_f32 v[86:87], v[86:87], v[86:87], v[90:91]
	v_mul_f32_e32 v84, v129, v129
	v_pk_add_f32 v[90:91], v[86:87], v[86:87] op_sel:[0,1] op_sel_hi:[1,0]
	v_cvt_f32_f16_e32 v130, v85
	v_pk_fma_f32 v[132:133], v[128:129], v[128:129], v[84:85] op_sel_hi:[1,1,0]
	v_cvt_f32_f16_sdwa v85, v82 dst_sel:DWORD dst_unused:UNUSED_PAD src0_sel:WORD_1
	v_cvt_f32_f16_e32 v84, v82
	v_cvt_f32_f16_sdwa v87, v83 dst_sel:DWORD dst_unused:UNUSED_PAD src0_sel:WORD_1
	v_cvt_f32_f16_e32 v86, v83
	v_mul_f32_e32 v82, v131, v131
	v_pk_add_f32 v[88:89], v[88:89], v[88:89] op_sel:[0,1] op_sel_hi:[1,0]
	v_pk_fma_f32 v[82:83], v[130:131], v[130:131], v[82:83] op_sel_hi:[1,1,0]
	v_pk_mul_f32 v[134:135], v[84:85], v[84:85]
	v_pk_mul_f32 v[136:137], v[86:87], v[86:87]
	v_mov_b32_e32 v89, v134
	v_mov_b32_e32 v91, v135
	v_mov_b32_e32 v133, v136
	v_mov_b32_e32 v83, v137
	v_pk_add_f32 v[88:89], v[88:89], v[90:91]
	v_pk_add_f32 v[82:83], v[132:133], v[82:83]
	v_pk_mul_f32 v[106:107], v[22:23], v[106:107]
	v_pk_add_f32 v[82:83], v[88:89], v[82:83]
	v_pk_mul_f32 v[104:105], v[20:21], v[104:105]
	v_add_f32_e32 v82, v82, v83
	global_store_dwordx4 v[112:113], v[104:107], off offset:1024 nt
	v_pk_mul_f32 v[88:89], v[102:103], v[98:99] op_sel_hi:[1,0]
	v_add_f32_dpp v82, v82, v82 quad_perm:[1,0,3,2] row_mask:0xf bank_mask:0xf bound_ctrl:1
	v_pk_mul_f32 v[104:105], v[144:145], v[98:99] op_sel_hi:[1,0]
	v_pk_mul_f32 v[106:107], v[146:147], v[98:99] op_sel_hi:[1,0]
	v_add_f32_dpp v82, v82, v82 quad_perm:[2,3,0,1] row_mask:0xf bank_mask:0xf bound_ctrl:1
	v_pk_mul_f32 v[106:107], v[26:27], v[106:107]
	v_pk_mul_f32 v[104:105], v[24:25], v[104:105]
	v_add_f32_dpp v82, v82, v82 row_half_mirror row_mask:0xf bank_mask:0xf bound_ctrl:1
	global_store_dwordx4 v[112:113], v[104:107], off offset:2048 nt
	s_nop 0
	v_add_f32_dpp v82, v82, v82 row_mirror row_mask:0xf bank_mask:0xf bound_ctrl:1
	v_cvt_f32_f16_sdwa v107, v75 dst_sel:DWORD dst_unused:UNUSED_PAD src0_sel:WORD_1
	v_readlane_b32 s10, v82, 16
	v_readlane_b32 s11, v82, 48
	v_readlane_b32 s0, v82, 0
	v_readlane_b32 s1, v82, 32
	v_mov_b32_e32 v82, s10
	v_mov_b32_e32 v83, s11
	v_pk_add_f32 v[82:83], s[0:1], v[82:83]
	v_cvt_f32_f16_e32 v106, v75
	v_add_f32_e32 v82, v82, v83
; #define GAS __attribute__((address_space(1)))
; #define LAS __attribute__((address_space(3)))
; #define FN_LOAD(dst, k_) do { const GAS v2u* xr_ = (const GAS v2u*)(X + (size_t)(nw + 2048 * (k_)) * D) + F.lane; \
;         _Pragma("unroll") for (int j = 0; j < 8; ++j) dst[j] = __builtin_nontemporal_load(xr_ + 64 * j); } while (0)
; __device__ __forceinline__ void final_norm_phase2(const Args& a, Frame& F) {
;     ...
;     FN_LOAD(r0, 0); FN_LOAD(r1, 1); FN_LOAD(r2, 2); FN_LOAD(r3, 3); FN_LOAD(r4, 4); FN_LOAD(r5, 5); FN_LOAD(r6, 6); FN_LOAD(r7, 7);
;     for (int q = F.tid; q < D / 4; q += NWAVES * 64) ((LAS f32x4*)GL)[q] = ((const GAS f32x4*)gain)[q];
;     asm volatile("s_waitcnt lgkmcnt(0)" ::: "memory"); __builtin_amdgcn_s_barrier(); asm volatile("" ::: "memory");
;     FN_FINISH(r0, 0); FN_FINISH(r1, 1); FN_FINISH(r2, 2); FN_FINISH(r3, 3); FN_FINISH(r4, 4); FN_FINISH(r5, 5); FN_FINISH(r6, 6); FN_FINISH(r7, 7);
	v_fmamk_f32 v82, v82, 0x3a000000, v151
	v_mul_f32_e32 v83, 0x4f800000, v82
	v_cmp_gt_f32_e32 vcc, s18, v82
	s_nop 1
	v_cndmask_b32_e32 v90, v82, v83, vcc
	v_sqrt_f32_e32 v91, v90
	v_pk_mul_f32 v[82:83], v[100:101], v[98:99] op_sel_hi:[1,0]
	v_add_u32_e32 v98, -1, v91
	v_fma_f32 v99, -v98, v91, v90
	v_cmp_ge_f32_e64 s[0:1], 0, v99
	v_add_u32_e32 v99, 1, v91
	s_nop 0
	v_cndmask_b32_e64 v98, v91, v98, s[0:1]
	v_fma_f32 v91, -v99, v91, v90
	v_cmp_lt_f32_e64 s[0:1], 0, v91
	s_nop 1
	v_cndmask_b32_e64 v91, v98, v99, s[0:1]
	v_mul_f32_e32 v98, 0x37800000, v91
	v_cndmask_b32_e32 v91, v91, v98, vcc
	v_cmp_class_f32_e32 vcc, v90, v152
	s_nop 1
	v_cndmask_b32_e32 v98, v91, v90, vcc
	v_div_scale_f32 v99, s[0:1], v98, v98, 1.0
	v_rcp_f32_e32 v100, v99
	v_pk_mul_f32 v[90:91], v[30:31], v[88:89]
	v_pk_mul_f32 v[88:89], v[28:29], v[82:83]
	global_store_dwordx4 v[112:113], v[88:91], off offset:3072 nt
	v_fma_f32 v82, -v99, v100, 1.0
	v_fmac_f32_e32 v100, v82, v100
	v_div_scale_f32 v82, vcc, 1.0, v98, 1.0
	v_mul_f32_e32 v83, v82, v100
	v_fma_f32 v88, -v99, v83, v82
	v_fmac_f32_e32 v83, v88, v100
	v_fma_f32 v82, -v99, v83, v82
	v_div_fmas_f32 v82, v82, v100, v83
	v_div_fixup_f32 v82, v82, v98, 1.0
	s_lshl_b64 s[0:1], s[8:9], 2
	s_add_u32 s0, s24, s0
	v_pk_mul_f32 v[88:89], v[108:109], v[82:83] op_sel_hi:[1,0]
	v_pk_mul_f32 v[90:91], v[110:111], v[82:83] op_sel_hi:[1,0]
	s_addc_u32 s1, s25, s1
	v_pk_mul_f32 v[90:91], v[2:3], v[90:91]
	v_pk_mul_f32 v[88:89], v[0:1], v[88:89]
	global_store_dwordx4 v48, v[88:91], s[0:1] nt
	v_lshl_add_u64 v[98:99], s[0:1], 0, v[48:49]
	v_cvt_f32_f16_sdwa v109, v72 dst_sel:DWORD dst_unused:UNUSED_PAD src0_sel:WORD_1
	v_pk_mul_f32 v[88:89], v[96:97], v[82:83] op_sel_hi:[1,0]
	v_pk_mul_f32 v[90:91], v[114:115], v[82:83] op_sel_hi:[1,0]
	v_pk_mul_f32 v[88:89], v[4:5], v[88:89]
	v_pk_mul_f32 v[90:91], v[6:7], v[90:91]
	global_store_dwordx4 v48, v[88:91], s[0:1] offset:1024 nt
	v_add_co_u32_e32 v96, vcc, s16, v98
	s_nop 0
	v_pk_mul_f32 v[88:89], v[116:117], v[82:83] op_sel_hi:[1,0]
	v_pk_mul_f32 v[90:91], v[118:119], v[82:83] op_sel_hi:[1,0]
	v_pk_mul_f32 v[88:89], v[8:9], v[88:89]
	v_pk_mul_f32 v[90:91], v[10:11], v[90:91]
	global_store_dwordx4 v48, v[88:91], s[0:1] offset:2048 nt
	v_addc_co_u32_e32 v97, vcc, 0, v99, vcc
	s_nop 0
	v_pk_mul_f32 v[88:89], v[120:121], v[82:83] op_sel_hi:[1,0]
	v_pk_mul_f32 v[90:91], v[122:123], v[82:83] op_sel_hi:[1,0]
	v_pk_mul_f32 v[88:89], v[12:13], v[88:89]
	v_pk_mul_f32 v[90:91], v[14:15], v[90:91]
	global_store_dwordx4 v48, v[88:91], s[0:1] offset:3072 nt
	v_cvt_f32_f16_sdwa v99, v79 dst_sel:DWORD dst_unused:UNUSED_PAD src0_sel:WORD_1
	v_cvt_f32_f16_e32 v98, v79
	v_pk_mul_f32 v[88:89], v[124:125], v[82:83] op_sel_hi:[1,0]
	v_pk_mul_f32 v[90:91], v[126:127], v[82:83] op_sel_hi:[1,0]
	v_pk_mul_f32 v[88:89], v[16:17], v[88:89]
	v_pk_mul_f32 v[90:91], v[18:19], v[90:91]
	global_store_dwordx4 v[96:97], v[88:91], off nt
	v_mov_b32_e32 v103, v99
	v_cvt_f32_f16_e32 v108, v72
	v_pk_mul_f32 v[88:89], v[92:93], v[82:83] op_sel_hi:[1,0]
	v_pk_mul_f32 v[90:91], v[94:95], v[82:83] op_sel_hi:[1,0]
	v_cvt_f32_f16_sdwa v93, v80 dst_sel:DWORD dst_unused:UNUSED_PAD src0_sel:WORD_1
	v_cvt_f32_f16_sdwa v95, v81 dst_sel:DWORD dst_unused:UNUSED_PAD src0_sel:WORD_1
	v_cvt_f32_f16_e32 v94, v81
	v_cvt_f32_f16_sdwa v81, v78 dst_sel:DWORD dst_unused:UNUSED_PAD src0_sel:WORD_1
	v_cvt_f32_f16_e32 v92, v80
	v_cvt_f32_f16_e32 v80, v78
	v_mov_b32_e32 v100, v93
	v_mov_b32_e32 v101, v81
	v_mov_b32_e32 v78, v92
	v_mov_b32_e32 v79, v80
	v_pk_mul_f32 v[100:101], v[100:101], v[100:101]
	v_mov_b32_e32 v102, v95
	v_pk_fma_f32 v[78:79], v[78:79], v[78:79], v[100:101]
	v_mov_b32_e32 v100, v94
	v_mov_b32_e32 v101, v98
	v_pk_mul_f32 v[102:103], v[102:103], v[102:103]
	v_cvt_f32_f16_sdwa v111, v73 dst_sel:DWORD dst_unused:UNUSED_PAD src0_sel:WORD_1
	v_pk_fma_f32 v[100:101], v[100:101], v[100:101], v[102:103]
	v_cvt_f32_f16_sdwa v103, v77 dst_sel:DWORD dst_unused:UNUSED_PAD src0_sel:WORD_1
	v_pk_add_f32 v[78:79], v[78:79], v[100:101]
	v_cvt_f32_f16_sdwa v101, v76 dst_sel:DWORD dst_unused:UNUSED_PAD src0_sel:WORD_1
	v_cvt_f32_f16_e32 v100, v76
	v_cvt_f32_f16_e32 v102, v77
	v_mov_b32_e32 v105, v103
	v_mov_b32_e32 v104, v101
	v_mov_b32_e32 v76, v100
	v_mov_b32_e32 v77, v102
	v_pk_mul_f32 v[104:105], v[104:105], v[104:105]
	v_cvt_f32_f16_e32 v110, v73
	v_pk_fma_f32 v[76:77], v[76:77], v[76:77], v[104:105]
	v_cvt_f32_f16_sdwa v105, v74 dst_sel:DWORD dst_unused:UNUSED_PAD src0_sel:WORD_1
	v_cvt_f32_f16_e32 v104, v74
	v_mul_f32_e32 v72, v107, v107
	v_pk_add_f32 v[78:79], v[78:79], v[78:79] op_sel:[0,1] op_sel_hi:[1,0]
	v_mul_f32_e32 v74, v105, v105
	v_pk_add_f32 v[76:77], v[76:77], v[76:77] op_sel:[0,1] op_sel_hi:[1,0]
	v_pk_fma_f32 v[74:75], v[104:105], v[104:105], v[74:75] op_sel_hi:[1,1,0]
	v_pk_fma_f32 v[72:73], v[106:107], v[106:107], v[72:73] op_sel_hi:[1,1,0]
	v_pk_mul_f32 v[112:113], v[108:109], v[108:109]
	v_pk_mul_f32 v[114:115], v[110:111], v[110:111]
	v_mov_b32_e32 v79, v112
	v_mov_b32_e32 v77, v113
	v_mov_b32_e32 v75, v114
	v_mov_b32_e32 v73, v115
	v_pk_add_f32 v[76:77], v[78:79], v[76:77]
	v_pk_add_f32 v[72:73], v[74:75], v[72:73]
	v_cvt_f32_f16_sdwa v79, v71 dst_sel:DWORD dst_unused:UNUSED_PAD src0_sel:WORD_1
	v_pk_add_f32 v[72:73], v[76:77], v[72:73]
	v_cvt_f32_f16_sdwa v77, v70 dst_sel:DWORD dst_unused:UNUSED_PAD src0_sel:WORD_1
	v_cvt_f32_f16_e32 v76, v70
	v_cvt_f32_f16_e32 v78, v71
	v_cvt_f32_f16_sdwa v113, v68 dst_sel:DWORD dst_unused:UNUSED_PAD src0_sel:WORD_1
	v_cvt_f32_f16_e32 v112, v68
	v_mov_b32_e32 v74, v77
	v_mov_b32_e32 v75, v79
	v_mov_b32_e32 v70, v76
	v_mov_b32_e32 v71, v78
	v_pk_mul_f32 v[74:75], v[74:75], v[74:75]
; #define GAS __attribute__((address_space(1)))
; #define LAS __attribute__((address_space(3)))
; #define FN_LOAD(dst, k_) do { const GAS v2u* xr_ = (const GAS v2u*)(X + (size_t)(nw + 2048 * (k_)) * D) + F.lane; \
;         _Pragma("unroll") for (int j = 0; j < 8; ++j) dst[j] = __builtin_nontemporal_load(xr_ + 64 * j); } while (0)
; __device__ __forceinline__ void final_norm_phase2(const Args& a, Frame& F) {
;     ...
;     FN_LOAD(r0, 0); FN_LOAD(r1, 1); FN_LOAD(r2, 2); FN_LOAD(r3, 3); FN_LOAD(r4, 4); FN_LOAD(r5, 5); FN_LOAD(r6, 6); FN_LOAD(r7, 7);
;     for (int q = F.tid; q < D / 4; q += NWAVES * 64) ((LAS f32x4*)GL)[q] = ((const GAS f32x4*)gain)[q];
;     asm volatile("s_waitcnt lgkmcnt(0)" ::: "memory"); __builtin_amdgcn_s_barrier(); asm volatile("" ::: "memory");
;     FN_FINISH(r0, 0); FN_FINISH(r1, 1); FN_FINISH(r2, 2); FN_FINISH(r3, 3); FN_FINISH(r4, 4); FN_FINISH(r5, 5); FN_FINISH(r6, 6); FN_FINISH(r7, 7);
	v_cvt_f32_f16_sdwa v115, v69 dst_sel:DWORD dst_unused:UNUSED_PAD src0_sel:WORD_1
	v_pk_fma_f32 v[70:71], v[70:71], v[70:71], v[74:75]
	v_mul_f32_e32 v68, v113, v113
	v_pk_add_f32 v[74:75], v[70:71], v[70:71] op_sel:[0,1] op_sel_hi:[1,0]
	v_cvt_f32_f16_e32 v114, v69
	v_pk_fma_f32 v[116:117], v[112:113], v[112:113], v[68:69] op_sel_hi:[1,1,0]
	v_cvt_f32_f16_sdwa v69, v66 dst_sel:DWORD dst_unused:UNUSED_PAD src0_sel:WORD_1
	v_cvt_f32_f16_e32 v68, v66
	v_cvt_f32_f16_sdwa v71, v67 dst_sel:DWORD dst_unused:UNUSED_PAD src0_sel:WORD_1
	v_cvt_f32_f16_e32 v70, v67
	v_mul_f32_e32 v66, v115, v115
	v_pk_add_f32 v[72:73], v[72:73], v[72:73] op_sel:[0,1] op_sel_hi:[1,0]
	v_pk_fma_f32 v[66:67], v[114:115], v[114:115], v[66:67] op_sel_hi:[1,1,0]
	v_pk_mul_f32 v[118:119], v[68:69], v[68:69]
	v_pk_mul_f32 v[120:121], v[70:71], v[70:71]
	v_mov_b32_e32 v73, v118
	v_mov_b32_e32 v75, v119
	v_mov_b32_e32 v117, v120
	v_mov_b32_e32 v67, v121
	v_pk_add_f32 v[72:73], v[72:73], v[74:75]
	v_pk_add_f32 v[66:67], v[116:117], v[66:67]
	v_pk_mul_f32 v[90:91], v[22:23], v[90:91]
	v_pk_add_f32 v[66:67], v[72:73], v[66:67]
	v_pk_mul_f32 v[88:89], v[20:21], v[88:89]
	v_add_f32_e32 v66, v66, v67
	global_store_dwordx4 v[96:97], v[88:91], off offset:1024 nt
	v_pk_mul_f32 v[72:73], v[86:87], v[82:83] op_sel_hi:[1,0]
	v_add_f32_dpp v66, v66, v66 quad_perm:[1,0,3,2] row_mask:0xf bank_mask:0xf bound_ctrl:1
	v_pk_mul_f32 v[88:89], v[128:129], v[82:83] op_sel_hi:[1,0]
	v_pk_mul_f32 v[90:91], v[130:131], v[82:83] op_sel_hi:[1,0]
	v_add_f32_dpp v66, v66, v66 quad_perm:[2,3,0,1] row_mask:0xf bank_mask:0xf bound_ctrl:1
	v_pk_mul_f32 v[90:91], v[26:27], v[90:91]
	v_pk_mul_f32 v[88:89], v[24:25], v[88:89]
	v_add_f32_dpp v66, v66, v66 row_half_mirror row_mask:0xf bank_mask:0xf bound_ctrl:1
	global_store_dwordx4 v[96:97], v[88:91], off offset:2048 nt
	s_nop 0
	v_add_f32_dpp v66, v66, v66 row_mirror row_mask:0xf bank_mask:0xf bound_ctrl:1
	v_cvt_f32_f16_sdwa v91, v59 dst_sel:DWORD dst_unused:UNUSED_PAD src0_sel:WORD_1
	v_readlane_b32 s8, v66, 16
	v_readlane_b32 s9, v66, 48
	v_readlane_b32 s0, v66, 0
	v_readlane_b32 s1, v66, 32
	v_mov_b32_e32 v66, s8
	v_mov_b32_e32 v67, s9
	v_pk_add_f32 v[66:67], s[0:1], v[66:67]
	v_cvt_f32_f16_e32 v90, v59
	v_add_f32_e32 v66, v66, v67
	v_fmamk_f32 v66, v66, 0x3a000000, v151
	v_mul_f32_e32 v67, 0x4f800000, v66
	v_cmp_gt_f32_e32 vcc, s18, v66
	s_nop 1
	v_cndmask_b32_e32 v74, v66, v67, vcc
	v_sqrt_f32_e32 v75, v74
	v_pk_mul_f32 v[66:67], v[84:85], v[82:83] op_sel_hi:[1,0]
	v_add_u32_e32 v82, -1, v75
	v_fma_f32 v83, -v82, v75, v74
	v_cmp_ge_f32_e64 s[0:1], 0, v83
	v_add_u32_e32 v83, 1, v75
	s_nop 0
	v_cndmask_b32_e64 v82, v75, v82, s[0:1]
	v_fma_f32 v75, -v83, v75, v74
	v_cmp_lt_f32_e64 s[0:1], 0, v75
	s_nop 1
	v_cndmask_b32_e64 v75, v82, v83, s[0:1]
	v_mul_f32_e32 v82, 0x37800000, v75
	v_cndmask_b32_e32 v75, v75, v82, vcc
	v_cmp_class_f32_e32 vcc, v74, v152
	s_nop 1
	v_cndmask_b32_e32 v82, v75, v74, vcc
	v_div_scale_f32 v83, s[0:1], v82, v82, 1.0
	v_rcp_f32_e32 v84, v83
	v_pk_mul_f32 v[74:75], v[30:31], v[72:73]
	v_pk_mul_f32 v[72:73], v[28:29], v[66:67]
	global_store_dwordx4 v[96:97], v[72:75], off offset:3072 nt
	v_fma_f32 v66, -v83, v84, 1.0
	v_fmac_f32_e32 v84, v66, v84
	v_div_scale_f32 v66, vcc, 1.0, v82, 1.0
	v_mul_f32_e32 v67, v66, v84
	v_fma_f32 v72, -v83, v67, v66
	v_fmac_f32_e32 v67, v72, v84
	v_fma_f32 v66, -v83, v67, v66
	v_div_fmas_f32 v66, v66, v84, v67
	v_div_fixup_f32 v66, v66, v82, 1.0
	s_lshl_b64 s[0:1], s[6:7], 2
	s_add_u32 s0, s24, s0
	v_pk_mul_f32 v[72:73], v[92:93], v[66:67] op_sel_hi:[1,0]
	v_pk_mul_f32 v[74:75], v[94:95], v[66:67] op_sel_hi:[1,0]
	s_addc_u32 s1, s25, s1
	v_pk_mul_f32 v[74:75], v[2:3], v[74:75]
	v_pk_mul_f32 v[72:73], v[0:1], v[72:73]
	global_store_dwordx4 v48, v[72:75], s[0:1] nt
	v_lshl_add_u64 v[82:83], s[0:1], 0, v[48:49]
	v_cvt_f32_f16_sdwa v93, v56 dst_sel:DWORD dst_unused:UNUSED_PAD src0_sel:WORD_1
	v_pk_mul_f32 v[72:73], v[80:81], v[66:67] op_sel_hi:[1,0]
	v_pk_mul_f32 v[74:75], v[98:99], v[66:67] op_sel_hi:[1,0]
	v_pk_mul_f32 v[72:73], v[4:5], v[72:73]
	v_pk_mul_f32 v[74:75], v[6:7], v[74:75]
	global_store_dwordx4 v48, v[72:75], s[0:1] offset:1024 nt
	v_add_co_u32_e32 v80, vcc, s16, v82
	s_nop 0
	v_pk_mul_f32 v[72:73], v[100:101], v[66:67] op_sel_hi:[1,0]
	v_pk_mul_f32 v[74:75], v[102:103], v[66:67] op_sel_hi:[1,0]
	v_pk_mul_f32 v[72:73], v[8:9], v[72:73]
	v_pk_mul_f32 v[74:75], v[10:11], v[74:75]
	global_store_dwordx4 v48, v[72:75], s[0:1] offset:2048 nt
	v_addc_co_u32_e32 v81, vcc, 0, v83, vcc
	s_nop 0
	v_pk_mul_f32 v[72:73], v[104:105], v[66:67] op_sel_hi:[1,0]
	v_pk_mul_f32 v[74:75], v[106:107], v[66:67] op_sel_hi:[1,0]
	v_pk_mul_f32 v[72:73], v[12:13], v[72:73]
	v_pk_mul_f32 v[74:75], v[14:15], v[74:75]
	global_store_dwordx4 v48, v[72:75], s[0:1] offset:3072 nt
	v_cvt_f32_f16_sdwa v83, v63 dst_sel:DWORD dst_unused:UNUSED_PAD src0_sel:WORD_1
	v_cvt_f32_f16_e32 v82, v63
	v_pk_mul_f32 v[72:73], v[108:109], v[66:67] op_sel_hi:[1,0]
	v_pk_mul_f32 v[74:75], v[110:111], v[66:67] op_sel_hi:[1,0]
	v_pk_mul_f32 v[72:73], v[16:17], v[72:73]
	v_pk_mul_f32 v[74:75], v[18:19], v[74:75]
	global_store_dwordx4 v[80:81], v[72:75], off nt
	v_mov_b32_e32 v87, v83
	v_cvt_f32_f16_e32 v92, v56
	v_pk_mul_f32 v[72:73], v[76:77], v[66:67] op_sel_hi:[1,0]
	v_pk_mul_f32 v[74:75], v[78:79], v[66:67] op_sel_hi:[1,0]
	v_cvt_f32_f16_sdwa v77, v64 dst_sel:DWORD dst_unused:UNUSED_PAD src0_sel:WORD_1
	v_cvt_f32_f16_sdwa v79, v65 dst_sel:DWORD dst_unused:UNUSED_PAD src0_sel:WORD_1
	v_cvt_f32_f16_e32 v78, v65
	v_cvt_f32_f16_sdwa v65, v62 dst_sel:DWORD dst_unused:UNUSED_PAD src0_sel:WORD_1
	v_cvt_f32_f16_e32 v76, v64
	v_cvt_f32_f16_e32 v64, v62
; #define GAS __attribute__((address_space(1)))
; #define LAS __attribute__((address_space(3)))
; #define FN_LOAD(dst, k_) do { const GAS v2u* xr_ = (const GAS v2u*)(X + (size_t)(nw + 2048 * (k_)) * D) + F.lane; \
;         _Pragma("unroll") for (int j = 0; j < 8; ++j) dst[j] = __builtin_nontemporal_load(xr_ + 64 * j); } while (0)
; __device__ __forceinline__ void final_norm_phase2(const Args& a, Frame& F) {
;     ...
;     FN_LOAD(r0, 0); FN_LOAD(r1, 1); FN_LOAD(r2, 2); FN_LOAD(r3, 3); FN_LOAD(r4, 4); FN_LOAD(r5, 5); FN_LOAD(r6, 6); FN_LOAD(r7, 7);
;     for (int q = F.tid; q < D / 4; q += NWAVES * 64) ((LAS f32x4*)GL)[q] = ((const GAS f32x4*)gain)[q];
;     asm volatile("s_waitcnt lgkmcnt(0)" ::: "memory"); __builtin_amdgcn_s_barrier(); asm volatile("" ::: "memory");
;     FN_FINISH(r0, 0); FN_FINISH(r1, 1); FN_FINISH(r2, 2); FN_FINISH(r3, 3); FN_FINISH(r4, 4); FN_FINISH(r5, 5); FN_FINISH(r6, 6); FN_FINISH(r7, 7);
	v_mov_b32_e32 v84, v77
	v_mov_b32_e32 v85, v65
	v_mov_b32_e32 v62, v76
	v_mov_b32_e32 v63, v64
	v_pk_mul_f32 v[84:85], v[84:85], v[84:85]
	v_mov_b32_e32 v86, v79
	v_pk_fma_f32 v[62:63], v[62:63], v[62:63], v[84:85]
	v_mov_b32_e32 v84, v78
	v_mov_b32_e32 v85, v82
	v_pk_mul_f32 v[86:87], v[86:87], v[86:87]
	v_cvt_f32_f16_sdwa v95, v57 dst_sel:DWORD dst_unused:UNUSED_PAD src0_sel:WORD_1
	v_pk_fma_f32 v[84:85], v[84:85], v[84:85], v[86:87]
	v_cvt_f32_f16_sdwa v87, v61 dst_sel:DWORD dst_unused:UNUSED_PAD src0_sel:WORD_1
	v_pk_add_f32 v[62:63], v[62:63], v[84:85]
	v_cvt_f32_f16_sdwa v85, v60 dst_sel:DWORD dst_unused:UNUSED_PAD src0_sel:WORD_1
	v_cvt_f32_f16_e32 v84, v60
	v_cvt_f32_f16_e32 v86, v61
	v_mov_b32_e32 v89, v87
	v_mov_b32_e32 v88, v85
	v_mov_b32_e32 v60, v84
	v_mov_b32_e32 v61, v86
	v_pk_mul_f32 v[88:89], v[88:89], v[88:89]
	v_cvt_f32_f16_e32 v94, v57
	v_pk_fma_f32 v[60:61], v[60:61], v[60:61], v[88:89]
	v_cvt_f32_f16_sdwa v89, v58 dst_sel:DWORD dst_unused:UNUSED_PAD src0_sel:WORD_1
	v_cvt_f32_f16_e32 v88, v58
	v_mul_f32_e32 v56, v91, v91
	v_pk_add_f32 v[62:63], v[62:63], v[62:63] op_sel:[0,1] op_sel_hi:[1,0]
	v_mul_f32_e32 v58, v89, v89
	v_pk_add_f32 v[60:61], v[60:61], v[60:61] op_sel:[0,1] op_sel_hi:[1,0]
	v_pk_fma_f32 v[58:59], v[88:89], v[88:89], v[58:59] op_sel_hi:[1,1,0]
	v_pk_fma_f32 v[56:57], v[90:91], v[90:91], v[56:57] op_sel_hi:[1,1,0]
	v_pk_mul_f32 v[96:97], v[92:93], v[92:93]
	v_pk_mul_f32 v[98:99], v[94:95], v[94:95]
	v_mov_b32_e32 v63, v96
	v_mov_b32_e32 v61, v97
	v_mov_b32_e32 v59, v98
	v_mov_b32_e32 v57, v99
	v_pk_add_f32 v[60:61], v[62:63], v[60:61]
	v_pk_add_f32 v[56:57], v[58:59], v[56:57]
	v_cvt_f32_f16_sdwa v63, v55 dst_sel:DWORD dst_unused:UNUSED_PAD src0_sel:WORD_1
	v_pk_add_f32 v[56:57], v[60:61], v[56:57]
	v_cvt_f32_f16_sdwa v61, v54 dst_sel:DWORD dst_unused:UNUSED_PAD src0_sel:WORD_1
	v_cvt_f32_f16_e32 v60, v54
	v_cvt_f32_f16_e32 v62, v55
	v_cvt_f32_f16_sdwa v97, v52 dst_sel:DWORD dst_unused:UNUSED_PAD src0_sel:WORD_1
	v_cvt_f32_f16_e32 v96, v52
	v_mov_b32_e32 v58, v61
	v_mov_b32_e32 v59, v63
	v_mov_b32_e32 v54, v60
	v_mov_b32_e32 v55, v62
	v_pk_mul_f32 v[58:59], v[58:59], v[58:59]
	v_cvt_f32_f16_sdwa v99, v53 dst_sel:DWORD dst_unused:UNUSED_PAD src0_sel:WORD_1
	v_pk_fma_f32 v[54:55], v[54:55], v[54:55], v[58:59]
	v_mul_f32_e32 v52, v97, v97
	v_pk_add_f32 v[58:59], v[54:55], v[54:55] op_sel:[0,1] op_sel_hi:[1,0]
	v_cvt_f32_f16_e32 v98, v53
	v_pk_fma_f32 v[100:101], v[96:97], v[96:97], v[52:53] op_sel_hi:[1,1,0]
	v_cvt_f32_f16_sdwa v53, v50 dst_sel:DWORD dst_unused:UNUSED_PAD src0_sel:WORD_1
	v_cvt_f32_f16_e32 v52, v50
	v_cvt_f32_f16_sdwa v55, v51 dst_sel:DWORD dst_unused:UNUSED_PAD src0_sel:WORD_1
	v_cvt_f32_f16_e32 v54, v51
	v_mul_f32_e32 v50, v99, v99
	v_pk_add_f32 v[56:57], v[56:57], v[56:57] op_sel:[0,1] op_sel_hi:[1,0]
	v_pk_fma_f32 v[50:51], v[98:99], v[98:99], v[50:51] op_sel_hi:[1,1,0]
	v_pk_mul_f32 v[102:103], v[52:53], v[52:53]
	v_pk_mul_f32 v[104:105], v[54:55], v[54:55]
	v_mov_b32_e32 v57, v102
	v_mov_b32_e32 v59, v103
	v_mov_b32_e32 v101, v104
	v_mov_b32_e32 v51, v105
	v_pk_add_f32 v[56:57], v[56:57], v[58:59]
	v_pk_add_f32 v[50:51], v[100:101], v[50:51]
	v_pk_mul_f32 v[74:75], v[22:23], v[74:75]
	v_pk_add_f32 v[50:51], v[56:57], v[50:51]
	v_pk_mul_f32 v[72:73], v[20:21], v[72:73]
	v_add_f32_e32 v50, v50, v51
	global_store_dwordx4 v[80:81], v[72:75], off offset:1024 nt
	v_pk_mul_f32 v[56:57], v[70:71], v[66:67] op_sel_hi:[1,0]
	v_add_f32_dpp v50, v50, v50 quad_perm:[1,0,3,2] row_mask:0xf bank_mask:0xf bound_ctrl:1
	v_pk_mul_f32 v[72:73], v[112:113], v[66:67] op_sel_hi:[1,0]
	v_pk_mul_f32 v[74:75], v[114:115], v[66:67] op_sel_hi:[1,0]
	v_add_f32_dpp v50, v50, v50 quad_perm:[2,3,0,1] row_mask:0xf bank_mask:0xf bound_ctrl:1
	v_pk_mul_f32 v[74:75], v[26:27], v[74:75]
	v_pk_mul_f32 v[72:73], v[24:25], v[72:73]
	v_add_f32_dpp v50, v50, v50 row_half_mirror row_mask:0xf bank_mask:0xf bound_ctrl:1
	global_store_dwordx4 v[80:81], v[72:75], off offset:2048 nt
	s_nop 0
	v_add_f32_dpp v50, v50, v50 row_mirror row_mask:0xf bank_mask:0xf bound_ctrl:1
	v_cvt_f32_f16_sdwa v75, v41 dst_sel:DWORD dst_unused:UNUSED_PAD src0_sel:WORD_1
	v_readlane_b32 s6, v50, 16
	v_readlane_b32 s7, v50, 48
	v_readlane_b32 s0, v50, 0
	v_readlane_b32 s1, v50, 32
	v_mov_b32_e32 v50, s6
	v_mov_b32_e32 v51, s7
	v_pk_add_f32 v[50:51], s[0:1], v[50:51]
	v_cvt_f32_f16_e32 v74, v41
	v_add_f32_e32 v50, v50, v51
	v_fmamk_f32 v50, v50, 0x3a000000, v151
	v_mul_f32_e32 v51, 0x4f800000, v50
	v_cmp_gt_f32_e32 vcc, s18, v50
	s_nop 1
	v_cndmask_b32_e32 v58, v50, v51, vcc
	v_sqrt_f32_e32 v59, v58
	v_pk_mul_f32 v[50:51], v[68:69], v[66:67] op_sel_hi:[1,0]
	v_add_u32_e32 v66, -1, v59
	v_fma_f32 v67, -v66, v59, v58
	v_cmp_ge_f32_e64 s[0:1], 0, v67
	v_add_u32_e32 v67, 1, v59
	s_nop 0
	v_cndmask_b32_e64 v66, v59, v66, s[0:1]
	v_fma_f32 v59, -v67, v59, v58
	v_cmp_lt_f32_e64 s[0:1], 0, v59
	s_nop 1
	v_cndmask_b32_e64 v59, v66, v67, s[0:1]
	v_mul_f32_e32 v66, 0x37800000, v59
	v_cndmask_b32_e32 v59, v59, v66, vcc
	v_cmp_class_f32_e32 vcc, v58, v152
	s_nop 1
	v_cndmask_b32_e32 v66, v59, v58, vcc
	v_div_scale_f32 v67, s[0:1], v66, v66, 1.0
	v_rcp_f32_e32 v68, v67
	v_pk_mul_f32 v[58:59], v[30:31], v[56:57]
	v_pk_mul_f32 v[56:57], v[28:29], v[50:51]
	global_store_dwordx4 v[80:81], v[56:59], off offset:3072 nt
	v_fma_f32 v50, -v67, v68, 1.0
	v_fmac_f32_e32 v68, v50, v68
	v_div_scale_f32 v50, vcc, 1.0, v66, 1.0
	v_mul_f32_e32 v51, v50, v68
	v_fma_f32 v56, -v67, v51, v50
	v_fmac_f32_e32 v51, v56, v68
	v_fma_f32 v50, -v67, v51, v50
	v_div_fmas_f32 v50, v50, v68, v51
	v_div_fixup_f32 v50, v50, v66, 1.0
	s_lshl_b64 s[0:1], s[4:5], 2
	s_add_u32 s0, s24, s0
; #define GAS __attribute__((address_space(1)))
; #define LAS __attribute__((address_space(3)))
; #define FN_LOAD(dst, k_) do { const GAS v2u* xr_ = (const GAS v2u*)(X + (size_t)(nw + 2048 * (k_)) * D) + F.lane; \
;         _Pragma("unroll") for (int j = 0; j < 8; ++j) dst[j] = __builtin_nontemporal_load(xr_ + 64 * j); } while (0)
; __device__ __forceinline__ void final_norm_phase2(const Args& a, Frame& F) {
;     ...
;     FN_LOAD(r0, 0); FN_LOAD(r1, 1); FN_LOAD(r2, 2); FN_LOAD(r3, 3); FN_LOAD(r4, 4); FN_LOAD(r5, 5); FN_LOAD(r6, 6); FN_LOAD(r7, 7);
;     for (int q = F.tid; q < D / 4; q += NWAVES * 64) ((LAS f32x4*)GL)[q] = ((const GAS f32x4*)gain)[q];
;     asm volatile("s_waitcnt lgkmcnt(0)" ::: "memory"); __builtin_amdgcn_s_barrier(); asm volatile("" ::: "memory");
;     FN_FINISH(r0, 0); FN_FINISH(r1, 1); FN_FINISH(r2, 2); FN_FINISH(r3, 3); FN_FINISH(r4, 4); FN_FINISH(r5, 5); FN_FINISH(r6, 6); FN_FINISH(r7, 7);
	v_pk_mul_f32 v[56:57], v[76:77], v[50:51] op_sel_hi:[1,0]
	v_pk_mul_f32 v[58:59], v[78:79], v[50:51] op_sel_hi:[1,0]
	s_addc_u32 s1, s25, s1
	v_pk_mul_f32 v[58:59], v[2:3], v[58:59]
	v_pk_mul_f32 v[56:57], v[0:1], v[56:57]
	global_store_dwordx4 v48, v[56:59], s[0:1] nt
	v_lshl_add_u64 v[66:67], s[0:1], 0, v[48:49]
	v_cvt_f32_f16_sdwa v77, v38 dst_sel:DWORD dst_unused:UNUSED_PAD src0_sel:WORD_1
	v_pk_mul_f32 v[56:57], v[64:65], v[50:51] op_sel_hi:[1,0]
	v_pk_mul_f32 v[58:59], v[82:83], v[50:51] op_sel_hi:[1,0]
	v_pk_mul_f32 v[56:57], v[4:5], v[56:57]
	v_pk_mul_f32 v[58:59], v[6:7], v[58:59]
	global_store_dwordx4 v48, v[56:59], s[0:1] offset:1024 nt
	v_add_co_u32_e32 v64, vcc, s16, v66
	s_nop 0
	v_pk_mul_f32 v[56:57], v[84:85], v[50:51] op_sel_hi:[1,0]
	v_pk_mul_f32 v[58:59], v[86:87], v[50:51] op_sel_hi:[1,0]
	v_pk_mul_f32 v[56:57], v[8:9], v[56:57]
	v_pk_mul_f32 v[58:59], v[10:11], v[58:59]
	global_store_dwordx4 v48, v[56:59], s[0:1] offset:2048 nt
	v_addc_co_u32_e32 v65, vcc, 0, v67, vcc
	s_nop 0
	v_pk_mul_f32 v[56:57], v[88:89], v[50:51] op_sel_hi:[1,0]
	v_pk_mul_f32 v[58:59], v[90:91], v[50:51] op_sel_hi:[1,0]
	v_pk_mul_f32 v[56:57], v[12:13], v[56:57]
	v_pk_mul_f32 v[58:59], v[14:15], v[58:59]
	global_store_dwordx4 v48, v[56:59], s[0:1] offset:3072 nt
	v_cvt_f32_f16_sdwa v67, v45 dst_sel:DWORD dst_unused:UNUSED_PAD src0_sel:WORD_1
	v_cvt_f32_f16_e32 v66, v45
	v_pk_mul_f32 v[56:57], v[92:93], v[50:51] op_sel_hi:[1,0]
	v_pk_mul_f32 v[58:59], v[94:95], v[50:51] op_sel_hi:[1,0]
	v_pk_mul_f32 v[56:57], v[16:17], v[56:57]
	v_pk_mul_f32 v[58:59], v[18:19], v[58:59]
	global_store_dwordx4 v[64:65], v[56:59], off nt
	v_mov_b32_e32 v71, v67
	v_cvt_f32_f16_e32 v76, v38
	v_pk_mul_f32 v[56:57], v[60:61], v[50:51] op_sel_hi:[1,0]
	v_pk_mul_f32 v[58:59], v[62:63], v[50:51] op_sel_hi:[1,0]
	v_cvt_f32_f16_sdwa v61, v46 dst_sel:DWORD dst_unused:UNUSED_PAD src0_sel:WORD_1
	v_cvt_f32_f16_sdwa v63, v47 dst_sel:DWORD dst_unused:UNUSED_PAD src0_sel:WORD_1
	v_cvt_f32_f16_e32 v62, v47
	v_cvt_f32_f16_sdwa v47, v44 dst_sel:DWORD dst_unused:UNUSED_PAD src0_sel:WORD_1
	v_cvt_f32_f16_e32 v60, v46
	v_cvt_f32_f16_e32 v46, v44
	v_mov_b32_e32 v68, v61
	v_mov_b32_e32 v69, v47
	v_mov_b32_e32 v44, v60
	v_mov_b32_e32 v45, v46
	v_pk_mul_f32 v[68:69], v[68:69], v[68:69]
	v_mov_b32_e32 v70, v63
	v_pk_fma_f32 v[44:45], v[44:45], v[44:45], v[68:69]
	v_mov_b32_e32 v68, v62
	v_mov_b32_e32 v69, v66
	v_pk_mul_f32 v[70:71], v[70:71], v[70:71]
	v_cvt_f32_f16_sdwa v79, v39 dst_sel:DWORD dst_unused:UNUSED_PAD src0_sel:WORD_1
	v_pk_fma_f32 v[68:69], v[68:69], v[68:69], v[70:71]
	v_cvt_f32_f16_sdwa v71, v43 dst_sel:DWORD dst_unused:UNUSED_PAD src0_sel:WORD_1
	v_pk_add_f32 v[44:45], v[44:45], v[68:69]
	v_cvt_f32_f16_sdwa v69, v42 dst_sel:DWORD dst_unused:UNUSED_PAD src0_sel:WORD_1
	v_cvt_f32_f16_e32 v68, v42
	v_cvt_f32_f16_e32 v70, v43
	v_mov_b32_e32 v73, v71
	v_mov_b32_e32 v72, v69
	v_mov_b32_e32 v42, v68
	v_mov_b32_e32 v43, v70
	v_pk_mul_f32 v[72:73], v[72:73], v[72:73]
	v_cvt_f32_f16_e32 v78, v39
	v_pk_fma_f32 v[42:43], v[42:43], v[42:43], v[72:73]
	v_cvt_f32_f16_sdwa v73, v40 dst_sel:DWORD dst_unused:UNUSED_PAD src0_sel:WORD_1
	v_cvt_f32_f16_e32 v72, v40
	v_mul_f32_e32 v38, v75, v75
	v_pk_add_f32 v[44:45], v[44:45], v[44:45] op_sel:[0,1] op_sel_hi:[1,0]
	v_mul_f32_e32 v40, v73, v73
	v_pk_add_f32 v[42:43], v[42:43], v[42:43] op_sel:[0,1] op_sel_hi:[1,0]
	v_pk_fma_f32 v[40:41], v[72:73], v[72:73], v[40:41] op_sel_hi:[1,1,0]
	v_pk_fma_f32 v[38:39], v[74:75], v[74:75], v[38:39] op_sel_hi:[1,1,0]
	v_pk_mul_f32 v[80:81], v[76:77], v[76:77]
	v_pk_mul_f32 v[82:83], v[78:79], v[78:79]
	v_mov_b32_e32 v45, v80
	v_mov_b32_e32 v43, v81
	v_mov_b32_e32 v41, v82
	v_mov_b32_e32 v39, v83
	v_pk_add_f32 v[42:43], v[44:45], v[42:43]
	v_pk_add_f32 v[38:39], v[40:41], v[38:39]
	v_cvt_f32_f16_sdwa v41, v36 dst_sel:DWORD dst_unused:UNUSED_PAD src0_sel:WORD_1
	v_pk_add_f32 v[38:39], v[42:43], v[38:39]
	v_cvt_f32_f16_sdwa v43, v37 dst_sel:DWORD dst_unused:UNUSED_PAD src0_sel:WORD_1
	v_cvt_f32_f16_e32 v40, v36
	v_cvt_f32_f16_e32 v42, v37
	v_mov_b32_e32 v44, v41
	v_mov_b32_e32 v45, v43
	v_mov_b32_e32 v36, v40
	v_mov_b32_e32 v37, v42
	v_pk_mul_f32 v[44:45], v[44:45], v[44:45]
	v_cvt_f32_f16_sdwa v81, v35 dst_sel:DWORD dst_unused:UNUSED_PAD src0_sel:WORD_1
	v_pk_fma_f32 v[36:37], v[36:37], v[36:37], v[44:45]
	v_cvt_f32_f16_sdwa v45, v34 dst_sel:DWORD dst_unused:UNUSED_PAD src0_sel:WORD_1
	v_cvt_f32_f16_e32 v44, v34
	v_cvt_f32_f16_e32 v80, v35
	v_cvt_f32_f16_sdwa v83, v32 dst_sel:DWORD dst_unused:UNUSED_PAD src0_sel:WORD_1
	v_cvt_f32_f16_e32 v82, v32
	v_cvt_f32_f16_sdwa v85, v33 dst_sel:DWORD dst_unused:UNUSED_PAD src0_sel:WORD_1
	v_cvt_f32_f16_e32 v84, v33
	v_mul_f32_e32 v34, v45, v45
	v_mul_f32_e32 v32, v81, v81
	v_pk_add_f32 v[38:39], v[38:39], v[38:39] op_sel:[0,1] op_sel_hi:[1,0]
	v_pk_add_f32 v[36:37], v[36:37], v[36:37] op_sel:[0,1] op_sel_hi:[1,0]
	v_pk_fma_f32 v[34:35], v[44:45], v[44:45], v[34:35] op_sel_hi:[1,1,0]
; #define GAS __attribute__((address_space(1)))
; #define LAS __attribute__((address_space(3)))
; #define FN_LOAD(dst, k_) do { const GAS v2u* xr_ = (const GAS v2u*)(X + (size_t)(nw + 2048 * (k_)) * D) + F.lane; \
;         _Pragma("unroll") for (int j = 0; j < 8; ++j) dst[j] = __builtin_nontemporal_load(xr_ + 64 * j); } while (0)
; __device__ __forceinline__ void final_norm_phase2(const Args& a, Frame& F) {
;     ...
;     FN_LOAD(r0, 0); FN_LOAD(r1, 1); FN_LOAD(r2, 2); FN_LOAD(r3, 3); FN_LOAD(r4, 4); FN_LOAD(r5, 5); FN_LOAD(r6, 6); FN_LOAD(r7, 7);
;     for (int q = F.tid; q < D / 4; q += NWAVES * 64) ((LAS f32x4*)GL)[q] = ((const GAS f32x4*)gain)[q];
;     asm volatile("s_waitcnt lgkmcnt(0)" ::: "memory"); __builtin_amdgcn_s_barrier(); asm volatile("" ::: "memory");
;     FN_FINISH(r0, 0); FN_FINISH(r1, 1); FN_FINISH(r2, 2); FN_FINISH(r3, 3); FN_FINISH(r4, 4); FN_FINISH(r5, 5); FN_FINISH(r6, 6); FN_FINISH(r7, 7);
	v_pk_fma_f32 v[32:33], v[80:81], v[80:81], v[32:33] op_sel_hi:[1,1,0]
	v_pk_mul_f32 v[86:87], v[82:83], v[82:83]
	v_pk_mul_f32 v[88:89], v[84:85], v[84:85]
	v_mov_b32_e32 v39, v86
	v_mov_b32_e32 v37, v87
	v_mov_b32_e32 v35, v88
	v_mov_b32_e32 v33, v89
	v_pk_add_f32 v[36:37], v[38:39], v[36:37]
	v_pk_add_f32 v[32:33], v[34:35], v[32:33]
	v_pk_mul_f32 v[34:35], v[54:55], v[50:51] op_sel_hi:[1,0]
	v_pk_add_f32 v[32:33], v[36:37], v[32:33]
	v_pk_mul_f32 v[34:35], v[30:31], v[34:35]
	v_add_f32_e32 v32, v32, v33
	v_pk_mul_f32 v[58:59], v[22:23], v[58:59]
	v_pk_mul_f32 v[56:57], v[20:21], v[56:57]
	v_add_f32_dpp v32, v32, v32 quad_perm:[1,0,3,2] row_mask:0xf bank_mask:0xf bound_ctrl:1
	global_store_dwordx4 v[64:65], v[56:59], off offset:1024 nt
	s_nop 0
	v_add_f32_dpp v32, v32, v32 quad_perm:[2,3,0,1] row_mask:0xf bank_mask:0xf bound_ctrl:1
	v_pk_mul_f32 v[56:57], v[96:97], v[50:51] op_sel_hi:[1,0]
	v_pk_mul_f32 v[58:59], v[98:99], v[50:51] op_sel_hi:[1,0]
	v_add_f32_dpp v32, v32, v32 row_half_mirror row_mask:0xf bank_mask:0xf bound_ctrl:1
	v_pk_mul_f32 v[58:59], v[26:27], v[58:59]
	v_pk_mul_f32 v[56:57], v[24:25], v[56:57]
	v_add_f32_dpp v32, v32, v32 row_mirror row_mask:0xf bank_mask:0xf bound_ctrl:1
	global_store_dwordx4 v[64:65], v[56:59], off offset:2048 nt
	v_readlane_b32 s4, v32, 16
	v_readlane_b32 s5, v32, 48
	v_readlane_b32 s0, v32, 0
	v_readlane_b32 s1, v32, 32
	v_mov_b32_e32 v32, s4
	v_mov_b32_e32 v33, s5
	v_pk_add_f32 v[32:33], s[0:1], v[32:33]
	s_nop 0
	v_add_f32_e32 v32, v32, v33
	v_fmac_f32_e32 v151, 0x3a000000, v32
	v_mul_f32_e32 v32, 0x4f800000, v151
	v_cmp_gt_f32_e32 vcc, s18, v151
	s_nop 1
	v_cndmask_b32_e32 v36, v151, v32, vcc
	v_sqrt_f32_e32 v37, v36
	v_pk_mul_f32 v[32:33], v[52:53], v[50:51] op_sel_hi:[1,0]
	v_add_u32_e32 v38, -1, v37
	v_fma_f32 v39, -v38, v37, v36
	v_cmp_ge_f32_e64 s[0:1], 0, v39
	v_add_u32_e32 v39, 1, v37
	v_pk_mul_f32 v[32:33], v[28:29], v[32:33]
	v_cndmask_b32_e64 v38, v37, v38, s[0:1]
	v_fma_f32 v37, -v39, v37, v36
	v_cmp_lt_f32_e64 s[0:1], 0, v37
	global_store_dwordx4 v[64:65], v[32:35], off offset:3072 nt
	s_nop 0
	v_cndmask_b32_e64 v37, v38, v39, s[0:1]
	v_mul_f32_e32 v38, 0x37800000, v37
	v_cndmask_b32_e32 v37, v37, v38, vcc
	v_cmp_class_f32_e32 vcc, v36, v152
	s_nop 1
	v_cndmask_b32_e32 v36, v37, v36, vcc
	v_div_scale_f32 v37, s[0:1], v36, v36, 1.0
	v_rcp_f32_e32 v38, v37
	s_lshl_b64 s[0:1], s[2:3], 2
	s_add_u32 s0, s24, s0
	s_addc_u32 s1, s25, s1
	v_fma_f32 v32, -v37, v38, 1.0
	v_fmac_f32_e32 v38, v32, v38
	v_div_scale_f32 v32, vcc, 1.0, v36, 1.0
	v_mul_f32_e32 v33, v32, v38
	v_fma_f32 v34, -v37, v33, v32
	v_fmac_f32_e32 v33, v34, v38
	v_fma_f32 v32, -v37, v33, v32
	v_div_fmas_f32 v32, v32, v38, v33
	v_div_fixup_f32 v32, v32, v36, 1.0
	v_pk_mul_f32 v[36:37], v[60:61], v[32:33] op_sel_hi:[1,0]
	v_pk_mul_f32 v[38:39], v[62:63], v[32:33] op_sel_hi:[1,0]
	v_pk_mul_f32 v[0:1], v[0:1], v[36:37]
	v_pk_mul_f32 v[2:3], v[2:3], v[38:39]
	global_store_dwordx4 v48, v[0:3], s[0:1] nt
	v_lshl_add_u64 v[34:35], s[0:1], 0, v[48:49]
	s_nop 0
	v_pk_mul_f32 v[0:1], v[46:47], v[32:33] op_sel_hi:[1,0]
	v_pk_mul_f32 v[2:3], v[66:67], v[32:33] op_sel_hi:[1,0]
	v_pk_mul_f32 v[0:1], v[4:5], v[0:1]
	v_pk_mul_f32 v[2:3], v[6:7], v[2:3]
	global_store_dwordx4 v48, v[0:3], s[0:1] offset:1024 nt
	v_add_co_u32_e32 v4, vcc, s16, v34
	s_nop 0
	v_pk_mul_f32 v[0:1], v[68:69], v[32:33] op_sel_hi:[1,0]
	v_pk_mul_f32 v[2:3], v[70:71], v[32:33] op_sel_hi:[1,0]
	v_pk_mul_f32 v[0:1], v[8:9], v[0:1]
	v_pk_mul_f32 v[2:3], v[10:11], v[2:3]
	global_store_dwordx4 v48, v[0:3], s[0:1] offset:2048 nt
	v_addc_co_u32_e32 v5, vcc, 0, v35, vcc
	s_nop 0
	v_pk_mul_f32 v[0:1], v[72:73], v[32:33] op_sel_hi:[1,0]
	v_pk_mul_f32 v[2:3], v[74:75], v[32:33] op_sel_hi:[1,0]
	v_pk_mul_f32 v[0:1], v[12:13], v[0:1]
	v_pk_mul_f32 v[2:3], v[14:15], v[2:3]
	global_store_dwordx4 v48, v[0:3], s[0:1] offset:3072 nt
	s_nop 1
	v_pk_mul_f32 v[0:1], v[76:77], v[32:33] op_sel_hi:[1,0]
	v_pk_mul_f32 v[2:3], v[78:79], v[32:33] op_sel_hi:[1,0]
	v_pk_mul_f32 v[0:1], v[16:17], v[0:1]
	v_pk_mul_f32 v[2:3], v[18:19], v[2:3]
	global_store_dwordx4 v[4:5], v[0:3], off nt
	s_nop 1
	v_pk_mul_f32 v[0:1], v[40:41], v[32:33] op_sel_hi:[1,0]
	v_pk_mul_f32 v[2:3], v[42:43], v[32:33] op_sel_hi:[1,0]
	v_pk_mul_f32 v[0:1], v[20:21], v[0:1]
	v_pk_mul_f32 v[2:3], v[22:23], v[2:3]
	global_store_dwordx4 v[4:5], v[0:3], off offset:1024 nt
	s_nop 1
	v_pk_mul_f32 v[0:1], v[44:45], v[32:33] op_sel_hi:[1,0]
	v_pk_mul_f32 v[2:3], v[80:81], v[32:33] op_sel_hi:[1,0]
	v_pk_mul_f32 v[0:1], v[24:25], v[0:1]
	v_pk_mul_f32 v[2:3], v[26:27], v[2:3]
	global_store_dwordx4 v[4:5], v[0:3], off offset:2048 nt
	s_nop 1
	v_pk_mul_f32 v[0:1], v[82:83], v[32:33] op_sel_hi:[1,0]
	v_pk_mul_f32 v[2:3], v[84:85], v[32:33] op_sel_hi:[1,0]
	v_pk_mul_f32 v[0:1], v[28:29], v[0:1]
	v_pk_mul_f32 v[2:3], v[30:31], v[2:3]
	global_store_dwordx4 v[4:5], v[0:3], off offset:3072 nt
